# GEMM loops: scalar/VALU instructions that sat between a segment's last MFMA and its post-MFMA barrier moved to just after the barrier (start of the load segment)
# speedup vs baseline: 1.0074x; 1.0074x over previous
; #define PG8_STAGE(bufoff, gbase, voff) do { _Pragma("unroll") for (int _i = 0; _i < 2; ++_i) \
;         __builtin_amdgcn_global_load_lds((const unsigned*)((const char*)(gbase) + (voff)[_i]), (LAS unsigned*)(lds + (bufoff) + ldsw + _i * 8192), 16, 0, 0); } while (0)
; #define PG8_LDA(dst, b, h) do { _Pragma("unroll") for (int m = 0; m < 4; ++m) _Pragma("unroll") for (int k = 0; k < 2; ++k) dst[m][k] = *(const LAS bf16x8*)(lds + PG8_SA(b, h) + aoff + m * 2048 + k * 1024); } while (0)
; #define PG8_LDB(dst, b, h) do { _Pragma("unroll") for (int n = 0; n < 2; ++n) _Pragma("unroll") for (int k = 0; k < 2; ++k) dst[n][k] = *(const LAS bf16x8*)(lds + PG8_SB(b, h) + boff + n * 2048 + k * 1024); } while (0)
; #define PG8_WAIT_V(n) asm volatile("s_waitcnt vmcnt(" #n ")" ::: "memory")
; #define PG8_WAIT_L(n) asm volatile("s_waitcnt lgkmcnt(" #n ")" ::: "memory")
; #define PG8_BAR __builtin_amdgcn_s_barrier()
; #define PG8_SCHED __builtin_amdgcn_sched_barrier(0)
; template <class Epi, class Sched>
; __device__ __forceinline__ void gemm_phase(LAS unsigned char* lds, const Gemm g, const Sched& S, const Epi& E) {
;     ...
;         const bool has_next = S.next(ui + 1, nxt);
;         const char* nA = has_next ? (const char*)g.A + (size_t)nxt.pm * tstep : cA; const char* nB = has_next ? (const char*)g.Bt + (size_t)nxt.pn * tstep : cB;
;         for (int t = 0; t < nt; t += 2) {
;             const bool last = (t == nt - 2);
;             const char* a1 = cA + (size_t)(t + 1) * kstep;
;             const char* a2 = last ? nA : cA + (size_t)(t + 2) * kstep; const char* b2 = last ? nB : cB + (size_t)(t + 2) * kstep;
;             const char* a3 = a2 + kstep; const char* b3 = b2 + kstep;
;             PG8_LDB(B0, 0, 0); PG8_SCHED; PG8_LDA(At, 0, 0); PG8_STAGE(PG8_SA(1, 1), a1 + hstep, voffA);
;             PG8_WAIT_L(8); PG8_BAR; PG8_WAIT_L(0); PG8_MMA(0, 0, At, B0); PG8_BAR; PG8_SCHED;
;             PG8_LDB(B1, 0, 1); PG8_STAGE(PG8_SB(0, 0), b2, voffB);
;             PG8_BAR; PG8_WAIT_L(0); PG8_MMA(0, 1, At, B1); PG8_BAR;
;             PG8_LDA(At, 0, 1); PG8_STAGE(PG8_SA(0, 0), a2, voffA);
;             PG8_BAR; PG8_WAIT_L(0); PG8_MMA(1, 0, At, B0); PG8_BAR; PG8_SCHED;
;             PG8_STAGE(PG8_SB(0, 1), b2 + hstep, voffB);
;             PG8_WAIT_V(6); PG8_BAR; PG8_MMA(1, 1, At, B1); PG8_BAR;
.LBB0_234:
	s_ashr_i32 s7, s6, 31
	v_cmp_lt_i64_e32 vcc, s[8:9], v[140:141]
	s_lshl_b64 s[8:9], s[6:7], 19
	s_add_u32 s8, s96, s8
	s_addc_u32 s9, s97, s9
	s_and_b64 s[10:11], vcc, exec
	s_cselect_b32 s7, s9, s15
	s_cselect_b32 s44, s8, s14
	s_ashr_i32 s5, s4, 31
	s_lshl_b64 s[10:11], s[4:5], 19
	s_add_u32 s10, s72, s10
	s_addc_u32 s11, s73, s11
	s_and_b64 s[16:17], vcc, exec
	s_cselect_b32 s5, s11, s19
	s_cselect_b32 s45, s10, s18
	s_add_u32 s14, s14, 0x40080
	s_addc_u32 s15, s15, 0
	s_add_u32 s46, s18, 0x100
	s_addc_u32 s47, s19, 0
	s_mov_b32 s48, -2
	ds_read_b128 v[150:153], v147
	ds_read_b128 v[154:157], v147 offset:1024
	ds_read_b128 v[158:161], v147 offset:2048
	ds_read_b128 v[162:165], v147 offset:3072
	s_add_u32 s16, s14, 0xfffc0080
	s_addc_u32 s17, s15, -1
	s_cmp_eq_u32 s48, 12
	s_cselect_b32 s23, s7, s17
	s_cselect_b32 s22, s44, s16
	s_cselect_b32 s19, s5, s47
	s_cselect_b32 s18, s45, s46
	s_add_i32 m0, s13, 0xc000
	ds_read_b128 v[166:169], v148
	ds_read_b128 v[170:173], v148 offset:1024
	ds_read_b128 v[174:177], v148 offset:2048
	ds_read_b128 v[178:181], v148 offset:3072
	ds_read_b128 v[182:185], v148 offset:4096
	ds_read_b128 v[186:189], v148 offset:5120
	ds_read_b128 v[190:193], v148 offset:6144
	ds_read_b128 v[194:197], v148 offset:7168
	global_load_lds_dwordx4 v136, s[14:15]
	s_add_i32 m0, s13, 0xe000
	s_nop 0
	global_load_lds_dwordx4 v138, s[14:15]
	s_waitcnt lgkmcnt(8)
	s_waitcnt vmcnt(8)
	s_setprio 1
	s_barrier
	s_waitcnt lgkmcnt(0)
	v_mfma_f32_16x16x32_bf16 v[124:127], v[150:153], v[166:169], 0
	v_mfma_f32_16x16x32_bf16 v[116:119], v[158:161], v[166:169], 0
	v_mfma_f32_16x16x32_bf16 v[108:111], v[150:153], v[174:177], 0
	v_mfma_f32_16x16x32_bf16 v[100:103], v[158:161], v[174:177], 0
	v_mfma_f32_16x16x32_bf16 v[92:95], v[150:153], v[182:185], 0
	v_mfma_f32_16x16x32_bf16 v[84:87], v[158:161], v[182:185], 0
	v_mfma_f32_16x16x32_bf16 v[76:79], v[150:153], v[190:193], 0
	v_mfma_f32_16x16x32_bf16 v[68:71], v[158:161], v[190:193], 0
	v_mfma_f32_16x16x32_bf16 v[124:127], v[154:157], v[170:173], v[124:127]
	v_mfma_f32_16x16x32_bf16 v[116:119], v[162:165], v[170:173], v[116:119]
	v_mfma_f32_16x16x32_bf16 v[108:111], v[154:157], v[178:181], v[108:111]
	v_mfma_f32_16x16x32_bf16 v[100:103], v[162:165], v[178:181], v[100:103]
	v_mfma_f32_16x16x32_bf16 v[92:95], v[154:157], v[186:189], v[92:95]
	v_mfma_f32_16x16x32_bf16 v[84:87], v[162:165], v[186:189], v[84:87]
	v_mfma_f32_16x16x32_bf16 v[76:79], v[154:157], v[194:197], v[76:79]
	v_mfma_f32_16x16x32_bf16 v[68:71], v[162:165], v[194:197], v[68:71]
	s_barrier
	s_setprio 0
	s_add_i32 s16, s40, s25
	s_mov_b32 m0, s16
	ds_read_b128 v[202:205], v149
	ds_read_b128 v[206:209], v149 offset:1024
	ds_read_b128 v[210:213], v149 offset:2048
	ds_read_b128 v[214:217], v149 offset:3072
	global_load_lds_dwordx4 v132, s[18:19]
	s_add_i32 m0, s16, 0x2000
	s_nop 0
	global_load_lds_dwordx4 v128, s[18:19]
	s_waitcnt vmcnt(8)
	s_setprio 1
	s_barrier
	s_waitcnt lgkmcnt(0)
	v_mfma_f32_16x16x32_bf16 v[120:123], v[202:205], v[166:169], 0
	v_mfma_f32_16x16x32_bf16 v[112:115], v[210:213], v[166:169], 0
	v_mfma_f32_16x16x32_bf16 v[104:107], v[202:205], v[174:177], 0
	v_mfma_f32_16x16x32_bf16 v[96:99], v[210:213], v[174:177], 0
	v_mfma_f32_16x16x32_bf16 v[88:91], v[202:205], v[182:185], 0
	v_mfma_f32_16x16x32_bf16 v[80:83], v[210:213], v[182:185], 0
	v_mfma_f32_16x16x32_bf16 v[72:75], v[202:205], v[190:193], 0
	v_mfma_f32_16x16x32_bf16 v[64:67], v[210:213], v[190:193], 0
	v_mfma_f32_16x16x32_bf16 v[120:123], v[206:209], v[170:173], v[120:123]
	v_mfma_f32_16x16x32_bf16 v[112:115], v[214:217], v[170:173], v[112:115]
	v_mfma_f32_16x16x32_bf16 v[104:107], v[206:209], v[178:181], v[104:107]
	v_mfma_f32_16x16x32_bf16 v[96:99], v[214:217], v[178:181], v[96:99]
	v_mfma_f32_16x16x32_bf16 v[88:91], v[206:209], v[186:189], v[88:91]
	v_mfma_f32_16x16x32_bf16 v[80:83], v[214:217], v[186:189], v[80:83]
	v_mfma_f32_16x16x32_bf16 v[72:75], v[206:209], v[194:197], v[72:75]
	v_mfma_f32_16x16x32_bf16 v[64:67], v[214:217], v[194:197], v[64:67]
	s_barrier
	s_setprio 0
	s_mov_b32 m0, s13
	ds_read_b128 v[166:169], v148 offset:16384
	ds_read_b128 v[170:173], v148 offset:17408
	ds_read_b128 v[174:177], v148 offset:18432
	ds_read_b128 v[178:181], v148 offset:19456
	ds_read_b128 v[182:185], v148 offset:20480
	ds_read_b128 v[186:189], v148 offset:21504
	ds_read_b128 v[190:193], v148 offset:22528
	ds_read_b128 v[194:197], v148 offset:23552
	global_load_lds_dwordx4 v134, s[22:23]
	s_mov_b32 m0, s28
	s_nop 0
	global_load_lds_dwordx4 v130, s[22:23]
	s_setprio 1
	s_barrier
	s_waitcnt lgkmcnt(0)
	v_mfma_f32_16x16x32_bf16 v[60:63], v[150:153], v[166:169], 0
	v_mfma_f32_16x16x32_bf16 v[56:59], v[158:161], v[166:169], 0
	v_mfma_f32_16x16x32_bf16 v[44:47], v[150:153], v[174:177], 0
	v_mfma_f32_16x16x32_bf16 v[40:43], v[158:161], v[174:177], 0
	v_mfma_f32_16x16x32_bf16 v[28:31], v[150:153], v[182:185], 0
	v_mfma_f32_16x16x32_bf16 v[24:27], v[158:161], v[182:185], 0
	v_mfma_f32_16x16x32_bf16 v[12:15], v[150:153], v[190:193], 0
	v_mfma_f32_16x16x32_bf16 v[8:11], v[158:161], v[190:193], 0
	v_mfma_f32_16x16x32_bf16 v[60:63], v[154:157], v[170:173], v[60:63]
	v_mfma_f32_16x16x32_bf16 v[56:59], v[162:165], v[170:173], v[56:59]
	v_mfma_f32_16x16x32_bf16 v[44:47], v[154:157], v[178:181], v[44:47]
	v_mfma_f32_16x16x32_bf16 v[40:43], v[162:165], v[178:181], v[40:43]
	v_mfma_f32_16x16x32_bf16 v[28:31], v[154:157], v[186:189], v[28:31]
	v_mfma_f32_16x16x32_bf16 v[24:27], v[162:165], v[186:189], v[24:27]
	v_mfma_f32_16x16x32_bf16 v[12:15], v[154:157], v[194:197], v[12:15]
	v_mfma_f32_16x16x32_bf16 v[8:11], v[162:165], v[194:197], v[8:11]
	s_barrier
; #define PG8_STAGE(bufoff, gbase, voff) do { _Pragma("unroll") for (int _i = 0; _i < 2; ++_i) \
;         __builtin_amdgcn_global_load_lds((const unsigned*)((const char*)(gbase) + (voff)[_i]), (LAS unsigned*)(lds + (bufoff) + ldsw + _i * 8192), 16, 0, 0); } while (0)
; #define PG8_LDA(dst, b, h) do { _Pragma("unroll") for (int m = 0; m < 4; ++m) _Pragma("unroll") for (int k = 0; k < 2; ++k) dst[m][k] = *(const LAS bf16x8*)(lds + PG8_SA(b, h) + aoff + m * 2048 + k * 1024); } while (0)
; #define PG8_LDB(dst, b, h) do { _Pragma("unroll") for (int n = 0; n < 2; ++n) _Pragma("unroll") for (int k = 0; k < 2; ++k) dst[n][k] = *(const LAS bf16x8*)(lds + PG8_SB(b, h) + boff + n * 2048 + k * 1024); } while (0)
; #define PG8_WAIT_V(n) asm volatile("s_waitcnt vmcnt(" #n ")" ::: "memory")
; #define PG8_WAIT_L(n) asm volatile("s_waitcnt lgkmcnt(" #n ")" ::: "memory")
; #define PG8_BAR __builtin_amdgcn_s_barrier()
; #define PG8_SCHED __builtin_amdgcn_sched_barrier(0)
; template <class Epi, class Sched>
; __device__ __forceinline__ void gemm_phase(LAS unsigned char* lds, const Gemm g, const Sched& S, const Epi& E) {
;     ...
;             PG8_LDB(B0, 0, 0); PG8_SCHED; PG8_LDA(At, 0, 0); PG8_STAGE(PG8_SA(1, 1), a1 + hstep, voffA);
;             PG8_WAIT_L(8); PG8_BAR; PG8_WAIT_L(0); PG8_MMA(0, 0, At, B0); PG8_BAR; PG8_SCHED;
;             PG8_LDB(B1, 0, 1); PG8_STAGE(PG8_SB(0, 0), b2, voffB);
;             PG8_BAR; PG8_WAIT_L(0); PG8_MMA(0, 1, At, B1); PG8_BAR;
;             PG8_LDA(At, 0, 1); PG8_STAGE(PG8_SA(0, 0), a2, voffA);
;             PG8_BAR; PG8_WAIT_L(0); PG8_MMA(1, 0, At, B0); PG8_BAR; PG8_SCHED;
;             PG8_STAGE(PG8_SB(0, 1), b2 + hstep, voffB);
;             PG8_WAIT_V(6); PG8_BAR; PG8_MMA(1, 1, At, B1); PG8_BAR;
;             PG8_LDB(B0, 1, 0); PG8_SCHED; PG8_LDA(At, 1, 0); PG8_STAGE(PG8_SA(0, 1), a2 + hstep, voffA);
;             PG8_WAIT_L(8); PG8_BAR; PG8_WAIT_L(0); PG8_MMA(0, 0, At, B0); PG8_BAR; PG8_SCHED;
;             PG8_LDB(B1, 1, 1); PG8_STAGE(PG8_SB(1, 0), b3, voffB);
;             PG8_BAR; PG8_WAIT_L(0); PG8_MMA(0, 1, At, B1); PG8_BAR;
;             PG8_LDA(At, 1, 1); PG8_STAGE(PG8_SA(1, 0), a3, voffA);
;             PG8_BAR; PG8_WAIT_L(0); PG8_MMA(1, 0, At, B0); PG8_BAR; PG8_SCHED;
;             PG8_STAGE(PG8_SB(1, 1), b3 + hstep, voffB);
;             PG8_WAIT_V(6); PG8_BAR; PG8_MMA(1, 1, At, B1); PG8_BAR;
	s_setprio 0
	s_add_u32 s16, s18, 0x40000
	s_addc_u32 s17, s19, 0
	s_add_i32 s20, s41, s25
	s_mov_b32 m0, s20
	s_nop 0
	global_load_lds_dwordx4 v132, s[16:17]
	s_add_i32 m0, s20, 0x2000
	s_nop 0
	global_load_lds_dwordx4 v128, s[16:17]
	s_add_u32 s16, s22, 0x40000
	s_addc_u32 s17, s23, 0
	s_mov_b32 m0, s29
	s_nop 0
	global_load_lds_dwordx4 v134, s[16:17]
	s_mov_b32 m0, s33
	s_nop 0
	global_load_lds_dwordx4 v130, s[16:17]
	s_waitcnt vmcnt(10)
	s_setprio 1
	s_barrier
	v_mfma_f32_16x16x32_bf16 v[52:55], v[202:205], v[166:169], 0
	v_mfma_f32_16x16x32_bf16 v[48:51], v[210:213], v[166:169], 0
	v_mfma_f32_16x16x32_bf16 v[36:39], v[202:205], v[174:177], 0
	v_mfma_f32_16x16x32_bf16 v[32:35], v[210:213], v[174:177], 0
	v_mfma_f32_16x16x32_bf16 v[20:23], v[202:205], v[182:185], 0
	v_mfma_f32_16x16x32_bf16 v[16:19], v[210:213], v[182:185], 0
	v_mfma_f32_16x16x32_bf16 v[4:7], v[202:205], v[190:193], 0
	v_mfma_f32_16x16x32_bf16 v[0:3], v[210:213], v[190:193], 0
	v_mfma_f32_16x16x32_bf16 v[52:55], v[206:209], v[170:173], v[52:55]
	v_mfma_f32_16x16x32_bf16 v[48:51], v[214:217], v[170:173], v[48:51]
	v_mfma_f32_16x16x32_bf16 v[36:39], v[206:209], v[178:181], v[36:39]
	v_mfma_f32_16x16x32_bf16 v[32:35], v[214:217], v[178:181], v[32:35]
	v_mfma_f32_16x16x32_bf16 v[20:23], v[206:209], v[186:189], v[20:23]
	v_mfma_f32_16x16x32_bf16 v[16:19], v[214:217], v[186:189], v[16:19]
	v_mfma_f32_16x16x32_bf16 v[4:7], v[206:209], v[194:197], v[4:7]
	v_mfma_f32_16x16x32_bf16 v[0:3], v[214:217], v[194:197], v[0:3]
	s_barrier
	s_setprio 0
	s_add_i32 s20, 0, 0x18000
	v_add_u32_e32 v162, s20, v146
	ds_read_b128 v[150:153], v162
	ds_read_b128 v[154:157], v162 offset:1024
	ds_read_b128 v[158:161], v162 offset:2048
	ds_read_b128 v[162:165], v162 offset:3072
	ds_read_b128 v[166:169], v148 offset:32768
	ds_read_b128 v[170:173], v148 offset:33792
	ds_read_b128 v[174:177], v148 offset:34816
	ds_read_b128 v[178:181], v148 offset:35840
	ds_read_b128 v[182:185], v148 offset:36864
	ds_read_b128 v[186:189], v148 offset:37888
	ds_read_b128 v[190:193], v148 offset:38912
	ds_read_b128 v[194:197], v148 offset:39936
	s_waitcnt lgkmcnt(8)
	s_waitcnt vmcnt(8)
	s_setprio 1
	s_barrier
	s_waitcnt lgkmcnt(0)
	v_mfma_f32_16x16x32_bf16 v[124:127], v[150:153], v[166:169], v[124:127]
	v_mfma_f32_16x16x32_bf16 v[116:119], v[158:161], v[166:169], v[116:119]
	v_mfma_f32_16x16x32_bf16 v[108:111], v[150:153], v[174:177], v[108:111]
	v_mfma_f32_16x16x32_bf16 v[100:103], v[158:161], v[174:177], v[100:103]
	v_mfma_f32_16x16x32_bf16 v[92:95], v[150:153], v[182:185], v[92:95]
	v_mfma_f32_16x16x32_bf16 v[84:87], v[158:161], v[182:185], v[84:87]
	v_mfma_f32_16x16x32_bf16 v[76:79], v[150:153], v[190:193], v[76:79]
	v_mfma_f32_16x16x32_bf16 v[68:71], v[158:161], v[190:193], v[68:71]
	v_mfma_f32_16x16x32_bf16 v[124:127], v[154:157], v[170:173], v[124:127]
	v_mfma_f32_16x16x32_bf16 v[116:119], v[162:165], v[170:173], v[116:119]
	v_mfma_f32_16x16x32_bf16 v[108:111], v[154:157], v[178:181], v[108:111]
	v_mfma_f32_16x16x32_bf16 v[100:103], v[162:165], v[178:181], v[100:103]
	v_mfma_f32_16x16x32_bf16 v[92:95], v[154:157], v[186:189], v[92:95]
	v_mfma_f32_16x16x32_bf16 v[84:87], v[162:165], v[186:189], v[84:87]
	v_mfma_f32_16x16x32_bf16 v[76:79], v[154:157], v[194:197], v[76:79]
	v_mfma_f32_16x16x32_bf16 v[68:71], v[162:165], v[194:197], v[68:71]
	s_barrier
	s_setprio 0
	s_add_i32 s21, 0, 0x1c000
	s_add_i32 s16, s20, s25
	v_add_u32_e32 v214, s21, v146
	s_add_u32 s0, s18, 0x80
	s_addc_u32 s1, s19, 0
	s_mov_b32 m0, s16
	ds_read_b128 v[202:205], v214
	ds_read_b128 v[206:209], v214 offset:1024
	ds_read_b128 v[210:213], v214 offset:2048
	ds_read_b128 v[214:217], v214 offset:3072
	global_load_lds_dwordx4 v132, s[0:1]
	s_add_i32 m0, s16, 0x2000
	s_nop 0
	global_load_lds_dwordx4 v128, s[0:1]
	s_waitcnt vmcnt(8)
	s_setprio 1
	s_barrier
	s_waitcnt lgkmcnt(0)
	v_mfma_f32_16x16x32_bf16 v[120:123], v[202:205], v[166:169], v[120:123]
	v_mfma_f32_16x16x32_bf16 v[112:115], v[210:213], v[166:169], v[112:115]
	v_mfma_f32_16x16x32_bf16 v[104:107], v[202:205], v[174:177], v[104:107]
	v_mfma_f32_16x16x32_bf16 v[96:99], v[210:213], v[174:177], v[96:99]
	v_mfma_f32_16x16x32_bf16 v[88:91], v[202:205], v[182:185], v[88:91]
	v_mfma_f32_16x16x32_bf16 v[80:83], v[210:213], v[182:185], v[80:83]
	v_mfma_f32_16x16x32_bf16 v[72:75], v[202:205], v[190:193], v[72:75]
	v_mfma_f32_16x16x32_bf16 v[64:67], v[210:213], v[190:193], v[64:67]
	v_mfma_f32_16x16x32_bf16 v[120:123], v[206:209], v[170:173], v[120:123]
	v_mfma_f32_16x16x32_bf16 v[112:115], v[214:217], v[170:173], v[112:115]
	v_mfma_f32_16x16x32_bf16 v[104:107], v[206:209], v[178:181], v[104:107]
	v_mfma_f32_16x16x32_bf16 v[96:99], v[214:217], v[178:181], v[96:99]
	v_mfma_f32_16x16x32_bf16 v[88:91], v[206:209], v[186:189], v[88:91]
	v_mfma_f32_16x16x32_bf16 v[80:83], v[214:217], v[186:189], v[80:83]
	v_mfma_f32_16x16x32_bf16 v[72:75], v[206:209], v[194:197], v[72:75]
	v_mfma_f32_16x16x32_bf16 v[64:67], v[214:217], v[194:197], v[64:67]
	s_barrier
	s_setprio 0
	s_mov_b32 m0, s36
	s_add_u32 s0, s22, 0x80
	s_addc_u32 s1, s23, 0
	ds_read_b128 v[166:169], v148 offset:49152
	ds_read_b128 v[170:173], v148 offset:50176
	ds_read_b128 v[174:177], v148 offset:51200
	ds_read_b128 v[178:181], v148 offset:52224
	ds_read_b128 v[182:185], v148 offset:53248
	ds_read_b128 v[186:189], v148 offset:54272
	ds_read_b128 v[190:193], v148 offset:55296
	ds_read_b128 v[194:197], v148 offset:56320
	global_load_lds_dwordx4 v134, s[0:1]
	s_mov_b32 m0, s37
	s_nop 0
	global_load_lds_dwordx4 v130, s[0:1]
	s_setprio 1
	s_barrier
; #define PG8_STAGE(bufoff, gbase, voff) do { _Pragma("unroll") for (int _i = 0; _i < 2; ++_i) \
;         __builtin_amdgcn_global_load_lds((const unsigned*)((const char*)(gbase) + (voff)[_i]), (LAS unsigned*)(lds + (bufoff) + ldsw + _i * 8192), 16, 0, 0); } while (0)
; #define PG8_LDA(dst, b, h) do { _Pragma("unroll") for (int m = 0; m < 4; ++m) _Pragma("unroll") for (int k = 0; k < 2; ++k) dst[m][k] = *(const LAS bf16x8*)(lds + PG8_SA(b, h) + aoff + m * 2048 + k * 1024); } while (0)
; #define PG8_WAIT_V(n) asm volatile("s_waitcnt vmcnt(" #n ")" ::: "memory")
; #define PG8_WAIT_L(n) asm volatile("s_waitcnt lgkmcnt(" #n ")" ::: "memory")
; template <class Epi, class Sched>
; __device__ __forceinline__ void gemm_phase(LAS unsigned char* lds, const Gemm g, const Sched& S, const Epi& E) {
;     ...
;         for (int t = 0; t < nt; t += 2) {
;             const bool last = (t == nt - 2);
;             const char* a1 = cA + (size_t)(t + 1) * kstep;
;             const char* a2 = last ? nA : cA + (size_t)(t + 2) * kstep; const char* b2 = last ? nB : cB + (size_t)(t + 2) * kstep;
;             const char* a3 = a2 + kstep; const char* b3 = b2 + kstep;
;             PG8_LDB(B0, 0, 0); PG8_SCHED; PG8_LDA(At, 0, 0); PG8_STAGE(PG8_SA(1, 1), a1 + hstep, voffA);
;             PG8_WAIT_L(8); PG8_BAR; PG8_WAIT_L(0); PG8_MMA(0, 0, At, B0); PG8_BAR; PG8_SCHED;
;             PG8_LDB(B1, 0, 1); PG8_STAGE(PG8_SB(0, 0), b2, voffB);
;             PG8_BAR; PG8_WAIT_L(0); PG8_MMA(0, 1, At, B1); PG8_BAR;
;             PG8_LDA(At, 0, 1); PG8_STAGE(PG8_SA(0, 0), a2, voffA);
;             PG8_BAR; PG8_WAIT_L(0); PG8_MMA(1, 0, At, B0); PG8_BAR; PG8_SCHED;
;             PG8_STAGE(PG8_SB(0, 1), b2 + hstep, voffB);
;             PG8_WAIT_V(6); PG8_BAR; PG8_MMA(1, 1, At, B1); PG8_BAR;
;             PG8_LDB(B0, 1, 0); PG8_SCHED; PG8_LDA(At, 1, 0); PG8_STAGE(PG8_SA(0, 1), a2 + hstep, voffA);
;             PG8_WAIT_L(8); PG8_BAR; PG8_WAIT_L(0); PG8_MMA(0, 0, At, B0); PG8_BAR; PG8_SCHED;
;             PG8_LDB(B1, 1, 1); PG8_STAGE(PG8_SB(1, 0), b3, voffB);
;             PG8_BAR; PG8_WAIT_L(0); PG8_MMA(0, 1, At, B1); PG8_BAR;
;             PG8_LDA(At, 1, 1); PG8_STAGE(PG8_SA(1, 0), a3, voffA);
;             PG8_BAR; PG8_WAIT_L(0); PG8_MMA(1, 0, At, B0); PG8_BAR; PG8_SCHED;
;             PG8_STAGE(PG8_SB(1, 1), b3 + hstep, voffB);
;             PG8_WAIT_V(6); PG8_BAR; PG8_MMA(1, 1, At, B1); PG8_BAR;
	s_waitcnt lgkmcnt(0)
	v_mfma_f32_16x16x32_bf16 v[60:63], v[150:153], v[166:169], v[60:63]
	v_mfma_f32_16x16x32_bf16 v[56:59], v[158:161], v[166:169], v[56:59]
	v_mfma_f32_16x16x32_bf16 v[44:47], v[150:153], v[174:177], v[44:47]
	v_mfma_f32_16x16x32_bf16 v[40:43], v[158:161], v[174:177], v[40:43]
	v_mfma_f32_16x16x32_bf16 v[28:31], v[150:153], v[182:185], v[28:31]
	v_mfma_f32_16x16x32_bf16 v[24:27], v[158:161], v[182:185], v[24:27]
	v_mfma_f32_16x16x32_bf16 v[12:15], v[150:153], v[190:193], v[12:15]
	v_mfma_f32_16x16x32_bf16 v[8:11], v[158:161], v[190:193], v[8:11]
	v_mfma_f32_16x16x32_bf16 v[60:63], v[154:157], v[170:173], v[60:63]
	v_mfma_f32_16x16x32_bf16 v[56:59], v[162:165], v[170:173], v[56:59]
	v_mfma_f32_16x16x32_bf16 v[44:47], v[154:157], v[178:181], v[44:47]
	v_mfma_f32_16x16x32_bf16 v[40:43], v[162:165], v[178:181], v[40:43]
	v_mfma_f32_16x16x32_bf16 v[28:31], v[154:157], v[186:189], v[28:31]
	v_mfma_f32_16x16x32_bf16 v[24:27], v[162:165], v[186:189], v[24:27]
	v_mfma_f32_16x16x32_bf16 v[12:15], v[154:157], v[194:197], v[12:15]
	v_mfma_f32_16x16x32_bf16 v[8:11], v[162:165], v[194:197], v[8:11]
	s_barrier
	s_setprio 0
	s_add_u32 s16, s18, 0x40080
	s_addc_u32 s17, s19, 0
	s_add_i32 s18, s21, s25
	s_mov_b32 m0, s18
	s_nop 0
	global_load_lds_dwordx4 v132, s[16:17]
	s_add_i32 m0, s18, 0x2000
	s_nop 0
	global_load_lds_dwordx4 v128, s[16:17]
	s_waitcnt vmcnt(8)
	s_setprio 1
	s_barrier
	v_mfma_f32_16x16x32_bf16 v[52:55], v[202:205], v[166:169], v[52:55]
	v_mfma_f32_16x16x32_bf16 v[48:51], v[210:213], v[166:169], v[48:51]
	v_mfma_f32_16x16x32_bf16 v[36:39], v[202:205], v[174:177], v[36:39]
	v_mfma_f32_16x16x32_bf16 v[32:35], v[210:213], v[174:177], v[32:35]
	v_mfma_f32_16x16x32_bf16 v[20:23], v[202:205], v[182:185], v[20:23]
	v_mfma_f32_16x16x32_bf16 v[16:19], v[210:213], v[182:185], v[16:19]
	v_mfma_f32_16x16x32_bf16 v[4:7], v[202:205], v[190:193], v[4:7]
	v_mfma_f32_16x16x32_bf16 v[0:3], v[210:213], v[190:193], v[0:3]
	v_mfma_f32_16x16x32_bf16 v[52:55], v[206:209], v[170:173], v[52:55]
	v_mfma_f32_16x16x32_bf16 v[48:51], v[214:217], v[170:173], v[48:51]
	v_mfma_f32_16x16x32_bf16 v[36:39], v[206:209], v[178:181], v[36:39]
	v_mfma_f32_16x16x32_bf16 v[32:35], v[214:217], v[178:181], v[32:35]
	v_mfma_f32_16x16x32_bf16 v[20:23], v[206:209], v[186:189], v[20:23]
	v_mfma_f32_16x16x32_bf16 v[16:19], v[214:217], v[186:189], v[16:19]
	v_mfma_f32_16x16x32_bf16 v[4:7], v[206:209], v[194:197], v[4:7]
	v_mfma_f32_16x16x32_bf16 v[0:3], v[214:217], v[194:197], v[0:3]
	s_barrier
	s_setprio 0
	s_add_i32 s48, s48, 2
	s_add_u32 s14, s14, 0x100
	s_addc_u32 s15, s15, 0
	s_add_u32 s46, s46, 0x100
	s_addc_u32 s47, s47, 0
	s_cmp_gt_u32 s48, 13
.LBB0_235:
	ds_read_b128 v[150:153], v147
	ds_read_b128 v[154:157], v147 offset:1024
	ds_read_b128 v[158:161], v147 offset:2048
	ds_read_b128 v[162:165], v147 offset:3072
	s_add_u32 s16, s14, 0xfffc0080
	s_addc_u32 s17, s15, -1
	s_cmp_eq_u32 s48, 12
	s_cselect_b32 s23, s7, s17
	s_cselect_b32 s22, s44, s16
	s_cselect_b32 s19, s5, s47
	s_cselect_b32 s18, s45, s46
	s_add_i32 m0, s13, 0xc000
	ds_read_b128 v[166:169], v148
	ds_read_b128 v[170:173], v148 offset:1024
	ds_read_b128 v[174:177], v148 offset:2048
	ds_read_b128 v[178:181], v148 offset:3072
	ds_read_b128 v[182:185], v148 offset:4096
	ds_read_b128 v[186:189], v148 offset:5120
	ds_read_b128 v[190:193], v148 offset:6144
	ds_read_b128 v[194:197], v148 offset:7168
	global_load_lds_dwordx4 v136, s[14:15]
	s_add_i32 m0, s13, 0xe000
	s_nop 0
	global_load_lds_dwordx4 v138, s[14:15]
	s_waitcnt lgkmcnt(8)
	s_waitcnt vmcnt(8)
	s_setprio 1
	s_barrier
	s_waitcnt lgkmcnt(0)
	v_mfma_f32_16x16x32_bf16 v[124:127], v[150:153], v[166:169], v[124:127]
	v_mfma_f32_16x16x32_bf16 v[116:119], v[158:161], v[166:169], v[116:119]
	v_mfma_f32_16x16x32_bf16 v[108:111], v[150:153], v[174:177], v[108:111]
	v_mfma_f32_16x16x32_bf16 v[100:103], v[158:161], v[174:177], v[100:103]
	v_mfma_f32_16x16x32_bf16 v[92:95], v[150:153], v[182:185], v[92:95]
	v_mfma_f32_16x16x32_bf16 v[84:87], v[158:161], v[182:185], v[84:87]
	v_mfma_f32_16x16x32_bf16 v[76:79], v[150:153], v[190:193], v[76:79]
	v_mfma_f32_16x16x32_bf16 v[68:71], v[158:161], v[190:193], v[68:71]
	v_mfma_f32_16x16x32_bf16 v[124:127], v[154:157], v[170:173], v[124:127]
	v_mfma_f32_16x16x32_bf16 v[116:119], v[162:165], v[170:173], v[116:119]
	v_mfma_f32_16x16x32_bf16 v[108:111], v[154:157], v[178:181], v[108:111]
	v_mfma_f32_16x16x32_bf16 v[100:103], v[162:165], v[178:181], v[100:103]
	v_mfma_f32_16x16x32_bf16 v[92:95], v[154:157], v[186:189], v[92:95]
	v_mfma_f32_16x16x32_bf16 v[84:87], v[162:165], v[186:189], v[84:87]
	v_mfma_f32_16x16x32_bf16 v[76:79], v[154:157], v[194:197], v[76:79]
	v_mfma_f32_16x16x32_bf16 v[68:71], v[162:165], v[194:197], v[68:71]
	s_barrier
	s_setprio 0
	s_add_i32 s16, s40, s25
	s_mov_b32 m0, s16
	ds_read_b128 v[202:205], v149
	ds_read_b128 v[206:209], v149 offset:1024
	ds_read_b128 v[210:213], v149 offset:2048
	ds_read_b128 v[214:217], v149 offset:3072
	global_load_lds_dwordx4 v132, s[18:19]
	s_add_i32 m0, s16, 0x2000
	s_nop 0
	global_load_lds_dwordx4 v128, s[18:19]
	s_waitcnt vmcnt(8)
	s_setprio 1
	s_barrier
; #define PG8_STAGE(bufoff, gbase, voff) do { _Pragma("unroll") for (int _i = 0; _i < 2; ++_i) \
;         __builtin_amdgcn_global_load_lds((const unsigned*)((const char*)(gbase) + (voff)[_i]), (LAS unsigned*)(lds + (bufoff) + ldsw + _i * 8192), 16, 0, 0); } while (0)
; #define PG8_LDA(dst, b, h) do { _Pragma("unroll") for (int m = 0; m < 4; ++m) _Pragma("unroll") for (int k = 0; k < 2; ++k) dst[m][k] = *(const LAS bf16x8*)(lds + PG8_SA(b, h) + aoff + m * 2048 + k * 1024); } while (0)
; #define PG8_LDB(dst, b, h) do { _Pragma("unroll") for (int n = 0; n < 2; ++n) _Pragma("unroll") for (int k = 0; k < 2; ++k) dst[n][k] = *(const LAS bf16x8*)(lds + PG8_SB(b, h) + boff + n * 2048 + k * 1024); } while (0)
; #define PG8_WAIT_V(n) asm volatile("s_waitcnt vmcnt(" #n ")" ::: "memory")
; #define PG8_WAIT_L(n) asm volatile("s_waitcnt lgkmcnt(" #n ")" ::: "memory")
; #define PG8_BAR __builtin_amdgcn_s_barrier()
; #define PG8_SCHED __builtin_amdgcn_sched_barrier(0)
; template <class Epi, class Sched>
; __device__ __forceinline__ void gemm_phase(LAS unsigned char* lds, const Gemm g, const Sched& S, const Epi& E) {
;     ...
;             PG8_LDB(B0, 0, 0); PG8_SCHED; PG8_LDA(At, 0, 0); PG8_STAGE(PG8_SA(1, 1), a1 + hstep, voffA);
;             PG8_WAIT_L(8); PG8_BAR; PG8_WAIT_L(0); PG8_MMA(0, 0, At, B0); PG8_BAR; PG8_SCHED;
;             PG8_LDB(B1, 0, 1); PG8_STAGE(PG8_SB(0, 0), b2, voffB);
;             PG8_BAR; PG8_WAIT_L(0); PG8_MMA(0, 1, At, B1); PG8_BAR;
;             PG8_LDA(At, 0, 1); PG8_STAGE(PG8_SA(0, 0), a2, voffA);
;             PG8_BAR; PG8_WAIT_L(0); PG8_MMA(1, 0, At, B0); PG8_BAR; PG8_SCHED;
;             PG8_STAGE(PG8_SB(0, 1), b2 + hstep, voffB);
;             PG8_WAIT_V(6); PG8_BAR; PG8_MMA(1, 1, At, B1); PG8_BAR;
;             PG8_LDB(B0, 1, 0); PG8_SCHED; PG8_LDA(At, 1, 0); PG8_STAGE(PG8_SA(0, 1), a2 + hstep, voffA);
;             PG8_WAIT_L(8); PG8_BAR; PG8_WAIT_L(0); PG8_MMA(0, 0, At, B0); PG8_BAR; PG8_SCHED;
;             PG8_LDB(B1, 1, 1); PG8_STAGE(PG8_SB(1, 0), b3, voffB);
;             PG8_BAR; PG8_WAIT_L(0); PG8_MMA(0, 1, At, B1); PG8_BAR;
;             PG8_LDA(At, 1, 1); PG8_STAGE(PG8_SA(1, 0), a3, voffA);
;             PG8_BAR; PG8_WAIT_L(0); PG8_MMA(1, 0, At, B0); PG8_BAR; PG8_SCHED;
;             PG8_STAGE(PG8_SB(1, 1), b3 + hstep, voffB);
;             PG8_WAIT_V(6); PG8_BAR; PG8_MMA(1, 1, At, B1); PG8_BAR;
	s_waitcnt lgkmcnt(0)
	v_mfma_f32_16x16x32_bf16 v[120:123], v[202:205], v[166:169], v[120:123]
	v_mfma_f32_16x16x32_bf16 v[112:115], v[210:213], v[166:169], v[112:115]
	v_mfma_f32_16x16x32_bf16 v[104:107], v[202:205], v[174:177], v[104:107]
	v_mfma_f32_16x16x32_bf16 v[96:99], v[210:213], v[174:177], v[96:99]
	v_mfma_f32_16x16x32_bf16 v[88:91], v[202:205], v[182:185], v[88:91]
	v_mfma_f32_16x16x32_bf16 v[80:83], v[210:213], v[182:185], v[80:83]
	v_mfma_f32_16x16x32_bf16 v[72:75], v[202:205], v[190:193], v[72:75]
	v_mfma_f32_16x16x32_bf16 v[64:67], v[210:213], v[190:193], v[64:67]
	v_mfma_f32_16x16x32_bf16 v[120:123], v[206:209], v[170:173], v[120:123]
	v_mfma_f32_16x16x32_bf16 v[112:115], v[214:217], v[170:173], v[112:115]
	v_mfma_f32_16x16x32_bf16 v[104:107], v[206:209], v[178:181], v[104:107]
	v_mfma_f32_16x16x32_bf16 v[96:99], v[214:217], v[178:181], v[96:99]
	v_mfma_f32_16x16x32_bf16 v[88:91], v[206:209], v[186:189], v[88:91]
	v_mfma_f32_16x16x32_bf16 v[80:83], v[214:217], v[186:189], v[80:83]
	v_mfma_f32_16x16x32_bf16 v[72:75], v[206:209], v[194:197], v[72:75]
	v_mfma_f32_16x16x32_bf16 v[64:67], v[214:217], v[194:197], v[64:67]
	s_barrier
	s_setprio 0
	s_mov_b32 m0, s13
	ds_read_b128 v[166:169], v148 offset:16384
	ds_read_b128 v[170:173], v148 offset:17408
	ds_read_b128 v[174:177], v148 offset:18432
	ds_read_b128 v[178:181], v148 offset:19456
	ds_read_b128 v[182:185], v148 offset:20480
	ds_read_b128 v[186:189], v148 offset:21504
	ds_read_b128 v[190:193], v148 offset:22528
	ds_read_b128 v[194:197], v148 offset:23552
	global_load_lds_dwordx4 v134, s[22:23]
	s_mov_b32 m0, s28
	s_nop 0
	global_load_lds_dwordx4 v130, s[22:23]
	s_setprio 1
	s_barrier
	s_waitcnt lgkmcnt(0)
	v_mfma_f32_16x16x32_bf16 v[60:63], v[150:153], v[166:169], v[60:63]
	v_mfma_f32_16x16x32_bf16 v[56:59], v[158:161], v[166:169], v[56:59]
	v_mfma_f32_16x16x32_bf16 v[44:47], v[150:153], v[174:177], v[44:47]
	v_mfma_f32_16x16x32_bf16 v[40:43], v[158:161], v[174:177], v[40:43]
	v_mfma_f32_16x16x32_bf16 v[28:31], v[150:153], v[182:185], v[28:31]
	v_mfma_f32_16x16x32_bf16 v[24:27], v[158:161], v[182:185], v[24:27]
	v_mfma_f32_16x16x32_bf16 v[12:15], v[150:153], v[190:193], v[12:15]
	v_mfma_f32_16x16x32_bf16 v[8:11], v[158:161], v[190:193], v[8:11]
	v_mfma_f32_16x16x32_bf16 v[60:63], v[154:157], v[170:173], v[60:63]
	v_mfma_f32_16x16x32_bf16 v[56:59], v[162:165], v[170:173], v[56:59]
	v_mfma_f32_16x16x32_bf16 v[44:47], v[154:157], v[178:181], v[44:47]
	v_mfma_f32_16x16x32_bf16 v[40:43], v[162:165], v[178:181], v[40:43]
	v_mfma_f32_16x16x32_bf16 v[28:31], v[154:157], v[186:189], v[28:31]
	v_mfma_f32_16x16x32_bf16 v[24:27], v[162:165], v[186:189], v[24:27]
	v_mfma_f32_16x16x32_bf16 v[12:15], v[154:157], v[194:197], v[12:15]
	v_mfma_f32_16x16x32_bf16 v[8:11], v[162:165], v[194:197], v[8:11]
	s_barrier
	s_setprio 0
	s_add_u32 s16, s18, 0x40000
	s_addc_u32 s17, s19, 0
	s_add_i32 s20, s41, s25
	s_mov_b32 m0, s20
	s_nop 0
	global_load_lds_dwordx4 v132, s[16:17]
	s_add_i32 m0, s20, 0x2000
	s_nop 0
	global_load_lds_dwordx4 v128, s[16:17]
	s_add_u32 s16, s22, 0x40000
	s_addc_u32 s17, s23, 0
	s_mov_b32 m0, s29
	s_nop 0
	global_load_lds_dwordx4 v134, s[16:17]
	s_mov_b32 m0, s33
	s_nop 0
	global_load_lds_dwordx4 v130, s[16:17]
	s_waitcnt vmcnt(10)
	s_setprio 1
	s_barrier
	v_mfma_f32_16x16x32_bf16 v[52:55], v[202:205], v[166:169], v[52:55]
	v_mfma_f32_16x16x32_bf16 v[48:51], v[210:213], v[166:169], v[48:51]
	v_mfma_f32_16x16x32_bf16 v[36:39], v[202:205], v[174:177], v[36:39]
	v_mfma_f32_16x16x32_bf16 v[32:35], v[210:213], v[174:177], v[32:35]
	v_mfma_f32_16x16x32_bf16 v[20:23], v[202:205], v[182:185], v[20:23]
	v_mfma_f32_16x16x32_bf16 v[16:19], v[210:213], v[182:185], v[16:19]
	v_mfma_f32_16x16x32_bf16 v[4:7], v[202:205], v[190:193], v[4:7]
	v_mfma_f32_16x16x32_bf16 v[0:3], v[210:213], v[190:193], v[0:3]
	v_mfma_f32_16x16x32_bf16 v[52:55], v[206:209], v[170:173], v[52:55]
	v_mfma_f32_16x16x32_bf16 v[48:51], v[214:217], v[170:173], v[48:51]
	v_mfma_f32_16x16x32_bf16 v[36:39], v[206:209], v[178:181], v[36:39]
	v_mfma_f32_16x16x32_bf16 v[32:35], v[214:217], v[178:181], v[32:35]
	v_mfma_f32_16x16x32_bf16 v[20:23], v[206:209], v[186:189], v[20:23]
	v_mfma_f32_16x16x32_bf16 v[16:19], v[214:217], v[186:189], v[16:19]
	v_mfma_f32_16x16x32_bf16 v[4:7], v[206:209], v[194:197], v[4:7]
	v_mfma_f32_16x16x32_bf16 v[0:3], v[214:217], v[194:197], v[0:3]
	s_barrier
	s_setprio 0
	s_add_i32 s20, 0, 0x18000
	v_add_u32_e32 v162, s20, v146
	ds_read_b128 v[150:153], v162
	ds_read_b128 v[154:157], v162 offset:1024
	ds_read_b128 v[158:161], v162 offset:2048
	ds_read_b128 v[162:165], v162 offset:3072
	ds_read_b128 v[166:169], v148 offset:32768
	ds_read_b128 v[170:173], v148 offset:33792
	ds_read_b128 v[174:177], v148 offset:34816
	ds_read_b128 v[178:181], v148 offset:35840
	ds_read_b128 v[182:185], v148 offset:36864
	ds_read_b128 v[186:189], v148 offset:37888
	ds_read_b128 v[190:193], v148 offset:38912
	ds_read_b128 v[194:197], v148 offset:39936
	s_waitcnt lgkmcnt(8)
	s_waitcnt vmcnt(8)
	s_setprio 1
	s_barrier
; #define PG8_STAGE(bufoff, gbase, voff) do { _Pragma("unroll") for (int _i = 0; _i < 2; ++_i) \
;         __builtin_amdgcn_global_load_lds((const unsigned*)((const char*)(gbase) + (voff)[_i]), (LAS unsigned*)(lds + (bufoff) + ldsw + _i * 8192), 16, 0, 0); } while (0)
; #define PG8_LDA(dst, b, h) do { _Pragma("unroll") for (int m = 0; m < 4; ++m) _Pragma("unroll") for (int k = 0; k < 2; ++k) dst[m][k] = *(const LAS bf16x8*)(lds + PG8_SA(b, h) + aoff + m * 2048 + k * 1024); } while (0)
; #define PG8_LDB(dst, b, h) do { _Pragma("unroll") for (int n = 0; n < 2; ++n) _Pragma("unroll") for (int k = 0; k < 2; ++k) dst[n][k] = *(const LAS bf16x8*)(lds + PG8_SB(b, h) + boff + n * 2048 + k * 1024); } while (0)
; #define PG8_WAIT_V(n) asm volatile("s_waitcnt vmcnt(" #n ")" ::: "memory")
; #define PG8_WAIT_L(n) asm volatile("s_waitcnt lgkmcnt(" #n ")" ::: "memory")
; #define PG8_BAR __builtin_amdgcn_s_barrier()
; #define PG8_SCHED __builtin_amdgcn_sched_barrier(0)
; template <class Epi, class Sched>
; __device__ __forceinline__ void gemm_phase(LAS unsigned char* lds, const Gemm g, const Sched& S, const Epi& E) {
;     ...
;             PG8_LDB(B0, 0, 0); PG8_SCHED; PG8_LDA(At, 0, 0); PG8_STAGE(PG8_SA(1, 1), a1 + hstep, voffA);
;             PG8_WAIT_L(8); PG8_BAR; PG8_WAIT_L(0); PG8_MMA(0, 0, At, B0); PG8_BAR; PG8_SCHED;
;             PG8_LDB(B1, 0, 1); PG8_STAGE(PG8_SB(0, 0), b2, voffB);
;             PG8_BAR; PG8_WAIT_L(0); PG8_MMA(0, 1, At, B1); PG8_BAR;
;             PG8_LDA(At, 0, 1); PG8_STAGE(PG8_SA(0, 0), a2, voffA);
;             PG8_BAR; PG8_WAIT_L(0); PG8_MMA(1, 0, At, B0); PG8_BAR; PG8_SCHED;
;             PG8_STAGE(PG8_SB(0, 1), b2 + hstep, voffB);
;             PG8_WAIT_V(6); PG8_BAR; PG8_MMA(1, 1, At, B1); PG8_BAR;
;             PG8_LDB(B0, 1, 0); PG8_SCHED; PG8_LDA(At, 1, 0); PG8_STAGE(PG8_SA(0, 1), a2 + hstep, voffA);
;             PG8_WAIT_L(8); PG8_BAR; PG8_WAIT_L(0); PG8_MMA(0, 0, At, B0); PG8_BAR; PG8_SCHED;
;             PG8_LDB(B1, 1, 1); PG8_STAGE(PG8_SB(1, 0), b3, voffB);
;             PG8_BAR; PG8_WAIT_L(0); PG8_MMA(0, 1, At, B1); PG8_BAR;
;             PG8_LDA(At, 1, 1); PG8_STAGE(PG8_SA(1, 0), a3, voffA);
;             PG8_BAR; PG8_WAIT_L(0); PG8_MMA(1, 0, At, B0); PG8_BAR; PG8_SCHED;
;             PG8_STAGE(PG8_SB(1, 1), b3 + hstep, voffB);
;             PG8_WAIT_V(6); PG8_BAR; PG8_MMA(1, 1, At, B1); PG8_BAR;
	s_waitcnt lgkmcnt(0)
	v_mfma_f32_16x16x32_bf16 v[124:127], v[150:153], v[166:169], v[124:127]
	v_mfma_f32_16x16x32_bf16 v[116:119], v[158:161], v[166:169], v[116:119]
	v_mfma_f32_16x16x32_bf16 v[108:111], v[150:153], v[174:177], v[108:111]
	v_mfma_f32_16x16x32_bf16 v[100:103], v[158:161], v[174:177], v[100:103]
	v_mfma_f32_16x16x32_bf16 v[92:95], v[150:153], v[182:185], v[92:95]
	v_mfma_f32_16x16x32_bf16 v[84:87], v[158:161], v[182:185], v[84:87]
	v_mfma_f32_16x16x32_bf16 v[76:79], v[150:153], v[190:193], v[76:79]
	v_mfma_f32_16x16x32_bf16 v[68:71], v[158:161], v[190:193], v[68:71]
	v_mfma_f32_16x16x32_bf16 v[124:127], v[154:157], v[170:173], v[124:127]
	v_mfma_f32_16x16x32_bf16 v[116:119], v[162:165], v[170:173], v[116:119]
	v_mfma_f32_16x16x32_bf16 v[108:111], v[154:157], v[178:181], v[108:111]
	v_mfma_f32_16x16x32_bf16 v[100:103], v[162:165], v[178:181], v[100:103]
	v_mfma_f32_16x16x32_bf16 v[92:95], v[154:157], v[186:189], v[92:95]
	v_mfma_f32_16x16x32_bf16 v[84:87], v[162:165], v[186:189], v[84:87]
	v_mfma_f32_16x16x32_bf16 v[76:79], v[154:157], v[194:197], v[76:79]
	v_mfma_f32_16x16x32_bf16 v[68:71], v[162:165], v[194:197], v[68:71]
	s_barrier
	s_setprio 0
	s_add_i32 s21, 0, 0x1c000
	s_add_i32 s16, s20, s25
	v_add_u32_e32 v214, s21, v146
	s_add_u32 s0, s18, 0x80
	s_addc_u32 s1, s19, 0
	s_mov_b32 m0, s16
	ds_read_b128 v[202:205], v214
	ds_read_b128 v[206:209], v214 offset:1024
	ds_read_b128 v[210:213], v214 offset:2048
	ds_read_b128 v[214:217], v214 offset:3072
	global_load_lds_dwordx4 v132, s[0:1]
	s_add_i32 m0, s16, 0x2000
	s_nop 0
	global_load_lds_dwordx4 v128, s[0:1]
	s_waitcnt vmcnt(8)
	s_setprio 1
	s_barrier
	s_waitcnt lgkmcnt(0)
	v_mfma_f32_16x16x32_bf16 v[120:123], v[202:205], v[166:169], v[120:123]
	v_mfma_f32_16x16x32_bf16 v[112:115], v[210:213], v[166:169], v[112:115]
	v_mfma_f32_16x16x32_bf16 v[104:107], v[202:205], v[174:177], v[104:107]
	v_mfma_f32_16x16x32_bf16 v[96:99], v[210:213], v[174:177], v[96:99]
	v_mfma_f32_16x16x32_bf16 v[88:91], v[202:205], v[182:185], v[88:91]
	v_mfma_f32_16x16x32_bf16 v[80:83], v[210:213], v[182:185], v[80:83]
	v_mfma_f32_16x16x32_bf16 v[72:75], v[202:205], v[190:193], v[72:75]
	v_mfma_f32_16x16x32_bf16 v[64:67], v[210:213], v[190:193], v[64:67]
	v_mfma_f32_16x16x32_bf16 v[120:123], v[206:209], v[170:173], v[120:123]
	v_mfma_f32_16x16x32_bf16 v[112:115], v[214:217], v[170:173], v[112:115]
	v_mfma_f32_16x16x32_bf16 v[104:107], v[206:209], v[178:181], v[104:107]
	v_mfma_f32_16x16x32_bf16 v[96:99], v[214:217], v[178:181], v[96:99]
	v_mfma_f32_16x16x32_bf16 v[88:91], v[206:209], v[186:189], v[88:91]
	v_mfma_f32_16x16x32_bf16 v[80:83], v[214:217], v[186:189], v[80:83]
	v_mfma_f32_16x16x32_bf16 v[72:75], v[206:209], v[194:197], v[72:75]
	v_mfma_f32_16x16x32_bf16 v[64:67], v[214:217], v[194:197], v[64:67]
	s_barrier
	s_setprio 0
	s_mov_b32 m0, s36
	s_add_u32 s0, s22, 0x80
	s_addc_u32 s1, s23, 0
	ds_read_b128 v[166:169], v148 offset:49152
	ds_read_b128 v[170:173], v148 offset:50176
	ds_read_b128 v[174:177], v148 offset:51200
	ds_read_b128 v[178:181], v148 offset:52224
	ds_read_b128 v[182:185], v148 offset:53248
	ds_read_b128 v[186:189], v148 offset:54272
	ds_read_b128 v[190:193], v148 offset:55296
	ds_read_b128 v[194:197], v148 offset:56320
	global_load_lds_dwordx4 v134, s[0:1]
	s_mov_b32 m0, s37
	s_nop 0
	global_load_lds_dwordx4 v130, s[0:1]
	s_setprio 1
	s_barrier
	s_waitcnt lgkmcnt(0)
	v_mfma_f32_16x16x32_bf16 v[60:63], v[150:153], v[166:169], v[60:63]
	v_mfma_f32_16x16x32_bf16 v[56:59], v[158:161], v[166:169], v[56:59]
	v_mfma_f32_16x16x32_bf16 v[44:47], v[150:153], v[174:177], v[44:47]
	v_mfma_f32_16x16x32_bf16 v[40:43], v[158:161], v[174:177], v[40:43]
	v_mfma_f32_16x16x32_bf16 v[28:31], v[150:153], v[182:185], v[28:31]
	v_mfma_f32_16x16x32_bf16 v[24:27], v[158:161], v[182:185], v[24:27]
	v_mfma_f32_16x16x32_bf16 v[12:15], v[150:153], v[190:193], v[12:15]
	v_mfma_f32_16x16x32_bf16 v[8:11], v[158:161], v[190:193], v[8:11]
	v_mfma_f32_16x16x32_bf16 v[60:63], v[154:157], v[170:173], v[60:63]
	v_mfma_f32_16x16x32_bf16 v[56:59], v[162:165], v[170:173], v[56:59]
	v_mfma_f32_16x16x32_bf16 v[44:47], v[154:157], v[178:181], v[44:47]
	v_mfma_f32_16x16x32_bf16 v[40:43], v[162:165], v[178:181], v[40:43]
	v_mfma_f32_16x16x32_bf16 v[28:31], v[154:157], v[186:189], v[28:31]
	v_mfma_f32_16x16x32_bf16 v[24:27], v[162:165], v[186:189], v[24:27]
	v_mfma_f32_16x16x32_bf16 v[12:15], v[154:157], v[194:197], v[12:15]
	v_mfma_f32_16x16x32_bf16 v[8:11], v[162:165], v[194:197], v[8:11]
	s_barrier
	s_setprio 0
	s_add_u32 s16, s18, 0x40080
	s_addc_u32 s17, s19, 0
	s_add_i32 s18, s21, s25
	s_mov_b32 m0, s18
	s_nop 0
	global_load_lds_dwordx4 v132, s[16:17]
	s_add_i32 m0, s18, 0x2000
	s_nop 0
	global_load_lds_dwordx4 v128, s[16:17]
	s_waitcnt vmcnt(8)
	s_setprio 1
	s_barrier
	v_mfma_f32_16x16x32_bf16 v[52:55], v[202:205], v[166:169], v[52:55]
	v_mfma_f32_16x16x32_bf16 v[48:51], v[210:213], v[166:169], v[48:51]
	v_mfma_f32_16x16x32_bf16 v[36:39], v[202:205], v[174:177], v[36:39]
	v_mfma_f32_16x16x32_bf16 v[32:35], v[210:213], v[174:177], v[32:35]
	v_mfma_f32_16x16x32_bf16 v[20:23], v[202:205], v[182:185], v[20:23]
	v_mfma_f32_16x16x32_bf16 v[16:19], v[210:213], v[182:185], v[16:19]
	v_mfma_f32_16x16x32_bf16 v[4:7], v[202:205], v[190:193], v[4:7]
	v_mfma_f32_16x16x32_bf16 v[0:3], v[210:213], v[190:193], v[0:3]
	v_mfma_f32_16x16x32_bf16 v[52:55], v[206:209], v[170:173], v[52:55]
	v_mfma_f32_16x16x32_bf16 v[48:51], v[214:217], v[170:173], v[48:51]
	v_mfma_f32_16x16x32_bf16 v[36:39], v[206:209], v[178:181], v[36:39]
	v_mfma_f32_16x16x32_bf16 v[32:35], v[214:217], v[178:181], v[32:35]
	v_mfma_f32_16x16x32_bf16 v[20:23], v[206:209], v[186:189], v[20:23]
	v_mfma_f32_16x16x32_bf16 v[16:19], v[214:217], v[186:189], v[16:19]
	v_mfma_f32_16x16x32_bf16 v[4:7], v[206:209], v[194:197], v[4:7]
	v_mfma_f32_16x16x32_bf16 v[0:3], v[214:217], v[194:197], v[0:3]
	s_setprio 0
	s_add_i32 s48, s48, 2
	s_add_u32 s14, s14, 0x100
	s_addc_u32 s15, s15, 0
	s_add_u32 s46, s46, 0x100
	s_addc_u32 s47, s47, 0
	s_cmp_gt_u32 s48, 13
	s_cbranch_scc1 .Lconc_last_g0
	s_barrier
	s_branch .LBB0_235

; #define PG8_STAGE(bufoff, gbase, voff) do { _Pragma("unroll") for (int _i = 0; _i < 2; ++_i) \
;         __builtin_amdgcn_global_load_lds((const unsigned*)((const char*)(gbase) + (voff)[_i]), (LAS unsigned*)(lds + (bufoff) + ldsw + _i * 8192), 16, 0, 0); } while (0)
; #define PG8_LDA(dst, b, h) do { _Pragma("unroll") for (int m = 0; m < 4; ++m) _Pragma("unroll") for (int k = 0; k < 2; ++k) dst[m][k] = *(const LAS bf16x8*)(lds + PG8_SA(b, h) + aoff + m * 2048 + k * 1024); } while (0)
; template <class Epi, class Sched>
; __device__ __forceinline__ void gemm_phase(LAS unsigned char* lds, const Gemm g, const Sched& S, const Epi& E) {
;     ...
;         const char* nA = has_next ? (const char*)g.A + (size_t)nxt.pm * tstep : cA; const char* nB = has_next ? (const char*)g.Bt + (size_t)nxt.pn * tstep : cB;
;         for (int t = 0; t < nt; t += 2) {
;             const bool last = (t == nt - 2);
;             const char* a1 = cA + (size_t)(t + 1) * kstep;
;             const char* a2 = last ? nA : cA + (size_t)(t + 2) * kstep; const char* b2 = last ? nB : cB + (size_t)(t + 2) * kstep;
;             const char* a3 = a2 + kstep; const char* b3 = b2 + kstep;
;             PG8_LDB(B0, 0, 0); PG8_SCHED; PG8_LDA(At, 0, 0); PG8_STAGE(PG8_SA(1, 1), a1 + hstep, voffA);
;             PG8_WAIT_L(8); PG8_BAR; PG8_WAIT_L(0); PG8_MMA(0, 0, At, B0); PG8_BAR; PG8_SCHED;
;             PG8_LDB(B1, 0, 1); PG8_STAGE(PG8_SB(0, 0), b2, voffB);
;             PG8_BAR; PG8_WAIT_L(0); PG8_MMA(0, 1, At, B1); PG8_BAR;
;             PG8_LDA(At, 0, 1); PG8_STAGE(PG8_SA(0, 0), a2, voffA);
;             PG8_BAR; PG8_WAIT_L(0); PG8_MMA(1, 0, At, B0); PG8_BAR; PG8_SCHED;
;             PG8_STAGE(PG8_SB(0, 1), b2 + hstep, voffB);
;             PG8_WAIT_V(6); PG8_BAR; PG8_MMA(1, 1, At, B1); PG8_BAR;
;             PG8_LDB(B0, 1, 0); PG8_SCHED; PG8_LDA(At, 1, 0); PG8_STAGE(PG8_SA(0, 1), a2 + hstep, voffA);
;             PG8_WAIT_L(8); PG8_BAR; PG8_WAIT_L(0); PG8_MMA(0, 0, At, B0); PG8_BAR; PG8_SCHED;
;             PG8_LDB(B1, 1, 1); PG8_STAGE(PG8_SB(1, 0), b3, voffB);
;             PG8_BAR; PG8_WAIT_L(0); PG8_MMA(0, 1, At, B1); PG8_BAR;
;             PG8_LDA(At, 1, 1); PG8_STAGE(PG8_SA(1, 0), a3, voffA);
;             PG8_BAR; PG8_WAIT_L(0); PG8_MMA(1, 0, At, B0); PG8_BAR; PG8_SCHED;
;             PG8_STAGE(PG8_SB(1, 1), b3 + hstep, voffB);
;             PG8_WAIT_V(6); PG8_BAR; PG8_MMA(1, 1, At, B1); PG8_BAR;
.LBB0_304:
	s_add_u32 s0, s28, 0x100
	s_addc_u32 s67, s29, 0
	s_mov_b32 s68, -2
	ds_read_b128 v[144:147], v165
	ds_read_b128 v[148:151], v165 offset:1024
	ds_read_b128 v[152:155], v165 offset:2048
	ds_read_b128 v[156:159], v165 offset:3072
	s_add_u32 s28, s26, 0x100
	s_addc_u32 s29, s27, 0
	s_cmp_eq_u32 s68, 40
	s_cselect_b32 s37, s5, s29
	s_cselect_b32 s36, s4, s28
	s_cselect_b32 s35, s7, s67
	s_cselect_b32 s34, s6, s0
	v_lshl_add_u64 v[160:161], s[26:27], 0, v[136:137]
	s_add_i32 m0, s42, 0xc000
	ds_read_b128 v[168:171], v166
	ds_read_b128 v[172:175], v166 offset:1024
	ds_read_b128 v[176:179], v166 offset:2048
	ds_read_b128 v[180:183], v166 offset:3072
	ds_read_b128 v[184:187], v166 offset:4096
	ds_read_b128 v[188:191], v166 offset:5120
	ds_read_b128 v[192:195], v166 offset:6144
	ds_read_b128 v[196:199], v166 offset:7168
	global_load_lds_dwordx4 v[160:161], off
	v_lshl_add_u64 v[160:161], s[26:27], 0, v[138:139]
	s_add_i32 m0, s42, 0xe000
	s_nop 0
	global_load_lds_dwordx4 v[160:161], off
	s_waitcnt lgkmcnt(8)
	s_waitcnt vmcnt(8)
	s_setprio 1
	s_barrier
	s_waitcnt lgkmcnt(0)
	v_mfma_f32_16x16x32_bf16 v[124:127], v[144:147], v[168:171], 0
	v_mfma_f32_16x16x32_bf16 v[120:123], v[152:155], v[168:171], 0
	v_mfma_f32_16x16x32_bf16 v[116:119], v[144:147], v[176:179], 0
	v_mfma_f32_16x16x32_bf16 v[104:107], v[152:155], v[176:179], 0
	v_mfma_f32_16x16x32_bf16 v[96:99], v[144:147], v[184:187], 0
	v_mfma_f32_16x16x32_bf16 v[88:91], v[152:155], v[184:187], 0
	v_mfma_f32_16x16x32_bf16 v[80:83], v[144:147], v[192:195], 0
	v_mfma_f32_16x16x32_bf16 v[72:75], v[152:155], v[192:195], 0
	v_mfma_f32_16x16x32_bf16 v[124:127], v[148:151], v[172:175], v[124:127]
	v_mfma_f32_16x16x32_bf16 v[120:123], v[156:159], v[172:175], v[120:123]
	v_mfma_f32_16x16x32_bf16 v[116:119], v[148:151], v[180:183], v[116:119]
	v_mfma_f32_16x16x32_bf16 v[104:107], v[156:159], v[180:183], v[104:107]
	v_mfma_f32_16x16x32_bf16 v[96:99], v[148:151], v[188:191], v[96:99]
	v_mfma_f32_16x16x32_bf16 v[88:91], v[156:159], v[188:191], v[88:91]
	v_mfma_f32_16x16x32_bf16 v[80:83], v[148:151], v[196:199], v[80:83]
	v_mfma_f32_16x16x32_bf16 v[72:75], v[156:159], v[196:199], v[72:75]
	s_barrier
	s_setprio 0
	s_add_i32 s16, s58, s40
	s_mov_b32 m0, s16
	ds_read_b128 v[202:205], v167
	ds_read_b128 v[206:209], v167 offset:1024
	ds_read_b128 v[210:213], v167 offset:2048
	ds_read_b128 v[214:217], v167 offset:3072
	global_load_lds_dwordx4 v132, s[34:35]
	s_add_i32 m0, s16, 0x2000
	s_nop 0
	global_load_lds_dwordx4 v128, s[34:35]
	s_waitcnt vmcnt(8)
	s_setprio 1
	s_barrier
	s_waitcnt lgkmcnt(0)
	v_mfma_f32_16x16x32_bf16 v[112:115], v[202:205], v[168:171], 0
	v_mfma_f32_16x16x32_bf16 v[108:111], v[210:213], v[168:171], 0
	v_mfma_f32_16x16x32_bf16 v[100:103], v[202:205], v[176:179], 0
	v_mfma_f32_16x16x32_bf16 v[92:95], v[210:213], v[176:179], 0
	v_mfma_f32_16x16x32_bf16 v[84:87], v[202:205], v[184:187], 0
	v_mfma_f32_16x16x32_bf16 v[76:79], v[210:213], v[184:187], 0
	v_mfma_f32_16x16x32_bf16 v[68:71], v[202:205], v[192:195], 0
	v_mfma_f32_16x16x32_bf16 v[64:67], v[210:213], v[192:195], 0
	v_mfma_f32_16x16x32_bf16 v[112:115], v[206:209], v[172:175], v[112:115]
	v_mfma_f32_16x16x32_bf16 v[108:111], v[214:217], v[172:175], v[108:111]
	v_mfma_f32_16x16x32_bf16 v[100:103], v[206:209], v[180:183], v[100:103]
	v_mfma_f32_16x16x32_bf16 v[92:95], v[214:217], v[180:183], v[92:95]
	v_mfma_f32_16x16x32_bf16 v[84:87], v[206:209], v[188:191], v[84:87]
	v_mfma_f32_16x16x32_bf16 v[76:79], v[214:217], v[188:191], v[76:79]
	v_mfma_f32_16x16x32_bf16 v[68:71], v[206:209], v[196:199], v[68:71]
	v_mfma_f32_16x16x32_bf16 v[64:67], v[214:217], v[196:199], v[64:67]
	s_barrier
	s_setprio 0
	s_mov_b32 m0, s42
	ds_read_b128 v[168:171], v166 offset:16384
	ds_read_b128 v[172:175], v166 offset:17408
	ds_read_b128 v[176:179], v166 offset:18432
	ds_read_b128 v[180:183], v166 offset:19456
	ds_read_b128 v[184:187], v166 offset:20480
	ds_read_b128 v[188:191], v166 offset:21504
	ds_read_b128 v[192:195], v166 offset:22528
	ds_read_b128 v[196:199], v166 offset:23552
	global_load_lds_dwordx4 v134, s[36:37]
	s_mov_b32 m0, s43
	s_nop 0
	global_load_lds_dwordx4 v130, s[36:37]
	s_setprio 1
	s_barrier
	s_waitcnt lgkmcnt(0)
	v_mfma_f32_16x16x32_bf16 v[60:63], v[144:147], v[168:171], 0
	v_mfma_f32_16x16x32_bf16 v[56:59], v[152:155], v[168:171], 0
	v_mfma_f32_16x16x32_bf16 v[48:51], v[144:147], v[176:179], 0
	v_mfma_f32_16x16x32_bf16 v[40:43], v[152:155], v[176:179], 0
	v_mfma_f32_16x16x32_bf16 v[32:35], v[144:147], v[184:187], 0
	v_mfma_f32_16x16x32_bf16 v[24:27], v[152:155], v[184:187], 0
	v_mfma_f32_16x16x32_bf16 v[16:19], v[144:147], v[192:195], 0
	v_mfma_f32_16x16x32_bf16 v[8:11], v[152:155], v[192:195], 0
	v_mfma_f32_16x16x32_bf16 v[60:63], v[148:151], v[172:175], v[60:63]
	v_mfma_f32_16x16x32_bf16 v[56:59], v[156:159], v[172:175], v[56:59]
	v_mfma_f32_16x16x32_bf16 v[48:51], v[148:151], v[180:183], v[48:51]
	v_mfma_f32_16x16x32_bf16 v[40:43], v[156:159], v[180:183], v[40:43]
	v_mfma_f32_16x16x32_bf16 v[32:35], v[148:151], v[188:191], v[32:35]
	v_mfma_f32_16x16x32_bf16 v[24:27], v[156:159], v[188:191], v[24:27]
	v_mfma_f32_16x16x32_bf16 v[16:19], v[148:151], v[196:199], v[16:19]
	v_mfma_f32_16x16x32_bf16 v[8:11], v[156:159], v[196:199], v[8:11]
	s_barrier
	s_setprio 0
	s_add_u32 s16, s34, 0xb0000
	s_addc_u32 s17, s35, 0
	s_add_i32 s20, s59, s40
	s_mov_b32 m0, s20
	s_nop 0
	global_load_lds_dwordx4 v132, s[16:17]
	s_add_i32 m0, s20, 0x2000
	s_nop 0
	global_load_lds_dwordx4 v128, s[16:17]
	s_add_u32 s16, s36, 0xb0000
	s_addc_u32 s17, s37, 0
	s_mov_b32 m0, s44
	s_nop 0
	global_load_lds_dwordx4 v134, s[16:17]
	s_mov_b32 m0, s45
	s_nop 0
	global_load_lds_dwordx4 v130, s[16:17]
	s_waitcnt vmcnt(10)
	s_setprio 1
	s_barrier
; #define PG8_STAGE(bufoff, gbase, voff) do { _Pragma("unroll") for (int _i = 0; _i < 2; ++_i) \
;         __builtin_amdgcn_global_load_lds((const unsigned*)((const char*)(gbase) + (voff)[_i]), (LAS unsigned*)(lds + (bufoff) + ldsw + _i * 8192), 16, 0, 0); } while (0)
; #define PG8_LDA(dst, b, h) do { _Pragma("unroll") for (int m = 0; m < 4; ++m) _Pragma("unroll") for (int k = 0; k < 2; ++k) dst[m][k] = *(const LAS bf16x8*)(lds + PG8_SA(b, h) + aoff + m * 2048 + k * 1024); } while (0)
; #define PG8_LDB(dst, b, h) do { _Pragma("unroll") for (int n = 0; n < 2; ++n) _Pragma("unroll") for (int k = 0; k < 2; ++k) dst[n][k] = *(const LAS bf16x8*)(lds + PG8_SB(b, h) + boff + n * 2048 + k * 1024); } while (0)
; #define PG8_WAIT_V(n) asm volatile("s_waitcnt vmcnt(" #n ")" ::: "memory")
; #define PG8_WAIT_L(n) asm volatile("s_waitcnt lgkmcnt(" #n ")" ::: "memory")
; #define PG8_BAR __builtin_amdgcn_s_barrier()
; #define PG8_SCHED __builtin_amdgcn_sched_barrier(0)
; template <class Epi, class Sched>
; __device__ __forceinline__ void gemm_phase(LAS unsigned char* lds, const Gemm g, const Sched& S, const Epi& E) {
;     ...
;             PG8_LDB(B0, 0, 0); PG8_SCHED; PG8_LDA(At, 0, 0); PG8_STAGE(PG8_SA(1, 1), a1 + hstep, voffA);
;             PG8_WAIT_L(8); PG8_BAR; PG8_WAIT_L(0); PG8_MMA(0, 0, At, B0); PG8_BAR; PG8_SCHED;
;             PG8_LDB(B1, 0, 1); PG8_STAGE(PG8_SB(0, 0), b2, voffB);
;             PG8_BAR; PG8_WAIT_L(0); PG8_MMA(0, 1, At, B1); PG8_BAR;
;             PG8_LDA(At, 0, 1); PG8_STAGE(PG8_SA(0, 0), a2, voffA);
;             PG8_BAR; PG8_WAIT_L(0); PG8_MMA(1, 0, At, B0); PG8_BAR; PG8_SCHED;
;             PG8_STAGE(PG8_SB(0, 1), b2 + hstep, voffB);
;             PG8_WAIT_V(6); PG8_BAR; PG8_MMA(1, 1, At, B1); PG8_BAR;
;             PG8_LDB(B0, 1, 0); PG8_SCHED; PG8_LDA(At, 1, 0); PG8_STAGE(PG8_SA(0, 1), a2 + hstep, voffA);
;             PG8_WAIT_L(8); PG8_BAR; PG8_WAIT_L(0); PG8_MMA(0, 0, At, B0); PG8_BAR; PG8_SCHED;
;             PG8_LDB(B1, 1, 1); PG8_STAGE(PG8_SB(1, 0), b3, voffB);
;             PG8_BAR; PG8_WAIT_L(0); PG8_MMA(0, 1, At, B1); PG8_BAR;
;             PG8_LDA(At, 1, 1); PG8_STAGE(PG8_SA(1, 0), a3, voffA);
;             PG8_BAR; PG8_WAIT_L(0); PG8_MMA(1, 0, At, B0); PG8_BAR; PG8_SCHED;
;             PG8_STAGE(PG8_SB(1, 1), b3 + hstep, voffB);
;             PG8_WAIT_V(6); PG8_BAR; PG8_MMA(1, 1, At, B1); PG8_BAR;
	v_mfma_f32_16x16x32_bf16 v[52:55], v[202:205], v[168:171], 0
	v_mfma_f32_16x16x32_bf16 v[44:47], v[210:213], v[168:171], 0
	v_mfma_f32_16x16x32_bf16 v[36:39], v[202:205], v[176:179], 0
	v_mfma_f32_16x16x32_bf16 v[28:31], v[210:213], v[176:179], 0
	v_mfma_f32_16x16x32_bf16 v[20:23], v[202:205], v[184:187], 0
	v_mfma_f32_16x16x32_bf16 v[12:15], v[210:213], v[184:187], 0
	v_mfma_f32_16x16x32_bf16 v[4:7], v[202:205], v[192:195], 0
	v_mfma_f32_16x16x32_bf16 v[0:3], v[210:213], v[192:195], 0
	v_mfma_f32_16x16x32_bf16 v[52:55], v[206:209], v[172:175], v[52:55]
	v_mfma_f32_16x16x32_bf16 v[44:47], v[214:217], v[172:175], v[44:47]
	v_mfma_f32_16x16x32_bf16 v[36:39], v[206:209], v[180:183], v[36:39]
	v_mfma_f32_16x16x32_bf16 v[28:31], v[214:217], v[180:183], v[28:31]
	v_mfma_f32_16x16x32_bf16 v[20:23], v[206:209], v[188:191], v[20:23]
	v_mfma_f32_16x16x32_bf16 v[12:15], v[214:217], v[188:191], v[12:15]
	v_mfma_f32_16x16x32_bf16 v[4:7], v[206:209], v[196:199], v[4:7]
	v_mfma_f32_16x16x32_bf16 v[0:3], v[214:217], v[196:199], v[0:3]
	s_barrier
	s_setprio 0
	s_add_i32 s20, 0, 0x18000
	v_add_u32_e32 v156, s20, v164
	ds_read_b128 v[144:147], v156
	ds_read_b128 v[148:151], v156 offset:1024
	ds_read_b128 v[152:155], v156 offset:2048
	ds_read_b128 v[156:159], v156 offset:3072
	ds_read_b128 v[168:171], v166 offset:32768
	ds_read_b128 v[172:175], v166 offset:33792
	ds_read_b128 v[176:179], v166 offset:34816
	ds_read_b128 v[180:183], v166 offset:35840
	ds_read_b128 v[184:187], v166 offset:36864
	ds_read_b128 v[188:191], v166 offset:37888
	ds_read_b128 v[192:195], v166 offset:38912
	ds_read_b128 v[196:199], v166 offset:39936
	s_waitcnt lgkmcnt(8)
	s_waitcnt vmcnt(8)
	s_setprio 1
	s_barrier
	s_waitcnt lgkmcnt(0)
	v_mfma_f32_16x16x32_bf16 v[124:127], v[144:147], v[168:171], v[124:127]
	v_mfma_f32_16x16x32_bf16 v[120:123], v[152:155], v[168:171], v[120:123]
	v_mfma_f32_16x16x32_bf16 v[116:119], v[144:147], v[176:179], v[116:119]
	v_mfma_f32_16x16x32_bf16 v[104:107], v[152:155], v[176:179], v[104:107]
	v_mfma_f32_16x16x32_bf16 v[96:99], v[144:147], v[184:187], v[96:99]
	v_mfma_f32_16x16x32_bf16 v[88:91], v[152:155], v[184:187], v[88:91]
	v_mfma_f32_16x16x32_bf16 v[80:83], v[144:147], v[192:195], v[80:83]
	v_mfma_f32_16x16x32_bf16 v[72:75], v[152:155], v[192:195], v[72:75]
	v_mfma_f32_16x16x32_bf16 v[124:127], v[148:151], v[172:175], v[124:127]
	v_mfma_f32_16x16x32_bf16 v[120:123], v[156:159], v[172:175], v[120:123]
	v_mfma_f32_16x16x32_bf16 v[116:119], v[148:151], v[180:183], v[116:119]
	v_mfma_f32_16x16x32_bf16 v[104:107], v[156:159], v[180:183], v[104:107]
	v_mfma_f32_16x16x32_bf16 v[96:99], v[148:151], v[188:191], v[96:99]
	v_mfma_f32_16x16x32_bf16 v[88:91], v[156:159], v[188:191], v[88:91]
	v_mfma_f32_16x16x32_bf16 v[80:83], v[148:151], v[196:199], v[80:83]
	v_mfma_f32_16x16x32_bf16 v[72:75], v[156:159], v[196:199], v[72:75]
	s_barrier
	s_setprio 0
	s_add_i32 s21, 0, 0x1c000
	s_add_i32 s16, s20, s40
	v_add_u32_e32 v214, s21, v164
	s_add_u32 s8, s34, 0x80
	s_addc_u32 s9, s35, 0
	s_mov_b32 m0, s16
	ds_read_b128 v[202:205], v214
	ds_read_b128 v[206:209], v214 offset:1024
	ds_read_b128 v[210:213], v214 offset:2048
	ds_read_b128 v[214:217], v214 offset:3072
	global_load_lds_dwordx4 v132, s[8:9]
	s_add_i32 m0, s16, 0x2000
	s_nop 0
	global_load_lds_dwordx4 v128, s[8:9]
	s_waitcnt vmcnt(8)
	s_setprio 1
	s_barrier
	s_waitcnt lgkmcnt(0)
	v_mfma_f32_16x16x32_bf16 v[112:115], v[202:205], v[168:171], v[112:115]
	v_mfma_f32_16x16x32_bf16 v[108:111], v[210:213], v[168:171], v[108:111]
	v_mfma_f32_16x16x32_bf16 v[100:103], v[202:205], v[176:179], v[100:103]
	v_mfma_f32_16x16x32_bf16 v[92:95], v[210:213], v[176:179], v[92:95]
	v_mfma_f32_16x16x32_bf16 v[84:87], v[202:205], v[184:187], v[84:87]
	v_mfma_f32_16x16x32_bf16 v[76:79], v[210:213], v[184:187], v[76:79]
	v_mfma_f32_16x16x32_bf16 v[68:71], v[202:205], v[192:195], v[68:71]
	v_mfma_f32_16x16x32_bf16 v[64:67], v[210:213], v[192:195], v[64:67]
	v_mfma_f32_16x16x32_bf16 v[112:115], v[206:209], v[172:175], v[112:115]
	v_mfma_f32_16x16x32_bf16 v[108:111], v[214:217], v[172:175], v[108:111]
	v_mfma_f32_16x16x32_bf16 v[100:103], v[206:209], v[180:183], v[100:103]
	v_mfma_f32_16x16x32_bf16 v[92:95], v[214:217], v[180:183], v[92:95]
	v_mfma_f32_16x16x32_bf16 v[84:87], v[206:209], v[188:191], v[84:87]
	v_mfma_f32_16x16x32_bf16 v[76:79], v[214:217], v[188:191], v[76:79]
	v_mfma_f32_16x16x32_bf16 v[68:71], v[206:209], v[196:199], v[68:71]
	v_mfma_f32_16x16x32_bf16 v[64:67], v[214:217], v[196:199], v[64:67]
	s_barrier
	s_setprio 0
	s_mov_b32 m0, s52
	s_add_u32 s8, s36, 0x80
	s_addc_u32 s9, s37, 0
	ds_read_b128 v[168:171], v166 offset:49152
	ds_read_b128 v[172:175], v166 offset:50176
	ds_read_b128 v[176:179], v166 offset:51200
	ds_read_b128 v[180:183], v166 offset:52224
	ds_read_b128 v[184:187], v166 offset:53248
	ds_read_b128 v[188:191], v166 offset:54272
	ds_read_b128 v[192:195], v166 offset:55296
	ds_read_b128 v[196:199], v166 offset:56320
	global_load_lds_dwordx4 v134, s[8:9]
	s_mov_b32 m0, s53
	s_nop 0
	global_load_lds_dwordx4 v130, s[8:9]
	s_setprio 1
	s_barrier
	s_waitcnt lgkmcnt(0)
	v_mfma_f32_16x16x32_bf16 v[60:63], v[144:147], v[168:171], v[60:63]
	v_mfma_f32_16x16x32_bf16 v[56:59], v[152:155], v[168:171], v[56:59]
	v_mfma_f32_16x16x32_bf16 v[48:51], v[144:147], v[176:179], v[48:51]
	v_mfma_f32_16x16x32_bf16 v[40:43], v[152:155], v[176:179], v[40:43]
	v_mfma_f32_16x16x32_bf16 v[32:35], v[144:147], v[184:187], v[32:35]
	v_mfma_f32_16x16x32_bf16 v[24:27], v[152:155], v[184:187], v[24:27]
	v_mfma_f32_16x16x32_bf16 v[16:19], v[144:147], v[192:195], v[16:19]
	v_mfma_f32_16x16x32_bf16 v[8:11], v[152:155], v[192:195], v[8:11]
	v_mfma_f32_16x16x32_bf16 v[60:63], v[148:151], v[172:175], v[60:63]
	v_mfma_f32_16x16x32_bf16 v[56:59], v[156:159], v[172:175], v[56:59]
	v_mfma_f32_16x16x32_bf16 v[48:51], v[148:151], v[180:183], v[48:51]
	v_mfma_f32_16x16x32_bf16 v[40:43], v[156:159], v[180:183], v[40:43]
	v_mfma_f32_16x16x32_bf16 v[32:35], v[148:151], v[188:191], v[32:35]
	v_mfma_f32_16x16x32_bf16 v[24:27], v[156:159], v[188:191], v[24:27]
	v_mfma_f32_16x16x32_bf16 v[16:19], v[148:151], v[196:199], v[16:19]
	v_mfma_f32_16x16x32_bf16 v[8:11], v[156:159], v[196:199], v[8:11]
	s_barrier
; #define PG8_STAGE(bufoff, gbase, voff) do { _Pragma("unroll") for (int _i = 0; _i < 2; ++_i) \
;         __builtin_amdgcn_global_load_lds((const unsigned*)((const char*)(gbase) + (voff)[_i]), (LAS unsigned*)(lds + (bufoff) + ldsw + _i * 8192), 16, 0, 0); } while (0)
; #define PG8_LDA(dst, b, h) do { _Pragma("unroll") for (int m = 0; m < 4; ++m) _Pragma("unroll") for (int k = 0; k < 2; ++k) dst[m][k] = *(const LAS bf16x8*)(lds + PG8_SA(b, h) + aoff + m * 2048 + k * 1024); } while (0)
; #define PG8_WAIT_V(n) asm volatile("s_waitcnt vmcnt(" #n ")" ::: "memory")
; #define PG8_WAIT_L(n) asm volatile("s_waitcnt lgkmcnt(" #n ")" ::: "memory")
; template <class Epi, class Sched>
; __device__ __forceinline__ void gemm_phase(LAS unsigned char* lds, const Gemm g, const Sched& S, const Epi& E) {
;     ...
;         for (int t = 0; t < nt; t += 2) {
;             const bool last = (t == nt - 2);
;             const char* a1 = cA + (size_t)(t + 1) * kstep;
;             const char* a2 = last ? nA : cA + (size_t)(t + 2) * kstep; const char* b2 = last ? nB : cB + (size_t)(t + 2) * kstep;
;             const char* a3 = a2 + kstep; const char* b3 = b2 + kstep;
;             PG8_LDB(B0, 0, 0); PG8_SCHED; PG8_LDA(At, 0, 0); PG8_STAGE(PG8_SA(1, 1), a1 + hstep, voffA);
;             PG8_WAIT_L(8); PG8_BAR; PG8_WAIT_L(0); PG8_MMA(0, 0, At, B0); PG8_BAR; PG8_SCHED;
;             PG8_LDB(B1, 0, 1); PG8_STAGE(PG8_SB(0, 0), b2, voffB);
;             PG8_BAR; PG8_WAIT_L(0); PG8_MMA(0, 1, At, B1); PG8_BAR;
;             PG8_LDA(At, 0, 1); PG8_STAGE(PG8_SA(0, 0), a2, voffA);
;             PG8_BAR; PG8_WAIT_L(0); PG8_MMA(1, 0, At, B0); PG8_BAR; PG8_SCHED;
;             PG8_STAGE(PG8_SB(0, 1), b2 + hstep, voffB);
;             PG8_WAIT_V(6); PG8_BAR; PG8_MMA(1, 1, At, B1); PG8_BAR;
;             PG8_LDB(B0, 1, 0); PG8_SCHED; PG8_LDA(At, 1, 0); PG8_STAGE(PG8_SA(0, 1), a2 + hstep, voffA);
;             PG8_WAIT_L(8); PG8_BAR; PG8_WAIT_L(0); PG8_MMA(0, 0, At, B0); PG8_BAR; PG8_SCHED;
;             PG8_LDB(B1, 1, 1); PG8_STAGE(PG8_SB(1, 0), b3, voffB);
;             PG8_BAR; PG8_WAIT_L(0); PG8_MMA(0, 1, At, B1); PG8_BAR;
;             PG8_LDA(At, 1, 1); PG8_STAGE(PG8_SA(1, 0), a3, voffA);
;             PG8_BAR; PG8_WAIT_L(0); PG8_MMA(1, 0, At, B0); PG8_BAR; PG8_SCHED;
;             PG8_STAGE(PG8_SB(1, 1), b3 + hstep, voffB);
;             PG8_WAIT_V(6); PG8_BAR; PG8_MMA(1, 1, At, B1); PG8_BAR;
	s_setprio 0
	s_add_u32 s16, s34, 0xb0080
	s_addc_u32 s17, s35, 0
	s_add_i32 s20, s21, s40
	s_mov_b32 m0, s20
	s_nop 0
	global_load_lds_dwordx4 v132, s[16:17]
	s_add_i32 m0, s20, 0x2000
	s_nop 0
	global_load_lds_dwordx4 v128, s[16:17]
	s_waitcnt vmcnt(8)
	s_setprio 1
	s_barrier
	v_mfma_f32_16x16x32_bf16 v[52:55], v[202:205], v[168:171], v[52:55]
	v_mfma_f32_16x16x32_bf16 v[44:47], v[210:213], v[168:171], v[44:47]
	v_mfma_f32_16x16x32_bf16 v[36:39], v[202:205], v[176:179], v[36:39]
	v_mfma_f32_16x16x32_bf16 v[28:31], v[210:213], v[176:179], v[28:31]
	v_mfma_f32_16x16x32_bf16 v[20:23], v[202:205], v[184:187], v[20:23]
	v_mfma_f32_16x16x32_bf16 v[12:15], v[210:213], v[184:187], v[12:15]
	v_mfma_f32_16x16x32_bf16 v[4:7], v[202:205], v[192:195], v[4:7]
	v_mfma_f32_16x16x32_bf16 v[0:3], v[210:213], v[192:195], v[0:3]
	v_mfma_f32_16x16x32_bf16 v[52:55], v[206:209], v[172:175], v[52:55]
	v_mfma_f32_16x16x32_bf16 v[44:47], v[214:217], v[172:175], v[44:47]
	v_mfma_f32_16x16x32_bf16 v[36:39], v[206:209], v[180:183], v[36:39]
	v_mfma_f32_16x16x32_bf16 v[28:31], v[214:217], v[180:183], v[28:31]
	v_mfma_f32_16x16x32_bf16 v[20:23], v[206:209], v[188:191], v[20:23]
	v_mfma_f32_16x16x32_bf16 v[12:15], v[214:217], v[188:191], v[12:15]
	v_mfma_f32_16x16x32_bf16 v[4:7], v[206:209], v[196:199], v[4:7]
	v_mfma_f32_16x16x32_bf16 v[0:3], v[214:217], v[196:199], v[0:3]
	s_barrier
	s_setprio 0
	s_add_i32 s68, s68, 2
	s_add_u32 s0, s0, 0x100
	s_addc_u32 s67, s67, 0
	s_cmp_gt_u32 s68, 41
	s_mov_b64 s[26:27], s[28:29]
.LBB0_305:
	ds_read_b128 v[144:147], v165
	ds_read_b128 v[148:151], v165 offset:1024
	ds_read_b128 v[152:155], v165 offset:2048
	ds_read_b128 v[156:159], v165 offset:3072
	s_add_u32 s28, s26, 0x100
	s_addc_u32 s29, s27, 0
	s_cmp_eq_u32 s68, 40
	s_cselect_b32 s37, s5, s29
	s_cselect_b32 s36, s4, s28
	s_cselect_b32 s35, s7, s67
	s_cselect_b32 s34, s6, s0
	v_lshl_add_u64 v[160:161], s[26:27], 0, v[136:137]
	s_add_i32 m0, s42, 0xc000
	ds_read_b128 v[168:171], v166
	ds_read_b128 v[172:175], v166 offset:1024
	ds_read_b128 v[176:179], v166 offset:2048
	ds_read_b128 v[180:183], v166 offset:3072
	ds_read_b128 v[184:187], v166 offset:4096
	ds_read_b128 v[188:191], v166 offset:5120
	ds_read_b128 v[192:195], v166 offset:6144
	ds_read_b128 v[196:199], v166 offset:7168
	global_load_lds_dwordx4 v[160:161], off
	v_lshl_add_u64 v[160:161], s[26:27], 0, v[138:139]
	s_add_i32 m0, s42, 0xe000
	s_nop 0
	global_load_lds_dwordx4 v[160:161], off
	s_waitcnt lgkmcnt(8)
	s_waitcnt vmcnt(8)
	s_setprio 1
	s_barrier
	s_waitcnt lgkmcnt(0)
	v_mfma_f32_16x16x32_bf16 v[124:127], v[144:147], v[168:171], v[124:127]
	v_mfma_f32_16x16x32_bf16 v[120:123], v[152:155], v[168:171], v[120:123]
	v_mfma_f32_16x16x32_bf16 v[116:119], v[144:147], v[176:179], v[116:119]
	v_mfma_f32_16x16x32_bf16 v[104:107], v[152:155], v[176:179], v[104:107]
	v_mfma_f32_16x16x32_bf16 v[96:99], v[144:147], v[184:187], v[96:99]
	v_mfma_f32_16x16x32_bf16 v[88:91], v[152:155], v[184:187], v[88:91]
	v_mfma_f32_16x16x32_bf16 v[80:83], v[144:147], v[192:195], v[80:83]
	v_mfma_f32_16x16x32_bf16 v[72:75], v[152:155], v[192:195], v[72:75]
	v_mfma_f32_16x16x32_bf16 v[124:127], v[148:151], v[172:175], v[124:127]
	v_mfma_f32_16x16x32_bf16 v[120:123], v[156:159], v[172:175], v[120:123]
	v_mfma_f32_16x16x32_bf16 v[116:119], v[148:151], v[180:183], v[116:119]
	v_mfma_f32_16x16x32_bf16 v[104:107], v[156:159], v[180:183], v[104:107]
	v_mfma_f32_16x16x32_bf16 v[96:99], v[148:151], v[188:191], v[96:99]
	v_mfma_f32_16x16x32_bf16 v[88:91], v[156:159], v[188:191], v[88:91]
	v_mfma_f32_16x16x32_bf16 v[80:83], v[148:151], v[196:199], v[80:83]
	v_mfma_f32_16x16x32_bf16 v[72:75], v[156:159], v[196:199], v[72:75]
	s_barrier
	s_setprio 0
	s_add_i32 s16, s58, s40
	s_mov_b32 m0, s16
	ds_read_b128 v[202:205], v167
	ds_read_b128 v[206:209], v167 offset:1024
	ds_read_b128 v[210:213], v167 offset:2048
	ds_read_b128 v[214:217], v167 offset:3072
	global_load_lds_dwordx4 v132, s[34:35]
	s_add_i32 m0, s16, 0x2000
	s_nop 0
	global_load_lds_dwordx4 v128, s[34:35]
	s_waitcnt vmcnt(8)
	s_setprio 1
	s_barrier
	s_waitcnt lgkmcnt(0)
	v_mfma_f32_16x16x32_bf16 v[112:115], v[202:205], v[168:171], v[112:115]
	v_mfma_f32_16x16x32_bf16 v[108:111], v[210:213], v[168:171], v[108:111]
	v_mfma_f32_16x16x32_bf16 v[100:103], v[202:205], v[176:179], v[100:103]
	v_mfma_f32_16x16x32_bf16 v[92:95], v[210:213], v[176:179], v[92:95]
	v_mfma_f32_16x16x32_bf16 v[84:87], v[202:205], v[184:187], v[84:87]
	v_mfma_f32_16x16x32_bf16 v[76:79], v[210:213], v[184:187], v[76:79]
	v_mfma_f32_16x16x32_bf16 v[68:71], v[202:205], v[192:195], v[68:71]
	v_mfma_f32_16x16x32_bf16 v[64:67], v[210:213], v[192:195], v[64:67]
	v_mfma_f32_16x16x32_bf16 v[112:115], v[206:209], v[172:175], v[112:115]
	v_mfma_f32_16x16x32_bf16 v[108:111], v[214:217], v[172:175], v[108:111]
	v_mfma_f32_16x16x32_bf16 v[100:103], v[206:209], v[180:183], v[100:103]
	v_mfma_f32_16x16x32_bf16 v[92:95], v[214:217], v[180:183], v[92:95]
	v_mfma_f32_16x16x32_bf16 v[84:87], v[206:209], v[188:191], v[84:87]
	v_mfma_f32_16x16x32_bf16 v[76:79], v[214:217], v[188:191], v[76:79]
	v_mfma_f32_16x16x32_bf16 v[68:71], v[206:209], v[196:199], v[68:71]
	v_mfma_f32_16x16x32_bf16 v[64:67], v[214:217], v[196:199], v[64:67]
	s_barrier
	s_setprio 0
	s_mov_b32 m0, s42
	ds_read_b128 v[168:171], v166 offset:16384
	ds_read_b128 v[172:175], v166 offset:17408
	ds_read_b128 v[176:179], v166 offset:18432
	ds_read_b128 v[180:183], v166 offset:19456
	ds_read_b128 v[184:187], v166 offset:20480
	ds_read_b128 v[188:191], v166 offset:21504
	ds_read_b128 v[192:195], v166 offset:22528
	ds_read_b128 v[196:199], v166 offset:23552
	global_load_lds_dwordx4 v134, s[36:37]
	s_mov_b32 m0, s43
	s_nop 0
	global_load_lds_dwordx4 v130, s[36:37]
	s_setprio 1
	s_barrier
; #define PG8_STAGE(bufoff, gbase, voff) do { _Pragma("unroll") for (int _i = 0; _i < 2; ++_i) \
;         __builtin_amdgcn_global_load_lds((const unsigned*)((const char*)(gbase) + (voff)[_i]), (LAS unsigned*)(lds + (bufoff) + ldsw + _i * 8192), 16, 0, 0); } while (0)
; #define PG8_LDA(dst, b, h) do { _Pragma("unroll") for (int m = 0; m < 4; ++m) _Pragma("unroll") for (int k = 0; k < 2; ++k) dst[m][k] = *(const LAS bf16x8*)(lds + PG8_SA(b, h) + aoff + m * 2048 + k * 1024); } while (0)
; #define PG8_LDB(dst, b, h) do { _Pragma("unroll") for (int n = 0; n < 2; ++n) _Pragma("unroll") for (int k = 0; k < 2; ++k) dst[n][k] = *(const LAS bf16x8*)(lds + PG8_SB(b, h) + boff + n * 2048 + k * 1024); } while (0)
; #define PG8_WAIT_V(n) asm volatile("s_waitcnt vmcnt(" #n ")" ::: "memory")
; #define PG8_WAIT_L(n) asm volatile("s_waitcnt lgkmcnt(" #n ")" ::: "memory")
; #define PG8_BAR __builtin_amdgcn_s_barrier()
; #define PG8_SCHED __builtin_amdgcn_sched_barrier(0)
; template <class Epi, class Sched>
; __device__ __forceinline__ void gemm_phase(LAS unsigned char* lds, const Gemm g, const Sched& S, const Epi& E) {
;     ...
;             PG8_LDB(B0, 0, 0); PG8_SCHED; PG8_LDA(At, 0, 0); PG8_STAGE(PG8_SA(1, 1), a1 + hstep, voffA);
;             PG8_WAIT_L(8); PG8_BAR; PG8_WAIT_L(0); PG8_MMA(0, 0, At, B0); PG8_BAR; PG8_SCHED;
;             PG8_LDB(B1, 0, 1); PG8_STAGE(PG8_SB(0, 0), b2, voffB);
;             PG8_BAR; PG8_WAIT_L(0); PG8_MMA(0, 1, At, B1); PG8_BAR;
;             PG8_LDA(At, 0, 1); PG8_STAGE(PG8_SA(0, 0), a2, voffA);
;             PG8_BAR; PG8_WAIT_L(0); PG8_MMA(1, 0, At, B0); PG8_BAR; PG8_SCHED;
;             PG8_STAGE(PG8_SB(0, 1), b2 + hstep, voffB);
;             PG8_WAIT_V(6); PG8_BAR; PG8_MMA(1, 1, At, B1); PG8_BAR;
;             PG8_LDB(B0, 1, 0); PG8_SCHED; PG8_LDA(At, 1, 0); PG8_STAGE(PG8_SA(0, 1), a2 + hstep, voffA);
;             PG8_WAIT_L(8); PG8_BAR; PG8_WAIT_L(0); PG8_MMA(0, 0, At, B0); PG8_BAR; PG8_SCHED;
;             PG8_LDB(B1, 1, 1); PG8_STAGE(PG8_SB(1, 0), b3, voffB);
;             PG8_BAR; PG8_WAIT_L(0); PG8_MMA(0, 1, At, B1); PG8_BAR;
;             PG8_LDA(At, 1, 1); PG8_STAGE(PG8_SA(1, 0), a3, voffA);
;             PG8_BAR; PG8_WAIT_L(0); PG8_MMA(1, 0, At, B0); PG8_BAR; PG8_SCHED;
;             PG8_STAGE(PG8_SB(1, 1), b3 + hstep, voffB);
;             PG8_WAIT_V(6); PG8_BAR; PG8_MMA(1, 1, At, B1); PG8_BAR;
	s_waitcnt lgkmcnt(0)
	v_mfma_f32_16x16x32_bf16 v[60:63], v[144:147], v[168:171], v[60:63]
	v_mfma_f32_16x16x32_bf16 v[56:59], v[152:155], v[168:171], v[56:59]
	v_mfma_f32_16x16x32_bf16 v[48:51], v[144:147], v[176:179], v[48:51]
	v_mfma_f32_16x16x32_bf16 v[40:43], v[152:155], v[176:179], v[40:43]
	v_mfma_f32_16x16x32_bf16 v[32:35], v[144:147], v[184:187], v[32:35]
	v_mfma_f32_16x16x32_bf16 v[24:27], v[152:155], v[184:187], v[24:27]
	v_mfma_f32_16x16x32_bf16 v[16:19], v[144:147], v[192:195], v[16:19]
	v_mfma_f32_16x16x32_bf16 v[8:11], v[152:155], v[192:195], v[8:11]
	v_mfma_f32_16x16x32_bf16 v[60:63], v[148:151], v[172:175], v[60:63]
	v_mfma_f32_16x16x32_bf16 v[56:59], v[156:159], v[172:175], v[56:59]
	v_mfma_f32_16x16x32_bf16 v[48:51], v[148:151], v[180:183], v[48:51]
	v_mfma_f32_16x16x32_bf16 v[40:43], v[156:159], v[180:183], v[40:43]
	v_mfma_f32_16x16x32_bf16 v[32:35], v[148:151], v[188:191], v[32:35]
	v_mfma_f32_16x16x32_bf16 v[24:27], v[156:159], v[188:191], v[24:27]
	v_mfma_f32_16x16x32_bf16 v[16:19], v[148:151], v[196:199], v[16:19]
	v_mfma_f32_16x16x32_bf16 v[8:11], v[156:159], v[196:199], v[8:11]
	s_barrier
	s_setprio 0
	s_add_u32 s16, s34, 0xb0000
	s_addc_u32 s17, s35, 0
	s_add_i32 s20, s59, s40
	s_mov_b32 m0, s20
	s_nop 0
	global_load_lds_dwordx4 v132, s[16:17]
	s_add_i32 m0, s20, 0x2000
	s_nop 0
	global_load_lds_dwordx4 v128, s[16:17]
	s_add_u32 s16, s36, 0xb0000
	s_addc_u32 s17, s37, 0
	s_mov_b32 m0, s44
	s_nop 0
	global_load_lds_dwordx4 v134, s[16:17]
	s_mov_b32 m0, s45
	s_nop 0
	global_load_lds_dwordx4 v130, s[16:17]
	s_waitcnt vmcnt(10)
	s_setprio 1
	s_barrier
	v_mfma_f32_16x16x32_bf16 v[52:55], v[202:205], v[168:171], v[52:55]
	v_mfma_f32_16x16x32_bf16 v[44:47], v[210:213], v[168:171], v[44:47]
	v_mfma_f32_16x16x32_bf16 v[36:39], v[202:205], v[176:179], v[36:39]
	v_mfma_f32_16x16x32_bf16 v[28:31], v[210:213], v[176:179], v[28:31]
	v_mfma_f32_16x16x32_bf16 v[20:23], v[202:205], v[184:187], v[20:23]
	v_mfma_f32_16x16x32_bf16 v[12:15], v[210:213], v[184:187], v[12:15]
	v_mfma_f32_16x16x32_bf16 v[4:7], v[202:205], v[192:195], v[4:7]
	v_mfma_f32_16x16x32_bf16 v[0:3], v[210:213], v[192:195], v[0:3]
	v_mfma_f32_16x16x32_bf16 v[52:55], v[206:209], v[172:175], v[52:55]
	v_mfma_f32_16x16x32_bf16 v[44:47], v[214:217], v[172:175], v[44:47]
	v_mfma_f32_16x16x32_bf16 v[36:39], v[206:209], v[180:183], v[36:39]
	v_mfma_f32_16x16x32_bf16 v[28:31], v[214:217], v[180:183], v[28:31]
	v_mfma_f32_16x16x32_bf16 v[20:23], v[206:209], v[188:191], v[20:23]
	v_mfma_f32_16x16x32_bf16 v[12:15], v[214:217], v[188:191], v[12:15]
	v_mfma_f32_16x16x32_bf16 v[4:7], v[206:209], v[196:199], v[4:7]
	v_mfma_f32_16x16x32_bf16 v[0:3], v[214:217], v[196:199], v[0:3]
	s_barrier
	s_setprio 0
	s_add_i32 s20, 0, 0x18000
	v_add_u32_e32 v156, s20, v164
	ds_read_b128 v[144:147], v156
	ds_read_b128 v[148:151], v156 offset:1024
	ds_read_b128 v[152:155], v156 offset:2048
	ds_read_b128 v[156:159], v156 offset:3072
	ds_read_b128 v[168:171], v166 offset:32768
	ds_read_b128 v[172:175], v166 offset:33792
	ds_read_b128 v[176:179], v166 offset:34816
	ds_read_b128 v[180:183], v166 offset:35840
	ds_read_b128 v[184:187], v166 offset:36864
	ds_read_b128 v[188:191], v166 offset:37888
	ds_read_b128 v[192:195], v166 offset:38912
	ds_read_b128 v[196:199], v166 offset:39936
	s_waitcnt lgkmcnt(8)
	s_waitcnt vmcnt(8)
	s_setprio 1
	s_barrier
	s_waitcnt lgkmcnt(0)
	v_mfma_f32_16x16x32_bf16 v[124:127], v[144:147], v[168:171], v[124:127]
	v_mfma_f32_16x16x32_bf16 v[120:123], v[152:155], v[168:171], v[120:123]
	v_mfma_f32_16x16x32_bf16 v[116:119], v[144:147], v[176:179], v[116:119]
	v_mfma_f32_16x16x32_bf16 v[104:107], v[152:155], v[176:179], v[104:107]
	v_mfma_f32_16x16x32_bf16 v[96:99], v[144:147], v[184:187], v[96:99]
	v_mfma_f32_16x16x32_bf16 v[88:91], v[152:155], v[184:187], v[88:91]
	v_mfma_f32_16x16x32_bf16 v[80:83], v[144:147], v[192:195], v[80:83]
	v_mfma_f32_16x16x32_bf16 v[72:75], v[152:155], v[192:195], v[72:75]
	v_mfma_f32_16x16x32_bf16 v[124:127], v[148:151], v[172:175], v[124:127]
	v_mfma_f32_16x16x32_bf16 v[120:123], v[156:159], v[172:175], v[120:123]
	v_mfma_f32_16x16x32_bf16 v[116:119], v[148:151], v[180:183], v[116:119]
	v_mfma_f32_16x16x32_bf16 v[104:107], v[156:159], v[180:183], v[104:107]
	v_mfma_f32_16x16x32_bf16 v[96:99], v[148:151], v[188:191], v[96:99]
	v_mfma_f32_16x16x32_bf16 v[88:91], v[156:159], v[188:191], v[88:91]
	v_mfma_f32_16x16x32_bf16 v[80:83], v[148:151], v[196:199], v[80:83]
	v_mfma_f32_16x16x32_bf16 v[72:75], v[156:159], v[196:199], v[72:75]
	s_barrier
	s_setprio 0
	s_add_i32 s21, 0, 0x1c000
	s_add_i32 s16, s20, s40
	v_add_u32_e32 v214, s21, v164
	s_add_u32 s8, s34, 0x80
	s_addc_u32 s9, s35, 0
	s_mov_b32 m0, s16
	ds_read_b128 v[202:205], v214
	ds_read_b128 v[206:209], v214 offset:1024
	ds_read_b128 v[210:213], v214 offset:2048
	ds_read_b128 v[214:217], v214 offset:3072
	global_load_lds_dwordx4 v132, s[8:9]
	s_add_i32 m0, s16, 0x2000
	s_nop 0
	global_load_lds_dwordx4 v128, s[8:9]
	s_waitcnt vmcnt(8)
	s_setprio 1
	s_barrier
; #define PG8_STAGE(bufoff, gbase, voff) do { _Pragma("unroll") for (int _i = 0; _i < 2; ++_i) \
;         __builtin_amdgcn_global_load_lds((const unsigned*)((const char*)(gbase) + (voff)[_i]), (LAS unsigned*)(lds + (bufoff) + ldsw + _i * 8192), 16, 0, 0); } while (0)
; template <class Epi, class Sched>
; __device__ __forceinline__ void gemm_phase(LAS unsigned char* lds, const Gemm g, const Sched& S, const Epi& E) {
;     ...
;         for (int t = 0; t < nt; t += 2) {
;             const bool last = (t == nt - 2);
;             const char* a1 = cA + (size_t)(t + 1) * kstep;
;             const char* a2 = last ? nA : cA + (size_t)(t + 2) * kstep; const char* b2 = last ? nB : cB + (size_t)(t + 2) * kstep;
;             const char* a3 = a2 + kstep; const char* b3 = b2 + kstep;
;             PG8_LDB(B0, 0, 0); PG8_SCHED; PG8_LDA(At, 0, 0); PG8_STAGE(PG8_SA(1, 1), a1 + hstep, voffA);
;             PG8_WAIT_L(8); PG8_BAR; PG8_WAIT_L(0); PG8_MMA(0, 0, At, B0); PG8_BAR; PG8_SCHED;
;             PG8_LDB(B1, 0, 1); PG8_STAGE(PG8_SB(0, 0), b2, voffB);
;             PG8_BAR; PG8_WAIT_L(0); PG8_MMA(0, 1, At, B1); PG8_BAR;
;             PG8_LDA(At, 0, 1); PG8_STAGE(PG8_SA(0, 0), a2, voffA);
;             PG8_BAR; PG8_WAIT_L(0); PG8_MMA(1, 0, At, B0); PG8_BAR; PG8_SCHED;
;             PG8_STAGE(PG8_SB(0, 1), b2 + hstep, voffB);
;             PG8_WAIT_V(6); PG8_BAR; PG8_MMA(1, 1, At, B1); PG8_BAR;
;             PG8_LDB(B0, 1, 0); PG8_SCHED; PG8_LDA(At, 1, 0); PG8_STAGE(PG8_SA(0, 1), a2 + hstep, voffA);
;             PG8_WAIT_L(8); PG8_BAR; PG8_WAIT_L(0); PG8_MMA(0, 0, At, B0); PG8_BAR; PG8_SCHED;
;             PG8_LDB(B1, 1, 1); PG8_STAGE(PG8_SB(1, 0), b3, voffB);
;             PG8_BAR; PG8_WAIT_L(0); PG8_MMA(0, 1, At, B1); PG8_BAR;
;             PG8_LDA(At, 1, 1); PG8_STAGE(PG8_SA(1, 0), a3, voffA);
;             PG8_BAR; PG8_WAIT_L(0); PG8_MMA(1, 0, At, B0); PG8_BAR; PG8_SCHED;
;             PG8_STAGE(PG8_SB(1, 1), b3 + hstep, voffB);
;             PG8_WAIT_V(6); PG8_BAR; PG8_MMA(1, 1, At, B1); PG8_BAR;
;     __device__ __forceinline__ void operator()(const AccT& acc, const Unit& u, int wr, int wc, int fr, int fq) const {
;     ...
;         const int rowt = u.pm * 256; const bool isc = rowt >= MX; const int b = isc ? 32 : (rowt >> 11);
;         const float* res = isc ? res_c + (size_t)(rowt - MX) * DM : res_x + (size_t)rowt * DM; bf16_t* out = hb + (size_t)rowt * DM;
	s_waitcnt lgkmcnt(0)
	v_mfma_f32_16x16x32_bf16 v[112:115], v[202:205], v[168:171], v[112:115]
	v_mfma_f32_16x16x32_bf16 v[108:111], v[210:213], v[168:171], v[108:111]
	v_mfma_f32_16x16x32_bf16 v[100:103], v[202:205], v[176:179], v[100:103]
	v_mfma_f32_16x16x32_bf16 v[92:95], v[210:213], v[176:179], v[92:95]
	v_mfma_f32_16x16x32_bf16 v[84:87], v[202:205], v[184:187], v[84:87]
	v_mfma_f32_16x16x32_bf16 v[76:79], v[210:213], v[184:187], v[76:79]
	v_mfma_f32_16x16x32_bf16 v[68:71], v[202:205], v[192:195], v[68:71]
	v_mfma_f32_16x16x32_bf16 v[64:67], v[210:213], v[192:195], v[64:67]
	v_mfma_f32_16x16x32_bf16 v[112:115], v[206:209], v[172:175], v[112:115]
	v_mfma_f32_16x16x32_bf16 v[108:111], v[214:217], v[172:175], v[108:111]
	v_mfma_f32_16x16x32_bf16 v[100:103], v[206:209], v[180:183], v[100:103]
	v_mfma_f32_16x16x32_bf16 v[92:95], v[214:217], v[180:183], v[92:95]
	v_mfma_f32_16x16x32_bf16 v[84:87], v[206:209], v[188:191], v[84:87]
	v_mfma_f32_16x16x32_bf16 v[76:79], v[214:217], v[188:191], v[76:79]
	v_mfma_f32_16x16x32_bf16 v[68:71], v[206:209], v[196:199], v[68:71]
	v_mfma_f32_16x16x32_bf16 v[64:67], v[214:217], v[196:199], v[64:67]
	s_barrier
	s_setprio 0
	s_mov_b32 m0, s52
	s_add_u32 s8, s36, 0x80
	s_addc_u32 s9, s37, 0
	ds_read_b128 v[168:171], v166 offset:49152
	ds_read_b128 v[172:175], v166 offset:50176
	ds_read_b128 v[176:179], v166 offset:51200
	ds_read_b128 v[180:183], v166 offset:52224
	ds_read_b128 v[184:187], v166 offset:53248
	ds_read_b128 v[188:191], v166 offset:54272
	ds_read_b128 v[192:195], v166 offset:55296
	ds_read_b128 v[196:199], v166 offset:56320
	global_load_lds_dwordx4 v134, s[8:9]
	s_mov_b32 m0, s53
	s_nop 0
	global_load_lds_dwordx4 v130, s[8:9]
	s_setprio 1
	s_barrier
	s_waitcnt lgkmcnt(0)
	v_mfma_f32_16x16x32_bf16 v[60:63], v[144:147], v[168:171], v[60:63]
	v_mfma_f32_16x16x32_bf16 v[56:59], v[152:155], v[168:171], v[56:59]
	v_mfma_f32_16x16x32_bf16 v[48:51], v[144:147], v[176:179], v[48:51]
	v_mfma_f32_16x16x32_bf16 v[40:43], v[152:155], v[176:179], v[40:43]
	v_mfma_f32_16x16x32_bf16 v[32:35], v[144:147], v[184:187], v[32:35]
	v_mfma_f32_16x16x32_bf16 v[24:27], v[152:155], v[184:187], v[24:27]
	v_mfma_f32_16x16x32_bf16 v[16:19], v[144:147], v[192:195], v[16:19]
	v_mfma_f32_16x16x32_bf16 v[8:11], v[152:155], v[192:195], v[8:11]
	v_mfma_f32_16x16x32_bf16 v[60:63], v[148:151], v[172:175], v[60:63]
	v_mfma_f32_16x16x32_bf16 v[56:59], v[156:159], v[172:175], v[56:59]
	v_mfma_f32_16x16x32_bf16 v[48:51], v[148:151], v[180:183], v[48:51]
	v_mfma_f32_16x16x32_bf16 v[40:43], v[156:159], v[180:183], v[40:43]
	v_mfma_f32_16x16x32_bf16 v[32:35], v[148:151], v[188:191], v[32:35]
	v_mfma_f32_16x16x32_bf16 v[24:27], v[156:159], v[188:191], v[24:27]
	v_mfma_f32_16x16x32_bf16 v[16:19], v[148:151], v[196:199], v[16:19]
	v_mfma_f32_16x16x32_bf16 v[8:11], v[156:159], v[196:199], v[8:11]
	s_barrier
	s_setprio 0
	s_add_u32 s16, s34, 0xb0080
	s_addc_u32 s17, s35, 0
	s_add_i32 s20, s21, s40
	s_mov_b32 m0, s20
	s_nop 0
	global_load_lds_dwordx4 v132, s[16:17]
	s_add_i32 m0, s20, 0x2000
	s_nop 0
	global_load_lds_dwordx4 v128, s[16:17]
	s_waitcnt vmcnt(8)
	s_setprio 1
	s_barrier
	v_mfma_f32_16x16x32_bf16 v[52:55], v[202:205], v[168:171], v[52:55]
	v_mfma_f32_16x16x32_bf16 v[44:47], v[210:213], v[168:171], v[44:47]
	v_mfma_f32_16x16x32_bf16 v[36:39], v[202:205], v[176:179], v[36:39]
	v_mfma_f32_16x16x32_bf16 v[28:31], v[210:213], v[176:179], v[28:31]
	v_mfma_f32_16x16x32_bf16 v[20:23], v[202:205], v[184:187], v[20:23]
	v_mfma_f32_16x16x32_bf16 v[12:15], v[210:213], v[184:187], v[12:15]
	v_mfma_f32_16x16x32_bf16 v[4:7], v[202:205], v[192:195], v[4:7]
	v_mfma_f32_16x16x32_bf16 v[0:3], v[210:213], v[192:195], v[0:3]
	v_mfma_f32_16x16x32_bf16 v[52:55], v[206:209], v[172:175], v[52:55]
	v_mfma_f32_16x16x32_bf16 v[44:47], v[214:217], v[172:175], v[44:47]
	v_mfma_f32_16x16x32_bf16 v[36:39], v[206:209], v[180:183], v[36:39]
	v_mfma_f32_16x16x32_bf16 v[28:31], v[214:217], v[180:183], v[28:31]
	v_mfma_f32_16x16x32_bf16 v[20:23], v[206:209], v[188:191], v[20:23]
	v_mfma_f32_16x16x32_bf16 v[12:15], v[214:217], v[188:191], v[12:15]
	v_mfma_f32_16x16x32_bf16 v[4:7], v[206:209], v[196:199], v[4:7]
	v_mfma_f32_16x16x32_bf16 v[0:3], v[214:217], v[196:199], v[0:3]
	s_barrier
	s_setprio 0
	s_add_i32 s68, s68, 2
	s_add_u32 s0, s0, 0x100
	s_addc_u32 s67, s67, 0
	s_cmp_gt_u32 s68, 41
	s_mov_b64 s[26:27], s[28:29]
	s_cbranch_scc0 .LBB0_305
	s_lshl_b32 s0, s66, 8
	v_mov_b32_e32 v145, v163
	v_mov_b32_e32 v144, v162
	s_cmpk_lt_i32 s66, 0x100
	s_cbranch_scc0 .LBB0_308
	s_ashr_i32 s29, s0, 31
	s_mov_b32 s28, s0
	s_lshl_b64 s[16:17], s[28:29], 12
	v_readlane_b32 s80, v254, 23
	v_readlane_b32 s81, v254, 24
	s_add_u32 s26, s80, s16
	v_readlane_b32 s82, v254, 25
	v_readlane_b32 s83, v254, 26
	v_readlane_b32 s84, v254, 27
	v_readlane_b32 s85, v254, 28
	v_readlane_b32 s86, v254, 29
	v_readlane_b32 s87, v254, 30
	v_readlane_b32 s88, v254, 31
	v_readlane_b32 s89, v254, 32
	v_readlane_b32 s90, v254, 33
	v_readlane_b32 s91, v254, 34
	v_readlane_b32 s92, v254, 35
	v_readlane_b32 s93, v254, 36
	v_readlane_b32 s94, v254, 37
	v_readlane_b32 s95, v254, 38
	s_addc_u32 s27, s81, s17
	s_cbranch_execnz .LBB0_297
	s_branch .LBB0_296

; #define PG8_STAGE(bufoff, gbase, voff) do { _Pragma("unroll") for (int _i = 0; _i < 2; ++_i) \
;         __builtin_amdgcn_global_load_lds((const unsigned*)((const char*)(gbase) + (voff)[_i]), (LAS unsigned*)(lds + (bufoff) + ldsw + _i * 8192), 16, 0, 0); } while (0)
; #define PG8_WAIT_V(n) asm volatile("s_waitcnt vmcnt(" #n ")" ::: "memory")
; #define PG8_WAIT_L(n) asm volatile("s_waitcnt lgkmcnt(" #n ")" ::: "memory")
; template <class Epi, class Sched>
; __device__ __forceinline__ void gemm_phase(LAS unsigned char* lds, const Gemm g, const Sched& S, const Epi& E) {
;     ...
;         const bool has_next = S.next(ui + 1, nxt);
;         const char* nA = has_next ? (const char*)g.A + (size_t)nxt.pm * tstep : cA; const char* nB = has_next ? (const char*)g.Bt + (size_t)nxt.pn * tstep : cB;
;         for (int t = 0; t < nt; t += 2) {
;             const bool last = (t == nt - 2);
;             const char* a1 = cA + (size_t)(t + 1) * kstep;
;             const char* a2 = last ? nA : cA + (size_t)(t + 2) * kstep; const char* b2 = last ? nB : cB + (size_t)(t + 2) * kstep;
;             const char* a3 = a2 + kstep; const char* b3 = b2 + kstep;
;             PG8_LDB(B0, 0, 0); PG8_SCHED; PG8_LDA(At, 0, 0); PG8_STAGE(PG8_SA(1, 1), a1 + hstep, voffA);
;             PG8_WAIT_L(8); PG8_BAR; PG8_WAIT_L(0); PG8_MMA(0, 0, At, B0); PG8_BAR; PG8_SCHED;
;             PG8_LDB(B1, 0, 1); PG8_STAGE(PG8_SB(0, 0), b2, voffB);
;             PG8_BAR; PG8_WAIT_L(0); PG8_MMA(0, 1, At, B1); PG8_BAR;
;             PG8_LDA(At, 0, 1); PG8_STAGE(PG8_SA(0, 0), a2, voffA);
;             PG8_BAR; PG8_WAIT_L(0); PG8_MMA(1, 0, At, B0); PG8_BAR; PG8_SCHED;
;             PG8_STAGE(PG8_SB(0, 1), b2 + hstep, voffB);
;             PG8_WAIT_V(6); PG8_BAR; PG8_MMA(1, 1, At, B1); PG8_BAR;
;             PG8_LDB(B0, 1, 0); PG8_SCHED; PG8_LDA(At, 1, 0); PG8_STAGE(PG8_SA(0, 1), a2 + hstep, voffA);
;             PG8_WAIT_L(8); PG8_BAR; PG8_WAIT_L(0); PG8_MMA(0, 0, At, B0); PG8_BAR; PG8_SCHED;
;             PG8_LDB(B1, 1, 1); PG8_STAGE(PG8_SB(1, 0), b3, voffB);
;             PG8_BAR; PG8_WAIT_L(0); PG8_MMA(0, 1, At, B1); PG8_BAR;
;             PG8_LDA(At, 1, 1); PG8_STAGE(PG8_SA(1, 0), a3, voffA);
;             PG8_BAR; PG8_WAIT_L(0); PG8_MMA(1, 0, At, B0); PG8_BAR; PG8_SCHED;
;             PG8_STAGE(PG8_SB(1, 1), b3 + hstep, voffB);
;             PG8_WAIT_V(6); PG8_BAR; PG8_MMA(1, 1, At, B1); PG8_BAR;
.LBB0_577:
	s_ashr_i32 s21, s20, 31
	v_cmp_lt_i64_e32 vcc, s[22:23], v[156:157]
	s_lshl_b64 s[22:23], s[20:21], 19
	s_add_u32 s22, s96, s22
	s_addc_u32 s23, s97, s23
	s_and_b64 s[24:25], vcc, exec
	s_cselect_b32 s5, s23, s7
	s_cselect_b32 s21, s22, s6
	s_ashr_i32 s19, s18, 31
	s_lshl_b64 s[24:25], s[18:19], 19
	s_add_u32 s24, s31, s24
	s_addc_u32 s25, s33, s25
	s_and_b64 s[28:29], vcc, exec
	s_cselect_b32 s19, s25, s27
	s_cselect_b32 s53, s24, s26
	s_add_u32 s6, s6, 0x40080
	s_addc_u32 s7, s7, 0
	s_add_u32 s54, s26, 0x100
	s_addc_u32 s55, s27, 0
	s_mov_b32 s56, -2
	s_waitcnt lgkmcnt(0)
	ds_read_b128 v[128:131], v167
	ds_read_b128 v[132:135], v167 offset:1024
	ds_read_b128 v[136:139], v167 offset:2048
	ds_read_b128 v[160:163], v167 offset:3072
	s_add_u32 s26, s6, 0xfffc0080
	s_addc_u32 s27, s7, -1
	s_cmp_eq_u32 s56, 12
	s_cselect_b32 s29, s5, s27
	s_cselect_b32 s28, s21, s26
	s_cselect_b32 s27, s19, s55
	s_cselect_b32 s26, s53, s54
	s_add_i32 m0, s37, 0xc000
	ds_read_b128 v[170:173], v168
	ds_read_b128 v[174:177], v168 offset:1024
	ds_read_b128 v[178:181], v168 offset:2048
	ds_read_b128 v[182:185], v168 offset:3072
	ds_read_b128 v[186:189], v168 offset:4096
	ds_read_b128 v[190:193], v168 offset:5120
	ds_read_b128 v[194:197], v168 offset:6144
	ds_read_b128 v[202:205], v168 offset:7168
	global_load_lds_dwordx4 v152, s[6:7]
	s_add_i32 m0, s37, 0xe000
	s_nop 0
	global_load_lds_dwordx4 v154, s[6:7]
	s_waitcnt lgkmcnt(8)
	s_waitcnt vmcnt(8)
	s_setprio 1
	s_barrier
	s_waitcnt lgkmcnt(0)
	v_mfma_f32_16x16x32_bf16 v[124:127], v[128:131], v[170:173], 0
	v_mfma_f32_16x16x32_bf16 v[120:123], v[136:139], v[170:173], 0
	v_mfma_f32_16x16x32_bf16 v[108:111], v[128:131], v[178:181], 0
	v_mfma_f32_16x16x32_bf16 v[104:107], v[136:139], v[178:181], 0
	v_mfma_f32_16x16x32_bf16 v[92:95], v[128:131], v[186:189], 0
	v_mfma_f32_16x16x32_bf16 v[88:91], v[136:139], v[186:189], 0
	v_mfma_f32_16x16x32_bf16 v[76:79], v[128:131], v[194:197], 0
	v_mfma_f32_16x16x32_bf16 v[72:75], v[136:139], v[194:197], 0
	v_mfma_f32_16x16x32_bf16 v[124:127], v[132:135], v[174:177], v[124:127]
	v_mfma_f32_16x16x32_bf16 v[120:123], v[160:163], v[174:177], v[120:123]
	v_mfma_f32_16x16x32_bf16 v[108:111], v[132:135], v[182:185], v[108:111]
	v_mfma_f32_16x16x32_bf16 v[104:107], v[160:163], v[182:185], v[104:107]
	v_mfma_f32_16x16x32_bf16 v[92:95], v[132:135], v[190:193], v[92:95]
	v_mfma_f32_16x16x32_bf16 v[88:91], v[160:163], v[190:193], v[88:91]
	v_mfma_f32_16x16x32_bf16 v[76:79], v[132:135], v[202:205], v[76:79]
	v_mfma_f32_16x16x32_bf16 v[72:75], v[160:163], v[202:205], v[72:75]
	s_barrier
	s_setprio 0
	s_add_i32 s57, s48, s34
	s_mov_b32 m0, s57
	ds_read_b128 v[206:209], v169
	ds_read_b128 v[210:213], v169 offset:1024
	ds_read_b128 v[214:217], v169 offset:2048
	ds_read_b128 v[218:221], v169 offset:3072
	global_load_lds_dwordx4 v146, s[26:27]
	s_add_i32 m0, s57, 0x2000
	s_nop 0
	global_load_lds_dwordx4 v142, s[26:27]
	s_waitcnt vmcnt(8)
	s_setprio 1
	s_barrier
	s_waitcnt lgkmcnt(0)
	v_mfma_f32_16x16x32_bf16 v[116:119], v[206:209], v[170:173], 0
	v_mfma_f32_16x16x32_bf16 v[112:115], v[214:217], v[170:173], 0
	v_mfma_f32_16x16x32_bf16 v[100:103], v[206:209], v[178:181], 0
	v_mfma_f32_16x16x32_bf16 v[96:99], v[214:217], v[178:181], 0
	v_mfma_f32_16x16x32_bf16 v[84:87], v[206:209], v[186:189], 0
	v_mfma_f32_16x16x32_bf16 v[80:83], v[214:217], v[186:189], 0
	v_mfma_f32_16x16x32_bf16 v[68:71], v[206:209], v[194:197], 0
	v_mfma_f32_16x16x32_bf16 v[64:67], v[214:217], v[194:197], 0
	v_mfma_f32_16x16x32_bf16 v[116:119], v[210:213], v[174:177], v[116:119]
	v_mfma_f32_16x16x32_bf16 v[112:115], v[218:221], v[174:177], v[112:115]
	v_mfma_f32_16x16x32_bf16 v[100:103], v[210:213], v[182:185], v[100:103]
	v_mfma_f32_16x16x32_bf16 v[96:99], v[218:221], v[182:185], v[96:99]
	v_mfma_f32_16x16x32_bf16 v[84:87], v[210:213], v[190:193], v[84:87]
	v_mfma_f32_16x16x32_bf16 v[80:83], v[218:221], v[190:193], v[80:83]
	v_mfma_f32_16x16x32_bf16 v[68:71], v[210:213], v[202:205], v[68:71]
	v_mfma_f32_16x16x32_bf16 v[64:67], v[218:221], v[202:205], v[64:67]
	s_barrier
	s_setprio 0
	s_mov_b32 m0, s37
	v_lshl_add_u64 v[222:223], s[28:29], 0, v[148:149]
	ds_read_b128 v[170:173], v168 offset:16384
	ds_read_b128 v[174:177], v168 offset:17408
	ds_read_b128 v[178:181], v168 offset:18432
	ds_read_b128 v[182:185], v168 offset:19456
	ds_read_b128 v[186:189], v168 offset:20480
	ds_read_b128 v[190:193], v168 offset:21504
	ds_read_b128 v[194:197], v168 offset:22528
	ds_read_b128 v[202:205], v168 offset:23552
	global_load_lds_dwordx4 v148, s[28:29]
	v_lshl_add_u64 v[224:225], s[28:29], 0, v[144:145]
	s_mov_b32 m0, s38
	s_nop 0
	global_load_lds_dwordx4 v144, s[28:29]
	s_setprio 1
	s_barrier
	s_waitcnt lgkmcnt(0)
	v_mfma_f32_16x16x32_bf16 v[60:63], v[128:131], v[170:173], 0
	v_mfma_f32_16x16x32_bf16 v[56:59], v[136:139], v[170:173], 0
	v_mfma_f32_16x16x32_bf16 v[44:47], v[128:131], v[178:181], 0
	v_mfma_f32_16x16x32_bf16 v[40:43], v[136:139], v[178:181], 0
	v_mfma_f32_16x16x32_bf16 v[28:31], v[128:131], v[186:189], 0
	v_mfma_f32_16x16x32_bf16 v[24:27], v[136:139], v[186:189], 0
	v_mfma_f32_16x16x32_bf16 v[12:15], v[128:131], v[194:197], 0
	v_mfma_f32_16x16x32_bf16 v[8:11], v[136:139], v[194:197], 0
	v_mfma_f32_16x16x32_bf16 v[60:63], v[132:135], v[174:177], v[60:63]
	v_mfma_f32_16x16x32_bf16 v[56:59], v[160:163], v[174:177], v[56:59]
	v_mfma_f32_16x16x32_bf16 v[44:47], v[132:135], v[182:185], v[44:47]
	v_mfma_f32_16x16x32_bf16 v[40:43], v[160:163], v[182:185], v[40:43]
	v_mfma_f32_16x16x32_bf16 v[28:31], v[132:135], v[190:193], v[28:31]
	v_mfma_f32_16x16x32_bf16 v[24:27], v[160:163], v[190:193], v[24:27]
	v_mfma_f32_16x16x32_bf16 v[12:15], v[132:135], v[202:205], v[12:15]
	v_mfma_f32_16x16x32_bf16 v[8:11], v[160:163], v[202:205], v[8:11]
	s_barrier
; #define PG8_STAGE(bufoff, gbase, voff) do { _Pragma("unroll") for (int _i = 0; _i < 2; ++_i) \
;         __builtin_amdgcn_global_load_lds((const unsigned*)((const char*)(gbase) + (voff)[_i]), (LAS unsigned*)(lds + (bufoff) + ldsw + _i * 8192), 16, 0, 0); } while (0)
; #define PG8_LDA(dst, b, h) do { _Pragma("unroll") for (int m = 0; m < 4; ++m) _Pragma("unroll") for (int k = 0; k < 2; ++k) dst[m][k] = *(const LAS bf16x8*)(lds + PG8_SA(b, h) + aoff + m * 2048 + k * 1024); } while (0)
; #define PG8_LDB(dst, b, h) do { _Pragma("unroll") for (int n = 0; n < 2; ++n) _Pragma("unroll") for (int k = 0; k < 2; ++k) dst[n][k] = *(const LAS bf16x8*)(lds + PG8_SB(b, h) + boff + n * 2048 + k * 1024); } while (0)
; #define PG8_WAIT_V(n) asm volatile("s_waitcnt vmcnt(" #n ")" ::: "memory")
; #define PG8_WAIT_L(n) asm volatile("s_waitcnt lgkmcnt(" #n ")" ::: "memory")
; #define PG8_BAR __builtin_amdgcn_s_barrier()
; #define PG8_SCHED __builtin_amdgcn_sched_barrier(0)
; template <class Epi, class Sched>
; __device__ __forceinline__ void gemm_phase(LAS unsigned char* lds, const Gemm g, const Sched& S, const Epi& E) {
;     ...
;             PG8_LDB(B0, 0, 0); PG8_SCHED; PG8_LDA(At, 0, 0); PG8_STAGE(PG8_SA(1, 1), a1 + hstep, voffA);
;             PG8_WAIT_L(8); PG8_BAR; PG8_WAIT_L(0); PG8_MMA(0, 0, At, B0); PG8_BAR; PG8_SCHED;
;             PG8_LDB(B1, 0, 1); PG8_STAGE(PG8_SB(0, 0), b2, voffB);
;             PG8_BAR; PG8_WAIT_L(0); PG8_MMA(0, 1, At, B1); PG8_BAR;
;             PG8_LDA(At, 0, 1); PG8_STAGE(PG8_SA(0, 0), a2, voffA);
;             PG8_BAR; PG8_WAIT_L(0); PG8_MMA(1, 0, At, B0); PG8_BAR; PG8_SCHED;
;             PG8_STAGE(PG8_SB(0, 1), b2 + hstep, voffB);
;             PG8_WAIT_V(6); PG8_BAR; PG8_MMA(1, 1, At, B1); PG8_BAR;
;             PG8_LDB(B0, 1, 0); PG8_SCHED; PG8_LDA(At, 1, 0); PG8_STAGE(PG8_SA(0, 1), a2 + hstep, voffA);
;             PG8_WAIT_L(8); PG8_BAR; PG8_WAIT_L(0); PG8_MMA(0, 0, At, B0); PG8_BAR; PG8_SCHED;
;             PG8_LDB(B1, 1, 1); PG8_STAGE(PG8_SB(1, 0), b3, voffB);
;             PG8_BAR; PG8_WAIT_L(0); PG8_MMA(0, 1, At, B1); PG8_BAR;
;             PG8_LDA(At, 1, 1); PG8_STAGE(PG8_SA(1, 0), a3, voffA);
;             PG8_BAR; PG8_WAIT_L(0); PG8_MMA(1, 0, At, B0); PG8_BAR; PG8_SCHED;
;             PG8_STAGE(PG8_SB(1, 1), b3 + hstep, voffB);
;             PG8_WAIT_V(6); PG8_BAR; PG8_MMA(1, 1, At, B1); PG8_BAR;
	s_setprio 0
	s_add_u32 s58, s26, 0x40000
	s_addc_u32 s59, s27, 0
	s_add_i32 s57, s49, s34
	s_mov_b32 m0, s57
	s_nop 0
	global_load_lds_dwordx4 v146, s[58:59]
	s_add_i32 m0, s57, 0x2000
	s_nop 0
	global_load_lds_dwordx4 v142, s[58:59]
	s_add_u32 s28, s28, 0x40000
	s_addc_u32 s29, s29, 0
	s_mov_b32 m0, s39
	s_nop 0
	global_load_lds_dwordx4 v148, s[28:29]
	s_mov_b32 m0, s40
	s_nop 0
	global_load_lds_dwordx4 v144, s[28:29]
	s_waitcnt vmcnt(10)
	s_setprio 1
	s_barrier
	v_mfma_f32_16x16x32_bf16 v[52:55], v[206:209], v[170:173], 0
	v_mfma_f32_16x16x32_bf16 v[48:51], v[214:217], v[170:173], 0
	v_mfma_f32_16x16x32_bf16 v[36:39], v[206:209], v[178:181], 0
	v_mfma_f32_16x16x32_bf16 v[32:35], v[214:217], v[178:181], 0
	v_mfma_f32_16x16x32_bf16 v[20:23], v[206:209], v[186:189], 0
	v_mfma_f32_16x16x32_bf16 v[16:19], v[214:217], v[186:189], 0
	v_mfma_f32_16x16x32_bf16 v[4:7], v[206:209], v[194:197], 0
	v_mfma_f32_16x16x32_bf16 v[0:3], v[214:217], v[194:197], 0
	v_mfma_f32_16x16x32_bf16 v[52:55], v[210:213], v[174:177], v[52:55]
	v_mfma_f32_16x16x32_bf16 v[48:51], v[218:221], v[174:177], v[48:51]
	v_mfma_f32_16x16x32_bf16 v[36:39], v[210:213], v[182:185], v[36:39]
	v_mfma_f32_16x16x32_bf16 v[32:35], v[218:221], v[182:185], v[32:35]
	v_mfma_f32_16x16x32_bf16 v[20:23], v[210:213], v[190:193], v[20:23]
	v_mfma_f32_16x16x32_bf16 v[16:19], v[218:221], v[190:193], v[16:19]
	v_mfma_f32_16x16x32_bf16 v[4:7], v[210:213], v[202:205], v[4:7]
	v_mfma_f32_16x16x32_bf16 v[0:3], v[218:221], v[202:205], v[0:3]
	s_barrier
	s_setprio 0
	s_add_i32 s57, 0, 0x18000
	v_add_u32_e32 v150, s57, v166
	ds_read_b128 v[128:131], v150
	ds_read_b128 v[132:135], v150 offset:1024
	ds_read_b128 v[136:139], v150 offset:2048
	ds_read_b128 v[160:163], v150 offset:3072
	ds_read_b128 v[170:173], v168 offset:32768
	ds_read_b128 v[174:177], v168 offset:33792
	ds_read_b128 v[178:181], v168 offset:34816
	ds_read_b128 v[182:185], v168 offset:35840
	ds_read_b128 v[186:189], v168 offset:36864
	ds_read_b128 v[190:193], v168 offset:37888
	ds_read_b128 v[194:197], v168 offset:38912
	ds_read_b128 v[202:205], v168 offset:39936
	s_waitcnt lgkmcnt(8)
	s_waitcnt vmcnt(8)
	s_setprio 1
	s_barrier
	s_waitcnt lgkmcnt(0)
	v_mfma_f32_16x16x32_bf16 v[124:127], v[128:131], v[170:173], v[124:127]
	v_mfma_f32_16x16x32_bf16 v[120:123], v[136:139], v[170:173], v[120:123]
	v_mfma_f32_16x16x32_bf16 v[108:111], v[128:131], v[178:181], v[108:111]
	v_mfma_f32_16x16x32_bf16 v[104:107], v[136:139], v[178:181], v[104:107]
	v_mfma_f32_16x16x32_bf16 v[92:95], v[128:131], v[186:189], v[92:95]
	v_mfma_f32_16x16x32_bf16 v[88:91], v[136:139], v[186:189], v[88:91]
	v_mfma_f32_16x16x32_bf16 v[76:79], v[128:131], v[194:197], v[76:79]
	v_mfma_f32_16x16x32_bf16 v[72:75], v[136:139], v[194:197], v[72:75]
	v_mfma_f32_16x16x32_bf16 v[124:127], v[132:135], v[174:177], v[124:127]
	v_mfma_f32_16x16x32_bf16 v[120:123], v[160:163], v[174:177], v[120:123]
	v_mfma_f32_16x16x32_bf16 v[108:111], v[132:135], v[182:185], v[108:111]
	v_mfma_f32_16x16x32_bf16 v[104:107], v[160:163], v[182:185], v[104:107]
	v_mfma_f32_16x16x32_bf16 v[92:95], v[132:135], v[190:193], v[92:95]
	v_mfma_f32_16x16x32_bf16 v[88:91], v[160:163], v[190:193], v[88:91]
	v_mfma_f32_16x16x32_bf16 v[76:79], v[132:135], v[202:205], v[76:79]
	v_mfma_f32_16x16x32_bf16 v[72:75], v[160:163], v[202:205], v[72:75]
	s_barrier
	s_setprio 0
	s_add_i32 s28, 0, 0x1c000
	s_add_i32 s29, s57, s34
	v_add_u32_e32 v150, s28, v166
	s_add_u32 s0, s26, 0x80
	s_addc_u32 s1, s27, 0
	s_mov_b32 m0, s29
	ds_read_b128 v[206:209], v150
	ds_read_b128 v[210:213], v150 offset:1024
	ds_read_b128 v[214:217], v150 offset:2048
	ds_read_b128 v[218:221], v150 offset:3072
	global_load_lds_dwordx4 v146, s[0:1]
	s_add_i32 m0, s29, 0x2000
	s_nop 0
	global_load_lds_dwordx4 v142, s[0:1]
	s_waitcnt vmcnt(8)
	s_setprio 1
	s_barrier
	s_waitcnt lgkmcnt(0)
	v_mfma_f32_16x16x32_bf16 v[116:119], v[206:209], v[170:173], v[116:119]
	v_mfma_f32_16x16x32_bf16 v[112:115], v[214:217], v[170:173], v[112:115]
	v_mfma_f32_16x16x32_bf16 v[100:103], v[206:209], v[178:181], v[100:103]
	v_mfma_f32_16x16x32_bf16 v[96:99], v[214:217], v[178:181], v[96:99]
	v_mfma_f32_16x16x32_bf16 v[84:87], v[206:209], v[186:189], v[84:87]
	v_mfma_f32_16x16x32_bf16 v[80:83], v[214:217], v[186:189], v[80:83]
	v_mfma_f32_16x16x32_bf16 v[68:71], v[206:209], v[194:197], v[68:71]
	v_mfma_f32_16x16x32_bf16 v[64:67], v[214:217], v[194:197], v[64:67]
	v_mfma_f32_16x16x32_bf16 v[116:119], v[210:213], v[174:177], v[116:119]
	v_mfma_f32_16x16x32_bf16 v[112:115], v[218:221], v[174:177], v[112:115]
	v_mfma_f32_16x16x32_bf16 v[100:103], v[210:213], v[182:185], v[100:103]
	v_mfma_f32_16x16x32_bf16 v[96:99], v[218:221], v[182:185], v[96:99]
	v_mfma_f32_16x16x32_bf16 v[84:87], v[210:213], v[190:193], v[84:87]
	v_mfma_f32_16x16x32_bf16 v[80:83], v[218:221], v[190:193], v[80:83]
	v_mfma_f32_16x16x32_bf16 v[68:71], v[210:213], v[202:205], v[68:71]
	v_mfma_f32_16x16x32_bf16 v[64:67], v[218:221], v[202:205], v[64:67]
	s_barrier
	s_setprio 0
	s_mov_b32 m0, s44
	s_mov_b64 s[0:1], 0x80
	v_lshl_add_u64 v[140:141], v[222:223], 0, s[0:1]
	ds_read_b128 v[170:173], v168 offset:49152
	ds_read_b128 v[174:177], v168 offset:50176
	ds_read_b128 v[178:181], v168 offset:51200
	ds_read_b128 v[182:185], v168 offset:52224
	ds_read_b128 v[186:189], v168 offset:53248
	ds_read_b128 v[190:193], v168 offset:54272
	ds_read_b128 v[194:197], v168 offset:55296
	ds_read_b128 v[202:205], v168 offset:56320
	global_load_lds_dwordx4 v[140:141], off
	v_lshl_add_u64 v[140:141], v[224:225], 0, s[0:1]
	s_mov_b32 m0, s45
	s_nop 0
	global_load_lds_dwordx4 v[140:141], off
	s_setprio 1
	s_barrier
; #define PG8_STAGE(bufoff, gbase, voff) do { _Pragma("unroll") for (int _i = 0; _i < 2; ++_i) \
;         __builtin_amdgcn_global_load_lds((const unsigned*)((const char*)(gbase) + (voff)[_i]), (LAS unsigned*)(lds + (bufoff) + ldsw + _i * 8192), 16, 0, 0); } while (0)
; #define PG8_LDA(dst, b, h) do { _Pragma("unroll") for (int m = 0; m < 4; ++m) _Pragma("unroll") for (int k = 0; k < 2; ++k) dst[m][k] = *(const LAS bf16x8*)(lds + PG8_SA(b, h) + aoff + m * 2048 + k * 1024); } while (0)
; #define PG8_WAIT_V(n) asm volatile("s_waitcnt vmcnt(" #n ")" ::: "memory")
; #define PG8_WAIT_L(n) asm volatile("s_waitcnt lgkmcnt(" #n ")" ::: "memory")
; template <class Epi, class Sched>
; __device__ __forceinline__ void gemm_phase(LAS unsigned char* lds, const Gemm g, const Sched& S, const Epi& E) {
;     ...
;         for (int t = 0; t < nt; t += 2) {
;             const bool last = (t == nt - 2);
;             const char* a1 = cA + (size_t)(t + 1) * kstep;
;             const char* a2 = last ? nA : cA + (size_t)(t + 2) * kstep; const char* b2 = last ? nB : cB + (size_t)(t + 2) * kstep;
;             const char* a3 = a2 + kstep; const char* b3 = b2 + kstep;
;             PG8_LDB(B0, 0, 0); PG8_SCHED; PG8_LDA(At, 0, 0); PG8_STAGE(PG8_SA(1, 1), a1 + hstep, voffA);
;             PG8_WAIT_L(8); PG8_BAR; PG8_WAIT_L(0); PG8_MMA(0, 0, At, B0); PG8_BAR; PG8_SCHED;
;             PG8_LDB(B1, 0, 1); PG8_STAGE(PG8_SB(0, 0), b2, voffB);
;             PG8_BAR; PG8_WAIT_L(0); PG8_MMA(0, 1, At, B1); PG8_BAR;
;             PG8_LDA(At, 0, 1); PG8_STAGE(PG8_SA(0, 0), a2, voffA);
;             PG8_BAR; PG8_WAIT_L(0); PG8_MMA(1, 0, At, B0); PG8_BAR; PG8_SCHED;
;             PG8_STAGE(PG8_SB(0, 1), b2 + hstep, voffB);
;             PG8_WAIT_V(6); PG8_BAR; PG8_MMA(1, 1, At, B1); PG8_BAR;
;             PG8_LDB(B0, 1, 0); PG8_SCHED; PG8_LDA(At, 1, 0); PG8_STAGE(PG8_SA(0, 1), a2 + hstep, voffA);
;             PG8_WAIT_L(8); PG8_BAR; PG8_WAIT_L(0); PG8_MMA(0, 0, At, B0); PG8_BAR; PG8_SCHED;
;             PG8_LDB(B1, 1, 1); PG8_STAGE(PG8_SB(1, 0), b3, voffB);
;             PG8_BAR; PG8_WAIT_L(0); PG8_MMA(0, 1, At, B1); PG8_BAR;
;             PG8_LDA(At, 1, 1); PG8_STAGE(PG8_SA(1, 0), a3, voffA);
;             PG8_BAR; PG8_WAIT_L(0); PG8_MMA(1, 0, At, B0); PG8_BAR; PG8_SCHED;
;             PG8_STAGE(PG8_SB(1, 1), b3 + hstep, voffB);
;             PG8_WAIT_V(6); PG8_BAR; PG8_MMA(1, 1, At, B1); PG8_BAR;
	s_waitcnt lgkmcnt(0)
	v_mfma_f32_16x16x32_bf16 v[60:63], v[128:131], v[170:173], v[60:63]
	v_mfma_f32_16x16x32_bf16 v[56:59], v[136:139], v[170:173], v[56:59]
	v_mfma_f32_16x16x32_bf16 v[44:47], v[128:131], v[178:181], v[44:47]
	v_mfma_f32_16x16x32_bf16 v[40:43], v[136:139], v[178:181], v[40:43]
	v_mfma_f32_16x16x32_bf16 v[28:31], v[128:131], v[186:189], v[28:31]
	v_mfma_f32_16x16x32_bf16 v[24:27], v[136:139], v[186:189], v[24:27]
	v_mfma_f32_16x16x32_bf16 v[12:15], v[128:131], v[194:197], v[12:15]
	v_mfma_f32_16x16x32_bf16 v[8:11], v[136:139], v[194:197], v[8:11]
	v_mfma_f32_16x16x32_bf16 v[60:63], v[132:135], v[174:177], v[60:63]
	v_mfma_f32_16x16x32_bf16 v[56:59], v[160:163], v[174:177], v[56:59]
	v_mfma_f32_16x16x32_bf16 v[44:47], v[132:135], v[182:185], v[44:47]
	v_mfma_f32_16x16x32_bf16 v[40:43], v[160:163], v[182:185], v[40:43]
	v_mfma_f32_16x16x32_bf16 v[28:31], v[132:135], v[190:193], v[28:31]
	v_mfma_f32_16x16x32_bf16 v[24:27], v[160:163], v[190:193], v[24:27]
	v_mfma_f32_16x16x32_bf16 v[12:15], v[132:135], v[202:205], v[12:15]
	v_mfma_f32_16x16x32_bf16 v[8:11], v[160:163], v[202:205], v[8:11]
	s_barrier
	s_setprio 0
	s_add_u32 s26, s26, 0x40080
	s_addc_u32 s27, s27, 0
	s_add_i32 s28, s28, s34
	s_mov_b32 m0, s28
	s_nop 0
	global_load_lds_dwordx4 v146, s[26:27]
	s_add_i32 m0, s28, 0x2000
	s_nop 0
	global_load_lds_dwordx4 v142, s[26:27]
	s_waitcnt vmcnt(8)
	s_setprio 1
	s_barrier
	v_mfma_f32_16x16x32_bf16 v[52:55], v[206:209], v[170:173], v[52:55]
	v_mfma_f32_16x16x32_bf16 v[48:51], v[214:217], v[170:173], v[48:51]
	v_mfma_f32_16x16x32_bf16 v[36:39], v[206:209], v[178:181], v[36:39]
	v_mfma_f32_16x16x32_bf16 v[32:35], v[214:217], v[178:181], v[32:35]
	v_mfma_f32_16x16x32_bf16 v[20:23], v[206:209], v[186:189], v[20:23]
	v_mfma_f32_16x16x32_bf16 v[16:19], v[214:217], v[186:189], v[16:19]
	v_mfma_f32_16x16x32_bf16 v[4:7], v[206:209], v[194:197], v[4:7]
	v_mfma_f32_16x16x32_bf16 v[0:3], v[214:217], v[194:197], v[0:3]
	v_mfma_f32_16x16x32_bf16 v[52:55], v[210:213], v[174:177], v[52:55]
	v_mfma_f32_16x16x32_bf16 v[48:51], v[218:221], v[174:177], v[48:51]
	v_mfma_f32_16x16x32_bf16 v[36:39], v[210:213], v[182:185], v[36:39]
	v_mfma_f32_16x16x32_bf16 v[32:35], v[218:221], v[182:185], v[32:35]
	v_mfma_f32_16x16x32_bf16 v[20:23], v[210:213], v[190:193], v[20:23]
	v_mfma_f32_16x16x32_bf16 v[16:19], v[218:221], v[190:193], v[16:19]
	v_mfma_f32_16x16x32_bf16 v[4:7], v[210:213], v[202:205], v[4:7]
	v_mfma_f32_16x16x32_bf16 v[0:3], v[218:221], v[202:205], v[0:3]
	s_barrier
	s_setprio 0
	s_add_i32 s56, s56, 2
	s_add_u32 s6, s6, 0x100
	s_addc_u32 s7, s7, 0
	s_add_u32 s54, s54, 0x100
	s_addc_u32 s55, s55, 0
	s_cmp_gt_u32 s56, 13
.LBB0_578:
	ds_read_b128 v[128:131], v167
	ds_read_b128 v[132:135], v167 offset:1024
	ds_read_b128 v[136:139], v167 offset:2048
	ds_read_b128 v[160:163], v167 offset:3072
	s_add_u32 s26, s6, 0xfffc0080
	s_addc_u32 s27, s7, -1
	s_cmp_eq_u32 s56, 12
	s_cselect_b32 s29, s5, s27
	s_cselect_b32 s28, s21, s26
	s_cselect_b32 s27, s19, s55
	s_cselect_b32 s26, s53, s54
	s_add_i32 m0, s37, 0xc000
	ds_read_b128 v[170:173], v168
	ds_read_b128 v[174:177], v168 offset:1024
	ds_read_b128 v[178:181], v168 offset:2048
	ds_read_b128 v[182:185], v168 offset:3072
	ds_read_b128 v[186:189], v168 offset:4096
	ds_read_b128 v[190:193], v168 offset:5120
	ds_read_b128 v[194:197], v168 offset:6144
	ds_read_b128 v[202:205], v168 offset:7168
	global_load_lds_dwordx4 v152, s[6:7]
	s_add_i32 m0, s37, 0xe000
	s_nop 0
	global_load_lds_dwordx4 v154, s[6:7]
	s_waitcnt lgkmcnt(8)
	s_waitcnt vmcnt(8)
	s_setprio 1
	s_barrier
	s_waitcnt lgkmcnt(0)
	v_mfma_f32_16x16x32_bf16 v[124:127], v[128:131], v[170:173], v[124:127]
	v_mfma_f32_16x16x32_bf16 v[120:123], v[136:139], v[170:173], v[120:123]
	v_mfma_f32_16x16x32_bf16 v[108:111], v[128:131], v[178:181], v[108:111]
	v_mfma_f32_16x16x32_bf16 v[104:107], v[136:139], v[178:181], v[104:107]
	v_mfma_f32_16x16x32_bf16 v[92:95], v[128:131], v[186:189], v[92:95]
	v_mfma_f32_16x16x32_bf16 v[88:91], v[136:139], v[186:189], v[88:91]
	v_mfma_f32_16x16x32_bf16 v[76:79], v[128:131], v[194:197], v[76:79]
	v_mfma_f32_16x16x32_bf16 v[72:75], v[136:139], v[194:197], v[72:75]
	v_mfma_f32_16x16x32_bf16 v[124:127], v[132:135], v[174:177], v[124:127]
	v_mfma_f32_16x16x32_bf16 v[120:123], v[160:163], v[174:177], v[120:123]
	v_mfma_f32_16x16x32_bf16 v[108:111], v[132:135], v[182:185], v[108:111]
	v_mfma_f32_16x16x32_bf16 v[104:107], v[160:163], v[182:185], v[104:107]
	v_mfma_f32_16x16x32_bf16 v[92:95], v[132:135], v[190:193], v[92:95]
	v_mfma_f32_16x16x32_bf16 v[88:91], v[160:163], v[190:193], v[88:91]
	v_mfma_f32_16x16x32_bf16 v[76:79], v[132:135], v[202:205], v[76:79]
	v_mfma_f32_16x16x32_bf16 v[72:75], v[160:163], v[202:205], v[72:75]
	s_barrier
	s_setprio 0
	s_add_i32 s57, s48, s34
	s_mov_b32 m0, s57
	ds_read_b128 v[206:209], v169
	ds_read_b128 v[210:213], v169 offset:1024
	ds_read_b128 v[214:217], v169 offset:2048
	ds_read_b128 v[218:221], v169 offset:3072
	global_load_lds_dwordx4 v146, s[26:27]
	s_add_i32 m0, s57, 0x2000
	s_nop 0
	global_load_lds_dwordx4 v142, s[26:27]
	s_waitcnt vmcnt(8)
	s_setprio 1
	s_barrier
; #define PG8_STAGE(bufoff, gbase, voff) do { _Pragma("unroll") for (int _i = 0; _i < 2; ++_i) \
;         __builtin_amdgcn_global_load_lds((const unsigned*)((const char*)(gbase) + (voff)[_i]), (LAS unsigned*)(lds + (bufoff) + ldsw + _i * 8192), 16, 0, 0); } while (0)
; #define PG8_LDA(dst, b, h) do { _Pragma("unroll") for (int m = 0; m < 4; ++m) _Pragma("unroll") for (int k = 0; k < 2; ++k) dst[m][k] = *(const LAS bf16x8*)(lds + PG8_SA(b, h) + aoff + m * 2048 + k * 1024); } while (0)
; #define PG8_LDB(dst, b, h) do { _Pragma("unroll") for (int n = 0; n < 2; ++n) _Pragma("unroll") for (int k = 0; k < 2; ++k) dst[n][k] = *(const LAS bf16x8*)(lds + PG8_SB(b, h) + boff + n * 2048 + k * 1024); } while (0)
; #define PG8_WAIT_V(n) asm volatile("s_waitcnt vmcnt(" #n ")" ::: "memory")
; #define PG8_WAIT_L(n) asm volatile("s_waitcnt lgkmcnt(" #n ")" ::: "memory")
; #define PG8_BAR __builtin_amdgcn_s_barrier()
; #define PG8_SCHED __builtin_amdgcn_sched_barrier(0)
; template <class Epi, class Sched>
; __device__ __forceinline__ void gemm_phase(LAS unsigned char* lds, const Gemm g, const Sched& S, const Epi& E) {
;     ...
;             PG8_LDB(B0, 0, 0); PG8_SCHED; PG8_LDA(At, 0, 0); PG8_STAGE(PG8_SA(1, 1), a1 + hstep, voffA);
;             PG8_WAIT_L(8); PG8_BAR; PG8_WAIT_L(0); PG8_MMA(0, 0, At, B0); PG8_BAR; PG8_SCHED;
;             PG8_LDB(B1, 0, 1); PG8_STAGE(PG8_SB(0, 0), b2, voffB);
;             PG8_BAR; PG8_WAIT_L(0); PG8_MMA(0, 1, At, B1); PG8_BAR;
;             PG8_LDA(At, 0, 1); PG8_STAGE(PG8_SA(0, 0), a2, voffA);
;             PG8_BAR; PG8_WAIT_L(0); PG8_MMA(1, 0, At, B0); PG8_BAR; PG8_SCHED;
;             PG8_STAGE(PG8_SB(0, 1), b2 + hstep, voffB);
;             PG8_WAIT_V(6); PG8_BAR; PG8_MMA(1, 1, At, B1); PG8_BAR;
;             PG8_LDB(B0, 1, 0); PG8_SCHED; PG8_LDA(At, 1, 0); PG8_STAGE(PG8_SA(0, 1), a2 + hstep, voffA);
;             PG8_WAIT_L(8); PG8_BAR; PG8_WAIT_L(0); PG8_MMA(0, 0, At, B0); PG8_BAR; PG8_SCHED;
;             PG8_LDB(B1, 1, 1); PG8_STAGE(PG8_SB(1, 0), b3, voffB);
;             PG8_BAR; PG8_WAIT_L(0); PG8_MMA(0, 1, At, B1); PG8_BAR;
;             PG8_LDA(At, 1, 1); PG8_STAGE(PG8_SA(1, 0), a3, voffA);
;             PG8_BAR; PG8_WAIT_L(0); PG8_MMA(1, 0, At, B0); PG8_BAR; PG8_SCHED;
;             PG8_STAGE(PG8_SB(1, 1), b3 + hstep, voffB);
;             PG8_WAIT_V(6); PG8_BAR; PG8_MMA(1, 1, At, B1); PG8_BAR;
	s_waitcnt lgkmcnt(0)
	v_mfma_f32_16x16x32_bf16 v[116:119], v[206:209], v[170:173], v[116:119]
	v_mfma_f32_16x16x32_bf16 v[112:115], v[214:217], v[170:173], v[112:115]
	v_mfma_f32_16x16x32_bf16 v[100:103], v[206:209], v[178:181], v[100:103]
	v_mfma_f32_16x16x32_bf16 v[96:99], v[214:217], v[178:181], v[96:99]
	v_mfma_f32_16x16x32_bf16 v[84:87], v[206:209], v[186:189], v[84:87]
	v_mfma_f32_16x16x32_bf16 v[80:83], v[214:217], v[186:189], v[80:83]
	v_mfma_f32_16x16x32_bf16 v[68:71], v[206:209], v[194:197], v[68:71]
	v_mfma_f32_16x16x32_bf16 v[64:67], v[214:217], v[194:197], v[64:67]
	v_mfma_f32_16x16x32_bf16 v[116:119], v[210:213], v[174:177], v[116:119]
	v_mfma_f32_16x16x32_bf16 v[112:115], v[218:221], v[174:177], v[112:115]
	v_mfma_f32_16x16x32_bf16 v[100:103], v[210:213], v[182:185], v[100:103]
	v_mfma_f32_16x16x32_bf16 v[96:99], v[218:221], v[182:185], v[96:99]
	v_mfma_f32_16x16x32_bf16 v[84:87], v[210:213], v[190:193], v[84:87]
	v_mfma_f32_16x16x32_bf16 v[80:83], v[218:221], v[190:193], v[80:83]
	v_mfma_f32_16x16x32_bf16 v[68:71], v[210:213], v[202:205], v[68:71]
	v_mfma_f32_16x16x32_bf16 v[64:67], v[218:221], v[202:205], v[64:67]
	s_barrier
	s_setprio 0
	s_mov_b32 m0, s37
	v_lshl_add_u64 v[222:223], s[28:29], 0, v[148:149]
	ds_read_b128 v[170:173], v168 offset:16384
	ds_read_b128 v[174:177], v168 offset:17408
	ds_read_b128 v[178:181], v168 offset:18432
	ds_read_b128 v[182:185], v168 offset:19456
	ds_read_b128 v[186:189], v168 offset:20480
	ds_read_b128 v[190:193], v168 offset:21504
	ds_read_b128 v[194:197], v168 offset:22528
	ds_read_b128 v[202:205], v168 offset:23552
	global_load_lds_dwordx4 v148, s[28:29]
	v_lshl_add_u64 v[224:225], s[28:29], 0, v[144:145]
	s_mov_b32 m0, s38
	s_nop 0
	global_load_lds_dwordx4 v144, s[28:29]
	s_setprio 1
	s_barrier
	s_waitcnt lgkmcnt(0)
	v_mfma_f32_16x16x32_bf16 v[60:63], v[128:131], v[170:173], v[60:63]
	v_mfma_f32_16x16x32_bf16 v[56:59], v[136:139], v[170:173], v[56:59]
	v_mfma_f32_16x16x32_bf16 v[44:47], v[128:131], v[178:181], v[44:47]
	v_mfma_f32_16x16x32_bf16 v[40:43], v[136:139], v[178:181], v[40:43]
	v_mfma_f32_16x16x32_bf16 v[28:31], v[128:131], v[186:189], v[28:31]
	v_mfma_f32_16x16x32_bf16 v[24:27], v[136:139], v[186:189], v[24:27]
	v_mfma_f32_16x16x32_bf16 v[12:15], v[128:131], v[194:197], v[12:15]
	v_mfma_f32_16x16x32_bf16 v[8:11], v[136:139], v[194:197], v[8:11]
	v_mfma_f32_16x16x32_bf16 v[60:63], v[132:135], v[174:177], v[60:63]
	v_mfma_f32_16x16x32_bf16 v[56:59], v[160:163], v[174:177], v[56:59]
	v_mfma_f32_16x16x32_bf16 v[44:47], v[132:135], v[182:185], v[44:47]
	v_mfma_f32_16x16x32_bf16 v[40:43], v[160:163], v[182:185], v[40:43]
	v_mfma_f32_16x16x32_bf16 v[28:31], v[132:135], v[190:193], v[28:31]
	v_mfma_f32_16x16x32_bf16 v[24:27], v[160:163], v[190:193], v[24:27]
	v_mfma_f32_16x16x32_bf16 v[12:15], v[132:135], v[202:205], v[12:15]
	v_mfma_f32_16x16x32_bf16 v[8:11], v[160:163], v[202:205], v[8:11]
	s_barrier
	s_setprio 0
	s_add_u32 s58, s26, 0x40000
	s_addc_u32 s59, s27, 0
	s_add_i32 s57, s49, s34
	s_mov_b32 m0, s57
	s_nop 0
	global_load_lds_dwordx4 v146, s[58:59]
	s_add_i32 m0, s57, 0x2000
	s_nop 0
	global_load_lds_dwordx4 v142, s[58:59]
	s_add_u32 s28, s28, 0x40000
	s_addc_u32 s29, s29, 0
	s_mov_b32 m0, s39
	s_nop 0
	global_load_lds_dwordx4 v148, s[28:29]
	s_mov_b32 m0, s40
	s_nop 0
	global_load_lds_dwordx4 v144, s[28:29]
	s_waitcnt vmcnt(10)
	s_setprio 1
	s_barrier
	v_mfma_f32_16x16x32_bf16 v[52:55], v[206:209], v[170:173], v[52:55]
	v_mfma_f32_16x16x32_bf16 v[48:51], v[214:217], v[170:173], v[48:51]
	v_mfma_f32_16x16x32_bf16 v[36:39], v[206:209], v[178:181], v[36:39]
	v_mfma_f32_16x16x32_bf16 v[32:35], v[214:217], v[178:181], v[32:35]
	v_mfma_f32_16x16x32_bf16 v[20:23], v[206:209], v[186:189], v[20:23]
	v_mfma_f32_16x16x32_bf16 v[16:19], v[214:217], v[186:189], v[16:19]
	v_mfma_f32_16x16x32_bf16 v[4:7], v[206:209], v[194:197], v[4:7]
	v_mfma_f32_16x16x32_bf16 v[0:3], v[214:217], v[194:197], v[0:3]
	v_mfma_f32_16x16x32_bf16 v[52:55], v[210:213], v[174:177], v[52:55]
	v_mfma_f32_16x16x32_bf16 v[48:51], v[218:221], v[174:177], v[48:51]
	v_mfma_f32_16x16x32_bf16 v[36:39], v[210:213], v[182:185], v[36:39]
	v_mfma_f32_16x16x32_bf16 v[32:35], v[218:221], v[182:185], v[32:35]
	v_mfma_f32_16x16x32_bf16 v[20:23], v[210:213], v[190:193], v[20:23]
	v_mfma_f32_16x16x32_bf16 v[16:19], v[218:221], v[190:193], v[16:19]
	v_mfma_f32_16x16x32_bf16 v[4:7], v[210:213], v[202:205], v[4:7]
	v_mfma_f32_16x16x32_bf16 v[0:3], v[218:221], v[202:205], v[0:3]
	s_barrier
	s_setprio 0
	s_add_i32 s57, 0, 0x18000
	v_add_u32_e32 v150, s57, v166
	ds_read_b128 v[128:131], v150
	ds_read_b128 v[132:135], v150 offset:1024
	ds_read_b128 v[136:139], v150 offset:2048
	ds_read_b128 v[160:163], v150 offset:3072
	ds_read_b128 v[170:173], v168 offset:32768
	ds_read_b128 v[174:177], v168 offset:33792
	ds_read_b128 v[178:181], v168 offset:34816
	ds_read_b128 v[182:185], v168 offset:35840
	ds_read_b128 v[186:189], v168 offset:36864
	ds_read_b128 v[190:193], v168 offset:37888
	ds_read_b128 v[194:197], v168 offset:38912
	ds_read_b128 v[202:205], v168 offset:39936
	s_waitcnt lgkmcnt(8)
	s_waitcnt vmcnt(8)
	s_setprio 1
	s_barrier
; #define PG8_STAGE(bufoff, gbase, voff) do { _Pragma("unroll") for (int _i = 0; _i < 2; ++_i) \
;         __builtin_amdgcn_global_load_lds((const unsigned*)((const char*)(gbase) + (voff)[_i]), (LAS unsigned*)(lds + (bufoff) + ldsw + _i * 8192), 16, 0, 0); } while (0)
; #define PG8_LDA(dst, b, h) do { _Pragma("unroll") for (int m = 0; m < 4; ++m) _Pragma("unroll") for (int k = 0; k < 2; ++k) dst[m][k] = *(const LAS bf16x8*)(lds + PG8_SA(b, h) + aoff + m * 2048 + k * 1024); } while (0)
; #define PG8_LDB(dst, b, h) do { _Pragma("unroll") for (int n = 0; n < 2; ++n) _Pragma("unroll") for (int k = 0; k < 2; ++k) dst[n][k] = *(const LAS bf16x8*)(lds + PG8_SB(b, h) + boff + n * 2048 + k * 1024); } while (0)
; #define PG8_WAIT_V(n) asm volatile("s_waitcnt vmcnt(" #n ")" ::: "memory")
; #define PG8_WAIT_L(n) asm volatile("s_waitcnt lgkmcnt(" #n ")" ::: "memory")
; #define PG8_BAR __builtin_amdgcn_s_barrier()
; #define PG8_SCHED __builtin_amdgcn_sched_barrier(0)
; template <class Epi, class Sched>
; __device__ __forceinline__ void gemm_phase(LAS unsigned char* lds, const Gemm g, const Sched& S, const Epi& E) {
;     ...
;             PG8_LDB(B0, 0, 0); PG8_SCHED; PG8_LDA(At, 0, 0); PG8_STAGE(PG8_SA(1, 1), a1 + hstep, voffA);
;             PG8_WAIT_L(8); PG8_BAR; PG8_WAIT_L(0); PG8_MMA(0, 0, At, B0); PG8_BAR; PG8_SCHED;
;             PG8_LDB(B1, 0, 1); PG8_STAGE(PG8_SB(0, 0), b2, voffB);
;             PG8_BAR; PG8_WAIT_L(0); PG8_MMA(0, 1, At, B1); PG8_BAR;
;             PG8_LDA(At, 0, 1); PG8_STAGE(PG8_SA(0, 0), a2, voffA);
;             PG8_BAR; PG8_WAIT_L(0); PG8_MMA(1, 0, At, B0); PG8_BAR; PG8_SCHED;
;             PG8_STAGE(PG8_SB(0, 1), b2 + hstep, voffB);
;             PG8_WAIT_V(6); PG8_BAR; PG8_MMA(1, 1, At, B1); PG8_BAR;
;             PG8_LDB(B0, 1, 0); PG8_SCHED; PG8_LDA(At, 1, 0); PG8_STAGE(PG8_SA(0, 1), a2 + hstep, voffA);
;             PG8_WAIT_L(8); PG8_BAR; PG8_WAIT_L(0); PG8_MMA(0, 0, At, B0); PG8_BAR; PG8_SCHED;
;             PG8_LDB(B1, 1, 1); PG8_STAGE(PG8_SB(1, 0), b3, voffB);
;             PG8_BAR; PG8_WAIT_L(0); PG8_MMA(0, 1, At, B1); PG8_BAR;
;             PG8_LDA(At, 1, 1); PG8_STAGE(PG8_SA(1, 0), a3, voffA);
;             PG8_BAR; PG8_WAIT_L(0); PG8_MMA(1, 0, At, B0); PG8_BAR; PG8_SCHED;
;             PG8_STAGE(PG8_SB(1, 1), b3 + hstep, voffB);
;             PG8_WAIT_V(6); PG8_BAR; PG8_MMA(1, 1, At, B1); PG8_BAR;
	s_waitcnt lgkmcnt(0)
	v_mfma_f32_16x16x32_bf16 v[124:127], v[128:131], v[170:173], v[124:127]
	v_mfma_f32_16x16x32_bf16 v[120:123], v[136:139], v[170:173], v[120:123]
	v_mfma_f32_16x16x32_bf16 v[108:111], v[128:131], v[178:181], v[108:111]
	v_mfma_f32_16x16x32_bf16 v[104:107], v[136:139], v[178:181], v[104:107]
	v_mfma_f32_16x16x32_bf16 v[92:95], v[128:131], v[186:189], v[92:95]
	v_mfma_f32_16x16x32_bf16 v[88:91], v[136:139], v[186:189], v[88:91]
	v_mfma_f32_16x16x32_bf16 v[76:79], v[128:131], v[194:197], v[76:79]
	v_mfma_f32_16x16x32_bf16 v[72:75], v[136:139], v[194:197], v[72:75]
	v_mfma_f32_16x16x32_bf16 v[124:127], v[132:135], v[174:177], v[124:127]
	v_mfma_f32_16x16x32_bf16 v[120:123], v[160:163], v[174:177], v[120:123]
	v_mfma_f32_16x16x32_bf16 v[108:111], v[132:135], v[182:185], v[108:111]
	v_mfma_f32_16x16x32_bf16 v[104:107], v[160:163], v[182:185], v[104:107]
	v_mfma_f32_16x16x32_bf16 v[92:95], v[132:135], v[190:193], v[92:95]
	v_mfma_f32_16x16x32_bf16 v[88:91], v[160:163], v[190:193], v[88:91]
	v_mfma_f32_16x16x32_bf16 v[76:79], v[132:135], v[202:205], v[76:79]
	v_mfma_f32_16x16x32_bf16 v[72:75], v[160:163], v[202:205], v[72:75]
	s_barrier
	s_setprio 0
	s_add_i32 s28, 0, 0x1c000
	s_add_i32 s29, s57, s34
	v_add_u32_e32 v150, s28, v166
	s_add_u32 s0, s26, 0x80
	s_addc_u32 s1, s27, 0
	s_mov_b32 m0, s29
	ds_read_b128 v[206:209], v150
	ds_read_b128 v[210:213], v150 offset:1024
	ds_read_b128 v[214:217], v150 offset:2048
	ds_read_b128 v[218:221], v150 offset:3072
	global_load_lds_dwordx4 v146, s[0:1]
	s_add_i32 m0, s29, 0x2000
	s_nop 0
	global_load_lds_dwordx4 v142, s[0:1]
	s_waitcnt vmcnt(8)
	s_setprio 1
	s_barrier
	s_waitcnt lgkmcnt(0)
	v_mfma_f32_16x16x32_bf16 v[116:119], v[206:209], v[170:173], v[116:119]
	v_mfma_f32_16x16x32_bf16 v[112:115], v[214:217], v[170:173], v[112:115]
	v_mfma_f32_16x16x32_bf16 v[100:103], v[206:209], v[178:181], v[100:103]
	v_mfma_f32_16x16x32_bf16 v[96:99], v[214:217], v[178:181], v[96:99]
	v_mfma_f32_16x16x32_bf16 v[84:87], v[206:209], v[186:189], v[84:87]
	v_mfma_f32_16x16x32_bf16 v[80:83], v[214:217], v[186:189], v[80:83]
	v_mfma_f32_16x16x32_bf16 v[68:71], v[206:209], v[194:197], v[68:71]
	v_mfma_f32_16x16x32_bf16 v[64:67], v[214:217], v[194:197], v[64:67]
	v_mfma_f32_16x16x32_bf16 v[116:119], v[210:213], v[174:177], v[116:119]
	v_mfma_f32_16x16x32_bf16 v[112:115], v[218:221], v[174:177], v[112:115]
	v_mfma_f32_16x16x32_bf16 v[100:103], v[210:213], v[182:185], v[100:103]
	v_mfma_f32_16x16x32_bf16 v[96:99], v[218:221], v[182:185], v[96:99]
	v_mfma_f32_16x16x32_bf16 v[84:87], v[210:213], v[190:193], v[84:87]
	v_mfma_f32_16x16x32_bf16 v[80:83], v[218:221], v[190:193], v[80:83]
	v_mfma_f32_16x16x32_bf16 v[68:71], v[210:213], v[202:205], v[68:71]
	v_mfma_f32_16x16x32_bf16 v[64:67], v[218:221], v[202:205], v[64:67]
	s_barrier
	s_setprio 0
	s_mov_b32 m0, s44
	s_mov_b64 s[0:1], 0x80
	v_lshl_add_u64 v[140:141], v[222:223], 0, s[0:1]
	ds_read_b128 v[170:173], v168 offset:49152
	ds_read_b128 v[174:177], v168 offset:50176
	ds_read_b128 v[178:181], v168 offset:51200
	ds_read_b128 v[182:185], v168 offset:52224
	ds_read_b128 v[186:189], v168 offset:53248
	ds_read_b128 v[190:193], v168 offset:54272
	ds_read_b128 v[194:197], v168 offset:55296
	ds_read_b128 v[202:205], v168 offset:56320
	global_load_lds_dwordx4 v[140:141], off
	v_lshl_add_u64 v[140:141], v[224:225], 0, s[0:1]
	s_mov_b32 m0, s45
	s_nop 0
	global_load_lds_dwordx4 v[140:141], off
	s_setprio 1
	s_barrier
; #define PG8_STAGE(bufoff, gbase, voff) do { _Pragma("unroll") for (int _i = 0; _i < 2; ++_i) \
;         __builtin_amdgcn_global_load_lds((const unsigned*)((const char*)(gbase) + (voff)[_i]), (LAS unsigned*)(lds + (bufoff) + ldsw + _i * 8192), 16, 0, 0); } while (0)
; #define PG8_LDA(dst, b, h) do { _Pragma("unroll") for (int m = 0; m < 4; ++m) _Pragma("unroll") for (int k = 0; k < 2; ++k) dst[m][k] = *(const LAS bf16x8*)(lds + PG8_SA(b, h) + aoff + m * 2048 + k * 1024); } while (0)
; #define PG8_LDB(dst, b, h) do { _Pragma("unroll") for (int n = 0; n < 2; ++n) _Pragma("unroll") for (int k = 0; k < 2; ++k) dst[n][k] = *(const LAS bf16x8*)(lds + PG8_SB(b, h) + boff + n * 2048 + k * 1024); } while (0)
; #define PG8_BAR __builtin_amdgcn_s_barrier()
; template <class Epi, class Sched>
; __device__ __forceinline__ void gemm_phase(LAS unsigned char* lds, const Gemm g, const Sched& S, const Epi& E) {
;     ...
;             PG8_WAIT_V(6); PG8_BAR; PG8_MMA(1, 1, At, B1); PG8_BAR;
;             PG8_LDB(B0, 1, 0); PG8_SCHED; PG8_LDA(At, 1, 0); PG8_STAGE(PG8_SA(0, 1), a2 + hstep, voffA);
;             PG8_WAIT_L(8); PG8_BAR; PG8_WAIT_L(0); PG8_MMA(0, 0, At, B0); PG8_BAR; PG8_SCHED;
;             PG8_LDB(B1, 1, 1); PG8_STAGE(PG8_SB(1, 0), b3, voffB);
;             PG8_BAR; PG8_WAIT_L(0); PG8_MMA(0, 1, At, B1); PG8_BAR;
;             PG8_LDA(At, 1, 1); PG8_STAGE(PG8_SA(1, 0), a3, voffA);
;             PG8_BAR; PG8_WAIT_L(0); PG8_MMA(1, 0, At, B0); PG8_BAR; PG8_SCHED;
;             PG8_STAGE(PG8_SB(1, 1), b3 + hstep, voffB);
;             PG8_WAIT_V(6); PG8_BAR; PG8_MMA(1, 1, At, B1); PG8_BAR;
;     __device__ __forceinline__ void operator()(const AccT& acc, const Unit& u, int wr, int wc, int fr, int fq) const {
;     ...
;         const int row0 = u.pm * 256 + wr * 64 + fr, col0 = u.pn * 256 + wc * 32 + 8 * fq;
;         const bool rope = u.pn < 2;
;         const int i = 4 * (wc & 1) + fq;
; #pragma unroll
;         for (int ai = 0; ai < 2; ++ai)
; #pragma unroll
;             for (int m = 0; m < 4; ++m) {
;                 const int row = row0 + ai * 128 + m * 16;
;                 f32x4 cs = {1.f, 1.f, 1.f, 1.f}, sn = {0.f, 0.f, 0.f, 0.f};
;                 if (rope) { const int t = row & 2047; const int pos = (i < 4) ? (t >> 6) : (t & 63);
;                     cs = *(const f32x4*)(ropeA + pos * 16 + ((4 * i) & 15)); sn = *(const f32x4*)(ropeA + 1024 + pos * 16 + ((4 * i) & 15)); }
	s_waitcnt lgkmcnt(0)
	v_mfma_f32_16x16x32_bf16 v[60:63], v[128:131], v[170:173], v[60:63]
	v_mfma_f32_16x16x32_bf16 v[56:59], v[136:139], v[170:173], v[56:59]
	v_mfma_f32_16x16x32_bf16 v[44:47], v[128:131], v[178:181], v[44:47]
	v_mfma_f32_16x16x32_bf16 v[40:43], v[136:139], v[178:181], v[40:43]
	v_mfma_f32_16x16x32_bf16 v[28:31], v[128:131], v[186:189], v[28:31]
	v_mfma_f32_16x16x32_bf16 v[24:27], v[136:139], v[186:189], v[24:27]
	v_mfma_f32_16x16x32_bf16 v[12:15], v[128:131], v[194:197], v[12:15]
	v_mfma_f32_16x16x32_bf16 v[8:11], v[136:139], v[194:197], v[8:11]
	v_mfma_f32_16x16x32_bf16 v[60:63], v[132:135], v[174:177], v[60:63]
	v_mfma_f32_16x16x32_bf16 v[56:59], v[160:163], v[174:177], v[56:59]
	v_mfma_f32_16x16x32_bf16 v[44:47], v[132:135], v[182:185], v[44:47]
	v_mfma_f32_16x16x32_bf16 v[40:43], v[160:163], v[182:185], v[40:43]
	v_mfma_f32_16x16x32_bf16 v[28:31], v[132:135], v[190:193], v[28:31]
	v_mfma_f32_16x16x32_bf16 v[24:27], v[160:163], v[190:193], v[24:27]
	v_mfma_f32_16x16x32_bf16 v[12:15], v[132:135], v[202:205], v[12:15]
	v_mfma_f32_16x16x32_bf16 v[8:11], v[160:163], v[202:205], v[8:11]
	s_barrier
	s_setprio 0
	s_add_u32 s26, s26, 0x40080
	s_addc_u32 s27, s27, 0
	s_add_i32 s28, s28, s34
	s_mov_b32 m0, s28
	s_nop 0
	global_load_lds_dwordx4 v146, s[26:27]
	s_add_i32 m0, s28, 0x2000
	s_nop 0
	global_load_lds_dwordx4 v142, s[26:27]
	s_waitcnt vmcnt(8)
	s_setprio 1
	s_barrier
	v_mfma_f32_16x16x32_bf16 v[52:55], v[206:209], v[170:173], v[52:55]
	v_mfma_f32_16x16x32_bf16 v[48:51], v[214:217], v[170:173], v[48:51]
	v_mfma_f32_16x16x32_bf16 v[36:39], v[206:209], v[178:181], v[36:39]
	v_mfma_f32_16x16x32_bf16 v[32:35], v[214:217], v[178:181], v[32:35]
	v_mfma_f32_16x16x32_bf16 v[20:23], v[206:209], v[186:189], v[20:23]
	v_mfma_f32_16x16x32_bf16 v[16:19], v[214:217], v[186:189], v[16:19]
	v_mfma_f32_16x16x32_bf16 v[4:7], v[206:209], v[194:197], v[4:7]
	v_mfma_f32_16x16x32_bf16 v[0:3], v[214:217], v[194:197], v[0:3]
	v_mfma_f32_16x16x32_bf16 v[52:55], v[210:213], v[174:177], v[52:55]
	v_mfma_f32_16x16x32_bf16 v[48:51], v[218:221], v[174:177], v[48:51]
	v_mfma_f32_16x16x32_bf16 v[36:39], v[210:213], v[182:185], v[36:39]
	v_mfma_f32_16x16x32_bf16 v[32:35], v[218:221], v[182:185], v[32:35]
	v_mfma_f32_16x16x32_bf16 v[20:23], v[210:213], v[190:193], v[20:23]
	v_mfma_f32_16x16x32_bf16 v[16:19], v[218:221], v[190:193], v[16:19]
	v_mfma_f32_16x16x32_bf16 v[4:7], v[210:213], v[202:205], v[4:7]
	v_mfma_f32_16x16x32_bf16 v[0:3], v[218:221], v[202:205], v[0:3]
	s_barrier
	s_setprio 0
	s_add_i32 s56, s56, 2
	s_add_u32 s6, s6, 0x100
	s_addc_u32 s7, s7, 0
	s_add_u32 s54, s54, 0x100
	s_addc_u32 s55, s55, 0
	s_cmp_gt_u32 s56, 13
	s_cbranch_scc0 .LBB0_578
	v_mov_b32_e32 v129, v165
	v_mov_b32_e32 v173, v164
	s_lshl_b32 s4, s4, 8
	s_add_i32 s4, s4, s42
	v_add_u32_e32 v128, s46, v129
	v_add_u32_e32 v170, s4, v173
	v_cmp_gt_i32_e64 s[4:5], 4, v128
	v_lshlrev_b32_e32 v128, 2, v128
	s_cmp_lt_i32 s52, 2
	v_and_b32_e32 v130, 12, v128
	s_cselect_b64 s[26:27], -1, 0
	s_cmp_gt_i32 s52, 1
	v_and_b32_e32 v172, 63, v173
	v_mov_b32_e32 v128, 1.0
	v_mov_b32_e32 v132, 0
	v_lshlrev_b32_e32 v162, 2, v130
	v_mov_b32_e32 v134, 0
	v_mov_b32_e32 v135, 0
	v_mov_b32_e32 v136, 0
	v_mov_b32_e32 v137, 0
	v_mov_b32_e32 v138, 1.0
	v_mov_b32_e32 v139, 1.0
	v_mov_b32_e32 v140, 1.0
	v_mov_b32_e32 v141, 1.0
	s_cbranch_scc1 .LBB0_581
	v_bfe_u32 v130, v170, 6, 5
	v_cndmask_b32_e64 v130, v172, v130, s[4:5]
	v_lshlrev_b32_e32 v150, 6, v130
	v_lshl_add_u64 v[130:131], s[16:17], 0, v[150:151]
	v_mov_b32_e32 v163, v151
	v_lshl_add_u64 v[134:135], s[8:9], 0, v[150:151]
	v_lshl_add_u64 v[130:131], v[130:131], 0, v[162:163]
	v_lshl_add_u64 v[134:135], v[134:135], 0, v[162:163]
	global_load_dwordx4 v[138:141], v[130:131], off
	s_nop 0
	global_load_dwordx4 v[134:137], v[134:135], off
	s_waitcnt vmcnt(0)

; #define PG8_STAGE(bufoff, gbase, voff) do { _Pragma("unroll") for (int _i = 0; _i < 2; ++_i) \
;         __builtin_amdgcn_global_load_lds((const unsigned*)((const char*)(gbase) + (voff)[_i]), (LAS unsigned*)(lds + (bufoff) + ldsw + _i * 8192), 16, 0, 0); } while (0)
; #define PG8_WAIT_V(n) asm volatile("s_waitcnt vmcnt(" #n ")" ::: "memory")
; #define PG8_WAIT_L(n) asm volatile("s_waitcnt lgkmcnt(" #n ")" ::: "memory")
; template <class Epi, class Sched>
; __device__ __forceinline__ void gemm_phase(LAS unsigned char* lds, const Gemm g, const Sched& S, const Epi& E) {
;     ...
;         const bool has_next = S.next(ui + 1, nxt);
;         const char* nA = has_next ? (const char*)g.A + (size_t)nxt.pm * tstep : cA; const char* nB = has_next ? (const char*)g.Bt + (size_t)nxt.pn * tstep : cB;
;         for (int t = 0; t < nt; t += 2) {
;             const bool last = (t == nt - 2);
;             const char* a1 = cA + (size_t)(t + 1) * kstep;
;             const char* a2 = last ? nA : cA + (size_t)(t + 2) * kstep; const char* b2 = last ? nB : cB + (size_t)(t + 2) * kstep;
;             const char* a3 = a2 + kstep; const char* b3 = b2 + kstep;
;             PG8_LDB(B0, 0, 0); PG8_SCHED; PG8_LDA(At, 0, 0); PG8_STAGE(PG8_SA(1, 1), a1 + hstep, voffA);
;             PG8_WAIT_L(8); PG8_BAR; PG8_WAIT_L(0); PG8_MMA(0, 0, At, B0); PG8_BAR; PG8_SCHED;
;             PG8_LDB(B1, 0, 1); PG8_STAGE(PG8_SB(0, 0), b2, voffB);
;             PG8_BAR; PG8_WAIT_L(0); PG8_MMA(0, 1, At, B1); PG8_BAR;
;             PG8_LDA(At, 0, 1); PG8_STAGE(PG8_SA(0, 0), a2, voffA);
;             PG8_BAR; PG8_WAIT_L(0); PG8_MMA(1, 0, At, B0); PG8_BAR; PG8_SCHED;
;             PG8_STAGE(PG8_SB(0, 1), b2 + hstep, voffB);
;             PG8_WAIT_V(6); PG8_BAR; PG8_MMA(1, 1, At, B1); PG8_BAR;
;             PG8_LDB(B0, 1, 0); PG8_SCHED; PG8_LDA(At, 1, 0); PG8_STAGE(PG8_SA(0, 1), a2 + hstep, voffA);
;             PG8_WAIT_L(8); PG8_BAR; PG8_WAIT_L(0); PG8_MMA(0, 0, At, B0); PG8_BAR; PG8_SCHED;
;             PG8_LDB(B1, 1, 1); PG8_STAGE(PG8_SB(1, 0), b3, voffB);
;             PG8_BAR; PG8_WAIT_L(0); PG8_MMA(0, 1, At, B1); PG8_BAR;
;             PG8_LDA(At, 1, 1); PG8_STAGE(PG8_SA(1, 0), a3, voffA);
;             PG8_BAR; PG8_WAIT_L(0); PG8_MMA(1, 0, At, B0); PG8_BAR; PG8_SCHED;
;             PG8_STAGE(PG8_SB(1, 1), b3 + hstep, voffB);
;             PG8_WAIT_V(6); PG8_BAR; PG8_MMA(1, 1, At, B1); PG8_BAR;
.LBB0_612:
	s_ashr_i32 s35, s34, 31
	v_cmp_lt_i64_e32 vcc, s[6:7], v[142:143]
	s_lshl_b64 s[6:7], s[34:35], 19
	s_add_u32 s36, s40, s6
	s_addc_u32 s37, s41, s7
	s_and_b64 s[6:7], vcc, exec
	s_cselect_b32 s8, s37, s1
	s_cselect_b32 s9, s36, s0
	s_ashr_i32 s31, s30, 31
	s_lshl_b64 s[6:7], s[30:31], 19
	s_add_u32 s38, s96, s6
	s_addc_u32 s39, s97, s7
	s_and_b64 s[6:7], vcc, exec
	s_cselect_b32 s31, s39, s5
	s_cselect_b32 s35, s38, s4
	s_add_u32 s0, s0, 0x40080
	s_addc_u32 s1, s1, 0
	s_add_u32 s65, s4, 0x100
	s_addc_u32 s66, s5, 0
	s_mov_b32 s67, -2
	s_waitcnt lgkmcnt(0)
	ds_read_b128 v[146:149], v171
	ds_read_b128 v[150:153], v171 offset:1024
	ds_read_b128 v[154:157], v171 offset:2048
	ds_read_b128 v[158:161], v171 offset:3072
	s_add_u32 s4, s0, 0xfffc0080
	s_addc_u32 s5, s1, -1
	s_cmp_eq_u32 s67, 12
	s_cselect_b32 s7, s8, s5
	s_cselect_b32 s6, s9, s4
	s_cselect_b32 s5, s31, s66
	s_cselect_b32 s4, s35, s65
	s_add_i32 m0, s45, 0xc000
	ds_read_b128 v[162:165], v172
	ds_read_b128 v[178:181], v172 offset:1024
	ds_read_b128 v[182:185], v172 offset:2048
	ds_read_b128 v[186:189], v172 offset:3072
	ds_read_b128 v[190:193], v172 offset:4096
	ds_read_b128 v[194:197], v172 offset:5120
	ds_read_b128 v[202:205], v172 offset:6144
	ds_read_b128 v[206:209], v172 offset:7168
	global_load_lds_dwordx4 v138, s[0:1]
	s_add_i32 m0, s45, 0xe000
	s_nop 0
	global_load_lds_dwordx4 v140, s[0:1]
	s_waitcnt lgkmcnt(8)
	s_waitcnt vmcnt(8)
	s_setprio 1
	s_barrier
	s_waitcnt lgkmcnt(0)
	v_mfma_f32_16x16x32_bf16 v[124:127], v[146:149], v[162:165], 0
	v_mfma_f32_16x16x32_bf16 v[120:123], v[154:157], v[162:165], 0
	v_mfma_f32_16x16x32_bf16 v[108:111], v[146:149], v[182:185], 0
	v_mfma_f32_16x16x32_bf16 v[104:107], v[154:157], v[182:185], 0
	v_mfma_f32_16x16x32_bf16 v[92:95], v[146:149], v[190:193], 0
	v_mfma_f32_16x16x32_bf16 v[88:91], v[154:157], v[190:193], 0
	v_mfma_f32_16x16x32_bf16 v[76:79], v[146:149], v[202:205], 0
	v_mfma_f32_16x16x32_bf16 v[72:75], v[154:157], v[202:205], 0
	v_mfma_f32_16x16x32_bf16 v[124:127], v[150:153], v[178:181], v[124:127]
	v_mfma_f32_16x16x32_bf16 v[120:123], v[158:161], v[178:181], v[120:123]
	v_mfma_f32_16x16x32_bf16 v[108:111], v[150:153], v[186:189], v[108:111]
	v_mfma_f32_16x16x32_bf16 v[104:107], v[158:161], v[186:189], v[104:107]
	v_mfma_f32_16x16x32_bf16 v[92:95], v[150:153], v[194:197], v[92:95]
	v_mfma_f32_16x16x32_bf16 v[88:91], v[158:161], v[194:197], v[88:91]
	v_mfma_f32_16x16x32_bf16 v[76:79], v[150:153], v[206:209], v[76:79]
	v_mfma_f32_16x16x32_bf16 v[72:75], v[158:161], v[206:209], v[72:75]
	s_barrier
	s_setprio 0
	s_add_i32 s68, s57, s44
	s_mov_b32 m0, s68
	ds_read_b128 v[210:213], v173
	ds_read_b128 v[214:217], v173 offset:1024
	ds_read_b128 v[218:221], v173 offset:2048
	ds_read_b128 v[222:225], v173 offset:3072
	global_load_lds_dwordx4 v130, s[4:5]
	s_add_i32 m0, s68, 0x2000
	s_nop 0
	global_load_lds_dwordx4 v134, s[4:5]
	s_waitcnt vmcnt(8)
	s_setprio 1
	s_barrier
	s_waitcnt lgkmcnt(0)
	v_mfma_f32_16x16x32_bf16 v[116:119], v[210:213], v[162:165], 0
	v_mfma_f32_16x16x32_bf16 v[112:115], v[218:221], v[162:165], 0
	v_mfma_f32_16x16x32_bf16 v[100:103], v[210:213], v[182:185], 0
	v_mfma_f32_16x16x32_bf16 v[96:99], v[218:221], v[182:185], 0
	v_mfma_f32_16x16x32_bf16 v[84:87], v[210:213], v[190:193], 0
	v_mfma_f32_16x16x32_bf16 v[80:83], v[218:221], v[190:193], 0
	v_mfma_f32_16x16x32_bf16 v[68:71], v[210:213], v[202:205], 0
	v_mfma_f32_16x16x32_bf16 v[64:67], v[218:221], v[202:205], 0
	v_mfma_f32_16x16x32_bf16 v[116:119], v[214:217], v[178:181], v[116:119]
	v_mfma_f32_16x16x32_bf16 v[112:115], v[222:225], v[178:181], v[112:115]
	v_mfma_f32_16x16x32_bf16 v[100:103], v[214:217], v[186:189], v[100:103]
	v_mfma_f32_16x16x32_bf16 v[96:99], v[222:225], v[186:189], v[96:99]
	v_mfma_f32_16x16x32_bf16 v[84:87], v[214:217], v[194:197], v[84:87]
	v_mfma_f32_16x16x32_bf16 v[80:83], v[222:225], v[194:197], v[80:83]
	v_mfma_f32_16x16x32_bf16 v[68:71], v[214:217], v[206:209], v[68:71]
	v_mfma_f32_16x16x32_bf16 v[64:67], v[222:225], v[206:209], v[64:67]
	s_barrier
	s_setprio 0
	s_mov_b32 m0, s45
	v_lshl_add_u64 v[226:227], s[6:7], 0, v[128:129]
	ds_read_b128 v[162:165], v172 offset:16384
	ds_read_b128 v[178:181], v172 offset:17408
	ds_read_b128 v[182:185], v172 offset:18432
	ds_read_b128 v[186:189], v172 offset:19456
	ds_read_b128 v[190:193], v172 offset:20480
	ds_read_b128 v[194:197], v172 offset:21504
	ds_read_b128 v[202:205], v172 offset:22528
	ds_read_b128 v[206:209], v172 offset:23552
	global_load_lds_dwordx4 v128, s[6:7]
	v_lshl_add_u64 v[228:229], s[6:7], 0, v[132:133]
	s_mov_b32 m0, s46
	s_nop 0
	global_load_lds_dwordx4 v132, s[6:7]
	s_setprio 1
	s_barrier
	s_waitcnt lgkmcnt(0)
	v_mfma_f32_16x16x32_bf16 v[60:63], v[146:149], v[162:165], 0
	v_mfma_f32_16x16x32_bf16 v[56:59], v[154:157], v[162:165], 0
	v_mfma_f32_16x16x32_bf16 v[44:47], v[146:149], v[182:185], 0
	v_mfma_f32_16x16x32_bf16 v[40:43], v[154:157], v[182:185], 0
	v_mfma_f32_16x16x32_bf16 v[28:31], v[146:149], v[190:193], 0
	v_mfma_f32_16x16x32_bf16 v[24:27], v[154:157], v[190:193], 0
	v_mfma_f32_16x16x32_bf16 v[12:15], v[146:149], v[202:205], 0
	v_mfma_f32_16x16x32_bf16 v[8:11], v[154:157], v[202:205], 0
	v_mfma_f32_16x16x32_bf16 v[60:63], v[150:153], v[178:181], v[60:63]
	v_mfma_f32_16x16x32_bf16 v[56:59], v[158:161], v[178:181], v[56:59]
	v_mfma_f32_16x16x32_bf16 v[44:47], v[150:153], v[186:189], v[44:47]
	v_mfma_f32_16x16x32_bf16 v[40:43], v[158:161], v[186:189], v[40:43]
	v_mfma_f32_16x16x32_bf16 v[28:31], v[150:153], v[194:197], v[28:31]
	v_mfma_f32_16x16x32_bf16 v[24:27], v[158:161], v[194:197], v[24:27]
	v_mfma_f32_16x16x32_bf16 v[12:15], v[150:153], v[206:209], v[12:15]
	v_mfma_f32_16x16x32_bf16 v[8:11], v[158:161], v[206:209], v[8:11]
	s_barrier
; #define PG8_STAGE(bufoff, gbase, voff) do { _Pragma("unroll") for (int _i = 0; _i < 2; ++_i) \
;         __builtin_amdgcn_global_load_lds((const unsigned*)((const char*)(gbase) + (voff)[_i]), (LAS unsigned*)(lds + (bufoff) + ldsw + _i * 8192), 16, 0, 0); } while (0)
; #define PG8_LDA(dst, b, h) do { _Pragma("unroll") for (int m = 0; m < 4; ++m) _Pragma("unroll") for (int k = 0; k < 2; ++k) dst[m][k] = *(const LAS bf16x8*)(lds + PG8_SA(b, h) + aoff + m * 2048 + k * 1024); } while (0)
; #define PG8_LDB(dst, b, h) do { _Pragma("unroll") for (int n = 0; n < 2; ++n) _Pragma("unroll") for (int k = 0; k < 2; ++k) dst[n][k] = *(const LAS bf16x8*)(lds + PG8_SB(b, h) + boff + n * 2048 + k * 1024); } while (0)
; #define PG8_WAIT_V(n) asm volatile("s_waitcnt vmcnt(" #n ")" ::: "memory")
; #define PG8_WAIT_L(n) asm volatile("s_waitcnt lgkmcnt(" #n ")" ::: "memory")
; #define PG8_BAR __builtin_amdgcn_s_barrier()
; #define PG8_SCHED __builtin_amdgcn_sched_barrier(0)
; template <class Epi, class Sched>
; __device__ __forceinline__ void gemm_phase(LAS unsigned char* lds, const Gemm g, const Sched& S, const Epi& E) {
;     ...
;             PG8_LDB(B0, 0, 0); PG8_SCHED; PG8_LDA(At, 0, 0); PG8_STAGE(PG8_SA(1, 1), a1 + hstep, voffA);
;             PG8_WAIT_L(8); PG8_BAR; PG8_WAIT_L(0); PG8_MMA(0, 0, At, B0); PG8_BAR; PG8_SCHED;
;             PG8_LDB(B1, 0, 1); PG8_STAGE(PG8_SB(0, 0), b2, voffB);
;             PG8_BAR; PG8_WAIT_L(0); PG8_MMA(0, 1, At, B1); PG8_BAR;
;             PG8_LDA(At, 0, 1); PG8_STAGE(PG8_SA(0, 0), a2, voffA);
;             PG8_BAR; PG8_WAIT_L(0); PG8_MMA(1, 0, At, B0); PG8_BAR; PG8_SCHED;
;             PG8_STAGE(PG8_SB(0, 1), b2 + hstep, voffB);
;             PG8_WAIT_V(6); PG8_BAR; PG8_MMA(1, 1, At, B1); PG8_BAR;
;             PG8_LDB(B0, 1, 0); PG8_SCHED; PG8_LDA(At, 1, 0); PG8_STAGE(PG8_SA(0, 1), a2 + hstep, voffA);
;             PG8_WAIT_L(8); PG8_BAR; PG8_WAIT_L(0); PG8_MMA(0, 0, At, B0); PG8_BAR; PG8_SCHED;
;             PG8_LDB(B1, 1, 1); PG8_STAGE(PG8_SB(1, 0), b3, voffB);
;             PG8_BAR; PG8_WAIT_L(0); PG8_MMA(0, 1, At, B1); PG8_BAR;
;             PG8_LDA(At, 1, 1); PG8_STAGE(PG8_SA(1, 0), a3, voffA);
;             PG8_BAR; PG8_WAIT_L(0); PG8_MMA(1, 0, At, B0); PG8_BAR; PG8_SCHED;
;             PG8_STAGE(PG8_SB(1, 1), b3 + hstep, voffB);
;             PG8_WAIT_V(6); PG8_BAR; PG8_MMA(1, 1, At, B1); PG8_BAR;
	s_setprio 0
	s_add_u32 s68, s4, 0x40000
	s_addc_u32 s69, s5, 0
	s_add_i32 s70, s58, s44
	s_mov_b32 m0, s70
	s_nop 0
	global_load_lds_dwordx4 v130, s[68:69]
	s_add_i32 m0, s70, 0x2000
	s_nop 0
	global_load_lds_dwordx4 v134, s[68:69]
	s_add_u32 s6, s6, 0x40000
	s_addc_u32 s7, s7, 0
	s_mov_b32 m0, s47
	s_nop 0
	global_load_lds_dwordx4 v128, s[6:7]
	s_mov_b32 m0, s48
	s_nop 0
	global_load_lds_dwordx4 v132, s[6:7]
	s_waitcnt vmcnt(10)
	s_setprio 1
	s_barrier
	v_mfma_f32_16x16x32_bf16 v[52:55], v[210:213], v[162:165], 0
	v_mfma_f32_16x16x32_bf16 v[48:51], v[218:221], v[162:165], 0
	v_mfma_f32_16x16x32_bf16 v[36:39], v[210:213], v[182:185], 0
	v_mfma_f32_16x16x32_bf16 v[32:35], v[218:221], v[182:185], 0
	v_mfma_f32_16x16x32_bf16 v[20:23], v[210:213], v[190:193], 0
	v_mfma_f32_16x16x32_bf16 v[16:19], v[218:221], v[190:193], 0
	v_mfma_f32_16x16x32_bf16 v[4:7], v[210:213], v[202:205], 0
	v_mfma_f32_16x16x32_bf16 v[0:3], v[218:221], v[202:205], 0
	v_mfma_f32_16x16x32_bf16 v[52:55], v[214:217], v[178:181], v[52:55]
	v_mfma_f32_16x16x32_bf16 v[48:51], v[222:225], v[178:181], v[48:51]
	v_mfma_f32_16x16x32_bf16 v[36:39], v[214:217], v[186:189], v[36:39]
	v_mfma_f32_16x16x32_bf16 v[32:35], v[222:225], v[186:189], v[32:35]
	v_mfma_f32_16x16x32_bf16 v[20:23], v[214:217], v[194:197], v[20:23]
	v_mfma_f32_16x16x32_bf16 v[16:19], v[222:225], v[194:197], v[16:19]
	v_mfma_f32_16x16x32_bf16 v[4:7], v[214:217], v[206:209], v[4:7]
	v_mfma_f32_16x16x32_bf16 v[0:3], v[222:225], v[206:209], v[0:3]
	s_barrier
	s_setprio 0
	s_add_i32 s68, 0, 0x18000
	v_add_u32_e32 v136, s68, v170
	ds_read_b128 v[146:149], v136
	ds_read_b128 v[150:153], v136 offset:1024
	ds_read_b128 v[154:157], v136 offset:2048
	ds_read_b128 v[158:161], v136 offset:3072
	ds_read_b128 v[162:165], v172 offset:32768
	ds_read_b128 v[178:181], v172 offset:33792
	ds_read_b128 v[182:185], v172 offset:34816
	ds_read_b128 v[186:189], v172 offset:35840
	ds_read_b128 v[190:193], v172 offset:36864
	ds_read_b128 v[194:197], v172 offset:37888
	ds_read_b128 v[202:205], v172 offset:38912
	ds_read_b128 v[206:209], v172 offset:39936
	s_waitcnt lgkmcnt(8)
	s_waitcnt vmcnt(8)
	s_setprio 1
	s_barrier
	s_waitcnt lgkmcnt(0)
	v_mfma_f32_16x16x32_bf16 v[124:127], v[146:149], v[162:165], v[124:127]
	v_mfma_f32_16x16x32_bf16 v[120:123], v[154:157], v[162:165], v[120:123]
	v_mfma_f32_16x16x32_bf16 v[108:111], v[146:149], v[182:185], v[108:111]
	v_mfma_f32_16x16x32_bf16 v[104:107], v[154:157], v[182:185], v[104:107]
	v_mfma_f32_16x16x32_bf16 v[92:95], v[146:149], v[190:193], v[92:95]
	v_mfma_f32_16x16x32_bf16 v[88:91], v[154:157], v[190:193], v[88:91]
	v_mfma_f32_16x16x32_bf16 v[76:79], v[146:149], v[202:205], v[76:79]
	v_mfma_f32_16x16x32_bf16 v[72:75], v[154:157], v[202:205], v[72:75]
	v_mfma_f32_16x16x32_bf16 v[124:127], v[150:153], v[178:181], v[124:127]
	v_mfma_f32_16x16x32_bf16 v[120:123], v[158:161], v[178:181], v[120:123]
	v_mfma_f32_16x16x32_bf16 v[108:111], v[150:153], v[186:189], v[108:111]
	v_mfma_f32_16x16x32_bf16 v[104:107], v[158:161], v[186:189], v[104:107]
	v_mfma_f32_16x16x32_bf16 v[92:95], v[150:153], v[194:197], v[92:95]
	v_mfma_f32_16x16x32_bf16 v[88:91], v[158:161], v[194:197], v[88:91]
	v_mfma_f32_16x16x32_bf16 v[76:79], v[150:153], v[206:209], v[76:79]
	v_mfma_f32_16x16x32_bf16 v[72:75], v[158:161], v[206:209], v[72:75]
	s_barrier
	s_setprio 0
	s_add_i32 s6, 0, 0x1c000
	s_add_i32 s7, s68, s44
	v_add_u32_e32 v136, s6, v170
	s_add_u32 s20, s4, 0x80
	s_addc_u32 s21, s5, 0
	s_mov_b32 m0, s7
	ds_read_b128 v[210:213], v136
	ds_read_b128 v[214:217], v136 offset:1024
	ds_read_b128 v[218:221], v136 offset:2048
	ds_read_b128 v[222:225], v136 offset:3072
	global_load_lds_dwordx4 v130, s[20:21]
	s_add_i32 m0, s7, 0x2000
	s_nop 0
	global_load_lds_dwordx4 v134, s[20:21]
	s_waitcnt vmcnt(8)
	s_setprio 1
	s_barrier
	s_waitcnt lgkmcnt(0)
	v_mfma_f32_16x16x32_bf16 v[116:119], v[210:213], v[162:165], v[116:119]
	v_mfma_f32_16x16x32_bf16 v[112:115], v[218:221], v[162:165], v[112:115]
	v_mfma_f32_16x16x32_bf16 v[100:103], v[210:213], v[182:185], v[100:103]
	v_mfma_f32_16x16x32_bf16 v[96:99], v[218:221], v[182:185], v[96:99]
	v_mfma_f32_16x16x32_bf16 v[84:87], v[210:213], v[190:193], v[84:87]
	v_mfma_f32_16x16x32_bf16 v[80:83], v[218:221], v[190:193], v[80:83]
	v_mfma_f32_16x16x32_bf16 v[68:71], v[210:213], v[202:205], v[68:71]
	v_mfma_f32_16x16x32_bf16 v[64:67], v[218:221], v[202:205], v[64:67]
	v_mfma_f32_16x16x32_bf16 v[116:119], v[214:217], v[178:181], v[116:119]
	v_mfma_f32_16x16x32_bf16 v[112:115], v[222:225], v[178:181], v[112:115]
	v_mfma_f32_16x16x32_bf16 v[100:103], v[214:217], v[186:189], v[100:103]
	v_mfma_f32_16x16x32_bf16 v[96:99], v[222:225], v[186:189], v[96:99]
	v_mfma_f32_16x16x32_bf16 v[84:87], v[214:217], v[194:197], v[84:87]
	v_mfma_f32_16x16x32_bf16 v[80:83], v[222:225], v[194:197], v[80:83]
	v_mfma_f32_16x16x32_bf16 v[68:71], v[214:217], v[206:209], v[68:71]
	v_mfma_f32_16x16x32_bf16 v[64:67], v[222:225], v[206:209], v[64:67]
	s_barrier
	s_setprio 0
	s_mov_b32 m0, s54
	s_mov_b64 s[20:21], 0x80
	v_lshl_add_u64 v[166:167], v[226:227], 0, s[20:21]
	ds_read_b128 v[162:165], v172 offset:49152
	ds_read_b128 v[178:181], v172 offset:50176
	ds_read_b128 v[182:185], v172 offset:51200
	ds_read_b128 v[186:189], v172 offset:52224
	ds_read_b128 v[190:193], v172 offset:53248
	ds_read_b128 v[194:197], v172 offset:54272
	ds_read_b128 v[202:205], v172 offset:55296
	ds_read_b128 v[206:209], v172 offset:56320
	global_load_lds_dwordx4 v[166:167], off
	v_lshl_add_u64 v[166:167], v[228:229], 0, s[20:21]
	s_mov_b32 m0, s55
	s_nop 0
	global_load_lds_dwordx4 v[166:167], off
	s_setprio 1
	s_barrier
; #define PG8_STAGE(bufoff, gbase, voff) do { _Pragma("unroll") for (int _i = 0; _i < 2; ++_i) \
;         __builtin_amdgcn_global_load_lds((const unsigned*)((const char*)(gbase) + (voff)[_i]), (LAS unsigned*)(lds + (bufoff) + ldsw + _i * 8192), 16, 0, 0); } while (0)
; #define PG8_LDA(dst, b, h) do { _Pragma("unroll") for (int m = 0; m < 4; ++m) _Pragma("unroll") for (int k = 0; k < 2; ++k) dst[m][k] = *(const LAS bf16x8*)(lds + PG8_SA(b, h) + aoff + m * 2048 + k * 1024); } while (0)
; #define PG8_WAIT_V(n) asm volatile("s_waitcnt vmcnt(" #n ")" ::: "memory")
; #define PG8_WAIT_L(n) asm volatile("s_waitcnt lgkmcnt(" #n ")" ::: "memory")
; template <class Epi, class Sched>
; __device__ __forceinline__ void gemm_phase(LAS unsigned char* lds, const Gemm g, const Sched& S, const Epi& E) {
;     ...
;         for (int t = 0; t < nt; t += 2) {
;             const bool last = (t == nt - 2);
;             const char* a1 = cA + (size_t)(t + 1) * kstep;
;             const char* a2 = last ? nA : cA + (size_t)(t + 2) * kstep; const char* b2 = last ? nB : cB + (size_t)(t + 2) * kstep;
;             const char* a3 = a2 + kstep; const char* b3 = b2 + kstep;
;             PG8_LDB(B0, 0, 0); PG8_SCHED; PG8_LDA(At, 0, 0); PG8_STAGE(PG8_SA(1, 1), a1 + hstep, voffA);
;             PG8_WAIT_L(8); PG8_BAR; PG8_WAIT_L(0); PG8_MMA(0, 0, At, B0); PG8_BAR; PG8_SCHED;
;             PG8_LDB(B1, 0, 1); PG8_STAGE(PG8_SB(0, 0), b2, voffB);
;             PG8_BAR; PG8_WAIT_L(0); PG8_MMA(0, 1, At, B1); PG8_BAR;
;             PG8_LDA(At, 0, 1); PG8_STAGE(PG8_SA(0, 0), a2, voffA);
;             PG8_BAR; PG8_WAIT_L(0); PG8_MMA(1, 0, At, B0); PG8_BAR; PG8_SCHED;
;             PG8_STAGE(PG8_SB(0, 1), b2 + hstep, voffB);
;             PG8_WAIT_V(6); PG8_BAR; PG8_MMA(1, 1, At, B1); PG8_BAR;
;             PG8_LDB(B0, 1, 0); PG8_SCHED; PG8_LDA(At, 1, 0); PG8_STAGE(PG8_SA(0, 1), a2 + hstep, voffA);
;             PG8_WAIT_L(8); PG8_BAR; PG8_WAIT_L(0); PG8_MMA(0, 0, At, B0); PG8_BAR; PG8_SCHED;
;             PG8_LDB(B1, 1, 1); PG8_STAGE(PG8_SB(1, 0), b3, voffB);
;             PG8_BAR; PG8_WAIT_L(0); PG8_MMA(0, 1, At, B1); PG8_BAR;
;             PG8_LDA(At, 1, 1); PG8_STAGE(PG8_SA(1, 0), a3, voffA);
;             PG8_BAR; PG8_WAIT_L(0); PG8_MMA(1, 0, At, B0); PG8_BAR; PG8_SCHED;
;             PG8_STAGE(PG8_SB(1, 1), b3 + hstep, voffB);
;             PG8_WAIT_V(6); PG8_BAR; PG8_MMA(1, 1, At, B1); PG8_BAR;
	s_waitcnt lgkmcnt(0)
	v_mfma_f32_16x16x32_bf16 v[60:63], v[146:149], v[162:165], v[60:63]
	v_mfma_f32_16x16x32_bf16 v[56:59], v[154:157], v[162:165], v[56:59]
	v_mfma_f32_16x16x32_bf16 v[44:47], v[146:149], v[182:185], v[44:47]
	v_mfma_f32_16x16x32_bf16 v[40:43], v[154:157], v[182:185], v[40:43]
	v_mfma_f32_16x16x32_bf16 v[28:31], v[146:149], v[190:193], v[28:31]
	v_mfma_f32_16x16x32_bf16 v[24:27], v[154:157], v[190:193], v[24:27]
	v_mfma_f32_16x16x32_bf16 v[12:15], v[146:149], v[202:205], v[12:15]
	v_mfma_f32_16x16x32_bf16 v[8:11], v[154:157], v[202:205], v[8:11]
	v_mfma_f32_16x16x32_bf16 v[60:63], v[150:153], v[178:181], v[60:63]
	v_mfma_f32_16x16x32_bf16 v[56:59], v[158:161], v[178:181], v[56:59]
	v_mfma_f32_16x16x32_bf16 v[44:47], v[150:153], v[186:189], v[44:47]
	v_mfma_f32_16x16x32_bf16 v[40:43], v[158:161], v[186:189], v[40:43]
	v_mfma_f32_16x16x32_bf16 v[28:31], v[150:153], v[194:197], v[28:31]
	v_mfma_f32_16x16x32_bf16 v[24:27], v[158:161], v[194:197], v[24:27]
	v_mfma_f32_16x16x32_bf16 v[12:15], v[150:153], v[206:209], v[12:15]
	v_mfma_f32_16x16x32_bf16 v[8:11], v[158:161], v[206:209], v[8:11]
	s_barrier
	s_setprio 0
	s_add_u32 s4, s4, 0x40080
	s_addc_u32 s5, s5, 0
	s_add_i32 s6, s6, s44
	s_mov_b32 m0, s6
	s_nop 0
	global_load_lds_dwordx4 v130, s[4:5]
	s_add_i32 m0, s6, 0x2000
	s_nop 0
	global_load_lds_dwordx4 v134, s[4:5]
	s_waitcnt vmcnt(8)
	s_setprio 1
	s_barrier
	v_mfma_f32_16x16x32_bf16 v[52:55], v[210:213], v[162:165], v[52:55]
	v_mfma_f32_16x16x32_bf16 v[48:51], v[218:221], v[162:165], v[48:51]
	v_mfma_f32_16x16x32_bf16 v[36:39], v[210:213], v[182:185], v[36:39]
	v_mfma_f32_16x16x32_bf16 v[32:35], v[218:221], v[182:185], v[32:35]
	v_mfma_f32_16x16x32_bf16 v[20:23], v[210:213], v[190:193], v[20:23]
	v_mfma_f32_16x16x32_bf16 v[16:19], v[218:221], v[190:193], v[16:19]
	v_mfma_f32_16x16x32_bf16 v[4:7], v[210:213], v[202:205], v[4:7]
	v_mfma_f32_16x16x32_bf16 v[0:3], v[218:221], v[202:205], v[0:3]
	v_mfma_f32_16x16x32_bf16 v[52:55], v[214:217], v[178:181], v[52:55]
	v_mfma_f32_16x16x32_bf16 v[48:51], v[222:225], v[178:181], v[48:51]
	v_mfma_f32_16x16x32_bf16 v[36:39], v[214:217], v[186:189], v[36:39]
	v_mfma_f32_16x16x32_bf16 v[32:35], v[222:225], v[186:189], v[32:35]
	v_mfma_f32_16x16x32_bf16 v[20:23], v[214:217], v[194:197], v[20:23]
	v_mfma_f32_16x16x32_bf16 v[16:19], v[222:225], v[194:197], v[16:19]
	v_mfma_f32_16x16x32_bf16 v[4:7], v[214:217], v[206:209], v[4:7]
	v_mfma_f32_16x16x32_bf16 v[0:3], v[222:225], v[206:209], v[0:3]
	s_barrier
	s_setprio 0
	s_add_i32 s67, s67, 2
	s_add_u32 s0, s0, 0x100
	s_addc_u32 s1, s1, 0
	s_add_u32 s65, s65, 0x100
	s_addc_u32 s66, s66, 0
	s_cmp_gt_u32 s67, 13
.LBB0_613:
	ds_read_b128 v[146:149], v171
	ds_read_b128 v[150:153], v171 offset:1024
	ds_read_b128 v[154:157], v171 offset:2048
	ds_read_b128 v[158:161], v171 offset:3072
	s_add_u32 s4, s0, 0xfffc0080
	s_addc_u32 s5, s1, -1
	s_cmp_eq_u32 s67, 12
	s_cselect_b32 s7, s8, s5
	s_cselect_b32 s6, s9, s4
	s_cselect_b32 s5, s31, s66
	s_cselect_b32 s4, s35, s65
	s_add_i32 m0, s45, 0xc000
	ds_read_b128 v[162:165], v172
	ds_read_b128 v[178:181], v172 offset:1024
	ds_read_b128 v[182:185], v172 offset:2048
	ds_read_b128 v[186:189], v172 offset:3072
	ds_read_b128 v[190:193], v172 offset:4096
	ds_read_b128 v[194:197], v172 offset:5120
	ds_read_b128 v[202:205], v172 offset:6144
	ds_read_b128 v[206:209], v172 offset:7168
	global_load_lds_dwordx4 v138, s[0:1]
	s_add_i32 m0, s45, 0xe000
	s_nop 0
	global_load_lds_dwordx4 v140, s[0:1]
	s_waitcnt lgkmcnt(8)
	s_waitcnt vmcnt(8)
	s_setprio 1
	s_barrier
	s_waitcnt lgkmcnt(0)
	v_mfma_f32_16x16x32_bf16 v[124:127], v[146:149], v[162:165], v[124:127]
	v_mfma_f32_16x16x32_bf16 v[120:123], v[154:157], v[162:165], v[120:123]
	v_mfma_f32_16x16x32_bf16 v[108:111], v[146:149], v[182:185], v[108:111]
	v_mfma_f32_16x16x32_bf16 v[104:107], v[154:157], v[182:185], v[104:107]
	v_mfma_f32_16x16x32_bf16 v[92:95], v[146:149], v[190:193], v[92:95]
	v_mfma_f32_16x16x32_bf16 v[88:91], v[154:157], v[190:193], v[88:91]
	v_mfma_f32_16x16x32_bf16 v[76:79], v[146:149], v[202:205], v[76:79]
	v_mfma_f32_16x16x32_bf16 v[72:75], v[154:157], v[202:205], v[72:75]
	v_mfma_f32_16x16x32_bf16 v[124:127], v[150:153], v[178:181], v[124:127]
	v_mfma_f32_16x16x32_bf16 v[120:123], v[158:161], v[178:181], v[120:123]
	v_mfma_f32_16x16x32_bf16 v[108:111], v[150:153], v[186:189], v[108:111]
	v_mfma_f32_16x16x32_bf16 v[104:107], v[158:161], v[186:189], v[104:107]
	v_mfma_f32_16x16x32_bf16 v[92:95], v[150:153], v[194:197], v[92:95]
	v_mfma_f32_16x16x32_bf16 v[88:91], v[158:161], v[194:197], v[88:91]
	v_mfma_f32_16x16x32_bf16 v[76:79], v[150:153], v[206:209], v[76:79]
	v_mfma_f32_16x16x32_bf16 v[72:75], v[158:161], v[206:209], v[72:75]
	s_barrier
	s_setprio 0
	s_add_i32 s68, s57, s44
	s_mov_b32 m0, s68
	ds_read_b128 v[210:213], v173
	ds_read_b128 v[214:217], v173 offset:1024
	ds_read_b128 v[218:221], v173 offset:2048
	ds_read_b128 v[222:225], v173 offset:3072
	global_load_lds_dwordx4 v130, s[4:5]
	s_add_i32 m0, s68, 0x2000
	s_nop 0
	global_load_lds_dwordx4 v134, s[4:5]
	s_waitcnt vmcnt(8)
	s_setprio 1
	s_barrier
; #define PG8_STAGE(bufoff, gbase, voff) do { _Pragma("unroll") for (int _i = 0; _i < 2; ++_i) \
;         __builtin_amdgcn_global_load_lds((const unsigned*)((const char*)(gbase) + (voff)[_i]), (LAS unsigned*)(lds + (bufoff) + ldsw + _i * 8192), 16, 0, 0); } while (0)
; #define PG8_LDA(dst, b, h) do { _Pragma("unroll") for (int m = 0; m < 4; ++m) _Pragma("unroll") for (int k = 0; k < 2; ++k) dst[m][k] = *(const LAS bf16x8*)(lds + PG8_SA(b, h) + aoff + m * 2048 + k * 1024); } while (0)
; #define PG8_LDB(dst, b, h) do { _Pragma("unroll") for (int n = 0; n < 2; ++n) _Pragma("unroll") for (int k = 0; k < 2; ++k) dst[n][k] = *(const LAS bf16x8*)(lds + PG8_SB(b, h) + boff + n * 2048 + k * 1024); } while (0)
; #define PG8_WAIT_V(n) asm volatile("s_waitcnt vmcnt(" #n ")" ::: "memory")
; #define PG8_WAIT_L(n) asm volatile("s_waitcnt lgkmcnt(" #n ")" ::: "memory")
; #define PG8_BAR __builtin_amdgcn_s_barrier()
; #define PG8_SCHED __builtin_amdgcn_sched_barrier(0)
; template <class Epi, class Sched>
; __device__ __forceinline__ void gemm_phase(LAS unsigned char* lds, const Gemm g, const Sched& S, const Epi& E) {
;     ...
;             PG8_LDB(B0, 0, 0); PG8_SCHED; PG8_LDA(At, 0, 0); PG8_STAGE(PG8_SA(1, 1), a1 + hstep, voffA);
;             PG8_WAIT_L(8); PG8_BAR; PG8_WAIT_L(0); PG8_MMA(0, 0, At, B0); PG8_BAR; PG8_SCHED;
;             PG8_LDB(B1, 0, 1); PG8_STAGE(PG8_SB(0, 0), b2, voffB);
;             PG8_BAR; PG8_WAIT_L(0); PG8_MMA(0, 1, At, B1); PG8_BAR;
;             PG8_LDA(At, 0, 1); PG8_STAGE(PG8_SA(0, 0), a2, voffA);
;             PG8_BAR; PG8_WAIT_L(0); PG8_MMA(1, 0, At, B0); PG8_BAR; PG8_SCHED;
;             PG8_STAGE(PG8_SB(0, 1), b2 + hstep, voffB);
;             PG8_WAIT_V(6); PG8_BAR; PG8_MMA(1, 1, At, B1); PG8_BAR;
;             PG8_LDB(B0, 1, 0); PG8_SCHED; PG8_LDA(At, 1, 0); PG8_STAGE(PG8_SA(0, 1), a2 + hstep, voffA);
;             PG8_WAIT_L(8); PG8_BAR; PG8_WAIT_L(0); PG8_MMA(0, 0, At, B0); PG8_BAR; PG8_SCHED;
;             PG8_LDB(B1, 1, 1); PG8_STAGE(PG8_SB(1, 0), b3, voffB);
;             PG8_BAR; PG8_WAIT_L(0); PG8_MMA(0, 1, At, B1); PG8_BAR;
;             PG8_LDA(At, 1, 1); PG8_STAGE(PG8_SA(1, 0), a3, voffA);
;             PG8_BAR; PG8_WAIT_L(0); PG8_MMA(1, 0, At, B0); PG8_BAR; PG8_SCHED;
;             PG8_STAGE(PG8_SB(1, 1), b3 + hstep, voffB);
;             PG8_WAIT_V(6); PG8_BAR; PG8_MMA(1, 1, At, B1); PG8_BAR;
	s_waitcnt lgkmcnt(0)
	v_mfma_f32_16x16x32_bf16 v[116:119], v[210:213], v[162:165], v[116:119]
	v_mfma_f32_16x16x32_bf16 v[112:115], v[218:221], v[162:165], v[112:115]
	v_mfma_f32_16x16x32_bf16 v[100:103], v[210:213], v[182:185], v[100:103]
	v_mfma_f32_16x16x32_bf16 v[96:99], v[218:221], v[182:185], v[96:99]
	v_mfma_f32_16x16x32_bf16 v[84:87], v[210:213], v[190:193], v[84:87]
	v_mfma_f32_16x16x32_bf16 v[80:83], v[218:221], v[190:193], v[80:83]
	v_mfma_f32_16x16x32_bf16 v[68:71], v[210:213], v[202:205], v[68:71]
	v_mfma_f32_16x16x32_bf16 v[64:67], v[218:221], v[202:205], v[64:67]
	v_mfma_f32_16x16x32_bf16 v[116:119], v[214:217], v[178:181], v[116:119]
	v_mfma_f32_16x16x32_bf16 v[112:115], v[222:225], v[178:181], v[112:115]
	v_mfma_f32_16x16x32_bf16 v[100:103], v[214:217], v[186:189], v[100:103]
	v_mfma_f32_16x16x32_bf16 v[96:99], v[222:225], v[186:189], v[96:99]
	v_mfma_f32_16x16x32_bf16 v[84:87], v[214:217], v[194:197], v[84:87]
	v_mfma_f32_16x16x32_bf16 v[80:83], v[222:225], v[194:197], v[80:83]
	v_mfma_f32_16x16x32_bf16 v[68:71], v[214:217], v[206:209], v[68:71]
	v_mfma_f32_16x16x32_bf16 v[64:67], v[222:225], v[206:209], v[64:67]
	s_barrier
	s_setprio 0
	s_mov_b32 m0, s45
	v_lshl_add_u64 v[226:227], s[6:7], 0, v[128:129]
	ds_read_b128 v[162:165], v172 offset:16384
	ds_read_b128 v[178:181], v172 offset:17408
	ds_read_b128 v[182:185], v172 offset:18432
	ds_read_b128 v[186:189], v172 offset:19456
	ds_read_b128 v[190:193], v172 offset:20480
	ds_read_b128 v[194:197], v172 offset:21504
	ds_read_b128 v[202:205], v172 offset:22528
	ds_read_b128 v[206:209], v172 offset:23552
	global_load_lds_dwordx4 v128, s[6:7]
	v_lshl_add_u64 v[228:229], s[6:7], 0, v[132:133]
	s_mov_b32 m0, s46
	s_nop 0
	global_load_lds_dwordx4 v132, s[6:7]
	s_setprio 1
	s_barrier
	s_waitcnt lgkmcnt(0)
	v_mfma_f32_16x16x32_bf16 v[60:63], v[146:149], v[162:165], v[60:63]
	v_mfma_f32_16x16x32_bf16 v[56:59], v[154:157], v[162:165], v[56:59]
	v_mfma_f32_16x16x32_bf16 v[44:47], v[146:149], v[182:185], v[44:47]
	v_mfma_f32_16x16x32_bf16 v[40:43], v[154:157], v[182:185], v[40:43]
	v_mfma_f32_16x16x32_bf16 v[28:31], v[146:149], v[190:193], v[28:31]
	v_mfma_f32_16x16x32_bf16 v[24:27], v[154:157], v[190:193], v[24:27]
	v_mfma_f32_16x16x32_bf16 v[12:15], v[146:149], v[202:205], v[12:15]
	v_mfma_f32_16x16x32_bf16 v[8:11], v[154:157], v[202:205], v[8:11]
	v_mfma_f32_16x16x32_bf16 v[60:63], v[150:153], v[178:181], v[60:63]
	v_mfma_f32_16x16x32_bf16 v[56:59], v[158:161], v[178:181], v[56:59]
	v_mfma_f32_16x16x32_bf16 v[44:47], v[150:153], v[186:189], v[44:47]
	v_mfma_f32_16x16x32_bf16 v[40:43], v[158:161], v[186:189], v[40:43]
	v_mfma_f32_16x16x32_bf16 v[28:31], v[150:153], v[194:197], v[28:31]
	v_mfma_f32_16x16x32_bf16 v[24:27], v[158:161], v[194:197], v[24:27]
	v_mfma_f32_16x16x32_bf16 v[12:15], v[150:153], v[206:209], v[12:15]
	v_mfma_f32_16x16x32_bf16 v[8:11], v[158:161], v[206:209], v[8:11]
	s_barrier
	s_setprio 0
	s_add_u32 s68, s4, 0x40000
	s_addc_u32 s69, s5, 0
	s_add_i32 s70, s58, s44
	s_mov_b32 m0, s70
	s_nop 0
	global_load_lds_dwordx4 v130, s[68:69]
	s_add_i32 m0, s70, 0x2000
	s_nop 0
	global_load_lds_dwordx4 v134, s[68:69]
	s_add_u32 s6, s6, 0x40000
	s_addc_u32 s7, s7, 0
	s_mov_b32 m0, s47
	s_nop 0
	global_load_lds_dwordx4 v128, s[6:7]
	s_mov_b32 m0, s48
	s_nop 0
	global_load_lds_dwordx4 v132, s[6:7]
	s_waitcnt vmcnt(10)
	s_setprio 1
	s_barrier
	v_mfma_f32_16x16x32_bf16 v[52:55], v[210:213], v[162:165], v[52:55]
	v_mfma_f32_16x16x32_bf16 v[48:51], v[218:221], v[162:165], v[48:51]
	v_mfma_f32_16x16x32_bf16 v[36:39], v[210:213], v[182:185], v[36:39]
	v_mfma_f32_16x16x32_bf16 v[32:35], v[218:221], v[182:185], v[32:35]
	v_mfma_f32_16x16x32_bf16 v[20:23], v[210:213], v[190:193], v[20:23]
	v_mfma_f32_16x16x32_bf16 v[16:19], v[218:221], v[190:193], v[16:19]
	v_mfma_f32_16x16x32_bf16 v[4:7], v[210:213], v[202:205], v[4:7]
	v_mfma_f32_16x16x32_bf16 v[0:3], v[218:221], v[202:205], v[0:3]
	v_mfma_f32_16x16x32_bf16 v[52:55], v[214:217], v[178:181], v[52:55]
	v_mfma_f32_16x16x32_bf16 v[48:51], v[222:225], v[178:181], v[48:51]
	v_mfma_f32_16x16x32_bf16 v[36:39], v[214:217], v[186:189], v[36:39]
	v_mfma_f32_16x16x32_bf16 v[32:35], v[222:225], v[186:189], v[32:35]
	v_mfma_f32_16x16x32_bf16 v[20:23], v[214:217], v[194:197], v[20:23]
	v_mfma_f32_16x16x32_bf16 v[16:19], v[222:225], v[194:197], v[16:19]
	v_mfma_f32_16x16x32_bf16 v[4:7], v[214:217], v[206:209], v[4:7]
	v_mfma_f32_16x16x32_bf16 v[0:3], v[222:225], v[206:209], v[0:3]
	s_barrier
	s_setprio 0
	s_add_i32 s68, 0, 0x18000
	v_add_u32_e32 v136, s68, v170
	ds_read_b128 v[146:149], v136
	ds_read_b128 v[150:153], v136 offset:1024
	ds_read_b128 v[154:157], v136 offset:2048
	ds_read_b128 v[158:161], v136 offset:3072
	ds_read_b128 v[162:165], v172 offset:32768
	ds_read_b128 v[178:181], v172 offset:33792
	ds_read_b128 v[182:185], v172 offset:34816
	ds_read_b128 v[186:189], v172 offset:35840
	ds_read_b128 v[190:193], v172 offset:36864
	ds_read_b128 v[194:197], v172 offset:37888
	ds_read_b128 v[202:205], v172 offset:38912
	ds_read_b128 v[206:209], v172 offset:39936
	s_waitcnt lgkmcnt(8)
	s_waitcnt vmcnt(8)
	s_setprio 1
	s_barrier
; #define PG8_STAGE(bufoff, gbase, voff) do { _Pragma("unroll") for (int _i = 0; _i < 2; ++_i) \
;         __builtin_amdgcn_global_load_lds((const unsigned*)((const char*)(gbase) + (voff)[_i]), (LAS unsigned*)(lds + (bufoff) + ldsw + _i * 8192), 16, 0, 0); } while (0)
; #define PG8_LDA(dst, b, h) do { _Pragma("unroll") for (int m = 0; m < 4; ++m) _Pragma("unroll") for (int k = 0; k < 2; ++k) dst[m][k] = *(const LAS bf16x8*)(lds + PG8_SA(b, h) + aoff + m * 2048 + k * 1024); } while (0)
; #define PG8_LDB(dst, b, h) do { _Pragma("unroll") for (int n = 0; n < 2; ++n) _Pragma("unroll") for (int k = 0; k < 2; ++k) dst[n][k] = *(const LAS bf16x8*)(lds + PG8_SB(b, h) + boff + n * 2048 + k * 1024); } while (0)
; #define PG8_WAIT_V(n) asm volatile("s_waitcnt vmcnt(" #n ")" ::: "memory")
; #define PG8_WAIT_L(n) asm volatile("s_waitcnt lgkmcnt(" #n ")" ::: "memory")
; #define PG8_BAR __builtin_amdgcn_s_barrier()
; #define PG8_SCHED __builtin_amdgcn_sched_barrier(0)
; template <class Epi, class Sched>
; __device__ __forceinline__ void gemm_phase(LAS unsigned char* lds, const Gemm g, const Sched& S, const Epi& E) {
;     ...
;             PG8_LDB(B0, 0, 0); PG8_SCHED; PG8_LDA(At, 0, 0); PG8_STAGE(PG8_SA(1, 1), a1 + hstep, voffA);
;             PG8_WAIT_L(8); PG8_BAR; PG8_WAIT_L(0); PG8_MMA(0, 0, At, B0); PG8_BAR; PG8_SCHED;
;             PG8_LDB(B1, 0, 1); PG8_STAGE(PG8_SB(0, 0), b2, voffB);
;             PG8_BAR; PG8_WAIT_L(0); PG8_MMA(0, 1, At, B1); PG8_BAR;
;             PG8_LDA(At, 0, 1); PG8_STAGE(PG8_SA(0, 0), a2, voffA);
;             PG8_BAR; PG8_WAIT_L(0); PG8_MMA(1, 0, At, B0); PG8_BAR; PG8_SCHED;
;             PG8_STAGE(PG8_SB(0, 1), b2 + hstep, voffB);
;             PG8_WAIT_V(6); PG8_BAR; PG8_MMA(1, 1, At, B1); PG8_BAR;
;             PG8_LDB(B0, 1, 0); PG8_SCHED; PG8_LDA(At, 1, 0); PG8_STAGE(PG8_SA(0, 1), a2 + hstep, voffA);
;             PG8_WAIT_L(8); PG8_BAR; PG8_WAIT_L(0); PG8_MMA(0, 0, At, B0); PG8_BAR; PG8_SCHED;
;             PG8_LDB(B1, 1, 1); PG8_STAGE(PG8_SB(1, 0), b3, voffB);
;             PG8_BAR; PG8_WAIT_L(0); PG8_MMA(0, 1, At, B1); PG8_BAR;
;             PG8_LDA(At, 1, 1); PG8_STAGE(PG8_SA(1, 0), a3, voffA);
;             PG8_BAR; PG8_WAIT_L(0); PG8_MMA(1, 0, At, B0); PG8_BAR; PG8_SCHED;
;             PG8_STAGE(PG8_SB(1, 1), b3 + hstep, voffB);
;             PG8_WAIT_V(6); PG8_BAR; PG8_MMA(1, 1, At, B1); PG8_BAR;
	s_waitcnt lgkmcnt(0)
	v_mfma_f32_16x16x32_bf16 v[124:127], v[146:149], v[162:165], v[124:127]
	v_mfma_f32_16x16x32_bf16 v[120:123], v[154:157], v[162:165], v[120:123]
	v_mfma_f32_16x16x32_bf16 v[108:111], v[146:149], v[182:185], v[108:111]
	v_mfma_f32_16x16x32_bf16 v[104:107], v[154:157], v[182:185], v[104:107]
	v_mfma_f32_16x16x32_bf16 v[92:95], v[146:149], v[190:193], v[92:95]
	v_mfma_f32_16x16x32_bf16 v[88:91], v[154:157], v[190:193], v[88:91]
	v_mfma_f32_16x16x32_bf16 v[76:79], v[146:149], v[202:205], v[76:79]
	v_mfma_f32_16x16x32_bf16 v[72:75], v[154:157], v[202:205], v[72:75]
	v_mfma_f32_16x16x32_bf16 v[124:127], v[150:153], v[178:181], v[124:127]
	v_mfma_f32_16x16x32_bf16 v[120:123], v[158:161], v[178:181], v[120:123]
	v_mfma_f32_16x16x32_bf16 v[108:111], v[150:153], v[186:189], v[108:111]
	v_mfma_f32_16x16x32_bf16 v[104:107], v[158:161], v[186:189], v[104:107]
	v_mfma_f32_16x16x32_bf16 v[92:95], v[150:153], v[194:197], v[92:95]
	v_mfma_f32_16x16x32_bf16 v[88:91], v[158:161], v[194:197], v[88:91]
	v_mfma_f32_16x16x32_bf16 v[76:79], v[150:153], v[206:209], v[76:79]
	v_mfma_f32_16x16x32_bf16 v[72:75], v[158:161], v[206:209], v[72:75]
	s_barrier
	s_setprio 0
	s_add_i32 s6, 0, 0x1c000
	s_add_i32 s7, s68, s44
	v_add_u32_e32 v136, s6, v170
	s_add_u32 s20, s4, 0x80
	s_addc_u32 s21, s5, 0
	s_mov_b32 m0, s7
	ds_read_b128 v[210:213], v136
	ds_read_b128 v[214:217], v136 offset:1024
	ds_read_b128 v[218:221], v136 offset:2048
	ds_read_b128 v[222:225], v136 offset:3072
	global_load_lds_dwordx4 v130, s[20:21]
	s_add_i32 m0, s7, 0x2000
	s_nop 0
	global_load_lds_dwordx4 v134, s[20:21]
	s_waitcnt vmcnt(8)
	s_setprio 1
	s_barrier
	s_waitcnt lgkmcnt(0)
	v_mfma_f32_16x16x32_bf16 v[116:119], v[210:213], v[162:165], v[116:119]
	v_mfma_f32_16x16x32_bf16 v[112:115], v[218:221], v[162:165], v[112:115]
	v_mfma_f32_16x16x32_bf16 v[100:103], v[210:213], v[182:185], v[100:103]
	v_mfma_f32_16x16x32_bf16 v[96:99], v[218:221], v[182:185], v[96:99]
	v_mfma_f32_16x16x32_bf16 v[84:87], v[210:213], v[190:193], v[84:87]
	v_mfma_f32_16x16x32_bf16 v[80:83], v[218:221], v[190:193], v[80:83]
	v_mfma_f32_16x16x32_bf16 v[68:71], v[210:213], v[202:205], v[68:71]
	v_mfma_f32_16x16x32_bf16 v[64:67], v[218:221], v[202:205], v[64:67]
	v_mfma_f32_16x16x32_bf16 v[116:119], v[214:217], v[178:181], v[116:119]
	v_mfma_f32_16x16x32_bf16 v[112:115], v[222:225], v[178:181], v[112:115]
	v_mfma_f32_16x16x32_bf16 v[100:103], v[214:217], v[186:189], v[100:103]
	v_mfma_f32_16x16x32_bf16 v[96:99], v[222:225], v[186:189], v[96:99]
	v_mfma_f32_16x16x32_bf16 v[84:87], v[214:217], v[194:197], v[84:87]
	v_mfma_f32_16x16x32_bf16 v[80:83], v[222:225], v[194:197], v[80:83]
	v_mfma_f32_16x16x32_bf16 v[68:71], v[214:217], v[206:209], v[68:71]
	v_mfma_f32_16x16x32_bf16 v[64:67], v[222:225], v[206:209], v[64:67]
	s_barrier
	s_setprio 0
	s_mov_b32 m0, s54
	s_mov_b64 s[20:21], 0x80
	v_lshl_add_u64 v[166:167], v[226:227], 0, s[20:21]
	ds_read_b128 v[162:165], v172 offset:49152
	ds_read_b128 v[178:181], v172 offset:50176
	ds_read_b128 v[182:185], v172 offset:51200
	ds_read_b128 v[186:189], v172 offset:52224
	ds_read_b128 v[190:193], v172 offset:53248
	ds_read_b128 v[194:197], v172 offset:54272
	ds_read_b128 v[202:205], v172 offset:55296
	ds_read_b128 v[206:209], v172 offset:56320
	global_load_lds_dwordx4 v[166:167], off
	v_lshl_add_u64 v[166:167], v[228:229], 0, s[20:21]
	s_mov_b32 m0, s55
	s_nop 0
	global_load_lds_dwordx4 v[166:167], off
	s_setprio 1
	s_barrier
	s_waitcnt lgkmcnt(0)
	v_mfma_f32_16x16x32_bf16 v[60:63], v[146:149], v[162:165], v[60:63]
	v_mfma_f32_16x16x32_bf16 v[56:59], v[154:157], v[162:165], v[56:59]
	v_mfma_f32_16x16x32_bf16 v[44:47], v[146:149], v[182:185], v[44:47]
	v_mfma_f32_16x16x32_bf16 v[40:43], v[154:157], v[182:185], v[40:43]
	v_mfma_f32_16x16x32_bf16 v[28:31], v[146:149], v[190:193], v[28:31]
	v_mfma_f32_16x16x32_bf16 v[24:27], v[154:157], v[190:193], v[24:27]
	v_mfma_f32_16x16x32_bf16 v[12:15], v[146:149], v[202:205], v[12:15]
	v_mfma_f32_16x16x32_bf16 v[8:11], v[154:157], v[202:205], v[8:11]
	v_mfma_f32_16x16x32_bf16 v[60:63], v[150:153], v[178:181], v[60:63]
	v_mfma_f32_16x16x32_bf16 v[56:59], v[158:161], v[178:181], v[56:59]
	v_mfma_f32_16x16x32_bf16 v[44:47], v[150:153], v[186:189], v[44:47]
	v_mfma_f32_16x16x32_bf16 v[40:43], v[158:161], v[186:189], v[40:43]
	v_mfma_f32_16x16x32_bf16 v[28:31], v[150:153], v[194:197], v[28:31]
	v_mfma_f32_16x16x32_bf16 v[24:27], v[158:161], v[194:197], v[24:27]
	v_mfma_f32_16x16x32_bf16 v[12:15], v[150:153], v[206:209], v[12:15]
	v_mfma_f32_16x16x32_bf16 v[8:11], v[158:161], v[206:209], v[8:11]
	s_barrier
	s_setprio 0
	s_add_u32 s4, s4, 0x40080
	s_addc_u32 s5, s5, 0
	s_add_i32 s6, s6, s44
	s_mov_b32 m0, s6
	s_nop 0
	global_load_lds_dwordx4 v130, s[4:5]
	s_add_i32 m0, s6, 0x2000
	s_nop 0
	global_load_lds_dwordx4 v134, s[4:5]
	s_waitcnt vmcnt(8)
	s_setprio 1
	s_barrier
	v_mfma_f32_16x16x32_bf16 v[52:55], v[210:213], v[162:165], v[52:55]
	v_mfma_f32_16x16x32_bf16 v[48:51], v[218:221], v[162:165], v[48:51]
	v_mfma_f32_16x16x32_bf16 v[36:39], v[210:213], v[182:185], v[36:39]
	v_mfma_f32_16x16x32_bf16 v[32:35], v[218:221], v[182:185], v[32:35]
	v_mfma_f32_16x16x32_bf16 v[20:23], v[210:213], v[190:193], v[20:23]
	v_mfma_f32_16x16x32_bf16 v[16:19], v[218:221], v[190:193], v[16:19]
	v_mfma_f32_16x16x32_bf16 v[4:7], v[210:213], v[202:205], v[4:7]
	v_mfma_f32_16x16x32_bf16 v[0:3], v[218:221], v[202:205], v[0:3]
	v_mfma_f32_16x16x32_bf16 v[52:55], v[214:217], v[178:181], v[52:55]
	v_mfma_f32_16x16x32_bf16 v[48:51], v[222:225], v[178:181], v[48:51]
	v_mfma_f32_16x16x32_bf16 v[36:39], v[214:217], v[186:189], v[36:39]
	v_mfma_f32_16x16x32_bf16 v[32:35], v[222:225], v[186:189], v[32:35]
	v_mfma_f32_16x16x32_bf16 v[20:23], v[214:217], v[194:197], v[20:23]
	v_mfma_f32_16x16x32_bf16 v[16:19], v[222:225], v[194:197], v[16:19]
	v_mfma_f32_16x16x32_bf16 v[4:7], v[214:217], v[206:209], v[4:7]
	v_mfma_f32_16x16x32_bf16 v[0:3], v[222:225], v[206:209], v[0:3]
	s_barrier
; #define PG8_BAR __builtin_amdgcn_s_barrier()
; template <class Epi, class Sched>
; __device__ __forceinline__ void gemm_phase(LAS unsigned char* lds, const Gemm g, const Sched& S, const Epi& E) {
;     ...
;             PG8_WAIT_V(6); PG8_BAR; PG8_MMA(1, 1, At, B1); PG8_BAR;
;         }
;         E(acc, cur, wr, wc, fr, fq);
;         if (!has_next) break;
;     __device__ __forceinline__ void operator()(const AccT& acc, const Unit& u, int wr, int wc, int fr, int fq) const {
;     ...
;         const int rbase = wr * 64 + fr;
;         const int tb = u.pn * 256 + wc * 32 + 8 * fq;
;         const int o0 = wc * 32 + 8 * fq;
;         const int j = fr & 3; const float sgn = ((fr >> 2) & 1) ? 1.0f : -1.0f;
; #pragma unroll
;         for (int ai = 0; ai < 2; ++ai) {
;             const int hh = 2 * ai + wr;
;             const float l2f = lgd[hh] * 1.4426950408889634f, l2b = lgd[4 + hh] * 1.4426950408889634f;
;             const float zf0 = exp2f((float)(127 - o0) * l2f), zfs = exp2f(-l2f), zb0 = exp2f((float)o0 * l2b), zbs = exp2f(l2b);
; #pragma unroll
;             for (int m = 0; m < 4; ++m) {
;                 const int r = rbase + ai * 128 + m * 16;
;                 const int d = 4 * (2 * m + (fr >> 3)) + j;
; #pragma unroll
;                 for (int bj = 0; bj < 2; ++bj) {
;                     const int t0 = tb + bj * 128;
;                     float v[8];
; #pragma unroll
;                     for (int jj = 0; jj < 4; ++jj) { v[jj] = acc[ai][bj][m][0][jj]; v[4 + jj] = acc[ai][bj][m][1][jj]; }
;                     if constexpr (ROPE) {
;                         const int t = t0 & 2047;
; #pragma unroll
;                         for (int hf = 0; hf < 2; ++hf) {
;                             f32x4 cs, sn;
;                             if (m < 2) { const float c1 = ropeA[(t >> 6) * 16 + d], s1 = ropeA[1024 + (t >> 6) * 16 + d]; cs = (f32x4){c1, c1, c1, c1}; sn = (f32x4){s1, s1, s1, s1}; }
;                             else { const float* cb = ropeA + 2048 + (d - 16) * 64 + (t & 63) + 4 * hf; cs = *(const f32x4*)(cb); sn = *(const f32x4*)(cb + 1024); }
; #pragma unroll
;                             for (int jj = 0; jj < 4; ++jj) { const float pr = __shfl_xor(v[4 * hf + jj], 4); v[4 * hf + jj] = v[4 * hf + jj] * cs[jj] + sgn * pr * sn[jj]; }
;                             __builtin_amdgcn_sched_barrier(0);
;                         }
;                     }
	s_setprio 0
	s_add_i32 s67, s67, 2
	s_add_u32 s0, s0, 0x100
	s_addc_u32 s1, s1, 0
	s_add_u32 s65, s65, 0x100
	s_addc_u32 s66, s66, 0
	s_cmp_gt_u32 s67, 13
	s_cbranch_scc0 .LBB0_613
	v_mov_b32_e32 v136, v169
	v_mov_b32_e32 v150, v168
	s_lshl_b32 s0, s33, 8
	global_load_dword v154, v137, s[22:23]
	global_load_dword v155, v137, s[22:23] offset:16
	s_or_b32 s0, s0, s53
	v_lshlrev_b32_e32 v151, 3, v136
	v_ashrrev_i32_e32 v136, 1, v150
	v_add_u32_e32 v162, s0, v151
	v_bfi_b32 v136, -4, v136, v150
	v_lshrrev_b32_e32 v146, 2, v162
	v_add_u32_e32 v192, 0x400, v136
	v_and_b32_e32 v187, 0x1f0, v146
	v_add_u32_e32 v146, v192, v187
	v_add_u32_e32 v148, v187, v136
	v_ashrrev_i32_e32 v147, 31, v146
	v_ashrrev_i32_e32 v149, 31, v148
	v_lshl_add_u64 v[146:147], v[146:147], 2, s[16:17]
	v_lshl_add_u64 v[148:149], v[148:149], 2, s[16:17]
	global_load_dword v153, v[146:147], off
	global_load_dword v166, v[148:149], off
	v_and_b32_e32 v157, 64, v174
	v_xor_b32_e32 v156, 4, v174
	v_add_u32_e32 v157, 64, v157
	v_cmp_lt_i32_e32 vcc, v156, v157
	v_mov_b32_e32 v152, v124
	v_add_u32_e32 v151, s53, v151
	v_cndmask_b32_e32 v156, v174, v156, vcc
	v_lshlrev_b32_e32 v177, 2, v156
	ds_bpermute_b32 v124, v177, v124
	v_sub_u32_e32 v156, 0x7f, v151
	v_add_u32_e32 v164, s52, v150
	v_and_b32_e32 v150, 4, v150
	v_cvt_f32_i32_e32 v179, v156
	v_cvt_f32_i32_e32 v178, v151
	v_cmp_eq_u32_e32 vcc, 0, v150
	ds_bpermute_b32 v157, v177, v125
	ds_bpermute_b32 v158, v177, v127
	s_waitcnt lgkmcnt(0)
	v_cndmask_b32_e64 v167, v124, -v124, vcc
	ds_bpermute_b32 v151, v177, v126
	v_ashrrev_i32_e32 v165, 31, v164
	v_and_b32_e32 v186, 56, v162
	s_waitcnt lgkmcnt(0)
	v_cndmask_b32_e64 v151, v151, -v151, vcc
	s_waitcnt vmcnt(0)
	v_mul_f32_e32 v124, 0x3fb8aa3b, v154
	v_mul_f32_e32 v150, 0x3fb8aa3b, v155
	v_cmp_lt_f32_e64 s[4:5], s60, v124
	v_mul_f32_e32 v156, v124, v179
	v_cmp_gt_f32_e64 s[6:7], s59, v150
	v_cndmask_b32_e64 v159, 0, v176, s[4:5]
	v_mul_f32_e32 v160, v150, v178
	v_cndmask_b32_e64 v161, 0, v176, s[6:7]
	v_cmp_gt_f32_e64 s[8:9], s59, v156
	v_fmac_f32_e32 v159, 0xbfb8aa3b, v154
	s_and_b64 s[0:1], s[4:5], exec
	v_cmp_gt_f32_e64 s[4:5], s59, v160
	v_fmac_f32_e32 v161, 0x3fb8aa3b, v155
	v_cndmask_b32_e64 v154, 0, v176, s[8:9]
	v_exp_f32_e32 v155, v159
	v_cndmask_b32_e64 v159, 0, v176, s[4:5]
	v_fmac_f32_e32 v154, v124, v179
	v_fmac_f32_e32 v159, v150, v178
	v_exp_f32_e32 v150, v154
	v_cndmask_b32_e64 v156, 0, v175, s[8:9]
	s_cselect_b32 s8, 0xffffffc0, 0
	v_exp_f32_e32 v161, v161
	v_exp_f32_e32 v159, v159
	v_ldexp_f32 v163, v155, s8
	v_pk_mul_f32 v[154:155], v[152:153], v[166:167]
	v_cndmask_b32_e64 v167, v157, -v157, vcc
	v_mov_b32_e32 v152, v125
	s_and_b64 s[0:1], s[6:7], exec
	v_add_f32_e32 v190, v154, v155
	v_pk_mul_f32 v[154:155], v[152:153], v[166:167]
	v_cndmask_b32_e64 v167, v158, -v158, vcc
	v_mov_b32_e32 v152, v127
	v_cndmask_b32_e64 v160, 0, v175, s[4:5]
	s_cselect_b32 s0, 0xffffffc0, 0
	v_ldexp_f32 v180, v150, v156
	v_add_f32_e32 v191, v154, v155
	v_pk_mul_f32 v[154:155], v[152:153], v[166:167]
	v_ldexp_f32 v124, v161, s0
	v_mul_f32_e32 v161, v126, v166
	v_ldexp_f32 v150, v159, v160
	v_mul_f32_e32 v181, v163, v180
	v_add_f32_e32 v193, v154, v155
	global_load_dword v188, v[148:149], off
	global_load_dword v157, v[146:147], off
	ds_bpermute_b32 v127, v177, v121
	v_mov_b32_e32 v156, v121
	ds_bpermute_b32 v121, v177, v123
	ds_bpermute_b32 v125, v177, v120
	ds_bpermute_b32 v152, v177, v122
	s_waitcnt lgkmcnt(3)
	v_cndmask_b32_e64 v189, v127, -v127, vcc
	s_waitcnt lgkmcnt(1)
	v_cndmask_b32_e64 v158, v125, -v125, vcc
	s_waitcnt lgkmcnt(0)
	v_cndmask_b32_e64 v127, v152, -v152, vcc
	s_waitcnt vmcnt(1)
	v_mul_f32_e32 v159, v120, v188
	s_waitcnt vmcnt(0)
	v_pk_mul_f32 v[154:155], v[156:157], v[188:189]
	v_cndmask_b32_e64 v189, v121, -v121, vcc
	v_mov_b32_e32 v156, v123
	v_add_f32_e32 v121, v154, v155
	v_pk_mul_f32 v[154:155], v[156:157], v[188:189]
	s_nop 0
	v_add_f32_e32 v123, v154, v155
	v_mov_b32_e32 v125, v153
	v_pk_mul_f32 v[152:153], v[124:125], v[150:151]
	v_mov_b32_e32 v125, v161
	v_pk_mul_f32 v[154:155], v[124:125], v[152:153]
	v_mov_b32_e32 v125, v157
	v_mov_b32_e32 v155, v158
	v_pk_mul_f32 v[156:157], v[124:125], v[154:155]
	v_mov_b32_e32 v158, v124
	v_pk_mul_f32 v[158:159], v[158:159], v[156:157]
	v_mul_f32_e32 v167, v163, v181
	v_mov_b32_e32 v159, v127
	v_mul_f32_e32 v183, v163, v167
	v_pk_mul_f32 v[160:161], v[124:125], v[158:159]
	v_mul_f32_e32 v182, v163, v183
	v_mul_f32_e32 v151, v124, v160
	v_mul_f32_e32 v185, v163, v182
	v_mul_f32_e32 v155, v124, v151
	v_mul_f32_e32 v124, v180, v190
	v_mul_f32_e32 v125, v181, v191
	v_fma_f32 v153, v126, v166, v153
	v_mul_f32_e32 v184, v163, v185
	v_cvt_pk_bf16_f32 v124, v124, v125
	v_mul_f32_e32 v125, v167, v153
	v_mul_f32_e32 v126, v183, v193
	v_fma_f32 v120, v120, v188, v157
	v_mul_f32_e32 v159, v163, v184
	v_cvt_pk_bf16_f32 v125, v125, v126
	v_mul_f32_e32 v126, v182, v120
	v_mul_f32_e32 v127, v185, v121
	v_fma_f32 v122, v122, v188, v161
	v_cvt_pk_bf16_f32 v126, v126, v127
	v_mul_f32_e32 v127, v184, v122
	v_mul_f32_e32 v157, v159, v123
	v_cvt_pk_bf16_f32 v127, v127, v157
	v_mul_f32_e32 v157, v150, v190
	v_mul_f32_e32 v120, v158, v120
	v_mul_f32_e32 v121, v160, v121
	v_mul_f32_e32 v161, v152, v191
	v_cvt_pk_bf16_f32 v188, v157, v161
	v_mul_f32_e32 v153, v154, v153
	v_mul_f32_e32 v157, v156, v193
	v_cvt_pk_bf16_f32 v189, v153, v157
	v_cvt_pk_bf16_f32 v190, v120, v121
	v_mul_f32_e32 v120, v151, v122
	v_mul_f32_e32 v121, v155, v123
	v_cvt_pk_bf16_f32 v191, v120, v121
	v_lshlrev_b64 v[120:121], 17, v[164:165]
	v_lshl_add_u64 v[120:121], s[80:81], 0, v[120:121]
	v_ashrrev_i32_e32 v163, 31, v162
	v_lshl_add_u64 v[120:121], v[162:163], 1, v[120:121]
	s_mov_b64 s[0:1], 0x2000000
	global_store_dwordx4 v[120:121], v[124:127], off
	s_nop 1
	v_lshl_add_u64 v[126:127], v[120:121], 0, s[0:1]
	s_brev_b32 s0, 64
	v_add_co_u32_e64 v122, s[4:5], s0, v120
	s_nop 1
	v_addc_co_u32_e64 v123, s[4:5], 0, v121, s[4:5]
	global_store_dwordx4 v[122:123], v[188:191], off
	v_add_u32_e32 v122, 0x80, v162
	v_lshrrev_b32_e32 v122, 2, v122
	v_and_b32_e32 v153, 0x1f0, v122
	v_add_u32_e32 v122, v153, v192
	v_add_u32_e32 v124, v153, v136
	v_ashrrev_i32_e32 v123, 31, v122
	v_ashrrev_i32_e32 v125, 31, v124
	v_lshl_add_u64 v[122:123], v[122:123], 2, s[16:17]
	v_lshl_add_u64 v[124:125], v[124:125], 2, s[16:17]
	global_load_dword v163, v[122:123], off
	global_load_dword v164, v[124:125], off
	ds_bpermute_b32 v157, v177, v116
	v_mov_b32_e32 v162, v116
	ds_bpermute_b32 v116, v177, v117
	ds_bpermute_b32 v161, v177, v118
	ds_bpermute_b32 v166, v177, v119
	s_waitcnt lgkmcnt(3)
; __device__ __forceinline__ unsigned cvt_pk_bf16(float lo, float hi) { unsigned r; asm volatile("v_cvt_pk_bf16_f32 %0, %1, %2" : "=v"(r) : "v"(lo), "v"(hi)); return r; }
;     __device__ __forceinline__ void operator()(const AccT& acc, const Unit& u, int wr, int wc, int fr, int fq) const {
;     ...
;                 const int r = rbase + ai * 128 + m * 16;
;                 const int d = 4 * (2 * m + (fr >> 3)) + j;
; #pragma unroll
;                 for (int bj = 0; bj < 2; ++bj) {
;                     const int t0 = tb + bj * 128;
;                     float v[8];
; #pragma unroll
;                     for (int jj = 0; jj < 4; ++jj) { v[jj] = acc[ai][bj][m][0][jj]; v[4 + jj] = acc[ai][bj][m][1][jj]; }
;                     if constexpr (ROPE) {
;                         const int t = t0 & 2047;
; #pragma unroll
;                         for (int hf = 0; hf < 2; ++hf) {
;                             f32x4 cs, sn;
;                             if (m < 2) { const float c1 = ropeA[(t >> 6) * 16 + d], s1 = ropeA[1024 + (t >> 6) * 16 + d]; cs = (f32x4){c1, c1, c1, c1}; sn = (f32x4){s1, s1, s1, s1}; }
;                             else { const float* cb = ropeA + 2048 + (d - 16) * 64 + (t & 63) + 4 * hf; cs = *(const f32x4*)(cb); sn = *(const f32x4*)(cb + 1024); }
; #pragma unroll
;                             for (int jj = 0; jj < 4; ++jj) { const float pr = __shfl_xor(v[4 * hf + jj], 4); v[4 * hf + jj] = v[4 * hf + jj] * cs[jj] + sgn * pr * sn[jj]; }
;                             __builtin_amdgcn_sched_barrier(0);
;                         }
;                     }
;                     float zf[8], zb[8]; zf[0] = zf0; zb[0] = zb0;
; #pragma unroll
;                     for (int jj = 1; jj < 8; ++jj) { zf[jj] = zf[jj - 1] * zfs; zb[jj] = zb[jj - 1] * zbs; }
;                     u32x4 wf, wb;
;                     wf.x = cvt_pk_bf16(v[0] * zf[0], v[1] * zf[1]); wf.y = cvt_pk_bf16(v[2] * zf[2], v[3] * zf[3]); wf.z = cvt_pk_bf16(v[4] * zf[4], v[5] * zf[5]); wf.w = cvt_pk_bf16(v[6] * zf[6], v[7] * zf[7]);
;                     wb.x = cvt_pk_bf16(v[0] * zb[0], v[1] * zb[1]); wb.y = cvt_pk_bf16(v[2] * zb[2], v[3] * zb[3]); wb.z = cvt_pk_bf16(v[4] * zb[4], v[5] * zb[5]); wb.w = cvt_pk_bf16(v[6] * zb[6], v[7] * zb[7]);
;                     *(u32x4*)(KTZ + (size_t)r * NT + t0) = wf;
;                     *(u32x4*)(KTZ + (size_t)(256 + r) * NT + t0) = wb;
	v_cndmask_b32_e64 v165, v157, -v157, vcc
	s_waitcnt vmcnt(0)
	v_pk_mul_f32 v[188:189], v[162:163], v[164:165]
	s_waitcnt lgkmcnt(2)
	v_cndmask_b32_e64 v165, v116, -v116, vcc
	v_mov_b32_e32 v162, v117
	v_pk_mul_f32 v[116:117], v[162:163], v[164:165]
	s_waitcnt lgkmcnt(1)
	v_cndmask_b32_e64 v165, v161, -v161, vcc
	v_mov_b32_e32 v162, v118
	v_add_f32_e32 v161, v116, v117
	v_pk_mul_f32 v[116:117], v[162:163], v[164:165]
	s_waitcnt lgkmcnt(0)
	v_cndmask_b32_e64 v165, v166, -v166, vcc
	v_mov_b32_e32 v162, v119
	v_add_f32_e32 v166, v116, v117
	v_pk_mul_f32 v[116:117], v[162:163], v[164:165]
	v_add_f32_e32 v157, v188, v189
	v_add_f32_e32 v164, v116, v117
	global_load_dword v117, v[122:123], off
	global_load_dword v118, v[124:125], off
	ds_bpermute_b32 v119, v177, v112
	v_mov_b32_e32 v116, v112
	ds_bpermute_b32 v112, v177, v113
	ds_bpermute_b32 v165, v177, v114
	ds_bpermute_b32 v188, v177, v115
	s_waitcnt lgkmcnt(3)
	v_cndmask_b32_e64 v119, v119, -v119, vcc
	s_waitcnt vmcnt(0)
	v_pk_mul_f32 v[162:163], v[116:117], v[118:119]
	s_waitcnt lgkmcnt(2)
	v_cndmask_b32_e64 v119, v112, -v112, vcc
	v_mov_b32_e32 v116, v113
	v_pk_mul_f32 v[112:113], v[116:117], v[118:119]
	s_waitcnt lgkmcnt(1)
	v_cndmask_b32_e64 v119, v165, -v165, vcc
	v_mov_b32_e32 v116, v114
	v_add_f32_e32 v162, v162, v163
	v_add_f32_e32 v163, v112, v113
	v_pk_mul_f32 v[112:113], v[116:117], v[118:119]
	s_waitcnt lgkmcnt(0)
	v_cndmask_b32_e64 v119, v188, -v188, vcc
	v_mov_b32_e32 v116, v115
	v_add_f32_e32 v165, v112, v113
	v_pk_mul_f32 v[112:113], v[116:117], v[118:119]
	s_nop 0
	v_add_f32_e32 v119, v112, v113
	v_mul_f32_e32 v112, v180, v157
	v_mul_f32_e32 v113, v181, v161
	v_cvt_pk_bf16_f32 v112, v112, v113
	v_mul_f32_e32 v113, v167, v166
	v_mul_f32_e32 v114, v183, v164
	v_cvt_pk_bf16_f32 v113, v113, v114
	v_mul_f32_e32 v114, v182, v162
	v_mul_f32_e32 v115, v185, v163
	v_cvt_pk_bf16_f32 v114, v114, v115
	v_mul_f32_e32 v115, v184, v165
	v_mul_f32_e32 v116, v159, v119
	v_cvt_pk_bf16_f32 v115, v115, v116
	v_mul_f32_e32 v116, v150, v157
	v_mul_f32_e32 v117, v152, v161
	v_cvt_pk_bf16_f32 v116, v116, v117
	v_mul_f32_e32 v117, v154, v166
	v_mul_f32_e32 v118, v156, v164
	v_cvt_pk_bf16_f32 v117, v117, v118
	v_mul_f32_e32 v118, v158, v162
	v_mul_f32_e32 v157, v160, v163
	v_mul_f32_e32 v119, v155, v119
	v_cvt_pk_bf16_f32 v118, v118, v157
	v_mul_f32_e32 v157, v151, v165
	v_cvt_pk_bf16_f32 v119, v157, v119
	global_store_dwordx4 v[120:121], v[112:115], off offset:256
	global_store_dwordx4 v[126:127], v[116:119], off offset:256
	v_add_u32_e32 v161, 0x408, v136
	v_add_u32_e32 v157, 8, v136
	v_add_u32_e32 v112, v161, v187
	v_add_u32_e32 v114, v187, v157
	v_ashrrev_i32_e32 v113, 31, v112
	v_ashrrev_i32_e32 v115, 31, v114
	v_lshl_add_u64 v[112:113], v[112:113], 2, s[16:17]
	v_lshl_add_u64 v[114:115], v[114:115], 2, s[16:17]
	global_load_dword v117, v[112:113], off
	global_load_dword v118, v[114:115], off
	ds_bpermute_b32 v119, v177, v108
	v_mov_b32_e32 v116, v108
	ds_bpermute_b32 v108, v177, v109
	ds_bpermute_b32 v162, v177, v110
	ds_bpermute_b32 v163, v177, v111
	s_waitcnt lgkmcnt(3)
	v_cndmask_b32_e64 v119, v119, -v119, vcc
	s_waitcnt vmcnt(0)
	v_pk_mul_f32 v[126:127], v[116:117], v[118:119]
	s_waitcnt lgkmcnt(2)
	v_cndmask_b32_e64 v119, v108, -v108, vcc
	v_mov_b32_e32 v116, v109
	v_pk_mul_f32 v[108:109], v[116:117], v[118:119]
	s_waitcnt lgkmcnt(1)
	v_cndmask_b32_e64 v119, v162, -v162, vcc
	v_mov_b32_e32 v116, v110
	v_add_f32_e32 v126, v126, v127
	v_add_f32_e32 v127, v108, v109
	v_pk_mul_f32 v[108:109], v[116:117], v[118:119]
	s_waitcnt lgkmcnt(0)
	v_cndmask_b32_e64 v119, v163, -v163, vcc
	v_mov_b32_e32 v116, v111
	v_add_f32_e32 v162, v108, v109
	v_pk_mul_f32 v[108:109], v[116:117], v[118:119]
	s_nop 0
	v_add_f32_e32 v118, v108, v109
	global_load_dword v109, v[112:113], off
	global_load_dword v110, v[114:115], off
	ds_bpermute_b32 v111, v177, v104
	v_mov_b32_e32 v108, v104
	ds_bpermute_b32 v104, v177, v105
	ds_bpermute_b32 v119, v177, v106
	ds_bpermute_b32 v163, v177, v107
	s_waitcnt lgkmcnt(3)
	v_cndmask_b32_e64 v111, v111, -v111, vcc
	s_waitcnt vmcnt(0)
	v_pk_mul_f32 v[116:117], v[108:109], v[110:111]
	s_waitcnt lgkmcnt(2)
	v_cndmask_b32_e64 v111, v104, -v104, vcc
	v_mov_b32_e32 v108, v105
	v_pk_mul_f32 v[104:105], v[108:109], v[110:111]
	s_waitcnt lgkmcnt(1)
	v_cndmask_b32_e64 v111, v119, -v119, vcc
	v_mov_b32_e32 v108, v106
	v_add_f32_e32 v119, v104, v105
	v_pk_mul_f32 v[104:105], v[108:109], v[110:111]
	s_waitcnt lgkmcnt(0)
	v_cndmask_b32_e64 v111, v163, -v163, vcc
	v_mov_b32_e32 v108, v107
	v_add_f32_e32 v163, v104, v105
	v_pk_mul_f32 v[104:105], v[108:109], v[110:111]
	v_add_f32_e32 v164, v116, v117
	v_add_f32_e32 v108, v104, v105
	v_mul_f32_e32 v104, v180, v126
	v_mul_f32_e32 v105, v181, v127
	v_cvt_pk_bf16_f32 v104, v104, v105
	v_mul_f32_e32 v105, v167, v162
	v_mul_f32_e32 v106, v183, v118
	v_cvt_pk_bf16_f32 v105, v105, v106
	v_mul_f32_e32 v106, v182, v164
	v_mul_f32_e32 v107, v185, v119
	v_cvt_pk_bf16_f32 v106, v106, v107
	v_mul_f32_e32 v107, v184, v163
	v_mul_f32_e32 v109, v159, v108
	v_cvt_pk_bf16_f32 v107, v107, v109
	v_mul_f32_e32 v109, v150, v126
	v_mul_f32_e32 v110, v152, v127
	v_cvt_pk_bf16_f32 v116, v109, v110
	v_mul_f32_e32 v109, v154, v162
	v_mul_f32_e32 v110, v156, v118
	v_cvt_pk_bf16_f32 v117, v109, v110
	v_mul_f32_e32 v109, v158, v164
	v_mul_f32_e32 v110, v160, v119
	v_cvt_pk_bf16_f32 v118, v109, v110
	v_mul_f32_e32 v109, v151, v163
	v_mul_f32_e32 v108, v155, v108
	s_mov_b64 s[0:1], 0x200000
	v_cvt_pk_bf16_f32 v119, v109, v108
	v_lshl_add_u64 v[108:109], v[120:121], 0, s[0:1]
	s_mov_b32 s0, 0x200000
	v_add_co_u32_e64 v110, s[4:5], s0, v120
	s_mov_b64 s[0:1], 0x2200000
	s_nop 0
	v_addc_co_u32_e64 v111, s[4:5], 0, v121, s[4:5]
	global_store_dwordx4 v[110:111], v[104:107], off
	v_lshl_add_u64 v[110:111], v[120:121], 0, s[0:1]
	s_mov_b32 s0, 0x2200000
	v_add_co_u32_e64 v104, s[4:5], s0, v120
	s_nop 1
	v_addc_co_u32_e64 v105, s[4:5], 0, v121, s[4:5]
	global_store_dwordx4 v[104:105], v[116:119], off
	v_add_u32_e32 v104, v153, v161
	v_add_u32_e32 v106, v153, v157
	v_ashrrev_i32_e32 v105, 31, v104
	v_ashrrev_i32_e32 v107, 31, v106
	v_lshl_add_u64 v[104:105], v[104:105], 2, s[16:17]
	v_lshl_add_u64 v[106:107], v[106:107], 2, s[16:17]
	global_load_dword v117, v[104:105], off
	global_load_dword v118, v[106:107], off
	ds_bpermute_b32 v119, v177, v100
	v_mov_b32_e32 v116, v100
	ds_bpermute_b32 v100, v177, v101
	ds_bpermute_b32 v153, v177, v102
	ds_bpermute_b32 v157, v177, v103
	s_waitcnt lgkmcnt(3)
;     __device__ __forceinline__ void operator()(const AccT& acc, const Unit& u, int wr, int wc, int fr, int fq) const {
;     ...
;                 const int r = rbase + ai * 128 + m * 16;
;                 const int d = 4 * (2 * m + (fr >> 3)) + j;
; #pragma unroll
;                 for (int bj = 0; bj < 2; ++bj) {
;                     const int t0 = tb + bj * 128;
;                     float v[8];
; #pragma unroll
;                     for (int jj = 0; jj < 4; ++jj) { v[jj] = acc[ai][bj][m][0][jj]; v[4 + jj] = acc[ai][bj][m][1][jj]; }
;                     if constexpr (ROPE) {
;                         const int t = t0 & 2047;
; #pragma unroll
;                         for (int hf = 0; hf < 2; ++hf) {
;                             f32x4 cs, sn;
;                             if (m < 2) { const float c1 = ropeA[(t >> 6) * 16 + d], s1 = ropeA[1024 + (t >> 6) * 16 + d]; cs = (f32x4){c1, c1, c1, c1}; sn = (f32x4){s1, s1, s1, s1}; }
;                             else { const float* cb = ropeA + 2048 + (d - 16) * 64 + (t & 63) + 4 * hf; cs = *(const f32x4*)(cb); sn = *(const f32x4*)(cb + 1024); }
; #pragma unroll
;                             for (int jj = 0; jj < 4; ++jj) { const float pr = __shfl_xor(v[4 * hf + jj], 4); v[4 * hf + jj] = v[4 * hf + jj] * cs[jj] + sgn * pr * sn[jj]; }
;                             __builtin_amdgcn_sched_barrier(0);
;                         }
;                     }
;                     float zf[8], zb[8]; zf[0] = zf0; zb[0] = zb0;
; #pragma unroll
;                     for (int jj = 1; jj < 8; ++jj) { zf[jj] = zf[jj - 1] * zfs; zb[jj] = zb[jj - 1] * zbs; }
;                     u32x4 wf, wb;
;                     wf.x = cvt_pk_bf16(v[0] * zf[0], v[1] * zf[1]); wf.y = cvt_pk_bf16(v[2] * zf[2], v[3] * zf[3]); wf.z = cvt_pk_bf16(v[4] * zf[4], v[5] * zf[5]); wf.w = cvt_pk_bf16(v[6] * zf[6], v[7] * zf[7]);
;                     wb.x = cvt_pk_bf16(v[0] * zb[0], v[1] * zb[1]); wb.y = cvt_pk_bf16(v[2] * zb[2], v[3] * zb[3]); wb.z = cvt_pk_bf16(v[4] * zb[4], v[5] * zb[5]); wb.w = cvt_pk_bf16(v[6] * zb[6], v[7] * zb[7]);
;                     *(u32x4*)(KTZ + (size_t)r * NT + t0) = wf;
;                     *(u32x4*)(KTZ + (size_t)(256 + r) * NT + t0) = wb;
;                     __builtin_amdgcn_sched_barrier(0);
	v_cndmask_b32_e64 v119, v119, -v119, vcc
	s_waitcnt vmcnt(0)
	v_pk_mul_f32 v[126:127], v[116:117], v[118:119]
	s_waitcnt lgkmcnt(2)
	v_cndmask_b32_e64 v119, v100, -v100, vcc
	v_mov_b32_e32 v116, v101
	v_pk_mul_f32 v[100:101], v[116:117], v[118:119]
	s_waitcnt lgkmcnt(1)
	v_cndmask_b32_e64 v119, v153, -v153, vcc
	v_mov_b32_e32 v116, v102
	v_add_f32_e32 v126, v126, v127
	v_add_f32_e32 v127, v100, v101
	v_pk_mul_f32 v[100:101], v[116:117], v[118:119]
	s_waitcnt lgkmcnt(0)
	v_cndmask_b32_e64 v119, v157, -v157, vcc
	v_mov_b32_e32 v116, v103
	v_add_f32_e32 v153, v100, v101
	v_pk_mul_f32 v[100:101], v[116:117], v[118:119]
	s_nop 0
	v_add_f32_e32 v118, v100, v101
	global_load_dword v101, v[104:105], off
	global_load_dword v102, v[106:107], off
	ds_bpermute_b32 v103, v177, v96
	v_mov_b32_e32 v100, v96
	ds_bpermute_b32 v96, v177, v97
	ds_bpermute_b32 v119, v177, v98
	ds_bpermute_b32 v157, v177, v99
	s_waitcnt lgkmcnt(3)
	v_cndmask_b32_e64 v103, v103, -v103, vcc
	s_waitcnt vmcnt(0)
	v_pk_mul_f32 v[116:117], v[100:101], v[102:103]
	s_waitcnt lgkmcnt(2)
	v_cndmask_b32_e64 v103, v96, -v96, vcc
	v_mov_b32_e32 v100, v97
	v_pk_mul_f32 v[96:97], v[100:101], v[102:103]
	s_waitcnt lgkmcnt(1)
	v_cndmask_b32_e64 v103, v119, -v119, vcc
	v_mov_b32_e32 v100, v98
	v_add_f32_e32 v116, v116, v117
	v_add_f32_e32 v117, v96, v97
	v_pk_mul_f32 v[96:97], v[100:101], v[102:103]
	s_waitcnt lgkmcnt(0)
	v_cndmask_b32_e64 v103, v157, -v157, vcc
	v_mov_b32_e32 v100, v99
	v_add_f32_e32 v119, v96, v97
	v_pk_mul_f32 v[96:97], v[100:101], v[102:103]
	s_nop 0
	v_add_f32_e32 v103, v96, v97
	v_mul_f32_e32 v96, v180, v126
	v_mul_f32_e32 v97, v181, v127
	v_cvt_pk_bf16_f32 v96, v96, v97
	v_mul_f32_e32 v97, v167, v153
	v_mul_f32_e32 v98, v183, v118
	v_cvt_pk_bf16_f32 v97, v97, v98
	v_mul_f32_e32 v98, v182, v116
	v_mul_f32_e32 v99, v185, v117
	v_cvt_pk_bf16_f32 v98, v98, v99
	v_mul_f32_e32 v99, v184, v119
	v_mul_f32_e32 v100, v159, v103
	v_cvt_pk_bf16_f32 v99, v99, v100
	v_mul_f32_e32 v100, v150, v126
	v_mul_f32_e32 v101, v152, v127
	v_cvt_pk_bf16_f32 v100, v100, v101
	v_mul_f32_e32 v101, v154, v153
	v_mul_f32_e32 v102, v156, v118
	v_cvt_pk_bf16_f32 v101, v101, v102
	v_mul_f32_e32 v102, v158, v116
	v_mul_f32_e32 v116, v160, v117
	v_mul_f32_e32 v103, v155, v103
	v_cvt_pk_bf16_f32 v102, v102, v116
	v_mul_f32_e32 v116, v151, v119
	v_cvt_pk_bf16_f32 v103, v116, v103
	global_store_dwordx4 v[108:109], v[96:99], off offset:256
	global_store_dwordx4 v[110:111], v[100:103], off offset:256
	s_nop 1
	v_lshlrev_b32_e32 v100, 6, v136
	v_ashrrev_i32_e32 v101, 31, v100
	v_lshlrev_b64 v[102:103], 2, v[100:101]
	v_lshl_add_u64 v[96:97], s[24:25], 0, v[102:103]
	v_lshlrev_b32_e32 v136, 2, v186
	v_lshl_add_u64 v[96:97], v[96:97], 0, v[136:137]
	v_add_co_u32_e64 v98, s[4:5], s61, v96
	ds_bpermute_b32 v101, v177, v92
	s_nop 0
	v_addc_co_u32_e64 v99, s[4:5], 0, v97, s[4:5]
	global_load_dwordx4 v[108:111], v[98:99], off
	global_load_dwordx4 v[116:119], v[96:97], off
	ds_bpermute_b32 v127, v177, v93
	ds_bpermute_b32 v153, v177, v94
	ds_bpermute_b32 v157, v177, v95
	v_mov_b32_e32 v126, v92
	v_mov_b32_e32 v92, v94
	s_waitcnt lgkmcnt(3)
	v_cndmask_b32_e64 v163, v101, -v101, vcc
	s_waitcnt lgkmcnt(2)
	v_cndmask_b32_e64 v165, v127, -v127, vcc
	s_waitcnt lgkmcnt(1)
	v_cndmask_b32_e64 v187, v153, -v153, vcc
	s_waitcnt lgkmcnt(0)
	v_cndmask_b32_e64 v189, v157, -v157, vcc
	s_waitcnt vmcnt(1)
	v_mov_b32_e32 v127, v108
	s_waitcnt vmcnt(0)
	v_mov_b32_e32 v162, v116
	v_mov_b32_e32 v108, v93
	v_mov_b32_e32 v164, v117
	v_mov_b32_e32 v93, v110
	v_mov_b32_e32 v186, v118
	v_mov_b32_e32 v110, v95
	v_mov_b32_e32 v188, v119
	v_pk_mul_f32 v[94:95], v[126:127], v[162:163]
	v_pk_mul_f32 v[108:109], v[108:109], v[164:165]
	v_pk_mul_f32 v[92:93], v[92:93], v[186:187]
	v_pk_mul_f32 v[110:111], v[110:111], v[188:189]
	v_add_f32_e32 v101, v94, v95
	v_add_f32_e32 v153, v108, v109
	v_add_f32_e32 v157, v92, v93
	v_add_f32_e32 v161, v110, v111
	v_lshl_add_u64 v[92:93], s[16:17], 0, v[102:103]
	v_lshl_add_u64 v[94:95], v[92:93], 0, v[136:137]
	v_add_co_u32_e64 v92, s[4:5], s62, v94
	ds_bpermute_b32 v103, v177, v88
	s_nop 0
	v_addc_co_u32_e64 v93, s[4:5], 0, v95, s[4:5]
	v_add_co_u32_e64 v94, s[4:5], s49, v94
	ds_bpermute_b32 v126, v177, v89
	s_nop 0
	v_addc_co_u32_e64 v95, s[4:5], 0, v95, s[4:5]
	global_load_dwordx4 v[108:111], v[92:93], off offset:16
	global_load_dwordx4 v[116:119], v[94:95], off offset:16
	ds_bpermute_b32 v162, v177, v90
	ds_bpermute_b32 v164, v177, v91
	v_mov_b32_e32 v102, v88
	v_mov_b32_e32 v88, v90
	s_waitcnt lgkmcnt(3)
	v_cndmask_b32_e64 v127, v103, -v103, vcc
	s_waitcnt lgkmcnt(2)
	v_cndmask_b32_e64 v163, v126, -v126, vcc
	s_waitcnt lgkmcnt(1)
	v_cndmask_b32_e64 v165, v162, -v162, vcc
	s_waitcnt lgkmcnt(0)
	v_cndmask_b32_e64 v187, v164, -v164, vcc
	s_waitcnt vmcnt(1)
	v_mov_b32_e32 v103, v108
	s_waitcnt vmcnt(0)
;     __device__ __forceinline__ void operator()(const AccT& acc, const Unit& u, int wr, int wc, int fr, int fq) const {
;     ...
;                 const int r = rbase + ai * 128 + m * 16;
;                 const int d = 4 * (2 * m + (fr >> 3)) + j;
; #pragma unroll
;                 for (int bj = 0; bj < 2; ++bj) {
;                     const int t0 = tb + bj * 128;
;                     float v[8];
; #pragma unroll
;                     for (int jj = 0; jj < 4; ++jj) { v[jj] = acc[ai][bj][m][0][jj]; v[4 + jj] = acc[ai][bj][m][1][jj]; }
;                     if constexpr (ROPE) {
;                         const int t = t0 & 2047;
; #pragma unroll
;                         for (int hf = 0; hf < 2; ++hf) {
;                             f32x4 cs, sn;
;                             if (m < 2) { const float c1 = ropeA[(t >> 6) * 16 + d], s1 = ropeA[1024 + (t >> 6) * 16 + d]; cs = (f32x4){c1, c1, c1, c1}; sn = (f32x4){s1, s1, s1, s1}; }
;                             else { const float* cb = ropeA + 2048 + (d - 16) * 64 + (t & 63) + 4 * hf; cs = *(const f32x4*)(cb); sn = *(const f32x4*)(cb + 1024); }
; #pragma unroll
;                             for (int jj = 0; jj < 4; ++jj) { const float pr = __shfl_xor(v[4 * hf + jj], 4); v[4 * hf + jj] = v[4 * hf + jj] * cs[jj] + sgn * pr * sn[jj]; }
;                             __builtin_amdgcn_sched_barrier(0);
;                         }
;                     }
;                     float zf[8], zb[8]; zf[0] = zf0; zb[0] = zb0;
; #pragma unroll
;                     for (int jj = 1; jj < 8; ++jj) { zf[jj] = zf[jj - 1] * zfs; zb[jj] = zb[jj - 1] * zbs; }
;                     u32x4 wf, wb;
;                     wf.x = cvt_pk_bf16(v[0] * zf[0], v[1] * zf[1]); wf.y = cvt_pk_bf16(v[2] * zf[2], v[3] * zf[3]); wf.z = cvt_pk_bf16(v[4] * zf[4], v[5] * zf[5]); wf.w = cvt_pk_bf16(v[6] * zf[6], v[7] * zf[7]);
;                     wb.x = cvt_pk_bf16(v[0] * zb[0], v[1] * zb[1]); wb.y = cvt_pk_bf16(v[2] * zb[2], v[3] * zb[3]); wb.z = cvt_pk_bf16(v[4] * zb[4], v[5] * zb[5]); wb.w = cvt_pk_bf16(v[6] * zb[6], v[7] * zb[7]);
;                     *(u32x4*)(KTZ + (size_t)r * NT + t0) = wf;
;                     *(u32x4*)(KTZ + (size_t)(256 + r) * NT + t0) = wb;
;                     __builtin_amdgcn_sched_barrier(0);
	v_mov_b32_e32 v126, v116
	v_mov_b32_e32 v108, v89
	v_mov_b32_e32 v162, v117
	v_mov_b32_e32 v89, v110
	v_mov_b32_e32 v164, v118
	v_mov_b32_e32 v110, v91
	v_mov_b32_e32 v186, v119
	v_pk_mul_f32 v[90:91], v[102:103], v[126:127]
	v_pk_mul_f32 v[102:103], v[108:109], v[162:163]
	v_pk_mul_f32 v[88:89], v[88:89], v[164:165]
	v_pk_mul_f32 v[108:109], v[110:111], v[186:187]
	v_add_f32_e32 v90, v90, v91
	v_add_f32_e32 v91, v102, v103
	v_add_f32_e32 v88, v88, v89
	v_add_f32_e32 v89, v108, v109
	v_mul_f32_e32 v102, v180, v101
	v_mul_f32_e32 v103, v181, v153
	v_cvt_pk_bf16_f32 v108, v102, v103
	v_mul_f32_e32 v102, v167, v157
	v_mul_f32_e32 v103, v183, v161
	v_cvt_pk_bf16_f32 v109, v102, v103
	v_mul_f32_e32 v102, v182, v90
	v_mul_f32_e32 v103, v185, v91
	v_cvt_pk_bf16_f32 v110, v102, v103
	v_mul_f32_e32 v102, v184, v88
	v_mul_f32_e32 v103, v159, v89
	v_cvt_pk_bf16_f32 v111, v102, v103
	v_mul_f32_e32 v101, v150, v101
	v_mul_f32_e32 v102, v152, v153
	v_mul_f32_e32 v88, v151, v88
	v_mul_f32_e32 v89, v155, v89
	s_mov_b64 s[0:1], 0x400000
	v_cvt_pk_bf16_f32 v116, v101, v102
	v_mul_f32_e32 v101, v154, v157
	v_mul_f32_e32 v102, v156, v161
	v_cvt_pk_bf16_f32 v117, v101, v102
	v_mul_f32_e32 v90, v158, v90
	v_mul_f32_e32 v91, v160, v91
	v_cvt_pk_bf16_f32 v118, v90, v91
	v_cvt_pk_bf16_f32 v119, v88, v89
	v_lshl_add_u64 v[88:89], v[120:121], 0, s[0:1]
	s_mov_b32 s0, 0x400000
	v_add_co_u32_e64 v90, s[4:5], s0, v120
	s_mov_b64 s[0:1], 0x2400000
	s_nop 0
	v_addc_co_u32_e64 v91, s[4:5], 0, v121, s[4:5]
	global_store_dwordx4 v[90:91], v[108:111], off
	v_lshl_add_u64 v[90:91], v[120:121], 0, s[0:1]
	s_mov_b32 s0, 0x2400000
	v_add_co_u32_e64 v102, s[4:5], s0, v120
	s_nop 1
	v_addc_co_u32_e64 v103, s[4:5], 0, v121, s[4:5]
	global_store_dwordx4 v[102:103], v[116:119], off
	global_load_dwordx4 v[108:111], v[98:99], off
	s_nop 0
	global_load_dwordx4 v[116:119], v[96:97], off
	ds_bpermute_b32 v101, v177, v84
	ds_bpermute_b32 v103, v177, v85
	ds_bpermute_b32 v126, v177, v86
	ds_bpermute_b32 v153, v177, v87
	v_mov_b32_e32 v102, v84
	v_mov_b32_e32 v84, v86
	s_waitcnt lgkmcnt(3)
	v_cndmask_b32_e64 v127, v101, -v101, vcc
	s_waitcnt lgkmcnt(2)
	v_cndmask_b32_e64 v163, v103, -v103, vcc
	s_waitcnt lgkmcnt(1)
	v_cndmask_b32_e64 v165, v126, -v126, vcc
	s_waitcnt lgkmcnt(0)
	v_cndmask_b32_e64 v187, v153, -v153, vcc
	s_waitcnt vmcnt(1)
	v_mov_b32_e32 v103, v108
	s_waitcnt vmcnt(0)
	v_mov_b32_e32 v126, v116
	v_mov_b32_e32 v108, v85
	v_mov_b32_e32 v162, v117
	v_mov_b32_e32 v85, v110
	v_mov_b32_e32 v164, v118
	v_mov_b32_e32 v110, v87
	v_mov_b32_e32 v186, v119
	v_pk_mul_f32 v[86:87], v[102:103], v[126:127]
	v_pk_mul_f32 v[102:103], v[108:109], v[162:163]
	v_pk_mul_f32 v[84:85], v[84:85], v[164:165]
	v_pk_mul_f32 v[108:109], v[110:111], v[186:187]
	v_add_f32_e32 v101, v86, v87
	v_add_f32_e32 v153, v102, v103
	v_add_f32_e32 v157, v84, v85
	v_add_f32_e32 v161, v108, v109
	global_load_dwordx4 v[84:87], v[92:93], off offset:16
	global_load_dwordx4 v[108:111], v[94:95], off offset:16
	ds_bpermute_b32 v103, v177, v80
	ds_bpermute_b32 v116, v177, v81
	ds_bpermute_b32 v118, v177, v82
	ds_bpermute_b32 v126, v177, v83
	v_mov_b32_e32 v102, v80
	v_mov_b32_e32 v80, v82
	s_waitcnt lgkmcnt(3)
	v_cndmask_b32_e64 v117, v103, -v103, vcc
	s_waitcnt lgkmcnt(2)
	v_cndmask_b32_e64 v119, v116, -v116, vcc
	s_waitcnt lgkmcnt(1)
	v_cndmask_b32_e64 v127, v118, -v118, vcc
	s_waitcnt lgkmcnt(0)
	v_cndmask_b32_e64 v163, v126, -v126, vcc
	s_waitcnt vmcnt(1)
	v_mov_b32_e32 v103, v84
	s_waitcnt vmcnt(0)
	v_mov_b32_e32 v116, v108
	v_mov_b32_e32 v84, v81
	v_mov_b32_e32 v118, v109
	v_mov_b32_e32 v81, v86
	v_mov_b32_e32 v126, v110
	v_mov_b32_e32 v86, v83
	v_mov_b32_e32 v162, v111
	v_pk_mul_f32 v[82:83], v[102:103], v[116:117]
	v_pk_mul_f32 v[84:85], v[84:85], v[118:119]
	v_pk_mul_f32 v[80:81], v[80:81], v[126:127]
	v_pk_mul_f32 v[86:87], v[86:87], v[162:163]
	v_add_f32_e32 v102, v82, v83
	v_add_f32_e32 v103, v84, v85
	v_add_f32_e32 v108, v80, v81
	v_add_f32_e32 v87, v86, v87
	v_mul_f32_e32 v80, v180, v101
	v_mul_f32_e32 v81, v181, v153
	v_cvt_pk_bf16_f32 v80, v80, v81
	v_mul_f32_e32 v81, v167, v157
	v_mul_f32_e32 v82, v183, v161
	v_cvt_pk_bf16_f32 v81, v81, v82
	v_mul_f32_e32 v82, v182, v102
	v_mul_f32_e32 v83, v185, v103
	v_cvt_pk_bf16_f32 v82, v82, v83
	v_mul_f32_e32 v83, v184, v108
	v_mul_f32_e32 v84, v159, v87
	v_cvt_pk_bf16_f32 v83, v83, v84
	v_mul_f32_e32 v84, v150, v101
	v_mul_f32_e32 v85, v152, v153
	v_cvt_pk_bf16_f32 v84, v84, v85
	v_mul_f32_e32 v85, v154, v157
	v_mul_f32_e32 v86, v156, v161
	v_cvt_pk_bf16_f32 v85, v85, v86
	v_mul_f32_e32 v86, v158, v102
	v_mul_f32_e32 v101, v160, v103
	v_mul_f32_e32 v87, v155, v87
	v_cvt_pk_bf16_f32 v86, v86, v101
	v_mul_f32_e32 v101, v151, v108
	v_cvt_pk_bf16_f32 v87, v101, v87
	global_store_dwordx4 v[88:89], v[80:83], off offset:256
	global_store_dwordx4 v[90:91], v[84:87], off offset:256
	s_nop 0
	v_add_u32_e32 v80, 0x200, v100
	v_ashrrev_i32_e32 v81, 31, v80
	v_lshl_add_u64 v[82:83], s[24:25], 0, v[136:137]
	v_lshlrev_b64 v[100:101], 2, v[80:81]
	v_lshl_add_u64 v[80:81], v[82:83], 0, v[100:101]
	v_add_co_u32_e64 v82, s[4:5], s61, v80
	ds_bpermute_b32 v103, v177, v76
	s_nop 0
	v_addc_co_u32_e64 v83, s[4:5], 0, v81, s[4:5]
	global_load_dwordx4 v[84:87], v[82:83], off
	global_load_dwordx4 v[88:91], v[80:81], off
	ds_bpermute_b32 v108, v177, v77
	ds_bpermute_b32 v110, v177, v78
	ds_bpermute_b32 v116, v177, v79
	v_mov_b32_e32 v102, v76
	v_mov_b32_e32 v76, v78
	s_waitcnt lgkmcnt(3)
	v_cndmask_b32_e64 v109, v103, -v103, vcc
	s_waitcnt lgkmcnt(2)
	v_cndmask_b32_e64 v111, v108, -v108, vcc
	s_waitcnt lgkmcnt(1)
	v_cndmask_b32_e64 v117, v110, -v110, vcc
	s_waitcnt lgkmcnt(0)
;     __device__ __forceinline__ void operator()(const AccT& acc, const Unit& u, int wr, int wc, int fr, int fq) const {
;     ...
;                 const int r = rbase + ai * 128 + m * 16;
;                 const int d = 4 * (2 * m + (fr >> 3)) + j;
; #pragma unroll
;                 for (int bj = 0; bj < 2; ++bj) {
;                     const int t0 = tb + bj * 128;
;                     float v[8];
; #pragma unroll
;                     for (int jj = 0; jj < 4; ++jj) { v[jj] = acc[ai][bj][m][0][jj]; v[4 + jj] = acc[ai][bj][m][1][jj]; }
;                     if constexpr (ROPE) {
;                         const int t = t0 & 2047;
; #pragma unroll
;                         for (int hf = 0; hf < 2; ++hf) {
;                             f32x4 cs, sn;
;                             if (m < 2) { const float c1 = ropeA[(t >> 6) * 16 + d], s1 = ropeA[1024 + (t >> 6) * 16 + d]; cs = (f32x4){c1, c1, c1, c1}; sn = (f32x4){s1, s1, s1, s1}; }
;                             else { const float* cb = ropeA + 2048 + (d - 16) * 64 + (t & 63) + 4 * hf; cs = *(const f32x4*)(cb); sn = *(const f32x4*)(cb + 1024); }
; #pragma unroll
;                             for (int jj = 0; jj < 4; ++jj) { const float pr = __shfl_xor(v[4 * hf + jj], 4); v[4 * hf + jj] = v[4 * hf + jj] * cs[jj] + sgn * pr * sn[jj]; }
;                             __builtin_amdgcn_sched_barrier(0);
;                         }
;                     }
;                     float zf[8], zb[8]; zf[0] = zf0; zb[0] = zb0;
; #pragma unroll
;                     for (int jj = 1; jj < 8; ++jj) { zf[jj] = zf[jj - 1] * zfs; zb[jj] = zb[jj - 1] * zbs; }
;                     u32x4 wf, wb;
;                     wf.x = cvt_pk_bf16(v[0] * zf[0], v[1] * zf[1]); wf.y = cvt_pk_bf16(v[2] * zf[2], v[3] * zf[3]); wf.z = cvt_pk_bf16(v[4] * zf[4], v[5] * zf[5]); wf.w = cvt_pk_bf16(v[6] * zf[6], v[7] * zf[7]);
;                     wb.x = cvt_pk_bf16(v[0] * zb[0], v[1] * zb[1]); wb.y = cvt_pk_bf16(v[2] * zb[2], v[3] * zb[3]); wb.z = cvt_pk_bf16(v[4] * zb[4], v[5] * zb[5]); wb.w = cvt_pk_bf16(v[6] * zb[6], v[7] * zb[7]);
;                     *(u32x4*)(KTZ + (size_t)r * NT + t0) = wf;
;                     *(u32x4*)(KTZ + (size_t)(256 + r) * NT + t0) = wb;
;                     __builtin_amdgcn_sched_barrier(0);
	v_cndmask_b32_e64 v119, v116, -v116, vcc
	s_waitcnt vmcnt(1)
	v_mov_b32_e32 v103, v84
	s_waitcnt vmcnt(0)
	v_mov_b32_e32 v108, v88
	v_mov_b32_e32 v84, v77
	v_mov_b32_e32 v110, v89
	v_mov_b32_e32 v77, v86
	v_mov_b32_e32 v116, v90
	v_mov_b32_e32 v86, v79
	v_mov_b32_e32 v118, v91
	v_pk_mul_f32 v[78:79], v[102:103], v[108:109]
	v_pk_mul_f32 v[84:85], v[84:85], v[110:111]
	v_pk_mul_f32 v[76:77], v[76:77], v[116:117]
	v_pk_mul_f32 v[86:87], v[86:87], v[118:119]
	v_add_f32_e32 v118, v78, v79
	v_add_f32_e32 v119, v84, v85
	v_add_f32_e32 v126, v76, v77
	v_add_f32_e32 v127, v86, v87
	v_lshl_add_u64 v[76:77], s[16:17], 0, v[100:101]
	v_lshl_add_u64 v[78:79], v[76:77], 0, v[136:137]
	v_add_co_u32_e64 v76, s[4:5], s62, v78
	ds_bpermute_b32 v101, v177, v72
	s_nop 0
	v_addc_co_u32_e64 v77, s[4:5], 0, v79, s[4:5]
	v_add_co_u32_e64 v78, s[4:5], s49, v78
	ds_bpermute_b32 v102, v177, v73
	s_nop 0
	v_addc_co_u32_e64 v79, s[4:5], 0, v79, s[4:5]
	global_load_dwordx4 v[84:87], v[76:77], off offset:16
	global_load_dwordx4 v[88:91], v[78:79], off offset:16
	ds_bpermute_b32 v108, v177, v74
	ds_bpermute_b32 v110, v177, v75
	v_mov_b32_e32 v100, v72
	v_mov_b32_e32 v72, v74
	s_waitcnt lgkmcnt(3)
	v_cndmask_b32_e64 v103, v101, -v101, vcc
	s_waitcnt lgkmcnt(2)
	v_cndmask_b32_e64 v109, v102, -v102, vcc
	s_waitcnt lgkmcnt(1)
	v_cndmask_b32_e64 v111, v108, -v108, vcc
	s_waitcnt lgkmcnt(0)
	v_cndmask_b32_e64 v117, v110, -v110, vcc
	s_waitcnt vmcnt(1)
	v_mov_b32_e32 v101, v84
	s_waitcnt vmcnt(0)
	v_mov_b32_e32 v102, v88
	v_mov_b32_e32 v84, v73
	v_mov_b32_e32 v108, v89
	v_mov_b32_e32 v73, v86
	v_mov_b32_e32 v110, v90
	v_mov_b32_e32 v86, v75
	v_mov_b32_e32 v116, v91
	v_pk_mul_f32 v[74:75], v[100:101], v[102:103]
	v_pk_mul_f32 v[84:85], v[84:85], v[108:109]
	v_pk_mul_f32 v[72:73], v[72:73], v[110:111]
	v_pk_mul_f32 v[86:87], v[86:87], v[116:117]
	v_add_f32_e32 v74, v74, v75
	v_add_f32_e32 v75, v84, v85
	v_add_f32_e32 v72, v72, v73
	v_add_f32_e32 v73, v86, v87
	v_mul_f32_e32 v84, v180, v118
	v_mul_f32_e32 v85, v181, v119
	v_cvt_pk_bf16_f32 v84, v84, v85
	v_mul_f32_e32 v85, v167, v126
	v_mul_f32_e32 v86, v183, v127
	v_cvt_pk_bf16_f32 v85, v85, v86
	v_mul_f32_e32 v86, v182, v74
	v_mul_f32_e32 v87, v185, v75
	v_cvt_pk_bf16_f32 v86, v86, v87
	v_mul_f32_e32 v87, v184, v72
	v_mul_f32_e32 v88, v159, v73
	v_cvt_pk_bf16_f32 v87, v87, v88
	v_mul_f32_e32 v88, v150, v118
	v_mul_f32_e32 v89, v152, v119
	v_cvt_pk_bf16_f32 v88, v88, v89
	v_mul_f32_e32 v89, v154, v126
	v_mul_f32_e32 v90, v156, v127
	v_mul_f32_e32 v72, v151, v72
	v_mul_f32_e32 v73, v155, v73
	s_mov_b64 s[0:1], 0x600000
	v_cvt_pk_bf16_f32 v89, v89, v90
	v_mul_f32_e32 v74, v158, v74
	v_mul_f32_e32 v75, v160, v75
	v_cvt_pk_bf16_f32 v90, v74, v75
	v_cvt_pk_bf16_f32 v91, v72, v73
	v_lshl_add_u64 v[72:73], v[120:121], 0, s[0:1]
	s_mov_b32 s0, 0x600000
	v_add_co_u32_e64 v74, s[4:5], s0, v120
	s_mov_b64 s[0:1], 0x2600000
	s_nop 0
	v_addc_co_u32_e64 v75, s[4:5], 0, v121, s[4:5]
	global_store_dwordx4 v[74:75], v[84:87], off
	v_lshl_add_u64 v[74:75], v[120:121], 0, s[0:1]
	s_mov_b32 s0, 0x2600000
	v_add_co_u32_e64 v84, s[4:5], s0, v120
	s_nop 1
	v_addc_co_u32_e64 v85, s[4:5], 0, v121, s[4:5]
	global_store_dwordx4 v[84:85], v[88:91], off
	global_load_dwordx4 v[84:87], v[82:83], off
	s_nop 0
	global_load_dwordx4 v[88:91], v[80:81], off
	ds_bpermute_b32 v101, v177, v68
	ds_bpermute_b32 v102, v177, v69
	ds_bpermute_b32 v108, v177, v70
	ds_bpermute_b32 v110, v177, v71
	v_mov_b32_e32 v100, v68
	v_mov_b32_e32 v68, v70
	s_waitcnt lgkmcnt(3)
	v_cndmask_b32_e64 v103, v101, -v101, vcc
	s_waitcnt lgkmcnt(2)
	v_cndmask_b32_e64 v109, v102, -v102, vcc
	s_waitcnt lgkmcnt(1)
	v_cndmask_b32_e64 v111, v108, -v108, vcc
	s_waitcnt lgkmcnt(0)
	v_cndmask_b32_e64 v117, v110, -v110, vcc
	s_waitcnt vmcnt(1)
	v_mov_b32_e32 v101, v84
	s_waitcnt vmcnt(0)
	v_mov_b32_e32 v102, v88
	v_mov_b32_e32 v84, v69
	v_mov_b32_e32 v108, v89
	v_mov_b32_e32 v69, v86
	v_mov_b32_e32 v110, v90
	v_mov_b32_e32 v86, v71
	v_mov_b32_e32 v116, v91
	v_pk_mul_f32 v[70:71], v[100:101], v[102:103]
	v_pk_mul_f32 v[84:85], v[84:85], v[108:109]
	v_pk_mul_f32 v[68:69], v[68:69], v[110:111]
	v_pk_mul_f32 v[86:87], v[86:87], v[116:117]
	v_add_f32_e32 v110, v70, v71
	v_add_f32_e32 v111, v84, v85
	v_add_f32_e32 v116, v68, v69
	v_add_f32_e32 v117, v86, v87
	global_load_dwordx4 v[68:71], v[76:77], off offset:16
	global_load_dwordx4 v[84:87], v[78:79], off offset:16
	ds_bpermute_b32 v89, v177, v64
	ds_bpermute_b32 v90, v177, v65
	ds_bpermute_b32 v100, v177, v66
	ds_bpermute_b32 v102, v177, v67
	v_mov_b32_e32 v88, v64
	v_mov_b32_e32 v64, v66
	s_waitcnt lgkmcnt(3)
	v_cndmask_b32_e64 v91, v89, -v89, vcc
	s_waitcnt lgkmcnt(2)
	v_cndmask_b32_e64 v101, v90, -v90, vcc
	s_waitcnt lgkmcnt(1)
	v_cndmask_b32_e64 v103, v100, -v100, vcc
	s_waitcnt lgkmcnt(0)
	v_cndmask_b32_e64 v109, v102, -v102, vcc
	s_waitcnt vmcnt(1)
	v_mov_b32_e32 v89, v68
	s_waitcnt vmcnt(0)
;     __device__ __forceinline__ void operator()(const AccT& acc, const Unit& u, int wr, int wc, int fr, int fq) const {
;     ...
;         for (int ai = 0; ai < 2; ++ai) {
;             const int hh = 2 * ai + wr;
;             const float l2f = lgd[hh] * 1.4426950408889634f, l2b = lgd[4 + hh] * 1.4426950408889634f;
;             const float zf0 = exp2f((float)(127 - o0) * l2f), zfs = exp2f(-l2f), zb0 = exp2f((float)o0 * l2b), zbs = exp2f(l2b);
; #pragma unroll
;             for (int m = 0; m < 4; ++m) {
;                 const int r = rbase + ai * 128 + m * 16;
;                 const int d = 4 * (2 * m + (fr >> 3)) + j;
; #pragma unroll
;                 for (int bj = 0; bj < 2; ++bj) {
;                     const int t0 = tb + bj * 128;
;                     float v[8];
; #pragma unroll
;                     for (int jj = 0; jj < 4; ++jj) { v[jj] = acc[ai][bj][m][0][jj]; v[4 + jj] = acc[ai][bj][m][1][jj]; }
;                     if constexpr (ROPE) {
;                         const int t = t0 & 2047;
; #pragma unroll
;                         for (int hf = 0; hf < 2; ++hf) {
;                             f32x4 cs, sn;
;                             if (m < 2) { const float c1 = ropeA[(t >> 6) * 16 + d], s1 = ropeA[1024 + (t >> 6) * 16 + d]; cs = (f32x4){c1, c1, c1, c1}; sn = (f32x4){s1, s1, s1, s1}; }
;                             else { const float* cb = ropeA + 2048 + (d - 16) * 64 + (t & 63) + 4 * hf; cs = *(const f32x4*)(cb); sn = *(const f32x4*)(cb + 1024); }
; #pragma unroll
;                             for (int jj = 0; jj < 4; ++jj) { const float pr = __shfl_xor(v[4 * hf + jj], 4); v[4 * hf + jj] = v[4 * hf + jj] * cs[jj] + sgn * pr * sn[jj]; }
;                             __builtin_amdgcn_sched_barrier(0);
;                         }
;                     }
;                     float zf[8], zb[8]; zf[0] = zf0; zb[0] = zb0;
; #pragma unroll
;                     for (int jj = 1; jj < 8; ++jj) { zf[jj] = zf[jj - 1] * zfs; zb[jj] = zb[jj - 1] * zbs; }
;                     u32x4 wf, wb;
;                     wf.x = cvt_pk_bf16(v[0] * zf[0], v[1] * zf[1]); wf.y = cvt_pk_bf16(v[2] * zf[2], v[3] * zf[3]); wf.z = cvt_pk_bf16(v[4] * zf[4], v[5] * zf[5]); wf.w = cvt_pk_bf16(v[6] * zf[6], v[7] * zf[7]);
	v_mov_b32_e32 v90, v84
	v_mov_b32_e32 v68, v65
	v_mov_b32_e32 v100, v85
	v_mov_b32_e32 v65, v70
	v_mov_b32_e32 v102, v86
	v_mov_b32_e32 v70, v67
	v_mov_b32_e32 v108, v87
	v_pk_mul_f32 v[66:67], v[88:89], v[90:91]
	v_pk_mul_f32 v[68:69], v[68:69], v[100:101]
	v_pk_mul_f32 v[64:65], v[64:65], v[102:103]
	v_pk_mul_f32 v[70:71], v[70:71], v[108:109]
	v_add_f32_e32 v84, v66, v67
	v_add_f32_e32 v85, v68, v69
	v_add_f32_e32 v86, v64, v65
	v_add_f32_e32 v71, v70, v71
	v_mul_f32_e32 v64, v180, v110
	v_mul_f32_e32 v65, v181, v111
	v_cvt_pk_bf16_f32 v64, v64, v65
	v_mul_f32_e32 v65, v167, v116
	v_mul_f32_e32 v66, v183, v117
	v_cvt_pk_bf16_f32 v65, v65, v66
	v_mul_f32_e32 v66, v182, v84
	v_mul_f32_e32 v67, v185, v85
	v_cvt_pk_bf16_f32 v66, v66, v67
	v_mul_f32_e32 v67, v184, v86
	v_mul_f32_e32 v68, v159, v71
	v_cvt_pk_bf16_f32 v67, v67, v68
	v_mul_f32_e32 v68, v150, v110
	v_mul_f32_e32 v69, v152, v111
	v_cvt_pk_bf16_f32 v68, v68, v69
	v_mul_f32_e32 v69, v154, v116
	v_mul_f32_e32 v70, v156, v117
	v_cvt_pk_bf16_f32 v69, v69, v70
	v_mul_f32_e32 v70, v158, v84
	v_mul_f32_e32 v84, v160, v85
	v_mul_f32_e32 v71, v155, v71
	v_cvt_pk_bf16_f32 v70, v70, v84
	v_mul_f32_e32 v84, v151, v86
	v_cvt_pk_bf16_f32 v71, v84, v71
	global_store_dwordx4 v[72:73], v[64:67], off offset:256
	global_store_dwordx4 v[74:75], v[68:71], off offset:256
	global_load_dword v64, v137, s[22:23] offset:8
	s_nop 0
	global_load_dword v70, v137, s[22:23] offset:24
	global_load_dword v67, v[146:147], off
	global_load_dword v74, v[148:149], off
	ds_bpermute_b32 v65, v177, v60
	ds_bpermute_b32 v68, v177, v62
	v_mov_b32_e32 v66, v60
	ds_bpermute_b32 v60, v177, v61
	ds_bpermute_b32 v71, v177, v63
	s_waitcnt lgkmcnt(3)
	v_cndmask_b32_e64 v75, v65, -v65, vcc
	s_waitcnt lgkmcnt(2)
	v_cndmask_b32_e64 v65, v68, -v68, vcc
	s_waitcnt vmcnt(3)
	v_mul_f32_e32 v72, 0x3fb8aa3b, v64
	s_waitcnt vmcnt(2)
	v_mul_f32_e32 v73, 0x3fb8aa3b, v70
	v_mul_f32_e32 v84, v72, v179
	s_waitcnt vmcnt(0)
	v_pk_mul_f32 v[68:69], v[66:67], v[74:75]
	s_waitcnt lgkmcnt(1)
	v_cndmask_b32_e64 v75, v60, -v60, vcc
	v_mov_b32_e32 v66, v61
	v_cmp_lt_f32_e64 s[4:5], s60, v72
	v_mul_f32_e32 v87, v73, v178
	v_pk_mul_f32 v[60:61], v[66:67], v[74:75]
	s_waitcnt lgkmcnt(0)
	v_cndmask_b32_e64 v75, v71, -v71, vcc
	v_mov_b32_e32 v66, v63
	v_cmp_gt_f32_e64 s[8:9], s59, v84
	v_cndmask_b32_e64 v86, 0, v176, s[4:5]
	v_cmp_gt_f32_e64 s[6:7], s59, v73
	s_and_b64 s[0:1], s[4:5], exec
	v_cmp_gt_f32_e64 s[4:5], s59, v87
	v_add_f32_e32 v110, v60, v61
	v_pk_mul_f32 v[60:61], v[66:67], v[74:75]
	v_cndmask_b32_e64 v66, 0, v176, s[8:9]
	v_cndmask_b32_e64 v88, 0, v176, s[6:7]
	v_add_f32_e32 v89, v68, v69
	v_fmac_f32_e32 v86, 0xbfb8aa3b, v64
	v_cndmask_b32_e64 v69, 0, v176, s[4:5]
	v_fmac_f32_e32 v66, v72, v179
	v_fmac_f32_e32 v88, 0x3fb8aa3b, v70
	v_exp_f32_e32 v68, v86
	v_fmac_f32_e32 v69, v73, v178
	v_exp_f32_e32 v66, v66
	v_exp_f32_e32 v70, v88
	v_exp_f32_e32 v69, v69
	v_cndmask_b32_e64 v63, 0, v175, s[8:9]
	s_cselect_b32 s8, 0xffffffc0, 0
	s_and_b64 s[0:1], s[6:7], exec
	v_cndmask_b32_e64 v64, 0, v175, s[4:5]
	s_cselect_b32 s0, 0xffffffc0, 0
	v_ldexp_f32 v100, v68, s8
	v_ldexp_f32 v63, v66, v63
	v_mul_f32_e32 v85, v62, v74
	v_ldexp_f32 v90, v70, s0
	v_ldexp_f32 v64, v69, v64
	v_mul_f32_e32 v75, v100, v63
	v_add_f32_e32 v111, v60, v61
	global_load_dword v108, v[148:149], off
	global_load_dword v69, v[146:147], off
	ds_bpermute_b32 v61, v177, v57
	ds_bpermute_b32 v60, v177, v56
	v_mov_b32_e32 v68, v57
	ds_bpermute_b32 v57, v177, v59
	ds_bpermute_b32 v66, v177, v58
	s_waitcnt lgkmcnt(3)
	v_cndmask_b32_e64 v109, v61, -v61, vcc
	s_waitcnt lgkmcnt(2)
	v_cndmask_b32_e64 v70, v60, -v60, vcc
	s_waitcnt lgkmcnt(0)
	v_cndmask_b32_e64 v72, v66, -v66, vcc
	s_waitcnt vmcnt(1)
	v_mul_f32_e32 v71, v56, v108
	s_waitcnt vmcnt(0)
	v_pk_mul_f32 v[60:61], v[68:69], v[108:109]
	v_cndmask_b32_e64 v109, v57, -v57, vcc
	v_mov_b32_e32 v68, v59
	v_add_f32_e32 v57, v60, v61
	v_pk_mul_f32 v[60:61], v[68:69], v[108:109]
	s_nop 0
	v_add_f32_e32 v59, v60, v61
	v_mov_b32_e32 v91, v67
	v_pk_mul_f32 v[60:61], v[90:91], v[64:65]
	v_mov_b32_e32 v91, v85
	v_pk_mul_f32 v[66:67], v[90:91], v[60:61]
	v_mov_b32_e32 v91, v69
	v_mov_b32_e32 v67, v70
	v_mul_f32_e32 v84, v100, v75
	v_pk_mul_f32 v[68:69], v[90:91], v[66:67]
	v_mov_b32_e32 v70, v90
	v_mul_f32_e32 v86, v100, v84
	v_pk_mul_f32 v[70:71], v[70:71], v[68:69]
	v_mul_f32_e32 v85, v100, v86
	v_mov_b32_e32 v71, v72
	v_mul_f32_e32 v88, v100, v85
	v_pk_mul_f32 v[72:73], v[90:91], v[70:71]
	v_fma_f32 v61, v62, v74, v61
	v_mul_f32_e32 v87, v100, v88
	v_mul_f32_e32 v65, v90, v72
	v_mul_f32_e32 v62, v84, v61
	v_fma_f32 v56, v56, v108, v69
	v_mul_f32_e32 v71, v100, v87
	v_mul_f32_e32 v67, v90, v65
	v_mul_f32_e32 v90, v63, v89
	v_mul_f32_e32 v91, v75, v110
	v_cvt_pk_bf16_f32 v100, v90, v91
	v_mul_f32_e32 v74, v86, v111
	v_cvt_pk_bf16_f32 v101, v62, v74
	v_mul_f32_e32 v62, v85, v56
	v_fma_f32 v58, v58, v108, v73
	v_mul_f32_e32 v69, v88, v57
	v_cvt_pk_bf16_f32 v102, v62, v69
	v_mul_f32_e32 v62, v87, v58
	v_mul_f32_e32 v69, v71, v59
	v_cvt_pk_bf16_f32 v103, v62, v69
	v_mul_f32_e32 v62, v64, v89
	v_mul_f32_e32 v56, v70, v56
	v_mul_f32_e32 v57, v72, v57
	v_mul_f32_e32 v69, v60, v110
	v_cvt_pk_bf16_f32 v108, v62, v69
	v_mul_f32_e32 v61, v66, v61
	v_mul_f32_e32 v62, v68, v111
	v_cvt_pk_bf16_f32 v109, v61, v62
	v_cvt_pk_bf16_f32 v110, v56, v57
	v_mul_f32_e32 v56, v65, v58
	v_mul_f32_e32 v57, v67, v59
	s_mov_b64 s[0:1], 0x1000000
	v_cvt_pk_bf16_f32 v111, v56, v57
	v_lshl_add_u64 v[56:57], v[120:121], 0, s[0:1]
	s_mov_b32 s0, 0x1000000
	v_add_co_u32_e64 v58, s[4:5], s0, v120
	s_mov_b64 s[0:1], 0x3000000
	s_nop 0
	v_addc_co_u32_e64 v59, s[4:5], 0, v121, s[4:5]
	global_store_dwordx4 v[58:59], v[100:103], off
	v_lshl_add_u64 v[58:59], v[120:121], 0, s[0:1]
	s_mov_b32 s0, 0x3000000
	v_add_co_u32_e64 v90, s[4:5], s0, v120
	s_nop 1
	v_addc_co_u32_e64 v91, s[4:5], 0, v121, s[4:5]
	global_store_dwordx4 v[90:91], v[108:111], off
	global_load_dword v91, v[122:123], off
	s_nop 0
	global_load_dword v100, v[124:125], off
	ds_bpermute_b32 v61, v177, v52
	v_mov_b32_e32 v90, v52
	ds_bpermute_b32 v52, v177, v53
	ds_bpermute_b32 v62, v177, v54
	ds_bpermute_b32 v69, v177, v55
	s_waitcnt lgkmcnt(3)
;     __device__ __forceinline__ void operator()(const AccT& acc, const Unit& u, int wr, int wc, int fr, int fq) const {
;     ...
;                 const int r = rbase + ai * 128 + m * 16;
;                 const int d = 4 * (2 * m + (fr >> 3)) + j;
; #pragma unroll
;                 for (int bj = 0; bj < 2; ++bj) {
;                     const int t0 = tb + bj * 128;
;                     float v[8];
; #pragma unroll
;                     for (int jj = 0; jj < 4; ++jj) { v[jj] = acc[ai][bj][m][0][jj]; v[4 + jj] = acc[ai][bj][m][1][jj]; }
;                     if constexpr (ROPE) {
;                         const int t = t0 & 2047;
; #pragma unroll
;                         for (int hf = 0; hf < 2; ++hf) {
;                             f32x4 cs, sn;
;                             if (m < 2) { const float c1 = ropeA[(t >> 6) * 16 + d], s1 = ropeA[1024 + (t >> 6) * 16 + d]; cs = (f32x4){c1, c1, c1, c1}; sn = (f32x4){s1, s1, s1, s1}; }
;                             else { const float* cb = ropeA + 2048 + (d - 16) * 64 + (t & 63) + 4 * hf; cs = *(const f32x4*)(cb); sn = *(const f32x4*)(cb + 1024); }
; #pragma unroll
;                             for (int jj = 0; jj < 4; ++jj) { const float pr = __shfl_xor(v[4 * hf + jj], 4); v[4 * hf + jj] = v[4 * hf + jj] * cs[jj] + sgn * pr * sn[jj]; }
;                             __builtin_amdgcn_sched_barrier(0);
;                         }
;                     }
;                     float zf[8], zb[8]; zf[0] = zf0; zb[0] = zb0;
; #pragma unroll
;                     for (int jj = 1; jj < 8; ++jj) { zf[jj] = zf[jj - 1] * zfs; zb[jj] = zb[jj - 1] * zbs; }
;                     u32x4 wf, wb;
;                     wf.x = cvt_pk_bf16(v[0] * zf[0], v[1] * zf[1]); wf.y = cvt_pk_bf16(v[2] * zf[2], v[3] * zf[3]); wf.z = cvt_pk_bf16(v[4] * zf[4], v[5] * zf[5]); wf.w = cvt_pk_bf16(v[6] * zf[6], v[7] * zf[7]);
;                     wb.x = cvt_pk_bf16(v[0] * zb[0], v[1] * zb[1]); wb.y = cvt_pk_bf16(v[2] * zb[2], v[3] * zb[3]); wb.z = cvt_pk_bf16(v[4] * zb[4], v[5] * zb[5]); wb.w = cvt_pk_bf16(v[6] * zb[6], v[7] * zb[7]);
;                     *(u32x4*)(KTZ + (size_t)r * NT + t0) = wf;
;                     *(u32x4*)(KTZ + (size_t)(256 + r) * NT + t0) = wb;
;                     __builtin_amdgcn_sched_barrier(0);
	v_cndmask_b32_e64 v101, v61, -v61, vcc
	s_waitcnt vmcnt(0)
	v_pk_mul_f32 v[102:103], v[90:91], v[100:101]
	s_waitcnt lgkmcnt(2)
	v_cndmask_b32_e64 v101, v52, -v52, vcc
	v_mov_b32_e32 v90, v53
	v_pk_mul_f32 v[52:53], v[90:91], v[100:101]
	s_waitcnt lgkmcnt(1)
	v_cndmask_b32_e64 v101, v62, -v62, vcc
	v_mov_b32_e32 v90, v54
	v_add_f32_e32 v62, v52, v53
	v_pk_mul_f32 v[52:53], v[90:91], v[100:101]
	s_waitcnt lgkmcnt(0)
	v_cndmask_b32_e64 v101, v69, -v69, vcc
	v_mov_b32_e32 v90, v55
	v_add_f32_e32 v69, v52, v53
	v_pk_mul_f32 v[52:53], v[90:91], v[100:101]
	v_add_f32_e32 v61, v102, v103
	v_add_f32_e32 v73, v52, v53
	global_load_dword v53, v[122:123], off
	global_load_dword v54, v[124:125], off
	ds_bpermute_b32 v55, v177, v48
	v_mov_b32_e32 v52, v48
	ds_bpermute_b32 v48, v177, v49
	ds_bpermute_b32 v74, v177, v50
	ds_bpermute_b32 v89, v177, v51
	s_waitcnt lgkmcnt(3)
	v_cndmask_b32_e64 v55, v55, -v55, vcc
	s_waitcnt vmcnt(0)
	v_pk_mul_f32 v[90:91], v[52:53], v[54:55]
	s_waitcnt lgkmcnt(2)
	v_cndmask_b32_e64 v55, v48, -v48, vcc
	v_mov_b32_e32 v52, v49
	v_pk_mul_f32 v[48:49], v[52:53], v[54:55]
	s_waitcnt lgkmcnt(1)
	v_cndmask_b32_e64 v55, v74, -v74, vcc
	v_mov_b32_e32 v52, v50
	v_add_f32_e32 v74, v48, v49
	v_pk_mul_f32 v[48:49], v[52:53], v[54:55]
	s_waitcnt lgkmcnt(0)
	v_cndmask_b32_e64 v55, v89, -v89, vcc
	v_mov_b32_e32 v52, v51
	v_add_f32_e32 v89, v48, v49
	v_pk_mul_f32 v[48:49], v[52:53], v[54:55]
	v_add_f32_e32 v90, v90, v91
	v_add_f32_e32 v55, v48, v49
	v_mul_f32_e32 v48, v63, v61
	v_mul_f32_e32 v49, v75, v62
	v_cvt_pk_bf16_f32 v48, v48, v49
	v_mul_f32_e32 v49, v84, v69
	v_mul_f32_e32 v50, v86, v73
	v_cvt_pk_bf16_f32 v49, v49, v50
	v_mul_f32_e32 v50, v85, v90
	v_mul_f32_e32 v51, v88, v74
	v_cvt_pk_bf16_f32 v50, v50, v51
	v_mul_f32_e32 v51, v87, v89
	v_mul_f32_e32 v52, v71, v55
	v_cvt_pk_bf16_f32 v51, v51, v52
	v_mul_f32_e32 v52, v64, v61
	v_mul_f32_e32 v53, v60, v62
	v_cvt_pk_bf16_f32 v52, v52, v53
	v_mul_f32_e32 v53, v66, v69
	v_mul_f32_e32 v54, v68, v73
	v_cvt_pk_bf16_f32 v53, v53, v54
	v_mul_f32_e32 v54, v70, v90
	v_mul_f32_e32 v61, v72, v74
	v_mul_f32_e32 v55, v67, v55
	v_cvt_pk_bf16_f32 v54, v54, v61
	v_mul_f32_e32 v61, v65, v89
	v_cvt_pk_bf16_f32 v55, v61, v55
	global_store_dwordx4 v[56:57], v[48:51], off offset:256
	global_store_dwordx4 v[58:59], v[52:55], off offset:256
	global_load_dword v49, v[112:113], off
	s_nop 0
	global_load_dword v50, v[114:115], off
	ds_bpermute_b32 v51, v177, v44
	v_mov_b32_e32 v48, v44
	ds_bpermute_b32 v44, v177, v45
	ds_bpermute_b32 v54, v177, v46
	ds_bpermute_b32 v55, v177, v47
	s_waitcnt lgkmcnt(3)
	v_cndmask_b32_e64 v51, v51, -v51, vcc
	s_waitcnt vmcnt(0)
	v_pk_mul_f32 v[52:53], v[48:49], v[50:51]
	s_waitcnt lgkmcnt(2)
	v_cndmask_b32_e64 v51, v44, -v44, vcc
	v_mov_b32_e32 v48, v45
	v_pk_mul_f32 v[44:45], v[48:49], v[50:51]
	s_waitcnt lgkmcnt(1)
	v_cndmask_b32_e64 v51, v54, -v54, vcc
	v_mov_b32_e32 v48, v46
	v_add_f32_e32 v52, v52, v53
	v_add_f32_e32 v53, v44, v45
	v_pk_mul_f32 v[44:45], v[48:49], v[50:51]
	s_waitcnt lgkmcnt(0)
	v_cndmask_b32_e64 v51, v55, -v55, vcc
	v_mov_b32_e32 v48, v47
	v_add_f32_e32 v54, v44, v45
	v_pk_mul_f32 v[44:45], v[48:49], v[50:51]
	s_nop 0
	v_add_f32_e32 v50, v44, v45
	global_load_dword v45, v[112:113], off
	global_load_dword v46, v[114:115], off
	ds_bpermute_b32 v47, v177, v40
	v_mov_b32_e32 v44, v40
	ds_bpermute_b32 v40, v177, v41
	ds_bpermute_b32 v51, v177, v42
	ds_bpermute_b32 v55, v177, v43
	s_waitcnt lgkmcnt(3)
	v_cndmask_b32_e64 v47, v47, -v47, vcc
	s_waitcnt vmcnt(0)
	v_pk_mul_f32 v[48:49], v[44:45], v[46:47]
	s_waitcnt lgkmcnt(2)
	v_cndmask_b32_e64 v47, v40, -v40, vcc
	v_mov_b32_e32 v44, v41
	v_pk_mul_f32 v[40:41], v[44:45], v[46:47]
	s_waitcnt lgkmcnt(1)
	v_cndmask_b32_e64 v47, v51, -v51, vcc
	v_mov_b32_e32 v44, v42
	v_add_f32_e32 v48, v48, v49
	v_add_f32_e32 v49, v40, v41
	v_pk_mul_f32 v[40:41], v[44:45], v[46:47]
	s_waitcnt lgkmcnt(0)
	v_cndmask_b32_e64 v47, v55, -v55, vcc
	v_mov_b32_e32 v44, v43
	v_add_f32_e32 v51, v40, v41
	v_pk_mul_f32 v[40:41], v[44:45], v[46:47]
	s_nop 0
	v_add_f32_e32 v40, v40, v41
	v_mul_f32_e32 v41, v63, v52
	v_mul_f32_e32 v42, v75, v53
	v_cvt_pk_bf16_f32 v42, v41, v42
	v_mul_f32_e32 v41, v84, v54
	v_mul_f32_e32 v43, v86, v50
	v_cvt_pk_bf16_f32 v43, v41, v43
	v_mul_f32_e32 v41, v85, v48
	v_mul_f32_e32 v44, v88, v49
	v_cvt_pk_bf16_f32 v44, v41, v44
	v_mul_f32_e32 v41, v87, v51
	v_mul_f32_e32 v45, v71, v40
	v_cvt_pk_bf16_f32 v45, v41, v45
	v_mul_f32_e32 v41, v64, v52
	v_mul_f32_e32 v46, v60, v53
	v_cvt_pk_bf16_f32 v46, v41, v46
	v_mul_f32_e32 v41, v66, v54
	v_mul_f32_e32 v47, v68, v50
	v_cvt_pk_bf16_f32 v47, v41, v47
	v_mul_f32_e32 v41, v70, v48
	v_mul_f32_e32 v48, v72, v49
	v_cvt_pk_bf16_f32 v48, v41, v48
	v_mul_f32_e32 v41, v65, v51
	v_mul_f32_e32 v40, v67, v40
	s_mov_b64 s[0:1], 0x1200000
	v_cvt_pk_bf16_f32 v49, v41, v40
	v_lshl_add_u64 v[40:41], v[120:121], 0, s[0:1]
	s_mov_b32 s0, 0x1200000
	v_add_co_u32_e64 v50, s[4:5], s0, v120
	s_mov_b64 s[0:1], 0x3200000
	s_nop 0
	v_addc_co_u32_e64 v51, s[4:5], 0, v121, s[4:5]
	global_store_dwordx4 v[50:51], v[42:45], off
	s_nop 1
	v_lshl_add_u64 v[42:43], v[120:121], 0, s[0:1]
	s_mov_b32 s0, 0x3200000
	v_add_co_u32_e64 v44, s[4:5], s0, v120
	s_nop 1
	v_addc_co_u32_e64 v45, s[4:5], 0, v121, s[4:5]
	global_store_dwordx4 v[44:45], v[46:49], off
	global_load_dword v45, v[104:105], off
	s_nop 0
	global_load_dword v46, v[106:107], off
	ds_bpermute_b32 v47, v177, v36
	v_mov_b32_e32 v44, v36
	ds_bpermute_b32 v36, v177, v37
	ds_bpermute_b32 v50, v177, v38
	ds_bpermute_b32 v51, v177, v39
	s_waitcnt lgkmcnt(3)
	v_cndmask_b32_e64 v47, v47, -v47, vcc
	s_waitcnt vmcnt(0)
	v_pk_mul_f32 v[48:49], v[44:45], v[46:47]
	s_waitcnt lgkmcnt(2)
;     __device__ __forceinline__ void operator()(const AccT& acc, const Unit& u, int wr, int wc, int fr, int fq) const {
;     ...
;                 const int r = rbase + ai * 128 + m * 16;
;                 const int d = 4 * (2 * m + (fr >> 3)) + j;
; #pragma unroll
;                 for (int bj = 0; bj < 2; ++bj) {
;                     const int t0 = tb + bj * 128;
;                     float v[8];
; #pragma unroll
;                     for (int jj = 0; jj < 4; ++jj) { v[jj] = acc[ai][bj][m][0][jj]; v[4 + jj] = acc[ai][bj][m][1][jj]; }
;                     if constexpr (ROPE) {
;                         const int t = t0 & 2047;
; #pragma unroll
;                         for (int hf = 0; hf < 2; ++hf) {
;                             f32x4 cs, sn;
;                             if (m < 2) { const float c1 = ropeA[(t >> 6) * 16 + d], s1 = ropeA[1024 + (t >> 6) * 16 + d]; cs = (f32x4){c1, c1, c1, c1}; sn = (f32x4){s1, s1, s1, s1}; }
;                             else { const float* cb = ropeA + 2048 + (d - 16) * 64 + (t & 63) + 4 * hf; cs = *(const f32x4*)(cb); sn = *(const f32x4*)(cb + 1024); }
; #pragma unroll
;                             for (int jj = 0; jj < 4; ++jj) { const float pr = __shfl_xor(v[4 * hf + jj], 4); v[4 * hf + jj] = v[4 * hf + jj] * cs[jj] + sgn * pr * sn[jj]; }
;                             __builtin_amdgcn_sched_barrier(0);
;                         }
;                     }
;                     float zf[8], zb[8]; zf[0] = zf0; zb[0] = zb0;
; #pragma unroll
;                     for (int jj = 1; jj < 8; ++jj) { zf[jj] = zf[jj - 1] * zfs; zb[jj] = zb[jj - 1] * zbs; }
;                     u32x4 wf, wb;
;                     wf.x = cvt_pk_bf16(v[0] * zf[0], v[1] * zf[1]); wf.y = cvt_pk_bf16(v[2] * zf[2], v[3] * zf[3]); wf.z = cvt_pk_bf16(v[4] * zf[4], v[5] * zf[5]); wf.w = cvt_pk_bf16(v[6] * zf[6], v[7] * zf[7]);
;                     wb.x = cvt_pk_bf16(v[0] * zb[0], v[1] * zb[1]); wb.y = cvt_pk_bf16(v[2] * zb[2], v[3] * zb[3]); wb.z = cvt_pk_bf16(v[4] * zb[4], v[5] * zb[5]); wb.w = cvt_pk_bf16(v[6] * zb[6], v[7] * zb[7]);
;                     *(u32x4*)(KTZ + (size_t)r * NT + t0) = wf;
;                     *(u32x4*)(KTZ + (size_t)(256 + r) * NT + t0) = wb;
;                     __builtin_amdgcn_sched_barrier(0);
	v_cndmask_b32_e64 v47, v36, -v36, vcc
	v_mov_b32_e32 v44, v37
	v_pk_mul_f32 v[36:37], v[44:45], v[46:47]
	s_waitcnt lgkmcnt(1)
	v_cndmask_b32_e64 v47, v50, -v50, vcc
	v_mov_b32_e32 v44, v38
	v_add_f32_e32 v48, v48, v49
	v_add_f32_e32 v49, v36, v37
	v_pk_mul_f32 v[36:37], v[44:45], v[46:47]
	s_waitcnt lgkmcnt(0)
	v_cndmask_b32_e64 v47, v51, -v51, vcc
	v_mov_b32_e32 v44, v39
	v_add_f32_e32 v50, v36, v37
	v_pk_mul_f32 v[36:37], v[44:45], v[46:47]
	s_nop 0
	v_add_f32_e32 v46, v36, v37
	global_load_dword v37, v[104:105], off
	global_load_dword v38, v[106:107], off
	ds_bpermute_b32 v39, v177, v32
	v_mov_b32_e32 v36, v32
	ds_bpermute_b32 v32, v177, v33
	ds_bpermute_b32 v47, v177, v34
	ds_bpermute_b32 v51, v177, v35
	s_waitcnt lgkmcnt(3)
	v_cndmask_b32_e64 v39, v39, -v39, vcc
	s_waitcnt vmcnt(0)
	v_pk_mul_f32 v[44:45], v[36:37], v[38:39]
	s_waitcnt lgkmcnt(2)
	v_cndmask_b32_e64 v39, v32, -v32, vcc
	v_mov_b32_e32 v36, v33
	v_pk_mul_f32 v[32:33], v[36:37], v[38:39]
	s_waitcnt lgkmcnt(1)
	v_cndmask_b32_e64 v39, v47, -v47, vcc
	v_mov_b32_e32 v36, v34
	v_add_f32_e32 v44, v44, v45
	v_add_f32_e32 v45, v32, v33
	v_pk_mul_f32 v[32:33], v[36:37], v[38:39]
	s_waitcnt lgkmcnt(0)
	v_cndmask_b32_e64 v39, v51, -v51, vcc
	v_mov_b32_e32 v36, v35
	v_add_f32_e32 v47, v32, v33
	v_pk_mul_f32 v[32:33], v[36:37], v[38:39]
	s_nop 0
	v_add_f32_e32 v39, v32, v33
	v_mul_f32_e32 v32, v63, v48
	v_mul_f32_e32 v33, v75, v49
	v_cvt_pk_bf16_f32 v32, v32, v33
	v_mul_f32_e32 v33, v84, v50
	v_mul_f32_e32 v34, v86, v46
	v_cvt_pk_bf16_f32 v33, v33, v34
	v_mul_f32_e32 v34, v85, v44
	v_mul_f32_e32 v35, v88, v45
	v_cvt_pk_bf16_f32 v34, v34, v35
	v_mul_f32_e32 v35, v87, v47
	v_mul_f32_e32 v36, v71, v39
	v_cvt_pk_bf16_f32 v35, v35, v36
	v_mul_f32_e32 v36, v64, v48
	v_mul_f32_e32 v37, v60, v49
	v_cvt_pk_bf16_f32 v36, v36, v37
	v_mul_f32_e32 v37, v66, v50
	v_mul_f32_e32 v38, v68, v46
	v_cvt_pk_bf16_f32 v37, v37, v38
	v_mul_f32_e32 v38, v70, v44
	v_mul_f32_e32 v44, v72, v45
	v_mul_f32_e32 v39, v67, v39
	v_cvt_pk_bf16_f32 v38, v38, v44
	v_mul_f32_e32 v44, v65, v47
	v_cvt_pk_bf16_f32 v39, v44, v39
	global_store_dwordx4 v[40:41], v[32:35], off offset:256
	global_store_dwordx4 v[42:43], v[36:39], off offset:256
	global_load_dwordx4 v[32:35], v[98:99], off
	s_nop 0
	global_load_dwordx4 v[36:39], v[96:97], off
	ds_bpermute_b32 v41, v177, v28
	ds_bpermute_b32 v42, v177, v29
	ds_bpermute_b32 v44, v177, v30
	ds_bpermute_b32 v46, v177, v31
	v_mov_b32_e32 v40, v28
	v_mov_b32_e32 v28, v30
	s_waitcnt lgkmcnt(3)
	v_cndmask_b32_e64 v43, v41, -v41, vcc
	s_waitcnt lgkmcnt(2)
	v_cndmask_b32_e64 v45, v42, -v42, vcc
	s_waitcnt lgkmcnt(1)
	v_cndmask_b32_e64 v47, v44, -v44, vcc
	s_waitcnt lgkmcnt(0)
	v_cndmask_b32_e64 v49, v46, -v46, vcc
	s_waitcnt vmcnt(1)
	v_mov_b32_e32 v41, v32
	s_waitcnt vmcnt(0)
	v_mov_b32_e32 v42, v36
	v_mov_b32_e32 v32, v29
	v_mov_b32_e32 v44, v37
	v_mov_b32_e32 v29, v34
	v_mov_b32_e32 v46, v38
	v_mov_b32_e32 v34, v31
	v_mov_b32_e32 v48, v39
	v_pk_mul_f32 v[30:31], v[40:41], v[42:43]
	v_pk_mul_f32 v[32:33], v[32:33], v[44:45]
	v_pk_mul_f32 v[28:29], v[28:29], v[46:47]
	v_pk_mul_f32 v[34:35], v[34:35], v[48:49]
	v_add_f32_e32 v46, v30, v31
	v_add_f32_e32 v47, v32, v33
	v_add_f32_e32 v48, v28, v29
	v_add_f32_e32 v49, v34, v35
	global_load_dwordx4 v[28:31], v[92:93], off offset:16
	global_load_dwordx4 v[32:35], v[94:95], off offset:16
	ds_bpermute_b32 v37, v177, v24
	ds_bpermute_b32 v38, v177, v25
	ds_bpermute_b32 v40, v177, v26
	ds_bpermute_b32 v42, v177, v27
	v_mov_b32_e32 v36, v24
	v_mov_b32_e32 v24, v26
	s_waitcnt lgkmcnt(3)
	v_cndmask_b32_e64 v39, v37, -v37, vcc
	s_waitcnt lgkmcnt(2)
	v_cndmask_b32_e64 v41, v38, -v38, vcc
	s_waitcnt lgkmcnt(1)
	v_cndmask_b32_e64 v43, v40, -v40, vcc
	s_waitcnt lgkmcnt(0)
	v_cndmask_b32_e64 v45, v42, -v42, vcc
	s_waitcnt vmcnt(1)
	v_mov_b32_e32 v37, v28
	s_waitcnt vmcnt(0)
	v_mov_b32_e32 v38, v32
	v_mov_b32_e32 v28, v25
	v_mov_b32_e32 v40, v33
	v_mov_b32_e32 v25, v30
	v_mov_b32_e32 v42, v34
	v_mov_b32_e32 v30, v27
	v_mov_b32_e32 v44, v35
	v_pk_mul_f32 v[26:27], v[36:37], v[38:39]
	v_pk_mul_f32 v[28:29], v[28:29], v[40:41]
	v_pk_mul_f32 v[24:25], v[24:25], v[42:43]
	v_pk_mul_f32 v[30:31], v[30:31], v[44:45]
	v_add_f32_e32 v32, v26, v27
	v_add_f32_e32 v33, v28, v29
	v_add_f32_e32 v24, v24, v25
	v_add_f32_e32 v25, v30, v31
	v_mul_f32_e32 v26, v63, v46
	v_mul_f32_e32 v27, v75, v47
	v_cvt_pk_bf16_f32 v26, v26, v27
	v_mul_f32_e32 v27, v84, v48
	v_mul_f32_e32 v28, v86, v49
	v_cvt_pk_bf16_f32 v27, v27, v28
	v_mul_f32_e32 v28, v85, v32
	v_mul_f32_e32 v29, v88, v33
	v_cvt_pk_bf16_f32 v28, v28, v29
	v_mul_f32_e32 v29, v87, v24
	v_mul_f32_e32 v30, v71, v25
	v_cvt_pk_bf16_f32 v29, v29, v30
	v_mul_f32_e32 v30, v64, v46
	v_mul_f32_e32 v31, v60, v47
	v_cvt_pk_bf16_f32 v30, v30, v31
	v_mul_f32_e32 v31, v66, v48
	v_mul_f32_e32 v32, v70, v32
	v_mul_f32_e32 v33, v72, v33
	v_mul_f32_e32 v24, v65, v24
	v_mul_f32_e32 v25, v67, v25
	s_mov_b64 s[0:1], 0x1400000
	v_mul_f32_e32 v34, v68, v49
	v_cvt_pk_bf16_f32 v31, v31, v34
	v_cvt_pk_bf16_f32 v32, v32, v33
	v_cvt_pk_bf16_f32 v33, v24, v25
	v_lshl_add_u64 v[24:25], v[120:121], 0, s[0:1]
	s_mov_b32 s0, 0x1400000
	v_add_co_u32_e64 v34, s[4:5], s0, v120
	s_mov_b64 s[0:1], 0x3400000
	s_nop 0
	v_addc_co_u32_e64 v35, s[4:5], 0, v121, s[4:5]
	global_store_dwordx4 v[34:35], v[26:29], off
	s_nop 1
	v_lshl_add_u64 v[26:27], v[120:121], 0, s[0:1]
	s_mov_b32 s0, 0x3400000
	v_add_co_u32_e64 v28, s[4:5], s0, v120
	s_nop 1
	v_addc_co_u32_e64 v29, s[4:5], 0, v121, s[4:5]
	global_store_dwordx4 v[28:29], v[30:33], off
	global_load_dwordx4 v[28:31], v[98:99], off
	s_nop 0
	global_load_dwordx4 v[32:35], v[96:97], off
	ds_bpermute_b32 v37, v177, v20
	ds_bpermute_b32 v38, v177, v21
	ds_bpermute_b32 v40, v177, v22
	ds_bpermute_b32 v42, v177, v23
	v_mov_b32_e32 v36, v20
	v_mov_b32_e32 v20, v22
	s_waitcnt lgkmcnt(3)
;     __device__ __forceinline__ void operator()(const AccT& acc, const Unit& u, int wr, int wc, int fr, int fq) const {
;     ...
;                 const int r = rbase + ai * 128 + m * 16;
;                 const int d = 4 * (2 * m + (fr >> 3)) + j;
; #pragma unroll
;                 for (int bj = 0; bj < 2; ++bj) {
;                     const int t0 = tb + bj * 128;
;                     float v[8];
; #pragma unroll
;                     for (int jj = 0; jj < 4; ++jj) { v[jj] = acc[ai][bj][m][0][jj]; v[4 + jj] = acc[ai][bj][m][1][jj]; }
;                     if constexpr (ROPE) {
;                         const int t = t0 & 2047;
; #pragma unroll
;                         for (int hf = 0; hf < 2; ++hf) {
;                             f32x4 cs, sn;
;                             if (m < 2) { const float c1 = ropeA[(t >> 6) * 16 + d], s1 = ropeA[1024 + (t >> 6) * 16 + d]; cs = (f32x4){c1, c1, c1, c1}; sn = (f32x4){s1, s1, s1, s1}; }
;                             else { const float* cb = ropeA + 2048 + (d - 16) * 64 + (t & 63) + 4 * hf; cs = *(const f32x4*)(cb); sn = *(const f32x4*)(cb + 1024); }
; #pragma unroll
;                             for (int jj = 0; jj < 4; ++jj) { const float pr = __shfl_xor(v[4 * hf + jj], 4); v[4 * hf + jj] = v[4 * hf + jj] * cs[jj] + sgn * pr * sn[jj]; }
;                             __builtin_amdgcn_sched_barrier(0);
;                         }
;                     }
;                     float zf[8], zb[8]; zf[0] = zf0; zb[0] = zb0;
; #pragma unroll
;                     for (int jj = 1; jj < 8; ++jj) { zf[jj] = zf[jj - 1] * zfs; zb[jj] = zb[jj - 1] * zbs; }
;                     u32x4 wf, wb;
;                     wf.x = cvt_pk_bf16(v[0] * zf[0], v[1] * zf[1]); wf.y = cvt_pk_bf16(v[2] * zf[2], v[3] * zf[3]); wf.z = cvt_pk_bf16(v[4] * zf[4], v[5] * zf[5]); wf.w = cvt_pk_bf16(v[6] * zf[6], v[7] * zf[7]);
;                     wb.x = cvt_pk_bf16(v[0] * zb[0], v[1] * zb[1]); wb.y = cvt_pk_bf16(v[2] * zb[2], v[3] * zb[3]); wb.z = cvt_pk_bf16(v[4] * zb[4], v[5] * zb[5]); wb.w = cvt_pk_bf16(v[6] * zb[6], v[7] * zb[7]);
;                     *(u32x4*)(KTZ + (size_t)r * NT + t0) = wf;
;                     *(u32x4*)(KTZ + (size_t)(256 + r) * NT + t0) = wb;
;                     __builtin_amdgcn_sched_barrier(0);
	v_cndmask_b32_e64 v39, v37, -v37, vcc
	s_waitcnt lgkmcnt(2)
	v_cndmask_b32_e64 v41, v38, -v38, vcc
	s_waitcnt lgkmcnt(1)
	v_cndmask_b32_e64 v43, v40, -v40, vcc
	s_waitcnt lgkmcnt(0)
	v_cndmask_b32_e64 v45, v42, -v42, vcc
	s_waitcnt vmcnt(1)
	v_mov_b32_e32 v37, v28
	s_waitcnt vmcnt(0)
	v_mov_b32_e32 v38, v32
	v_mov_b32_e32 v28, v21
	v_mov_b32_e32 v40, v33
	v_mov_b32_e32 v21, v30
	v_mov_b32_e32 v42, v34
	v_mov_b32_e32 v30, v23
	v_mov_b32_e32 v44, v35
	v_pk_mul_f32 v[22:23], v[36:37], v[38:39]
	v_pk_mul_f32 v[28:29], v[28:29], v[40:41]
	v_pk_mul_f32 v[20:21], v[20:21], v[42:43]
	v_pk_mul_f32 v[30:31], v[30:31], v[44:45]
	v_add_f32_e32 v42, v22, v23
	v_add_f32_e32 v43, v28, v29
	v_add_f32_e32 v44, v20, v21
	v_add_f32_e32 v45, v30, v31
	global_load_dwordx4 v[20:23], v[92:93], off offset:16
	global_load_dwordx4 v[28:31], v[94:95], off offset:16
	ds_bpermute_b32 v33, v177, v16
	ds_bpermute_b32 v34, v177, v17
	ds_bpermute_b32 v36, v177, v18
	ds_bpermute_b32 v38, v177, v19
	v_mov_b32_e32 v32, v16
	v_mov_b32_e32 v16, v18
	s_waitcnt lgkmcnt(3)
	v_cndmask_b32_e64 v35, v33, -v33, vcc
	s_waitcnt lgkmcnt(2)
	v_cndmask_b32_e64 v37, v34, -v34, vcc
	s_waitcnt lgkmcnt(1)
	v_cndmask_b32_e64 v39, v36, -v36, vcc
	s_waitcnt lgkmcnt(0)
	v_cndmask_b32_e64 v41, v38, -v38, vcc
	s_waitcnt vmcnt(1)
	v_mov_b32_e32 v33, v20
	s_waitcnt vmcnt(0)
	v_mov_b32_e32 v34, v28
	v_mov_b32_e32 v20, v17
	v_mov_b32_e32 v36, v29
	v_mov_b32_e32 v17, v22
	v_mov_b32_e32 v38, v30
	v_mov_b32_e32 v22, v19
	v_mov_b32_e32 v40, v31
	v_pk_mul_f32 v[18:19], v[32:33], v[34:35]
	v_pk_mul_f32 v[20:21], v[20:21], v[36:37]
	v_pk_mul_f32 v[16:17], v[16:17], v[38:39]
	v_pk_mul_f32 v[22:23], v[22:23], v[40:41]
	v_add_f32_e32 v28, v18, v19
	v_add_f32_e32 v29, v20, v21
	v_add_f32_e32 v30, v16, v17
	v_add_f32_e32 v23, v22, v23
	v_mul_f32_e32 v16, v63, v42
	v_mul_f32_e32 v17, v75, v43
	v_cvt_pk_bf16_f32 v16, v16, v17
	v_mul_f32_e32 v17, v84, v44
	v_mul_f32_e32 v18, v86, v45
	v_cvt_pk_bf16_f32 v17, v17, v18
	v_mul_f32_e32 v18, v85, v28
	v_mul_f32_e32 v19, v88, v29
	v_cvt_pk_bf16_f32 v18, v18, v19
	v_mul_f32_e32 v19, v87, v30
	v_mul_f32_e32 v20, v71, v23
	v_cvt_pk_bf16_f32 v19, v19, v20
	v_mul_f32_e32 v20, v64, v42
	v_mul_f32_e32 v21, v60, v43
	v_cvt_pk_bf16_f32 v20, v20, v21
	v_mul_f32_e32 v21, v66, v44
	v_mul_f32_e32 v22, v68, v45
	v_cvt_pk_bf16_f32 v21, v21, v22
	v_mul_f32_e32 v22, v70, v28
	v_mul_f32_e32 v28, v72, v29
	v_mul_f32_e32 v23, v67, v23
	v_cvt_pk_bf16_f32 v22, v22, v28
	v_mul_f32_e32 v28, v65, v30
	v_cvt_pk_bf16_f32 v23, v28, v23
	global_store_dwordx4 v[24:25], v[16:19], off offset:256
	global_store_dwordx4 v[26:27], v[20:23], off offset:256
	global_load_dwordx4 v[16:19], v[82:83], off
	s_nop 0
	global_load_dwordx4 v[20:23], v[80:81], off
	ds_bpermute_b32 v25, v177, v12
	ds_bpermute_b32 v26, v177, v13
	ds_bpermute_b32 v28, v177, v14
	ds_bpermute_b32 v30, v177, v15
	v_mov_b32_e32 v24, v12
	v_mov_b32_e32 v12, v14
	s_waitcnt lgkmcnt(3)
	v_cndmask_b32_e64 v27, v25, -v25, vcc
	s_waitcnt lgkmcnt(2)
	v_cndmask_b32_e64 v29, v26, -v26, vcc
	s_waitcnt lgkmcnt(1)
	v_cndmask_b32_e64 v31, v28, -v28, vcc
	s_waitcnt lgkmcnt(0)
	v_cndmask_b32_e64 v33, v30, -v30, vcc
	s_waitcnt vmcnt(1)
	v_mov_b32_e32 v25, v16
	s_waitcnt vmcnt(0)
	v_mov_b32_e32 v26, v20
	v_mov_b32_e32 v16, v13
	v_mov_b32_e32 v28, v21
	v_mov_b32_e32 v13, v18
	v_mov_b32_e32 v30, v22
	v_mov_b32_e32 v18, v15
	v_mov_b32_e32 v32, v23
	v_pk_mul_f32 v[14:15], v[24:25], v[26:27]
	v_pk_mul_f32 v[16:17], v[16:17], v[28:29]
	v_pk_mul_f32 v[12:13], v[12:13], v[30:31]
	v_pk_mul_f32 v[18:19], v[18:19], v[32:33]
	v_add_f32_e32 v30, v14, v15
	v_add_f32_e32 v31, v16, v17
	v_add_f32_e32 v32, v12, v13
	v_add_f32_e32 v33, v18, v19
	global_load_dwordx4 v[12:15], v[76:77], off offset:16
	global_load_dwordx4 v[16:19], v[78:79], off offset:16
	ds_bpermute_b32 v21, v177, v8
	ds_bpermute_b32 v22, v177, v9
	ds_bpermute_b32 v24, v177, v10
	ds_bpermute_b32 v26, v177, v11
	v_mov_b32_e32 v20, v8
	v_mov_b32_e32 v8, v10
	s_waitcnt lgkmcnt(3)
	v_cndmask_b32_e64 v23, v21, -v21, vcc
	s_waitcnt lgkmcnt(2)
	v_cndmask_b32_e64 v25, v22, -v22, vcc
	s_waitcnt lgkmcnt(1)
	v_cndmask_b32_e64 v27, v24, -v24, vcc
	s_waitcnt lgkmcnt(0)
	v_cndmask_b32_e64 v29, v26, -v26, vcc
	s_waitcnt vmcnt(1)
	v_mov_b32_e32 v21, v12
	s_waitcnt vmcnt(0)
;     __device__ __forceinline__ void operator()(const AccT& acc, const Unit& u, int wr, int wc, int fr, int fq) const {
;     ...
;                 const int r = rbase + ai * 128 + m * 16;
;                 const int d = 4 * (2 * m + (fr >> 3)) + j;
; #pragma unroll
;                 for (int bj = 0; bj < 2; ++bj) {
;                     const int t0 = tb + bj * 128;
;                     float v[8];
; #pragma unroll
;                     for (int jj = 0; jj < 4; ++jj) { v[jj] = acc[ai][bj][m][0][jj]; v[4 + jj] = acc[ai][bj][m][1][jj]; }
;                     if constexpr (ROPE) {
;                         const int t = t0 & 2047;
; #pragma unroll
;                         for (int hf = 0; hf < 2; ++hf) {
;                             f32x4 cs, sn;
;                             if (m < 2) { const float c1 = ropeA[(t >> 6) * 16 + d], s1 = ropeA[1024 + (t >> 6) * 16 + d]; cs = (f32x4){c1, c1, c1, c1}; sn = (f32x4){s1, s1, s1, s1}; }
;                             else { const float* cb = ropeA + 2048 + (d - 16) * 64 + (t & 63) + 4 * hf; cs = *(const f32x4*)(cb); sn = *(const f32x4*)(cb + 1024); }
; #pragma unroll
;                             for (int jj = 0; jj < 4; ++jj) { const float pr = __shfl_xor(v[4 * hf + jj], 4); v[4 * hf + jj] = v[4 * hf + jj] * cs[jj] + sgn * pr * sn[jj]; }
;                             __builtin_amdgcn_sched_barrier(0);
;                         }
;                     }
;                     float zf[8], zb[8]; zf[0] = zf0; zb[0] = zb0;
; #pragma unroll
;                     for (int jj = 1; jj < 8; ++jj) { zf[jj] = zf[jj - 1] * zfs; zb[jj] = zb[jj - 1] * zbs; }
;                     u32x4 wf, wb;
;                     wf.x = cvt_pk_bf16(v[0] * zf[0], v[1] * zf[1]); wf.y = cvt_pk_bf16(v[2] * zf[2], v[3] * zf[3]); wf.z = cvt_pk_bf16(v[4] * zf[4], v[5] * zf[5]); wf.w = cvt_pk_bf16(v[6] * zf[6], v[7] * zf[7]);
;                     wb.x = cvt_pk_bf16(v[0] * zb[0], v[1] * zb[1]); wb.y = cvt_pk_bf16(v[2] * zb[2], v[3] * zb[3]); wb.z = cvt_pk_bf16(v[4] * zb[4], v[5] * zb[5]); wb.w = cvt_pk_bf16(v[6] * zb[6], v[7] * zb[7]);
;                     *(u32x4*)(KTZ + (size_t)r * NT + t0) = wf;
;                     *(u32x4*)(KTZ + (size_t)(256 + r) * NT + t0) = wb;
;                     __builtin_amdgcn_sched_barrier(0);
	v_mov_b32_e32 v22, v16
	v_mov_b32_e32 v12, v9
	v_mov_b32_e32 v24, v17
	v_mov_b32_e32 v9, v14
	v_mov_b32_e32 v26, v18
	v_mov_b32_e32 v14, v11
	v_mov_b32_e32 v28, v19
	v_pk_mul_f32 v[10:11], v[20:21], v[22:23]
	v_pk_mul_f32 v[12:13], v[12:13], v[24:25]
	v_pk_mul_f32 v[8:9], v[8:9], v[26:27]
	v_pk_mul_f32 v[14:15], v[14:15], v[28:29]
	v_add_f32_e32 v16, v10, v11
	v_add_f32_e32 v17, v12, v13
	v_add_f32_e32 v8, v8, v9
	v_add_f32_e32 v9, v14, v15
	v_mul_f32_e32 v10, v63, v30
	v_mul_f32_e32 v11, v75, v31
	v_cvt_pk_bf16_f32 v10, v10, v11
	v_mul_f32_e32 v11, v84, v32
	v_mul_f32_e32 v12, v86, v33
	v_cvt_pk_bf16_f32 v11, v11, v12
	v_mul_f32_e32 v12, v85, v16
	v_mul_f32_e32 v13, v88, v17
	v_cvt_pk_bf16_f32 v12, v12, v13
	v_mul_f32_e32 v13, v87, v8
	v_mul_f32_e32 v14, v71, v9
	v_cvt_pk_bf16_f32 v13, v13, v14
	v_mul_f32_e32 v14, v64, v30
	v_mul_f32_e32 v15, v60, v31
	v_cvt_pk_bf16_f32 v14, v14, v15
	v_mul_f32_e32 v15, v66, v32
	v_mul_f32_e32 v18, v68, v33
	v_cvt_pk_bf16_f32 v15, v15, v18
	v_add_co_u32_e64 v18, s[4:5], s63, v120
	v_mul_f32_e32 v16, v70, v16
	v_mul_f32_e32 v17, v72, v17
	v_addc_co_u32_e64 v19, s[4:5], 0, v121, s[4:5]
	v_cvt_pk_bf16_f32 v16, v16, v17
	v_mul_f32_e32 v8, v65, v8
	v_mul_f32_e32 v9, v67, v9
	v_cvt_pk_bf16_f32 v17, v8, v9
	global_store_dwordx4 v[18:19], v[10:13], off
	v_lshl_add_u64 v[8:9], v[120:121], 0, s[26:27]
	s_nop 0
	v_add_co_u32_e64 v12, s[4:5], s64, v120
	v_lshl_add_u64 v[10:11], v[120:121], 0, s[28:29]
	s_nop 0
	v_addc_co_u32_e64 v13, s[4:5], 0, v121, s[4:5]
	global_store_dwordx4 v[12:13], v[14:17], off
	global_load_dwordx4 v[12:15], v[82:83], off
	s_nop 0
	global_load_dwordx4 v[16:19], v[80:81], off
	ds_bpermute_b32 v34, v177, v4
	ds_bpermute_b32 v32, v177, v5
	ds_bpermute_b32 v33, v177, v6
	ds_bpermute_b32 v28, v177, v7
	global_load_dwordx4 v[20:23], v[76:77], off offset:16
	global_load_dwordx4 v[24:27], v[78:79], off offset:16
	s_waitcnt lgkmcnt(0)
	v_cndmask_b32_e64 v29, v28, -v28, vcc
	v_mov_b32_e32 v30, v7
	s_waitcnt vmcnt(3)
	v_mov_b32_e32 v31, v15
	s_waitcnt vmcnt(2)
	v_mov_b32_e32 v28, v19
	v_cndmask_b32_e64 v19, v33, -v33, vcc
	v_mov_b32_e32 v7, v14
	v_cndmask_b32_e64 v15, v32, -v32, vcc
	v_mov_b32_e32 v32, v5
	v_mov_b32_e32 v33, v13
	v_mov_b32_e32 v14, v17
	v_cndmask_b32_e64 v17, v34, -v34, vcc
	v_mov_b32_e32 v5, v12
	ds_bpermute_b32 v13, v177, v0
	v_mov_b32_e32 v12, v0
	ds_bpermute_b32 v34, v177, v1
	ds_bpermute_b32 v35, v177, v2
	v_mov_b32_e32 v0, v2
	ds_bpermute_b32 v2, v177, v3
	v_pk_mul_f32 v[28:29], v[30:31], v[28:29]
	v_pk_mul_f32 v[6:7], v[6:7], v[18:19]
	v_pk_mul_f32 v[14:15], v[32:33], v[14:15]
	v_pk_mul_f32 v[4:5], v[4:5], v[16:17]
	v_add_f32_e32 v18, v28, v29
	v_add_f32_e32 v19, v6, v7
	v_add_f32_e32 v28, v14, v15
	v_add_f32_e32 v29, v4, v5
	s_waitcnt lgkmcnt(3)
	v_cndmask_b32_e64 v5, v13, -v13, vcc
	s_waitcnt lgkmcnt(2)
	v_cndmask_b32_e64 v7, v34, -v34, vcc
	s_waitcnt lgkmcnt(1)
	v_cndmask_b32_e64 v15, v35, -v35, vcc
	s_waitcnt lgkmcnt(0)
	v_cndmask_b32_e64 v17, v2, -v2, vcc
	s_waitcnt vmcnt(1)
	v_mov_b32_e32 v13, v20
	s_waitcnt vmcnt(0)
	v_mov_b32_e32 v4, v24
	v_mov_b32_e32 v20, v1
	v_mov_b32_e32 v6, v25
	v_mov_b32_e32 v1, v22
	v_mov_b32_e32 v14, v26
	v_mov_b32_e32 v22, v3
	v_mov_b32_e32 v16, v27
	v_pk_mul_f32 v[2:3], v[12:13], v[4:5]
	v_pk_mul_f32 v[4:5], v[20:21], v[6:7]
	v_pk_mul_f32 v[0:1], v[0:1], v[14:15]
	v_pk_mul_f32 v[6:7], v[22:23], v[16:17]
	v_add_f32_e32 v12, v2, v3
	v_add_f32_e32 v13, v4, v5
	v_add_f32_e32 v14, v0, v1
	v_add_f32_e32 v7, v6, v7
	v_mul_f32_e32 v0, v63, v29
	v_mul_f32_e32 v1, v75, v28
	v_cvt_pk_bf16_f32 v0, v0, v1
	v_mul_f32_e32 v1, v84, v19
	v_mul_f32_e32 v2, v86, v18
	v_cvt_pk_bf16_f32 v1, v1, v2
	v_mul_f32_e32 v2, v85, v12
	v_mul_f32_e32 v3, v88, v13
	v_cvt_pk_bf16_f32 v2, v2, v3
	v_mul_f32_e32 v3, v87, v14
	v_mul_f32_e32 v4, v71, v7
	v_cvt_pk_bf16_f32 v3, v3, v4
	v_mul_f32_e32 v4, v64, v29
	v_mul_f32_e32 v5, v60, v28
	v_cvt_pk_bf16_f32 v4, v4, v5
	v_mul_f32_e32 v5, v66, v19
	v_mul_f32_e32 v6, v68, v18
	v_cvt_pk_bf16_f32 v5, v5, v6
	v_mul_f32_e32 v6, v70, v12
	v_mul_f32_e32 v12, v72, v13
	v_mul_f32_e32 v7, v67, v7
	v_cvt_pk_bf16_f32 v6, v6, v12
	v_mul_f32_e32 v12, v65, v14
	v_cvt_pk_bf16_f32 v7, v12, v7
	global_store_dwordx4 v[8:9], v[0:3], off offset:256
	global_store_dwordx4 v[10:11], v[4:7], off offset:256
	s_and_b64 vcc, exec, s[2:3]
	s_mov_b32 s33, s30
	s_mov_b64 s[4:5], s[38:39]
	s_mov_b64 s[0:1], s[36:37]
	s_cbranch_vccz .LBB0_606
	s_waitcnt vmcnt(0)
	s_cmpk_gt_u32 s42, 0xff
	s_cbranch_scc1 .LBB0_617
	s_barrier

; #define PG8_STAGE(bufoff, gbase, voff) do { _Pragma("unroll") for (int _i = 0; _i < 2; ++_i) \
;         __builtin_amdgcn_global_load_lds((const unsigned*)((const char*)(gbase) + (voff)[_i]), (LAS unsigned*)(lds + (bufoff) + ldsw + _i * 8192), 16, 0, 0); } while (0)
; #define PG8_LDA(dst, b, h) do { _Pragma("unroll") for (int m = 0; m < 4; ++m) _Pragma("unroll") for (int k = 0; k < 2; ++k) dst[m][k] = *(const LAS bf16x8*)(lds + PG8_SA(b, h) + aoff + m * 2048 + k * 1024); } while (0)
; #define PG8_LDB(dst, b, h) do { _Pragma("unroll") for (int n = 0; n < 2; ++n) _Pragma("unroll") for (int k = 0; k < 2; ++k) dst[n][k] = *(const LAS bf16x8*)(lds + PG8_SB(b, h) + boff + n * 2048 + k * 1024); } while (0)
; #define PG8_MMA(ai, bj, At, Bt) do { __builtin_amdgcn_s_setprio(1); _Pragma("unroll") for (int m = 0; m < 4; ++m) _Pragma("unroll") for (int n = 0; n < 2; ++n) _Pragma("unroll") for (int k = 0; k < 2; ++k) \
;         acc[ai][bj][m][n] = __builtin_amdgcn_mfma_f32_16x16x32_bf16(Bt[n][k], At[m][k], acc[ai][bj][m][n], 0, 0, 0); __builtin_amdgcn_s_setprio(0); } while (0)
; #define PG8_WAIT_L(n) asm volatile("s_waitcnt lgkmcnt(" #n ")" ::: "memory")
; template <class Epi, class Sched>
; __device__ __forceinline__ void gemm_phase(LAS unsigned char* lds, const Gemm g, const Sched& S, const Epi& E) {
;     ...
;         const bool has_next = S.next(ui + 1, nxt);
;         const char* nA = has_next ? (const char*)g.A + (size_t)nxt.pm * tstep : cA; const char* nB = has_next ? (const char*)g.Bt + (size_t)nxt.pn * tstep : cB;
;         for (int t = 0; t < nt; t += 2) {
;             const bool last = (t == nt - 2);
;             const char* a1 = cA + (size_t)(t + 1) * kstep;
;             const char* a2 = last ? nA : cA + (size_t)(t + 2) * kstep; const char* b2 = last ? nB : cB + (size_t)(t + 2) * kstep;
;             const char* a3 = a2 + kstep; const char* b3 = b2 + kstep;
;             PG8_LDB(B0, 0, 0); PG8_SCHED; PG8_LDA(At, 0, 0); PG8_STAGE(PG8_SA(1, 1), a1 + hstep, voffA);
;             PG8_WAIT_L(8); PG8_BAR; PG8_WAIT_L(0); PG8_MMA(0, 0, At, B0); PG8_BAR; PG8_SCHED;
;             PG8_LDB(B1, 0, 1); PG8_STAGE(PG8_SB(0, 0), b2, voffB);
;             PG8_BAR; PG8_WAIT_L(0); PG8_MMA(0, 1, At, B1); PG8_BAR;
;             PG8_LDA(At, 0, 1); PG8_STAGE(PG8_SA(0, 0), a2, voffA);
;             PG8_BAR; PG8_WAIT_L(0); PG8_MMA(1, 0, At, B0); PG8_BAR; PG8_SCHED;
.LBB0_632:
	s_ashr_i32 s23, s22, 31
	v_cmp_lt_i64_e32 vcc, s[24:25], v[140:141]
	s_lshl_b64 s[24:25], s[22:23], 19
	s_add_u32 s24, s38, s24
	s_addc_u32 s25, s39, s25
	s_and_b64 s[26:27], vcc, exec
	s_cselect_b32 s23, s25, s31
	s_cselect_b32 s61, s24, s30
	s_ashr_i32 s21, s20, 31
	s_lshl_b64 s[26:27], s[20:21], 19
	s_add_u32 s26, s96, s26
	s_addc_u32 s27, s97, s27
	s_and_b64 s[36:37], vcc, exec
	s_cselect_b32 s21, s27, s35
	s_cselect_b32 s62, s26, s34
	s_add_u32 s30, s30, 0x40080
	s_addc_u32 s31, s31, 0
	s_add_u32 s63, s34, 0x100
	s_addc_u32 s64, s35, 0
	s_mov_b32 s65, -2
	s_waitcnt lgkmcnt(0)
	ds_read_b128 v[150:153], v147
	ds_read_b128 v[154:157], v147 offset:1024
	ds_read_b128 v[158:161], v147 offset:2048
	ds_read_b128 v[162:165], v147 offset:3072
	s_add_u32 s34, s30, 0xfffc0080
	s_addc_u32 s35, s31, -1
	s_cmp_eq_u32 s65, 12
	s_cselect_b32 s37, s23, s35
	s_cselect_b32 s36, s61, s34
	s_cselect_b32 s35, s21, s64
	s_cselect_b32 s34, s62, s63
	s_add_i32 m0, s29, 0xc000
	ds_read_b128 v[166:169], v148
	ds_read_b128 v[170:173], v148 offset:1024
	ds_read_b128 v[174:177], v148 offset:2048
	ds_read_b128 v[178:181], v148 offset:3072
	ds_read_b128 v[182:185], v148 offset:4096
	ds_read_b128 v[186:189], v148 offset:5120
	ds_read_b128 v[190:193], v148 offset:6144
	ds_read_b128 v[194:197], v148 offset:7168
	global_load_lds_dwordx4 v136, s[30:31]
	s_add_i32 m0, s29, 0xe000
	s_nop 0
	global_load_lds_dwordx4 v138, s[30:31]
	s_waitcnt lgkmcnt(8)
	s_waitcnt vmcnt(8)
	s_setprio 1
	s_barrier
	s_waitcnt lgkmcnt(0)
	v_mfma_f32_16x16x32_bf16 v[124:127], v[150:153], v[166:169], 0
	v_mfma_f32_16x16x32_bf16 v[120:123], v[158:161], v[166:169], 0
	v_mfma_f32_16x16x32_bf16 v[116:119], v[150:153], v[174:177], 0
	v_mfma_f32_16x16x32_bf16 v[108:111], v[158:161], v[174:177], 0
	v_mfma_f32_16x16x32_bf16 v[100:103], v[150:153], v[182:185], 0
	v_mfma_f32_16x16x32_bf16 v[92:95], v[158:161], v[182:185], 0
	v_mfma_f32_16x16x32_bf16 v[84:87], v[150:153], v[190:193], 0
	v_mfma_f32_16x16x32_bf16 v[76:79], v[158:161], v[190:193], 0
	v_mfma_f32_16x16x32_bf16 v[124:127], v[154:157], v[170:173], v[124:127]
	v_mfma_f32_16x16x32_bf16 v[120:123], v[162:165], v[170:173], v[120:123]
	v_mfma_f32_16x16x32_bf16 v[116:119], v[154:157], v[178:181], v[116:119]
	v_mfma_f32_16x16x32_bf16 v[108:111], v[162:165], v[178:181], v[108:111]
	v_mfma_f32_16x16x32_bf16 v[100:103], v[154:157], v[186:189], v[100:103]
	v_mfma_f32_16x16x32_bf16 v[92:95], v[162:165], v[186:189], v[92:95]
	v_mfma_f32_16x16x32_bf16 v[84:87], v[154:157], v[194:197], v[84:87]
	v_mfma_f32_16x16x32_bf16 v[76:79], v[162:165], v[194:197], v[76:79]
	s_barrier
	s_setprio 0
	s_add_i32 s66, s54, s43
	s_mov_b32 m0, s66
	ds_read_b128 v[202:205], v149
	ds_read_b128 v[206:209], v149 offset:1024
	ds_read_b128 v[210:213], v149 offset:2048
	ds_read_b128 v[214:217], v149 offset:3072
	global_load_lds_dwordx4 v130, s[34:35]
	s_add_i32 m0, s66, 0x2000
	s_nop 0
	global_load_lds_dwordx4 v134, s[34:35]
	s_waitcnt vmcnt(8)
	s_setprio 1
	s_barrier
	s_waitcnt lgkmcnt(0)
	v_mfma_f32_16x16x32_bf16 v[112:115], v[202:205], v[166:169], 0
	v_mfma_f32_16x16x32_bf16 v[104:107], v[210:213], v[166:169], 0
	v_mfma_f32_16x16x32_bf16 v[96:99], v[202:205], v[174:177], 0
	v_mfma_f32_16x16x32_bf16 v[88:91], v[210:213], v[174:177], 0
	v_mfma_f32_16x16x32_bf16 v[80:83], v[202:205], v[182:185], 0
	v_mfma_f32_16x16x32_bf16 v[72:75], v[210:213], v[182:185], 0
	v_mfma_f32_16x16x32_bf16 v[68:71], v[202:205], v[190:193], 0
	v_mfma_f32_16x16x32_bf16 v[64:67], v[210:213], v[190:193], 0
	v_mfma_f32_16x16x32_bf16 v[112:115], v[206:209], v[170:173], v[112:115]
	v_mfma_f32_16x16x32_bf16 v[104:107], v[214:217], v[170:173], v[104:107]
	v_mfma_f32_16x16x32_bf16 v[96:99], v[206:209], v[178:181], v[96:99]
	v_mfma_f32_16x16x32_bf16 v[88:91], v[214:217], v[178:181], v[88:91]
	v_mfma_f32_16x16x32_bf16 v[80:83], v[206:209], v[186:189], v[80:83]
	v_mfma_f32_16x16x32_bf16 v[72:75], v[214:217], v[186:189], v[72:75]
	v_mfma_f32_16x16x32_bf16 v[68:71], v[206:209], v[194:197], v[68:71]
	v_mfma_f32_16x16x32_bf16 v[64:67], v[214:217], v[194:197], v[64:67]
	s_barrier
	s_setprio 0
	s_mov_b32 m0, s29
	v_lshl_add_u64 v[220:221], s[36:37], 0, v[128:129]
	ds_read_b128 v[166:169], v148 offset:16384
	ds_read_b128 v[170:173], v148 offset:17408
	ds_read_b128 v[174:177], v148 offset:18432
	ds_read_b128 v[178:181], v148 offset:19456
	ds_read_b128 v[182:185], v148 offset:20480
	ds_read_b128 v[186:189], v148 offset:21504
	ds_read_b128 v[190:193], v148 offset:22528
	ds_read_b128 v[194:197], v148 offset:23552
	global_load_lds_dwordx4 v128, s[36:37]
	v_lshl_add_u64 v[222:223], s[36:37], 0, v[132:133]
	s_mov_b32 m0, s44
	s_nop 0
	global_load_lds_dwordx4 v132, s[36:37]
	s_setprio 1
	s_barrier
	s_waitcnt lgkmcnt(0)
	v_mfma_f32_16x16x32_bf16 v[60:63], v[150:153], v[166:169], 0
	v_mfma_f32_16x16x32_bf16 v[56:59], v[158:161], v[166:169], 0
	v_mfma_f32_16x16x32_bf16 v[52:55], v[150:153], v[174:177], 0
	v_mfma_f32_16x16x32_bf16 v[44:47], v[158:161], v[174:177], 0
	v_mfma_f32_16x16x32_bf16 v[36:39], v[150:153], v[182:185], 0
	v_mfma_f32_16x16x32_bf16 v[28:31], v[158:161], v[182:185], 0
	v_mfma_f32_16x16x32_bf16 v[20:23], v[150:153], v[190:193], 0
	v_mfma_f32_16x16x32_bf16 v[12:15], v[158:161], v[190:193], 0
	v_mfma_f32_16x16x32_bf16 v[60:63], v[154:157], v[170:173], v[60:63]
	v_mfma_f32_16x16x32_bf16 v[56:59], v[162:165], v[170:173], v[56:59]
	v_mfma_f32_16x16x32_bf16 v[52:55], v[154:157], v[178:181], v[52:55]
	v_mfma_f32_16x16x32_bf16 v[44:47], v[162:165], v[178:181], v[44:47]
	v_mfma_f32_16x16x32_bf16 v[36:39], v[154:157], v[186:189], v[36:39]
	v_mfma_f32_16x16x32_bf16 v[28:31], v[162:165], v[186:189], v[28:31]
	v_mfma_f32_16x16x32_bf16 v[20:23], v[154:157], v[194:197], v[20:23]
	v_mfma_f32_16x16x32_bf16 v[12:15], v[162:165], v[194:197], v[12:15]
	s_barrier
; #define PG8_STAGE(bufoff, gbase, voff) do { _Pragma("unroll") for (int _i = 0; _i < 2; ++_i) \
;         __builtin_amdgcn_global_load_lds((const unsigned*)((const char*)(gbase) + (voff)[_i]), (LAS unsigned*)(lds + (bufoff) + ldsw + _i * 8192), 16, 0, 0); } while (0)
; #define PG8_LDA(dst, b, h) do { _Pragma("unroll") for (int m = 0; m < 4; ++m) _Pragma("unroll") for (int k = 0; k < 2; ++k) dst[m][k] = *(const LAS bf16x8*)(lds + PG8_SA(b, h) + aoff + m * 2048 + k * 1024); } while (0)
; #define PG8_LDB(dst, b, h) do { _Pragma("unroll") for (int n = 0; n < 2; ++n) _Pragma("unroll") for (int k = 0; k < 2; ++k) dst[n][k] = *(const LAS bf16x8*)(lds + PG8_SB(b, h) + boff + n * 2048 + k * 1024); } while (0)
; #define PG8_MMA(ai, bj, At, Bt) do { __builtin_amdgcn_s_setprio(1); _Pragma("unroll") for (int m = 0; m < 4; ++m) _Pragma("unroll") for (int n = 0; n < 2; ++n) _Pragma("unroll") for (int k = 0; k < 2; ++k) \
;         acc[ai][bj][m][n] = __builtin_amdgcn_mfma_f32_16x16x32_bf16(Bt[n][k], At[m][k], acc[ai][bj][m][n], 0, 0, 0); __builtin_amdgcn_s_setprio(0); } while (0)
; #define PG8_WAIT_V(n) asm volatile("s_waitcnt vmcnt(" #n ")" ::: "memory")
; #define PG8_WAIT_L(n) asm volatile("s_waitcnt lgkmcnt(" #n ")" ::: "memory")
; #define PG8_BAR __builtin_amdgcn_s_barrier()
; #define PG8_SCHED __builtin_amdgcn_sched_barrier(0)
; template <class Epi, class Sched>
; __device__ __forceinline__ void gemm_phase(LAS unsigned char* lds, const Gemm g, const Sched& S, const Epi& E) {
;     ...
;             PG8_STAGE(PG8_SB(0, 1), b2 + hstep, voffB);
;             PG8_WAIT_V(6); PG8_BAR; PG8_MMA(1, 1, At, B1); PG8_BAR;
;             PG8_LDB(B0, 1, 0); PG8_SCHED; PG8_LDA(At, 1, 0); PG8_STAGE(PG8_SA(0, 1), a2 + hstep, voffA);
;             PG8_WAIT_L(8); PG8_BAR; PG8_WAIT_L(0); PG8_MMA(0, 0, At, B0); PG8_BAR; PG8_SCHED;
;             PG8_LDB(B1, 1, 1); PG8_STAGE(PG8_SB(1, 0), b3, voffB);
;             PG8_BAR; PG8_WAIT_L(0); PG8_MMA(0, 1, At, B1); PG8_BAR;
;             PG8_LDA(At, 1, 1); PG8_STAGE(PG8_SA(1, 0), a3, voffA);
	s_setprio 0
	s_add_u32 s66, s34, 0x40000
	s_addc_u32 s67, s35, 0
	s_add_i32 s68, s55, s43
	s_mov_b32 m0, s68
	s_nop 0
	global_load_lds_dwordx4 v130, s[66:67]
	s_add_i32 m0, s68, 0x2000
	s_nop 0
	global_load_lds_dwordx4 v134, s[66:67]
	s_add_u32 s36, s36, 0x40000
	s_addc_u32 s37, s37, 0
	s_mov_b32 m0, s45
	s_nop 0
	global_load_lds_dwordx4 v128, s[36:37]
	s_mov_b32 m0, s46
	s_nop 0
	global_load_lds_dwordx4 v132, s[36:37]
	s_waitcnt vmcnt(10)
	s_setprio 1
	s_barrier
	v_mfma_f32_16x16x32_bf16 v[48:51], v[202:205], v[166:169], 0
	v_mfma_f32_16x16x32_bf16 v[40:43], v[210:213], v[166:169], 0
	v_mfma_f32_16x16x32_bf16 v[32:35], v[202:205], v[174:177], 0
	v_mfma_f32_16x16x32_bf16 v[24:27], v[210:213], v[174:177], 0
	v_mfma_f32_16x16x32_bf16 v[16:19], v[202:205], v[182:185], 0
	v_mfma_f32_16x16x32_bf16 v[8:11], v[210:213], v[182:185], 0
	v_mfma_f32_16x16x32_bf16 v[4:7], v[202:205], v[190:193], 0
	v_mfma_f32_16x16x32_bf16 v[0:3], v[210:213], v[190:193], 0
	v_mfma_f32_16x16x32_bf16 v[48:51], v[206:209], v[170:173], v[48:51]
	v_mfma_f32_16x16x32_bf16 v[40:43], v[214:217], v[170:173], v[40:43]
	v_mfma_f32_16x16x32_bf16 v[32:35], v[206:209], v[178:181], v[32:35]
	v_mfma_f32_16x16x32_bf16 v[24:27], v[214:217], v[178:181], v[24:27]
	v_mfma_f32_16x16x32_bf16 v[16:19], v[206:209], v[186:189], v[16:19]
	v_mfma_f32_16x16x32_bf16 v[8:11], v[214:217], v[186:189], v[8:11]
	v_mfma_f32_16x16x32_bf16 v[4:7], v[206:209], v[194:197], v[4:7]
	v_mfma_f32_16x16x32_bf16 v[0:3], v[214:217], v[194:197], v[0:3]
	s_barrier
	s_setprio 0
	s_add_i32 s66, 0, 0x18000
	v_add_u32_e32 v162, s66, v146
	ds_read_b128 v[150:153], v162
	ds_read_b128 v[154:157], v162 offset:1024
	ds_read_b128 v[158:161], v162 offset:2048
	ds_read_b128 v[162:165], v162 offset:3072
	ds_read_b128 v[166:169], v148 offset:32768
	ds_read_b128 v[170:173], v148 offset:33792
	ds_read_b128 v[174:177], v148 offset:34816
	ds_read_b128 v[178:181], v148 offset:35840
	ds_read_b128 v[182:185], v148 offset:36864
	ds_read_b128 v[186:189], v148 offset:37888
	ds_read_b128 v[190:193], v148 offset:38912
	ds_read_b128 v[194:197], v148 offset:39936
	s_waitcnt lgkmcnt(8)
	s_waitcnt vmcnt(8)
	s_setprio 1
	s_barrier
	s_waitcnt lgkmcnt(0)
	v_mfma_f32_16x16x32_bf16 v[124:127], v[150:153], v[166:169], v[124:127]
	v_mfma_f32_16x16x32_bf16 v[120:123], v[158:161], v[166:169], v[120:123]
	v_mfma_f32_16x16x32_bf16 v[116:119], v[150:153], v[174:177], v[116:119]
	v_mfma_f32_16x16x32_bf16 v[108:111], v[158:161], v[174:177], v[108:111]
	v_mfma_f32_16x16x32_bf16 v[100:103], v[150:153], v[182:185], v[100:103]
	v_mfma_f32_16x16x32_bf16 v[92:95], v[158:161], v[182:185], v[92:95]
	v_mfma_f32_16x16x32_bf16 v[84:87], v[150:153], v[190:193], v[84:87]
	v_mfma_f32_16x16x32_bf16 v[76:79], v[158:161], v[190:193], v[76:79]
	v_mfma_f32_16x16x32_bf16 v[124:127], v[154:157], v[170:173], v[124:127]
	v_mfma_f32_16x16x32_bf16 v[120:123], v[162:165], v[170:173], v[120:123]
	v_mfma_f32_16x16x32_bf16 v[116:119], v[154:157], v[178:181], v[116:119]
	v_mfma_f32_16x16x32_bf16 v[108:111], v[162:165], v[178:181], v[108:111]
	v_mfma_f32_16x16x32_bf16 v[100:103], v[154:157], v[186:189], v[100:103]
	v_mfma_f32_16x16x32_bf16 v[92:95], v[162:165], v[186:189], v[92:95]
	v_mfma_f32_16x16x32_bf16 v[84:87], v[154:157], v[194:197], v[84:87]
	v_mfma_f32_16x16x32_bf16 v[76:79], v[162:165], v[194:197], v[76:79]
	s_barrier
	s_setprio 0
	s_add_i32 s36, 0, 0x1c000
	s_add_i32 s37, s66, s43
	v_add_u32_e32 v214, s36, v146
	s_add_u32 s4, s34, 0x80
	s_addc_u32 s5, s35, 0
	s_mov_b32 m0, s37
	ds_read_b128 v[202:205], v214
	ds_read_b128 v[206:209], v214 offset:1024
	ds_read_b128 v[210:213], v214 offset:2048
	ds_read_b128 v[214:217], v214 offset:3072
	global_load_lds_dwordx4 v130, s[4:5]
	s_add_i32 m0, s37, 0x2000
	s_nop 0
	global_load_lds_dwordx4 v134, s[4:5]
	s_waitcnt vmcnt(8)
	s_setprio 1
	s_barrier
	s_waitcnt lgkmcnt(0)
	v_mfma_f32_16x16x32_bf16 v[112:115], v[202:205], v[166:169], v[112:115]
	v_mfma_f32_16x16x32_bf16 v[104:107], v[210:213], v[166:169], v[104:107]
	v_mfma_f32_16x16x32_bf16 v[96:99], v[202:205], v[174:177], v[96:99]
	v_mfma_f32_16x16x32_bf16 v[88:91], v[210:213], v[174:177], v[88:91]
	v_mfma_f32_16x16x32_bf16 v[80:83], v[202:205], v[182:185], v[80:83]
	v_mfma_f32_16x16x32_bf16 v[72:75], v[210:213], v[182:185], v[72:75]
	v_mfma_f32_16x16x32_bf16 v[68:71], v[202:205], v[190:193], v[68:71]
	v_mfma_f32_16x16x32_bf16 v[64:67], v[210:213], v[190:193], v[64:67]
	v_mfma_f32_16x16x32_bf16 v[112:115], v[206:209], v[170:173], v[112:115]
	v_mfma_f32_16x16x32_bf16 v[104:107], v[214:217], v[170:173], v[104:107]
	v_mfma_f32_16x16x32_bf16 v[96:99], v[206:209], v[178:181], v[96:99]
	v_mfma_f32_16x16x32_bf16 v[88:91], v[214:217], v[178:181], v[88:91]
	v_mfma_f32_16x16x32_bf16 v[80:83], v[206:209], v[186:189], v[80:83]
	v_mfma_f32_16x16x32_bf16 v[72:75], v[214:217], v[186:189], v[72:75]
	v_mfma_f32_16x16x32_bf16 v[68:71], v[206:209], v[194:197], v[68:71]
	v_mfma_f32_16x16x32_bf16 v[64:67], v[214:217], v[194:197], v[64:67]
	s_barrier
	s_setprio 0
	s_mov_b32 m0, s51
	s_mov_b64 s[4:5], 0x80
	v_lshl_add_u64 v[198:199], v[220:221], 0, s[4:5]
	ds_read_b128 v[166:169], v148 offset:49152
	ds_read_b128 v[170:173], v148 offset:50176
	ds_read_b128 v[174:177], v148 offset:51200
	ds_read_b128 v[178:181], v148 offset:52224
	ds_read_b128 v[182:185], v148 offset:53248
	ds_read_b128 v[186:189], v148 offset:54272
	ds_read_b128 v[190:193], v148 offset:55296
	ds_read_b128 v[194:197], v148 offset:56320
	global_load_lds_dwordx4 v[198:199], off
	v_lshl_add_u64 v[198:199], v[222:223], 0, s[4:5]
	s_mov_b32 m0, s52
	s_nop 0
	global_load_lds_dwordx4 v[198:199], off
	s_setprio 1
	s_barrier
; #define PG8_STAGE(bufoff, gbase, voff) do { _Pragma("unroll") for (int _i = 0; _i < 2; ++_i) \
;         __builtin_amdgcn_global_load_lds((const unsigned*)((const char*)(gbase) + (voff)[_i]), (LAS unsigned*)(lds + (bufoff) + ldsw + _i * 8192), 16, 0, 0); } while (0)
; #define PG8_LDA(dst, b, h) do { _Pragma("unroll") for (int m = 0; m < 4; ++m) _Pragma("unroll") for (int k = 0; k < 2; ++k) dst[m][k] = *(const LAS bf16x8*)(lds + PG8_SA(b, h) + aoff + m * 2048 + k * 1024); } while (0)
; #define PG8_LDB(dst, b, h) do { _Pragma("unroll") for (int n = 0; n < 2; ++n) _Pragma("unroll") for (int k = 0; k < 2; ++k) dst[n][k] = *(const LAS bf16x8*)(lds + PG8_SB(b, h) + boff + n * 2048 + k * 1024); } while (0)
; #define PG8_MMA(ai, bj, At, Bt) do { __builtin_amdgcn_s_setprio(1); _Pragma("unroll") for (int m = 0; m < 4; ++m) _Pragma("unroll") for (int n = 0; n < 2; ++n) _Pragma("unroll") for (int k = 0; k < 2; ++k) \
;         acc[ai][bj][m][n] = __builtin_amdgcn_mfma_f32_16x16x32_bf16(Bt[n][k], At[m][k], acc[ai][bj][m][n], 0, 0, 0); __builtin_amdgcn_s_setprio(0); } while (0)
; #define PG8_WAIT_V(n) asm volatile("s_waitcnt vmcnt(" #n ")" ::: "memory")
; #define PG8_WAIT_L(n) asm volatile("s_waitcnt lgkmcnt(" #n ")" ::: "memory")
; #define PG8_BAR __builtin_amdgcn_s_barrier()
; #define PG8_SCHED __builtin_amdgcn_sched_barrier(0)
; template <class Epi, class Sched>
; __device__ __forceinline__ void gemm_phase(LAS unsigned char* lds, const Gemm g, const Sched& S, const Epi& E) {
;     ...
;             PG8_LDB(B0, 0, 0); PG8_SCHED; PG8_LDA(At, 0, 0); PG8_STAGE(PG8_SA(1, 1), a1 + hstep, voffA);
;             PG8_WAIT_L(8); PG8_BAR; PG8_WAIT_L(0); PG8_MMA(0, 0, At, B0); PG8_BAR; PG8_SCHED;
;             PG8_LDB(B1, 0, 1); PG8_STAGE(PG8_SB(0, 0), b2, voffB);
;             PG8_BAR; PG8_WAIT_L(0); PG8_MMA(0, 1, At, B1); PG8_BAR;
;             PG8_LDA(At, 0, 1); PG8_STAGE(PG8_SA(0, 0), a2, voffA);
;             PG8_BAR; PG8_WAIT_L(0); PG8_MMA(1, 0, At, B0); PG8_BAR; PG8_SCHED;
;     ...
;             PG8_BAR; PG8_WAIT_L(0); PG8_MMA(1, 0, At, B0); PG8_BAR; PG8_SCHED;
;             PG8_STAGE(PG8_SB(1, 1), b3 + hstep, voffB);
;             PG8_WAIT_V(6); PG8_BAR; PG8_MMA(1, 1, At, B1); PG8_BAR;
	s_waitcnt lgkmcnt(0)
	v_mfma_f32_16x16x32_bf16 v[60:63], v[150:153], v[166:169], v[60:63]
	v_mfma_f32_16x16x32_bf16 v[56:59], v[158:161], v[166:169], v[56:59]
	v_mfma_f32_16x16x32_bf16 v[52:55], v[150:153], v[174:177], v[52:55]
	v_mfma_f32_16x16x32_bf16 v[44:47], v[158:161], v[174:177], v[44:47]
	v_mfma_f32_16x16x32_bf16 v[36:39], v[150:153], v[182:185], v[36:39]
	v_mfma_f32_16x16x32_bf16 v[28:31], v[158:161], v[182:185], v[28:31]
	v_mfma_f32_16x16x32_bf16 v[20:23], v[150:153], v[190:193], v[20:23]
	v_mfma_f32_16x16x32_bf16 v[12:15], v[158:161], v[190:193], v[12:15]
	v_mfma_f32_16x16x32_bf16 v[60:63], v[154:157], v[170:173], v[60:63]
	v_mfma_f32_16x16x32_bf16 v[56:59], v[162:165], v[170:173], v[56:59]
	v_mfma_f32_16x16x32_bf16 v[52:55], v[154:157], v[178:181], v[52:55]
	v_mfma_f32_16x16x32_bf16 v[44:47], v[162:165], v[178:181], v[44:47]
	v_mfma_f32_16x16x32_bf16 v[36:39], v[154:157], v[186:189], v[36:39]
	v_mfma_f32_16x16x32_bf16 v[28:31], v[162:165], v[186:189], v[28:31]
	v_mfma_f32_16x16x32_bf16 v[20:23], v[154:157], v[194:197], v[20:23]
	v_mfma_f32_16x16x32_bf16 v[12:15], v[162:165], v[194:197], v[12:15]
	s_barrier
	s_setprio 0
	s_add_u32 s34, s34, 0x40080
	s_addc_u32 s35, s35, 0
	s_add_i32 s36, s36, s43
	s_mov_b32 m0, s36
	s_nop 0
	global_load_lds_dwordx4 v130, s[34:35]
	s_add_i32 m0, s36, 0x2000
	s_nop 0
	global_load_lds_dwordx4 v134, s[34:35]
	s_waitcnt vmcnt(8)
	s_setprio 1
	s_barrier
	v_mfma_f32_16x16x32_bf16 v[48:51], v[202:205], v[166:169], v[48:51]
	v_mfma_f32_16x16x32_bf16 v[40:43], v[210:213], v[166:169], v[40:43]
	v_mfma_f32_16x16x32_bf16 v[32:35], v[202:205], v[174:177], v[32:35]
	v_mfma_f32_16x16x32_bf16 v[24:27], v[210:213], v[174:177], v[24:27]
	v_mfma_f32_16x16x32_bf16 v[16:19], v[202:205], v[182:185], v[16:19]
	v_mfma_f32_16x16x32_bf16 v[8:11], v[210:213], v[182:185], v[8:11]
	v_mfma_f32_16x16x32_bf16 v[4:7], v[202:205], v[190:193], v[4:7]
	v_mfma_f32_16x16x32_bf16 v[0:3], v[210:213], v[190:193], v[0:3]
	v_mfma_f32_16x16x32_bf16 v[48:51], v[206:209], v[170:173], v[48:51]
	v_mfma_f32_16x16x32_bf16 v[40:43], v[214:217], v[170:173], v[40:43]
	v_mfma_f32_16x16x32_bf16 v[32:35], v[206:209], v[178:181], v[32:35]
	v_mfma_f32_16x16x32_bf16 v[24:27], v[214:217], v[178:181], v[24:27]
	v_mfma_f32_16x16x32_bf16 v[16:19], v[206:209], v[186:189], v[16:19]
	v_mfma_f32_16x16x32_bf16 v[8:11], v[214:217], v[186:189], v[8:11]
	v_mfma_f32_16x16x32_bf16 v[4:7], v[206:209], v[194:197], v[4:7]
	v_mfma_f32_16x16x32_bf16 v[0:3], v[214:217], v[194:197], v[0:3]
	s_barrier
	s_setprio 0
	s_add_i32 s65, s65, 2
	s_add_u32 s30, s30, 0x100
	s_addc_u32 s31, s31, 0
	s_add_u32 s63, s63, 0x100
	s_addc_u32 s64, s64, 0
	s_cmp_gt_u32 s65, 13
.LBB0_633:
	ds_read_b128 v[150:153], v147
	ds_read_b128 v[154:157], v147 offset:1024
	ds_read_b128 v[158:161], v147 offset:2048
	ds_read_b128 v[162:165], v147 offset:3072
	s_add_u32 s34, s30, 0xfffc0080
	s_addc_u32 s35, s31, -1
	s_cmp_eq_u32 s65, 12
	s_cselect_b32 s37, s23, s35
	s_cselect_b32 s36, s61, s34
	s_cselect_b32 s35, s21, s64
	s_cselect_b32 s34, s62, s63
	s_add_i32 m0, s29, 0xc000
	ds_read_b128 v[166:169], v148
	ds_read_b128 v[170:173], v148 offset:1024
	ds_read_b128 v[174:177], v148 offset:2048
	ds_read_b128 v[178:181], v148 offset:3072
	ds_read_b128 v[182:185], v148 offset:4096
	ds_read_b128 v[186:189], v148 offset:5120
	ds_read_b128 v[190:193], v148 offset:6144
	ds_read_b128 v[194:197], v148 offset:7168
	global_load_lds_dwordx4 v136, s[30:31]
	s_add_i32 m0, s29, 0xe000
	s_nop 0
	global_load_lds_dwordx4 v138, s[30:31]
	s_waitcnt lgkmcnt(8)
	s_waitcnt vmcnt(8)
	s_setprio 1
	s_barrier
	s_waitcnt lgkmcnt(0)
	v_mfma_f32_16x16x32_bf16 v[124:127], v[150:153], v[166:169], v[124:127]
	v_mfma_f32_16x16x32_bf16 v[120:123], v[158:161], v[166:169], v[120:123]
	v_mfma_f32_16x16x32_bf16 v[116:119], v[150:153], v[174:177], v[116:119]
	v_mfma_f32_16x16x32_bf16 v[108:111], v[158:161], v[174:177], v[108:111]
	v_mfma_f32_16x16x32_bf16 v[100:103], v[150:153], v[182:185], v[100:103]
	v_mfma_f32_16x16x32_bf16 v[92:95], v[158:161], v[182:185], v[92:95]
	v_mfma_f32_16x16x32_bf16 v[84:87], v[150:153], v[190:193], v[84:87]
	v_mfma_f32_16x16x32_bf16 v[76:79], v[158:161], v[190:193], v[76:79]
	v_mfma_f32_16x16x32_bf16 v[124:127], v[154:157], v[170:173], v[124:127]
	v_mfma_f32_16x16x32_bf16 v[120:123], v[162:165], v[170:173], v[120:123]
	v_mfma_f32_16x16x32_bf16 v[116:119], v[154:157], v[178:181], v[116:119]
	v_mfma_f32_16x16x32_bf16 v[108:111], v[162:165], v[178:181], v[108:111]
	v_mfma_f32_16x16x32_bf16 v[100:103], v[154:157], v[186:189], v[100:103]
	v_mfma_f32_16x16x32_bf16 v[92:95], v[162:165], v[186:189], v[92:95]
	v_mfma_f32_16x16x32_bf16 v[84:87], v[154:157], v[194:197], v[84:87]
	v_mfma_f32_16x16x32_bf16 v[76:79], v[162:165], v[194:197], v[76:79]
	s_barrier
	s_setprio 0
	s_add_i32 s66, s54, s43
	s_mov_b32 m0, s66
	ds_read_b128 v[202:205], v149
	ds_read_b128 v[206:209], v149 offset:1024
	ds_read_b128 v[210:213], v149 offset:2048
	ds_read_b128 v[214:217], v149 offset:3072
	global_load_lds_dwordx4 v130, s[34:35]
	s_add_i32 m0, s66, 0x2000
	s_nop 0
	global_load_lds_dwordx4 v134, s[34:35]
	s_waitcnt vmcnt(8)
	s_setprio 1
	s_barrier
; #define PG8_STAGE(bufoff, gbase, voff) do { _Pragma("unroll") for (int _i = 0; _i < 2; ++_i) \
;         __builtin_amdgcn_global_load_lds((const unsigned*)((const char*)(gbase) + (voff)[_i]), (LAS unsigned*)(lds + (bufoff) + ldsw + _i * 8192), 16, 0, 0); } while (0)
; #define PG8_LDA(dst, b, h) do { _Pragma("unroll") for (int m = 0; m < 4; ++m) _Pragma("unroll") for (int k = 0; k < 2; ++k) dst[m][k] = *(const LAS bf16x8*)(lds + PG8_SA(b, h) + aoff + m * 2048 + k * 1024); } while (0)
; #define PG8_LDB(dst, b, h) do { _Pragma("unroll") for (int n = 0; n < 2; ++n) _Pragma("unroll") for (int k = 0; k < 2; ++k) dst[n][k] = *(const LAS bf16x8*)(lds + PG8_SB(b, h) + boff + n * 2048 + k * 1024); } while (0)
; #define PG8_MMA(ai, bj, At, Bt) do { __builtin_amdgcn_s_setprio(1); _Pragma("unroll") for (int m = 0; m < 4; ++m) _Pragma("unroll") for (int n = 0; n < 2; ++n) _Pragma("unroll") for (int k = 0; k < 2; ++k) \
;         acc[ai][bj][m][n] = __builtin_amdgcn_mfma_f32_16x16x32_bf16(Bt[n][k], At[m][k], acc[ai][bj][m][n], 0, 0, 0); __builtin_amdgcn_s_setprio(0); } while (0)
; #define PG8_WAIT_V(n) asm volatile("s_waitcnt vmcnt(" #n ")" ::: "memory")
; #define PG8_WAIT_L(n) asm volatile("s_waitcnt lgkmcnt(" #n ")" ::: "memory")
; #define PG8_BAR __builtin_amdgcn_s_barrier()
; #define PG8_SCHED __builtin_amdgcn_sched_barrier(0)
; template <class Epi, class Sched>
; __device__ __forceinline__ void gemm_phase(LAS unsigned char* lds, const Gemm g, const Sched& S, const Epi& E) {
;     ...
;             PG8_BAR; PG8_WAIT_L(0); PG8_MMA(0, 1, At, B1); PG8_BAR;
;             PG8_LDA(At, 0, 1); PG8_STAGE(PG8_SA(0, 0), a2, voffA);
;             PG8_BAR; PG8_WAIT_L(0); PG8_MMA(1, 0, At, B0); PG8_BAR; PG8_SCHED;
;             PG8_STAGE(PG8_SB(0, 1), b2 + hstep, voffB);
;             PG8_WAIT_V(6); PG8_BAR; PG8_MMA(1, 1, At, B1); PG8_BAR;
;             PG8_LDB(B0, 1, 0); PG8_SCHED; PG8_LDA(At, 1, 0); PG8_STAGE(PG8_SA(0, 1), a2 + hstep, voffA);
;             PG8_WAIT_L(8); PG8_BAR; PG8_WAIT_L(0); PG8_MMA(0, 0, At, B0); PG8_BAR; PG8_SCHED;
	s_waitcnt lgkmcnt(0)
	v_mfma_f32_16x16x32_bf16 v[112:115], v[202:205], v[166:169], v[112:115]
	v_mfma_f32_16x16x32_bf16 v[104:107], v[210:213], v[166:169], v[104:107]
	v_mfma_f32_16x16x32_bf16 v[96:99], v[202:205], v[174:177], v[96:99]
	v_mfma_f32_16x16x32_bf16 v[88:91], v[210:213], v[174:177], v[88:91]
	v_mfma_f32_16x16x32_bf16 v[80:83], v[202:205], v[182:185], v[80:83]
	v_mfma_f32_16x16x32_bf16 v[72:75], v[210:213], v[182:185], v[72:75]
	v_mfma_f32_16x16x32_bf16 v[68:71], v[202:205], v[190:193], v[68:71]
	v_mfma_f32_16x16x32_bf16 v[64:67], v[210:213], v[190:193], v[64:67]
	v_mfma_f32_16x16x32_bf16 v[112:115], v[206:209], v[170:173], v[112:115]
	v_mfma_f32_16x16x32_bf16 v[104:107], v[214:217], v[170:173], v[104:107]
	v_mfma_f32_16x16x32_bf16 v[96:99], v[206:209], v[178:181], v[96:99]
	v_mfma_f32_16x16x32_bf16 v[88:91], v[214:217], v[178:181], v[88:91]
	v_mfma_f32_16x16x32_bf16 v[80:83], v[206:209], v[186:189], v[80:83]
	v_mfma_f32_16x16x32_bf16 v[72:75], v[214:217], v[186:189], v[72:75]
	v_mfma_f32_16x16x32_bf16 v[68:71], v[206:209], v[194:197], v[68:71]
	v_mfma_f32_16x16x32_bf16 v[64:67], v[214:217], v[194:197], v[64:67]
	s_barrier
	s_setprio 0
	s_mov_b32 m0, s29
	v_lshl_add_u64 v[220:221], s[36:37], 0, v[128:129]
	ds_read_b128 v[166:169], v148 offset:16384
	ds_read_b128 v[170:173], v148 offset:17408
	ds_read_b128 v[174:177], v148 offset:18432
	ds_read_b128 v[178:181], v148 offset:19456
	ds_read_b128 v[182:185], v148 offset:20480
	ds_read_b128 v[186:189], v148 offset:21504
	ds_read_b128 v[190:193], v148 offset:22528
	ds_read_b128 v[194:197], v148 offset:23552
	global_load_lds_dwordx4 v128, s[36:37]
	v_lshl_add_u64 v[222:223], s[36:37], 0, v[132:133]
	s_mov_b32 m0, s44
	s_nop 0
	global_load_lds_dwordx4 v132, s[36:37]
	s_setprio 1
	s_barrier
	s_waitcnt lgkmcnt(0)
	v_mfma_f32_16x16x32_bf16 v[60:63], v[150:153], v[166:169], v[60:63]
	v_mfma_f32_16x16x32_bf16 v[56:59], v[158:161], v[166:169], v[56:59]
	v_mfma_f32_16x16x32_bf16 v[52:55], v[150:153], v[174:177], v[52:55]
	v_mfma_f32_16x16x32_bf16 v[44:47], v[158:161], v[174:177], v[44:47]
	v_mfma_f32_16x16x32_bf16 v[36:39], v[150:153], v[182:185], v[36:39]
	v_mfma_f32_16x16x32_bf16 v[28:31], v[158:161], v[182:185], v[28:31]
	v_mfma_f32_16x16x32_bf16 v[20:23], v[150:153], v[190:193], v[20:23]
	v_mfma_f32_16x16x32_bf16 v[12:15], v[158:161], v[190:193], v[12:15]
	v_mfma_f32_16x16x32_bf16 v[60:63], v[154:157], v[170:173], v[60:63]
	v_mfma_f32_16x16x32_bf16 v[56:59], v[162:165], v[170:173], v[56:59]
	v_mfma_f32_16x16x32_bf16 v[52:55], v[154:157], v[178:181], v[52:55]
	v_mfma_f32_16x16x32_bf16 v[44:47], v[162:165], v[178:181], v[44:47]
	v_mfma_f32_16x16x32_bf16 v[36:39], v[154:157], v[186:189], v[36:39]
	v_mfma_f32_16x16x32_bf16 v[28:31], v[162:165], v[186:189], v[28:31]
	v_mfma_f32_16x16x32_bf16 v[20:23], v[154:157], v[194:197], v[20:23]
	v_mfma_f32_16x16x32_bf16 v[12:15], v[162:165], v[194:197], v[12:15]
	s_barrier
	s_setprio 0
	s_add_u32 s66, s34, 0x40000
	s_addc_u32 s67, s35, 0
	s_add_i32 s68, s55, s43
	s_mov_b32 m0, s68
	s_nop 0
	global_load_lds_dwordx4 v130, s[66:67]
	s_add_i32 m0, s68, 0x2000
	s_nop 0
	global_load_lds_dwordx4 v134, s[66:67]
	s_add_u32 s36, s36, 0x40000
	s_addc_u32 s37, s37, 0
	s_mov_b32 m0, s45
	s_nop 0
	global_load_lds_dwordx4 v128, s[36:37]
	s_mov_b32 m0, s46
	s_nop 0
	global_load_lds_dwordx4 v132, s[36:37]
	s_waitcnt vmcnt(10)
	s_setprio 1
	s_barrier
	v_mfma_f32_16x16x32_bf16 v[48:51], v[202:205], v[166:169], v[48:51]
	v_mfma_f32_16x16x32_bf16 v[40:43], v[210:213], v[166:169], v[40:43]
	v_mfma_f32_16x16x32_bf16 v[32:35], v[202:205], v[174:177], v[32:35]
	v_mfma_f32_16x16x32_bf16 v[24:27], v[210:213], v[174:177], v[24:27]
	v_mfma_f32_16x16x32_bf16 v[16:19], v[202:205], v[182:185], v[16:19]
	v_mfma_f32_16x16x32_bf16 v[8:11], v[210:213], v[182:185], v[8:11]
	v_mfma_f32_16x16x32_bf16 v[4:7], v[202:205], v[190:193], v[4:7]
	v_mfma_f32_16x16x32_bf16 v[0:3], v[210:213], v[190:193], v[0:3]
	v_mfma_f32_16x16x32_bf16 v[48:51], v[206:209], v[170:173], v[48:51]
	v_mfma_f32_16x16x32_bf16 v[40:43], v[214:217], v[170:173], v[40:43]
	v_mfma_f32_16x16x32_bf16 v[32:35], v[206:209], v[178:181], v[32:35]
	v_mfma_f32_16x16x32_bf16 v[24:27], v[214:217], v[178:181], v[24:27]
	v_mfma_f32_16x16x32_bf16 v[16:19], v[206:209], v[186:189], v[16:19]
	v_mfma_f32_16x16x32_bf16 v[8:11], v[214:217], v[186:189], v[8:11]
	v_mfma_f32_16x16x32_bf16 v[4:7], v[206:209], v[194:197], v[4:7]
	v_mfma_f32_16x16x32_bf16 v[0:3], v[214:217], v[194:197], v[0:3]
	s_barrier
	s_setprio 0
	s_add_i32 s66, 0, 0x18000
	v_add_u32_e32 v162, s66, v146
	ds_read_b128 v[150:153], v162
	ds_read_b128 v[154:157], v162 offset:1024
	ds_read_b128 v[158:161], v162 offset:2048
	ds_read_b128 v[162:165], v162 offset:3072
	ds_read_b128 v[166:169], v148 offset:32768
	ds_read_b128 v[170:173], v148 offset:33792
	ds_read_b128 v[174:177], v148 offset:34816
	ds_read_b128 v[178:181], v148 offset:35840
	ds_read_b128 v[182:185], v148 offset:36864
	ds_read_b128 v[186:189], v148 offset:37888
	ds_read_b128 v[190:193], v148 offset:38912
	ds_read_b128 v[194:197], v148 offset:39936
	s_waitcnt lgkmcnt(8)
	s_waitcnt vmcnt(8)
	s_setprio 1
	s_barrier
; #define PG8_STAGE(bufoff, gbase, voff) do { _Pragma("unroll") for (int _i = 0; _i < 2; ++_i) \
;         __builtin_amdgcn_global_load_lds((const unsigned*)((const char*)(gbase) + (voff)[_i]), (LAS unsigned*)(lds + (bufoff) + ldsw + _i * 8192), 16, 0, 0); } while (0)
; #define PG8_LDA(dst, b, h) do { _Pragma("unroll") for (int m = 0; m < 4; ++m) _Pragma("unroll") for (int k = 0; k < 2; ++k) dst[m][k] = *(const LAS bf16x8*)(lds + PG8_SA(b, h) + aoff + m * 2048 + k * 1024); } while (0)
; #define PG8_LDB(dst, b, h) do { _Pragma("unroll") for (int n = 0; n < 2; ++n) _Pragma("unroll") for (int k = 0; k < 2; ++k) dst[n][k] = *(const LAS bf16x8*)(lds + PG8_SB(b, h) + boff + n * 2048 + k * 1024); } while (0)
; #define PG8_MMA(ai, bj, At, Bt) do { __builtin_amdgcn_s_setprio(1); _Pragma("unroll") for (int m = 0; m < 4; ++m) _Pragma("unroll") for (int n = 0; n < 2; ++n) _Pragma("unroll") for (int k = 0; k < 2; ++k) \
;         acc[ai][bj][m][n] = __builtin_amdgcn_mfma_f32_16x16x32_bf16(Bt[n][k], At[m][k], acc[ai][bj][m][n], 0, 0, 0); __builtin_amdgcn_s_setprio(0); } while (0)
; #define PG8_WAIT_V(n) asm volatile("s_waitcnt vmcnt(" #n ")" ::: "memory")
; #define PG8_WAIT_L(n) asm volatile("s_waitcnt lgkmcnt(" #n ")" ::: "memory")
; #define PG8_BAR __builtin_amdgcn_s_barrier()
; #define PG8_SCHED __builtin_amdgcn_sched_barrier(0)
; template <class Epi, class Sched>
; __device__ __forceinline__ void gemm_phase(LAS unsigned char* lds, const Gemm g, const Sched& S, const Epi& E) {
;     ...
;             PG8_WAIT_L(8); PG8_BAR; PG8_WAIT_L(0); PG8_MMA(0, 0, At, B0); PG8_BAR; PG8_SCHED;
;             PG8_LDB(B1, 1, 1); PG8_STAGE(PG8_SB(1, 0), b3, voffB);
;             PG8_BAR; PG8_WAIT_L(0); PG8_MMA(0, 1, At, B1); PG8_BAR;
;             PG8_LDA(At, 1, 1); PG8_STAGE(PG8_SA(1, 0), a3, voffA);
;             PG8_BAR; PG8_WAIT_L(0); PG8_MMA(1, 0, At, B0); PG8_BAR; PG8_SCHED;
;             PG8_STAGE(PG8_SB(1, 1), b3 + hstep, voffB);
;             PG8_WAIT_V(6); PG8_BAR; PG8_MMA(1, 1, At, B1); PG8_BAR;
	s_waitcnt lgkmcnt(0)
	v_mfma_f32_16x16x32_bf16 v[124:127], v[150:153], v[166:169], v[124:127]
	v_mfma_f32_16x16x32_bf16 v[120:123], v[158:161], v[166:169], v[120:123]
	v_mfma_f32_16x16x32_bf16 v[116:119], v[150:153], v[174:177], v[116:119]
	v_mfma_f32_16x16x32_bf16 v[108:111], v[158:161], v[174:177], v[108:111]
	v_mfma_f32_16x16x32_bf16 v[100:103], v[150:153], v[182:185], v[100:103]
	v_mfma_f32_16x16x32_bf16 v[92:95], v[158:161], v[182:185], v[92:95]
	v_mfma_f32_16x16x32_bf16 v[84:87], v[150:153], v[190:193], v[84:87]
	v_mfma_f32_16x16x32_bf16 v[76:79], v[158:161], v[190:193], v[76:79]
	v_mfma_f32_16x16x32_bf16 v[124:127], v[154:157], v[170:173], v[124:127]
	v_mfma_f32_16x16x32_bf16 v[120:123], v[162:165], v[170:173], v[120:123]
	v_mfma_f32_16x16x32_bf16 v[116:119], v[154:157], v[178:181], v[116:119]
	v_mfma_f32_16x16x32_bf16 v[108:111], v[162:165], v[178:181], v[108:111]
	v_mfma_f32_16x16x32_bf16 v[100:103], v[154:157], v[186:189], v[100:103]
	v_mfma_f32_16x16x32_bf16 v[92:95], v[162:165], v[186:189], v[92:95]
	v_mfma_f32_16x16x32_bf16 v[84:87], v[154:157], v[194:197], v[84:87]
	v_mfma_f32_16x16x32_bf16 v[76:79], v[162:165], v[194:197], v[76:79]
	s_barrier
	s_setprio 0
	s_add_i32 s36, 0, 0x1c000
	s_add_i32 s37, s66, s43
	v_add_u32_e32 v214, s36, v146
	s_add_u32 s4, s34, 0x80
	s_addc_u32 s5, s35, 0
	s_mov_b32 m0, s37
	ds_read_b128 v[202:205], v214
	ds_read_b128 v[206:209], v214 offset:1024
	ds_read_b128 v[210:213], v214 offset:2048
	ds_read_b128 v[214:217], v214 offset:3072
	global_load_lds_dwordx4 v130, s[4:5]
	s_add_i32 m0, s37, 0x2000
	s_nop 0
	global_load_lds_dwordx4 v134, s[4:5]
	s_waitcnt vmcnt(8)
	s_setprio 1
	s_barrier
	s_waitcnt lgkmcnt(0)
	v_mfma_f32_16x16x32_bf16 v[112:115], v[202:205], v[166:169], v[112:115]
	v_mfma_f32_16x16x32_bf16 v[104:107], v[210:213], v[166:169], v[104:107]
	v_mfma_f32_16x16x32_bf16 v[96:99], v[202:205], v[174:177], v[96:99]
	v_mfma_f32_16x16x32_bf16 v[88:91], v[210:213], v[174:177], v[88:91]
	v_mfma_f32_16x16x32_bf16 v[80:83], v[202:205], v[182:185], v[80:83]
	v_mfma_f32_16x16x32_bf16 v[72:75], v[210:213], v[182:185], v[72:75]
	v_mfma_f32_16x16x32_bf16 v[68:71], v[202:205], v[190:193], v[68:71]
	v_mfma_f32_16x16x32_bf16 v[64:67], v[210:213], v[190:193], v[64:67]
	v_mfma_f32_16x16x32_bf16 v[112:115], v[206:209], v[170:173], v[112:115]
	v_mfma_f32_16x16x32_bf16 v[104:107], v[214:217], v[170:173], v[104:107]
	v_mfma_f32_16x16x32_bf16 v[96:99], v[206:209], v[178:181], v[96:99]
	v_mfma_f32_16x16x32_bf16 v[88:91], v[214:217], v[178:181], v[88:91]
	v_mfma_f32_16x16x32_bf16 v[80:83], v[206:209], v[186:189], v[80:83]
	v_mfma_f32_16x16x32_bf16 v[72:75], v[214:217], v[186:189], v[72:75]
	v_mfma_f32_16x16x32_bf16 v[68:71], v[206:209], v[194:197], v[68:71]
	v_mfma_f32_16x16x32_bf16 v[64:67], v[214:217], v[194:197], v[64:67]
	s_barrier
	s_setprio 0
	s_mov_b32 m0, s51
	s_mov_b64 s[4:5], 0x80
	v_lshl_add_u64 v[198:199], v[220:221], 0, s[4:5]
	ds_read_b128 v[166:169], v148 offset:49152
	ds_read_b128 v[170:173], v148 offset:50176
	ds_read_b128 v[174:177], v148 offset:51200
	ds_read_b128 v[178:181], v148 offset:52224
	ds_read_b128 v[182:185], v148 offset:53248
	ds_read_b128 v[186:189], v148 offset:54272
	ds_read_b128 v[190:193], v148 offset:55296
	ds_read_b128 v[194:197], v148 offset:56320
	global_load_lds_dwordx4 v[198:199], off
	v_lshl_add_u64 v[198:199], v[222:223], 0, s[4:5]
	s_mov_b32 m0, s52
	s_nop 0
	global_load_lds_dwordx4 v[198:199], off
	s_setprio 1
	s_barrier
	s_waitcnt lgkmcnt(0)
	v_mfma_f32_16x16x32_bf16 v[60:63], v[150:153], v[166:169], v[60:63]
	v_mfma_f32_16x16x32_bf16 v[56:59], v[158:161], v[166:169], v[56:59]
	v_mfma_f32_16x16x32_bf16 v[52:55], v[150:153], v[174:177], v[52:55]
	v_mfma_f32_16x16x32_bf16 v[44:47], v[158:161], v[174:177], v[44:47]
	v_mfma_f32_16x16x32_bf16 v[36:39], v[150:153], v[182:185], v[36:39]
	v_mfma_f32_16x16x32_bf16 v[28:31], v[158:161], v[182:185], v[28:31]
	v_mfma_f32_16x16x32_bf16 v[20:23], v[150:153], v[190:193], v[20:23]
	v_mfma_f32_16x16x32_bf16 v[12:15], v[158:161], v[190:193], v[12:15]
	v_mfma_f32_16x16x32_bf16 v[60:63], v[154:157], v[170:173], v[60:63]
	v_mfma_f32_16x16x32_bf16 v[56:59], v[162:165], v[170:173], v[56:59]
	v_mfma_f32_16x16x32_bf16 v[52:55], v[154:157], v[178:181], v[52:55]
	v_mfma_f32_16x16x32_bf16 v[44:47], v[162:165], v[178:181], v[44:47]
	v_mfma_f32_16x16x32_bf16 v[36:39], v[154:157], v[186:189], v[36:39]
	v_mfma_f32_16x16x32_bf16 v[28:31], v[162:165], v[186:189], v[28:31]
	v_mfma_f32_16x16x32_bf16 v[20:23], v[154:157], v[194:197], v[20:23]
	v_mfma_f32_16x16x32_bf16 v[12:15], v[162:165], v[194:197], v[12:15]
	s_barrier
	s_setprio 0
	s_add_u32 s34, s34, 0x40080
	s_addc_u32 s35, s35, 0
	s_add_i32 s36, s36, s43
	s_mov_b32 m0, s36
	s_nop 0
	global_load_lds_dwordx4 v130, s[34:35]
	s_add_i32 m0, s36, 0x2000
	s_nop 0
	global_load_lds_dwordx4 v134, s[34:35]
	s_waitcnt vmcnt(8)
	s_setprio 1
	s_barrier
	v_mfma_f32_16x16x32_bf16 v[48:51], v[202:205], v[166:169], v[48:51]
	v_mfma_f32_16x16x32_bf16 v[40:43], v[210:213], v[166:169], v[40:43]
	v_mfma_f32_16x16x32_bf16 v[32:35], v[202:205], v[174:177], v[32:35]
	v_mfma_f32_16x16x32_bf16 v[24:27], v[210:213], v[174:177], v[24:27]
	v_mfma_f32_16x16x32_bf16 v[16:19], v[202:205], v[182:185], v[16:19]
	v_mfma_f32_16x16x32_bf16 v[8:11], v[210:213], v[182:185], v[8:11]
	v_mfma_f32_16x16x32_bf16 v[4:7], v[202:205], v[190:193], v[4:7]
	v_mfma_f32_16x16x32_bf16 v[0:3], v[210:213], v[190:193], v[0:3]
	v_mfma_f32_16x16x32_bf16 v[48:51], v[206:209], v[170:173], v[48:51]
	v_mfma_f32_16x16x32_bf16 v[40:43], v[214:217], v[170:173], v[40:43]
	v_mfma_f32_16x16x32_bf16 v[32:35], v[206:209], v[178:181], v[32:35]
	v_mfma_f32_16x16x32_bf16 v[24:27], v[214:217], v[178:181], v[24:27]
	v_mfma_f32_16x16x32_bf16 v[16:19], v[206:209], v[186:189], v[16:19]
	v_mfma_f32_16x16x32_bf16 v[8:11], v[214:217], v[186:189], v[8:11]
	v_mfma_f32_16x16x32_bf16 v[4:7], v[206:209], v[194:197], v[4:7]
	v_mfma_f32_16x16x32_bf16 v[0:3], v[214:217], v[194:197], v[0:3]
	s_barrier
; __device__ __forceinline__ unsigned cvt_pk_bf16(float lo, float hi) { unsigned r; asm volatile("v_cvt_pk_bf16_f32 %0, %1, %2" : "=v"(r) : "v"(lo), "v"(hi)); return r; }
; #define PG8_MMA(ai, bj, At, Bt) do { __builtin_amdgcn_s_setprio(1); _Pragma("unroll") for (int m = 0; m < 4; ++m) _Pragma("unroll") for (int n = 0; n < 2; ++n) _Pragma("unroll") for (int k = 0; k < 2; ++k) \
;         acc[ai][bj][m][n] = __builtin_amdgcn_mfma_f32_16x16x32_bf16(Bt[n][k], At[m][k], acc[ai][bj][m][n], 0, 0, 0); __builtin_amdgcn_s_setprio(0); } while (0)
; #define PG8_WAIT_V(n) asm volatile("s_waitcnt vmcnt(" #n ")" ::: "memory")
; #define PG8_BAR __builtin_amdgcn_s_barrier()
; template <class Epi, class Sched>
; __device__ __forceinline__ void gemm_phase(LAS unsigned char* lds, const Gemm g, const Sched& S, const Epi& E) {
;     ...
;             PG8_WAIT_V(6); PG8_BAR; PG8_MMA(1, 1, At, B1); PG8_BAR;
;         }
;         E(acc, cur, wr, wc, fr, fq);
;         if (!has_next) break;
;     __device__ __forceinline__ void operator()(const AccT& acc, const Unit& u, int wr, int wc, int fr, int fq) const {
;     ...
;         const int rbase = u.pm * 256 + wr * 64 + fr;
;         const int tb = u.pn * 256 + wc * 32 + 8 * fq;
; #pragma unroll
;         for (int ai = 0; ai < 2; ++ai)
; #pragma unroll
;             for (int m = 0; m < 4; ++m) {
;                 const int r = rbase + ai * 128 + m * 16;
; #pragma unroll
;                 for (int bj = 0; bj < 2; ++bj) {
;                     const int t0 = tb + bj * 128;
;                     const f32x4 v0 = acc[ai][bj][m][0], v1 = acc[ai][bj][m][1];
;                     u32x4 w; w.x = cvt_pk_bf16(v0[0], v0[1]); w.y = cvt_pk_bf16(v0[2], v0[3]); w.z = cvt_pk_bf16(v1[0], v1[1]); w.w = cvt_pk_bf16(v1[2], v1[3]);
;                     *(u32x4*)(VT + (size_t)r * NT + t0) = w;
;                 }
;             }
	s_setprio 0
	s_add_i32 s65, s65, 2
	s_add_u32 s30, s30, 0x100
	s_addc_u32 s31, s31, 0
	s_add_u32 s63, s63, 0x100
	s_addc_u32 s64, s64, 0
	s_cmp_gt_u32 s65, 13
	s_cbranch_scc0 .LBB0_633
	v_mov_b32_e32 v150, v144
	v_mov_b32_e32 v151, v145
	s_lshl_b32 s21, s28, 8
	s_add_i32 s21, s21, s48
	v_add_u32_e32 v150, s21, v150
	s_lshl_b32 s21, s60, 8
	s_or_b32 s21, s21, s49
	v_lshl_add_u32 v152, v151, 3, s21
	v_ashrrev_i32_e32 v151, 31, v150
	v_cvt_pk_bf16_f32 v124, v124, v125
	v_cvt_pk_bf16_f32 v125, v126, v127
	v_cvt_pk_bf16_f32 v126, v120, v121
	v_lshlrev_b64 v[120:121], 17, v[150:151]
	v_lshl_add_u64 v[120:121], s[0:1], 0, v[120:121]
	v_ashrrev_i32_e32 v153, 31, v152
	v_lshl_add_u64 v[120:121], v[152:153], 1, v[120:121]
	s_mov_b32 s21, 0x200000
	v_cvt_pk_bf16_f32 v127, v122, v123
	global_store_dwordx4 v[120:121], v[124:127], off
	v_cvt_pk_bf16_f32 v112, v112, v113
	v_cvt_pk_bf16_f32 v113, v114, v115
	v_cvt_pk_bf16_f32 v114, v104, v105
	v_cvt_pk_bf16_f32 v115, v106, v107
	global_store_dwordx4 v[120:121], v[112:115], off offset:256
	v_cvt_pk_bf16_f32 v104, v116, v117
	v_cvt_pk_bf16_f32 v105, v118, v119
	v_cvt_pk_bf16_f32 v106, v108, v109
	v_cvt_pk_bf16_f32 v107, v110, v111
	s_mov_b64 s[30:31], 0x200000
	v_add_co_u32_e32 v110, vcc, s21, v120
	v_lshl_add_u64 v[108:109], v[120:121], 0, s[30:31]
	s_nop 0
	v_addc_co_u32_e32 v111, vcc, 0, v121, vcc
	s_mov_b32 s21, 0x400000
	global_store_dwordx4 v[110:111], v[104:107], off
	v_cvt_pk_bf16_f32 v96, v96, v97
	v_cvt_pk_bf16_f32 v97, v98, v99
	v_cvt_pk_bf16_f32 v98, v88, v89
	v_cvt_pk_bf16_f32 v99, v90, v91
	global_store_dwordx4 v[108:109], v[96:99], off offset:256
	v_cvt_pk_bf16_f32 v88, v100, v101
	v_cvt_pk_bf16_f32 v89, v102, v103
	v_cvt_pk_bf16_f32 v90, v92, v93
	v_cvt_pk_bf16_f32 v91, v94, v95
	s_mov_b64 s[30:31], 0x400000
	v_add_co_u32_e32 v94, vcc, s21, v120
	v_lshl_add_u64 v[92:93], v[120:121], 0, s[30:31]
	s_nop 0
	v_addc_co_u32_e32 v95, vcc, 0, v121, vcc
	s_mov_b32 s21, 0x600000
	global_store_dwordx4 v[94:95], v[88:91], off
	v_cvt_pk_bf16_f32 v80, v80, v81
	v_cvt_pk_bf16_f32 v81, v82, v83
	v_cvt_pk_bf16_f32 v82, v72, v73
	v_cvt_pk_bf16_f32 v83, v74, v75
	global_store_dwordx4 v[92:93], v[80:83], off offset:256
	v_cvt_pk_bf16_f32 v72, v84, v85
	v_cvt_pk_bf16_f32 v73, v86, v87
	v_cvt_pk_bf16_f32 v74, v76, v77
	v_cvt_pk_bf16_f32 v75, v78, v79
	s_mov_b64 s[30:31], 0x600000
	v_add_co_u32_e32 v78, vcc, s21, v120
	v_lshl_add_u64 v[76:77], v[120:121], 0, s[30:31]
	s_nop 0
	v_addc_co_u32_e32 v79, vcc, 0, v121, vcc
	global_store_dwordx4 v[78:79], v[72:75], off
	v_cvt_pk_bf16_f32 v68, v68, v69
	v_cvt_pk_bf16_f32 v69, v70, v71
	v_cvt_pk_bf16_f32 v70, v64, v65
	v_cvt_pk_bf16_f32 v71, v66, v67
	global_store_dwordx4 v[76:77], v[68:71], off offset:256
	v_cvt_pk_bf16_f32 v60, v60, v61
	v_cvt_pk_bf16_f32 v61, v62, v63
	v_cvt_pk_bf16_f32 v62, v56, v57
	v_cvt_pk_bf16_f32 v63, v58, v59
	s_mov_b64 s[30:31], 0x1000000
	v_add_co_u32_e32 v58, vcc, s56, v120
	v_lshl_add_u64 v[56:57], v[120:121], 0, s[30:31]
	s_nop 0
	v_addc_co_u32_e32 v59, vcc, 0, v121, vcc
	global_store_dwordx4 v[58:59], v[60:63], off
	v_cvt_pk_bf16_f32 v48, v48, v49
	v_cvt_pk_bf16_f32 v49, v50, v51
	v_cvt_pk_bf16_f32 v50, v40, v41
	v_cvt_pk_bf16_f32 v51, v42, v43
	global_store_dwordx4 v[56:57], v[48:51], off offset:256
	v_cvt_pk_bf16_f32 v40, v52, v53
	v_cvt_pk_bf16_f32 v41, v54, v55
	v_cvt_pk_bf16_f32 v42, v44, v45
	v_cvt_pk_bf16_f32 v43, v46, v47
	v_add_co_u32_e32 v46, vcc, s57, v120
	v_lshl_add_u64 v[44:45], v[120:121], 0, s[6:7]
	s_nop 0
	v_addc_co_u32_e32 v47, vcc, 0, v121, vcc
	global_store_dwordx4 v[46:47], v[40:43], off
	v_cvt_pk_bf16_f32 v32, v32, v33
	v_cvt_pk_bf16_f32 v33, v34, v35
	v_cvt_pk_bf16_f32 v34, v24, v25
	v_cvt_pk_bf16_f32 v35, v26, v27
	global_store_dwordx4 v[44:45], v[32:35], off offset:256
	v_cvt_pk_bf16_f32 v24, v36, v37
	v_cvt_pk_bf16_f32 v25, v38, v39
	v_cvt_pk_bf16_f32 v26, v28, v29
	v_cvt_pk_bf16_f32 v27, v30, v31
	v_add_co_u32_e32 v30, vcc, s58, v120
	v_lshl_add_u64 v[28:29], v[120:121], 0, s[8:9]
	s_nop 0
	v_addc_co_u32_e32 v31, vcc, 0, v121, vcc
	global_store_dwordx4 v[30:31], v[24:27], off
	v_cvt_pk_bf16_f32 v16, v16, v17
	v_cvt_pk_bf16_f32 v17, v18, v19
	v_cvt_pk_bf16_f32 v18, v8, v9
	v_cvt_pk_bf16_f32 v19, v10, v11
	global_store_dwordx4 v[28:29], v[16:19], off offset:256
	v_cvt_pk_bf16_f32 v8, v20, v21
	v_cvt_pk_bf16_f32 v9, v22, v23
	v_cvt_pk_bf16_f32 v10, v12, v13
	v_cvt_pk_bf16_f32 v11, v14, v15
	v_add_co_u32_e32 v14, vcc, s59, v120
	v_lshl_add_u64 v[12:13], v[120:121], 0, s[16:17]
	s_nop 0
	v_addc_co_u32_e32 v15, vcc, 0, v121, vcc
	s_and_b64 vcc, exec, s[2:3]
	s_mov_b32 s60, s20
	s_mov_b32 s28, s22
	s_mov_b64 s[34:35], s[26:27]
	s_mov_b64 s[30:31], s[24:25]
	global_store_dwordx4 v[14:15], v[8:11], off
	v_cvt_pk_bf16_f32 v4, v4, v5
	v_cvt_pk_bf16_f32 v5, v6, v7
	v_cvt_pk_bf16_f32 v6, v0, v1
	v_cvt_pk_bf16_f32 v7, v2, v3
	global_store_dwordx4 v[12:13], v[4:7], off offset:256
	s_cbranch_vccz .LBB0_626
	s_waitcnt vmcnt(0)
	s_cmpk_gt_u32 s33, 0xff
	s_cbranch_scc1 .LBB0_637
	s_barrier

; #define PG8_STAGE(bufoff, gbase, voff) do { _Pragma("unroll") for (int _i = 0; _i < 2; ++_i) \
;         __builtin_amdgcn_global_load_lds((const unsigned*)((const char*)(gbase) + (voff)[_i]), (LAS unsigned*)(lds + (bufoff) + ldsw + _i * 8192), 16, 0, 0); } while (0)
; #define PG8_LDA(dst, b, h) do { _Pragma("unroll") for (int m = 0; m < 4; ++m) _Pragma("unroll") for (int k = 0; k < 2; ++k) dst[m][k] = *(const LAS bf16x8*)(lds + PG8_SA(b, h) + aoff + m * 2048 + k * 1024); } while (0)
; #define PG8_LDB(dst, b, h) do { _Pragma("unroll") for (int n = 0; n < 2; ++n) _Pragma("unroll") for (int k = 0; k < 2; ++k) dst[n][k] = *(const LAS bf16x8*)(lds + PG8_SB(b, h) + boff + n * 2048 + k * 1024); } while (0)
; #define PG8_MMA(ai, bj, At, Bt) do { __builtin_amdgcn_s_setprio(1); _Pragma("unroll") for (int m = 0; m < 4; ++m) _Pragma("unroll") for (int n = 0; n < 2; ++n) _Pragma("unroll") for (int k = 0; k < 2; ++k) \
;         acc[ai][bj][m][n] = __builtin_amdgcn_mfma_f32_16x16x32_bf16(Bt[n][k], At[m][k], acc[ai][bj][m][n], 0, 0, 0); __builtin_amdgcn_s_setprio(0); } while (0)
; #define PG8_WAIT_L(n) asm volatile("s_waitcnt lgkmcnt(" #n ")" ::: "memory")
; template <class Epi, class Sched>
; __device__ __forceinline__ void gemm_phase(LAS unsigned char* lds, const Gemm g, const Sched& S, const Epi& E) {
;     ...
;         const bool has_next = S.next(ui + 1, nxt);
;         const char* nA = has_next ? (const char*)g.A + (size_t)nxt.pm * tstep : cA; const char* nB = has_next ? (const char*)g.Bt + (size_t)nxt.pn * tstep : cB;
;         for (int t = 0; t < nt; t += 2) {
;             const bool last = (t == nt - 2);
;             const char* a1 = cA + (size_t)(t + 1) * kstep;
;             const char* a2 = last ? nA : cA + (size_t)(t + 2) * kstep; const char* b2 = last ? nB : cB + (size_t)(t + 2) * kstep;
;             const char* a3 = a2 + kstep; const char* b3 = b2 + kstep;
;             PG8_LDB(B0, 0, 0); PG8_SCHED; PG8_LDA(At, 0, 0); PG8_STAGE(PG8_SA(1, 1), a1 + hstep, voffA);
;             PG8_WAIT_L(8); PG8_BAR; PG8_WAIT_L(0); PG8_MMA(0, 0, At, B0); PG8_BAR; PG8_SCHED;
;             PG8_LDB(B1, 0, 1); PG8_STAGE(PG8_SB(0, 0), b2, voffB);
;             PG8_BAR; PG8_WAIT_L(0); PG8_MMA(0, 1, At, B1); PG8_BAR;
;             PG8_LDA(At, 0, 1); PG8_STAGE(PG8_SA(0, 0), a2, voffA);
;             PG8_BAR; PG8_WAIT_L(0); PG8_MMA(1, 0, At, B0); PG8_BAR; PG8_SCHED;
.LBB0_652:
	s_ashr_i32 s9, s8, 31
	v_cmp_lt_i64_e32 vcc, s[16:17], v[142:143]
	s_lshl_b64 s[16:17], s[8:9], 19
	s_add_u32 s16, s14, s16
	s_addc_u32 s17, s15, s17
	s_and_b64 s[18:19], vcc, exec
	s_cselect_b32 s9, s17, s23
	s_cselect_b32 s48, s16, s22
	s_ashr_i32 s7, s6, 31
	s_lshl_b64 s[18:19], s[6:7], 19
	s_add_u32 s18, s12, s18
	s_addc_u32 s19, s13, s19
	s_and_b64 s[26:27], vcc, exec
	s_cselect_b32 s7, s19, s25
	s_cselect_b32 s49, s18, s24
	s_add_u32 s22, s22, 0x40080
	s_addc_u32 s23, s23, 0
	s_add_u32 s51, s24, 0x100
	s_addc_u32 s52, s25, 0
	s_mov_b32 s53, -2
	s_waitcnt lgkmcnt(0)
	ds_read_b128 v[152:155], v149
	ds_read_b128 v[156:159], v149 offset:1024
	ds_read_b128 v[160:163], v149 offset:2048
	ds_read_b128 v[164:167], v149 offset:3072
	s_add_u32 s24, s22, 0xfffc0080
	s_addc_u32 s25, s23, -1
	s_cmp_eq_u32 s53, 12
	s_cselect_b32 s27, s9, s25
	s_cselect_b32 s26, s48, s24
	s_cselect_b32 s25, s7, s52
	s_cselect_b32 s24, s49, s51
	s_add_i32 m0, s21, 0xc000
	ds_read_b128 v[168:171], v150
	ds_read_b128 v[172:175], v150 offset:1024
	ds_read_b128 v[176:179], v150 offset:2048
	ds_read_b128 v[180:183], v150 offset:3072
	ds_read_b128 v[184:187], v150 offset:4096
	ds_read_b128 v[188:191], v150 offset:5120
	ds_read_b128 v[192:195], v150 offset:6144
	ds_read_b128 v[196:199], v150 offset:7168
	global_load_lds_dwordx4 v138, s[22:23]
	s_add_i32 m0, s21, 0xe000
	s_nop 0
	global_load_lds_dwordx4 v140, s[22:23]
	s_waitcnt lgkmcnt(8)
	s_waitcnt vmcnt(8)
	s_setprio 1
	s_barrier
	s_waitcnt lgkmcnt(0)
	v_mfma_f32_16x16x32_bf16 v[124:127], v[152:155], v[168:171], 0
	v_mfma_f32_16x16x32_bf16 v[120:123], v[160:163], v[168:171], 0
	v_mfma_f32_16x16x32_bf16 v[112:115], v[152:155], v[176:179], 0
	v_mfma_f32_16x16x32_bf16 v[104:107], v[160:163], v[176:179], 0
	v_mfma_f32_16x16x32_bf16 v[96:99], v[152:155], v[184:187], 0
	v_mfma_f32_16x16x32_bf16 v[88:91], v[160:163], v[184:187], 0
	v_mfma_f32_16x16x32_bf16 v[80:83], v[152:155], v[192:195], 0
	v_mfma_f32_16x16x32_bf16 v[72:75], v[160:163], v[192:195], 0
	v_mfma_f32_16x16x32_bf16 v[124:127], v[156:159], v[172:175], v[124:127]
	v_mfma_f32_16x16x32_bf16 v[120:123], v[164:167], v[172:175], v[120:123]
	v_mfma_f32_16x16x32_bf16 v[112:115], v[156:159], v[180:183], v[112:115]
	v_mfma_f32_16x16x32_bf16 v[104:107], v[164:167], v[180:183], v[104:107]
	v_mfma_f32_16x16x32_bf16 v[96:99], v[156:159], v[188:191], v[96:99]
	v_mfma_f32_16x16x32_bf16 v[88:91], v[164:167], v[188:191], v[88:91]
	v_mfma_f32_16x16x32_bf16 v[80:83], v[156:159], v[196:199], v[80:83]
	v_mfma_f32_16x16x32_bf16 v[72:75], v[164:167], v[196:199], v[72:75]
	s_barrier
	s_setprio 0
	s_add_i32 s54, s45, s30
	s_mov_b32 m0, s54
	ds_read_b128 v[202:205], v151
	ds_read_b128 v[206:209], v151 offset:1024
	ds_read_b128 v[210:213], v151 offset:2048
	ds_read_b128 v[214:217], v151 offset:3072
	global_load_lds_dwordx4 v130, s[24:25]
	s_add_i32 m0, s54, 0x2000
	s_nop 0
	global_load_lds_dwordx4 v134, s[24:25]
	s_waitcnt vmcnt(8)
	s_setprio 1
	s_barrier
	s_waitcnt lgkmcnt(0)
	v_mfma_f32_16x16x32_bf16 v[116:119], v[202:205], v[168:171], 0
	v_mfma_f32_16x16x32_bf16 v[108:111], v[210:213], v[168:171], 0
	v_mfma_f32_16x16x32_bf16 v[100:103], v[202:205], v[176:179], 0
	v_mfma_f32_16x16x32_bf16 v[92:95], v[210:213], v[176:179], 0
	v_mfma_f32_16x16x32_bf16 v[84:87], v[202:205], v[184:187], 0
	v_mfma_f32_16x16x32_bf16 v[76:79], v[210:213], v[184:187], 0
	v_mfma_f32_16x16x32_bf16 v[68:71], v[202:205], v[192:195], 0
	v_mfma_f32_16x16x32_bf16 v[64:67], v[210:213], v[192:195], 0
	v_mfma_f32_16x16x32_bf16 v[116:119], v[206:209], v[172:175], v[116:119]
	v_mfma_f32_16x16x32_bf16 v[108:111], v[214:217], v[172:175], v[108:111]
	v_mfma_f32_16x16x32_bf16 v[100:103], v[206:209], v[180:183], v[100:103]
	v_mfma_f32_16x16x32_bf16 v[92:95], v[214:217], v[180:183], v[92:95]
	v_mfma_f32_16x16x32_bf16 v[84:87], v[206:209], v[188:191], v[84:87]
	v_mfma_f32_16x16x32_bf16 v[76:79], v[214:217], v[188:191], v[76:79]
	v_mfma_f32_16x16x32_bf16 v[68:71], v[206:209], v[196:199], v[68:71]
	v_mfma_f32_16x16x32_bf16 v[64:67], v[214:217], v[196:199], v[64:67]
	s_barrier
	s_setprio 0
	s_mov_b32 m0, s21
	v_lshl_add_u64 v[222:223], s[26:27], 0, v[128:129]
	ds_read_b128 v[168:171], v150 offset:16384
	ds_read_b128 v[172:175], v150 offset:17408
	ds_read_b128 v[176:179], v150 offset:18432
	ds_read_b128 v[180:183], v150 offset:19456
	ds_read_b128 v[184:187], v150 offset:20480
	ds_read_b128 v[188:191], v150 offset:21504
	ds_read_b128 v[192:195], v150 offset:22528
	ds_read_b128 v[196:199], v150 offset:23552
	global_load_lds_dwordx4 v128, s[26:27]
	v_lshl_add_u64 v[224:225], s[26:27], 0, v[132:133]
	s_mov_b32 m0, s31
	s_nop 0
	global_load_lds_dwordx4 v132, s[26:27]
	s_setprio 1
	s_barrier
	s_waitcnt lgkmcnt(0)
	v_mfma_f32_16x16x32_bf16 v[60:63], v[152:155], v[168:171], 0
	v_mfma_f32_16x16x32_bf16 v[56:59], v[160:163], v[168:171], 0
	v_mfma_f32_16x16x32_bf16 v[48:51], v[152:155], v[176:179], 0
	v_mfma_f32_16x16x32_bf16 v[40:43], v[160:163], v[176:179], 0
	v_mfma_f32_16x16x32_bf16 v[32:35], v[152:155], v[184:187], 0
	v_mfma_f32_16x16x32_bf16 v[24:27], v[160:163], v[184:187], 0
	v_mfma_f32_16x16x32_bf16 v[16:19], v[152:155], v[192:195], 0
	v_mfma_f32_16x16x32_bf16 v[8:11], v[160:163], v[192:195], 0
	v_mfma_f32_16x16x32_bf16 v[60:63], v[156:159], v[172:175], v[60:63]
	v_mfma_f32_16x16x32_bf16 v[56:59], v[164:167], v[172:175], v[56:59]
	v_mfma_f32_16x16x32_bf16 v[48:51], v[156:159], v[180:183], v[48:51]
	v_mfma_f32_16x16x32_bf16 v[40:43], v[164:167], v[180:183], v[40:43]
	v_mfma_f32_16x16x32_bf16 v[32:35], v[156:159], v[188:191], v[32:35]
	v_mfma_f32_16x16x32_bf16 v[24:27], v[164:167], v[188:191], v[24:27]
	v_mfma_f32_16x16x32_bf16 v[16:19], v[156:159], v[196:199], v[16:19]
	v_mfma_f32_16x16x32_bf16 v[8:11], v[164:167], v[196:199], v[8:11]
	s_barrier
; #define PG8_STAGE(bufoff, gbase, voff) do { _Pragma("unroll") for (int _i = 0; _i < 2; ++_i) \
;         __builtin_amdgcn_global_load_lds((const unsigned*)((const char*)(gbase) + (voff)[_i]), (LAS unsigned*)(lds + (bufoff) + ldsw + _i * 8192), 16, 0, 0); } while (0)
; #define PG8_LDA(dst, b, h) do { _Pragma("unroll") for (int m = 0; m < 4; ++m) _Pragma("unroll") for (int k = 0; k < 2; ++k) dst[m][k] = *(const LAS bf16x8*)(lds + PG8_SA(b, h) + aoff + m * 2048 + k * 1024); } while (0)
; #define PG8_LDB(dst, b, h) do { _Pragma("unroll") for (int n = 0; n < 2; ++n) _Pragma("unroll") for (int k = 0; k < 2; ++k) dst[n][k] = *(const LAS bf16x8*)(lds + PG8_SB(b, h) + boff + n * 2048 + k * 1024); } while (0)
; #define PG8_MMA(ai, bj, At, Bt) do { __builtin_amdgcn_s_setprio(1); _Pragma("unroll") for (int m = 0; m < 4; ++m) _Pragma("unroll") for (int n = 0; n < 2; ++n) _Pragma("unroll") for (int k = 0; k < 2; ++k) \
;         acc[ai][bj][m][n] = __builtin_amdgcn_mfma_f32_16x16x32_bf16(Bt[n][k], At[m][k], acc[ai][bj][m][n], 0, 0, 0); __builtin_amdgcn_s_setprio(0); } while (0)
; #define PG8_WAIT_V(n) asm volatile("s_waitcnt vmcnt(" #n ")" ::: "memory")
; #define PG8_WAIT_L(n) asm volatile("s_waitcnt lgkmcnt(" #n ")" ::: "memory")
; #define PG8_BAR __builtin_amdgcn_s_barrier()
; #define PG8_SCHED __builtin_amdgcn_sched_barrier(0)
; template <class Epi, class Sched>
; __device__ __forceinline__ void gemm_phase(LAS unsigned char* lds, const Gemm g, const Sched& S, const Epi& E) {
;     ...
;             PG8_STAGE(PG8_SB(0, 1), b2 + hstep, voffB);
;             PG8_WAIT_V(6); PG8_BAR; PG8_MMA(1, 1, At, B1); PG8_BAR;
;             PG8_LDB(B0, 1, 0); PG8_SCHED; PG8_LDA(At, 1, 0); PG8_STAGE(PG8_SA(0, 1), a2 + hstep, voffA);
;             PG8_WAIT_L(8); PG8_BAR; PG8_WAIT_L(0); PG8_MMA(0, 0, At, B0); PG8_BAR; PG8_SCHED;
;             PG8_LDB(B1, 1, 1); PG8_STAGE(PG8_SB(1, 0), b3, voffB);
;             PG8_BAR; PG8_WAIT_L(0); PG8_MMA(0, 1, At, B1); PG8_BAR;
;             PG8_LDA(At, 1, 1); PG8_STAGE(PG8_SA(1, 0), a3, voffA);
	s_setprio 0
	s_add_u32 s54, s24, 0x40000
	s_addc_u32 s55, s25, 0
	s_add_i32 s56, s46, s30
	s_mov_b32 m0, s56
	s_nop 0
	global_load_lds_dwordx4 v130, s[54:55]
	s_add_i32 m0, s56, 0x2000
	s_nop 0
	global_load_lds_dwordx4 v134, s[54:55]
	s_add_u32 s26, s26, 0x40000
	s_addc_u32 s27, s27, 0
	s_mov_b32 m0, s33
	s_nop 0
	global_load_lds_dwordx4 v128, s[26:27]
	s_mov_b32 m0, s34
	s_nop 0
	global_load_lds_dwordx4 v132, s[26:27]
	s_waitcnt vmcnt(10)
	s_setprio 1
	s_barrier
	v_mfma_f32_16x16x32_bf16 v[52:55], v[202:205], v[168:171], 0
	v_mfma_f32_16x16x32_bf16 v[44:47], v[210:213], v[168:171], 0
	v_mfma_f32_16x16x32_bf16 v[36:39], v[202:205], v[176:179], 0
	v_mfma_f32_16x16x32_bf16 v[28:31], v[210:213], v[176:179], 0
	v_mfma_f32_16x16x32_bf16 v[20:23], v[202:205], v[184:187], 0
	v_mfma_f32_16x16x32_bf16 v[12:15], v[210:213], v[184:187], 0
	v_mfma_f32_16x16x32_bf16 v[4:7], v[202:205], v[192:195], 0
	v_mfma_f32_16x16x32_bf16 v[0:3], v[210:213], v[192:195], 0
	v_mfma_f32_16x16x32_bf16 v[52:55], v[206:209], v[172:175], v[52:55]
	v_mfma_f32_16x16x32_bf16 v[44:47], v[214:217], v[172:175], v[44:47]
	v_mfma_f32_16x16x32_bf16 v[36:39], v[206:209], v[180:183], v[36:39]
	v_mfma_f32_16x16x32_bf16 v[28:31], v[214:217], v[180:183], v[28:31]
	v_mfma_f32_16x16x32_bf16 v[20:23], v[206:209], v[188:191], v[20:23]
	v_mfma_f32_16x16x32_bf16 v[12:15], v[214:217], v[188:191], v[12:15]
	v_mfma_f32_16x16x32_bf16 v[4:7], v[206:209], v[196:199], v[4:7]
	v_mfma_f32_16x16x32_bf16 v[0:3], v[214:217], v[196:199], v[0:3]
	s_barrier
	s_setprio 0
	s_add_i32 s54, 0, 0x18000
	v_add_u32_e32 v136, s54, v148
	ds_read_b128 v[152:155], v136
	ds_read_b128 v[156:159], v136 offset:1024
	ds_read_b128 v[160:163], v136 offset:2048
	ds_read_b128 v[164:167], v136 offset:3072
	ds_read_b128 v[168:171], v150 offset:32768
	ds_read_b128 v[172:175], v150 offset:33792
	ds_read_b128 v[176:179], v150 offset:34816
	ds_read_b128 v[180:183], v150 offset:35840
	ds_read_b128 v[184:187], v150 offset:36864
	ds_read_b128 v[188:191], v150 offset:37888
	ds_read_b128 v[192:195], v150 offset:38912
	ds_read_b128 v[196:199], v150 offset:39936
	s_waitcnt lgkmcnt(8)
	s_waitcnt vmcnt(8)
	s_setprio 1
	s_barrier
	s_waitcnt lgkmcnt(0)
	v_mfma_f32_16x16x32_bf16 v[124:127], v[152:155], v[168:171], v[124:127]
	v_mfma_f32_16x16x32_bf16 v[120:123], v[160:163], v[168:171], v[120:123]
	v_mfma_f32_16x16x32_bf16 v[112:115], v[152:155], v[176:179], v[112:115]
	v_mfma_f32_16x16x32_bf16 v[104:107], v[160:163], v[176:179], v[104:107]
	v_mfma_f32_16x16x32_bf16 v[96:99], v[152:155], v[184:187], v[96:99]
	v_mfma_f32_16x16x32_bf16 v[88:91], v[160:163], v[184:187], v[88:91]
	v_mfma_f32_16x16x32_bf16 v[80:83], v[152:155], v[192:195], v[80:83]
	v_mfma_f32_16x16x32_bf16 v[72:75], v[160:163], v[192:195], v[72:75]
	v_mfma_f32_16x16x32_bf16 v[124:127], v[156:159], v[172:175], v[124:127]
	v_mfma_f32_16x16x32_bf16 v[120:123], v[164:167], v[172:175], v[120:123]
	v_mfma_f32_16x16x32_bf16 v[112:115], v[156:159], v[180:183], v[112:115]
	v_mfma_f32_16x16x32_bf16 v[104:107], v[164:167], v[180:183], v[104:107]
	v_mfma_f32_16x16x32_bf16 v[96:99], v[156:159], v[188:191], v[96:99]
	v_mfma_f32_16x16x32_bf16 v[88:91], v[164:167], v[188:191], v[88:91]
	v_mfma_f32_16x16x32_bf16 v[80:83], v[156:159], v[196:199], v[80:83]
	v_mfma_f32_16x16x32_bf16 v[72:75], v[164:167], v[196:199], v[72:75]
	s_barrier
	s_setprio 0
	s_add_i32 s26, 0, 0x1c000
	s_add_i32 s27, s54, s30
	v_add_u32_e32 v136, s26, v148
	s_add_u32 s0, s24, 0x80
	s_addc_u32 s1, s25, 0
	s_mov_b32 m0, s27
	ds_read_b128 v[202:205], v136
	ds_read_b128 v[206:209], v136 offset:1024
	ds_read_b128 v[210:213], v136 offset:2048
	ds_read_b128 v[214:217], v136 offset:3072
	global_load_lds_dwordx4 v130, s[0:1]
	s_add_i32 m0, s27, 0x2000
	s_nop 0
	global_load_lds_dwordx4 v134, s[0:1]
	s_waitcnt vmcnt(8)
	s_setprio 1
	s_barrier
	s_waitcnt lgkmcnt(0)
	v_mfma_f32_16x16x32_bf16 v[116:119], v[202:205], v[168:171], v[116:119]
	v_mfma_f32_16x16x32_bf16 v[108:111], v[210:213], v[168:171], v[108:111]
	v_mfma_f32_16x16x32_bf16 v[100:103], v[202:205], v[176:179], v[100:103]
	v_mfma_f32_16x16x32_bf16 v[92:95], v[210:213], v[176:179], v[92:95]
	v_mfma_f32_16x16x32_bf16 v[84:87], v[202:205], v[184:187], v[84:87]
	v_mfma_f32_16x16x32_bf16 v[76:79], v[210:213], v[184:187], v[76:79]
	v_mfma_f32_16x16x32_bf16 v[68:71], v[202:205], v[192:195], v[68:71]
	v_mfma_f32_16x16x32_bf16 v[64:67], v[210:213], v[192:195], v[64:67]
	v_mfma_f32_16x16x32_bf16 v[116:119], v[206:209], v[172:175], v[116:119]
	v_mfma_f32_16x16x32_bf16 v[108:111], v[214:217], v[172:175], v[108:111]
	v_mfma_f32_16x16x32_bf16 v[100:103], v[206:209], v[180:183], v[100:103]
	v_mfma_f32_16x16x32_bf16 v[92:95], v[214:217], v[180:183], v[92:95]
	v_mfma_f32_16x16x32_bf16 v[84:87], v[206:209], v[188:191], v[84:87]
	v_mfma_f32_16x16x32_bf16 v[76:79], v[214:217], v[188:191], v[76:79]
	v_mfma_f32_16x16x32_bf16 v[68:71], v[206:209], v[196:199], v[68:71]
	v_mfma_f32_16x16x32_bf16 v[64:67], v[214:217], v[196:199], v[64:67]
	s_barrier
	s_setprio 0
	s_mov_b32 m0, s42
	s_mov_b64 s[0:1], 0x80
	v_lshl_add_u64 v[218:219], v[222:223], 0, s[0:1]
	ds_read_b128 v[168:171], v150 offset:49152
	ds_read_b128 v[172:175], v150 offset:50176
	ds_read_b128 v[176:179], v150 offset:51200
	ds_read_b128 v[180:183], v150 offset:52224
	ds_read_b128 v[184:187], v150 offset:53248
	ds_read_b128 v[188:191], v150 offset:54272
	ds_read_b128 v[192:195], v150 offset:55296
	ds_read_b128 v[196:199], v150 offset:56320
	global_load_lds_dwordx4 v[218:219], off
	v_lshl_add_u64 v[218:219], v[224:225], 0, s[0:1]
	s_mov_b32 m0, s43
	s_nop 0
	global_load_lds_dwordx4 v[218:219], off
	s_setprio 1
	s_barrier
; #define PG8_STAGE(bufoff, gbase, voff) do { _Pragma("unroll") for (int _i = 0; _i < 2; ++_i) \
;         __builtin_amdgcn_global_load_lds((const unsigned*)((const char*)(gbase) + (voff)[_i]), (LAS unsigned*)(lds + (bufoff) + ldsw + _i * 8192), 16, 0, 0); } while (0)
; #define PG8_LDA(dst, b, h) do { _Pragma("unroll") for (int m = 0; m < 4; ++m) _Pragma("unroll") for (int k = 0; k < 2; ++k) dst[m][k] = *(const LAS bf16x8*)(lds + PG8_SA(b, h) + aoff + m * 2048 + k * 1024); } while (0)
; #define PG8_LDB(dst, b, h) do { _Pragma("unroll") for (int n = 0; n < 2; ++n) _Pragma("unroll") for (int k = 0; k < 2; ++k) dst[n][k] = *(const LAS bf16x8*)(lds + PG8_SB(b, h) + boff + n * 2048 + k * 1024); } while (0)
; #define PG8_MMA(ai, bj, At, Bt) do { __builtin_amdgcn_s_setprio(1); _Pragma("unroll") for (int m = 0; m < 4; ++m) _Pragma("unroll") for (int n = 0; n < 2; ++n) _Pragma("unroll") for (int k = 0; k < 2; ++k) \
;         acc[ai][bj][m][n] = __builtin_amdgcn_mfma_f32_16x16x32_bf16(Bt[n][k], At[m][k], acc[ai][bj][m][n], 0, 0, 0); __builtin_amdgcn_s_setprio(0); } while (0)
; #define PG8_WAIT_V(n) asm volatile("s_waitcnt vmcnt(" #n ")" ::: "memory")
; #define PG8_WAIT_L(n) asm volatile("s_waitcnt lgkmcnt(" #n ")" ::: "memory")
; #define PG8_BAR __builtin_amdgcn_s_barrier()
; #define PG8_SCHED __builtin_amdgcn_sched_barrier(0)
; template <class Epi, class Sched>
; __device__ __forceinline__ void gemm_phase(LAS unsigned char* lds, const Gemm g, const Sched& S, const Epi& E) {
;     ...
;             PG8_LDB(B0, 0, 0); PG8_SCHED; PG8_LDA(At, 0, 0); PG8_STAGE(PG8_SA(1, 1), a1 + hstep, voffA);
;             PG8_WAIT_L(8); PG8_BAR; PG8_WAIT_L(0); PG8_MMA(0, 0, At, B0); PG8_BAR; PG8_SCHED;
;             PG8_LDB(B1, 0, 1); PG8_STAGE(PG8_SB(0, 0), b2, voffB);
;             PG8_BAR; PG8_WAIT_L(0); PG8_MMA(0, 1, At, B1); PG8_BAR;
;             PG8_LDA(At, 0, 1); PG8_STAGE(PG8_SA(0, 0), a2, voffA);
;             PG8_BAR; PG8_WAIT_L(0); PG8_MMA(1, 0, At, B0); PG8_BAR; PG8_SCHED;
;     ...
;             PG8_BAR; PG8_WAIT_L(0); PG8_MMA(1, 0, At, B0); PG8_BAR; PG8_SCHED;
;             PG8_STAGE(PG8_SB(1, 1), b3 + hstep, voffB);
;             PG8_WAIT_V(6); PG8_BAR; PG8_MMA(1, 1, At, B1); PG8_BAR;
	s_waitcnt lgkmcnt(0)
	v_mfma_f32_16x16x32_bf16 v[60:63], v[152:155], v[168:171], v[60:63]
	v_mfma_f32_16x16x32_bf16 v[56:59], v[160:163], v[168:171], v[56:59]
	v_mfma_f32_16x16x32_bf16 v[48:51], v[152:155], v[176:179], v[48:51]
	v_mfma_f32_16x16x32_bf16 v[40:43], v[160:163], v[176:179], v[40:43]
	v_mfma_f32_16x16x32_bf16 v[32:35], v[152:155], v[184:187], v[32:35]
	v_mfma_f32_16x16x32_bf16 v[24:27], v[160:163], v[184:187], v[24:27]
	v_mfma_f32_16x16x32_bf16 v[16:19], v[152:155], v[192:195], v[16:19]
	v_mfma_f32_16x16x32_bf16 v[8:11], v[160:163], v[192:195], v[8:11]
	v_mfma_f32_16x16x32_bf16 v[60:63], v[156:159], v[172:175], v[60:63]
	v_mfma_f32_16x16x32_bf16 v[56:59], v[164:167], v[172:175], v[56:59]
	v_mfma_f32_16x16x32_bf16 v[48:51], v[156:159], v[180:183], v[48:51]
	v_mfma_f32_16x16x32_bf16 v[40:43], v[164:167], v[180:183], v[40:43]
	v_mfma_f32_16x16x32_bf16 v[32:35], v[156:159], v[188:191], v[32:35]
	v_mfma_f32_16x16x32_bf16 v[24:27], v[164:167], v[188:191], v[24:27]
	v_mfma_f32_16x16x32_bf16 v[16:19], v[156:159], v[196:199], v[16:19]
	v_mfma_f32_16x16x32_bf16 v[8:11], v[164:167], v[196:199], v[8:11]
	s_barrier
	s_setprio 0
	s_add_u32 s24, s24, 0x40080
	s_addc_u32 s25, s25, 0
	s_add_i32 s26, s26, s30
	s_mov_b32 m0, s26
	s_nop 0
	global_load_lds_dwordx4 v130, s[24:25]
	s_add_i32 m0, s26, 0x2000
	s_nop 0
	global_load_lds_dwordx4 v134, s[24:25]
	s_waitcnt vmcnt(8)
	s_setprio 1
	s_barrier
	v_mfma_f32_16x16x32_bf16 v[52:55], v[202:205], v[168:171], v[52:55]
	v_mfma_f32_16x16x32_bf16 v[44:47], v[210:213], v[168:171], v[44:47]
	v_mfma_f32_16x16x32_bf16 v[36:39], v[202:205], v[176:179], v[36:39]
	v_mfma_f32_16x16x32_bf16 v[28:31], v[210:213], v[176:179], v[28:31]
	v_mfma_f32_16x16x32_bf16 v[20:23], v[202:205], v[184:187], v[20:23]
	v_mfma_f32_16x16x32_bf16 v[12:15], v[210:213], v[184:187], v[12:15]
	v_mfma_f32_16x16x32_bf16 v[4:7], v[202:205], v[192:195], v[4:7]
	v_mfma_f32_16x16x32_bf16 v[0:3], v[210:213], v[192:195], v[0:3]
	v_mfma_f32_16x16x32_bf16 v[52:55], v[206:209], v[172:175], v[52:55]
	v_mfma_f32_16x16x32_bf16 v[44:47], v[214:217], v[172:175], v[44:47]
	v_mfma_f32_16x16x32_bf16 v[36:39], v[206:209], v[180:183], v[36:39]
	v_mfma_f32_16x16x32_bf16 v[28:31], v[214:217], v[180:183], v[28:31]
	v_mfma_f32_16x16x32_bf16 v[20:23], v[206:209], v[188:191], v[20:23]
	v_mfma_f32_16x16x32_bf16 v[12:15], v[214:217], v[188:191], v[12:15]
	v_mfma_f32_16x16x32_bf16 v[4:7], v[206:209], v[196:199], v[4:7]
	v_mfma_f32_16x16x32_bf16 v[0:3], v[214:217], v[196:199], v[0:3]
	s_barrier
	s_setprio 0
	s_add_i32 s53, s53, 2
	s_add_u32 s22, s22, 0x100
	s_addc_u32 s23, s23, 0
	s_add_u32 s51, s51, 0x100
	s_addc_u32 s52, s52, 0
	s_cmp_gt_u32 s53, 13
.LBB0_653:
	ds_read_b128 v[152:155], v149
	ds_read_b128 v[156:159], v149 offset:1024
	ds_read_b128 v[160:163], v149 offset:2048
	ds_read_b128 v[164:167], v149 offset:3072
	s_add_u32 s24, s22, 0xfffc0080
	s_addc_u32 s25, s23, -1
	s_cmp_eq_u32 s53, 12
	s_cselect_b32 s27, s9, s25
	s_cselect_b32 s26, s48, s24
	s_cselect_b32 s25, s7, s52
	s_cselect_b32 s24, s49, s51
	s_add_i32 m0, s21, 0xc000
	ds_read_b128 v[168:171], v150
	ds_read_b128 v[172:175], v150 offset:1024
	ds_read_b128 v[176:179], v150 offset:2048
	ds_read_b128 v[180:183], v150 offset:3072
	ds_read_b128 v[184:187], v150 offset:4096
	ds_read_b128 v[188:191], v150 offset:5120
	ds_read_b128 v[192:195], v150 offset:6144
	ds_read_b128 v[196:199], v150 offset:7168
	global_load_lds_dwordx4 v138, s[22:23]
	s_add_i32 m0, s21, 0xe000
	s_nop 0
	global_load_lds_dwordx4 v140, s[22:23]
	s_waitcnt lgkmcnt(8)
	s_waitcnt vmcnt(8)
	s_setprio 1
	s_barrier
	s_waitcnt lgkmcnt(0)
	v_mfma_f32_16x16x32_bf16 v[124:127], v[152:155], v[168:171], v[124:127]
	v_mfma_f32_16x16x32_bf16 v[120:123], v[160:163], v[168:171], v[120:123]
	v_mfma_f32_16x16x32_bf16 v[112:115], v[152:155], v[176:179], v[112:115]
	v_mfma_f32_16x16x32_bf16 v[104:107], v[160:163], v[176:179], v[104:107]
	v_mfma_f32_16x16x32_bf16 v[96:99], v[152:155], v[184:187], v[96:99]
	v_mfma_f32_16x16x32_bf16 v[88:91], v[160:163], v[184:187], v[88:91]
	v_mfma_f32_16x16x32_bf16 v[80:83], v[152:155], v[192:195], v[80:83]
	v_mfma_f32_16x16x32_bf16 v[72:75], v[160:163], v[192:195], v[72:75]
	v_mfma_f32_16x16x32_bf16 v[124:127], v[156:159], v[172:175], v[124:127]
	v_mfma_f32_16x16x32_bf16 v[120:123], v[164:167], v[172:175], v[120:123]
	v_mfma_f32_16x16x32_bf16 v[112:115], v[156:159], v[180:183], v[112:115]
	v_mfma_f32_16x16x32_bf16 v[104:107], v[164:167], v[180:183], v[104:107]
	v_mfma_f32_16x16x32_bf16 v[96:99], v[156:159], v[188:191], v[96:99]
	v_mfma_f32_16x16x32_bf16 v[88:91], v[164:167], v[188:191], v[88:91]
	v_mfma_f32_16x16x32_bf16 v[80:83], v[156:159], v[196:199], v[80:83]
	v_mfma_f32_16x16x32_bf16 v[72:75], v[164:167], v[196:199], v[72:75]
	s_barrier
	s_setprio 0
	s_add_i32 s54, s45, s30
	s_mov_b32 m0, s54
	ds_read_b128 v[202:205], v151
	ds_read_b128 v[206:209], v151 offset:1024
	ds_read_b128 v[210:213], v151 offset:2048
	ds_read_b128 v[214:217], v151 offset:3072
	global_load_lds_dwordx4 v130, s[24:25]
	s_add_i32 m0, s54, 0x2000
	s_nop 0
	global_load_lds_dwordx4 v134, s[24:25]
	s_waitcnt vmcnt(8)
	s_setprio 1
	s_barrier
; #define PG8_STAGE(bufoff, gbase, voff) do { _Pragma("unroll") for (int _i = 0; _i < 2; ++_i) \
;         __builtin_amdgcn_global_load_lds((const unsigned*)((const char*)(gbase) + (voff)[_i]), (LAS unsigned*)(lds + (bufoff) + ldsw + _i * 8192), 16, 0, 0); } while (0)
; #define PG8_LDA(dst, b, h) do { _Pragma("unroll") for (int m = 0; m < 4; ++m) _Pragma("unroll") for (int k = 0; k < 2; ++k) dst[m][k] = *(const LAS bf16x8*)(lds + PG8_SA(b, h) + aoff + m * 2048 + k * 1024); } while (0)
; #define PG8_LDB(dst, b, h) do { _Pragma("unroll") for (int n = 0; n < 2; ++n) _Pragma("unroll") for (int k = 0; k < 2; ++k) dst[n][k] = *(const LAS bf16x8*)(lds + PG8_SB(b, h) + boff + n * 2048 + k * 1024); } while (0)
; #define PG8_MMA(ai, bj, At, Bt) do { __builtin_amdgcn_s_setprio(1); _Pragma("unroll") for (int m = 0; m < 4; ++m) _Pragma("unroll") for (int n = 0; n < 2; ++n) _Pragma("unroll") for (int k = 0; k < 2; ++k) \
;         acc[ai][bj][m][n] = __builtin_amdgcn_mfma_f32_16x16x32_bf16(Bt[n][k], At[m][k], acc[ai][bj][m][n], 0, 0, 0); __builtin_amdgcn_s_setprio(0); } while (0)
; #define PG8_WAIT_V(n) asm volatile("s_waitcnt vmcnt(" #n ")" ::: "memory")
; #define PG8_WAIT_L(n) asm volatile("s_waitcnt lgkmcnt(" #n ")" ::: "memory")
; #define PG8_BAR __builtin_amdgcn_s_barrier()
; #define PG8_SCHED __builtin_amdgcn_sched_barrier(0)
; template <class Epi, class Sched>
; __device__ __forceinline__ void gemm_phase(LAS unsigned char* lds, const Gemm g, const Sched& S, const Epi& E) {
;     ...
;             PG8_BAR; PG8_WAIT_L(0); PG8_MMA(0, 1, At, B1); PG8_BAR;
;             PG8_LDA(At, 0, 1); PG8_STAGE(PG8_SA(0, 0), a2, voffA);
;             PG8_BAR; PG8_WAIT_L(0); PG8_MMA(1, 0, At, B0); PG8_BAR; PG8_SCHED;
;             PG8_STAGE(PG8_SB(0, 1), b2 + hstep, voffB);
;             PG8_WAIT_V(6); PG8_BAR; PG8_MMA(1, 1, At, B1); PG8_BAR;
;             PG8_LDB(B0, 1, 0); PG8_SCHED; PG8_LDA(At, 1, 0); PG8_STAGE(PG8_SA(0, 1), a2 + hstep, voffA);
;             PG8_WAIT_L(8); PG8_BAR; PG8_WAIT_L(0); PG8_MMA(0, 0, At, B0); PG8_BAR; PG8_SCHED;
	s_waitcnt lgkmcnt(0)
	v_mfma_f32_16x16x32_bf16 v[116:119], v[202:205], v[168:171], v[116:119]
	v_mfma_f32_16x16x32_bf16 v[108:111], v[210:213], v[168:171], v[108:111]
	v_mfma_f32_16x16x32_bf16 v[100:103], v[202:205], v[176:179], v[100:103]
	v_mfma_f32_16x16x32_bf16 v[92:95], v[210:213], v[176:179], v[92:95]
	v_mfma_f32_16x16x32_bf16 v[84:87], v[202:205], v[184:187], v[84:87]
	v_mfma_f32_16x16x32_bf16 v[76:79], v[210:213], v[184:187], v[76:79]
	v_mfma_f32_16x16x32_bf16 v[68:71], v[202:205], v[192:195], v[68:71]
	v_mfma_f32_16x16x32_bf16 v[64:67], v[210:213], v[192:195], v[64:67]
	v_mfma_f32_16x16x32_bf16 v[116:119], v[206:209], v[172:175], v[116:119]
	v_mfma_f32_16x16x32_bf16 v[108:111], v[214:217], v[172:175], v[108:111]
	v_mfma_f32_16x16x32_bf16 v[100:103], v[206:209], v[180:183], v[100:103]
	v_mfma_f32_16x16x32_bf16 v[92:95], v[214:217], v[180:183], v[92:95]
	v_mfma_f32_16x16x32_bf16 v[84:87], v[206:209], v[188:191], v[84:87]
	v_mfma_f32_16x16x32_bf16 v[76:79], v[214:217], v[188:191], v[76:79]
	v_mfma_f32_16x16x32_bf16 v[68:71], v[206:209], v[196:199], v[68:71]
	v_mfma_f32_16x16x32_bf16 v[64:67], v[214:217], v[196:199], v[64:67]
	s_barrier
	s_setprio 0
	s_mov_b32 m0, s21
	v_lshl_add_u64 v[222:223], s[26:27], 0, v[128:129]
	ds_read_b128 v[168:171], v150 offset:16384
	ds_read_b128 v[172:175], v150 offset:17408
	ds_read_b128 v[176:179], v150 offset:18432
	ds_read_b128 v[180:183], v150 offset:19456
	ds_read_b128 v[184:187], v150 offset:20480
	ds_read_b128 v[188:191], v150 offset:21504
	ds_read_b128 v[192:195], v150 offset:22528
	ds_read_b128 v[196:199], v150 offset:23552
	global_load_lds_dwordx4 v128, s[26:27]
	v_lshl_add_u64 v[224:225], s[26:27], 0, v[132:133]
	s_mov_b32 m0, s31
	s_nop 0
	global_load_lds_dwordx4 v132, s[26:27]
	s_setprio 1
	s_barrier
	s_waitcnt lgkmcnt(0)
	v_mfma_f32_16x16x32_bf16 v[60:63], v[152:155], v[168:171], v[60:63]
	v_mfma_f32_16x16x32_bf16 v[56:59], v[160:163], v[168:171], v[56:59]
	v_mfma_f32_16x16x32_bf16 v[48:51], v[152:155], v[176:179], v[48:51]
	v_mfma_f32_16x16x32_bf16 v[40:43], v[160:163], v[176:179], v[40:43]
	v_mfma_f32_16x16x32_bf16 v[32:35], v[152:155], v[184:187], v[32:35]
	v_mfma_f32_16x16x32_bf16 v[24:27], v[160:163], v[184:187], v[24:27]
	v_mfma_f32_16x16x32_bf16 v[16:19], v[152:155], v[192:195], v[16:19]
	v_mfma_f32_16x16x32_bf16 v[8:11], v[160:163], v[192:195], v[8:11]
	v_mfma_f32_16x16x32_bf16 v[60:63], v[156:159], v[172:175], v[60:63]
	v_mfma_f32_16x16x32_bf16 v[56:59], v[164:167], v[172:175], v[56:59]
	v_mfma_f32_16x16x32_bf16 v[48:51], v[156:159], v[180:183], v[48:51]
	v_mfma_f32_16x16x32_bf16 v[40:43], v[164:167], v[180:183], v[40:43]
	v_mfma_f32_16x16x32_bf16 v[32:35], v[156:159], v[188:191], v[32:35]
	v_mfma_f32_16x16x32_bf16 v[24:27], v[164:167], v[188:191], v[24:27]
	v_mfma_f32_16x16x32_bf16 v[16:19], v[156:159], v[196:199], v[16:19]
	v_mfma_f32_16x16x32_bf16 v[8:11], v[164:167], v[196:199], v[8:11]
	s_barrier
	s_setprio 0
	s_add_u32 s54, s24, 0x40000
	s_addc_u32 s55, s25, 0
	s_add_i32 s56, s46, s30
	s_mov_b32 m0, s56
	s_nop 0
	global_load_lds_dwordx4 v130, s[54:55]
	s_add_i32 m0, s56, 0x2000
	s_nop 0
	global_load_lds_dwordx4 v134, s[54:55]
	s_add_u32 s26, s26, 0x40000
	s_addc_u32 s27, s27, 0
	s_mov_b32 m0, s33
	s_nop 0
	global_load_lds_dwordx4 v128, s[26:27]
	s_mov_b32 m0, s34
	s_nop 0
	global_load_lds_dwordx4 v132, s[26:27]
	s_waitcnt vmcnt(10)
	s_setprio 1
	s_barrier
	v_mfma_f32_16x16x32_bf16 v[52:55], v[202:205], v[168:171], v[52:55]
	v_mfma_f32_16x16x32_bf16 v[44:47], v[210:213], v[168:171], v[44:47]
	v_mfma_f32_16x16x32_bf16 v[36:39], v[202:205], v[176:179], v[36:39]
	v_mfma_f32_16x16x32_bf16 v[28:31], v[210:213], v[176:179], v[28:31]
	v_mfma_f32_16x16x32_bf16 v[20:23], v[202:205], v[184:187], v[20:23]
	v_mfma_f32_16x16x32_bf16 v[12:15], v[210:213], v[184:187], v[12:15]
	v_mfma_f32_16x16x32_bf16 v[4:7], v[202:205], v[192:195], v[4:7]
	v_mfma_f32_16x16x32_bf16 v[0:3], v[210:213], v[192:195], v[0:3]
	v_mfma_f32_16x16x32_bf16 v[52:55], v[206:209], v[172:175], v[52:55]
	v_mfma_f32_16x16x32_bf16 v[44:47], v[214:217], v[172:175], v[44:47]
	v_mfma_f32_16x16x32_bf16 v[36:39], v[206:209], v[180:183], v[36:39]
	v_mfma_f32_16x16x32_bf16 v[28:31], v[214:217], v[180:183], v[28:31]
	v_mfma_f32_16x16x32_bf16 v[20:23], v[206:209], v[188:191], v[20:23]
	v_mfma_f32_16x16x32_bf16 v[12:15], v[214:217], v[188:191], v[12:15]
	v_mfma_f32_16x16x32_bf16 v[4:7], v[206:209], v[196:199], v[4:7]
	v_mfma_f32_16x16x32_bf16 v[0:3], v[214:217], v[196:199], v[0:3]
	s_barrier
	s_setprio 0
	s_add_i32 s54, 0, 0x18000
	v_add_u32_e32 v136, s54, v148
	ds_read_b128 v[152:155], v136
	ds_read_b128 v[156:159], v136 offset:1024
	ds_read_b128 v[160:163], v136 offset:2048
	ds_read_b128 v[164:167], v136 offset:3072
	ds_read_b128 v[168:171], v150 offset:32768
	ds_read_b128 v[172:175], v150 offset:33792
	ds_read_b128 v[176:179], v150 offset:34816
	ds_read_b128 v[180:183], v150 offset:35840
	ds_read_b128 v[184:187], v150 offset:36864
	ds_read_b128 v[188:191], v150 offset:37888
	ds_read_b128 v[192:195], v150 offset:38912
	ds_read_b128 v[196:199], v150 offset:39936
	s_waitcnt lgkmcnt(8)
	s_waitcnt vmcnt(8)
	s_setprio 1
	s_barrier
; #define PG8_STAGE(bufoff, gbase, voff) do { _Pragma("unroll") for (int _i = 0; _i < 2; ++_i) \
;         __builtin_amdgcn_global_load_lds((const unsigned*)((const char*)(gbase) + (voff)[_i]), (LAS unsigned*)(lds + (bufoff) + ldsw + _i * 8192), 16, 0, 0); } while (0)
; #define PG8_LDA(dst, b, h) do { _Pragma("unroll") for (int m = 0; m < 4; ++m) _Pragma("unroll") for (int k = 0; k < 2; ++k) dst[m][k] = *(const LAS bf16x8*)(lds + PG8_SA(b, h) + aoff + m * 2048 + k * 1024); } while (0)
; #define PG8_LDB(dst, b, h) do { _Pragma("unroll") for (int n = 0; n < 2; ++n) _Pragma("unroll") for (int k = 0; k < 2; ++k) dst[n][k] = *(const LAS bf16x8*)(lds + PG8_SB(b, h) + boff + n * 2048 + k * 1024); } while (0)
; #define PG8_MMA(ai, bj, At, Bt) do { __builtin_amdgcn_s_setprio(1); _Pragma("unroll") for (int m = 0; m < 4; ++m) _Pragma("unroll") for (int n = 0; n < 2; ++n) _Pragma("unroll") for (int k = 0; k < 2; ++k) \
;         acc[ai][bj][m][n] = __builtin_amdgcn_mfma_f32_16x16x32_bf16(Bt[n][k], At[m][k], acc[ai][bj][m][n], 0, 0, 0); __builtin_amdgcn_s_setprio(0); } while (0)
; #define PG8_WAIT_V(n) asm volatile("s_waitcnt vmcnt(" #n ")" ::: "memory")
; #define PG8_WAIT_L(n) asm volatile("s_waitcnt lgkmcnt(" #n ")" ::: "memory")
; #define PG8_BAR __builtin_amdgcn_s_barrier()
; #define PG8_SCHED __builtin_amdgcn_sched_barrier(0)
; template <class Epi, class Sched>
; __device__ __forceinline__ void gemm_phase(LAS unsigned char* lds, const Gemm g, const Sched& S, const Epi& E) {
;     ...
;             PG8_WAIT_L(8); PG8_BAR; PG8_WAIT_L(0); PG8_MMA(0, 0, At, B0); PG8_BAR; PG8_SCHED;
;             PG8_LDB(B1, 1, 1); PG8_STAGE(PG8_SB(1, 0), b3, voffB);
;             PG8_BAR; PG8_WAIT_L(0); PG8_MMA(0, 1, At, B1); PG8_BAR;
;             PG8_LDA(At, 1, 1); PG8_STAGE(PG8_SA(1, 0), a3, voffA);
;             PG8_BAR; PG8_WAIT_L(0); PG8_MMA(1, 0, At, B0); PG8_BAR; PG8_SCHED;
;             PG8_STAGE(PG8_SB(1, 1), b3 + hstep, voffB);
;             PG8_WAIT_V(6); PG8_BAR; PG8_MMA(1, 1, At, B1); PG8_BAR;
	s_waitcnt lgkmcnt(0)
	v_mfma_f32_16x16x32_bf16 v[124:127], v[152:155], v[168:171], v[124:127]
	v_mfma_f32_16x16x32_bf16 v[120:123], v[160:163], v[168:171], v[120:123]
	v_mfma_f32_16x16x32_bf16 v[112:115], v[152:155], v[176:179], v[112:115]
	v_mfma_f32_16x16x32_bf16 v[104:107], v[160:163], v[176:179], v[104:107]
	v_mfma_f32_16x16x32_bf16 v[96:99], v[152:155], v[184:187], v[96:99]
	v_mfma_f32_16x16x32_bf16 v[88:91], v[160:163], v[184:187], v[88:91]
	v_mfma_f32_16x16x32_bf16 v[80:83], v[152:155], v[192:195], v[80:83]
	v_mfma_f32_16x16x32_bf16 v[72:75], v[160:163], v[192:195], v[72:75]
	v_mfma_f32_16x16x32_bf16 v[124:127], v[156:159], v[172:175], v[124:127]
	v_mfma_f32_16x16x32_bf16 v[120:123], v[164:167], v[172:175], v[120:123]
	v_mfma_f32_16x16x32_bf16 v[112:115], v[156:159], v[180:183], v[112:115]
	v_mfma_f32_16x16x32_bf16 v[104:107], v[164:167], v[180:183], v[104:107]
	v_mfma_f32_16x16x32_bf16 v[96:99], v[156:159], v[188:191], v[96:99]
	v_mfma_f32_16x16x32_bf16 v[88:91], v[164:167], v[188:191], v[88:91]
	v_mfma_f32_16x16x32_bf16 v[80:83], v[156:159], v[196:199], v[80:83]
	v_mfma_f32_16x16x32_bf16 v[72:75], v[164:167], v[196:199], v[72:75]
	s_barrier
	s_setprio 0
	s_add_i32 s26, 0, 0x1c000
	s_add_i32 s27, s54, s30
	v_add_u32_e32 v136, s26, v148
	s_add_u32 s0, s24, 0x80
	s_addc_u32 s1, s25, 0
	s_mov_b32 m0, s27
	ds_read_b128 v[202:205], v136
	ds_read_b128 v[206:209], v136 offset:1024
	ds_read_b128 v[210:213], v136 offset:2048
	ds_read_b128 v[214:217], v136 offset:3072
	global_load_lds_dwordx4 v130, s[0:1]
	s_add_i32 m0, s27, 0x2000
	s_nop 0
	global_load_lds_dwordx4 v134, s[0:1]
	s_waitcnt vmcnt(8)
	s_setprio 1
	s_barrier
	s_waitcnt lgkmcnt(0)
	v_mfma_f32_16x16x32_bf16 v[116:119], v[202:205], v[168:171], v[116:119]
	v_mfma_f32_16x16x32_bf16 v[108:111], v[210:213], v[168:171], v[108:111]
	v_mfma_f32_16x16x32_bf16 v[100:103], v[202:205], v[176:179], v[100:103]
	v_mfma_f32_16x16x32_bf16 v[92:95], v[210:213], v[176:179], v[92:95]
	v_mfma_f32_16x16x32_bf16 v[84:87], v[202:205], v[184:187], v[84:87]
	v_mfma_f32_16x16x32_bf16 v[76:79], v[210:213], v[184:187], v[76:79]
	v_mfma_f32_16x16x32_bf16 v[68:71], v[202:205], v[192:195], v[68:71]
	v_mfma_f32_16x16x32_bf16 v[64:67], v[210:213], v[192:195], v[64:67]
	v_mfma_f32_16x16x32_bf16 v[116:119], v[206:209], v[172:175], v[116:119]
	v_mfma_f32_16x16x32_bf16 v[108:111], v[214:217], v[172:175], v[108:111]
	v_mfma_f32_16x16x32_bf16 v[100:103], v[206:209], v[180:183], v[100:103]
	v_mfma_f32_16x16x32_bf16 v[92:95], v[214:217], v[180:183], v[92:95]
	v_mfma_f32_16x16x32_bf16 v[84:87], v[206:209], v[188:191], v[84:87]
	v_mfma_f32_16x16x32_bf16 v[76:79], v[214:217], v[188:191], v[76:79]
	v_mfma_f32_16x16x32_bf16 v[68:71], v[206:209], v[196:199], v[68:71]
	v_mfma_f32_16x16x32_bf16 v[64:67], v[214:217], v[196:199], v[64:67]
	s_barrier
	s_setprio 0
	s_mov_b32 m0, s42
	s_mov_b64 s[0:1], 0x80
	v_lshl_add_u64 v[218:219], v[222:223], 0, s[0:1]
	ds_read_b128 v[168:171], v150 offset:49152
	ds_read_b128 v[172:175], v150 offset:50176
	ds_read_b128 v[176:179], v150 offset:51200
	ds_read_b128 v[180:183], v150 offset:52224
	ds_read_b128 v[184:187], v150 offset:53248
	ds_read_b128 v[188:191], v150 offset:54272
	ds_read_b128 v[192:195], v150 offset:55296
	ds_read_b128 v[196:199], v150 offset:56320
	global_load_lds_dwordx4 v[218:219], off
	v_lshl_add_u64 v[218:219], v[224:225], 0, s[0:1]
	s_mov_b32 m0, s43
	s_nop 0
	global_load_lds_dwordx4 v[218:219], off
	s_setprio 1
	s_barrier
	s_waitcnt lgkmcnt(0)
	v_mfma_f32_16x16x32_bf16 v[60:63], v[152:155], v[168:171], v[60:63]
	v_mfma_f32_16x16x32_bf16 v[56:59], v[160:163], v[168:171], v[56:59]
	v_mfma_f32_16x16x32_bf16 v[48:51], v[152:155], v[176:179], v[48:51]
	v_mfma_f32_16x16x32_bf16 v[40:43], v[160:163], v[176:179], v[40:43]
	v_mfma_f32_16x16x32_bf16 v[32:35], v[152:155], v[184:187], v[32:35]
	v_mfma_f32_16x16x32_bf16 v[24:27], v[160:163], v[184:187], v[24:27]
	v_mfma_f32_16x16x32_bf16 v[16:19], v[152:155], v[192:195], v[16:19]
	v_mfma_f32_16x16x32_bf16 v[8:11], v[160:163], v[192:195], v[8:11]
	v_mfma_f32_16x16x32_bf16 v[60:63], v[156:159], v[172:175], v[60:63]
	v_mfma_f32_16x16x32_bf16 v[56:59], v[164:167], v[172:175], v[56:59]
	v_mfma_f32_16x16x32_bf16 v[48:51], v[156:159], v[180:183], v[48:51]
	v_mfma_f32_16x16x32_bf16 v[40:43], v[164:167], v[180:183], v[40:43]
	v_mfma_f32_16x16x32_bf16 v[32:35], v[156:159], v[188:191], v[32:35]
	v_mfma_f32_16x16x32_bf16 v[24:27], v[164:167], v[188:191], v[24:27]
	v_mfma_f32_16x16x32_bf16 v[16:19], v[156:159], v[196:199], v[16:19]
	v_mfma_f32_16x16x32_bf16 v[8:11], v[164:167], v[196:199], v[8:11]
	s_barrier
	s_setprio 0
	s_add_u32 s24, s24, 0x40080
	s_addc_u32 s25, s25, 0
	s_add_i32 s26, s26, s30
	s_mov_b32 m0, s26
	s_nop 0
	global_load_lds_dwordx4 v130, s[24:25]
	s_add_i32 m0, s26, 0x2000
	s_nop 0
	global_load_lds_dwordx4 v134, s[24:25]
	s_waitcnt vmcnt(8)
	s_setprio 1
	s_barrier
	v_mfma_f32_16x16x32_bf16 v[52:55], v[202:205], v[168:171], v[52:55]
	v_mfma_f32_16x16x32_bf16 v[44:47], v[210:213], v[168:171], v[44:47]
	v_mfma_f32_16x16x32_bf16 v[36:39], v[202:205], v[176:179], v[36:39]
	v_mfma_f32_16x16x32_bf16 v[28:31], v[210:213], v[176:179], v[28:31]
	v_mfma_f32_16x16x32_bf16 v[20:23], v[202:205], v[184:187], v[20:23]
	v_mfma_f32_16x16x32_bf16 v[12:15], v[210:213], v[184:187], v[12:15]
	v_mfma_f32_16x16x32_bf16 v[4:7], v[202:205], v[192:195], v[4:7]
	v_mfma_f32_16x16x32_bf16 v[0:3], v[210:213], v[192:195], v[0:3]
	v_mfma_f32_16x16x32_bf16 v[52:55], v[206:209], v[172:175], v[52:55]
	v_mfma_f32_16x16x32_bf16 v[44:47], v[214:217], v[172:175], v[44:47]
	v_mfma_f32_16x16x32_bf16 v[36:39], v[206:209], v[180:183], v[36:39]
	v_mfma_f32_16x16x32_bf16 v[28:31], v[214:217], v[180:183], v[28:31]
	v_mfma_f32_16x16x32_bf16 v[20:23], v[206:209], v[188:191], v[20:23]
	v_mfma_f32_16x16x32_bf16 v[12:15], v[214:217], v[188:191], v[12:15]
	v_mfma_f32_16x16x32_bf16 v[4:7], v[206:209], v[196:199], v[4:7]
	v_mfma_f32_16x16x32_bf16 v[0:3], v[214:217], v[196:199], v[0:3]
	s_barrier
; __device__ __forceinline__ unsigned cvt_pk_bf16(float lo, float hi) { unsigned r; asm volatile("v_cvt_pk_bf16_f32 %0, %1, %2" : "=v"(r) : "v"(lo), "v"(hi)); return r; }
; #define PG8_MMA(ai, bj, At, Bt) do { __builtin_amdgcn_s_setprio(1); _Pragma("unroll") for (int m = 0; m < 4; ++m) _Pragma("unroll") for (int n = 0; n < 2; ++n) _Pragma("unroll") for (int k = 0; k < 2; ++k) \
;         acc[ai][bj][m][n] = __builtin_amdgcn_mfma_f32_16x16x32_bf16(Bt[n][k], At[m][k], acc[ai][bj][m][n], 0, 0, 0); __builtin_amdgcn_s_setprio(0); } while (0)
; #define PG8_WAIT_V(n) asm volatile("s_waitcnt vmcnt(" #n ")" ::: "memory")
; #define PG8_BAR __builtin_amdgcn_s_barrier()
; template <class Epi, class Sched>
; __device__ __forceinline__ void gemm_phase(LAS unsigned char* lds, const Gemm g, const Sched& S, const Epi& E) {
;     ...
;             PG8_WAIT_V(6); PG8_BAR; PG8_MMA(1, 1, At, B1); PG8_BAR;
;         }
;         E(acc, cur, wr, wc, fr, fq);
;         if (!has_next) break;
;     __device__ __forceinline__ void operator()(const AccT& acc, const Unit& u, int wr, int wc, int fr, int fq) const {
;     ...
;         const int rbase = u.pm * 256 + wr * 64 + fr;
;         const int tb = u.pn * 256 + wc * 32 + 8 * fq;
; #pragma unroll
;         for (int ai = 0; ai < 2; ++ai)
; #pragma unroll
;             for (int m = 0; m < 4; ++m) {
;                 const int gm = rbase + ai * 128 + m * 16;
; #pragma unroll
;                 for (int bj = 0; bj < 2; ++bj) {
;                     const int t0 = tb + bj * 128;
;                     const f32x4 v0 = acc[ai][bj][m][0], v1 = acc[ai][bj][m][1];
;                     u32x4 w; w.x = cvt_pk_bf16(v0[0], v0[1]); w.y = cvt_pk_bf16(v0[2], v0[3]); w.z = cvt_pk_bf16(v1[0], v1[1]); w.w = cvt_pk_bf16(v1[2], v1[3]);
;                     *(u32x4*)(YT + ((size_t)((t0 >> 10) * 512 + gm)) * 2048 + part * 1024 + (t0 & 1023)) = w;
;                 }
;             }
	s_setprio 0
	s_add_i32 s53, s53, 2
	s_add_u32 s22, s22, 0x100
	s_addc_u32 s23, s23, 0
	s_add_u32 s51, s51, 0x100
	s_addc_u32 s52, s52, 0
	s_cmp_gt_u32 s53, 13
	s_cbranch_scc0 .LBB0_653
	v_mov_b32_e32 v136, v147
	v_mov_b32_e32 v152, v146
	s_lshl_b32 s7, s20, 8
	s_add_i32 s7, s7, s36
	v_add_u32_e32 v152, s7, v152
	s_lshl_b32 s7, s47, 8
	s_or_b32 s7, s7, s37
	v_lshl_add_u32 v153, v136, 3, s7
	v_cvt_pk_bf16_f32 v124, v124, v125
	v_cvt_pk_bf16_f32 v125, v126, v127
	v_cvt_pk_bf16_f32 v126, v120, v121
	v_ashrrev_i32_e32 v120, 1, v153
	v_cvt_pk_bf16_f32 v127, v122, v123
	v_and_b32_e32 v122, 0xfffffe00, v120
	v_add_u32_e32 v120, v122, v152
	v_ashrrev_i32_e32 v121, 31, v120
	v_lshlrev_b64 v[120:121], 12, v[120:121]
	v_and_b32_e32 v123, 0x3f8, v153
	v_lshl_add_u64 v[120:121], s[68:69], 0, v[120:121]
	v_lshlrev_b32_e32 v136, 1, v123
	v_lshl_add_u64 v[120:121], v[120:121], 0, v[136:137]
	global_store_dwordx4 v[120:121], v[124:127], off
	v_add_u32_e32 v120, 0x80, v153
	v_cvt_pk_bf16_f32 v116, v116, v117
	v_cvt_pk_bf16_f32 v117, v118, v119
	v_cvt_pk_bf16_f32 v118, v108, v109
	v_ashrrev_i32_e32 v108, 1, v120
	v_and_b32_e32 v121, 0xfffffe00, v108
	v_add_u32_e32 v108, v121, v152
	v_ashrrev_i32_e32 v109, 31, v108
	v_lshlrev_b64 v[108:109], 12, v[108:109]
	v_cvt_pk_bf16_f32 v119, v110, v111
	v_lshl_add_u64 v[110:111], s[68:69], 0, v[108:109]
	v_and_b32_e32 v108, 0x3f8, v120
	v_lshlrev_b32_e32 v108, 1, v108
	v_mov_b32_e32 v109, v137
	v_lshl_add_u64 v[110:111], v[110:111], 0, v[108:109]
	global_store_dwordx4 v[110:111], v[116:119], off
	v_cvt_pk_bf16_f32 v110, v112, v113
	v_cvt_pk_bf16_f32 v111, v114, v115
	v_cvt_pk_bf16_f32 v112, v104, v105
	v_cvt_pk_bf16_f32 v113, v106, v107
	s_and_b64 vcc, exec, s[4:5]
	s_nop 0
	v_add_u32_e32 v116, 16, v152
	v_add_u32_e32 v104, v122, v116
	v_ashrrev_i32_e32 v105, 31, v104
	v_lshlrev_b64 v[104:105], 12, v[104:105]
	v_lshl_add_u64 v[104:105], s[68:69], 0, v[104:105]
	v_lshl_add_u64 v[104:105], v[104:105], 0, v[136:137]
	global_store_dwordx4 v[104:105], v[110:113], off
	v_cvt_pk_bf16_f32 v100, v100, v101
	v_cvt_pk_bf16_f32 v101, v102, v103
	v_cvt_pk_bf16_f32 v102, v92, v93
	v_add_u32_e32 v92, v121, v116
	v_ashrrev_i32_e32 v93, 31, v92
	v_lshlrev_b64 v[92:93], 12, v[92:93]
	v_lshl_add_u64 v[92:93], s[68:69], 0, v[92:93]
	v_lshl_add_u64 v[92:93], v[92:93], 0, v[108:109]
	v_cvt_pk_bf16_f32 v103, v94, v95
	global_store_dwordx4 v[92:93], v[100:103], off
	v_cvt_pk_bf16_f32 v92, v96, v97
	v_cvt_pk_bf16_f32 v93, v98, v99
	v_cvt_pk_bf16_f32 v94, v88, v89
	v_cvt_pk_bf16_f32 v95, v90, v91
	s_mov_b32 s47, s6
	s_nop 0
	v_add_u32_e32 v100, 32, v152
	v_add_u32_e32 v88, v122, v100
	v_ashrrev_i32_e32 v89, 31, v88
	v_lshlrev_b64 v[88:89], 12, v[88:89]
	v_lshl_add_u64 v[88:89], s[68:69], 0, v[88:89]
	v_lshl_add_u64 v[88:89], v[88:89], 0, v[136:137]
	global_store_dwordx4 v[88:89], v[92:95], off
	v_cvt_pk_bf16_f32 v84, v84, v85
	v_cvt_pk_bf16_f32 v85, v86, v87
	v_cvt_pk_bf16_f32 v86, v76, v77
	v_add_u32_e32 v76, v121, v100
	v_ashrrev_i32_e32 v77, 31, v76
	v_lshlrev_b64 v[76:77], 12, v[76:77]
	v_lshl_add_u64 v[76:77], s[68:69], 0, v[76:77]
	v_lshl_add_u64 v[76:77], v[76:77], 0, v[108:109]
	v_cvt_pk_bf16_f32 v87, v78, v79
	global_store_dwordx4 v[76:77], v[84:87], off
	v_cvt_pk_bf16_f32 v76, v80, v81
	v_cvt_pk_bf16_f32 v77, v82, v83
	v_cvt_pk_bf16_f32 v78, v72, v73
	v_cvt_pk_bf16_f32 v79, v74, v75
	s_mov_b32 s20, s8
	s_nop 0
	v_add_u32_e32 v84, 48, v152
	v_add_u32_e32 v72, v122, v84
	v_ashrrev_i32_e32 v73, 31, v72
	v_lshlrev_b64 v[72:73], 12, v[72:73]
	v_lshl_add_u64 v[72:73], s[68:69], 0, v[72:73]
	v_lshl_add_u64 v[72:73], v[72:73], 0, v[136:137]
	global_store_dwordx4 v[72:73], v[76:79], off
; __device__ __forceinline__ unsigned cvt_pk_bf16(float lo, float hi) { unsigned r; asm volatile("v_cvt_pk_bf16_f32 %0, %1, %2" : "=v"(r) : "v"(lo), "v"(hi)); return r; }
; #define PG8_WAIT_V(n) asm volatile("s_waitcnt vmcnt(" #n ")" ::: "memory")
; #define PG8_BAR __builtin_amdgcn_s_barrier()
; template <class Epi, class Sched>
; __device__ __forceinline__ void gemm_phase(LAS unsigned char* lds, const Gemm g, const Sched& S, const Epi& E) {
;     ...
;         if (!has_next) break;
; #pragma unroll
;         for (int a = 0; a < 2; ++a)
; #pragma unroll
;             for (int b = 0; b < 2; ++b)
; #pragma unroll
;                 for (int m = 0; m < 4; ++m)
; #pragma unroll
;                     for (int n = 0; n < 2; ++n) acc[a][b][m][n] = (f32x4){0.f, 0.f, 0.f, 0.f};
;         cur = nxt; cA = nA; cB = nB; ++ui;
;     }
;     PG8_WAIT_V(0);
;     if (wr == 0) PG8_BAR;
;     PG8_BAR;
;     __device__ __forceinline__ void operator()(const AccT& acc, const Unit& u, int wr, int wc, int fr, int fq) const {
;     ...
;         const int rbase = u.pm * 256 + wr * 64 + fr;
;         const int tb = u.pn * 256 + wc * 32 + 8 * fq;
; #pragma unroll
;         for (int ai = 0; ai < 2; ++ai)
; #pragma unroll
;             for (int m = 0; m < 4; ++m) {
;                 const int gm = rbase + ai * 128 + m * 16;
; #pragma unroll
;                 for (int bj = 0; bj < 2; ++bj) {
;                     const int t0 = tb + bj * 128;
;                     const f32x4 v0 = acc[ai][bj][m][0], v1 = acc[ai][bj][m][1];
;                     u32x4 w; w.x = cvt_pk_bf16(v0[0], v0[1]); w.y = cvt_pk_bf16(v0[2], v0[3]); w.z = cvt_pk_bf16(v1[0], v1[1]); w.w = cvt_pk_bf16(v1[2], v1[3]);
;                     *(u32x4*)(YT + ((size_t)((t0 >> 10) * 512 + gm)) * 2048 + part * 1024 + (t0 & 1023)) = w;
;                 }
;             }
	v_cvt_pk_bf16_f32 v68, v68, v69
	v_cvt_pk_bf16_f32 v69, v70, v71
	v_cvt_pk_bf16_f32 v70, v64, v65
	v_add_u32_e32 v64, v121, v84
	v_ashrrev_i32_e32 v65, 31, v64
	v_lshlrev_b64 v[64:65], 12, v[64:65]
	v_lshl_add_u64 v[64:65], s[68:69], 0, v[64:65]
	v_lshl_add_u64 v[64:65], v[64:65], 0, v[108:109]
	v_cvt_pk_bf16_f32 v71, v66, v67
	global_store_dwordx4 v[64:65], v[68:71], off
	v_add_u32_e32 v64, 0x80, v152
	v_cvt_pk_bf16_f32 v60, v60, v61
	v_cvt_pk_bf16_f32 v61, v62, v63
	v_cvt_pk_bf16_f32 v62, v56, v57
	v_add_u32_e32 v56, v122, v64
	v_ashrrev_i32_e32 v57, 31, v56
	v_lshlrev_b64 v[56:57], 12, v[56:57]
	v_lshl_add_u64 v[56:57], s[68:69], 0, v[56:57]
	v_lshl_add_u64 v[56:57], v[56:57], 0, v[136:137]
	v_cvt_pk_bf16_f32 v63, v58, v59
	global_store_dwordx4 v[56:57], v[60:63], off
	v_cvt_pk_bf16_f32 v52, v52, v53
	v_cvt_pk_bf16_f32 v53, v54, v55
	v_cvt_pk_bf16_f32 v54, v44, v45
	v_add_u32_e32 v44, v121, v64
	v_ashrrev_i32_e32 v45, 31, v44
	v_lshlrev_b64 v[44:45], 12, v[44:45]
	v_lshl_add_u64 v[44:45], s[68:69], 0, v[44:45]
	v_lshl_add_u64 v[44:45], v[44:45], 0, v[108:109]
	v_cvt_pk_bf16_f32 v55, v46, v47
	global_store_dwordx4 v[44:45], v[52:55], off
	v_cvt_pk_bf16_f32 v44, v48, v49
	v_cvt_pk_bf16_f32 v45, v50, v51
	v_cvt_pk_bf16_f32 v46, v40, v41
	v_cvt_pk_bf16_f32 v47, v42, v43
	s_mov_b64 s[24:25], s[18:19]
	s_nop 0
	v_add_u32_e32 v52, 0x90, v152
	v_add_u32_e32 v40, v122, v52
	v_ashrrev_i32_e32 v41, 31, v40
	v_lshlrev_b64 v[40:41], 12, v[40:41]
	v_lshl_add_u64 v[40:41], s[68:69], 0, v[40:41]
	v_lshl_add_u64 v[40:41], v[40:41], 0, v[136:137]
	global_store_dwordx4 v[40:41], v[44:47], off
	v_cvt_pk_bf16_f32 v36, v36, v37
	v_cvt_pk_bf16_f32 v37, v38, v39
	v_cvt_pk_bf16_f32 v38, v28, v29
	v_add_u32_e32 v28, v121, v52
	v_ashrrev_i32_e32 v29, 31, v28
	v_lshlrev_b64 v[28:29], 12, v[28:29]
	v_lshl_add_u64 v[28:29], s[68:69], 0, v[28:29]
	v_lshl_add_u64 v[28:29], v[28:29], 0, v[108:109]
	v_cvt_pk_bf16_f32 v39, v30, v31
	global_store_dwordx4 v[28:29], v[36:39], off
	v_cvt_pk_bf16_f32 v28, v32, v33
	v_cvt_pk_bf16_f32 v29, v34, v35
	v_cvt_pk_bf16_f32 v30, v24, v25
	v_cvt_pk_bf16_f32 v31, v26, v27
	s_mov_b64 s[22:23], s[16:17]
	s_nop 0
	v_add_u32_e32 v36, 0xa0, v152
	v_add_u32_e32 v24, v122, v36
	v_ashrrev_i32_e32 v25, 31, v24
	v_lshlrev_b64 v[24:25], 12, v[24:25]
	v_lshl_add_u64 v[24:25], s[68:69], 0, v[24:25]
	v_lshl_add_u64 v[24:25], v[24:25], 0, v[136:137]
	global_store_dwordx4 v[24:25], v[28:31], off
	v_cvt_pk_bf16_f32 v20, v20, v21
	v_cvt_pk_bf16_f32 v21, v22, v23
	v_cvt_pk_bf16_f32 v22, v12, v13
	v_add_u32_e32 v12, v121, v36
	v_ashrrev_i32_e32 v13, 31, v12
	v_lshlrev_b64 v[12:13], 12, v[12:13]
	v_lshl_add_u64 v[12:13], s[68:69], 0, v[12:13]
	v_lshl_add_u64 v[12:13], v[12:13], 0, v[108:109]
	v_cvt_pk_bf16_f32 v23, v14, v15
	global_store_dwordx4 v[12:13], v[20:23], off
	v_cvt_pk_bf16_f32 v12, v16, v17
	v_cvt_pk_bf16_f32 v13, v18, v19
	v_cvt_pk_bf16_f32 v14, v8, v9
	v_cvt_pk_bf16_f32 v15, v10, v11
	s_nop 1
	v_add_u32_e32 v20, 0xb0, v152
	v_add_u32_e32 v8, v122, v20
	v_ashrrev_i32_e32 v9, 31, v8
	v_lshlrev_b64 v[8:9], 12, v[8:9]
	v_lshl_add_u64 v[8:9], s[68:69], 0, v[8:9]
	v_lshl_add_u64 v[8:9], v[8:9], 0, v[136:137]
	global_store_dwordx4 v[8:9], v[12:15], off
	v_cvt_pk_bf16_f32 v4, v4, v5
	v_cvt_pk_bf16_f32 v5, v6, v7
	v_cvt_pk_bf16_f32 v6, v0, v1
	v_add_u32_e32 v0, v121, v20
	v_ashrrev_i32_e32 v1, 31, v0
	v_lshlrev_b64 v[0:1], 12, v[0:1]
	v_lshl_add_u64 v[0:1], s[68:69], 0, v[0:1]
	v_lshl_add_u64 v[0:1], v[0:1], 0, v[108:109]
	v_cvt_pk_bf16_f32 v7, v2, v3
	global_store_dwordx4 v[0:1], v[4:7], off
	s_cbranch_vccz .LBB0_646
	s_waitcnt vmcnt(0)
	s_cmpk_gt_u32 s28, 0xff
	s_cbranch_scc1 .LBB0_657
	s_barrier

; #define PG8_STAGE(bufoff, gbase, voff) do { _Pragma("unroll") for (int _i = 0; _i < 2; ++_i) \
;         __builtin_amdgcn_global_load_lds((const unsigned*)((const char*)(gbase) + (voff)[_i]), (LAS unsigned*)(lds + (bufoff) + ldsw + _i * 8192), 16, 0, 0); } while (0)
; #define PG8_LDA(dst, b, h) do { _Pragma("unroll") for (int m = 0; m < 4; ++m) _Pragma("unroll") for (int k = 0; k < 2; ++k) dst[m][k] = *(const LAS bf16x8*)(lds + PG8_SA(b, h) + aoff + m * 2048 + k * 1024); } while (0)
; #define PG8_LDB(dst, b, h) do { _Pragma("unroll") for (int n = 0; n < 2; ++n) _Pragma("unroll") for (int k = 0; k < 2; ++k) dst[n][k] = *(const LAS bf16x8*)(lds + PG8_SB(b, h) + boff + n * 2048 + k * 1024); } while (0)
; #define PG8_MMA(ai, bj, At, Bt) do { __builtin_amdgcn_s_setprio(1); _Pragma("unroll") for (int m = 0; m < 4; ++m) _Pragma("unroll") for (int n = 0; n < 2; ++n) _Pragma("unroll") for (int k = 0; k < 2; ++k) \
;         acc[ai][bj][m][n] = __builtin_amdgcn_mfma_f32_16x16x32_bf16(Bt[n][k], At[m][k], acc[ai][bj][m][n], 0, 0, 0); __builtin_amdgcn_s_setprio(0); } while (0)
; #define PG8_WAIT_L(n) asm volatile("s_waitcnt lgkmcnt(" #n ")" ::: "memory")
; template <class Epi, class Sched>
; __device__ __forceinline__ void gemm_phase(LAS unsigned char* lds, const Gemm g, const Sched& S, const Epi& E) {
;     ...
;         const bool has_next = S.next(ui + 1, nxt);
;         const char* nA = has_next ? (const char*)g.A + (size_t)nxt.pm * tstep : cA; const char* nB = has_next ? (const char*)g.Bt + (size_t)nxt.pn * tstep : cB;
;         for (int t = 0; t < nt; t += 2) {
;             const bool last = (t == nt - 2);
;             const char* a1 = cA + (size_t)(t + 1) * kstep;
;             const char* a2 = last ? nA : cA + (size_t)(t + 2) * kstep; const char* b2 = last ? nB : cB + (size_t)(t + 2) * kstep;
;             const char* a3 = a2 + kstep; const char* b3 = b2 + kstep;
;             PG8_LDB(B0, 0, 0); PG8_SCHED; PG8_LDA(At, 0, 0); PG8_STAGE(PG8_SA(1, 1), a1 + hstep, voffA);
;             PG8_WAIT_L(8); PG8_BAR; PG8_WAIT_L(0); PG8_MMA(0, 0, At, B0); PG8_BAR; PG8_SCHED;
;             PG8_LDB(B1, 0, 1); PG8_STAGE(PG8_SB(0, 0), b2, voffB);
;             PG8_BAR; PG8_WAIT_L(0); PG8_MMA(0, 1, At, B1); PG8_BAR;
;             PG8_LDA(At, 0, 1); PG8_STAGE(PG8_SA(0, 0), a2, voffA);
;             PG8_BAR; PG8_WAIT_L(0); PG8_MMA(1, 0, At, B0); PG8_BAR; PG8_SCHED;
.LBB0_672:
	s_ashr_i32 s9, s8, 31
	v_cmp_lt_i64_e32 vcc, s[12:13], v[142:143]
	s_lshl_b64 s[12:13], s[8:9], 19
	s_add_u32 s12, s26, s12
	s_addc_u32 s13, s27, s13
	s_and_b64 s[14:15], vcc, exec
	s_cselect_b32 s9, s13, s19
	s_cselect_b32 s46, s12, s18
	s_ashr_i32 s7, s6, 31
	s_lshl_b64 s[14:15], s[6:7], 19
	s_add_u32 s14, s10, s14
	s_addc_u32 s15, s11, s15
	s_and_b64 s[22:23], vcc, exec
	s_cselect_b32 s7, s15, s21
	s_cselect_b32 s47, s14, s20
	s_add_u32 s18, s18, 0x40080
	s_addc_u32 s19, s19, 0
	s_add_u32 s48, s20, 0x100
	s_addc_u32 s49, s21, 0
	s_mov_b32 s51, -2
	s_waitcnt lgkmcnt(0)
	ds_read_b128 v[152:155], v149
	ds_read_b128 v[156:159], v149 offset:1024
	ds_read_b128 v[160:163], v149 offset:2048
	ds_read_b128 v[164:167], v149 offset:3072
	s_add_u32 s20, s18, 0xfffc0080
	s_addc_u32 s21, s19, -1
	s_cmp_eq_u32 s51, 12
	s_cselect_b32 s23, s9, s21
	s_cselect_b32 s22, s46, s20
	s_cselect_b32 s21, s7, s49
	s_cselect_b32 s20, s47, s48
	s_add_i32 m0, s17, 0xc000
	ds_read_b128 v[168:171], v150
	ds_read_b128 v[172:175], v150 offset:1024
	ds_read_b128 v[176:179], v150 offset:2048
	ds_read_b128 v[180:183], v150 offset:3072
	ds_read_b128 v[184:187], v150 offset:4096
	ds_read_b128 v[188:191], v150 offset:5120
	ds_read_b128 v[192:195], v150 offset:6144
	ds_read_b128 v[196:199], v150 offset:7168
	global_load_lds_dwordx4 v138, s[18:19]
	s_add_i32 m0, s17, 0xe000
	s_nop 0
	global_load_lds_dwordx4 v140, s[18:19]
	s_waitcnt lgkmcnt(8)
	s_waitcnt vmcnt(8)
	s_setprio 1
	s_barrier
	s_waitcnt lgkmcnt(0)
	v_mfma_f32_16x16x32_bf16 v[124:127], v[152:155], v[168:171], 0
	v_mfma_f32_16x16x32_bf16 v[120:123], v[160:163], v[168:171], 0
	v_mfma_f32_16x16x32_bf16 v[112:115], v[152:155], v[176:179], 0
	v_mfma_f32_16x16x32_bf16 v[104:107], v[160:163], v[176:179], 0
	v_mfma_f32_16x16x32_bf16 v[96:99], v[152:155], v[184:187], 0
	v_mfma_f32_16x16x32_bf16 v[88:91], v[160:163], v[184:187], 0
	v_mfma_f32_16x16x32_bf16 v[80:83], v[152:155], v[192:195], 0
	v_mfma_f32_16x16x32_bf16 v[72:75], v[160:163], v[192:195], 0
	v_mfma_f32_16x16x32_bf16 v[124:127], v[156:159], v[172:175], v[124:127]
	v_mfma_f32_16x16x32_bf16 v[120:123], v[164:167], v[172:175], v[120:123]
	v_mfma_f32_16x16x32_bf16 v[112:115], v[156:159], v[180:183], v[112:115]
	v_mfma_f32_16x16x32_bf16 v[104:107], v[164:167], v[180:183], v[104:107]
	v_mfma_f32_16x16x32_bf16 v[96:99], v[156:159], v[188:191], v[96:99]
	v_mfma_f32_16x16x32_bf16 v[88:91], v[164:167], v[188:191], v[88:91]
	v_mfma_f32_16x16x32_bf16 v[80:83], v[156:159], v[196:199], v[80:83]
	v_mfma_f32_16x16x32_bf16 v[72:75], v[164:167], v[196:199], v[72:75]
	s_barrier
	s_setprio 0
	s_add_i32 s52, s43, s28
	s_mov_b32 m0, s52
	ds_read_b128 v[202:205], v151
	ds_read_b128 v[206:209], v151 offset:1024
	ds_read_b128 v[210:213], v151 offset:2048
	ds_read_b128 v[214:217], v151 offset:3072
	global_load_lds_dwordx4 v130, s[20:21]
	s_add_i32 m0, s52, 0x2000
	s_nop 0
	global_load_lds_dwordx4 v134, s[20:21]
	s_waitcnt vmcnt(8)
	s_setprio 1
	s_barrier
	s_waitcnt lgkmcnt(0)
	v_mfma_f32_16x16x32_bf16 v[116:119], v[202:205], v[168:171], 0
	v_mfma_f32_16x16x32_bf16 v[108:111], v[210:213], v[168:171], 0
	v_mfma_f32_16x16x32_bf16 v[100:103], v[202:205], v[176:179], 0
	v_mfma_f32_16x16x32_bf16 v[92:95], v[210:213], v[176:179], 0
	v_mfma_f32_16x16x32_bf16 v[84:87], v[202:205], v[184:187], 0
	v_mfma_f32_16x16x32_bf16 v[76:79], v[210:213], v[184:187], 0
	v_mfma_f32_16x16x32_bf16 v[68:71], v[202:205], v[192:195], 0
	v_mfma_f32_16x16x32_bf16 v[64:67], v[210:213], v[192:195], 0
	v_mfma_f32_16x16x32_bf16 v[116:119], v[206:209], v[172:175], v[116:119]
	v_mfma_f32_16x16x32_bf16 v[108:111], v[214:217], v[172:175], v[108:111]
	v_mfma_f32_16x16x32_bf16 v[100:103], v[206:209], v[180:183], v[100:103]
	v_mfma_f32_16x16x32_bf16 v[92:95], v[214:217], v[180:183], v[92:95]
	v_mfma_f32_16x16x32_bf16 v[84:87], v[206:209], v[188:191], v[84:87]
	v_mfma_f32_16x16x32_bf16 v[76:79], v[214:217], v[188:191], v[76:79]
	v_mfma_f32_16x16x32_bf16 v[68:71], v[206:209], v[196:199], v[68:71]
	v_mfma_f32_16x16x32_bf16 v[64:67], v[214:217], v[196:199], v[64:67]
	s_barrier
	s_setprio 0
	s_mov_b32 m0, s17
	v_lshl_add_u64 v[222:223], s[22:23], 0, v[128:129]
	ds_read_b128 v[168:171], v150 offset:16384
	ds_read_b128 v[172:175], v150 offset:17408
	ds_read_b128 v[176:179], v150 offset:18432
	ds_read_b128 v[180:183], v150 offset:19456
	ds_read_b128 v[184:187], v150 offset:20480
	ds_read_b128 v[188:191], v150 offset:21504
	ds_read_b128 v[192:195], v150 offset:22528
	ds_read_b128 v[196:199], v150 offset:23552
	global_load_lds_dwordx4 v128, s[22:23]
	v_lshl_add_u64 v[224:225], s[22:23], 0, v[132:133]
	s_mov_b32 m0, s29
	s_nop 0
	global_load_lds_dwordx4 v132, s[22:23]
	s_setprio 1
	s_barrier
	s_waitcnt lgkmcnt(0)
	v_mfma_f32_16x16x32_bf16 v[60:63], v[152:155], v[168:171], 0
	v_mfma_f32_16x16x32_bf16 v[56:59], v[160:163], v[168:171], 0
	v_mfma_f32_16x16x32_bf16 v[48:51], v[152:155], v[176:179], 0
	v_mfma_f32_16x16x32_bf16 v[40:43], v[160:163], v[176:179], 0
	v_mfma_f32_16x16x32_bf16 v[32:35], v[152:155], v[184:187], 0
	v_mfma_f32_16x16x32_bf16 v[24:27], v[160:163], v[184:187], 0
	v_mfma_f32_16x16x32_bf16 v[16:19], v[152:155], v[192:195], 0
	v_mfma_f32_16x16x32_bf16 v[8:11], v[160:163], v[192:195], 0
	v_mfma_f32_16x16x32_bf16 v[60:63], v[156:159], v[172:175], v[60:63]
	v_mfma_f32_16x16x32_bf16 v[56:59], v[164:167], v[172:175], v[56:59]
	v_mfma_f32_16x16x32_bf16 v[48:51], v[156:159], v[180:183], v[48:51]
	v_mfma_f32_16x16x32_bf16 v[40:43], v[164:167], v[180:183], v[40:43]
	v_mfma_f32_16x16x32_bf16 v[32:35], v[156:159], v[188:191], v[32:35]
	v_mfma_f32_16x16x32_bf16 v[24:27], v[164:167], v[188:191], v[24:27]
	v_mfma_f32_16x16x32_bf16 v[16:19], v[156:159], v[196:199], v[16:19]
	v_mfma_f32_16x16x32_bf16 v[8:11], v[164:167], v[196:199], v[8:11]
	s_barrier
; #define PG8_STAGE(bufoff, gbase, voff) do { _Pragma("unroll") for (int _i = 0; _i < 2; ++_i) \
;         __builtin_amdgcn_global_load_lds((const unsigned*)((const char*)(gbase) + (voff)[_i]), (LAS unsigned*)(lds + (bufoff) + ldsw + _i * 8192), 16, 0, 0); } while (0)
; #define PG8_LDA(dst, b, h) do { _Pragma("unroll") for (int m = 0; m < 4; ++m) _Pragma("unroll") for (int k = 0; k < 2; ++k) dst[m][k] = *(const LAS bf16x8*)(lds + PG8_SA(b, h) + aoff + m * 2048 + k * 1024); } while (0)
; #define PG8_LDB(dst, b, h) do { _Pragma("unroll") for (int n = 0; n < 2; ++n) _Pragma("unroll") for (int k = 0; k < 2; ++k) dst[n][k] = *(const LAS bf16x8*)(lds + PG8_SB(b, h) + boff + n * 2048 + k * 1024); } while (0)
; #define PG8_MMA(ai, bj, At, Bt) do { __builtin_amdgcn_s_setprio(1); _Pragma("unroll") for (int m = 0; m < 4; ++m) _Pragma("unroll") for (int n = 0; n < 2; ++n) _Pragma("unroll") for (int k = 0; k < 2; ++k) \
;         acc[ai][bj][m][n] = __builtin_amdgcn_mfma_f32_16x16x32_bf16(Bt[n][k], At[m][k], acc[ai][bj][m][n], 0, 0, 0); __builtin_amdgcn_s_setprio(0); } while (0)
; #define PG8_WAIT_V(n) asm volatile("s_waitcnt vmcnt(" #n ")" ::: "memory")
; #define PG8_WAIT_L(n) asm volatile("s_waitcnt lgkmcnt(" #n ")" ::: "memory")
; #define PG8_BAR __builtin_amdgcn_s_barrier()
; #define PG8_SCHED __builtin_amdgcn_sched_barrier(0)
; template <class Epi, class Sched>
; __device__ __forceinline__ void gemm_phase(LAS unsigned char* lds, const Gemm g, const Sched& S, const Epi& E) {
;     ...
;             PG8_STAGE(PG8_SB(0, 1), b2 + hstep, voffB);
;             PG8_WAIT_V(6); PG8_BAR; PG8_MMA(1, 1, At, B1); PG8_BAR;
;             PG8_LDB(B0, 1, 0); PG8_SCHED; PG8_LDA(At, 1, 0); PG8_STAGE(PG8_SA(0, 1), a2 + hstep, voffA);
;             PG8_WAIT_L(8); PG8_BAR; PG8_WAIT_L(0); PG8_MMA(0, 0, At, B0); PG8_BAR; PG8_SCHED;
;             PG8_LDB(B1, 1, 1); PG8_STAGE(PG8_SB(1, 0), b3, voffB);
;             PG8_BAR; PG8_WAIT_L(0); PG8_MMA(0, 1, At, B1); PG8_BAR;
;             PG8_LDA(At, 1, 1); PG8_STAGE(PG8_SA(1, 0), a3, voffA);
	s_setprio 0
	s_add_u32 s52, s20, 0x40000
	s_addc_u32 s53, s21, 0
	s_add_i32 s54, s44, s28
	s_mov_b32 m0, s54
	s_nop 0
	global_load_lds_dwordx4 v130, s[52:53]
	s_add_i32 m0, s54, 0x2000
	s_nop 0
	global_load_lds_dwordx4 v134, s[52:53]
	s_add_u32 s22, s22, 0x40000
	s_addc_u32 s23, s23, 0
	s_mov_b32 m0, s30
	s_nop 0
	global_load_lds_dwordx4 v128, s[22:23]
	s_mov_b32 m0, s31
	s_nop 0
	global_load_lds_dwordx4 v132, s[22:23]
	s_waitcnt vmcnt(10)
	s_setprio 1
	s_barrier
	v_mfma_f32_16x16x32_bf16 v[52:55], v[202:205], v[168:171], 0
	v_mfma_f32_16x16x32_bf16 v[44:47], v[210:213], v[168:171], 0
	v_mfma_f32_16x16x32_bf16 v[36:39], v[202:205], v[176:179], 0
	v_mfma_f32_16x16x32_bf16 v[28:31], v[210:213], v[176:179], 0
	v_mfma_f32_16x16x32_bf16 v[20:23], v[202:205], v[184:187], 0
	v_mfma_f32_16x16x32_bf16 v[12:15], v[210:213], v[184:187], 0
	v_mfma_f32_16x16x32_bf16 v[4:7], v[202:205], v[192:195], 0
	v_mfma_f32_16x16x32_bf16 v[0:3], v[210:213], v[192:195], 0
	v_mfma_f32_16x16x32_bf16 v[52:55], v[206:209], v[172:175], v[52:55]
	v_mfma_f32_16x16x32_bf16 v[44:47], v[214:217], v[172:175], v[44:47]
	v_mfma_f32_16x16x32_bf16 v[36:39], v[206:209], v[180:183], v[36:39]
	v_mfma_f32_16x16x32_bf16 v[28:31], v[214:217], v[180:183], v[28:31]
	v_mfma_f32_16x16x32_bf16 v[20:23], v[206:209], v[188:191], v[20:23]
	v_mfma_f32_16x16x32_bf16 v[12:15], v[214:217], v[188:191], v[12:15]
	v_mfma_f32_16x16x32_bf16 v[4:7], v[206:209], v[196:199], v[4:7]
	v_mfma_f32_16x16x32_bf16 v[0:3], v[214:217], v[196:199], v[0:3]
	s_barrier
	s_setprio 0
	s_add_i32 s52, 0, 0x18000
	v_add_u32_e32 v136, s52, v148
	ds_read_b128 v[152:155], v136
	ds_read_b128 v[156:159], v136 offset:1024
	ds_read_b128 v[160:163], v136 offset:2048
	ds_read_b128 v[164:167], v136 offset:3072
	ds_read_b128 v[168:171], v150 offset:32768
	ds_read_b128 v[172:175], v150 offset:33792
	ds_read_b128 v[176:179], v150 offset:34816
	ds_read_b128 v[180:183], v150 offset:35840
	ds_read_b128 v[184:187], v150 offset:36864
	ds_read_b128 v[188:191], v150 offset:37888
	ds_read_b128 v[192:195], v150 offset:38912
	ds_read_b128 v[196:199], v150 offset:39936
	s_waitcnt lgkmcnt(8)
	s_waitcnt vmcnt(8)
	s_setprio 1
	s_barrier
	s_waitcnt lgkmcnt(0)
	v_mfma_f32_16x16x32_bf16 v[124:127], v[152:155], v[168:171], v[124:127]
	v_mfma_f32_16x16x32_bf16 v[120:123], v[160:163], v[168:171], v[120:123]
	v_mfma_f32_16x16x32_bf16 v[112:115], v[152:155], v[176:179], v[112:115]
	v_mfma_f32_16x16x32_bf16 v[104:107], v[160:163], v[176:179], v[104:107]
	v_mfma_f32_16x16x32_bf16 v[96:99], v[152:155], v[184:187], v[96:99]
	v_mfma_f32_16x16x32_bf16 v[88:91], v[160:163], v[184:187], v[88:91]
	v_mfma_f32_16x16x32_bf16 v[80:83], v[152:155], v[192:195], v[80:83]
	v_mfma_f32_16x16x32_bf16 v[72:75], v[160:163], v[192:195], v[72:75]
	v_mfma_f32_16x16x32_bf16 v[124:127], v[156:159], v[172:175], v[124:127]
	v_mfma_f32_16x16x32_bf16 v[120:123], v[164:167], v[172:175], v[120:123]
	v_mfma_f32_16x16x32_bf16 v[112:115], v[156:159], v[180:183], v[112:115]
	v_mfma_f32_16x16x32_bf16 v[104:107], v[164:167], v[180:183], v[104:107]
	v_mfma_f32_16x16x32_bf16 v[96:99], v[156:159], v[188:191], v[96:99]
	v_mfma_f32_16x16x32_bf16 v[88:91], v[164:167], v[188:191], v[88:91]
	v_mfma_f32_16x16x32_bf16 v[80:83], v[156:159], v[196:199], v[80:83]
	v_mfma_f32_16x16x32_bf16 v[72:75], v[164:167], v[196:199], v[72:75]
	s_barrier
	s_setprio 0
	s_add_i32 s22, 0, 0x1c000
	s_add_i32 s23, s52, s28
	v_add_u32_e32 v136, s22, v148
	s_add_u32 s0, s20, 0x80
	s_addc_u32 s1, s21, 0
	s_mov_b32 m0, s23
	ds_read_b128 v[202:205], v136
	ds_read_b128 v[206:209], v136 offset:1024
	ds_read_b128 v[210:213], v136 offset:2048
	ds_read_b128 v[214:217], v136 offset:3072
	global_load_lds_dwordx4 v130, s[0:1]
	s_add_i32 m0, s23, 0x2000
	s_nop 0
	global_load_lds_dwordx4 v134, s[0:1]
	s_waitcnt vmcnt(8)
	s_setprio 1
	s_barrier
	s_waitcnt lgkmcnt(0)
	v_mfma_f32_16x16x32_bf16 v[116:119], v[202:205], v[168:171], v[116:119]
	v_mfma_f32_16x16x32_bf16 v[108:111], v[210:213], v[168:171], v[108:111]
	v_mfma_f32_16x16x32_bf16 v[100:103], v[202:205], v[176:179], v[100:103]
	v_mfma_f32_16x16x32_bf16 v[92:95], v[210:213], v[176:179], v[92:95]
	v_mfma_f32_16x16x32_bf16 v[84:87], v[202:205], v[184:187], v[84:87]
	v_mfma_f32_16x16x32_bf16 v[76:79], v[210:213], v[184:187], v[76:79]
	v_mfma_f32_16x16x32_bf16 v[68:71], v[202:205], v[192:195], v[68:71]
	v_mfma_f32_16x16x32_bf16 v[64:67], v[210:213], v[192:195], v[64:67]
	v_mfma_f32_16x16x32_bf16 v[116:119], v[206:209], v[172:175], v[116:119]
	v_mfma_f32_16x16x32_bf16 v[108:111], v[214:217], v[172:175], v[108:111]
	v_mfma_f32_16x16x32_bf16 v[100:103], v[206:209], v[180:183], v[100:103]
	v_mfma_f32_16x16x32_bf16 v[92:95], v[214:217], v[180:183], v[92:95]
	v_mfma_f32_16x16x32_bf16 v[84:87], v[206:209], v[188:191], v[84:87]
	v_mfma_f32_16x16x32_bf16 v[76:79], v[214:217], v[188:191], v[76:79]
	v_mfma_f32_16x16x32_bf16 v[68:71], v[206:209], v[196:199], v[68:71]
	v_mfma_f32_16x16x32_bf16 v[64:67], v[214:217], v[196:199], v[64:67]
	s_barrier
	s_setprio 0
	s_mov_b32 m0, s36
	s_mov_b64 s[0:1], 0x80
	v_lshl_add_u64 v[218:219], v[222:223], 0, s[0:1]
	ds_read_b128 v[168:171], v150 offset:49152
	ds_read_b128 v[172:175], v150 offset:50176
	ds_read_b128 v[176:179], v150 offset:51200
	ds_read_b128 v[180:183], v150 offset:52224
	ds_read_b128 v[184:187], v150 offset:53248
	ds_read_b128 v[188:191], v150 offset:54272
	ds_read_b128 v[192:195], v150 offset:55296
	ds_read_b128 v[196:199], v150 offset:56320
	global_load_lds_dwordx4 v[218:219], off
	v_lshl_add_u64 v[218:219], v[224:225], 0, s[0:1]
	s_mov_b32 m0, s37
	s_nop 0
	global_load_lds_dwordx4 v[218:219], off
	s_setprio 1
	s_barrier
; #define PG8_STAGE(bufoff, gbase, voff) do { _Pragma("unroll") for (int _i = 0; _i < 2; ++_i) \
;         __builtin_amdgcn_global_load_lds((const unsigned*)((const char*)(gbase) + (voff)[_i]), (LAS unsigned*)(lds + (bufoff) + ldsw + _i * 8192), 16, 0, 0); } while (0)
; #define PG8_LDA(dst, b, h) do { _Pragma("unroll") for (int m = 0; m < 4; ++m) _Pragma("unroll") for (int k = 0; k < 2; ++k) dst[m][k] = *(const LAS bf16x8*)(lds + PG8_SA(b, h) + aoff + m * 2048 + k * 1024); } while (0)
; #define PG8_WAIT_V(n) asm volatile("s_waitcnt vmcnt(" #n ")" ::: "memory")
; #define PG8_WAIT_L(n) asm volatile("s_waitcnt lgkmcnt(" #n ")" ::: "memory")
; template <class Epi, class Sched>
; __device__ __forceinline__ void gemm_phase(LAS unsigned char* lds, const Gemm g, const Sched& S, const Epi& E) {
;     ...
;         for (int t = 0; t < nt; t += 2) {
;             const bool last = (t == nt - 2);
;             const char* a1 = cA + (size_t)(t + 1) * kstep;
;             const char* a2 = last ? nA : cA + (size_t)(t + 2) * kstep; const char* b2 = last ? nB : cB + (size_t)(t + 2) * kstep;
;             const char* a3 = a2 + kstep; const char* b3 = b2 + kstep;
;             PG8_LDB(B0, 0, 0); PG8_SCHED; PG8_LDA(At, 0, 0); PG8_STAGE(PG8_SA(1, 1), a1 + hstep, voffA);
;             PG8_WAIT_L(8); PG8_BAR; PG8_WAIT_L(0); PG8_MMA(0, 0, At, B0); PG8_BAR; PG8_SCHED;
;             PG8_LDB(B1, 0, 1); PG8_STAGE(PG8_SB(0, 0), b2, voffB);
;             PG8_BAR; PG8_WAIT_L(0); PG8_MMA(0, 1, At, B1); PG8_BAR;
;             PG8_LDA(At, 0, 1); PG8_STAGE(PG8_SA(0, 0), a2, voffA);
;             PG8_BAR; PG8_WAIT_L(0); PG8_MMA(1, 0, At, B0); PG8_BAR; PG8_SCHED;
;             PG8_STAGE(PG8_SB(0, 1), b2 + hstep, voffB);
;             PG8_WAIT_V(6); PG8_BAR; PG8_MMA(1, 1, At, B1); PG8_BAR;
;             PG8_LDB(B0, 1, 0); PG8_SCHED; PG8_LDA(At, 1, 0); PG8_STAGE(PG8_SA(0, 1), a2 + hstep, voffA);
;             PG8_WAIT_L(8); PG8_BAR; PG8_WAIT_L(0); PG8_MMA(0, 0, At, B0); PG8_BAR; PG8_SCHED;
;             PG8_LDB(B1, 1, 1); PG8_STAGE(PG8_SB(1, 0), b3, voffB);
;             PG8_BAR; PG8_WAIT_L(0); PG8_MMA(0, 1, At, B1); PG8_BAR;
;             PG8_LDA(At, 1, 1); PG8_STAGE(PG8_SA(1, 0), a3, voffA);
;             PG8_BAR; PG8_WAIT_L(0); PG8_MMA(1, 0, At, B0); PG8_BAR; PG8_SCHED;
;             PG8_STAGE(PG8_SB(1, 1), b3 + hstep, voffB);
;             PG8_WAIT_V(6); PG8_BAR; PG8_MMA(1, 1, At, B1); PG8_BAR;
	s_waitcnt lgkmcnt(0)
	v_mfma_f32_16x16x32_bf16 v[60:63], v[152:155], v[168:171], v[60:63]
	v_mfma_f32_16x16x32_bf16 v[56:59], v[160:163], v[168:171], v[56:59]
	v_mfma_f32_16x16x32_bf16 v[48:51], v[152:155], v[176:179], v[48:51]
	v_mfma_f32_16x16x32_bf16 v[40:43], v[160:163], v[176:179], v[40:43]
	v_mfma_f32_16x16x32_bf16 v[32:35], v[152:155], v[184:187], v[32:35]
	v_mfma_f32_16x16x32_bf16 v[24:27], v[160:163], v[184:187], v[24:27]
	v_mfma_f32_16x16x32_bf16 v[16:19], v[152:155], v[192:195], v[16:19]
	v_mfma_f32_16x16x32_bf16 v[8:11], v[160:163], v[192:195], v[8:11]
	v_mfma_f32_16x16x32_bf16 v[60:63], v[156:159], v[172:175], v[60:63]
	v_mfma_f32_16x16x32_bf16 v[56:59], v[164:167], v[172:175], v[56:59]
	v_mfma_f32_16x16x32_bf16 v[48:51], v[156:159], v[180:183], v[48:51]
	v_mfma_f32_16x16x32_bf16 v[40:43], v[164:167], v[180:183], v[40:43]
	v_mfma_f32_16x16x32_bf16 v[32:35], v[156:159], v[188:191], v[32:35]
	v_mfma_f32_16x16x32_bf16 v[24:27], v[164:167], v[188:191], v[24:27]
	v_mfma_f32_16x16x32_bf16 v[16:19], v[156:159], v[196:199], v[16:19]
	v_mfma_f32_16x16x32_bf16 v[8:11], v[164:167], v[196:199], v[8:11]
	s_barrier
	s_setprio 0
	s_add_u32 s20, s20, 0x40080
	s_addc_u32 s21, s21, 0
	s_add_i32 s22, s22, s28
	s_mov_b32 m0, s22
	s_nop 0
	global_load_lds_dwordx4 v130, s[20:21]
	s_add_i32 m0, s22, 0x2000
	s_nop 0
	global_load_lds_dwordx4 v134, s[20:21]
	s_waitcnt vmcnt(8)
	s_setprio 1
	s_barrier
	v_mfma_f32_16x16x32_bf16 v[52:55], v[202:205], v[168:171], v[52:55]
	v_mfma_f32_16x16x32_bf16 v[44:47], v[210:213], v[168:171], v[44:47]
	v_mfma_f32_16x16x32_bf16 v[36:39], v[202:205], v[176:179], v[36:39]
	v_mfma_f32_16x16x32_bf16 v[28:31], v[210:213], v[176:179], v[28:31]
	v_mfma_f32_16x16x32_bf16 v[20:23], v[202:205], v[184:187], v[20:23]
	v_mfma_f32_16x16x32_bf16 v[12:15], v[210:213], v[184:187], v[12:15]
	v_mfma_f32_16x16x32_bf16 v[4:7], v[202:205], v[192:195], v[4:7]
	v_mfma_f32_16x16x32_bf16 v[0:3], v[210:213], v[192:195], v[0:3]
	v_mfma_f32_16x16x32_bf16 v[52:55], v[206:209], v[172:175], v[52:55]
	v_mfma_f32_16x16x32_bf16 v[44:47], v[214:217], v[172:175], v[44:47]
	v_mfma_f32_16x16x32_bf16 v[36:39], v[206:209], v[180:183], v[36:39]
	v_mfma_f32_16x16x32_bf16 v[28:31], v[214:217], v[180:183], v[28:31]
	v_mfma_f32_16x16x32_bf16 v[20:23], v[206:209], v[188:191], v[20:23]
	v_mfma_f32_16x16x32_bf16 v[12:15], v[214:217], v[188:191], v[12:15]
	v_mfma_f32_16x16x32_bf16 v[4:7], v[206:209], v[196:199], v[4:7]
	v_mfma_f32_16x16x32_bf16 v[0:3], v[214:217], v[196:199], v[0:3]
	s_barrier
	s_setprio 0
	s_add_i32 s51, s51, 2
	s_add_u32 s18, s18, 0x100
	s_addc_u32 s19, s19, 0
	s_add_u32 s48, s48, 0x100
	s_addc_u32 s49, s49, 0
	s_cmp_gt_u32 s51, 13
.LBB0_673:
	ds_read_b128 v[152:155], v149
	ds_read_b128 v[156:159], v149 offset:1024
	ds_read_b128 v[160:163], v149 offset:2048
	ds_read_b128 v[164:167], v149 offset:3072
	s_add_u32 s20, s18, 0xfffc0080
	s_addc_u32 s21, s19, -1
	s_cmp_eq_u32 s51, 12
	s_cselect_b32 s23, s9, s21
	s_cselect_b32 s22, s46, s20
	s_cselect_b32 s21, s7, s49
	s_cselect_b32 s20, s47, s48
	s_add_i32 m0, s17, 0xc000
	ds_read_b128 v[168:171], v150
	ds_read_b128 v[172:175], v150 offset:1024
	ds_read_b128 v[176:179], v150 offset:2048
	ds_read_b128 v[180:183], v150 offset:3072
	ds_read_b128 v[184:187], v150 offset:4096
	ds_read_b128 v[188:191], v150 offset:5120
	ds_read_b128 v[192:195], v150 offset:6144
	ds_read_b128 v[196:199], v150 offset:7168
	global_load_lds_dwordx4 v138, s[18:19]
	s_add_i32 m0, s17, 0xe000
	s_nop 0
	global_load_lds_dwordx4 v140, s[18:19]
	s_waitcnt lgkmcnt(8)
	s_waitcnt vmcnt(8)
	s_setprio 1
	s_barrier
	s_waitcnt lgkmcnt(0)
	v_mfma_f32_16x16x32_bf16 v[124:127], v[152:155], v[168:171], v[124:127]
	v_mfma_f32_16x16x32_bf16 v[120:123], v[160:163], v[168:171], v[120:123]
	v_mfma_f32_16x16x32_bf16 v[112:115], v[152:155], v[176:179], v[112:115]
	v_mfma_f32_16x16x32_bf16 v[104:107], v[160:163], v[176:179], v[104:107]
	v_mfma_f32_16x16x32_bf16 v[96:99], v[152:155], v[184:187], v[96:99]
	v_mfma_f32_16x16x32_bf16 v[88:91], v[160:163], v[184:187], v[88:91]
	v_mfma_f32_16x16x32_bf16 v[80:83], v[152:155], v[192:195], v[80:83]
	v_mfma_f32_16x16x32_bf16 v[72:75], v[160:163], v[192:195], v[72:75]
	v_mfma_f32_16x16x32_bf16 v[124:127], v[156:159], v[172:175], v[124:127]
	v_mfma_f32_16x16x32_bf16 v[120:123], v[164:167], v[172:175], v[120:123]
	v_mfma_f32_16x16x32_bf16 v[112:115], v[156:159], v[180:183], v[112:115]
	v_mfma_f32_16x16x32_bf16 v[104:107], v[164:167], v[180:183], v[104:107]
	v_mfma_f32_16x16x32_bf16 v[96:99], v[156:159], v[188:191], v[96:99]
	v_mfma_f32_16x16x32_bf16 v[88:91], v[164:167], v[188:191], v[88:91]
	v_mfma_f32_16x16x32_bf16 v[80:83], v[156:159], v[196:199], v[80:83]
	v_mfma_f32_16x16x32_bf16 v[72:75], v[164:167], v[196:199], v[72:75]
	s_barrier
	s_setprio 0
	s_add_i32 s52, s43, s28
	s_mov_b32 m0, s52
	ds_read_b128 v[202:205], v151
	ds_read_b128 v[206:209], v151 offset:1024
	ds_read_b128 v[210:213], v151 offset:2048
	ds_read_b128 v[214:217], v151 offset:3072
	global_load_lds_dwordx4 v130, s[20:21]
	s_add_i32 m0, s52, 0x2000
	s_nop 0
	global_load_lds_dwordx4 v134, s[20:21]
	s_waitcnt vmcnt(8)
	s_setprio 1
	s_barrier
; #define PG8_STAGE(bufoff, gbase, voff) do { _Pragma("unroll") for (int _i = 0; _i < 2; ++_i) \
;         __builtin_amdgcn_global_load_lds((const unsigned*)((const char*)(gbase) + (voff)[_i]), (LAS unsigned*)(lds + (bufoff) + ldsw + _i * 8192), 16, 0, 0); } while (0)
; #define PG8_LDA(dst, b, h) do { _Pragma("unroll") for (int m = 0; m < 4; ++m) _Pragma("unroll") for (int k = 0; k < 2; ++k) dst[m][k] = *(const LAS bf16x8*)(lds + PG8_SA(b, h) + aoff + m * 2048 + k * 1024); } while (0)
; #define PG8_WAIT_V(n) asm volatile("s_waitcnt vmcnt(" #n ")" ::: "memory")
; #define PG8_WAIT_L(n) asm volatile("s_waitcnt lgkmcnt(" #n ")" ::: "memory")
; template <class Epi, class Sched>
; __device__ __forceinline__ void gemm_phase(LAS unsigned char* lds, const Gemm g, const Sched& S, const Epi& E) {
;     ...
;         for (int t = 0; t < nt; t += 2) {
;             const bool last = (t == nt - 2);
;             const char* a1 = cA + (size_t)(t + 1) * kstep;
;             const char* a2 = last ? nA : cA + (size_t)(t + 2) * kstep; const char* b2 = last ? nB : cB + (size_t)(t + 2) * kstep;
;             const char* a3 = a2 + kstep; const char* b3 = b2 + kstep;
;             PG8_LDB(B0, 0, 0); PG8_SCHED; PG8_LDA(At, 0, 0); PG8_STAGE(PG8_SA(1, 1), a1 + hstep, voffA);
;             PG8_WAIT_L(8); PG8_BAR; PG8_WAIT_L(0); PG8_MMA(0, 0, At, B0); PG8_BAR; PG8_SCHED;
;             PG8_LDB(B1, 0, 1); PG8_STAGE(PG8_SB(0, 0), b2, voffB);
;             PG8_BAR; PG8_WAIT_L(0); PG8_MMA(0, 1, At, B1); PG8_BAR;
;             PG8_LDA(At, 0, 1); PG8_STAGE(PG8_SA(0, 0), a2, voffA);
;             PG8_BAR; PG8_WAIT_L(0); PG8_MMA(1, 0, At, B0); PG8_BAR; PG8_SCHED;
;             PG8_STAGE(PG8_SB(0, 1), b2 + hstep, voffB);
;             PG8_WAIT_V(6); PG8_BAR; PG8_MMA(1, 1, At, B1); PG8_BAR;
;             PG8_LDB(B0, 1, 0); PG8_SCHED; PG8_LDA(At, 1, 0); PG8_STAGE(PG8_SA(0, 1), a2 + hstep, voffA);
;             PG8_WAIT_L(8); PG8_BAR; PG8_WAIT_L(0); PG8_MMA(0, 0, At, B0); PG8_BAR; PG8_SCHED;
;             PG8_LDB(B1, 1, 1); PG8_STAGE(PG8_SB(1, 0), b3, voffB);
;             PG8_BAR; PG8_WAIT_L(0); PG8_MMA(0, 1, At, B1); PG8_BAR;
;             PG8_LDA(At, 1, 1); PG8_STAGE(PG8_SA(1, 0), a3, voffA);
;             PG8_BAR; PG8_WAIT_L(0); PG8_MMA(1, 0, At, B0); PG8_BAR; PG8_SCHED;
;             PG8_STAGE(PG8_SB(1, 1), b3 + hstep, voffB);
;             PG8_WAIT_V(6); PG8_BAR; PG8_MMA(1, 1, At, B1); PG8_BAR;
	s_waitcnt lgkmcnt(0)
	v_mfma_f32_16x16x32_bf16 v[116:119], v[202:205], v[168:171], v[116:119]
	v_mfma_f32_16x16x32_bf16 v[108:111], v[210:213], v[168:171], v[108:111]
	v_mfma_f32_16x16x32_bf16 v[100:103], v[202:205], v[176:179], v[100:103]
	v_mfma_f32_16x16x32_bf16 v[92:95], v[210:213], v[176:179], v[92:95]
	v_mfma_f32_16x16x32_bf16 v[84:87], v[202:205], v[184:187], v[84:87]
	v_mfma_f32_16x16x32_bf16 v[76:79], v[210:213], v[184:187], v[76:79]
	v_mfma_f32_16x16x32_bf16 v[68:71], v[202:205], v[192:195], v[68:71]
	v_mfma_f32_16x16x32_bf16 v[64:67], v[210:213], v[192:195], v[64:67]
	v_mfma_f32_16x16x32_bf16 v[116:119], v[206:209], v[172:175], v[116:119]
	v_mfma_f32_16x16x32_bf16 v[108:111], v[214:217], v[172:175], v[108:111]
	v_mfma_f32_16x16x32_bf16 v[100:103], v[206:209], v[180:183], v[100:103]
	v_mfma_f32_16x16x32_bf16 v[92:95], v[214:217], v[180:183], v[92:95]
	v_mfma_f32_16x16x32_bf16 v[84:87], v[206:209], v[188:191], v[84:87]
	v_mfma_f32_16x16x32_bf16 v[76:79], v[214:217], v[188:191], v[76:79]
	v_mfma_f32_16x16x32_bf16 v[68:71], v[206:209], v[196:199], v[68:71]
	v_mfma_f32_16x16x32_bf16 v[64:67], v[214:217], v[196:199], v[64:67]
	s_barrier
	s_setprio 0
	s_mov_b32 m0, s17
	v_lshl_add_u64 v[222:223], s[22:23], 0, v[128:129]
	ds_read_b128 v[168:171], v150 offset:16384
	ds_read_b128 v[172:175], v150 offset:17408
	ds_read_b128 v[176:179], v150 offset:18432
	ds_read_b128 v[180:183], v150 offset:19456
	ds_read_b128 v[184:187], v150 offset:20480
	ds_read_b128 v[188:191], v150 offset:21504
	ds_read_b128 v[192:195], v150 offset:22528
	ds_read_b128 v[196:199], v150 offset:23552
	global_load_lds_dwordx4 v128, s[22:23]
	v_lshl_add_u64 v[224:225], s[22:23], 0, v[132:133]
	s_mov_b32 m0, s29
	s_nop 0
	global_load_lds_dwordx4 v132, s[22:23]
	s_setprio 1
	s_barrier
	s_waitcnt lgkmcnt(0)
	v_mfma_f32_16x16x32_bf16 v[60:63], v[152:155], v[168:171], v[60:63]
	v_mfma_f32_16x16x32_bf16 v[56:59], v[160:163], v[168:171], v[56:59]
	v_mfma_f32_16x16x32_bf16 v[48:51], v[152:155], v[176:179], v[48:51]
	v_mfma_f32_16x16x32_bf16 v[40:43], v[160:163], v[176:179], v[40:43]
	v_mfma_f32_16x16x32_bf16 v[32:35], v[152:155], v[184:187], v[32:35]
	v_mfma_f32_16x16x32_bf16 v[24:27], v[160:163], v[184:187], v[24:27]
	v_mfma_f32_16x16x32_bf16 v[16:19], v[152:155], v[192:195], v[16:19]
	v_mfma_f32_16x16x32_bf16 v[8:11], v[160:163], v[192:195], v[8:11]
	v_mfma_f32_16x16x32_bf16 v[60:63], v[156:159], v[172:175], v[60:63]
	v_mfma_f32_16x16x32_bf16 v[56:59], v[164:167], v[172:175], v[56:59]
	v_mfma_f32_16x16x32_bf16 v[48:51], v[156:159], v[180:183], v[48:51]
	v_mfma_f32_16x16x32_bf16 v[40:43], v[164:167], v[180:183], v[40:43]
	v_mfma_f32_16x16x32_bf16 v[32:35], v[156:159], v[188:191], v[32:35]
	v_mfma_f32_16x16x32_bf16 v[24:27], v[164:167], v[188:191], v[24:27]
	v_mfma_f32_16x16x32_bf16 v[16:19], v[156:159], v[196:199], v[16:19]
	v_mfma_f32_16x16x32_bf16 v[8:11], v[164:167], v[196:199], v[8:11]
	s_barrier
	s_setprio 0
	s_add_u32 s52, s20, 0x40000
	s_addc_u32 s53, s21, 0
	s_add_i32 s54, s44, s28
	s_mov_b32 m0, s54
	s_nop 0
	global_load_lds_dwordx4 v130, s[52:53]
	s_add_i32 m0, s54, 0x2000
	s_nop 0
	global_load_lds_dwordx4 v134, s[52:53]
	s_add_u32 s22, s22, 0x40000
	s_addc_u32 s23, s23, 0
	s_mov_b32 m0, s30
	s_nop 0
	global_load_lds_dwordx4 v128, s[22:23]
	s_mov_b32 m0, s31
	s_nop 0
	global_load_lds_dwordx4 v132, s[22:23]
	s_waitcnt vmcnt(10)
	s_setprio 1
	s_barrier
	v_mfma_f32_16x16x32_bf16 v[52:55], v[202:205], v[168:171], v[52:55]
	v_mfma_f32_16x16x32_bf16 v[44:47], v[210:213], v[168:171], v[44:47]
	v_mfma_f32_16x16x32_bf16 v[36:39], v[202:205], v[176:179], v[36:39]
	v_mfma_f32_16x16x32_bf16 v[28:31], v[210:213], v[176:179], v[28:31]
	v_mfma_f32_16x16x32_bf16 v[20:23], v[202:205], v[184:187], v[20:23]
	v_mfma_f32_16x16x32_bf16 v[12:15], v[210:213], v[184:187], v[12:15]
	v_mfma_f32_16x16x32_bf16 v[4:7], v[202:205], v[192:195], v[4:7]
	v_mfma_f32_16x16x32_bf16 v[0:3], v[210:213], v[192:195], v[0:3]
	v_mfma_f32_16x16x32_bf16 v[52:55], v[206:209], v[172:175], v[52:55]
	v_mfma_f32_16x16x32_bf16 v[44:47], v[214:217], v[172:175], v[44:47]
	v_mfma_f32_16x16x32_bf16 v[36:39], v[206:209], v[180:183], v[36:39]
	v_mfma_f32_16x16x32_bf16 v[28:31], v[214:217], v[180:183], v[28:31]
	v_mfma_f32_16x16x32_bf16 v[20:23], v[206:209], v[188:191], v[20:23]
	v_mfma_f32_16x16x32_bf16 v[12:15], v[214:217], v[188:191], v[12:15]
	v_mfma_f32_16x16x32_bf16 v[4:7], v[206:209], v[196:199], v[4:7]
	v_mfma_f32_16x16x32_bf16 v[0:3], v[214:217], v[196:199], v[0:3]
	s_barrier
	s_setprio 0
	s_add_i32 s52, 0, 0x18000
	v_add_u32_e32 v136, s52, v148
	ds_read_b128 v[152:155], v136
	ds_read_b128 v[156:159], v136 offset:1024
	ds_read_b128 v[160:163], v136 offset:2048
	ds_read_b128 v[164:167], v136 offset:3072
	ds_read_b128 v[168:171], v150 offset:32768
	ds_read_b128 v[172:175], v150 offset:33792
	ds_read_b128 v[176:179], v150 offset:34816
	ds_read_b128 v[180:183], v150 offset:35840
	ds_read_b128 v[184:187], v150 offset:36864
	ds_read_b128 v[188:191], v150 offset:37888
	ds_read_b128 v[192:195], v150 offset:38912
	ds_read_b128 v[196:199], v150 offset:39936
	s_waitcnt lgkmcnt(8)
	s_waitcnt vmcnt(8)
	s_setprio 1
	s_barrier
; #define PG8_STAGE(bufoff, gbase, voff) do { _Pragma("unroll") for (int _i = 0; _i < 2; ++_i) \
;         __builtin_amdgcn_global_load_lds((const unsigned*)((const char*)(gbase) + (voff)[_i]), (LAS unsigned*)(lds + (bufoff) + ldsw + _i * 8192), 16, 0, 0); } while (0)
; #define PG8_LDA(dst, b, h) do { _Pragma("unroll") for (int m = 0; m < 4; ++m) _Pragma("unroll") for (int k = 0; k < 2; ++k) dst[m][k] = *(const LAS bf16x8*)(lds + PG8_SA(b, h) + aoff + m * 2048 + k * 1024); } while (0)
; #define PG8_WAIT_V(n) asm volatile("s_waitcnt vmcnt(" #n ")" ::: "memory")
; #define PG8_WAIT_L(n) asm volatile("s_waitcnt lgkmcnt(" #n ")" ::: "memory")
; template <class Epi, class Sched>
; __device__ __forceinline__ void gemm_phase(LAS unsigned char* lds, const Gemm g, const Sched& S, const Epi& E) {
;     ...
;         for (int t = 0; t < nt; t += 2) {
;             const bool last = (t == nt - 2);
;             const char* a1 = cA + (size_t)(t + 1) * kstep;
;             const char* a2 = last ? nA : cA + (size_t)(t + 2) * kstep; const char* b2 = last ? nB : cB + (size_t)(t + 2) * kstep;
;             const char* a3 = a2 + kstep; const char* b3 = b2 + kstep;
;             PG8_LDB(B0, 0, 0); PG8_SCHED; PG8_LDA(At, 0, 0); PG8_STAGE(PG8_SA(1, 1), a1 + hstep, voffA);
;             PG8_WAIT_L(8); PG8_BAR; PG8_WAIT_L(0); PG8_MMA(0, 0, At, B0); PG8_BAR; PG8_SCHED;
;             PG8_LDB(B1, 0, 1); PG8_STAGE(PG8_SB(0, 0), b2, voffB);
;             PG8_BAR; PG8_WAIT_L(0); PG8_MMA(0, 1, At, B1); PG8_BAR;
;             PG8_LDA(At, 0, 1); PG8_STAGE(PG8_SA(0, 0), a2, voffA);
;             PG8_BAR; PG8_WAIT_L(0); PG8_MMA(1, 0, At, B0); PG8_BAR; PG8_SCHED;
;             PG8_STAGE(PG8_SB(0, 1), b2 + hstep, voffB);
;             PG8_WAIT_V(6); PG8_BAR; PG8_MMA(1, 1, At, B1); PG8_BAR;
;             PG8_LDB(B0, 1, 0); PG8_SCHED; PG8_LDA(At, 1, 0); PG8_STAGE(PG8_SA(0, 1), a2 + hstep, voffA);
;             PG8_WAIT_L(8); PG8_BAR; PG8_WAIT_L(0); PG8_MMA(0, 0, At, B0); PG8_BAR; PG8_SCHED;
;             PG8_LDB(B1, 1, 1); PG8_STAGE(PG8_SB(1, 0), b3, voffB);
;             PG8_BAR; PG8_WAIT_L(0); PG8_MMA(0, 1, At, B1); PG8_BAR;
;             PG8_LDA(At, 1, 1); PG8_STAGE(PG8_SA(1, 0), a3, voffA);
;             PG8_BAR; PG8_WAIT_L(0); PG8_MMA(1, 0, At, B0); PG8_BAR; PG8_SCHED;
;             PG8_STAGE(PG8_SB(1, 1), b3 + hstep, voffB);
;             PG8_WAIT_V(6); PG8_BAR; PG8_MMA(1, 1, At, B1); PG8_BAR;
	s_waitcnt lgkmcnt(0)
	v_mfma_f32_16x16x32_bf16 v[124:127], v[152:155], v[168:171], v[124:127]
	v_mfma_f32_16x16x32_bf16 v[120:123], v[160:163], v[168:171], v[120:123]
	v_mfma_f32_16x16x32_bf16 v[112:115], v[152:155], v[176:179], v[112:115]
	v_mfma_f32_16x16x32_bf16 v[104:107], v[160:163], v[176:179], v[104:107]
	v_mfma_f32_16x16x32_bf16 v[96:99], v[152:155], v[184:187], v[96:99]
	v_mfma_f32_16x16x32_bf16 v[88:91], v[160:163], v[184:187], v[88:91]
	v_mfma_f32_16x16x32_bf16 v[80:83], v[152:155], v[192:195], v[80:83]
	v_mfma_f32_16x16x32_bf16 v[72:75], v[160:163], v[192:195], v[72:75]
	v_mfma_f32_16x16x32_bf16 v[124:127], v[156:159], v[172:175], v[124:127]
	v_mfma_f32_16x16x32_bf16 v[120:123], v[164:167], v[172:175], v[120:123]
	v_mfma_f32_16x16x32_bf16 v[112:115], v[156:159], v[180:183], v[112:115]
	v_mfma_f32_16x16x32_bf16 v[104:107], v[164:167], v[180:183], v[104:107]
	v_mfma_f32_16x16x32_bf16 v[96:99], v[156:159], v[188:191], v[96:99]
	v_mfma_f32_16x16x32_bf16 v[88:91], v[164:167], v[188:191], v[88:91]
	v_mfma_f32_16x16x32_bf16 v[80:83], v[156:159], v[196:199], v[80:83]
	v_mfma_f32_16x16x32_bf16 v[72:75], v[164:167], v[196:199], v[72:75]
	s_barrier
	s_setprio 0
	s_add_i32 s22, 0, 0x1c000
	s_add_i32 s23, s52, s28
	v_add_u32_e32 v136, s22, v148
	s_add_u32 s0, s20, 0x80
	s_addc_u32 s1, s21, 0
	s_mov_b32 m0, s23
	ds_read_b128 v[202:205], v136
	ds_read_b128 v[206:209], v136 offset:1024
	ds_read_b128 v[210:213], v136 offset:2048
	ds_read_b128 v[214:217], v136 offset:3072
	global_load_lds_dwordx4 v130, s[0:1]
	s_add_i32 m0, s23, 0x2000
	s_nop 0
	global_load_lds_dwordx4 v134, s[0:1]
	s_waitcnt vmcnt(8)
	s_setprio 1
	s_barrier
	s_waitcnt lgkmcnt(0)
	v_mfma_f32_16x16x32_bf16 v[116:119], v[202:205], v[168:171], v[116:119]
	v_mfma_f32_16x16x32_bf16 v[108:111], v[210:213], v[168:171], v[108:111]
	v_mfma_f32_16x16x32_bf16 v[100:103], v[202:205], v[176:179], v[100:103]
	v_mfma_f32_16x16x32_bf16 v[92:95], v[210:213], v[176:179], v[92:95]
	v_mfma_f32_16x16x32_bf16 v[84:87], v[202:205], v[184:187], v[84:87]
	v_mfma_f32_16x16x32_bf16 v[76:79], v[210:213], v[184:187], v[76:79]
	v_mfma_f32_16x16x32_bf16 v[68:71], v[202:205], v[192:195], v[68:71]
	v_mfma_f32_16x16x32_bf16 v[64:67], v[210:213], v[192:195], v[64:67]
	v_mfma_f32_16x16x32_bf16 v[116:119], v[206:209], v[172:175], v[116:119]
	v_mfma_f32_16x16x32_bf16 v[108:111], v[214:217], v[172:175], v[108:111]
	v_mfma_f32_16x16x32_bf16 v[100:103], v[206:209], v[180:183], v[100:103]
	v_mfma_f32_16x16x32_bf16 v[92:95], v[214:217], v[180:183], v[92:95]
	v_mfma_f32_16x16x32_bf16 v[84:87], v[206:209], v[188:191], v[84:87]
	v_mfma_f32_16x16x32_bf16 v[76:79], v[214:217], v[188:191], v[76:79]
	v_mfma_f32_16x16x32_bf16 v[68:71], v[206:209], v[196:199], v[68:71]
	v_mfma_f32_16x16x32_bf16 v[64:67], v[214:217], v[196:199], v[64:67]
	s_barrier
	s_setprio 0
	s_mov_b32 m0, s36
	s_mov_b64 s[0:1], 0x80
	v_lshl_add_u64 v[218:219], v[222:223], 0, s[0:1]
	ds_read_b128 v[168:171], v150 offset:49152
	ds_read_b128 v[172:175], v150 offset:50176
	ds_read_b128 v[176:179], v150 offset:51200
	ds_read_b128 v[180:183], v150 offset:52224
	ds_read_b128 v[184:187], v150 offset:53248
	ds_read_b128 v[188:191], v150 offset:54272
	ds_read_b128 v[192:195], v150 offset:55296
	ds_read_b128 v[196:199], v150 offset:56320
	global_load_lds_dwordx4 v[218:219], off
	v_lshl_add_u64 v[218:219], v[224:225], 0, s[0:1]
	s_mov_b32 m0, s37
	s_nop 0
	global_load_lds_dwordx4 v[218:219], off
	s_setprio 1
	s_barrier
	s_waitcnt lgkmcnt(0)
	v_mfma_f32_16x16x32_bf16 v[60:63], v[152:155], v[168:171], v[60:63]
	v_mfma_f32_16x16x32_bf16 v[56:59], v[160:163], v[168:171], v[56:59]
	v_mfma_f32_16x16x32_bf16 v[48:51], v[152:155], v[176:179], v[48:51]
	v_mfma_f32_16x16x32_bf16 v[40:43], v[160:163], v[176:179], v[40:43]
	v_mfma_f32_16x16x32_bf16 v[32:35], v[152:155], v[184:187], v[32:35]
	v_mfma_f32_16x16x32_bf16 v[24:27], v[160:163], v[184:187], v[24:27]
	v_mfma_f32_16x16x32_bf16 v[16:19], v[152:155], v[192:195], v[16:19]
	v_mfma_f32_16x16x32_bf16 v[8:11], v[160:163], v[192:195], v[8:11]
	v_mfma_f32_16x16x32_bf16 v[60:63], v[156:159], v[172:175], v[60:63]
	v_mfma_f32_16x16x32_bf16 v[56:59], v[164:167], v[172:175], v[56:59]
	v_mfma_f32_16x16x32_bf16 v[48:51], v[156:159], v[180:183], v[48:51]
	v_mfma_f32_16x16x32_bf16 v[40:43], v[164:167], v[180:183], v[40:43]
	v_mfma_f32_16x16x32_bf16 v[32:35], v[156:159], v[188:191], v[32:35]
	v_mfma_f32_16x16x32_bf16 v[24:27], v[164:167], v[188:191], v[24:27]
	v_mfma_f32_16x16x32_bf16 v[16:19], v[156:159], v[196:199], v[16:19]
	v_mfma_f32_16x16x32_bf16 v[8:11], v[164:167], v[196:199], v[8:11]
	s_barrier
	s_setprio 0
	s_add_u32 s20, s20, 0x40080
	s_addc_u32 s21, s21, 0
	s_add_i32 s22, s22, s28
	s_mov_b32 m0, s22
	s_nop 0
	global_load_lds_dwordx4 v130, s[20:21]
	s_add_i32 m0, s22, 0x2000
	s_nop 0
	global_load_lds_dwordx4 v134, s[20:21]
	s_waitcnt vmcnt(8)
	s_setprio 1
	s_barrier
	v_mfma_f32_16x16x32_bf16 v[52:55], v[202:205], v[168:171], v[52:55]
	v_mfma_f32_16x16x32_bf16 v[44:47], v[210:213], v[168:171], v[44:47]
	v_mfma_f32_16x16x32_bf16 v[36:39], v[202:205], v[176:179], v[36:39]
	v_mfma_f32_16x16x32_bf16 v[28:31], v[210:213], v[176:179], v[28:31]
	v_mfma_f32_16x16x32_bf16 v[20:23], v[202:205], v[184:187], v[20:23]
	v_mfma_f32_16x16x32_bf16 v[12:15], v[210:213], v[184:187], v[12:15]
	v_mfma_f32_16x16x32_bf16 v[4:7], v[202:205], v[192:195], v[4:7]
	v_mfma_f32_16x16x32_bf16 v[0:3], v[210:213], v[192:195], v[0:3]
	v_mfma_f32_16x16x32_bf16 v[52:55], v[206:209], v[172:175], v[52:55]
	v_mfma_f32_16x16x32_bf16 v[44:47], v[214:217], v[172:175], v[44:47]
	v_mfma_f32_16x16x32_bf16 v[36:39], v[206:209], v[180:183], v[36:39]
	v_mfma_f32_16x16x32_bf16 v[28:31], v[214:217], v[180:183], v[28:31]
	v_mfma_f32_16x16x32_bf16 v[20:23], v[206:209], v[188:191], v[20:23]
	v_mfma_f32_16x16x32_bf16 v[12:15], v[214:217], v[188:191], v[12:15]
	v_mfma_f32_16x16x32_bf16 v[4:7], v[206:209], v[196:199], v[4:7]
	v_mfma_f32_16x16x32_bf16 v[0:3], v[214:217], v[196:199], v[0:3]
	s_barrier
; __device__ __forceinline__ unsigned cvt_pk_bf16(float lo, float hi) { unsigned r; asm volatile("v_cvt_pk_bf16_f32 %0, %1, %2" : "=v"(r) : "v"(lo), "v"(hi)); return r; }
; #define PG8_MMA(ai, bj, At, Bt) do { __builtin_amdgcn_s_setprio(1); _Pragma("unroll") for (int m = 0; m < 4; ++m) _Pragma("unroll") for (int n = 0; n < 2; ++n) _Pragma("unroll") for (int k = 0; k < 2; ++k) \
;         acc[ai][bj][m][n] = __builtin_amdgcn_mfma_f32_16x16x32_bf16(Bt[n][k], At[m][k], acc[ai][bj][m][n], 0, 0, 0); __builtin_amdgcn_s_setprio(0); } while (0)
; #define PG8_WAIT_V(n) asm volatile("s_waitcnt vmcnt(" #n ")" ::: "memory")
; #define PG8_BAR __builtin_amdgcn_s_barrier()
; template <class Epi, class Sched>
; __device__ __forceinline__ void gemm_phase(LAS unsigned char* lds, const Gemm g, const Sched& S, const Epi& E) {
;     ...
;             PG8_WAIT_V(6); PG8_BAR; PG8_MMA(1, 1, At, B1); PG8_BAR;
;     __device__ __forceinline__ void operator()(const AccT& acc, const Unit& u, int wr, int wc, int fr, int fq) const {
;         asm volatile("" : "+v"(fr), "+v"(fq));
;         const int rbase = u.pm * 256 + wr * 64 + fr;
;         const int tb = u.pn * 256 + wc * 32 + 8 * fq;
; #pragma unroll
;         for (int ai = 0; ai < 2; ++ai)
; #pragma unroll
;             for (int m = 0; m < 4; ++m) {
;                 const int gm = rbase + ai * 128 + m * 16;
; #pragma unroll
;                 for (int bj = 0; bj < 2; ++bj) {
;                     const int t0 = tb + bj * 128;
;                     const f32x4 v0 = acc[ai][bj][m][0], v1 = acc[ai][bj][m][1];
;                     u32x4 w; w.x = cvt_pk_bf16(v0[0], v0[1]); w.y = cvt_pk_bf16(v0[2], v0[3]); w.z = cvt_pk_bf16(v1[0], v1[1]); w.w = cvt_pk_bf16(v1[2], v1[3]);
;                     *(u32x4*)(YT + ((size_t)((t0 >> 10) * 512 + gm)) * 2048 + part * 1024 + (t0 & 1023)) = w;
;                 }
;             }
	s_setprio 0
	s_add_i32 s51, s51, 2
	s_add_u32 s18, s18, 0x100
	s_addc_u32 s19, s19, 0
	s_add_u32 s48, s48, 0x100
	s_addc_u32 s49, s49, 0
	s_cmp_gt_u32 s51, 13
	s_cbranch_scc0 .LBB0_673
	v_mov_b32_e32 v136, v147
	v_mov_b32_e32 v152, v146
	s_lshl_b32 s7, s16, 8
	s_add_i32 s7, s7, s34
	v_add_u32_e32 v152, s7, v152
	s_lshl_b32 s7, s45, 8
	s_or_b32 s7, s7, s35
	v_lshl_add_u32 v153, v136, 3, s7
	v_cvt_pk_bf16_f32 v124, v124, v125
	v_cvt_pk_bf16_f32 v125, v126, v127
	v_cvt_pk_bf16_f32 v126, v120, v121
	v_ashrrev_i32_e32 v120, 1, v153
	v_cvt_pk_bf16_f32 v127, v122, v123
	v_and_b32_e32 v122, 0xfffffe00, v120
	v_add_u32_e32 v120, v122, v152
	v_ashrrev_i32_e32 v121, 31, v120
	v_lshlrev_b64 v[120:121], 12, v[120:121]
	v_and_b32_e32 v123, 0x3f8, v153
	v_lshl_add_u64 v[120:121], s[4:5], 0, v[120:121]
	v_lshlrev_b32_e32 v136, 1, v123
	v_lshl_add_u64 v[120:121], v[120:121], 0, v[136:137]
	global_store_dwordx4 v[120:121], v[124:127], off
	v_add_u32_e32 v120, 0x80, v153
	v_cvt_pk_bf16_f32 v116, v116, v117
	v_cvt_pk_bf16_f32 v117, v118, v119
	v_cvt_pk_bf16_f32 v118, v108, v109
	v_ashrrev_i32_e32 v108, 1, v120
	v_and_b32_e32 v121, 0xfffffe00, v108
	v_add_u32_e32 v108, v121, v152
	v_ashrrev_i32_e32 v109, 31, v108
	v_lshlrev_b64 v[108:109], 12, v[108:109]
	v_cvt_pk_bf16_f32 v119, v110, v111
	v_lshl_add_u64 v[110:111], s[4:5], 0, v[108:109]
	v_and_b32_e32 v108, 0x3f8, v120
	v_lshlrev_b32_e32 v108, 1, v108
	v_mov_b32_e32 v109, v137
	v_lshl_add_u64 v[110:111], v[110:111], 0, v[108:109]
	global_store_dwordx4 v[110:111], v[116:119], off
	v_cvt_pk_bf16_f32 v110, v112, v113
	v_cvt_pk_bf16_f32 v111, v114, v115
	v_cvt_pk_bf16_f32 v112, v104, v105
	v_cvt_pk_bf16_f32 v113, v106, v107
	s_and_b64 vcc, exec, s[2:3]
	s_nop 0
	v_add_u32_e32 v116, 16, v152
	v_add_u32_e32 v104, v122, v116
	v_ashrrev_i32_e32 v105, 31, v104
	v_lshlrev_b64 v[104:105], 12, v[104:105]
	v_lshl_add_u64 v[104:105], s[4:5], 0, v[104:105]
	v_lshl_add_u64 v[104:105], v[104:105], 0, v[136:137]
	global_store_dwordx4 v[104:105], v[110:113], off
	v_cvt_pk_bf16_f32 v100, v100, v101
	v_cvt_pk_bf16_f32 v101, v102, v103
	v_cvt_pk_bf16_f32 v102, v92, v93
	v_add_u32_e32 v92, v121, v116
	v_ashrrev_i32_e32 v93, 31, v92
	v_lshlrev_b64 v[92:93], 12, v[92:93]
	v_lshl_add_u64 v[92:93], s[4:5], 0, v[92:93]
	v_lshl_add_u64 v[92:93], v[92:93], 0, v[108:109]
	v_cvt_pk_bf16_f32 v103, v94, v95
	global_store_dwordx4 v[92:93], v[100:103], off
	v_cvt_pk_bf16_f32 v92, v96, v97
	v_cvt_pk_bf16_f32 v93, v98, v99
	v_cvt_pk_bf16_f32 v94, v88, v89
	v_cvt_pk_bf16_f32 v95, v90, v91
	s_mov_b32 s45, s6
	s_nop 0
	v_add_u32_e32 v100, 32, v152
	v_add_u32_e32 v88, v122, v100
	v_ashrrev_i32_e32 v89, 31, v88
	v_lshlrev_b64 v[88:89], 12, v[88:89]
	v_lshl_add_u64 v[88:89], s[4:5], 0, v[88:89]
	v_lshl_add_u64 v[88:89], v[88:89], 0, v[136:137]
	global_store_dwordx4 v[88:89], v[92:95], off
	v_cvt_pk_bf16_f32 v84, v84, v85
	v_cvt_pk_bf16_f32 v85, v86, v87
	v_cvt_pk_bf16_f32 v86, v76, v77
	v_add_u32_e32 v76, v121, v100
	v_ashrrev_i32_e32 v77, 31, v76
	v_lshlrev_b64 v[76:77], 12, v[76:77]
	v_lshl_add_u64 v[76:77], s[4:5], 0, v[76:77]
	v_lshl_add_u64 v[76:77], v[76:77], 0, v[108:109]
	v_cvt_pk_bf16_f32 v87, v78, v79
	global_store_dwordx4 v[76:77], v[84:87], off
	v_cvt_pk_bf16_f32 v76, v80, v81
	v_cvt_pk_bf16_f32 v77, v82, v83
	v_cvt_pk_bf16_f32 v78, v72, v73
	v_cvt_pk_bf16_f32 v79, v74, v75
	s_mov_b32 s16, s8
	s_nop 0
	v_add_u32_e32 v84, 48, v152
	v_add_u32_e32 v72, v122, v84
	v_ashrrev_i32_e32 v73, 31, v72
	v_lshlrev_b64 v[72:73], 12, v[72:73]
	v_lshl_add_u64 v[72:73], s[4:5], 0, v[72:73]
	v_lshl_add_u64 v[72:73], v[72:73], 0, v[136:137]
	global_store_dwordx4 v[72:73], v[76:79], off
; __device__ __forceinline__ unsigned cvt_pk_bf16(float lo, float hi) { unsigned r; asm volatile("v_cvt_pk_bf16_f32 %0, %1, %2" : "=v"(r) : "v"(lo), "v"(hi)); return r; }
; #define PG8_WAIT_V(n) asm volatile("s_waitcnt vmcnt(" #n ")" ::: "memory")
; #define PG8_BAR __builtin_amdgcn_s_barrier()
; template <class Epi, class Sched>
; __device__ __forceinline__ void gemm_phase(LAS unsigned char* lds, const Gemm g, const Sched& S, const Epi& E) {
;     ...
;         if (!has_next) break;
; #pragma unroll
;         for (int a = 0; a < 2; ++a)
; #pragma unroll
;             for (int b = 0; b < 2; ++b)
; #pragma unroll
;                 for (int m = 0; m < 4; ++m)
; #pragma unroll
;                     for (int n = 0; n < 2; ++n) acc[a][b][m][n] = (f32x4){0.f, 0.f, 0.f, 0.f};
;         cur = nxt; cA = nA; cB = nB; ++ui;
;     }
;     PG8_WAIT_V(0);
;     if (wr == 0) PG8_BAR;
;     __device__ __forceinline__ void operator()(const AccT& acc, const Unit& u, int wr, int wc, int fr, int fq) const {
;         asm volatile("" : "+v"(fr), "+v"(fq));
;         const int rbase = u.pm * 256 + wr * 64 + fr;
;         const int tb = u.pn * 256 + wc * 32 + 8 * fq;
; #pragma unroll
;         for (int ai = 0; ai < 2; ++ai)
; #pragma unroll
;             for (int m = 0; m < 4; ++m) {
;                 const int gm = rbase + ai * 128 + m * 16;
; #pragma unroll
;                 for (int bj = 0; bj < 2; ++bj) {
;                     const int t0 = tb + bj * 128;
;                     const f32x4 v0 = acc[ai][bj][m][0], v1 = acc[ai][bj][m][1];
;                     u32x4 w; w.x = cvt_pk_bf16(v0[0], v0[1]); w.y = cvt_pk_bf16(v0[2], v0[3]); w.z = cvt_pk_bf16(v1[0], v1[1]); w.w = cvt_pk_bf16(v1[2], v1[3]);
;                     *(u32x4*)(YT + ((size_t)((t0 >> 10) * 512 + gm)) * 2048 + part * 1024 + (t0 & 1023)) = w;
;                 }
;             }
	v_cvt_pk_bf16_f32 v68, v68, v69
	v_cvt_pk_bf16_f32 v69, v70, v71
	v_cvt_pk_bf16_f32 v70, v64, v65
	v_add_u32_e32 v64, v121, v84
	v_ashrrev_i32_e32 v65, 31, v64
	v_lshlrev_b64 v[64:65], 12, v[64:65]
	v_lshl_add_u64 v[64:65], s[4:5], 0, v[64:65]
	v_lshl_add_u64 v[64:65], v[64:65], 0, v[108:109]
	v_cvt_pk_bf16_f32 v71, v66, v67
	global_store_dwordx4 v[64:65], v[68:71], off
	v_add_u32_e32 v64, 0x80, v152
	v_cvt_pk_bf16_f32 v60, v60, v61
	v_cvt_pk_bf16_f32 v61, v62, v63
	v_cvt_pk_bf16_f32 v62, v56, v57
	v_add_u32_e32 v56, v122, v64
	v_ashrrev_i32_e32 v57, 31, v56
	v_lshlrev_b64 v[56:57], 12, v[56:57]
	v_lshl_add_u64 v[56:57], s[4:5], 0, v[56:57]
	v_lshl_add_u64 v[56:57], v[56:57], 0, v[136:137]
	v_cvt_pk_bf16_f32 v63, v58, v59
	global_store_dwordx4 v[56:57], v[60:63], off
	v_cvt_pk_bf16_f32 v52, v52, v53
	v_cvt_pk_bf16_f32 v53, v54, v55
	v_cvt_pk_bf16_f32 v54, v44, v45
	v_add_u32_e32 v44, v121, v64
	v_ashrrev_i32_e32 v45, 31, v44
	v_lshlrev_b64 v[44:45], 12, v[44:45]
	v_lshl_add_u64 v[44:45], s[4:5], 0, v[44:45]
	v_lshl_add_u64 v[44:45], v[44:45], 0, v[108:109]
	v_cvt_pk_bf16_f32 v55, v46, v47
	global_store_dwordx4 v[44:45], v[52:55], off
	v_cvt_pk_bf16_f32 v44, v48, v49
	v_cvt_pk_bf16_f32 v45, v50, v51
	v_cvt_pk_bf16_f32 v46, v40, v41
	v_cvt_pk_bf16_f32 v47, v42, v43
	s_mov_b64 s[20:21], s[14:15]
	s_nop 0
	v_add_u32_e32 v52, 0x90, v152
	v_add_u32_e32 v40, v122, v52
	v_ashrrev_i32_e32 v41, 31, v40
	v_lshlrev_b64 v[40:41], 12, v[40:41]
	v_lshl_add_u64 v[40:41], s[4:5], 0, v[40:41]
	v_lshl_add_u64 v[40:41], v[40:41], 0, v[136:137]
	global_store_dwordx4 v[40:41], v[44:47], off
	v_cvt_pk_bf16_f32 v36, v36, v37
	v_cvt_pk_bf16_f32 v37, v38, v39
	v_cvt_pk_bf16_f32 v38, v28, v29
	v_add_u32_e32 v28, v121, v52
	v_ashrrev_i32_e32 v29, 31, v28
	v_lshlrev_b64 v[28:29], 12, v[28:29]
	v_lshl_add_u64 v[28:29], s[4:5], 0, v[28:29]
	v_lshl_add_u64 v[28:29], v[28:29], 0, v[108:109]
	v_cvt_pk_bf16_f32 v39, v30, v31
	global_store_dwordx4 v[28:29], v[36:39], off
	v_cvt_pk_bf16_f32 v28, v32, v33
	v_cvt_pk_bf16_f32 v29, v34, v35
	v_cvt_pk_bf16_f32 v30, v24, v25
	v_cvt_pk_bf16_f32 v31, v26, v27
	s_mov_b64 s[18:19], s[12:13]
	s_nop 0
	v_add_u32_e32 v36, 0xa0, v152
	v_add_u32_e32 v24, v122, v36
	v_ashrrev_i32_e32 v25, 31, v24
	v_lshlrev_b64 v[24:25], 12, v[24:25]
	v_lshl_add_u64 v[24:25], s[4:5], 0, v[24:25]
	v_lshl_add_u64 v[24:25], v[24:25], 0, v[136:137]
	global_store_dwordx4 v[24:25], v[28:31], off
	v_cvt_pk_bf16_f32 v20, v20, v21
	v_cvt_pk_bf16_f32 v21, v22, v23
	v_cvt_pk_bf16_f32 v22, v12, v13
	v_add_u32_e32 v12, v121, v36
	v_ashrrev_i32_e32 v13, 31, v12
	v_lshlrev_b64 v[12:13], 12, v[12:13]
	v_lshl_add_u64 v[12:13], s[4:5], 0, v[12:13]
	v_lshl_add_u64 v[12:13], v[12:13], 0, v[108:109]
	v_cvt_pk_bf16_f32 v23, v14, v15
	global_store_dwordx4 v[12:13], v[20:23], off
	v_cvt_pk_bf16_f32 v12, v16, v17
	v_cvt_pk_bf16_f32 v13, v18, v19
	v_cvt_pk_bf16_f32 v14, v8, v9
	v_cvt_pk_bf16_f32 v15, v10, v11
	s_nop 1
	v_add_u32_e32 v20, 0xb0, v152
	v_add_u32_e32 v8, v122, v20
	v_ashrrev_i32_e32 v9, 31, v8
	v_lshlrev_b64 v[8:9], 12, v[8:9]
	v_lshl_add_u64 v[8:9], s[4:5], 0, v[8:9]
	v_lshl_add_u64 v[8:9], v[8:9], 0, v[136:137]
	global_store_dwordx4 v[8:9], v[12:15], off
	v_cvt_pk_bf16_f32 v4, v4, v5
	v_cvt_pk_bf16_f32 v5, v6, v7
	v_cvt_pk_bf16_f32 v6, v0, v1
	v_add_u32_e32 v0, v121, v20
	v_ashrrev_i32_e32 v1, 31, v0
	v_lshlrev_b64 v[0:1], 12, v[0:1]
	v_lshl_add_u64 v[0:1], s[4:5], 0, v[0:1]
	v_lshl_add_u64 v[0:1], v[0:1], 0, v[108:109]
	v_cvt_pk_bf16_f32 v7, v2, v3
	global_store_dwordx4 v[0:1], v[4:7], off
	s_cbranch_vccz .LBB0_666
	s_waitcnt vmcnt(0)
	s_cmpk_gt_u32 s24, 0xff
	s_cbranch_scc1 .LBB0_677
	s_barrier

; #define PG8_STAGE(bufoff, gbase, voff) do { _Pragma("unroll") for (int _i = 0; _i < 2; ++_i) \
;         __builtin_amdgcn_global_load_lds((const unsigned*)((const char*)(gbase) + (voff)[_i]), (LAS unsigned*)(lds + (bufoff) + ldsw + _i * 8192), 16, 0, 0); } while (0)
; #define PG8_LDA(dst, b, h) do { _Pragma("unroll") for (int m = 0; m < 4; ++m) _Pragma("unroll") for (int k = 0; k < 2; ++k) dst[m][k] = *(const LAS bf16x8*)(lds + PG8_SA(b, h) + aoff + m * 2048 + k * 1024); } while (0)
; #define PG8_LDB(dst, b, h) do { _Pragma("unroll") for (int n = 0; n < 2; ++n) _Pragma("unroll") for (int k = 0; k < 2; ++k) dst[n][k] = *(const LAS bf16x8*)(lds + PG8_SB(b, h) + boff + n * 2048 + k * 1024); } while (0)
; #define PG8_WAIT_V(n) asm volatile("s_waitcnt vmcnt(" #n ")" ::: "memory")
; #define PG8_WAIT_L(n) asm volatile("s_waitcnt lgkmcnt(" #n ")" ::: "memory")
; #define PG8_BAR __builtin_amdgcn_s_barrier()
; #define PG8_SCHED __builtin_amdgcn_sched_barrier(0)
; template <class Epi, class Sched>
; __device__ __forceinline__ void gemm_phase(LAS unsigned char* lds, const Gemm g, const Sched& S, const Epi& E) {
;     ...
;         const bool has_next = S.next(ui + 1, nxt);
;         const char* nA = has_next ? (const char*)g.A + (size_t)nxt.pm * tstep : cA; const char* nB = has_next ? (const char*)g.Bt + (size_t)nxt.pn * tstep : cB;
;         for (int t = 0; t < nt; t += 2) {
;             const bool last = (t == nt - 2);
;             const char* a1 = cA + (size_t)(t + 1) * kstep;
;             const char* a2 = last ? nA : cA + (size_t)(t + 2) * kstep; const char* b2 = last ? nB : cB + (size_t)(t + 2) * kstep;
;             const char* a3 = a2 + kstep; const char* b3 = b2 + kstep;
;             PG8_LDB(B0, 0, 0); PG8_SCHED; PG8_LDA(At, 0, 0); PG8_STAGE(PG8_SA(1, 1), a1 + hstep, voffA);
;             PG8_WAIT_L(8); PG8_BAR; PG8_WAIT_L(0); PG8_MMA(0, 0, At, B0); PG8_BAR; PG8_SCHED;
;             PG8_LDB(B1, 0, 1); PG8_STAGE(PG8_SB(0, 0), b2, voffB);
;             PG8_BAR; PG8_WAIT_L(0); PG8_MMA(0, 1, At, B1); PG8_BAR;
;             PG8_LDA(At, 0, 1); PG8_STAGE(PG8_SA(0, 0), a2, voffA);
;             PG8_BAR; PG8_WAIT_L(0); PG8_MMA(1, 0, At, B0); PG8_BAR; PG8_SCHED;
;             PG8_STAGE(PG8_SB(0, 1), b2 + hstep, voffB);
;             PG8_WAIT_V(6); PG8_BAR; PG8_MMA(1, 1, At, B1); PG8_BAR;
.LBB0_692:
	s_ashr_i32 s19, s18, 31
	v_cmp_lt_i64_e64 s[24:25], s[20:21], 32
	s_lshl_b64 s[20:21], s[18:19], 19
	s_add_u32 s20, s40, s20
	s_addc_u32 s21, s41, s21
	s_and_b64 s[22:23], s[24:25], exec
	s_cselect_b32 s19, s21, s3
	s_cselect_b32 s57, s20, s2
	s_ashr_i32 s17, s16, 31
	s_lshl_b64 s[22:23], s[16:17], 19
	s_add_u32 s22, s28, s22
	s_addc_u32 s23, s29, s23
	s_and_b64 s[24:25], s[24:25], exec
	s_cselect_b32 s17, s23, s5
	s_cselect_b32 s58, s22, s4
	s_add_u32 s2, s2, 0x40080
	s_addc_u32 s3, s3, 0
	s_add_u32 s59, s4, 0x100
	s_addc_u32 s60, s5, 0
	s_mov_b32 s61, -2
	s_waitcnt lgkmcnt(0)
	ds_read_b128 v[140:143], v149
	ds_read_b128 v[154:157], v149 offset:1024
	ds_read_b128 v[158:161], v149 offset:2048
	ds_read_b128 v[162:165], v149 offset:3072
	s_add_u32 s4, s2, 0xfffc0080
	s_addc_u32 s5, s3, -1
	s_cmp_eq_u32 s61, 12
	s_cselect_b32 s25, s19, s5
	s_cselect_b32 s24, s57, s4
	s_cselect_b32 s5, s17, s60
	s_cselect_b32 s4, s58, s59
	s_add_i32 m0, s33, 0xc000
	ds_read_b128 v[166:169], v150
	ds_read_b128 v[170:173], v150 offset:1024
	ds_read_b128 v[174:177], v150 offset:2048
	ds_read_b128 v[178:181], v150 offset:3072
	ds_read_b128 v[182:185], v150 offset:4096
	ds_read_b128 v[186:189], v150 offset:5120
	ds_read_b128 v[190:193], v150 offset:6144
	ds_read_b128 v[194:197], v150 offset:7168
	global_load_lds_dwordx4 v136, s[2:3]
	s_add_i32 m0, s33, 0xe000
	s_nop 0
	global_load_lds_dwordx4 v138, s[2:3]
	s_waitcnt lgkmcnt(8)
	s_waitcnt vmcnt(8)
	s_setprio 1
	s_barrier
	s_waitcnt lgkmcnt(0)
	v_mfma_f32_16x16x32_bf16 v[124:127], v[140:143], v[166:169], 0
	v_mfma_f32_16x16x32_bf16 v[120:123], v[158:161], v[166:169], 0
	v_mfma_f32_16x16x32_bf16 v[108:111], v[140:143], v[174:177], 0
	v_mfma_f32_16x16x32_bf16 v[104:107], v[158:161], v[174:177], 0
	v_mfma_f32_16x16x32_bf16 v[92:95], v[140:143], v[182:185], 0
	v_mfma_f32_16x16x32_bf16 v[88:91], v[158:161], v[182:185], 0
	v_mfma_f32_16x16x32_bf16 v[76:79], v[140:143], v[190:193], 0
	v_mfma_f32_16x16x32_bf16 v[72:75], v[158:161], v[190:193], 0
	v_mfma_f32_16x16x32_bf16 v[124:127], v[154:157], v[170:173], v[124:127]
	v_mfma_f32_16x16x32_bf16 v[120:123], v[162:165], v[170:173], v[120:123]
	v_mfma_f32_16x16x32_bf16 v[108:111], v[154:157], v[178:181], v[108:111]
	v_mfma_f32_16x16x32_bf16 v[104:107], v[162:165], v[178:181], v[104:107]
	v_mfma_f32_16x16x32_bf16 v[92:95], v[154:157], v[186:189], v[92:95]
	v_mfma_f32_16x16x32_bf16 v[88:91], v[162:165], v[186:189], v[88:91]
	v_mfma_f32_16x16x32_bf16 v[76:79], v[154:157], v[194:197], v[76:79]
	v_mfma_f32_16x16x32_bf16 v[72:75], v[162:165], v[194:197], v[72:75]
	s_barrier
	s_setprio 0
	s_add_i32 s62, s47, s31
	s_mov_b32 m0, s62
	ds_read_b128 v[202:205], v151
	ds_read_b128 v[206:209], v151 offset:1024
	ds_read_b128 v[210:213], v151 offset:2048
	ds_read_b128 v[214:217], v151 offset:3072
	global_load_lds_dwordx4 v130, s[4:5]
	s_add_i32 m0, s62, 0x2000
	s_nop 0
	global_load_lds_dwordx4 v134, s[4:5]
	s_waitcnt vmcnt(8)
	s_setprio 1
	s_barrier
	s_waitcnt lgkmcnt(0)
	v_mfma_f32_16x16x32_bf16 v[116:119], v[202:205], v[166:169], 0
	v_mfma_f32_16x16x32_bf16 v[112:115], v[210:213], v[166:169], 0
	v_mfma_f32_16x16x32_bf16 v[100:103], v[202:205], v[174:177], 0
	v_mfma_f32_16x16x32_bf16 v[96:99], v[210:213], v[174:177], 0
	v_mfma_f32_16x16x32_bf16 v[84:87], v[202:205], v[182:185], 0
	v_mfma_f32_16x16x32_bf16 v[80:83], v[210:213], v[182:185], 0
	v_mfma_f32_16x16x32_bf16 v[68:71], v[202:205], v[190:193], 0
	v_mfma_f32_16x16x32_bf16 v[64:67], v[210:213], v[190:193], 0
	v_mfma_f32_16x16x32_bf16 v[116:119], v[206:209], v[170:173], v[116:119]
	v_mfma_f32_16x16x32_bf16 v[112:115], v[214:217], v[170:173], v[112:115]
	v_mfma_f32_16x16x32_bf16 v[100:103], v[206:209], v[178:181], v[100:103]
	v_mfma_f32_16x16x32_bf16 v[96:99], v[214:217], v[178:181], v[96:99]
	v_mfma_f32_16x16x32_bf16 v[84:87], v[206:209], v[186:189], v[84:87]
	v_mfma_f32_16x16x32_bf16 v[80:83], v[214:217], v[186:189], v[80:83]
	v_mfma_f32_16x16x32_bf16 v[68:71], v[206:209], v[194:197], v[68:71]
	v_mfma_f32_16x16x32_bf16 v[64:67], v[214:217], v[194:197], v[64:67]
	s_barrier
	s_setprio 0
	s_mov_b32 m0, s33
	v_lshl_add_u64 v[218:219], s[24:25], 0, v[128:129]
	ds_read_b128 v[166:169], v150 offset:16384
	ds_read_b128 v[170:173], v150 offset:17408
	ds_read_b128 v[174:177], v150 offset:18432
	ds_read_b128 v[178:181], v150 offset:19456
	ds_read_b128 v[182:185], v150 offset:20480
	ds_read_b128 v[186:189], v150 offset:21504
	ds_read_b128 v[190:193], v150 offset:22528
	ds_read_b128 v[194:197], v150 offset:23552
	global_load_lds_dwordx4 v128, s[24:25]
	v_lshl_add_u64 v[220:221], s[24:25], 0, v[132:133]
	s_mov_b32 m0, s34
	s_nop 0
	global_load_lds_dwordx4 v132, s[24:25]
	s_setprio 1
	s_barrier
	s_waitcnt lgkmcnt(0)
	v_mfma_f32_16x16x32_bf16 v[60:63], v[140:143], v[166:169], 0
	v_mfma_f32_16x16x32_bf16 v[56:59], v[158:161], v[166:169], 0
	v_mfma_f32_16x16x32_bf16 v[44:47], v[140:143], v[174:177], 0
	v_mfma_f32_16x16x32_bf16 v[40:43], v[158:161], v[174:177], 0
	v_mfma_f32_16x16x32_bf16 v[28:31], v[140:143], v[182:185], 0
	v_mfma_f32_16x16x32_bf16 v[24:27], v[158:161], v[182:185], 0
	v_mfma_f32_16x16x32_bf16 v[12:15], v[140:143], v[190:193], 0
	v_mfma_f32_16x16x32_bf16 v[8:11], v[158:161], v[190:193], 0
	v_mfma_f32_16x16x32_bf16 v[60:63], v[154:157], v[170:173], v[60:63]
	v_mfma_f32_16x16x32_bf16 v[56:59], v[162:165], v[170:173], v[56:59]
	v_mfma_f32_16x16x32_bf16 v[44:47], v[154:157], v[178:181], v[44:47]
	v_mfma_f32_16x16x32_bf16 v[40:43], v[162:165], v[178:181], v[40:43]
	v_mfma_f32_16x16x32_bf16 v[28:31], v[154:157], v[186:189], v[28:31]
	v_mfma_f32_16x16x32_bf16 v[24:27], v[162:165], v[186:189], v[24:27]
	v_mfma_f32_16x16x32_bf16 v[12:15], v[154:157], v[194:197], v[12:15]
	v_mfma_f32_16x16x32_bf16 v[8:11], v[162:165], v[194:197], v[8:11]
	s_barrier
; #define PG8_STAGE(bufoff, gbase, voff) do { _Pragma("unroll") for (int _i = 0; _i < 2; ++_i) \
;         __builtin_amdgcn_global_load_lds((const unsigned*)((const char*)(gbase) + (voff)[_i]), (LAS unsigned*)(lds + (bufoff) + ldsw + _i * 8192), 16, 0, 0); } while (0)
; #define PG8_LDA(dst, b, h) do { _Pragma("unroll") for (int m = 0; m < 4; ++m) _Pragma("unroll") for (int k = 0; k < 2; ++k) dst[m][k] = *(const LAS bf16x8*)(lds + PG8_SA(b, h) + aoff + m * 2048 + k * 1024); } while (0)
; #define PG8_LDB(dst, b, h) do { _Pragma("unroll") for (int n = 0; n < 2; ++n) _Pragma("unroll") for (int k = 0; k < 2; ++k) dst[n][k] = *(const LAS bf16x8*)(lds + PG8_SB(b, h) + boff + n * 2048 + k * 1024); } while (0)
; #define PG8_MMA(ai, bj, At, Bt) do { __builtin_amdgcn_s_setprio(1); _Pragma("unroll") for (int m = 0; m < 4; ++m) _Pragma("unroll") for (int n = 0; n < 2; ++n) _Pragma("unroll") for (int k = 0; k < 2; ++k) \
;         acc[ai][bj][m][n] = __builtin_amdgcn_mfma_f32_16x16x32_bf16(Bt[n][k], At[m][k], acc[ai][bj][m][n], 0, 0, 0); __builtin_amdgcn_s_setprio(0); } while (0)
; #define PG8_WAIT_V(n) asm volatile("s_waitcnt vmcnt(" #n ")" ::: "memory")
; #define PG8_WAIT_L(n) asm volatile("s_waitcnt lgkmcnt(" #n ")" ::: "memory")
; template <class Epi, class Sched>
; __device__ __forceinline__ void gemm_phase(LAS unsigned char* lds, const Gemm g, const Sched& S, const Epi& E) {
;     ...
;         for (int t = 0; t < nt; t += 2) {
;             const bool last = (t == nt - 2);
;             const char* a1 = cA + (size_t)(t + 1) * kstep;
;             const char* a2 = last ? nA : cA + (size_t)(t + 2) * kstep; const char* b2 = last ? nB : cB + (size_t)(t + 2) * kstep;
;             const char* a3 = a2 + kstep; const char* b3 = b2 + kstep;
;             PG8_LDB(B0, 0, 0); PG8_SCHED; PG8_LDA(At, 0, 0); PG8_STAGE(PG8_SA(1, 1), a1 + hstep, voffA);
;             PG8_WAIT_L(8); PG8_BAR; PG8_WAIT_L(0); PG8_MMA(0, 0, At, B0); PG8_BAR; PG8_SCHED;
;             PG8_LDB(B1, 0, 1); PG8_STAGE(PG8_SB(0, 0), b2, voffB);
;             PG8_BAR; PG8_WAIT_L(0); PG8_MMA(0, 1, At, B1); PG8_BAR;
;             PG8_LDA(At, 0, 1); PG8_STAGE(PG8_SA(0, 0), a2, voffA);
;             PG8_BAR; PG8_WAIT_L(0); PG8_MMA(1, 0, At, B0); PG8_BAR; PG8_SCHED;
;             PG8_STAGE(PG8_SB(0, 1), b2 + hstep, voffB);
;             PG8_WAIT_V(6); PG8_BAR; PG8_MMA(1, 1, At, B1); PG8_BAR;
	s_setprio 0
	s_add_u32 s62, s4, 0x40000
	s_addc_u32 s63, s5, 0
	s_add_i32 s64, s48, s31
	s_mov_b32 m0, s64
	s_nop 0
	global_load_lds_dwordx4 v130, s[62:63]
	s_add_i32 m0, s64, 0x2000
	s_nop 0
	global_load_lds_dwordx4 v134, s[62:63]
	s_add_u32 s24, s24, 0x40000
	s_addc_u32 s25, s25, 0
	s_mov_b32 m0, s35
	s_nop 0
	global_load_lds_dwordx4 v128, s[24:25]
	s_mov_b32 m0, s36
	s_nop 0
	global_load_lds_dwordx4 v132, s[24:25]
	s_waitcnt vmcnt(10)
	s_setprio 1
	s_barrier
	v_mfma_f32_16x16x32_bf16 v[52:55], v[202:205], v[166:169], 0
	v_mfma_f32_16x16x32_bf16 v[48:51], v[210:213], v[166:169], 0
	v_mfma_f32_16x16x32_bf16 v[36:39], v[202:205], v[174:177], 0
	v_mfma_f32_16x16x32_bf16 v[32:35], v[210:213], v[174:177], 0
	v_mfma_f32_16x16x32_bf16 v[20:23], v[202:205], v[182:185], 0
	v_mfma_f32_16x16x32_bf16 v[16:19], v[210:213], v[182:185], 0
	v_mfma_f32_16x16x32_bf16 v[4:7], v[202:205], v[190:193], 0
	v_mfma_f32_16x16x32_bf16 v[0:3], v[210:213], v[190:193], 0
	v_mfma_f32_16x16x32_bf16 v[52:55], v[206:209], v[170:173], v[52:55]
	v_mfma_f32_16x16x32_bf16 v[48:51], v[214:217], v[170:173], v[48:51]
	v_mfma_f32_16x16x32_bf16 v[36:39], v[206:209], v[178:181], v[36:39]
	v_mfma_f32_16x16x32_bf16 v[32:35], v[214:217], v[178:181], v[32:35]
	v_mfma_f32_16x16x32_bf16 v[20:23], v[206:209], v[186:189], v[20:23]
	v_mfma_f32_16x16x32_bf16 v[16:19], v[214:217], v[186:189], v[16:19]
	v_mfma_f32_16x16x32_bf16 v[4:7], v[206:209], v[194:197], v[4:7]
	v_mfma_f32_16x16x32_bf16 v[0:3], v[214:217], v[194:197], v[0:3]
	s_barrier
	s_setprio 0
	s_add_i32 s62, 0, 0x18000
	v_add_u32_e32 v162, s62, v148
	ds_read_b128 v[140:143], v162
	ds_read_b128 v[154:157], v162 offset:1024
	ds_read_b128 v[158:161], v162 offset:2048
	ds_read_b128 v[162:165], v162 offset:3072
	ds_read_b128 v[166:169], v150 offset:32768
	ds_read_b128 v[170:173], v150 offset:33792
	ds_read_b128 v[174:177], v150 offset:34816
	ds_read_b128 v[178:181], v150 offset:35840
	ds_read_b128 v[182:185], v150 offset:36864
	ds_read_b128 v[186:189], v150 offset:37888
	ds_read_b128 v[190:193], v150 offset:38912
	ds_read_b128 v[194:197], v150 offset:39936
	s_waitcnt lgkmcnt(8)
	s_waitcnt vmcnt(8)
	s_setprio 1
	s_barrier
	s_waitcnt lgkmcnt(0)
	v_mfma_f32_16x16x32_bf16 v[124:127], v[140:143], v[166:169], v[124:127]
	v_mfma_f32_16x16x32_bf16 v[120:123], v[158:161], v[166:169], v[120:123]
	v_mfma_f32_16x16x32_bf16 v[108:111], v[140:143], v[174:177], v[108:111]
	v_mfma_f32_16x16x32_bf16 v[104:107], v[158:161], v[174:177], v[104:107]
	v_mfma_f32_16x16x32_bf16 v[92:95], v[140:143], v[182:185], v[92:95]
	v_mfma_f32_16x16x32_bf16 v[88:91], v[158:161], v[182:185], v[88:91]
	v_mfma_f32_16x16x32_bf16 v[76:79], v[140:143], v[190:193], v[76:79]
	v_mfma_f32_16x16x32_bf16 v[72:75], v[158:161], v[190:193], v[72:75]
	v_mfma_f32_16x16x32_bf16 v[124:127], v[154:157], v[170:173], v[124:127]
	v_mfma_f32_16x16x32_bf16 v[120:123], v[162:165], v[170:173], v[120:123]
	v_mfma_f32_16x16x32_bf16 v[108:111], v[154:157], v[178:181], v[108:111]
	v_mfma_f32_16x16x32_bf16 v[104:107], v[162:165], v[178:181], v[104:107]
	v_mfma_f32_16x16x32_bf16 v[92:95], v[154:157], v[186:189], v[92:95]
	v_mfma_f32_16x16x32_bf16 v[88:91], v[162:165], v[186:189], v[88:91]
	v_mfma_f32_16x16x32_bf16 v[76:79], v[154:157], v[194:197], v[76:79]
	v_mfma_f32_16x16x32_bf16 v[72:75], v[162:165], v[194:197], v[72:75]
	s_barrier
	s_setprio 0
	s_add_i32 s24, 0, 0x1c000
	s_add_i32 s25, s62, s31
	v_add_u32_e32 v214, s24, v148
	s_add_u32 s0, s4, 0x80
	s_addc_u32 s1, s5, 0
	s_mov_b32 m0, s25
	ds_read_b128 v[202:205], v214
	ds_read_b128 v[206:209], v214 offset:1024
	ds_read_b128 v[210:213], v214 offset:2048
	ds_read_b128 v[214:217], v214 offset:3072
	global_load_lds_dwordx4 v130, s[0:1]
	s_add_i32 m0, s25, 0x2000
	s_nop 0
	global_load_lds_dwordx4 v134, s[0:1]
	s_waitcnt vmcnt(8)
	s_setprio 1
	s_barrier
	s_waitcnt lgkmcnt(0)
	v_mfma_f32_16x16x32_bf16 v[116:119], v[202:205], v[166:169], v[116:119]
	v_mfma_f32_16x16x32_bf16 v[112:115], v[210:213], v[166:169], v[112:115]
	v_mfma_f32_16x16x32_bf16 v[100:103], v[202:205], v[174:177], v[100:103]
	v_mfma_f32_16x16x32_bf16 v[96:99], v[210:213], v[174:177], v[96:99]
	v_mfma_f32_16x16x32_bf16 v[84:87], v[202:205], v[182:185], v[84:87]
	v_mfma_f32_16x16x32_bf16 v[80:83], v[210:213], v[182:185], v[80:83]
	v_mfma_f32_16x16x32_bf16 v[68:71], v[202:205], v[190:193], v[68:71]
	v_mfma_f32_16x16x32_bf16 v[64:67], v[210:213], v[190:193], v[64:67]
	v_mfma_f32_16x16x32_bf16 v[116:119], v[206:209], v[170:173], v[116:119]
	v_mfma_f32_16x16x32_bf16 v[112:115], v[214:217], v[170:173], v[112:115]
	v_mfma_f32_16x16x32_bf16 v[100:103], v[206:209], v[178:181], v[100:103]
	v_mfma_f32_16x16x32_bf16 v[96:99], v[214:217], v[178:181], v[96:99]
	v_mfma_f32_16x16x32_bf16 v[84:87], v[206:209], v[186:189], v[84:87]
	v_mfma_f32_16x16x32_bf16 v[80:83], v[214:217], v[186:189], v[80:83]
	v_mfma_f32_16x16x32_bf16 v[68:71], v[206:209], v[194:197], v[68:71]
	v_mfma_f32_16x16x32_bf16 v[64:67], v[214:217], v[194:197], v[64:67]
	s_barrier
	s_setprio 0
	s_mov_b32 m0, s44
	s_mov_b64 s[0:1], 0x80
	v_lshl_add_u64 v[144:145], v[218:219], 0, s[0:1]
	ds_read_b128 v[166:169], v150 offset:49152
	ds_read_b128 v[170:173], v150 offset:50176
	ds_read_b128 v[174:177], v150 offset:51200
	ds_read_b128 v[178:181], v150 offset:52224
	ds_read_b128 v[182:185], v150 offset:53248
	ds_read_b128 v[186:189], v150 offset:54272
	ds_read_b128 v[190:193], v150 offset:55296
	ds_read_b128 v[194:197], v150 offset:56320
	global_load_lds_dwordx4 v[144:145], off
	v_lshl_add_u64 v[144:145], v[220:221], 0, s[0:1]
	s_mov_b32 m0, s45
	s_nop 0
	global_load_lds_dwordx4 v[144:145], off
	s_setprio 1
	s_barrier
; #define PG8_STAGE(bufoff, gbase, voff) do { _Pragma("unroll") for (int _i = 0; _i < 2; ++_i) \
;         __builtin_amdgcn_global_load_lds((const unsigned*)((const char*)(gbase) + (voff)[_i]), (LAS unsigned*)(lds + (bufoff) + ldsw + _i * 8192), 16, 0, 0); } while (0)
; #define PG8_LDA(dst, b, h) do { _Pragma("unroll") for (int m = 0; m < 4; ++m) _Pragma("unroll") for (int k = 0; k < 2; ++k) dst[m][k] = *(const LAS bf16x8*)(lds + PG8_SA(b, h) + aoff + m * 2048 + k * 1024); } while (0)
; #define PG8_WAIT_V(n) asm volatile("s_waitcnt vmcnt(" #n ")" ::: "memory")
; #define PG8_WAIT_L(n) asm volatile("s_waitcnt lgkmcnt(" #n ")" ::: "memory")
; template <class Epi, class Sched>
; __device__ __forceinline__ void gemm_phase(LAS unsigned char* lds, const Gemm g, const Sched& S, const Epi& E) {
;     ...
;         for (int t = 0; t < nt; t += 2) {
;             const bool last = (t == nt - 2);
;             const char* a1 = cA + (size_t)(t + 1) * kstep;
;             const char* a2 = last ? nA : cA + (size_t)(t + 2) * kstep; const char* b2 = last ? nB : cB + (size_t)(t + 2) * kstep;
;             const char* a3 = a2 + kstep; const char* b3 = b2 + kstep;
;             PG8_LDB(B0, 0, 0); PG8_SCHED; PG8_LDA(At, 0, 0); PG8_STAGE(PG8_SA(1, 1), a1 + hstep, voffA);
;             PG8_WAIT_L(8); PG8_BAR; PG8_WAIT_L(0); PG8_MMA(0, 0, At, B0); PG8_BAR; PG8_SCHED;
;             PG8_LDB(B1, 0, 1); PG8_STAGE(PG8_SB(0, 0), b2, voffB);
;             PG8_BAR; PG8_WAIT_L(0); PG8_MMA(0, 1, At, B1); PG8_BAR;
;             PG8_LDA(At, 0, 1); PG8_STAGE(PG8_SA(0, 0), a2, voffA);
;             PG8_BAR; PG8_WAIT_L(0); PG8_MMA(1, 0, At, B0); PG8_BAR; PG8_SCHED;
;             PG8_STAGE(PG8_SB(0, 1), b2 + hstep, voffB);
;             PG8_WAIT_V(6); PG8_BAR; PG8_MMA(1, 1, At, B1); PG8_BAR;
;             PG8_LDB(B0, 1, 0); PG8_SCHED; PG8_LDA(At, 1, 0); PG8_STAGE(PG8_SA(0, 1), a2 + hstep, voffA);
;             PG8_WAIT_L(8); PG8_BAR; PG8_WAIT_L(0); PG8_MMA(0, 0, At, B0); PG8_BAR; PG8_SCHED;
;             PG8_LDB(B1, 1, 1); PG8_STAGE(PG8_SB(1, 0), b3, voffB);
;             PG8_BAR; PG8_WAIT_L(0); PG8_MMA(0, 1, At, B1); PG8_BAR;
;             PG8_LDA(At, 1, 1); PG8_STAGE(PG8_SA(1, 0), a3, voffA);
;             PG8_BAR; PG8_WAIT_L(0); PG8_MMA(1, 0, At, B0); PG8_BAR; PG8_SCHED;
;             PG8_STAGE(PG8_SB(1, 1), b3 + hstep, voffB);
;             PG8_WAIT_V(6); PG8_BAR; PG8_MMA(1, 1, At, B1); PG8_BAR;
	s_waitcnt lgkmcnt(0)
	v_mfma_f32_16x16x32_bf16 v[60:63], v[140:143], v[166:169], v[60:63]
	v_mfma_f32_16x16x32_bf16 v[56:59], v[158:161], v[166:169], v[56:59]
	v_mfma_f32_16x16x32_bf16 v[44:47], v[140:143], v[174:177], v[44:47]
	v_mfma_f32_16x16x32_bf16 v[40:43], v[158:161], v[174:177], v[40:43]
	v_mfma_f32_16x16x32_bf16 v[28:31], v[140:143], v[182:185], v[28:31]
	v_mfma_f32_16x16x32_bf16 v[24:27], v[158:161], v[182:185], v[24:27]
	v_mfma_f32_16x16x32_bf16 v[12:15], v[140:143], v[190:193], v[12:15]
	v_mfma_f32_16x16x32_bf16 v[8:11], v[158:161], v[190:193], v[8:11]
	v_mfma_f32_16x16x32_bf16 v[60:63], v[154:157], v[170:173], v[60:63]
	v_mfma_f32_16x16x32_bf16 v[56:59], v[162:165], v[170:173], v[56:59]
	v_mfma_f32_16x16x32_bf16 v[44:47], v[154:157], v[178:181], v[44:47]
	v_mfma_f32_16x16x32_bf16 v[40:43], v[162:165], v[178:181], v[40:43]
	v_mfma_f32_16x16x32_bf16 v[28:31], v[154:157], v[186:189], v[28:31]
	v_mfma_f32_16x16x32_bf16 v[24:27], v[162:165], v[186:189], v[24:27]
	v_mfma_f32_16x16x32_bf16 v[12:15], v[154:157], v[194:197], v[12:15]
	v_mfma_f32_16x16x32_bf16 v[8:11], v[162:165], v[194:197], v[8:11]
	s_barrier
	s_setprio 0
	s_add_u32 s4, s4, 0x40080
	s_addc_u32 s5, s5, 0
	s_add_i32 s24, s24, s31
	s_mov_b32 m0, s24
	s_nop 0
	global_load_lds_dwordx4 v130, s[4:5]
	s_add_i32 m0, s24, 0x2000
	s_nop 0
	global_load_lds_dwordx4 v134, s[4:5]
	s_waitcnt vmcnt(8)
	s_setprio 1
	s_barrier
	v_mfma_f32_16x16x32_bf16 v[52:55], v[202:205], v[166:169], v[52:55]
	v_mfma_f32_16x16x32_bf16 v[48:51], v[210:213], v[166:169], v[48:51]
	v_mfma_f32_16x16x32_bf16 v[36:39], v[202:205], v[174:177], v[36:39]
	v_mfma_f32_16x16x32_bf16 v[32:35], v[210:213], v[174:177], v[32:35]
	v_mfma_f32_16x16x32_bf16 v[20:23], v[202:205], v[182:185], v[20:23]
	v_mfma_f32_16x16x32_bf16 v[16:19], v[210:213], v[182:185], v[16:19]
	v_mfma_f32_16x16x32_bf16 v[4:7], v[202:205], v[190:193], v[4:7]
	v_mfma_f32_16x16x32_bf16 v[0:3], v[210:213], v[190:193], v[0:3]
	v_mfma_f32_16x16x32_bf16 v[52:55], v[206:209], v[170:173], v[52:55]
	v_mfma_f32_16x16x32_bf16 v[48:51], v[214:217], v[170:173], v[48:51]
	v_mfma_f32_16x16x32_bf16 v[36:39], v[206:209], v[178:181], v[36:39]
	v_mfma_f32_16x16x32_bf16 v[32:35], v[214:217], v[178:181], v[32:35]
	v_mfma_f32_16x16x32_bf16 v[20:23], v[206:209], v[186:189], v[20:23]
	v_mfma_f32_16x16x32_bf16 v[16:19], v[214:217], v[186:189], v[16:19]
	v_mfma_f32_16x16x32_bf16 v[4:7], v[206:209], v[194:197], v[4:7]
	v_mfma_f32_16x16x32_bf16 v[0:3], v[214:217], v[194:197], v[0:3]
	s_barrier
	s_setprio 0
	s_add_i32 s61, s61, 2
	s_add_u32 s2, s2, 0x100
	s_addc_u32 s3, s3, 0
	s_add_u32 s59, s59, 0x100
	s_addc_u32 s60, s60, 0
	s_cmp_gt_u32 s61, 13
.LBB0_693:
	ds_read_b128 v[140:143], v149
	ds_read_b128 v[154:157], v149 offset:1024
	ds_read_b128 v[158:161], v149 offset:2048
	ds_read_b128 v[162:165], v149 offset:3072
	s_add_u32 s4, s2, 0xfffc0080
	s_addc_u32 s5, s3, -1
	s_cmp_eq_u32 s61, 12
	s_cselect_b32 s25, s19, s5
	s_cselect_b32 s24, s57, s4
	s_cselect_b32 s5, s17, s60
	s_cselect_b32 s4, s58, s59
	s_add_i32 m0, s33, 0xc000
	ds_read_b128 v[166:169], v150
	ds_read_b128 v[170:173], v150 offset:1024
	ds_read_b128 v[174:177], v150 offset:2048
	ds_read_b128 v[178:181], v150 offset:3072
	ds_read_b128 v[182:185], v150 offset:4096
	ds_read_b128 v[186:189], v150 offset:5120
	ds_read_b128 v[190:193], v150 offset:6144
	ds_read_b128 v[194:197], v150 offset:7168
	global_load_lds_dwordx4 v136, s[2:3]
	s_add_i32 m0, s33, 0xe000
	s_nop 0
	global_load_lds_dwordx4 v138, s[2:3]
	s_waitcnt lgkmcnt(8)
	s_waitcnt vmcnt(8)
	s_setprio 1
	s_barrier
	s_waitcnt lgkmcnt(0)
	v_mfma_f32_16x16x32_bf16 v[124:127], v[140:143], v[166:169], v[124:127]
	v_mfma_f32_16x16x32_bf16 v[120:123], v[158:161], v[166:169], v[120:123]
	v_mfma_f32_16x16x32_bf16 v[108:111], v[140:143], v[174:177], v[108:111]
	v_mfma_f32_16x16x32_bf16 v[104:107], v[158:161], v[174:177], v[104:107]
	v_mfma_f32_16x16x32_bf16 v[92:95], v[140:143], v[182:185], v[92:95]
	v_mfma_f32_16x16x32_bf16 v[88:91], v[158:161], v[182:185], v[88:91]
	v_mfma_f32_16x16x32_bf16 v[76:79], v[140:143], v[190:193], v[76:79]
	v_mfma_f32_16x16x32_bf16 v[72:75], v[158:161], v[190:193], v[72:75]
	v_mfma_f32_16x16x32_bf16 v[124:127], v[154:157], v[170:173], v[124:127]
	v_mfma_f32_16x16x32_bf16 v[120:123], v[162:165], v[170:173], v[120:123]
	v_mfma_f32_16x16x32_bf16 v[108:111], v[154:157], v[178:181], v[108:111]
	v_mfma_f32_16x16x32_bf16 v[104:107], v[162:165], v[178:181], v[104:107]
	v_mfma_f32_16x16x32_bf16 v[92:95], v[154:157], v[186:189], v[92:95]
	v_mfma_f32_16x16x32_bf16 v[88:91], v[162:165], v[186:189], v[88:91]
	v_mfma_f32_16x16x32_bf16 v[76:79], v[154:157], v[194:197], v[76:79]
	v_mfma_f32_16x16x32_bf16 v[72:75], v[162:165], v[194:197], v[72:75]
	s_barrier
	s_setprio 0
	s_add_i32 s62, s47, s31
	s_mov_b32 m0, s62
	ds_read_b128 v[202:205], v151
	ds_read_b128 v[206:209], v151 offset:1024
	ds_read_b128 v[210:213], v151 offset:2048
	ds_read_b128 v[214:217], v151 offset:3072
	global_load_lds_dwordx4 v130, s[4:5]
	s_add_i32 m0, s62, 0x2000
	s_nop 0
	global_load_lds_dwordx4 v134, s[4:5]
	s_waitcnt vmcnt(8)
	s_setprio 1
	s_barrier
; #define PG8_STAGE(bufoff, gbase, voff) do { _Pragma("unroll") for (int _i = 0; _i < 2; ++_i) \
;         __builtin_amdgcn_global_load_lds((const unsigned*)((const char*)(gbase) + (voff)[_i]), (LAS unsigned*)(lds + (bufoff) + ldsw + _i * 8192), 16, 0, 0); } while (0)
; #define PG8_LDA(dst, b, h) do { _Pragma("unroll") for (int m = 0; m < 4; ++m) _Pragma("unroll") for (int k = 0; k < 2; ++k) dst[m][k] = *(const LAS bf16x8*)(lds + PG8_SA(b, h) + aoff + m * 2048 + k * 1024); } while (0)
; #define PG8_WAIT_V(n) asm volatile("s_waitcnt vmcnt(" #n ")" ::: "memory")
; #define PG8_WAIT_L(n) asm volatile("s_waitcnt lgkmcnt(" #n ")" ::: "memory")
; template <class Epi, class Sched>
; __device__ __forceinline__ void gemm_phase(LAS unsigned char* lds, const Gemm g, const Sched& S, const Epi& E) {
;     ...
;         for (int t = 0; t < nt; t += 2) {
;             const bool last = (t == nt - 2);
;             const char* a1 = cA + (size_t)(t + 1) * kstep;
;             const char* a2 = last ? nA : cA + (size_t)(t + 2) * kstep; const char* b2 = last ? nB : cB + (size_t)(t + 2) * kstep;
;             const char* a3 = a2 + kstep; const char* b3 = b2 + kstep;
;             PG8_LDB(B0, 0, 0); PG8_SCHED; PG8_LDA(At, 0, 0); PG8_STAGE(PG8_SA(1, 1), a1 + hstep, voffA);
;             PG8_WAIT_L(8); PG8_BAR; PG8_WAIT_L(0); PG8_MMA(0, 0, At, B0); PG8_BAR; PG8_SCHED;
;             PG8_LDB(B1, 0, 1); PG8_STAGE(PG8_SB(0, 0), b2, voffB);
;             PG8_BAR; PG8_WAIT_L(0); PG8_MMA(0, 1, At, B1); PG8_BAR;
;             PG8_LDA(At, 0, 1); PG8_STAGE(PG8_SA(0, 0), a2, voffA);
;             PG8_BAR; PG8_WAIT_L(0); PG8_MMA(1, 0, At, B0); PG8_BAR; PG8_SCHED;
;             PG8_STAGE(PG8_SB(0, 1), b2 + hstep, voffB);
;             PG8_WAIT_V(6); PG8_BAR; PG8_MMA(1, 1, At, B1); PG8_BAR;
;             PG8_LDB(B0, 1, 0); PG8_SCHED; PG8_LDA(At, 1, 0); PG8_STAGE(PG8_SA(0, 1), a2 + hstep, voffA);
;             PG8_WAIT_L(8); PG8_BAR; PG8_WAIT_L(0); PG8_MMA(0, 0, At, B0); PG8_BAR; PG8_SCHED;
;             PG8_LDB(B1, 1, 1); PG8_STAGE(PG8_SB(1, 0), b3, voffB);
;             PG8_BAR; PG8_WAIT_L(0); PG8_MMA(0, 1, At, B1); PG8_BAR;
;             PG8_LDA(At, 1, 1); PG8_STAGE(PG8_SA(1, 0), a3, voffA);
;             PG8_BAR; PG8_WAIT_L(0); PG8_MMA(1, 0, At, B0); PG8_BAR; PG8_SCHED;
;             PG8_STAGE(PG8_SB(1, 1), b3 + hstep, voffB);
;             PG8_WAIT_V(6); PG8_BAR; PG8_MMA(1, 1, At, B1); PG8_BAR;
	s_waitcnt lgkmcnt(0)
	v_mfma_f32_16x16x32_bf16 v[116:119], v[202:205], v[166:169], v[116:119]
	v_mfma_f32_16x16x32_bf16 v[112:115], v[210:213], v[166:169], v[112:115]
	v_mfma_f32_16x16x32_bf16 v[100:103], v[202:205], v[174:177], v[100:103]
	v_mfma_f32_16x16x32_bf16 v[96:99], v[210:213], v[174:177], v[96:99]
	v_mfma_f32_16x16x32_bf16 v[84:87], v[202:205], v[182:185], v[84:87]
	v_mfma_f32_16x16x32_bf16 v[80:83], v[210:213], v[182:185], v[80:83]
	v_mfma_f32_16x16x32_bf16 v[68:71], v[202:205], v[190:193], v[68:71]
	v_mfma_f32_16x16x32_bf16 v[64:67], v[210:213], v[190:193], v[64:67]
	v_mfma_f32_16x16x32_bf16 v[116:119], v[206:209], v[170:173], v[116:119]
	v_mfma_f32_16x16x32_bf16 v[112:115], v[214:217], v[170:173], v[112:115]
	v_mfma_f32_16x16x32_bf16 v[100:103], v[206:209], v[178:181], v[100:103]
	v_mfma_f32_16x16x32_bf16 v[96:99], v[214:217], v[178:181], v[96:99]
	v_mfma_f32_16x16x32_bf16 v[84:87], v[206:209], v[186:189], v[84:87]
	v_mfma_f32_16x16x32_bf16 v[80:83], v[214:217], v[186:189], v[80:83]
	v_mfma_f32_16x16x32_bf16 v[68:71], v[206:209], v[194:197], v[68:71]
	v_mfma_f32_16x16x32_bf16 v[64:67], v[214:217], v[194:197], v[64:67]
	s_barrier
	s_setprio 0
	s_mov_b32 m0, s33
	v_lshl_add_u64 v[218:219], s[24:25], 0, v[128:129]
	ds_read_b128 v[166:169], v150 offset:16384
	ds_read_b128 v[170:173], v150 offset:17408
	ds_read_b128 v[174:177], v150 offset:18432
	ds_read_b128 v[178:181], v150 offset:19456
	ds_read_b128 v[182:185], v150 offset:20480
	ds_read_b128 v[186:189], v150 offset:21504
	ds_read_b128 v[190:193], v150 offset:22528
	ds_read_b128 v[194:197], v150 offset:23552
	global_load_lds_dwordx4 v128, s[24:25]
	v_lshl_add_u64 v[220:221], s[24:25], 0, v[132:133]
	s_mov_b32 m0, s34
	s_nop 0
	global_load_lds_dwordx4 v132, s[24:25]
	s_setprio 1
	s_barrier
	s_waitcnt lgkmcnt(0)
	v_mfma_f32_16x16x32_bf16 v[60:63], v[140:143], v[166:169], v[60:63]
	v_mfma_f32_16x16x32_bf16 v[56:59], v[158:161], v[166:169], v[56:59]
	v_mfma_f32_16x16x32_bf16 v[44:47], v[140:143], v[174:177], v[44:47]
	v_mfma_f32_16x16x32_bf16 v[40:43], v[158:161], v[174:177], v[40:43]
	v_mfma_f32_16x16x32_bf16 v[28:31], v[140:143], v[182:185], v[28:31]
	v_mfma_f32_16x16x32_bf16 v[24:27], v[158:161], v[182:185], v[24:27]
	v_mfma_f32_16x16x32_bf16 v[12:15], v[140:143], v[190:193], v[12:15]
	v_mfma_f32_16x16x32_bf16 v[8:11], v[158:161], v[190:193], v[8:11]
	v_mfma_f32_16x16x32_bf16 v[60:63], v[154:157], v[170:173], v[60:63]
	v_mfma_f32_16x16x32_bf16 v[56:59], v[162:165], v[170:173], v[56:59]
	v_mfma_f32_16x16x32_bf16 v[44:47], v[154:157], v[178:181], v[44:47]
	v_mfma_f32_16x16x32_bf16 v[40:43], v[162:165], v[178:181], v[40:43]
	v_mfma_f32_16x16x32_bf16 v[28:31], v[154:157], v[186:189], v[28:31]
	v_mfma_f32_16x16x32_bf16 v[24:27], v[162:165], v[186:189], v[24:27]
	v_mfma_f32_16x16x32_bf16 v[12:15], v[154:157], v[194:197], v[12:15]
	v_mfma_f32_16x16x32_bf16 v[8:11], v[162:165], v[194:197], v[8:11]
	s_barrier
	s_setprio 0
	s_add_u32 s62, s4, 0x40000
	s_addc_u32 s63, s5, 0
	s_add_i32 s64, s48, s31
	s_mov_b32 m0, s64
	s_nop 0
	global_load_lds_dwordx4 v130, s[62:63]
	s_add_i32 m0, s64, 0x2000
	s_nop 0
	global_load_lds_dwordx4 v134, s[62:63]
	s_add_u32 s24, s24, 0x40000
	s_addc_u32 s25, s25, 0
	s_mov_b32 m0, s35
	s_nop 0
	global_load_lds_dwordx4 v128, s[24:25]
	s_mov_b32 m0, s36
	s_nop 0
	global_load_lds_dwordx4 v132, s[24:25]
	s_waitcnt vmcnt(10)
	s_setprio 1
	s_barrier
	v_mfma_f32_16x16x32_bf16 v[52:55], v[202:205], v[166:169], v[52:55]
	v_mfma_f32_16x16x32_bf16 v[48:51], v[210:213], v[166:169], v[48:51]
	v_mfma_f32_16x16x32_bf16 v[36:39], v[202:205], v[174:177], v[36:39]
	v_mfma_f32_16x16x32_bf16 v[32:35], v[210:213], v[174:177], v[32:35]
	v_mfma_f32_16x16x32_bf16 v[20:23], v[202:205], v[182:185], v[20:23]
	v_mfma_f32_16x16x32_bf16 v[16:19], v[210:213], v[182:185], v[16:19]
	v_mfma_f32_16x16x32_bf16 v[4:7], v[202:205], v[190:193], v[4:7]
	v_mfma_f32_16x16x32_bf16 v[0:3], v[210:213], v[190:193], v[0:3]
	v_mfma_f32_16x16x32_bf16 v[52:55], v[206:209], v[170:173], v[52:55]
	v_mfma_f32_16x16x32_bf16 v[48:51], v[214:217], v[170:173], v[48:51]
	v_mfma_f32_16x16x32_bf16 v[36:39], v[206:209], v[178:181], v[36:39]
	v_mfma_f32_16x16x32_bf16 v[32:35], v[214:217], v[178:181], v[32:35]
	v_mfma_f32_16x16x32_bf16 v[20:23], v[206:209], v[186:189], v[20:23]
	v_mfma_f32_16x16x32_bf16 v[16:19], v[214:217], v[186:189], v[16:19]
	v_mfma_f32_16x16x32_bf16 v[4:7], v[206:209], v[194:197], v[4:7]
	v_mfma_f32_16x16x32_bf16 v[0:3], v[214:217], v[194:197], v[0:3]
	s_barrier
	s_setprio 0
	s_add_i32 s62, 0, 0x18000
	v_add_u32_e32 v162, s62, v148
	ds_read_b128 v[140:143], v162
	ds_read_b128 v[154:157], v162 offset:1024
	ds_read_b128 v[158:161], v162 offset:2048
	ds_read_b128 v[162:165], v162 offset:3072
	ds_read_b128 v[166:169], v150 offset:32768
	ds_read_b128 v[170:173], v150 offset:33792
	ds_read_b128 v[174:177], v150 offset:34816
	ds_read_b128 v[178:181], v150 offset:35840
	ds_read_b128 v[182:185], v150 offset:36864
	ds_read_b128 v[186:189], v150 offset:37888
	ds_read_b128 v[190:193], v150 offset:38912
	ds_read_b128 v[194:197], v150 offset:39936
	s_waitcnt lgkmcnt(8)
	s_waitcnt vmcnt(8)
	s_setprio 1
	s_barrier
; #define PG8_STAGE(bufoff, gbase, voff) do { _Pragma("unroll") for (int _i = 0; _i < 2; ++_i) \
;         __builtin_amdgcn_global_load_lds((const unsigned*)((const char*)(gbase) + (voff)[_i]), (LAS unsigned*)(lds + (bufoff) + ldsw + _i * 8192), 16, 0, 0); } while (0)
; #define PG8_LDA(dst, b, h) do { _Pragma("unroll") for (int m = 0; m < 4; ++m) _Pragma("unroll") for (int k = 0; k < 2; ++k) dst[m][k] = *(const LAS bf16x8*)(lds + PG8_SA(b, h) + aoff + m * 2048 + k * 1024); } while (0)
; #define PG8_WAIT_V(n) asm volatile("s_waitcnt vmcnt(" #n ")" ::: "memory")
; #define PG8_WAIT_L(n) asm volatile("s_waitcnt lgkmcnt(" #n ")" ::: "memory")
; template <class Epi, class Sched>
; __device__ __forceinline__ void gemm_phase(LAS unsigned char* lds, const Gemm g, const Sched& S, const Epi& E) {
;     ...
;         for (int t = 0; t < nt; t += 2) {
;             const bool last = (t == nt - 2);
;             const char* a1 = cA + (size_t)(t + 1) * kstep;
;             const char* a2 = last ? nA : cA + (size_t)(t + 2) * kstep; const char* b2 = last ? nB : cB + (size_t)(t + 2) * kstep;
;             const char* a3 = a2 + kstep; const char* b3 = b2 + kstep;
;             PG8_LDB(B0, 0, 0); PG8_SCHED; PG8_LDA(At, 0, 0); PG8_STAGE(PG8_SA(1, 1), a1 + hstep, voffA);
;             PG8_WAIT_L(8); PG8_BAR; PG8_WAIT_L(0); PG8_MMA(0, 0, At, B0); PG8_BAR; PG8_SCHED;
;             PG8_LDB(B1, 0, 1); PG8_STAGE(PG8_SB(0, 0), b2, voffB);
;             PG8_BAR; PG8_WAIT_L(0); PG8_MMA(0, 1, At, B1); PG8_BAR;
;             PG8_LDA(At, 0, 1); PG8_STAGE(PG8_SA(0, 0), a2, voffA);
;             PG8_BAR; PG8_WAIT_L(0); PG8_MMA(1, 0, At, B0); PG8_BAR; PG8_SCHED;
;             PG8_STAGE(PG8_SB(0, 1), b2 + hstep, voffB);
;             PG8_WAIT_V(6); PG8_BAR; PG8_MMA(1, 1, At, B1); PG8_BAR;
;             PG8_LDB(B0, 1, 0); PG8_SCHED; PG8_LDA(At, 1, 0); PG8_STAGE(PG8_SA(0, 1), a2 + hstep, voffA);
;             PG8_WAIT_L(8); PG8_BAR; PG8_WAIT_L(0); PG8_MMA(0, 0, At, B0); PG8_BAR; PG8_SCHED;
;             PG8_LDB(B1, 1, 1); PG8_STAGE(PG8_SB(1, 0), b3, voffB);
;             PG8_BAR; PG8_WAIT_L(0); PG8_MMA(0, 1, At, B1); PG8_BAR;
;             PG8_LDA(At, 1, 1); PG8_STAGE(PG8_SA(1, 0), a3, voffA);
;             PG8_BAR; PG8_WAIT_L(0); PG8_MMA(1, 0, At, B0); PG8_BAR; PG8_SCHED;
;             PG8_STAGE(PG8_SB(1, 1), b3 + hstep, voffB);
;             PG8_WAIT_V(6); PG8_BAR; PG8_MMA(1, 1, At, B1); PG8_BAR;
	s_waitcnt lgkmcnt(0)
	v_mfma_f32_16x16x32_bf16 v[124:127], v[140:143], v[166:169], v[124:127]
	v_mfma_f32_16x16x32_bf16 v[120:123], v[158:161], v[166:169], v[120:123]
	v_mfma_f32_16x16x32_bf16 v[108:111], v[140:143], v[174:177], v[108:111]
	v_mfma_f32_16x16x32_bf16 v[104:107], v[158:161], v[174:177], v[104:107]
	v_mfma_f32_16x16x32_bf16 v[92:95], v[140:143], v[182:185], v[92:95]
	v_mfma_f32_16x16x32_bf16 v[88:91], v[158:161], v[182:185], v[88:91]
	v_mfma_f32_16x16x32_bf16 v[76:79], v[140:143], v[190:193], v[76:79]
	v_mfma_f32_16x16x32_bf16 v[72:75], v[158:161], v[190:193], v[72:75]
	v_mfma_f32_16x16x32_bf16 v[124:127], v[154:157], v[170:173], v[124:127]
	v_mfma_f32_16x16x32_bf16 v[120:123], v[162:165], v[170:173], v[120:123]
	v_mfma_f32_16x16x32_bf16 v[108:111], v[154:157], v[178:181], v[108:111]
	v_mfma_f32_16x16x32_bf16 v[104:107], v[162:165], v[178:181], v[104:107]
	v_mfma_f32_16x16x32_bf16 v[92:95], v[154:157], v[186:189], v[92:95]
	v_mfma_f32_16x16x32_bf16 v[88:91], v[162:165], v[186:189], v[88:91]
	v_mfma_f32_16x16x32_bf16 v[76:79], v[154:157], v[194:197], v[76:79]
	v_mfma_f32_16x16x32_bf16 v[72:75], v[162:165], v[194:197], v[72:75]
	s_barrier
	s_setprio 0
	s_add_i32 s24, 0, 0x1c000
	s_add_i32 s25, s62, s31
	v_add_u32_e32 v214, s24, v148
	s_add_u32 s0, s4, 0x80
	s_addc_u32 s1, s5, 0
	s_mov_b32 m0, s25
	ds_read_b128 v[202:205], v214
	ds_read_b128 v[206:209], v214 offset:1024
	ds_read_b128 v[210:213], v214 offset:2048
	ds_read_b128 v[214:217], v214 offset:3072
	global_load_lds_dwordx4 v130, s[0:1]
	s_add_i32 m0, s25, 0x2000
	s_nop 0
	global_load_lds_dwordx4 v134, s[0:1]
	s_waitcnt vmcnt(8)
	s_setprio 1
	s_barrier
	s_waitcnt lgkmcnt(0)
	v_mfma_f32_16x16x32_bf16 v[116:119], v[202:205], v[166:169], v[116:119]
	v_mfma_f32_16x16x32_bf16 v[112:115], v[210:213], v[166:169], v[112:115]
	v_mfma_f32_16x16x32_bf16 v[100:103], v[202:205], v[174:177], v[100:103]
	v_mfma_f32_16x16x32_bf16 v[96:99], v[210:213], v[174:177], v[96:99]
	v_mfma_f32_16x16x32_bf16 v[84:87], v[202:205], v[182:185], v[84:87]
	v_mfma_f32_16x16x32_bf16 v[80:83], v[210:213], v[182:185], v[80:83]
	v_mfma_f32_16x16x32_bf16 v[68:71], v[202:205], v[190:193], v[68:71]
	v_mfma_f32_16x16x32_bf16 v[64:67], v[210:213], v[190:193], v[64:67]
	v_mfma_f32_16x16x32_bf16 v[116:119], v[206:209], v[170:173], v[116:119]
	v_mfma_f32_16x16x32_bf16 v[112:115], v[214:217], v[170:173], v[112:115]
	v_mfma_f32_16x16x32_bf16 v[100:103], v[206:209], v[178:181], v[100:103]
	v_mfma_f32_16x16x32_bf16 v[96:99], v[214:217], v[178:181], v[96:99]
	v_mfma_f32_16x16x32_bf16 v[84:87], v[206:209], v[186:189], v[84:87]
	v_mfma_f32_16x16x32_bf16 v[80:83], v[214:217], v[186:189], v[80:83]
	v_mfma_f32_16x16x32_bf16 v[68:71], v[206:209], v[194:197], v[68:71]
	v_mfma_f32_16x16x32_bf16 v[64:67], v[214:217], v[194:197], v[64:67]
	s_barrier
	s_setprio 0
	s_mov_b32 m0, s44
	s_mov_b64 s[0:1], 0x80
	v_lshl_add_u64 v[144:145], v[218:219], 0, s[0:1]
	ds_read_b128 v[166:169], v150 offset:49152
	ds_read_b128 v[170:173], v150 offset:50176
	ds_read_b128 v[174:177], v150 offset:51200
	ds_read_b128 v[178:181], v150 offset:52224
	ds_read_b128 v[182:185], v150 offset:53248
	ds_read_b128 v[186:189], v150 offset:54272
	ds_read_b128 v[190:193], v150 offset:55296
	ds_read_b128 v[194:197], v150 offset:56320
	global_load_lds_dwordx4 v[144:145], off
	v_lshl_add_u64 v[144:145], v[220:221], 0, s[0:1]
	s_mov_b32 m0, s45
	s_nop 0
	global_load_lds_dwordx4 v[144:145], off
	s_setprio 1
	s_barrier
	s_waitcnt lgkmcnt(0)
	v_mfma_f32_16x16x32_bf16 v[60:63], v[140:143], v[166:169], v[60:63]
	v_mfma_f32_16x16x32_bf16 v[56:59], v[158:161], v[166:169], v[56:59]
	v_mfma_f32_16x16x32_bf16 v[44:47], v[140:143], v[174:177], v[44:47]
	v_mfma_f32_16x16x32_bf16 v[40:43], v[158:161], v[174:177], v[40:43]
	v_mfma_f32_16x16x32_bf16 v[28:31], v[140:143], v[182:185], v[28:31]
	v_mfma_f32_16x16x32_bf16 v[24:27], v[158:161], v[182:185], v[24:27]
	v_mfma_f32_16x16x32_bf16 v[12:15], v[140:143], v[190:193], v[12:15]
	v_mfma_f32_16x16x32_bf16 v[8:11], v[158:161], v[190:193], v[8:11]
	v_mfma_f32_16x16x32_bf16 v[60:63], v[154:157], v[170:173], v[60:63]
	v_mfma_f32_16x16x32_bf16 v[56:59], v[162:165], v[170:173], v[56:59]
	v_mfma_f32_16x16x32_bf16 v[44:47], v[154:157], v[178:181], v[44:47]
	v_mfma_f32_16x16x32_bf16 v[40:43], v[162:165], v[178:181], v[40:43]
	v_mfma_f32_16x16x32_bf16 v[28:31], v[154:157], v[186:189], v[28:31]
	v_mfma_f32_16x16x32_bf16 v[24:27], v[162:165], v[186:189], v[24:27]
	v_mfma_f32_16x16x32_bf16 v[12:15], v[154:157], v[194:197], v[12:15]
	v_mfma_f32_16x16x32_bf16 v[8:11], v[162:165], v[194:197], v[8:11]
	s_barrier
	s_setprio 0
	s_add_u32 s4, s4, 0x40080
	s_addc_u32 s5, s5, 0
	s_add_i32 s24, s24, s31
	s_mov_b32 m0, s24
	s_nop 0
	global_load_lds_dwordx4 v130, s[4:5]
	s_add_i32 m0, s24, 0x2000
	s_nop 0
	global_load_lds_dwordx4 v134, s[4:5]
	s_waitcnt vmcnt(8)
	s_setprio 1
	s_barrier
	v_mfma_f32_16x16x32_bf16 v[52:55], v[202:205], v[166:169], v[52:55]
	v_mfma_f32_16x16x32_bf16 v[48:51], v[210:213], v[166:169], v[48:51]
	v_mfma_f32_16x16x32_bf16 v[36:39], v[202:205], v[174:177], v[36:39]
	v_mfma_f32_16x16x32_bf16 v[32:35], v[210:213], v[174:177], v[32:35]
	v_mfma_f32_16x16x32_bf16 v[20:23], v[202:205], v[182:185], v[20:23]
	v_mfma_f32_16x16x32_bf16 v[16:19], v[210:213], v[182:185], v[16:19]
	v_mfma_f32_16x16x32_bf16 v[4:7], v[202:205], v[190:193], v[4:7]
	v_mfma_f32_16x16x32_bf16 v[0:3], v[210:213], v[190:193], v[0:3]
	v_mfma_f32_16x16x32_bf16 v[52:55], v[206:209], v[170:173], v[52:55]
	v_mfma_f32_16x16x32_bf16 v[48:51], v[214:217], v[170:173], v[48:51]
	v_mfma_f32_16x16x32_bf16 v[36:39], v[206:209], v[178:181], v[36:39]
	v_mfma_f32_16x16x32_bf16 v[32:35], v[214:217], v[178:181], v[32:35]
	v_mfma_f32_16x16x32_bf16 v[20:23], v[206:209], v[186:189], v[20:23]
	v_mfma_f32_16x16x32_bf16 v[16:19], v[214:217], v[186:189], v[16:19]
	v_mfma_f32_16x16x32_bf16 v[4:7], v[206:209], v[194:197], v[4:7]
	v_mfma_f32_16x16x32_bf16 v[0:3], v[214:217], v[194:197], v[0:3]
	s_barrier
; #define PG8_BAR __builtin_amdgcn_s_barrier()
; template <class Epi, class Sched>
; __device__ __forceinline__ void gemm_phase(LAS unsigned char* lds, const Gemm g, const Sched& S, const Epi& E) {
;     ...
;             PG8_WAIT_V(6); PG8_BAR; PG8_MMA(1, 1, At, B1); PG8_BAR;
;     __device__ __forceinline__ void operator()(const AccT& acc, const Unit& u, int wr, int wc, int fr, int fq) const {
;     ...
;         const int rbase = wr * 64 + fr;
;         const int tb = u.pn * 256 + wc * 32 + 8 * fq;
;         const int o0 = wc * 32 + 8 * fq;
;         const int j = fr & 3; const float sgn = ((fr >> 2) & 1) ? 1.0f : -1.0f;
; #pragma unroll
;         for (int ai = 0; ai < 2; ++ai) {
;             const int hh = 2 * ai + wr;
;             const float l2f = lgd[hh] * 1.4426950408889634f, l2b = lgd[4 + hh] * 1.4426950408889634f;
;             const float zf0 = exp2f((float)(127 - o0) * l2f), zfs = exp2f(-l2f), zb0 = exp2f((float)o0 * l2b), zbs = exp2f(l2b);
; #pragma unroll
;             for (int m = 0; m < 4; ++m) {
;                 const int r = rbase + ai * 128 + m * 16;
;                 const int d = 4 * (2 * m + (fr >> 3)) + j;
; #pragma unroll
;                 for (int bj = 0; bj < 2; ++bj) {
;                     const int t0 = tb + bj * 128;
;                     float v[8];
; #pragma unroll
;                     for (int jj = 0; jj < 4; ++jj) { v[jj] = acc[ai][bj][m][0][jj]; v[4 + jj] = acc[ai][bj][m][1][jj]; }
;                     if constexpr (ROPE) {
;                         const int t = t0 & 2047;
; #pragma unroll
;                         for (int hf = 0; hf < 2; ++hf) {
;                             f32x4 cs, sn;
;                             if (m < 2) { const float c1 = ropeA[(t >> 6) * 16 + d], s1 = ropeA[1024 + (t >> 6) * 16 + d]; cs = (f32x4){c1, c1, c1, c1}; sn = (f32x4){s1, s1, s1, s1}; }
;                             else { const float* cb = ropeA + 2048 + (d - 16) * 64 + (t & 63) + 4 * hf; cs = *(const f32x4*)(cb); sn = *(const f32x4*)(cb + 1024); }
; #pragma unroll
;                             for (int jj = 0; jj < 4; ++jj) { const float pr = __shfl_xor(v[4 * hf + jj], 4); v[4 * hf + jj] = v[4 * hf + jj] * cs[jj] + sgn * pr * sn[jj]; }
;                             __builtin_amdgcn_sched_barrier(0);
;                         }
;                     }
;                     float zf[8], zb[8]; zf[0] = zf0; zb[0] = zb0;
; #pragma unroll
	s_setprio 0
	s_add_i32 s61, s61, 2
	s_add_u32 s2, s2, 0x100
	s_addc_u32 s3, s3, 0
	s_add_u32 s59, s59, 0x100
	s_addc_u32 s60, s60, 0
	s_cmp_gt_u32 s61, 13
	s_cbranch_scc0 .LBB0_693
	v_mov_b32_e32 v141, v147
	v_mov_b32_e32 v140, v146
	global_load_dword v156, v131, s[6:7]
	global_load_dword v157, v131, s[6:7] offset:16
	s_lshl_b32 s2, s56, 8
	s_or_b32 s2, s2, s43
	v_add_u32_e32 v140, s42, v140
	v_lshlrev_b32_e32 v141, 3, v141
	v_add_u32_e32 v142, s2, v141
	v_add_u32_e32 v143, s43, v141
	v_ashrrev_i32_e32 v141, 31, v140
	v_sub_u32_e32 v144, 0x7f, v143
	v_lshlrev_b64 v[140:141], 14, v[140:141]
	v_cvt_f32_i32_e32 v154, v143
	v_ashrrev_i32_e32 v143, 31, v142
	v_cvt_f32_i32_e32 v155, v144
	v_lshl_add_u64 v[140:141], s[70:71], 0, v[140:141]
	s_mov_b32 s3, 0x400000
	v_lshl_add_u64 v[140:141], v[142:143], 1, v[140:141]
	v_add_co_u32_e32 v144, vcc, s3, v140
	s_mov_b64 s[4:5], 0x400000
	s_nop 0
	v_addc_co_u32_e32 v145, vcc, 0, v141, vcc
	v_lshl_add_u64 v[142:143], v[140:141], 0, s[4:5]
	s_waitcnt vmcnt(0)
	v_mul_f32_e32 v158, 0x3fb8aa3b, v156
	v_mul_f32_e32 v159, 0x3fb8aa3b, v157
	v_mul_f32_e32 v160, v158, v155
	v_cmp_lt_f32_e32 vcc, s51, v158
	v_mul_f32_e32 v162, v159, v154
	v_cmp_gt_f32_e64 s[2:3], s49, v159
	v_cndmask_b32_e32 v161, 0, v153, vcc
	v_cmp_gt_f32_e64 s[4:5], s49, v160
	v_cndmask_b32_e64 v163, 0, v153, s[2:3]
	s_and_b64 s[24:25], vcc, exec
	v_cmp_gt_f32_e32 vcc, s49, v162
	v_fmac_f32_e32 v163, 0x3fb8aa3b, v157
	v_cndmask_b32_e64 v157, 0, v153, s[4:5]
	v_cndmask_b32_e32 v162, 0, v153, vcc
	v_fmac_f32_e32 v161, 0xbfb8aa3b, v156
	v_fmac_f32_e32 v157, v158, v155
	v_fmac_f32_e32 v162, v159, v154
	v_exp_f32_e32 v161, v161
	v_exp_f32_e32 v163, v163
	v_exp_f32_e32 v157, v157
	v_exp_f32_e32 v158, v162
	v_cndmask_b32_e64 v160, 0, v152, s[4:5]
	s_cselect_b32 s4, 0xffffffc0, 0
	s_and_b64 s[2:3], s[2:3], exec
	v_cndmask_b32_e32 v156, 0, v152, vcc
	s_cselect_b32 s2, 0xffffffc0, 0
	v_ldexp_f32 v161, v161, s4
	v_ldexp_f32 v162, v163, s2
	v_ldexp_f32 v163, v157, v160
	v_ldexp_f32 v156, v158, v156
	v_mul_f32_e32 v164, v161, v163
	v_mul_f32_e32 v157, v162, v156
	v_mul_f32_e32 v158, v124, v163
	v_mul_f32_e32 v165, v124, v156
	v_mul_f32_e32 v166, v161, v164
	v_mul_f32_e32 v124, v162, v157
	v_mul_f32_e32 v159, v125, v164
	v_mul_f32_e32 v167, v125, v157
	v_mul_f32_e32 v168, v161, v166
	v_mul_f32_e32 v125, v162, v124
	v_cvt_pk_bf16_f32 v158, v158, v159
	v_mul_f32_e32 v159, v126, v166
	v_mul_f32_e32 v169, v126, v124
	v_mul_f32_e32 v170, v161, v168
	v_mul_f32_e32 v126, v162, v125
	v_mul_f32_e32 v171, v161, v170
	v_mul_f32_e32 v172, v162, v126
	v_mul_f32_e32 v160, v127, v168
	v_mul_f32_e32 v174, v161, v171
	v_mul_f32_e32 v175, v162, v172
	v_cvt_pk_bf16_f32 v159, v159, v160
	v_mul_f32_e32 v160, v120, v170
	v_mul_f32_e32 v173, v120, v126
	v_mul_f32_e32 v120, v121, v171
	v_mul_f32_e32 v177, v161, v174
	v_mul_f32_e32 v162, v162, v175
	v_mul_f32_e32 v176, v121, v172
	v_cvt_pk_bf16_f32 v160, v160, v120
	v_mul_f32_e32 v120, v122, v174
	v_mul_f32_e32 v121, v123, v177
	v_mul_f32_e32 v123, v123, v162
	v_cvt_pk_bf16_f32 v161, v120, v121
	v_mul_f32_e32 v127, v127, v125
	v_mul_f32_e32 v178, v122, v175
	v_cvt_pk_bf16_f32 v120, v165, v167
	v_cvt_pk_bf16_f32 v121, v169, v127
	v_cvt_pk_bf16_f32 v122, v173, v176
	v_cvt_pk_bf16_f32 v123, v178, v123
	global_store_dwordx4 v[140:141], v[158:161], off
	global_store_dwordx4 v[144:145], v[120:123], off
	s_nop 1
	v_mul_f32_e32 v120, v116, v163
	v_mul_f32_e32 v121, v117, v164
	v_cvt_pk_bf16_f32 v120, v120, v121
	v_mul_f32_e32 v121, v118, v166
	v_mul_f32_e32 v122, v119, v168
	v_cvt_pk_bf16_f32 v121, v121, v122
	v_mul_f32_e32 v122, v112, v170
	v_mul_f32_e32 v123, v113, v171
	v_cvt_pk_bf16_f32 v122, v122, v123
	v_mul_f32_e32 v123, v114, v174
	v_mul_f32_e32 v116, v116, v156
	v_mul_f32_e32 v117, v117, v157
	v_mul_f32_e32 v127, v115, v177
	v_cvt_pk_bf16_f32 v123, v123, v127
	v_cvt_pk_bf16_f32 v116, v116, v117
	v_mul_f32_e32 v117, v118, v124
	v_mul_f32_e32 v118, v119, v125
	v_mul_f32_e32 v112, v112, v126
	v_mul_f32_e32 v113, v113, v172
	v_cvt_pk_bf16_f32 v117, v117, v118
	v_cvt_pk_bf16_f32 v118, v112, v113
	v_mul_f32_e32 v112, v114, v175
	v_mul_f32_e32 v113, v115, v162
	v_cvt_pk_bf16_f32 v119, v112, v113
	global_store_dwordx4 v[140:141], v[120:123], off offset:256
	global_store_dwordx4 v[142:143], v[116:119], off offset:256
	v_mul_f32_e32 v112, v108, v163
	v_mul_f32_e32 v113, v109, v164
	v_cvt_pk_bf16_f32 v112, v112, v113
	v_mul_f32_e32 v113, v110, v166
	v_mul_f32_e32 v114, v111, v168
	v_cvt_pk_bf16_f32 v113, v113, v114
	v_mul_f32_e32 v114, v104, v170
	v_mul_f32_e32 v115, v105, v171
	v_cvt_pk_bf16_f32 v114, v114, v115
	v_mul_f32_e32 v115, v106, v174
	v_mul_f32_e32 v108, v108, v156
	v_mul_f32_e32 v109, v109, v157
	v_mul_f32_e32 v116, v107, v177
	v_cvt_pk_bf16_f32 v115, v115, v116
	v_cvt_pk_bf16_f32 v108, v108, v109
	v_mul_f32_e32 v109, v110, v124
	v_mul_f32_e32 v110, v111, v125
	v_mul_f32_e32 v104, v104, v126
	s_mov_b64 s[2:3], 0x40000
	v_cvt_pk_bf16_f32 v109, v109, v110
	v_mul_f32_e32 v105, v105, v172
	v_cvt_pk_bf16_f32 v110, v104, v105
	v_mul_f32_e32 v104, v106, v175
	v_lshl_add_u64 v[116:117], v[140:141], 0, s[2:3]
	s_mov_b32 s2, 0x40000
	v_mul_f32_e32 v105, v107, v162
	v_cvt_pk_bf16_f32 v111, v104, v105
	v_add_co_u32_e32 v104, vcc, s2, v140
	s_mov_b64 s[2:3], 0x440000
	s_nop 0
	v_addc_co_u32_e32 v105, vcc, 0, v141, vcc
	global_store_dwordx4 v[104:105], v[112:115], off
	s_nop 1
	v_lshl_add_u64 v[112:113], v[140:141], 0, s[2:3]
	s_mov_b32 s2, 0x440000
	v_add_co_u32_e32 v104, vcc, s2, v140
	s_nop 1
	v_addc_co_u32_e32 v105, vcc, 0, v141, vcc
	global_store_dwordx4 v[104:105], v[108:111], off
	v_mul_f32_e32 v104, v100, v163
	v_mul_f32_e32 v105, v101, v164
;     __device__ __forceinline__ void operator()(const AccT& acc, const Unit& u, int wr, int wc, int fr, int fq) const {
;     ...
;             for (int m = 0; m < 4; ++m) {
;                 const int r = rbase + ai * 128 + m * 16;
;                 const int d = 4 * (2 * m + (fr >> 3)) + j;
; #pragma unroll
;                 for (int bj = 0; bj < 2; ++bj) {
;                     const int t0 = tb + bj * 128;
;                     float v[8];
; #pragma unroll
;                     for (int jj = 0; jj < 4; ++jj) { v[jj] = acc[ai][bj][m][0][jj]; v[4 + jj] = acc[ai][bj][m][1][jj]; }
;                     if constexpr (ROPE) {
;                         const int t = t0 & 2047;
; #pragma unroll
;                         for (int hf = 0; hf < 2; ++hf) {
;                             f32x4 cs, sn;
;                             if (m < 2) { const float c1 = ropeA[(t >> 6) * 16 + d], s1 = ropeA[1024 + (t >> 6) * 16 + d]; cs = (f32x4){c1, c1, c1, c1}; sn = (f32x4){s1, s1, s1, s1}; }
;                             else { const float* cb = ropeA + 2048 + (d - 16) * 64 + (t & 63) + 4 * hf; cs = *(const f32x4*)(cb); sn = *(const f32x4*)(cb + 1024); }
; #pragma unroll
;                             for (int jj = 0; jj < 4; ++jj) { const float pr = __shfl_xor(v[4 * hf + jj], 4); v[4 * hf + jj] = v[4 * hf + jj] * cs[jj] + sgn * pr * sn[jj]; }
;                             __builtin_amdgcn_sched_barrier(0);
;                         }
;                     }
;                     float zf[8], zb[8]; zf[0] = zf0; zb[0] = zb0;
; #pragma unroll
;                     for (int jj = 1; jj < 8; ++jj) { zf[jj] = zf[jj - 1] * zfs; zb[jj] = zb[jj - 1] * zbs; }
;                     u32x4 wf, wb;
;                     wf.x = cvt_pk_bf16(v[0] * zf[0], v[1] * zf[1]); wf.y = cvt_pk_bf16(v[2] * zf[2], v[3] * zf[3]); wf.z = cvt_pk_bf16(v[4] * zf[4], v[5] * zf[5]); wf.w = cvt_pk_bf16(v[6] * zf[6], v[7] * zf[7]);
;                     wb.x = cvt_pk_bf16(v[0] * zb[0], v[1] * zb[1]); wb.y = cvt_pk_bf16(v[2] * zb[2], v[3] * zb[3]); wb.z = cvt_pk_bf16(v[4] * zb[4], v[5] * zb[5]); wb.w = cvt_pk_bf16(v[6] * zb[6], v[7] * zb[7]);
;                     *(u32x4*)(KTZ + (size_t)r * NT + t0) = wf;
;                     *(u32x4*)(KTZ + (size_t)(256 + r) * NT + t0) = wb;
	v_cvt_pk_bf16_f32 v104, v104, v105
	v_mul_f32_e32 v105, v102, v166
	v_mul_f32_e32 v106, v103, v168
	v_cvt_pk_bf16_f32 v105, v105, v106
	v_mul_f32_e32 v106, v96, v170
	v_mul_f32_e32 v107, v97, v171
	v_cvt_pk_bf16_f32 v106, v106, v107
	v_mul_f32_e32 v107, v98, v174
	v_mul_f32_e32 v100, v100, v156
	v_mul_f32_e32 v101, v101, v157
	v_mul_f32_e32 v108, v99, v177
	v_cvt_pk_bf16_f32 v107, v107, v108
	v_cvt_pk_bf16_f32 v100, v100, v101
	v_mul_f32_e32 v101, v102, v124
	v_mul_f32_e32 v102, v103, v125
	v_mul_f32_e32 v96, v96, v126
	v_mul_f32_e32 v97, v97, v172
	v_cvt_pk_bf16_f32 v101, v101, v102
	v_cvt_pk_bf16_f32 v102, v96, v97
	v_mul_f32_e32 v96, v98, v175
	v_mul_f32_e32 v97, v99, v162
	v_cvt_pk_bf16_f32 v103, v96, v97
	global_store_dwordx4 v[116:117], v[104:107], off offset:256
	global_store_dwordx4 v[112:113], v[100:103], off offset:256
	v_mul_f32_e32 v96, v92, v163
	v_mul_f32_e32 v97, v93, v164
	v_cvt_pk_bf16_f32 v96, v96, v97
	v_mul_f32_e32 v97, v94, v166
	v_mul_f32_e32 v98, v95, v168
	v_cvt_pk_bf16_f32 v97, v97, v98
	v_mul_f32_e32 v98, v88, v170
	v_mul_f32_e32 v99, v89, v171
	v_cvt_pk_bf16_f32 v98, v98, v99
	v_mul_f32_e32 v99, v90, v174
	v_mul_f32_e32 v92, v92, v156
	v_mul_f32_e32 v93, v93, v157
	v_mul_f32_e32 v100, v91, v177
	v_cvt_pk_bf16_f32 v99, v99, v100
	v_cvt_pk_bf16_f32 v92, v92, v93
	v_mul_f32_e32 v93, v94, v124
	v_mul_f32_e32 v94, v95, v125
	v_mul_f32_e32 v88, v88, v126
	s_mov_b64 s[2:3], 0x80000
	v_cvt_pk_bf16_f32 v93, v93, v94
	v_mul_f32_e32 v89, v89, v172
	v_cvt_pk_bf16_f32 v94, v88, v89
	v_mul_f32_e32 v88, v90, v175
	v_lshl_add_u64 v[100:101], v[140:141], 0, s[2:3]
	s_mov_b32 s2, 0x80000
	v_mul_f32_e32 v89, v91, v162
	v_cvt_pk_bf16_f32 v95, v88, v89
	v_add_co_u32_e32 v88, vcc, s2, v140
	s_mov_b64 s[2:3], 0x480000
	s_nop 0
	v_addc_co_u32_e32 v89, vcc, 0, v141, vcc
	global_store_dwordx4 v[88:89], v[96:99], off
	s_nop 1
	v_lshl_add_u64 v[96:97], v[140:141], 0, s[2:3]
	s_mov_b32 s2, 0x480000
	v_add_co_u32_e32 v88, vcc, s2, v140
	s_nop 1
	v_addc_co_u32_e32 v89, vcc, 0, v141, vcc
	global_store_dwordx4 v[88:89], v[92:95], off
	v_mul_f32_e32 v88, v84, v163
	v_mul_f32_e32 v89, v85, v164
	v_cvt_pk_bf16_f32 v88, v88, v89
	v_mul_f32_e32 v89, v86, v166
	v_mul_f32_e32 v90, v87, v168
	v_cvt_pk_bf16_f32 v89, v89, v90
	v_mul_f32_e32 v90, v80, v170
	v_mul_f32_e32 v91, v81, v171
	v_cvt_pk_bf16_f32 v90, v90, v91
	v_mul_f32_e32 v91, v82, v174
	v_mul_f32_e32 v84, v84, v156
	v_mul_f32_e32 v85, v85, v157
	v_mul_f32_e32 v92, v83, v177
	v_cvt_pk_bf16_f32 v91, v91, v92
	v_cvt_pk_bf16_f32 v84, v84, v85
	v_mul_f32_e32 v85, v86, v124
	v_mul_f32_e32 v86, v87, v125
	v_mul_f32_e32 v80, v80, v126
	v_mul_f32_e32 v81, v81, v172
	v_cvt_pk_bf16_f32 v85, v85, v86
	v_cvt_pk_bf16_f32 v86, v80, v81
	v_mul_f32_e32 v80, v82, v175
	v_mul_f32_e32 v81, v83, v162
	v_cvt_pk_bf16_f32 v87, v80, v81
	global_store_dwordx4 v[100:101], v[88:91], off offset:256
	global_store_dwordx4 v[96:97], v[84:87], off offset:256
	v_mul_f32_e32 v80, v76, v163
	v_mul_f32_e32 v81, v77, v164
	v_cvt_pk_bf16_f32 v80, v80, v81
	v_mul_f32_e32 v81, v78, v166
	v_mul_f32_e32 v82, v79, v168
	v_cvt_pk_bf16_f32 v81, v81, v82
	v_mul_f32_e32 v82, v72, v170
	v_mul_f32_e32 v83, v73, v171
	v_cvt_pk_bf16_f32 v82, v82, v83
	v_mul_f32_e32 v83, v74, v174
	v_mul_f32_e32 v76, v76, v156
	v_mul_f32_e32 v77, v77, v157
	v_mul_f32_e32 v84, v75, v177
	v_cvt_pk_bf16_f32 v83, v83, v84
	v_cvt_pk_bf16_f32 v76, v76, v77
	v_mul_f32_e32 v77, v78, v124
	v_mul_f32_e32 v78, v79, v125
	v_mul_f32_e32 v72, v72, v126
	s_mov_b64 s[2:3], 0xc0000
	v_cvt_pk_bf16_f32 v77, v77, v78
	v_mul_f32_e32 v73, v73, v172
	v_cvt_pk_bf16_f32 v78, v72, v73
	v_mul_f32_e32 v72, v74, v175
	v_lshl_add_u64 v[84:85], v[140:141], 0, s[2:3]
	s_mov_b32 s2, 0xc0000
	v_mul_f32_e32 v73, v75, v162
	v_cvt_pk_bf16_f32 v79, v72, v73
	v_add_co_u32_e32 v72, vcc, s2, v140
	s_mov_b64 s[2:3], 0x4c0000
	s_nop 0
	v_addc_co_u32_e32 v73, vcc, 0, v141, vcc
	global_store_dwordx4 v[72:73], v[80:83], off
	s_nop 1
	v_lshl_add_u64 v[80:81], v[140:141], 0, s[2:3]
	s_mov_b32 s2, 0x4c0000
	v_add_co_u32_e32 v72, vcc, s2, v140
	s_nop 1
	v_addc_co_u32_e32 v73, vcc, 0, v141, vcc
	global_store_dwordx4 v[72:73], v[76:79], off
	v_mul_f32_e32 v72, v68, v163
	v_mul_f32_e32 v73, v69, v164
	v_cvt_pk_bf16_f32 v72, v72, v73
	v_mul_f32_e32 v73, v70, v166
	v_mul_f32_e32 v74, v71, v168
	v_cvt_pk_bf16_f32 v73, v73, v74
	v_mul_f32_e32 v74, v64, v170
	v_mul_f32_e32 v75, v65, v171
	v_cvt_pk_bf16_f32 v74, v74, v75
	v_mul_f32_e32 v75, v66, v174
	v_mul_f32_e32 v68, v68, v156
	v_mul_f32_e32 v69, v69, v157
	v_mul_f32_e32 v76, v67, v177
	v_cvt_pk_bf16_f32 v75, v75, v76
	v_cvt_pk_bf16_f32 v68, v68, v69
	v_mul_f32_e32 v69, v70, v124
	v_mul_f32_e32 v70, v71, v125
	v_mul_f32_e32 v64, v64, v126
	v_mul_f32_e32 v65, v65, v172
	v_cvt_pk_bf16_f32 v69, v69, v70
	v_cvt_pk_bf16_f32 v70, v64, v65
	v_mul_f32_e32 v64, v66, v175
	v_mul_f32_e32 v65, v67, v162
	v_cvt_pk_bf16_f32 v71, v64, v65
	global_store_dwordx4 v[84:85], v[72:75], off offset:256
	global_store_dwordx4 v[80:81], v[68:71], off offset:256
	global_load_dword v70, v131, s[6:7] offset:8
	s_nop 0
	global_load_dword v71, v131, s[6:7] offset:24
	s_mov_b32 s17, 0x200000
	v_add_co_u32_e32 v76, vcc, s17, v140
	s_mov_b32 s19, 0x600000
	s_nop 0
	v_addc_co_u32_e32 v77, vcc, 0, v141, vcc
	v_add_co_u32_e32 v68, vcc, s19, v140
	s_mov_b64 s[2:3], 0x200000
	s_nop 0
	v_addc_co_u32_e32 v69, vcc, 0, v141, vcc
	s_mov_b64 s[4:5], 0x600000
	v_lshl_add_u64 v[64:65], v[140:141], 0, s[2:3]
	v_lshl_add_u64 v[66:67], v[140:141], 0, s[4:5]
	s_waitcnt vmcnt(0)
;     __device__ __forceinline__ void operator()(const AccT& acc, const Unit& u, int wr, int wc, int fr, int fq) const {
;     ...
;         for (int ai = 0; ai < 2; ++ai) {
;             const int hh = 2 * ai + wr;
;             const float l2f = lgd[hh] * 1.4426950408889634f, l2b = lgd[4 + hh] * 1.4426950408889634f;
;             const float zf0 = exp2f((float)(127 - o0) * l2f), zfs = exp2f(-l2f), zb0 = exp2f((float)o0 * l2b), zbs = exp2f(l2b);
; #pragma unroll
;             for (int m = 0; m < 4; ++m) {
;                 const int r = rbase + ai * 128 + m * 16;
;                 const int d = 4 * (2 * m + (fr >> 3)) + j;
; #pragma unroll
;                 for (int bj = 0; bj < 2; ++bj) {
;                     const int t0 = tb + bj * 128;
;                     float v[8];
; #pragma unroll
;                     for (int jj = 0; jj < 4; ++jj) { v[jj] = acc[ai][bj][m][0][jj]; v[4 + jj] = acc[ai][bj][m][1][jj]; }
;                     if constexpr (ROPE) {
;                         const int t = t0 & 2047;
; #pragma unroll
;                         for (int hf = 0; hf < 2; ++hf) {
;                             f32x4 cs, sn;
;                             if (m < 2) { const float c1 = ropeA[(t >> 6) * 16 + d], s1 = ropeA[1024 + (t >> 6) * 16 + d]; cs = (f32x4){c1, c1, c1, c1}; sn = (f32x4){s1, s1, s1, s1}; }
;                             else { const float* cb = ropeA + 2048 + (d - 16) * 64 + (t & 63) + 4 * hf; cs = *(const f32x4*)(cb); sn = *(const f32x4*)(cb + 1024); }
; #pragma unroll
;                             for (int jj = 0; jj < 4; ++jj) { const float pr = __shfl_xor(v[4 * hf + jj], 4); v[4 * hf + jj] = v[4 * hf + jj] * cs[jj] + sgn * pr * sn[jj]; }
;                             __builtin_amdgcn_sched_barrier(0);
;                         }
;                     }
;                     float zf[8], zb[8]; zf[0] = zf0; zb[0] = zb0;
; #pragma unroll
;                     for (int jj = 1; jj < 8; ++jj) { zf[jj] = zf[jj - 1] * zfs; zb[jj] = zb[jj - 1] * zbs; }
;                     u32x4 wf, wb;
;                     wf.x = cvt_pk_bf16(v[0] * zf[0], v[1] * zf[1]); wf.y = cvt_pk_bf16(v[2] * zf[2], v[3] * zf[3]); wf.z = cvt_pk_bf16(v[4] * zf[4], v[5] * zf[5]); wf.w = cvt_pk_bf16(v[6] * zf[6], v[7] * zf[7]);
	v_mul_f32_e32 v72, 0x3fb8aa3b, v70
	v_mul_f32_e32 v73, 0x3fb8aa3b, v71
	v_mul_f32_e32 v74, v72, v155
	v_cmp_lt_f32_e32 vcc, s51, v72
	v_mul_f32_e32 v78, v73, v154
	v_cmp_gt_f32_e64 s[2:3], s49, v73
	v_cndmask_b32_e32 v75, 0, v153, vcc
	v_cmp_gt_f32_e64 s[4:5], s49, v74
	v_cndmask_b32_e64 v79, 0, v153, s[2:3]
	s_and_b64 s[24:25], vcc, exec
	v_cmp_gt_f32_e32 vcc, s49, v78
	v_fmac_f32_e32 v79, 0x3fb8aa3b, v71
	v_cndmask_b32_e64 v71, 0, v153, s[4:5]
	v_cndmask_b32_e32 v78, 0, v153, vcc
	v_fmac_f32_e32 v75, 0xbfb8aa3b, v70
	v_fmac_f32_e32 v71, v72, v155
	v_fmac_f32_e32 v78, v73, v154
	v_exp_f32_e32 v75, v75
	v_exp_f32_e32 v79, v79
	v_exp_f32_e32 v71, v71
	v_exp_f32_e32 v72, v78
	v_cndmask_b32_e64 v74, 0, v152, s[4:5]
	s_cselect_b32 s4, 0xffffffc0, 0
	s_and_b64 s[2:3], s[2:3], exec
	v_cndmask_b32_e32 v70, 0, v152, vcc
	s_cselect_b32 s2, 0xffffffc0, 0
	v_ldexp_f32 v75, v75, s4
	v_ldexp_f32 v78, v79, s2
	v_ldexp_f32 v79, v71, v74
	v_ldexp_f32 v70, v72, v70
	v_mul_f32_e32 v80, v75, v79
	v_mul_f32_e32 v71, v78, v70
	v_mul_f32_e32 v72, v60, v79
	v_mul_f32_e32 v81, v60, v70
	v_mul_f32_e32 v82, v75, v80
	v_mul_f32_e32 v60, v78, v71
	v_mul_f32_e32 v83, v75, v82
	v_mul_f32_e32 v84, v78, v60
	v_mul_f32_e32 v85, v75, v83
	v_mul_f32_e32 v86, v78, v84
	v_mul_f32_e32 v73, v61, v80
	v_mul_f32_e32 v87, v75, v85
	v_mul_f32_e32 v88, v78, v86
	v_cvt_pk_bf16_f32 v72, v72, v73
	v_mul_f32_e32 v73, v62, v82
	v_mul_f32_e32 v74, v63, v83
	v_mul_f32_e32 v90, v75, v87
	v_mul_f32_e32 v91, v78, v88
	v_cvt_pk_bf16_f32 v73, v73, v74
	v_mul_f32_e32 v74, v56, v85
	v_mul_f32_e32 v89, v56, v86
	v_mul_f32_e32 v56, v57, v87
	v_mul_f32_e32 v93, v75, v90
	v_mul_f32_e32 v78, v78, v91
	v_mul_f32_e32 v92, v57, v88
	v_cvt_pk_bf16_f32 v74, v74, v56
	v_mul_f32_e32 v56, v58, v90
	v_mul_f32_e32 v57, v59, v93
	v_mul_f32_e32 v59, v59, v78
	v_cvt_pk_bf16_f32 v75, v56, v57
	v_mul_f32_e32 v61, v61, v71
	v_mul_f32_e32 v62, v62, v60
	v_mul_f32_e32 v63, v63, v84
	v_mul_f32_e32 v94, v58, v91
	v_cvt_pk_bf16_f32 v56, v81, v61
	v_cvt_pk_bf16_f32 v57, v62, v63
	v_cvt_pk_bf16_f32 v58, v89, v92
	v_cvt_pk_bf16_f32 v59, v94, v59
	global_store_dwordx4 v[76:77], v[72:75], off
	global_store_dwordx4 v[68:69], v[56:59], off
	s_nop 1
	v_mul_f32_e32 v56, v52, v79
	v_mul_f32_e32 v57, v53, v80
	v_cvt_pk_bf16_f32 v56, v56, v57
	v_mul_f32_e32 v57, v54, v82
	v_mul_f32_e32 v58, v55, v83
	v_cvt_pk_bf16_f32 v57, v57, v58
	v_mul_f32_e32 v58, v48, v85
	v_mul_f32_e32 v59, v49, v87
	v_cvt_pk_bf16_f32 v58, v58, v59
	v_mul_f32_e32 v59, v50, v90
	v_mul_f32_e32 v52, v52, v70
	v_mul_f32_e32 v53, v53, v71
	v_mul_f32_e32 v61, v51, v93
	v_cvt_pk_bf16_f32 v59, v59, v61
	v_cvt_pk_bf16_f32 v52, v52, v53
	v_mul_f32_e32 v53, v54, v60
	v_mul_f32_e32 v54, v55, v84
	v_mul_f32_e32 v48, v48, v86
	v_mul_f32_e32 v49, v49, v88
	v_cvt_pk_bf16_f32 v53, v53, v54
	v_cvt_pk_bf16_f32 v54, v48, v49
	v_mul_f32_e32 v48, v50, v91
	v_mul_f32_e32 v49, v51, v78
	v_cvt_pk_bf16_f32 v55, v48, v49
	global_store_dwordx4 v[64:65], v[56:59], off offset:256
	global_store_dwordx4 v[66:67], v[52:55], off offset:256
	v_mul_f32_e32 v48, v44, v79
	v_mul_f32_e32 v49, v45, v80
	v_cvt_pk_bf16_f32 v48, v48, v49
	v_mul_f32_e32 v49, v46, v82
	v_mul_f32_e32 v50, v47, v83
	v_cvt_pk_bf16_f32 v49, v49, v50
	v_mul_f32_e32 v50, v40, v85
	v_mul_f32_e32 v51, v41, v87
	v_cvt_pk_bf16_f32 v50, v50, v51
	v_mul_f32_e32 v51, v42, v90
	v_mul_f32_e32 v44, v44, v70
	v_mul_f32_e32 v45, v45, v71
	v_mul_f32_e32 v52, v43, v93
	v_cvt_pk_bf16_f32 v51, v51, v52
	v_cvt_pk_bf16_f32 v44, v44, v45
	v_mul_f32_e32 v45, v46, v60
	v_mul_f32_e32 v46, v47, v84
	v_mul_f32_e32 v40, v40, v86
	s_mov_b64 s[2:3], 0x240000
	v_cvt_pk_bf16_f32 v45, v45, v46
	v_mul_f32_e32 v41, v41, v88
	v_cvt_pk_bf16_f32 v46, v40, v41
	v_mul_f32_e32 v40, v42, v91
	v_lshl_add_u64 v[52:53], v[140:141], 0, s[2:3]
	s_mov_b32 s2, 0x240000
	v_mul_f32_e32 v41, v43, v78
	v_cvt_pk_bf16_f32 v47, v40, v41
	v_add_co_u32_e32 v40, vcc, s2, v140
	s_mov_b64 s[2:3], 0x640000
	s_nop 0
	v_addc_co_u32_e32 v41, vcc, 0, v141, vcc
	global_store_dwordx4 v[40:41], v[48:51], off
	s_nop 1
	v_lshl_add_u64 v[48:49], v[140:141], 0, s[2:3]
	s_mov_b32 s2, 0x640000
	v_add_co_u32_e32 v40, vcc, s2, v140
	s_nop 1
	v_addc_co_u32_e32 v41, vcc, 0, v141, vcc
	global_store_dwordx4 v[40:41], v[44:47], off
	v_mul_f32_e32 v40, v36, v79
	v_mul_f32_e32 v41, v37, v80
	v_cvt_pk_bf16_f32 v40, v40, v41
	v_mul_f32_e32 v41, v38, v82
	v_mul_f32_e32 v42, v39, v83
	v_cvt_pk_bf16_f32 v41, v41, v42
	v_mul_f32_e32 v42, v32, v85
	v_mul_f32_e32 v43, v33, v87
	v_cvt_pk_bf16_f32 v42, v42, v43
	v_mul_f32_e32 v43, v34, v90
	v_mul_f32_e32 v36, v36, v70
;     __device__ __forceinline__ void operator()(const AccT& acc, const Unit& u, int wr, int wc, int fr, int fq) const {
;     ...
;             for (int m = 0; m < 4; ++m) {
;                 const int r = rbase + ai * 128 + m * 16;
;                 const int d = 4 * (2 * m + (fr >> 3)) + j;
; #pragma unroll
;                 for (int bj = 0; bj < 2; ++bj) {
;                     const int t0 = tb + bj * 128;
;                     float v[8];
; #pragma unroll
;                     for (int jj = 0; jj < 4; ++jj) { v[jj] = acc[ai][bj][m][0][jj]; v[4 + jj] = acc[ai][bj][m][1][jj]; }
;                     if constexpr (ROPE) {
;                         const int t = t0 & 2047;
; #pragma unroll
;                         for (int hf = 0; hf < 2; ++hf) {
;                             f32x4 cs, sn;
;                             if (m < 2) { const float c1 = ropeA[(t >> 6) * 16 + d], s1 = ropeA[1024 + (t >> 6) * 16 + d]; cs = (f32x4){c1, c1, c1, c1}; sn = (f32x4){s1, s1, s1, s1}; }
;                             else { const float* cb = ropeA + 2048 + (d - 16) * 64 + (t & 63) + 4 * hf; cs = *(const f32x4*)(cb); sn = *(const f32x4*)(cb + 1024); }
; #pragma unroll
;                             for (int jj = 0; jj < 4; ++jj) { const float pr = __shfl_xor(v[4 * hf + jj], 4); v[4 * hf + jj] = v[4 * hf + jj] * cs[jj] + sgn * pr * sn[jj]; }
;                             __builtin_amdgcn_sched_barrier(0);
;                         }
;                     }
;                     float zf[8], zb[8]; zf[0] = zf0; zb[0] = zb0;
; #pragma unroll
;                     for (int jj = 1; jj < 8; ++jj) { zf[jj] = zf[jj - 1] * zfs; zb[jj] = zb[jj - 1] * zbs; }
;                     u32x4 wf, wb;
;                     wf.x = cvt_pk_bf16(v[0] * zf[0], v[1] * zf[1]); wf.y = cvt_pk_bf16(v[2] * zf[2], v[3] * zf[3]); wf.z = cvt_pk_bf16(v[4] * zf[4], v[5] * zf[5]); wf.w = cvt_pk_bf16(v[6] * zf[6], v[7] * zf[7]);
;                     wb.x = cvt_pk_bf16(v[0] * zb[0], v[1] * zb[1]); wb.y = cvt_pk_bf16(v[2] * zb[2], v[3] * zb[3]); wb.z = cvt_pk_bf16(v[4] * zb[4], v[5] * zb[5]); wb.w = cvt_pk_bf16(v[6] * zb[6], v[7] * zb[7]);
;                     *(u32x4*)(KTZ + (size_t)r * NT + t0) = wf;
;                     *(u32x4*)(KTZ + (size_t)(256 + r) * NT + t0) = wb;
	v_mul_f32_e32 v37, v37, v71
	v_mul_f32_e32 v44, v35, v93
	v_cvt_pk_bf16_f32 v43, v43, v44
	v_cvt_pk_bf16_f32 v36, v36, v37
	v_mul_f32_e32 v37, v38, v60
	v_mul_f32_e32 v38, v39, v84
	v_mul_f32_e32 v32, v32, v86
	v_mul_f32_e32 v33, v33, v88
	v_cvt_pk_bf16_f32 v37, v37, v38
	v_cvt_pk_bf16_f32 v38, v32, v33
	v_mul_f32_e32 v32, v34, v91
	v_mul_f32_e32 v33, v35, v78
	v_cvt_pk_bf16_f32 v39, v32, v33
	global_store_dwordx4 v[52:53], v[40:43], off offset:256
	global_store_dwordx4 v[48:49], v[36:39], off offset:256
	v_mul_f32_e32 v32, v28, v79
	v_mul_f32_e32 v33, v29, v80
	v_cvt_pk_bf16_f32 v32, v32, v33
	v_mul_f32_e32 v33, v30, v82
	v_mul_f32_e32 v34, v31, v83
	v_cvt_pk_bf16_f32 v33, v33, v34
	v_mul_f32_e32 v34, v24, v85
	v_mul_f32_e32 v35, v25, v87
	v_cvt_pk_bf16_f32 v34, v34, v35
	v_mul_f32_e32 v35, v26, v90
	v_mul_f32_e32 v28, v28, v70
	v_mul_f32_e32 v29, v29, v71
	v_mul_f32_e32 v36, v27, v93
	v_cvt_pk_bf16_f32 v35, v35, v36
	v_cvt_pk_bf16_f32 v28, v28, v29
	v_mul_f32_e32 v29, v30, v60
	v_mul_f32_e32 v30, v31, v84
	v_mul_f32_e32 v24, v24, v86
	v_cvt_pk_bf16_f32 v29, v29, v30
	v_mul_f32_e32 v25, v25, v88
	v_cvt_pk_bf16_f32 v30, v24, v25
	v_mul_f32_e32 v24, v26, v91
	v_mul_f32_e32 v25, v27, v78
	v_cvt_pk_bf16_f32 v31, v24, v25
	v_add_co_u32_e32 v24, vcc, s52, v140
	s_mov_b64 s[2:3], 0x280000
	s_nop 0
	v_addc_co_u32_e32 v25, vcc, 0, v141, vcc
	global_store_dwordx4 v[24:25], v[32:35], off
	v_add_co_u32_e32 v24, vcc, s53, v140
	v_lshl_add_u64 v[36:37], v[140:141], 0, s[2:3]
	s_nop 0
	v_addc_co_u32_e32 v25, vcc, 0, v141, vcc
	v_lshl_add_u64 v[32:33], v[140:141], 0, s[8:9]
	global_store_dwordx4 v[24:25], v[28:31], off
	v_mul_f32_e32 v24, v20, v79
	v_mul_f32_e32 v25, v21, v80
	v_cvt_pk_bf16_f32 v24, v24, v25
	v_mul_f32_e32 v25, v22, v82
	v_mul_f32_e32 v26, v23, v83
	v_cvt_pk_bf16_f32 v25, v25, v26
	v_mul_f32_e32 v26, v16, v85
	v_mul_f32_e32 v27, v17, v87
	v_cvt_pk_bf16_f32 v26, v26, v27
	v_mul_f32_e32 v27, v18, v90
	v_mul_f32_e32 v20, v20, v70
	v_mul_f32_e32 v21, v21, v71
	v_mul_f32_e32 v28, v19, v93
	v_cvt_pk_bf16_f32 v27, v27, v28
	v_cvt_pk_bf16_f32 v20, v20, v21
	v_mul_f32_e32 v21, v22, v60
	v_mul_f32_e32 v22, v23, v84
	v_mul_f32_e32 v16, v16, v86
	v_mul_f32_e32 v17, v17, v88
	v_cvt_pk_bf16_f32 v21, v21, v22
	v_cvt_pk_bf16_f32 v22, v16, v17
	v_mul_f32_e32 v16, v18, v91
	v_mul_f32_e32 v17, v19, v78
	v_cvt_pk_bf16_f32 v23, v16, v17
	global_store_dwordx4 v[36:37], v[24:27], off offset:256
	global_store_dwordx4 v[32:33], v[20:23], off offset:256
	v_mul_f32_e32 v16, v12, v79
	v_mul_f32_e32 v17, v13, v80
	v_cvt_pk_bf16_f32 v16, v16, v17
	v_mul_f32_e32 v17, v14, v82
	v_mul_f32_e32 v18, v15, v83
	v_cvt_pk_bf16_f32 v17, v17, v18
	v_mul_f32_e32 v18, v8, v85
	v_mul_f32_e32 v19, v9, v87
	v_cvt_pk_bf16_f32 v18, v18, v19
	v_mul_f32_e32 v19, v10, v90
	v_mul_f32_e32 v12, v12, v70
	v_mul_f32_e32 v13, v13, v71
	v_mul_f32_e32 v20, v11, v93
	v_cvt_pk_bf16_f32 v19, v19, v20
	v_cvt_pk_bf16_f32 v12, v12, v13
	v_mul_f32_e32 v13, v14, v60
	v_mul_f32_e32 v14, v15, v84
	v_mul_f32_e32 v8, v8, v86
	v_cvt_pk_bf16_f32 v13, v13, v14
	v_mul_f32_e32 v9, v9, v88
	v_cvt_pk_bf16_f32 v14, v8, v9
	v_mul_f32_e32 v8, v10, v91
	v_mul_f32_e32 v9, v11, v78
	v_cvt_pk_bf16_f32 v15, v8, v9
	v_add_co_u32_e32 v8, vcc, s54, v140
	v_lshl_add_u64 v[20:21], v[140:141], 0, s[10:11]
	s_nop 0
	v_addc_co_u32_e32 v9, vcc, 0, v141, vcc
	global_store_dwordx4 v[8:9], v[16:19], off
	v_add_co_u32_e32 v8, vcc, s55, v140
	s_nop 0
	v_lshl_add_u64 v[16:17], v[140:141], 0, s[12:13]
	v_addc_co_u32_e32 v9, vcc, 0, v141, vcc
	global_store_dwordx4 v[8:9], v[12:15], off
	v_mul_f32_e32 v8, v4, v79
	v_mul_f32_e32 v9, v5, v80
	v_cvt_pk_bf16_f32 v8, v8, v9
	v_mul_f32_e32 v9, v6, v82
	v_mul_f32_e32 v10, v7, v83
	v_cvt_pk_bf16_f32 v9, v9, v10
	v_mul_f32_e32 v10, v0, v85
	v_mul_f32_e32 v11, v1, v87
	v_cvt_pk_bf16_f32 v10, v10, v11
	v_mul_f32_e32 v11, v2, v90
	v_mul_f32_e32 v4, v4, v70
	v_mul_f32_e32 v5, v5, v71
	v_mul_f32_e32 v12, v3, v93
	v_cvt_pk_bf16_f32 v11, v11, v12
	v_cvt_pk_bf16_f32 v4, v4, v5
	v_mul_f32_e32 v5, v6, v60
	v_mul_f32_e32 v6, v7, v84
	v_mul_f32_e32 v0, v0, v86
	v_mul_f32_e32 v1, v1, v88
	v_cvt_pk_bf16_f32 v5, v5, v6
	v_cvt_pk_bf16_f32 v6, v0, v1
	v_mul_f32_e32 v0, v2, v91
	v_mul_f32_e32 v1, v3, v78
	v_cvt_pk_bf16_f32 v7, v0, v1
	global_store_dwordx4 v[20:21], v[8:11], off offset:256
	global_store_dwordx4 v[16:17], v[4:7], off offset:256
	s_and_b64 vcc, exec, s[14:15]
	s_mov_b32 s56, s16
	s_mov_b64 s[4:5], s[22:23]
	s_mov_b64 s[2:3], s[20:21]
	s_cbranch_vccz .LBB0_686
	s_waitcnt vmcnt(0)
	s_cmpk_gt_u32 s27, 0xff
	s_cbranch_scc1 .LBB0_697
	s_barrier

; #define PG8_STAGE(bufoff, gbase, voff) do { _Pragma("unroll") for (int _i = 0; _i < 2; ++_i) \
;         __builtin_amdgcn_global_load_lds((const unsigned*)((const char*)(gbase) + (voff)[_i]), (LAS unsigned*)(lds + (bufoff) + ldsw + _i * 8192), 16, 0, 0); } while (0)
; #define PG8_LDA(dst, b, h) do { _Pragma("unroll") for (int m = 0; m < 4; ++m) _Pragma("unroll") for (int k = 0; k < 2; ++k) dst[m][k] = *(const LAS bf16x8*)(lds + PG8_SA(b, h) + aoff + m * 2048 + k * 1024); } while (0)
; #define PG8_LDB(dst, b, h) do { _Pragma("unroll") for (int n = 0; n < 2; ++n) _Pragma("unroll") for (int k = 0; k < 2; ++k) dst[n][k] = *(const LAS bf16x8*)(lds + PG8_SB(b, h) + boff + n * 2048 + k * 1024); } while (0)
; #define PG8_WAIT_V(n) asm volatile("s_waitcnt vmcnt(" #n ")" ::: "memory")
; #define PG8_WAIT_L(n) asm volatile("s_waitcnt lgkmcnt(" #n ")" ::: "memory")
; #define PG8_BAR __builtin_amdgcn_s_barrier()
; #define PG8_SCHED __builtin_amdgcn_sched_barrier(0)
; template <class Epi, class Sched>
; __device__ __forceinline__ void gemm_phase(LAS unsigned char* lds, const Gemm g, const Sched& S, const Epi& E) {
;     ...
;         const bool has_next = S.next(ui + 1, nxt);
;         const char* nA = has_next ? (const char*)g.A + (size_t)nxt.pm * tstep : cA; const char* nB = has_next ? (const char*)g.Bt + (size_t)nxt.pn * tstep : cB;
;         for (int t = 0; t < nt; t += 2) {
;             const bool last = (t == nt - 2);
;             const char* a1 = cA + (size_t)(t + 1) * kstep;
;             const char* a2 = last ? nA : cA + (size_t)(t + 2) * kstep; const char* b2 = last ? nB : cB + (size_t)(t + 2) * kstep;
;             const char* a3 = a2 + kstep; const char* b3 = b2 + kstep;
;             PG8_LDB(B0, 0, 0); PG8_SCHED; PG8_LDA(At, 0, 0); PG8_STAGE(PG8_SA(1, 1), a1 + hstep, voffA);
;             PG8_WAIT_L(8); PG8_BAR; PG8_WAIT_L(0); PG8_MMA(0, 0, At, B0); PG8_BAR; PG8_SCHED;
;             PG8_LDB(B1, 0, 1); PG8_STAGE(PG8_SB(0, 0), b2, voffB);
;             PG8_BAR; PG8_WAIT_L(0); PG8_MMA(0, 1, At, B1); PG8_BAR;
;             PG8_LDA(At, 0, 1); PG8_STAGE(PG8_SA(0, 0), a2, voffA);
;             PG8_BAR; PG8_WAIT_L(0); PG8_MMA(1, 0, At, B0); PG8_BAR; PG8_SCHED;
;             PG8_STAGE(PG8_SB(0, 1), b2 + hstep, voffB);
;             PG8_WAIT_V(6); PG8_BAR; PG8_MMA(1, 1, At, B1); PG8_BAR;
.LBB0_712:
	s_ashr_i32 s15, s14, 31
	v_cmp_lt_i64_e64 s[26:27], s[16:17], 64
	s_lshl_b64 s[16:17], s[14:15], 19
	s_add_u32 s16, s38, s16
	s_addc_u32 s17, s39, s17
	s_and_b64 s[18:19], s[26:27], exec
	s_cselect_b32 s15, s17, s23
	s_cselect_b32 s54, s16, s22
	s_ashr_i32 s13, s12, 31
	s_lshl_b64 s[18:19], s[12:13], 19
	s_add_u32 s18, s28, s18
	s_addc_u32 s19, s29, s19
	s_and_b64 s[26:27], s[26:27], exec
	s_cselect_b32 s13, s19, s25
	s_cselect_b32 s55, s18, s24
	s_add_u32 s22, s22, 0x40080
	s_addc_u32 s23, s23, 0
	s_add_u32 s56, s24, 0x100
	s_addc_u32 s57, s25, 0
	s_mov_b32 s58, -2
	s_waitcnt lgkmcnt(0)
	ds_read_b128 v[146:149], v143
	ds_read_b128 v[150:153], v143 offset:1024
	ds_read_b128 v[154:157], v143 offset:2048
	ds_read_b128 v[158:161], v143 offset:3072
	s_add_u32 s24, s22, 0xfffc0080
	s_addc_u32 s25, s23, -1
	s_cmp_eq_u32 s58, 12
	s_cselect_b32 s27, s15, s25
	s_cselect_b32 s26, s54, s24
	s_cselect_b32 s25, s13, s57
	s_cselect_b32 s24, s55, s56
	s_add_i32 m0, s21, 0xc000
	ds_read_b128 v[162:165], v144
	ds_read_b128 v[166:169], v144 offset:1024
	ds_read_b128 v[170:173], v144 offset:2048
	ds_read_b128 v[174:177], v144 offset:3072
	ds_read_b128 v[178:181], v144 offset:4096
	ds_read_b128 v[182:185], v144 offset:5120
	ds_read_b128 v[186:189], v144 offset:6144
	ds_read_b128 v[190:193], v144 offset:7168
	global_load_lds_dwordx4 v136, s[22:23]
	s_add_i32 m0, s21, 0xe000
	s_nop 0
	global_load_lds_dwordx4 v138, s[22:23]
	s_waitcnt lgkmcnt(8)
	s_waitcnt vmcnt(8)
	s_setprio 1
	s_barrier
	s_waitcnt lgkmcnt(0)
	v_mfma_f32_16x16x32_bf16 v[124:127], v[146:149], v[162:165], 0
	v_mfma_f32_16x16x32_bf16 v[120:123], v[154:157], v[162:165], 0
	v_mfma_f32_16x16x32_bf16 v[116:119], v[146:149], v[170:173], 0
	v_mfma_f32_16x16x32_bf16 v[108:111], v[154:157], v[170:173], 0
	v_mfma_f32_16x16x32_bf16 v[100:103], v[146:149], v[178:181], 0
	v_mfma_f32_16x16x32_bf16 v[92:95], v[154:157], v[178:181], 0
	v_mfma_f32_16x16x32_bf16 v[84:87], v[146:149], v[186:189], 0
	v_mfma_f32_16x16x32_bf16 v[76:79], v[154:157], v[186:189], 0
	v_mfma_f32_16x16x32_bf16 v[124:127], v[150:153], v[166:169], v[124:127]
	v_mfma_f32_16x16x32_bf16 v[120:123], v[158:161], v[166:169], v[120:123]
	v_mfma_f32_16x16x32_bf16 v[116:119], v[150:153], v[174:177], v[116:119]
	v_mfma_f32_16x16x32_bf16 v[108:111], v[158:161], v[174:177], v[108:111]
	v_mfma_f32_16x16x32_bf16 v[100:103], v[150:153], v[182:185], v[100:103]
	v_mfma_f32_16x16x32_bf16 v[92:95], v[158:161], v[182:185], v[92:95]
	v_mfma_f32_16x16x32_bf16 v[84:87], v[150:153], v[190:193], v[84:87]
	v_mfma_f32_16x16x32_bf16 v[76:79], v[158:161], v[190:193], v[76:79]
	s_barrier
	s_setprio 0
	s_add_i32 s59, s46, s34
	s_mov_b32 m0, s59
	ds_read_b128 v[194:197], v145
	ds_read_b128 v[202:205], v145 offset:1024
	ds_read_b128 v[206:209], v145 offset:2048
	ds_read_b128 v[210:213], v145 offset:3072
	global_load_lds_dwordx4 v130, s[24:25]
	s_add_i32 m0, s59, 0x2000
	s_nop 0
	global_load_lds_dwordx4 v134, s[24:25]
	s_waitcnt vmcnt(8)
	s_setprio 1
	s_barrier
	s_waitcnt lgkmcnt(0)
	v_mfma_f32_16x16x32_bf16 v[112:115], v[194:197], v[162:165], 0
	v_mfma_f32_16x16x32_bf16 v[104:107], v[206:209], v[162:165], 0
	v_mfma_f32_16x16x32_bf16 v[96:99], v[194:197], v[170:173], 0
	v_mfma_f32_16x16x32_bf16 v[88:91], v[206:209], v[170:173], 0
	v_mfma_f32_16x16x32_bf16 v[80:83], v[194:197], v[178:181], 0
	v_mfma_f32_16x16x32_bf16 v[72:75], v[206:209], v[178:181], 0
	v_mfma_f32_16x16x32_bf16 v[68:71], v[194:197], v[186:189], 0
	v_mfma_f32_16x16x32_bf16 v[64:67], v[206:209], v[186:189], 0
	v_mfma_f32_16x16x32_bf16 v[112:115], v[202:205], v[166:169], v[112:115]
	v_mfma_f32_16x16x32_bf16 v[104:107], v[210:213], v[166:169], v[104:107]
	v_mfma_f32_16x16x32_bf16 v[96:99], v[202:205], v[174:177], v[96:99]
	v_mfma_f32_16x16x32_bf16 v[88:91], v[210:213], v[174:177], v[88:91]
	v_mfma_f32_16x16x32_bf16 v[80:83], v[202:205], v[182:185], v[80:83]
	v_mfma_f32_16x16x32_bf16 v[72:75], v[210:213], v[182:185], v[72:75]
	v_mfma_f32_16x16x32_bf16 v[68:71], v[202:205], v[190:193], v[68:71]
	v_mfma_f32_16x16x32_bf16 v[64:67], v[210:213], v[190:193], v[64:67]
	s_barrier
	s_setprio 0
	s_mov_b32 m0, s21
	v_lshl_add_u64 v[216:217], s[26:27], 0, v[128:129]
	ds_read_b128 v[162:165], v144 offset:16384
	ds_read_b128 v[166:169], v144 offset:17408
	ds_read_b128 v[170:173], v144 offset:18432
	ds_read_b128 v[174:177], v144 offset:19456
	ds_read_b128 v[178:181], v144 offset:20480
	ds_read_b128 v[182:185], v144 offset:21504
	ds_read_b128 v[186:189], v144 offset:22528
	ds_read_b128 v[190:193], v144 offset:23552
	global_load_lds_dwordx4 v128, s[26:27]
	v_lshl_add_u64 v[218:219], s[26:27], 0, v[132:133]
	s_mov_b32 m0, s35
	s_nop 0
	global_load_lds_dwordx4 v132, s[26:27]
	s_setprio 1
	s_barrier
	s_waitcnt lgkmcnt(0)
	v_mfma_f32_16x16x32_bf16 v[60:63], v[146:149], v[162:165], 0
	v_mfma_f32_16x16x32_bf16 v[56:59], v[154:157], v[162:165], 0
	v_mfma_f32_16x16x32_bf16 v[52:55], v[146:149], v[170:173], 0
	v_mfma_f32_16x16x32_bf16 v[44:47], v[154:157], v[170:173], 0
	v_mfma_f32_16x16x32_bf16 v[36:39], v[146:149], v[178:181], 0
	v_mfma_f32_16x16x32_bf16 v[28:31], v[154:157], v[178:181], 0
	v_mfma_f32_16x16x32_bf16 v[20:23], v[146:149], v[186:189], 0
	v_mfma_f32_16x16x32_bf16 v[12:15], v[154:157], v[186:189], 0
	v_mfma_f32_16x16x32_bf16 v[60:63], v[150:153], v[166:169], v[60:63]
	v_mfma_f32_16x16x32_bf16 v[56:59], v[158:161], v[166:169], v[56:59]
	v_mfma_f32_16x16x32_bf16 v[52:55], v[150:153], v[174:177], v[52:55]
	v_mfma_f32_16x16x32_bf16 v[44:47], v[158:161], v[174:177], v[44:47]
	v_mfma_f32_16x16x32_bf16 v[36:39], v[150:153], v[182:185], v[36:39]
	v_mfma_f32_16x16x32_bf16 v[28:31], v[158:161], v[182:185], v[28:31]
	v_mfma_f32_16x16x32_bf16 v[20:23], v[150:153], v[190:193], v[20:23]
	v_mfma_f32_16x16x32_bf16 v[12:15], v[158:161], v[190:193], v[12:15]
	s_barrier
; #define PG8_STAGE(bufoff, gbase, voff) do { _Pragma("unroll") for (int _i = 0; _i < 2; ++_i) \
;         __builtin_amdgcn_global_load_lds((const unsigned*)((const char*)(gbase) + (voff)[_i]), (LAS unsigned*)(lds + (bufoff) + ldsw + _i * 8192), 16, 0, 0); } while (0)
; #define PG8_LDA(dst, b, h) do { _Pragma("unroll") for (int m = 0; m < 4; ++m) _Pragma("unroll") for (int k = 0; k < 2; ++k) dst[m][k] = *(const LAS bf16x8*)(lds + PG8_SA(b, h) + aoff + m * 2048 + k * 1024); } while (0)
; #define PG8_LDB(dst, b, h) do { _Pragma("unroll") for (int n = 0; n < 2; ++n) _Pragma("unroll") for (int k = 0; k < 2; ++k) dst[n][k] = *(const LAS bf16x8*)(lds + PG8_SB(b, h) + boff + n * 2048 + k * 1024); } while (0)
; #define PG8_MMA(ai, bj, At, Bt) do { __builtin_amdgcn_s_setprio(1); _Pragma("unroll") for (int m = 0; m < 4; ++m) _Pragma("unroll") for (int n = 0; n < 2; ++n) _Pragma("unroll") for (int k = 0; k < 2; ++k) \
;         acc[ai][bj][m][n] = __builtin_amdgcn_mfma_f32_16x16x32_bf16(Bt[n][k], At[m][k], acc[ai][bj][m][n], 0, 0, 0); __builtin_amdgcn_s_setprio(0); } while (0)
; #define PG8_WAIT_V(n) asm volatile("s_waitcnt vmcnt(" #n ")" ::: "memory")
; #define PG8_WAIT_L(n) asm volatile("s_waitcnt lgkmcnt(" #n ")" ::: "memory")
; template <class Epi, class Sched>
; __device__ __forceinline__ void gemm_phase(LAS unsigned char* lds, const Gemm g, const Sched& S, const Epi& E) {
;     ...
;         for (int t = 0; t < nt; t += 2) {
;             const bool last = (t == nt - 2);
;             const char* a1 = cA + (size_t)(t + 1) * kstep;
;             const char* a2 = last ? nA : cA + (size_t)(t + 2) * kstep; const char* b2 = last ? nB : cB + (size_t)(t + 2) * kstep;
;             const char* a3 = a2 + kstep; const char* b3 = b2 + kstep;
;             PG8_LDB(B0, 0, 0); PG8_SCHED; PG8_LDA(At, 0, 0); PG8_STAGE(PG8_SA(1, 1), a1 + hstep, voffA);
;             PG8_WAIT_L(8); PG8_BAR; PG8_WAIT_L(0); PG8_MMA(0, 0, At, B0); PG8_BAR; PG8_SCHED;
;             PG8_LDB(B1, 0, 1); PG8_STAGE(PG8_SB(0, 0), b2, voffB);
;             PG8_BAR; PG8_WAIT_L(0); PG8_MMA(0, 1, At, B1); PG8_BAR;
;             PG8_LDA(At, 0, 1); PG8_STAGE(PG8_SA(0, 0), a2, voffA);
;             PG8_BAR; PG8_WAIT_L(0); PG8_MMA(1, 0, At, B0); PG8_BAR; PG8_SCHED;
;             PG8_STAGE(PG8_SB(0, 1), b2 + hstep, voffB);
;             PG8_WAIT_V(6); PG8_BAR; PG8_MMA(1, 1, At, B1); PG8_BAR;
	s_setprio 0
	s_add_u32 s60, s24, 0x40000
	s_addc_u32 s61, s25, 0
	s_add_i32 s59, s47, s34
	s_mov_b32 m0, s59
	s_nop 0
	global_load_lds_dwordx4 v130, s[60:61]
	s_add_i32 m0, s59, 0x2000
	s_nop 0
	global_load_lds_dwordx4 v134, s[60:61]
	s_add_u32 s26, s26, 0x40000
	s_addc_u32 s27, s27, 0
	s_mov_b32 m0, s36
	s_nop 0
	global_load_lds_dwordx4 v128, s[26:27]
	s_mov_b32 m0, s37
	s_nop 0
	global_load_lds_dwordx4 v132, s[26:27]
	s_waitcnt vmcnt(10)
	s_setprio 1
	s_barrier
	v_mfma_f32_16x16x32_bf16 v[48:51], v[194:197], v[162:165], 0
	v_mfma_f32_16x16x32_bf16 v[40:43], v[206:209], v[162:165], 0
	v_mfma_f32_16x16x32_bf16 v[32:35], v[194:197], v[170:173], 0
	v_mfma_f32_16x16x32_bf16 v[24:27], v[206:209], v[170:173], 0
	v_mfma_f32_16x16x32_bf16 v[16:19], v[194:197], v[178:181], 0
	v_mfma_f32_16x16x32_bf16 v[8:11], v[206:209], v[178:181], 0
	v_mfma_f32_16x16x32_bf16 v[4:7], v[194:197], v[186:189], 0
	v_mfma_f32_16x16x32_bf16 v[0:3], v[206:209], v[186:189], 0
	v_mfma_f32_16x16x32_bf16 v[48:51], v[202:205], v[166:169], v[48:51]
	v_mfma_f32_16x16x32_bf16 v[40:43], v[210:213], v[166:169], v[40:43]
	v_mfma_f32_16x16x32_bf16 v[32:35], v[202:205], v[174:177], v[32:35]
	v_mfma_f32_16x16x32_bf16 v[24:27], v[210:213], v[174:177], v[24:27]
	v_mfma_f32_16x16x32_bf16 v[16:19], v[202:205], v[182:185], v[16:19]
	v_mfma_f32_16x16x32_bf16 v[8:11], v[210:213], v[182:185], v[8:11]
	v_mfma_f32_16x16x32_bf16 v[4:7], v[202:205], v[190:193], v[4:7]
	v_mfma_f32_16x16x32_bf16 v[0:3], v[210:213], v[190:193], v[0:3]
	s_barrier
	s_setprio 0
	s_add_i32 s59, 0, 0x18000
	v_add_u32_e32 v158, s59, v142
	ds_read_b128 v[146:149], v158
	ds_read_b128 v[150:153], v158 offset:1024
	ds_read_b128 v[154:157], v158 offset:2048
	ds_read_b128 v[158:161], v158 offset:3072
	ds_read_b128 v[162:165], v144 offset:32768
	ds_read_b128 v[166:169], v144 offset:33792
	ds_read_b128 v[170:173], v144 offset:34816
	ds_read_b128 v[174:177], v144 offset:35840
	ds_read_b128 v[178:181], v144 offset:36864
	ds_read_b128 v[182:185], v144 offset:37888
	ds_read_b128 v[186:189], v144 offset:38912
	ds_read_b128 v[190:193], v144 offset:39936
	s_waitcnt lgkmcnt(8)
	s_waitcnt vmcnt(8)
	s_setprio 1
	s_barrier
	s_waitcnt lgkmcnt(0)
	v_mfma_f32_16x16x32_bf16 v[124:127], v[146:149], v[162:165], v[124:127]
	v_mfma_f32_16x16x32_bf16 v[120:123], v[154:157], v[162:165], v[120:123]
	v_mfma_f32_16x16x32_bf16 v[116:119], v[146:149], v[170:173], v[116:119]
	v_mfma_f32_16x16x32_bf16 v[108:111], v[154:157], v[170:173], v[108:111]
	v_mfma_f32_16x16x32_bf16 v[100:103], v[146:149], v[178:181], v[100:103]
	v_mfma_f32_16x16x32_bf16 v[92:95], v[154:157], v[178:181], v[92:95]
	v_mfma_f32_16x16x32_bf16 v[84:87], v[146:149], v[186:189], v[84:87]
	v_mfma_f32_16x16x32_bf16 v[76:79], v[154:157], v[186:189], v[76:79]
	v_mfma_f32_16x16x32_bf16 v[124:127], v[150:153], v[166:169], v[124:127]
	v_mfma_f32_16x16x32_bf16 v[120:123], v[158:161], v[166:169], v[120:123]
	v_mfma_f32_16x16x32_bf16 v[116:119], v[150:153], v[174:177], v[116:119]
	v_mfma_f32_16x16x32_bf16 v[108:111], v[158:161], v[174:177], v[108:111]
	v_mfma_f32_16x16x32_bf16 v[100:103], v[150:153], v[182:185], v[100:103]
	v_mfma_f32_16x16x32_bf16 v[92:95], v[158:161], v[182:185], v[92:95]
	v_mfma_f32_16x16x32_bf16 v[84:87], v[150:153], v[190:193], v[84:87]
	v_mfma_f32_16x16x32_bf16 v[76:79], v[158:161], v[190:193], v[76:79]
	s_barrier
	s_setprio 0
	s_add_i32 s26, 0, 0x1c000
	s_add_i32 s27, s59, s34
	v_add_u32_e32 v210, s26, v142
	s_add_u32 s0, s24, 0x80
	s_addc_u32 s1, s25, 0
	s_mov_b32 m0, s27
	ds_read_b128 v[194:197], v210
	ds_read_b128 v[202:205], v210 offset:1024
	ds_read_b128 v[206:209], v210 offset:2048
	ds_read_b128 v[210:213], v210 offset:3072
	global_load_lds_dwordx4 v130, s[0:1]
	s_add_i32 m0, s27, 0x2000
	s_nop 0
	global_load_lds_dwordx4 v134, s[0:1]
	s_waitcnt vmcnt(8)
	s_setprio 1
	s_barrier
	s_waitcnt lgkmcnt(0)
	v_mfma_f32_16x16x32_bf16 v[112:115], v[194:197], v[162:165], v[112:115]
	v_mfma_f32_16x16x32_bf16 v[104:107], v[206:209], v[162:165], v[104:107]
	v_mfma_f32_16x16x32_bf16 v[96:99], v[194:197], v[170:173], v[96:99]
	v_mfma_f32_16x16x32_bf16 v[88:91], v[206:209], v[170:173], v[88:91]
	v_mfma_f32_16x16x32_bf16 v[80:83], v[194:197], v[178:181], v[80:83]
	v_mfma_f32_16x16x32_bf16 v[72:75], v[206:209], v[178:181], v[72:75]
	v_mfma_f32_16x16x32_bf16 v[68:71], v[194:197], v[186:189], v[68:71]
	v_mfma_f32_16x16x32_bf16 v[64:67], v[206:209], v[186:189], v[64:67]
	v_mfma_f32_16x16x32_bf16 v[112:115], v[202:205], v[166:169], v[112:115]
	v_mfma_f32_16x16x32_bf16 v[104:107], v[210:213], v[166:169], v[104:107]
	v_mfma_f32_16x16x32_bf16 v[96:99], v[202:205], v[174:177], v[96:99]
	v_mfma_f32_16x16x32_bf16 v[88:91], v[210:213], v[174:177], v[88:91]
	v_mfma_f32_16x16x32_bf16 v[80:83], v[202:205], v[182:185], v[80:83]
	v_mfma_f32_16x16x32_bf16 v[72:75], v[210:213], v[182:185], v[72:75]
	v_mfma_f32_16x16x32_bf16 v[68:71], v[202:205], v[190:193], v[68:71]
	v_mfma_f32_16x16x32_bf16 v[64:67], v[210:213], v[190:193], v[64:67]
	s_barrier
	s_setprio 0
	s_mov_b32 m0, s43
	s_mov_b64 s[0:1], 0x80
	v_lshl_add_u64 v[198:199], v[216:217], 0, s[0:1]
	ds_read_b128 v[162:165], v144 offset:49152
	ds_read_b128 v[166:169], v144 offset:50176
	ds_read_b128 v[170:173], v144 offset:51200
	ds_read_b128 v[174:177], v144 offset:52224
	ds_read_b128 v[178:181], v144 offset:53248
	ds_read_b128 v[182:185], v144 offset:54272
	ds_read_b128 v[186:189], v144 offset:55296
	ds_read_b128 v[190:193], v144 offset:56320
	global_load_lds_dwordx4 v[198:199], off
	v_lshl_add_u64 v[198:199], v[218:219], 0, s[0:1]
	s_mov_b32 m0, s44
	s_nop 0
	global_load_lds_dwordx4 v[198:199], off
	s_setprio 1
	s_barrier
; #define PG8_STAGE(bufoff, gbase, voff) do { _Pragma("unroll") for (int _i = 0; _i < 2; ++_i) \
;         __builtin_amdgcn_global_load_lds((const unsigned*)((const char*)(gbase) + (voff)[_i]), (LAS unsigned*)(lds + (bufoff) + ldsw + _i * 8192), 16, 0, 0); } while (0)
; #define PG8_LDA(dst, b, h) do { _Pragma("unroll") for (int m = 0; m < 4; ++m) _Pragma("unroll") for (int k = 0; k < 2; ++k) dst[m][k] = *(const LAS bf16x8*)(lds + PG8_SA(b, h) + aoff + m * 2048 + k * 1024); } while (0)
; #define PG8_WAIT_V(n) asm volatile("s_waitcnt vmcnt(" #n ")" ::: "memory")
; #define PG8_WAIT_L(n) asm volatile("s_waitcnt lgkmcnt(" #n ")" ::: "memory")
; template <class Epi, class Sched>
; __device__ __forceinline__ void gemm_phase(LAS unsigned char* lds, const Gemm g, const Sched& S, const Epi& E) {
;     ...
;         for (int t = 0; t < nt; t += 2) {
;             const bool last = (t == nt - 2);
;             const char* a1 = cA + (size_t)(t + 1) * kstep;
;             const char* a2 = last ? nA : cA + (size_t)(t + 2) * kstep; const char* b2 = last ? nB : cB + (size_t)(t + 2) * kstep;
;             const char* a3 = a2 + kstep; const char* b3 = b2 + kstep;
;             PG8_LDB(B0, 0, 0); PG8_SCHED; PG8_LDA(At, 0, 0); PG8_STAGE(PG8_SA(1, 1), a1 + hstep, voffA);
;             PG8_WAIT_L(8); PG8_BAR; PG8_WAIT_L(0); PG8_MMA(0, 0, At, B0); PG8_BAR; PG8_SCHED;
;             PG8_LDB(B1, 0, 1); PG8_STAGE(PG8_SB(0, 0), b2, voffB);
;             PG8_BAR; PG8_WAIT_L(0); PG8_MMA(0, 1, At, B1); PG8_BAR;
;             PG8_LDA(At, 0, 1); PG8_STAGE(PG8_SA(0, 0), a2, voffA);
;             PG8_BAR; PG8_WAIT_L(0); PG8_MMA(1, 0, At, B0); PG8_BAR; PG8_SCHED;
;             PG8_STAGE(PG8_SB(0, 1), b2 + hstep, voffB);
;             PG8_WAIT_V(6); PG8_BAR; PG8_MMA(1, 1, At, B1); PG8_BAR;
;             PG8_LDB(B0, 1, 0); PG8_SCHED; PG8_LDA(At, 1, 0); PG8_STAGE(PG8_SA(0, 1), a2 + hstep, voffA);
;             PG8_WAIT_L(8); PG8_BAR; PG8_WAIT_L(0); PG8_MMA(0, 0, At, B0); PG8_BAR; PG8_SCHED;
;             PG8_LDB(B1, 1, 1); PG8_STAGE(PG8_SB(1, 0), b3, voffB);
;             PG8_BAR; PG8_WAIT_L(0); PG8_MMA(0, 1, At, B1); PG8_BAR;
;             PG8_LDA(At, 1, 1); PG8_STAGE(PG8_SA(1, 0), a3, voffA);
;             PG8_BAR; PG8_WAIT_L(0); PG8_MMA(1, 0, At, B0); PG8_BAR; PG8_SCHED;
;             PG8_STAGE(PG8_SB(1, 1), b3 + hstep, voffB);
;             PG8_WAIT_V(6); PG8_BAR; PG8_MMA(1, 1, At, B1); PG8_BAR;
	s_waitcnt lgkmcnt(0)
	v_mfma_f32_16x16x32_bf16 v[60:63], v[146:149], v[162:165], v[60:63]
	v_mfma_f32_16x16x32_bf16 v[56:59], v[154:157], v[162:165], v[56:59]
	v_mfma_f32_16x16x32_bf16 v[52:55], v[146:149], v[170:173], v[52:55]
	v_mfma_f32_16x16x32_bf16 v[44:47], v[154:157], v[170:173], v[44:47]
	v_mfma_f32_16x16x32_bf16 v[36:39], v[146:149], v[178:181], v[36:39]
	v_mfma_f32_16x16x32_bf16 v[28:31], v[154:157], v[178:181], v[28:31]
	v_mfma_f32_16x16x32_bf16 v[20:23], v[146:149], v[186:189], v[20:23]
	v_mfma_f32_16x16x32_bf16 v[12:15], v[154:157], v[186:189], v[12:15]
	v_mfma_f32_16x16x32_bf16 v[60:63], v[150:153], v[166:169], v[60:63]
	v_mfma_f32_16x16x32_bf16 v[56:59], v[158:161], v[166:169], v[56:59]
	v_mfma_f32_16x16x32_bf16 v[52:55], v[150:153], v[174:177], v[52:55]
	v_mfma_f32_16x16x32_bf16 v[44:47], v[158:161], v[174:177], v[44:47]
	v_mfma_f32_16x16x32_bf16 v[36:39], v[150:153], v[182:185], v[36:39]
	v_mfma_f32_16x16x32_bf16 v[28:31], v[158:161], v[182:185], v[28:31]
	v_mfma_f32_16x16x32_bf16 v[20:23], v[150:153], v[190:193], v[20:23]
	v_mfma_f32_16x16x32_bf16 v[12:15], v[158:161], v[190:193], v[12:15]
	s_barrier
	s_setprio 0
	s_add_u32 s24, s24, 0x40080
	s_addc_u32 s25, s25, 0
	s_add_i32 s26, s26, s34
	s_mov_b32 m0, s26
	s_nop 0
	global_load_lds_dwordx4 v130, s[24:25]
	s_add_i32 m0, s26, 0x2000
	s_nop 0
	global_load_lds_dwordx4 v134, s[24:25]
	s_waitcnt vmcnt(8)
	s_setprio 1
	s_barrier
	v_mfma_f32_16x16x32_bf16 v[48:51], v[194:197], v[162:165], v[48:51]
	v_mfma_f32_16x16x32_bf16 v[40:43], v[206:209], v[162:165], v[40:43]
	v_mfma_f32_16x16x32_bf16 v[32:35], v[194:197], v[170:173], v[32:35]
	v_mfma_f32_16x16x32_bf16 v[24:27], v[206:209], v[170:173], v[24:27]
	v_mfma_f32_16x16x32_bf16 v[16:19], v[194:197], v[178:181], v[16:19]
	v_mfma_f32_16x16x32_bf16 v[8:11], v[206:209], v[178:181], v[8:11]
	v_mfma_f32_16x16x32_bf16 v[4:7], v[194:197], v[186:189], v[4:7]
	v_mfma_f32_16x16x32_bf16 v[0:3], v[206:209], v[186:189], v[0:3]
	v_mfma_f32_16x16x32_bf16 v[48:51], v[202:205], v[166:169], v[48:51]
	v_mfma_f32_16x16x32_bf16 v[40:43], v[210:213], v[166:169], v[40:43]
	v_mfma_f32_16x16x32_bf16 v[32:35], v[202:205], v[174:177], v[32:35]
	v_mfma_f32_16x16x32_bf16 v[24:27], v[210:213], v[174:177], v[24:27]
	v_mfma_f32_16x16x32_bf16 v[16:19], v[202:205], v[182:185], v[16:19]
	v_mfma_f32_16x16x32_bf16 v[8:11], v[210:213], v[182:185], v[8:11]
	v_mfma_f32_16x16x32_bf16 v[4:7], v[202:205], v[190:193], v[4:7]
	v_mfma_f32_16x16x32_bf16 v[0:3], v[210:213], v[190:193], v[0:3]
	s_barrier
	s_setprio 0
	s_add_i32 s58, s58, 2
	s_add_u32 s22, s22, 0x100
	s_addc_u32 s23, s23, 0
	s_add_u32 s56, s56, 0x100
	s_addc_u32 s57, s57, 0
	s_cmp_gt_u32 s58, 13
.LBB0_713:
	ds_read_b128 v[146:149], v143
	ds_read_b128 v[150:153], v143 offset:1024
	ds_read_b128 v[154:157], v143 offset:2048
	ds_read_b128 v[158:161], v143 offset:3072
	s_add_u32 s24, s22, 0xfffc0080
	s_addc_u32 s25, s23, -1
	s_cmp_eq_u32 s58, 12
	s_cselect_b32 s27, s15, s25
	s_cselect_b32 s26, s54, s24
	s_cselect_b32 s25, s13, s57
	s_cselect_b32 s24, s55, s56
	s_add_i32 m0, s21, 0xc000
	ds_read_b128 v[162:165], v144
	ds_read_b128 v[166:169], v144 offset:1024
	ds_read_b128 v[170:173], v144 offset:2048
	ds_read_b128 v[174:177], v144 offset:3072
	ds_read_b128 v[178:181], v144 offset:4096
	ds_read_b128 v[182:185], v144 offset:5120
	ds_read_b128 v[186:189], v144 offset:6144
	ds_read_b128 v[190:193], v144 offset:7168
	global_load_lds_dwordx4 v136, s[22:23]
	s_add_i32 m0, s21, 0xe000
	s_nop 0
	global_load_lds_dwordx4 v138, s[22:23]
	s_waitcnt lgkmcnt(8)
	s_waitcnt vmcnt(8)
	s_setprio 1
	s_barrier
	s_waitcnt lgkmcnt(0)
	v_mfma_f32_16x16x32_bf16 v[124:127], v[146:149], v[162:165], v[124:127]
	v_mfma_f32_16x16x32_bf16 v[120:123], v[154:157], v[162:165], v[120:123]
	v_mfma_f32_16x16x32_bf16 v[116:119], v[146:149], v[170:173], v[116:119]
	v_mfma_f32_16x16x32_bf16 v[108:111], v[154:157], v[170:173], v[108:111]
	v_mfma_f32_16x16x32_bf16 v[100:103], v[146:149], v[178:181], v[100:103]
	v_mfma_f32_16x16x32_bf16 v[92:95], v[154:157], v[178:181], v[92:95]
	v_mfma_f32_16x16x32_bf16 v[84:87], v[146:149], v[186:189], v[84:87]
	v_mfma_f32_16x16x32_bf16 v[76:79], v[154:157], v[186:189], v[76:79]
	v_mfma_f32_16x16x32_bf16 v[124:127], v[150:153], v[166:169], v[124:127]
	v_mfma_f32_16x16x32_bf16 v[120:123], v[158:161], v[166:169], v[120:123]
	v_mfma_f32_16x16x32_bf16 v[116:119], v[150:153], v[174:177], v[116:119]
	v_mfma_f32_16x16x32_bf16 v[108:111], v[158:161], v[174:177], v[108:111]
	v_mfma_f32_16x16x32_bf16 v[100:103], v[150:153], v[182:185], v[100:103]
	v_mfma_f32_16x16x32_bf16 v[92:95], v[158:161], v[182:185], v[92:95]
	v_mfma_f32_16x16x32_bf16 v[84:87], v[150:153], v[190:193], v[84:87]
	v_mfma_f32_16x16x32_bf16 v[76:79], v[158:161], v[190:193], v[76:79]
	s_barrier
	s_setprio 0
	s_add_i32 s59, s46, s34
	s_mov_b32 m0, s59
	ds_read_b128 v[194:197], v145
	ds_read_b128 v[202:205], v145 offset:1024
	ds_read_b128 v[206:209], v145 offset:2048
	ds_read_b128 v[210:213], v145 offset:3072
	global_load_lds_dwordx4 v130, s[24:25]
	s_add_i32 m0, s59, 0x2000
	s_nop 0
	global_load_lds_dwordx4 v134, s[24:25]
	s_waitcnt vmcnt(8)
	s_setprio 1
	s_barrier
; #define PG8_STAGE(bufoff, gbase, voff) do { _Pragma("unroll") for (int _i = 0; _i < 2; ++_i) \
;         __builtin_amdgcn_global_load_lds((const unsigned*)((const char*)(gbase) + (voff)[_i]), (LAS unsigned*)(lds + (bufoff) + ldsw + _i * 8192), 16, 0, 0); } while (0)
; #define PG8_LDA(dst, b, h) do { _Pragma("unroll") for (int m = 0; m < 4; ++m) _Pragma("unroll") for (int k = 0; k < 2; ++k) dst[m][k] = *(const LAS bf16x8*)(lds + PG8_SA(b, h) + aoff + m * 2048 + k * 1024); } while (0)
; #define PG8_WAIT_V(n) asm volatile("s_waitcnt vmcnt(" #n ")" ::: "memory")
; #define PG8_WAIT_L(n) asm volatile("s_waitcnt lgkmcnt(" #n ")" ::: "memory")
; template <class Epi, class Sched>
; __device__ __forceinline__ void gemm_phase(LAS unsigned char* lds, const Gemm g, const Sched& S, const Epi& E) {
;     ...
;         for (int t = 0; t < nt; t += 2) {
;             const bool last = (t == nt - 2);
;             const char* a1 = cA + (size_t)(t + 1) * kstep;
;             const char* a2 = last ? nA : cA + (size_t)(t + 2) * kstep; const char* b2 = last ? nB : cB + (size_t)(t + 2) * kstep;
;             const char* a3 = a2 + kstep; const char* b3 = b2 + kstep;
;             PG8_LDB(B0, 0, 0); PG8_SCHED; PG8_LDA(At, 0, 0); PG8_STAGE(PG8_SA(1, 1), a1 + hstep, voffA);
;             PG8_WAIT_L(8); PG8_BAR; PG8_WAIT_L(0); PG8_MMA(0, 0, At, B0); PG8_BAR; PG8_SCHED;
;             PG8_LDB(B1, 0, 1); PG8_STAGE(PG8_SB(0, 0), b2, voffB);
;             PG8_BAR; PG8_WAIT_L(0); PG8_MMA(0, 1, At, B1); PG8_BAR;
;             PG8_LDA(At, 0, 1); PG8_STAGE(PG8_SA(0, 0), a2, voffA);
;             PG8_BAR; PG8_WAIT_L(0); PG8_MMA(1, 0, At, B0); PG8_BAR; PG8_SCHED;
;             PG8_STAGE(PG8_SB(0, 1), b2 + hstep, voffB);
;             PG8_WAIT_V(6); PG8_BAR; PG8_MMA(1, 1, At, B1); PG8_BAR;
;             PG8_LDB(B0, 1, 0); PG8_SCHED; PG8_LDA(At, 1, 0); PG8_STAGE(PG8_SA(0, 1), a2 + hstep, voffA);
;             PG8_WAIT_L(8); PG8_BAR; PG8_WAIT_L(0); PG8_MMA(0, 0, At, B0); PG8_BAR; PG8_SCHED;
;             PG8_LDB(B1, 1, 1); PG8_STAGE(PG8_SB(1, 0), b3, voffB);
;             PG8_BAR; PG8_WAIT_L(0); PG8_MMA(0, 1, At, B1); PG8_BAR;
;             PG8_LDA(At, 1, 1); PG8_STAGE(PG8_SA(1, 0), a3, voffA);
;             PG8_BAR; PG8_WAIT_L(0); PG8_MMA(1, 0, At, B0); PG8_BAR; PG8_SCHED;
;             PG8_STAGE(PG8_SB(1, 1), b3 + hstep, voffB);
;             PG8_WAIT_V(6); PG8_BAR; PG8_MMA(1, 1, At, B1); PG8_BAR;
	s_waitcnt lgkmcnt(0)
	v_mfma_f32_16x16x32_bf16 v[112:115], v[194:197], v[162:165], v[112:115]
	v_mfma_f32_16x16x32_bf16 v[104:107], v[206:209], v[162:165], v[104:107]
	v_mfma_f32_16x16x32_bf16 v[96:99], v[194:197], v[170:173], v[96:99]
	v_mfma_f32_16x16x32_bf16 v[88:91], v[206:209], v[170:173], v[88:91]
	v_mfma_f32_16x16x32_bf16 v[80:83], v[194:197], v[178:181], v[80:83]
	v_mfma_f32_16x16x32_bf16 v[72:75], v[206:209], v[178:181], v[72:75]
	v_mfma_f32_16x16x32_bf16 v[68:71], v[194:197], v[186:189], v[68:71]
	v_mfma_f32_16x16x32_bf16 v[64:67], v[206:209], v[186:189], v[64:67]
	v_mfma_f32_16x16x32_bf16 v[112:115], v[202:205], v[166:169], v[112:115]
	v_mfma_f32_16x16x32_bf16 v[104:107], v[210:213], v[166:169], v[104:107]
	v_mfma_f32_16x16x32_bf16 v[96:99], v[202:205], v[174:177], v[96:99]
	v_mfma_f32_16x16x32_bf16 v[88:91], v[210:213], v[174:177], v[88:91]
	v_mfma_f32_16x16x32_bf16 v[80:83], v[202:205], v[182:185], v[80:83]
	v_mfma_f32_16x16x32_bf16 v[72:75], v[210:213], v[182:185], v[72:75]
	v_mfma_f32_16x16x32_bf16 v[68:71], v[202:205], v[190:193], v[68:71]
	v_mfma_f32_16x16x32_bf16 v[64:67], v[210:213], v[190:193], v[64:67]
	s_barrier
	s_setprio 0
	s_mov_b32 m0, s21
	v_lshl_add_u64 v[216:217], s[26:27], 0, v[128:129]
	ds_read_b128 v[162:165], v144 offset:16384
	ds_read_b128 v[166:169], v144 offset:17408
	ds_read_b128 v[170:173], v144 offset:18432
	ds_read_b128 v[174:177], v144 offset:19456
	ds_read_b128 v[178:181], v144 offset:20480
	ds_read_b128 v[182:185], v144 offset:21504
	ds_read_b128 v[186:189], v144 offset:22528
	ds_read_b128 v[190:193], v144 offset:23552
	global_load_lds_dwordx4 v128, s[26:27]
	v_lshl_add_u64 v[218:219], s[26:27], 0, v[132:133]
	s_mov_b32 m0, s35
	s_nop 0
	global_load_lds_dwordx4 v132, s[26:27]
	s_setprio 1
	s_barrier
	s_waitcnt lgkmcnt(0)
	v_mfma_f32_16x16x32_bf16 v[60:63], v[146:149], v[162:165], v[60:63]
	v_mfma_f32_16x16x32_bf16 v[56:59], v[154:157], v[162:165], v[56:59]
	v_mfma_f32_16x16x32_bf16 v[52:55], v[146:149], v[170:173], v[52:55]
	v_mfma_f32_16x16x32_bf16 v[44:47], v[154:157], v[170:173], v[44:47]
	v_mfma_f32_16x16x32_bf16 v[36:39], v[146:149], v[178:181], v[36:39]
	v_mfma_f32_16x16x32_bf16 v[28:31], v[154:157], v[178:181], v[28:31]
	v_mfma_f32_16x16x32_bf16 v[20:23], v[146:149], v[186:189], v[20:23]
	v_mfma_f32_16x16x32_bf16 v[12:15], v[154:157], v[186:189], v[12:15]
	v_mfma_f32_16x16x32_bf16 v[60:63], v[150:153], v[166:169], v[60:63]
	v_mfma_f32_16x16x32_bf16 v[56:59], v[158:161], v[166:169], v[56:59]
	v_mfma_f32_16x16x32_bf16 v[52:55], v[150:153], v[174:177], v[52:55]
	v_mfma_f32_16x16x32_bf16 v[44:47], v[158:161], v[174:177], v[44:47]
	v_mfma_f32_16x16x32_bf16 v[36:39], v[150:153], v[182:185], v[36:39]
	v_mfma_f32_16x16x32_bf16 v[28:31], v[158:161], v[182:185], v[28:31]
	v_mfma_f32_16x16x32_bf16 v[20:23], v[150:153], v[190:193], v[20:23]
	v_mfma_f32_16x16x32_bf16 v[12:15], v[158:161], v[190:193], v[12:15]
	s_barrier
	s_setprio 0
	s_add_u32 s60, s24, 0x40000
	s_addc_u32 s61, s25, 0
	s_add_i32 s59, s47, s34
	s_mov_b32 m0, s59
	s_nop 0
	global_load_lds_dwordx4 v130, s[60:61]
	s_add_i32 m0, s59, 0x2000
	s_nop 0
	global_load_lds_dwordx4 v134, s[60:61]
	s_add_u32 s26, s26, 0x40000
	s_addc_u32 s27, s27, 0
	s_mov_b32 m0, s36
	s_nop 0
	global_load_lds_dwordx4 v128, s[26:27]
	s_mov_b32 m0, s37
	s_nop 0
	global_load_lds_dwordx4 v132, s[26:27]
	s_waitcnt vmcnt(10)
	s_setprio 1
	s_barrier
	v_mfma_f32_16x16x32_bf16 v[48:51], v[194:197], v[162:165], v[48:51]
	v_mfma_f32_16x16x32_bf16 v[40:43], v[206:209], v[162:165], v[40:43]
	v_mfma_f32_16x16x32_bf16 v[32:35], v[194:197], v[170:173], v[32:35]
	v_mfma_f32_16x16x32_bf16 v[24:27], v[206:209], v[170:173], v[24:27]
	v_mfma_f32_16x16x32_bf16 v[16:19], v[194:197], v[178:181], v[16:19]
	v_mfma_f32_16x16x32_bf16 v[8:11], v[206:209], v[178:181], v[8:11]
	v_mfma_f32_16x16x32_bf16 v[4:7], v[194:197], v[186:189], v[4:7]
	v_mfma_f32_16x16x32_bf16 v[0:3], v[206:209], v[186:189], v[0:3]
	v_mfma_f32_16x16x32_bf16 v[48:51], v[202:205], v[166:169], v[48:51]
	v_mfma_f32_16x16x32_bf16 v[40:43], v[210:213], v[166:169], v[40:43]
	v_mfma_f32_16x16x32_bf16 v[32:35], v[202:205], v[174:177], v[32:35]
	v_mfma_f32_16x16x32_bf16 v[24:27], v[210:213], v[174:177], v[24:27]
	v_mfma_f32_16x16x32_bf16 v[16:19], v[202:205], v[182:185], v[16:19]
	v_mfma_f32_16x16x32_bf16 v[8:11], v[210:213], v[182:185], v[8:11]
	v_mfma_f32_16x16x32_bf16 v[4:7], v[202:205], v[190:193], v[4:7]
	v_mfma_f32_16x16x32_bf16 v[0:3], v[210:213], v[190:193], v[0:3]
	s_barrier
	s_setprio 0
	s_add_i32 s59, 0, 0x18000
	v_add_u32_e32 v158, s59, v142
	ds_read_b128 v[146:149], v158
	ds_read_b128 v[150:153], v158 offset:1024
	ds_read_b128 v[154:157], v158 offset:2048
	ds_read_b128 v[158:161], v158 offset:3072
	ds_read_b128 v[162:165], v144 offset:32768
	ds_read_b128 v[166:169], v144 offset:33792
	ds_read_b128 v[170:173], v144 offset:34816
	ds_read_b128 v[174:177], v144 offset:35840
	ds_read_b128 v[178:181], v144 offset:36864
	ds_read_b128 v[182:185], v144 offset:37888
	ds_read_b128 v[186:189], v144 offset:38912
	ds_read_b128 v[190:193], v144 offset:39936
	s_waitcnt lgkmcnt(8)
	s_waitcnt vmcnt(8)
	s_setprio 1
	s_barrier
; #define PG8_STAGE(bufoff, gbase, voff) do { _Pragma("unroll") for (int _i = 0; _i < 2; ++_i) \
;         __builtin_amdgcn_global_load_lds((const unsigned*)((const char*)(gbase) + (voff)[_i]), (LAS unsigned*)(lds + (bufoff) + ldsw + _i * 8192), 16, 0, 0); } while (0)
; #define PG8_LDA(dst, b, h) do { _Pragma("unroll") for (int m = 0; m < 4; ++m) _Pragma("unroll") for (int k = 0; k < 2; ++k) dst[m][k] = *(const LAS bf16x8*)(lds + PG8_SA(b, h) + aoff + m * 2048 + k * 1024); } while (0)
; #define PG8_WAIT_V(n) asm volatile("s_waitcnt vmcnt(" #n ")" ::: "memory")
; #define PG8_WAIT_L(n) asm volatile("s_waitcnt lgkmcnt(" #n ")" ::: "memory")
; template <class Epi, class Sched>
; __device__ __forceinline__ void gemm_phase(LAS unsigned char* lds, const Gemm g, const Sched& S, const Epi& E) {
;     ...
;         for (int t = 0; t < nt; t += 2) {
;             const bool last = (t == nt - 2);
;             const char* a1 = cA + (size_t)(t + 1) * kstep;
;             const char* a2 = last ? nA : cA + (size_t)(t + 2) * kstep; const char* b2 = last ? nB : cB + (size_t)(t + 2) * kstep;
;             const char* a3 = a2 + kstep; const char* b3 = b2 + kstep;
;             PG8_LDB(B0, 0, 0); PG8_SCHED; PG8_LDA(At, 0, 0); PG8_STAGE(PG8_SA(1, 1), a1 + hstep, voffA);
;             PG8_WAIT_L(8); PG8_BAR; PG8_WAIT_L(0); PG8_MMA(0, 0, At, B0); PG8_BAR; PG8_SCHED;
;             PG8_LDB(B1, 0, 1); PG8_STAGE(PG8_SB(0, 0), b2, voffB);
;             PG8_BAR; PG8_WAIT_L(0); PG8_MMA(0, 1, At, B1); PG8_BAR;
;             PG8_LDA(At, 0, 1); PG8_STAGE(PG8_SA(0, 0), a2, voffA);
;             PG8_BAR; PG8_WAIT_L(0); PG8_MMA(1, 0, At, B0); PG8_BAR; PG8_SCHED;
;             PG8_STAGE(PG8_SB(0, 1), b2 + hstep, voffB);
;             PG8_WAIT_V(6); PG8_BAR; PG8_MMA(1, 1, At, B1); PG8_BAR;
;             PG8_LDB(B0, 1, 0); PG8_SCHED; PG8_LDA(At, 1, 0); PG8_STAGE(PG8_SA(0, 1), a2 + hstep, voffA);
;             PG8_WAIT_L(8); PG8_BAR; PG8_WAIT_L(0); PG8_MMA(0, 0, At, B0); PG8_BAR; PG8_SCHED;
;             PG8_LDB(B1, 1, 1); PG8_STAGE(PG8_SB(1, 0), b3, voffB);
;             PG8_BAR; PG8_WAIT_L(0); PG8_MMA(0, 1, At, B1); PG8_BAR;
;             PG8_LDA(At, 1, 1); PG8_STAGE(PG8_SA(1, 0), a3, voffA);
;             PG8_BAR; PG8_WAIT_L(0); PG8_MMA(1, 0, At, B0); PG8_BAR; PG8_SCHED;
;             PG8_STAGE(PG8_SB(1, 1), b3 + hstep, voffB);
;             PG8_WAIT_V(6); PG8_BAR; PG8_MMA(1, 1, At, B1); PG8_BAR;
	s_waitcnt lgkmcnt(0)
	v_mfma_f32_16x16x32_bf16 v[124:127], v[146:149], v[162:165], v[124:127]
	v_mfma_f32_16x16x32_bf16 v[120:123], v[154:157], v[162:165], v[120:123]
	v_mfma_f32_16x16x32_bf16 v[116:119], v[146:149], v[170:173], v[116:119]
	v_mfma_f32_16x16x32_bf16 v[108:111], v[154:157], v[170:173], v[108:111]
	v_mfma_f32_16x16x32_bf16 v[100:103], v[146:149], v[178:181], v[100:103]
	v_mfma_f32_16x16x32_bf16 v[92:95], v[154:157], v[178:181], v[92:95]
	v_mfma_f32_16x16x32_bf16 v[84:87], v[146:149], v[186:189], v[84:87]
	v_mfma_f32_16x16x32_bf16 v[76:79], v[154:157], v[186:189], v[76:79]
	v_mfma_f32_16x16x32_bf16 v[124:127], v[150:153], v[166:169], v[124:127]
	v_mfma_f32_16x16x32_bf16 v[120:123], v[158:161], v[166:169], v[120:123]
	v_mfma_f32_16x16x32_bf16 v[116:119], v[150:153], v[174:177], v[116:119]
	v_mfma_f32_16x16x32_bf16 v[108:111], v[158:161], v[174:177], v[108:111]
	v_mfma_f32_16x16x32_bf16 v[100:103], v[150:153], v[182:185], v[100:103]
	v_mfma_f32_16x16x32_bf16 v[92:95], v[158:161], v[182:185], v[92:95]
	v_mfma_f32_16x16x32_bf16 v[84:87], v[150:153], v[190:193], v[84:87]
	v_mfma_f32_16x16x32_bf16 v[76:79], v[158:161], v[190:193], v[76:79]
	s_barrier
	s_setprio 0
	s_add_i32 s26, 0, 0x1c000
	s_add_i32 s27, s59, s34
	v_add_u32_e32 v210, s26, v142
	s_add_u32 s0, s24, 0x80
	s_addc_u32 s1, s25, 0
	s_mov_b32 m0, s27
	ds_read_b128 v[194:197], v210
	ds_read_b128 v[202:205], v210 offset:1024
	ds_read_b128 v[206:209], v210 offset:2048
	ds_read_b128 v[210:213], v210 offset:3072
	global_load_lds_dwordx4 v130, s[0:1]
	s_add_i32 m0, s27, 0x2000
	s_nop 0
	global_load_lds_dwordx4 v134, s[0:1]
	s_waitcnt vmcnt(8)
	s_setprio 1
	s_barrier
	s_waitcnt lgkmcnt(0)
	v_mfma_f32_16x16x32_bf16 v[112:115], v[194:197], v[162:165], v[112:115]
	v_mfma_f32_16x16x32_bf16 v[104:107], v[206:209], v[162:165], v[104:107]
	v_mfma_f32_16x16x32_bf16 v[96:99], v[194:197], v[170:173], v[96:99]
	v_mfma_f32_16x16x32_bf16 v[88:91], v[206:209], v[170:173], v[88:91]
	v_mfma_f32_16x16x32_bf16 v[80:83], v[194:197], v[178:181], v[80:83]
	v_mfma_f32_16x16x32_bf16 v[72:75], v[206:209], v[178:181], v[72:75]
	v_mfma_f32_16x16x32_bf16 v[68:71], v[194:197], v[186:189], v[68:71]
	v_mfma_f32_16x16x32_bf16 v[64:67], v[206:209], v[186:189], v[64:67]
	v_mfma_f32_16x16x32_bf16 v[112:115], v[202:205], v[166:169], v[112:115]
	v_mfma_f32_16x16x32_bf16 v[104:107], v[210:213], v[166:169], v[104:107]
	v_mfma_f32_16x16x32_bf16 v[96:99], v[202:205], v[174:177], v[96:99]
	v_mfma_f32_16x16x32_bf16 v[88:91], v[210:213], v[174:177], v[88:91]
	v_mfma_f32_16x16x32_bf16 v[80:83], v[202:205], v[182:185], v[80:83]
	v_mfma_f32_16x16x32_bf16 v[72:75], v[210:213], v[182:185], v[72:75]
	v_mfma_f32_16x16x32_bf16 v[68:71], v[202:205], v[190:193], v[68:71]
	v_mfma_f32_16x16x32_bf16 v[64:67], v[210:213], v[190:193], v[64:67]
	s_barrier
	s_setprio 0
	s_mov_b32 m0, s43
	s_mov_b64 s[0:1], 0x80
	v_lshl_add_u64 v[198:199], v[216:217], 0, s[0:1]
	ds_read_b128 v[162:165], v144 offset:49152
	ds_read_b128 v[166:169], v144 offset:50176
	ds_read_b128 v[170:173], v144 offset:51200
	ds_read_b128 v[174:177], v144 offset:52224
	ds_read_b128 v[178:181], v144 offset:53248
	ds_read_b128 v[182:185], v144 offset:54272
	ds_read_b128 v[186:189], v144 offset:55296
	ds_read_b128 v[190:193], v144 offset:56320
	global_load_lds_dwordx4 v[198:199], off
	v_lshl_add_u64 v[198:199], v[218:219], 0, s[0:1]
	s_mov_b32 m0, s44
	s_nop 0
	global_load_lds_dwordx4 v[198:199], off
	s_setprio 1
	s_barrier
	s_waitcnt lgkmcnt(0)
	v_mfma_f32_16x16x32_bf16 v[60:63], v[146:149], v[162:165], v[60:63]
	v_mfma_f32_16x16x32_bf16 v[56:59], v[154:157], v[162:165], v[56:59]
	v_mfma_f32_16x16x32_bf16 v[52:55], v[146:149], v[170:173], v[52:55]
	v_mfma_f32_16x16x32_bf16 v[44:47], v[154:157], v[170:173], v[44:47]
	v_mfma_f32_16x16x32_bf16 v[36:39], v[146:149], v[178:181], v[36:39]
	v_mfma_f32_16x16x32_bf16 v[28:31], v[154:157], v[178:181], v[28:31]
	v_mfma_f32_16x16x32_bf16 v[20:23], v[146:149], v[186:189], v[20:23]
	v_mfma_f32_16x16x32_bf16 v[12:15], v[154:157], v[186:189], v[12:15]
	v_mfma_f32_16x16x32_bf16 v[60:63], v[150:153], v[166:169], v[60:63]
	v_mfma_f32_16x16x32_bf16 v[56:59], v[158:161], v[166:169], v[56:59]
	v_mfma_f32_16x16x32_bf16 v[52:55], v[150:153], v[174:177], v[52:55]
	v_mfma_f32_16x16x32_bf16 v[44:47], v[158:161], v[174:177], v[44:47]
	v_mfma_f32_16x16x32_bf16 v[36:39], v[150:153], v[182:185], v[36:39]
	v_mfma_f32_16x16x32_bf16 v[28:31], v[158:161], v[182:185], v[28:31]
	v_mfma_f32_16x16x32_bf16 v[20:23], v[150:153], v[190:193], v[20:23]
	v_mfma_f32_16x16x32_bf16 v[12:15], v[158:161], v[190:193], v[12:15]
	s_barrier
	s_setprio 0
	s_add_u32 s24, s24, 0x40080
	s_addc_u32 s25, s25, 0
	s_add_i32 s26, s26, s34
	s_mov_b32 m0, s26
	s_nop 0
	global_load_lds_dwordx4 v130, s[24:25]
	s_add_i32 m0, s26, 0x2000
	s_nop 0
	global_load_lds_dwordx4 v134, s[24:25]
	s_waitcnt vmcnt(8)
	s_setprio 1
	s_barrier
	v_mfma_f32_16x16x32_bf16 v[48:51], v[194:197], v[162:165], v[48:51]
	v_mfma_f32_16x16x32_bf16 v[40:43], v[206:209], v[162:165], v[40:43]
	v_mfma_f32_16x16x32_bf16 v[32:35], v[194:197], v[170:173], v[32:35]
	v_mfma_f32_16x16x32_bf16 v[24:27], v[206:209], v[170:173], v[24:27]
	v_mfma_f32_16x16x32_bf16 v[16:19], v[194:197], v[178:181], v[16:19]
	v_mfma_f32_16x16x32_bf16 v[8:11], v[206:209], v[178:181], v[8:11]
	v_mfma_f32_16x16x32_bf16 v[4:7], v[194:197], v[186:189], v[4:7]
	v_mfma_f32_16x16x32_bf16 v[0:3], v[206:209], v[186:189], v[0:3]
	v_mfma_f32_16x16x32_bf16 v[48:51], v[202:205], v[166:169], v[48:51]
	v_mfma_f32_16x16x32_bf16 v[40:43], v[210:213], v[166:169], v[40:43]
	v_mfma_f32_16x16x32_bf16 v[32:35], v[202:205], v[174:177], v[32:35]
	v_mfma_f32_16x16x32_bf16 v[24:27], v[210:213], v[174:177], v[24:27]
	v_mfma_f32_16x16x32_bf16 v[16:19], v[202:205], v[182:185], v[16:19]
	v_mfma_f32_16x16x32_bf16 v[8:11], v[210:213], v[182:185], v[8:11]
	v_mfma_f32_16x16x32_bf16 v[4:7], v[202:205], v[190:193], v[4:7]
	v_mfma_f32_16x16x32_bf16 v[0:3], v[210:213], v[190:193], v[0:3]
	s_barrier
; __device__ __forceinline__ unsigned cvt_pk_bf16(float lo, float hi) { unsigned r; asm volatile("v_cvt_pk_bf16_f32 %0, %1, %2" : "=v"(r) : "v"(lo), "v"(hi)); return r; }
; #define PG8_MMA(ai, bj, At, Bt) do { __builtin_amdgcn_s_setprio(1); _Pragma("unroll") for (int m = 0; m < 4; ++m) _Pragma("unroll") for (int n = 0; n < 2; ++n) _Pragma("unroll") for (int k = 0; k < 2; ++k) \
;         acc[ai][bj][m][n] = __builtin_amdgcn_mfma_f32_16x16x32_bf16(Bt[n][k], At[m][k], acc[ai][bj][m][n], 0, 0, 0); __builtin_amdgcn_s_setprio(0); } while (0)
; #define PG8_WAIT_V(n) asm volatile("s_waitcnt vmcnt(" #n ")" ::: "memory")
; #define PG8_BAR __builtin_amdgcn_s_barrier()
; template <class Epi, class Sched>
; __device__ __forceinline__ void gemm_phase(LAS unsigned char* lds, const Gemm g, const Sched& S, const Epi& E) {
;     ...
;             PG8_WAIT_V(6); PG8_BAR; PG8_MMA(1, 1, At, B1); PG8_BAR;
;     __device__ __forceinline__ void operator()(const AccT& acc, const Unit& u, int wr, int wc, int fr, int fq) const {
;         asm volatile("" : "+v"(fr), "+v"(fq));
;         const int rbase = u.pm * 256 + wr * 64 + fr;
;         const int tb = u.pn * 256 + wc * 32 + 8 * fq;
; #pragma unroll
;         for (int ai = 0; ai < 2; ++ai)
; #pragma unroll
;             for (int m = 0; m < 4; ++m) {
;                 const int r = rbase + ai * 128 + m * 16;
; #pragma unroll
;                 for (int bj = 0; bj < 2; ++bj) {
;                     const int t0 = tb + bj * 128;
;                     const f32x4 v0 = acc[ai][bj][m][0], v1 = acc[ai][bj][m][1];
;                     u32x4 w; w.x = cvt_pk_bf16(v0[0], v0[1]); w.y = cvt_pk_bf16(v0[2], v0[3]); w.z = cvt_pk_bf16(v1[0], v1[1]); w.w = cvt_pk_bf16(v1[2], v1[3]);
;                     *(u32x4*)(VT + (size_t)r * NT + t0) = w;
;                 }
;             }
	s_setprio 0
	s_add_i32 s58, s58, 2
	s_add_u32 s22, s22, 0x100
	s_addc_u32 s23, s23, 0
	s_add_u32 s56, s56, 0x100
	s_addc_u32 s57, s57, 0
	s_cmp_gt_u32 s58, 13
	s_cbranch_scc0 .LBB0_713
	v_mov_b32_e32 v146, v140
	v_mov_b32_e32 v147, v141
	s_lshl_b32 s13, s20, 8
	s_add_i32 s13, s13, s41
	v_add_u32_e32 v146, s13, v146
	s_lshl_b32 s13, s53, 8
	s_or_b32 s13, s13, s42
	v_lshl_add_u32 v148, v147, 3, s13
	v_ashrrev_i32_e32 v147, 31, v146
	v_cvt_pk_bf16_f32 v124, v124, v125
	v_cvt_pk_bf16_f32 v125, v126, v127
	v_cvt_pk_bf16_f32 v126, v120, v121
	v_lshlrev_b64 v[120:121], 14, v[146:147]
	v_lshl_add_u64 v[120:121], s[62:63], 0, v[120:121]
	v_ashrrev_i32_e32 v149, 31, v148
	v_lshl_add_u64 v[120:121], v[148:149], 1, v[120:121]
	s_mov_b32 s13, 0x40000
	v_cvt_pk_bf16_f32 v127, v122, v123
	global_store_dwordx4 v[120:121], v[124:127], off
	v_cvt_pk_bf16_f32 v112, v112, v113
	v_cvt_pk_bf16_f32 v113, v114, v115
	v_cvt_pk_bf16_f32 v114, v104, v105
	v_cvt_pk_bf16_f32 v115, v106, v107
	global_store_dwordx4 v[120:121], v[112:115], off offset:256
	v_cvt_pk_bf16_f32 v104, v116, v117
	v_cvt_pk_bf16_f32 v105, v118, v119
	v_cvt_pk_bf16_f32 v106, v108, v109
	v_cvt_pk_bf16_f32 v107, v110, v111
	s_mov_b64 s[22:23], 0x40000
	v_add_co_u32_e32 v110, vcc, s13, v120
	v_lshl_add_u64 v[108:109], v[120:121], 0, s[22:23]
	s_nop 0
	v_addc_co_u32_e32 v111, vcc, 0, v121, vcc
	s_mov_b32 s13, 0x80000
	global_store_dwordx4 v[110:111], v[104:107], off
	v_cvt_pk_bf16_f32 v96, v96, v97
	v_cvt_pk_bf16_f32 v97, v98, v99
	v_cvt_pk_bf16_f32 v98, v88, v89
	v_cvt_pk_bf16_f32 v99, v90, v91
	global_store_dwordx4 v[108:109], v[96:99], off offset:256
	v_cvt_pk_bf16_f32 v88, v100, v101
	v_cvt_pk_bf16_f32 v89, v102, v103
	v_cvt_pk_bf16_f32 v90, v92, v93
	v_cvt_pk_bf16_f32 v91, v94, v95
	s_mov_b64 s[22:23], 0x80000
	v_add_co_u32_e32 v94, vcc, s13, v120
	v_lshl_add_u64 v[92:93], v[120:121], 0, s[22:23]
	s_nop 0
	v_addc_co_u32_e32 v95, vcc, 0, v121, vcc
	global_store_dwordx4 v[94:95], v[88:91], off
	v_cvt_pk_bf16_f32 v80, v80, v81
	v_cvt_pk_bf16_f32 v81, v82, v83
	v_cvt_pk_bf16_f32 v82, v72, v73
	v_cvt_pk_bf16_f32 v83, v74, v75
	global_store_dwordx4 v[92:93], v[80:83], off offset:256
	v_cvt_pk_bf16_f32 v72, v84, v85
	v_cvt_pk_bf16_f32 v73, v86, v87
	v_cvt_pk_bf16_f32 v74, v76, v77
	v_cvt_pk_bf16_f32 v75, v78, v79
	s_mov_b64 s[22:23], 0xc0000
	v_add_co_u32_e32 v78, vcc, s48, v120
	v_lshl_add_u64 v[76:77], v[120:121], 0, s[22:23]
	s_nop 0
	v_addc_co_u32_e32 v79, vcc, 0, v121, vcc
	global_store_dwordx4 v[78:79], v[72:75], off
	v_cvt_pk_bf16_f32 v68, v68, v69
	v_cvt_pk_bf16_f32 v69, v70, v71
	v_cvt_pk_bf16_f32 v70, v64, v65
	v_cvt_pk_bf16_f32 v71, v66, v67
	global_store_dwordx4 v[76:77], v[68:71], off offset:256
	v_cvt_pk_bf16_f32 v60, v60, v61
	v_cvt_pk_bf16_f32 v61, v62, v63
	v_cvt_pk_bf16_f32 v62, v56, v57
	v_cvt_pk_bf16_f32 v63, v58, v59
	v_add_co_u32_e32 v58, vcc, s49, v120
	v_lshl_add_u64 v[56:57], v[120:121], 0, s[2:3]
	s_nop 0
	v_addc_co_u32_e32 v59, vcc, 0, v121, vcc
	global_store_dwordx4 v[58:59], v[60:63], off
	v_cvt_pk_bf16_f32 v48, v48, v49
	v_cvt_pk_bf16_f32 v49, v50, v51
	v_cvt_pk_bf16_f32 v50, v40, v41
	v_cvt_pk_bf16_f32 v51, v42, v43
	global_store_dwordx4 v[56:57], v[48:51], off offset:256
	v_cvt_pk_bf16_f32 v40, v52, v53
	v_cvt_pk_bf16_f32 v41, v54, v55
	v_cvt_pk_bf16_f32 v42, v44, v45
	v_cvt_pk_bf16_f32 v43, v46, v47
	v_add_co_u32_e32 v46, vcc, s50, v120
	v_lshl_add_u64 v[44:45], v[120:121], 0, s[4:5]
	s_nop 0
	v_addc_co_u32_e32 v47, vcc, 0, v121, vcc
	global_store_dwordx4 v[46:47], v[40:43], off
	v_cvt_pk_bf16_f32 v32, v32, v33
	v_cvt_pk_bf16_f32 v33, v34, v35
	v_cvt_pk_bf16_f32 v34, v24, v25
	v_cvt_pk_bf16_f32 v35, v26, v27
	global_store_dwordx4 v[44:45], v[32:35], off offset:256
	v_cvt_pk_bf16_f32 v24, v36, v37
	v_cvt_pk_bf16_f32 v25, v38, v39
	v_cvt_pk_bf16_f32 v26, v28, v29
	v_cvt_pk_bf16_f32 v27, v30, v31
	v_add_co_u32_e32 v30, vcc, s51, v120
	v_lshl_add_u64 v[28:29], v[120:121], 0, s[6:7]
	s_nop 0
	v_addc_co_u32_e32 v31, vcc, 0, v121, vcc
	global_store_dwordx4 v[30:31], v[24:27], off
	v_cvt_pk_bf16_f32 v16, v16, v17
	v_cvt_pk_bf16_f32 v17, v18, v19
	v_cvt_pk_bf16_f32 v18, v8, v9
	v_cvt_pk_bf16_f32 v19, v10, v11
	global_store_dwordx4 v[28:29], v[16:19], off offset:256
	v_cvt_pk_bf16_f32 v8, v20, v21
	v_cvt_pk_bf16_f32 v9, v22, v23
	v_cvt_pk_bf16_f32 v10, v12, v13
	v_cvt_pk_bf16_f32 v11, v14, v15
	v_add_co_u32_e32 v14, vcc, s52, v120
	v_lshl_add_u64 v[12:13], v[120:121], 0, s[8:9]
	s_nop 0
	v_addc_co_u32_e32 v15, vcc, 0, v121, vcc
	s_and_b64 vcc, exec, s[10:11]
	s_mov_b32 s53, s12
	s_mov_b32 s20, s14
	s_mov_b64 s[24:25], s[18:19]
	s_mov_b64 s[22:23], s[16:17]
	global_store_dwordx4 v[14:15], v[8:11], off
	v_cvt_pk_bf16_f32 v4, v4, v5
	v_cvt_pk_bf16_f32 v5, v6, v7
	v_cvt_pk_bf16_f32 v6, v0, v1
	v_cvt_pk_bf16_f32 v7, v2, v3
	global_store_dwordx4 v[12:13], v[4:7], off offset:256
	s_cbranch_vccz .LBB0_706
	s_waitcnt vmcnt(0)
	s_cmpk_gt_u32 s31, 0xff
	s_cbranch_scc1 .LBB0_717
	s_barrier

; #define PG8_STAGE(bufoff, gbase, voff) do { _Pragma("unroll") for (int _i = 0; _i < 2; ++_i) \
;         __builtin_amdgcn_global_load_lds((const unsigned*)((const char*)(gbase) + (voff)[_i]), (LAS unsigned*)(lds + (bufoff) + ldsw + _i * 8192), 16, 0, 0); } while (0)
; #define PG8_LDA(dst, b, h) do { _Pragma("unroll") for (int m = 0; m < 4; ++m) _Pragma("unroll") for (int k = 0; k < 2; ++k) dst[m][k] = *(const LAS bf16x8*)(lds + PG8_SA(b, h) + aoff + m * 2048 + k * 1024); } while (0)
; #define PG8_LDB(dst, b, h) do { _Pragma("unroll") for (int n = 0; n < 2; ++n) _Pragma("unroll") for (int k = 0; k < 2; ++k) dst[n][k] = *(const LAS bf16x8*)(lds + PG8_SB(b, h) + boff + n * 2048 + k * 1024); } while (0)
; #define PG8_WAIT_V(n) asm volatile("s_waitcnt vmcnt(" #n ")" ::: "memory")
; #define PG8_WAIT_L(n) asm volatile("s_waitcnt lgkmcnt(" #n ")" ::: "memory")
; #define PG8_BAR __builtin_amdgcn_s_barrier()
; #define PG8_SCHED __builtin_amdgcn_sched_barrier(0)
; template <class Epi, class Sched>
; __device__ __forceinline__ void gemm_phase(LAS unsigned char* lds, const Gemm g, const Sched& S, const Epi& E) {
;     ...
;         const bool has_next = S.next(ui + 1, nxt);
;         const char* nA = has_next ? (const char*)g.A + (size_t)nxt.pm * tstep : cA; const char* nB = has_next ? (const char*)g.Bt + (size_t)nxt.pn * tstep : cB;
;         for (int t = 0; t < nt; t += 2) {
;             const bool last = (t == nt - 2);
;             const char* a1 = cA + (size_t)(t + 1) * kstep;
;             const char* a2 = last ? nA : cA + (size_t)(t + 2) * kstep; const char* b2 = last ? nB : cB + (size_t)(t + 2) * kstep;
;             const char* a3 = a2 + kstep; const char* b3 = b2 + kstep;
;             PG8_LDB(B0, 0, 0); PG8_SCHED; PG8_LDA(At, 0, 0); PG8_STAGE(PG8_SA(1, 1), a1 + hstep, voffA);
;             PG8_WAIT_L(8); PG8_BAR; PG8_WAIT_L(0); PG8_MMA(0, 0, At, B0); PG8_BAR; PG8_SCHED;
;             PG8_LDB(B1, 0, 1); PG8_STAGE(PG8_SB(0, 0), b2, voffB);
;             PG8_BAR; PG8_WAIT_L(0); PG8_MMA(0, 1, At, B1); PG8_BAR;
;             PG8_LDA(At, 0, 1); PG8_STAGE(PG8_SA(0, 0), a2, voffA);
;             PG8_BAR; PG8_WAIT_L(0); PG8_MMA(1, 0, At, B0); PG8_BAR; PG8_SCHED;
;             PG8_STAGE(PG8_SB(0, 1), b2 + hstep, voffB);
;             PG8_WAIT_V(6); PG8_BAR; PG8_MMA(1, 1, At, B1); PG8_BAR;
.LBB0_825:
	s_ashr_i32 s7, s6, 31
	v_cmp_lt_i64_e32 vcc, s[8:9], v[156:157]
	s_lshl_b64 s[8:9], s[6:7], 20
	s_add_u32 s8, s22, s8
	s_addc_u32 s9, s23, s9
	s_and_b64 s[10:11], vcc, exec
	s_cselect_b32 s7, s9, s15
	s_cselect_b32 s39, s8, s14
	s_ashr_i32 s5, s4, 31
	s_lshl_b64 s[10:11], s[4:5], 20
	s_add_u32 s10, s50, s10
	s_addc_u32 s11, s51, s11
	s_and_b64 s[18:19], vcc, exec
	s_cselect_b32 s5, s11, s17
	s_cselect_b32 s40, s10, s16
	s_add_u32 s14, s14, 0x80080
	s_addc_u32 s15, s15, 0
	s_add_u32 s41, s16, 0x100
	s_addc_u32 s42, s17, 0
	s_mov_b32 s43, -2
	ds_read_b128 v[128:131], v168
	ds_read_b128 v[132:135], v168 offset:1024
	ds_read_b128 v[136:139], v168 offset:2048
	ds_read_b128 v[140:143], v168 offset:3072
	s_add_u32 s16, s14, 0xfff80080
	s_addc_u32 s17, s15, -1
	s_cmp_eq_u32 s43, 28
	s_cselect_b32 s19, s7, s17
	s_cselect_b32 s18, s39, s16
	s_cselect_b32 s17, s5, s42
	s_cselect_b32 s16, s40, s41
	s_add_i32 m0, s13, 0xc000
	ds_read_b128 v[162:165], v169
	ds_read_b128 v[172:175], v169 offset:1024
	ds_read_b128 v[176:179], v169 offset:2048
	ds_read_b128 v[180:183], v169 offset:3072
	ds_read_b128 v[184:187], v169 offset:4096
	ds_read_b128 v[188:191], v169 offset:5120
	ds_read_b128 v[192:195], v169 offset:6144
	ds_read_b128 v[196:199], v169 offset:7168
	global_load_lds_dwordx4 v152, s[14:15]
	s_add_i32 m0, s13, 0xe000
	s_nop 0
	global_load_lds_dwordx4 v154, s[14:15]
	s_waitcnt lgkmcnt(8)
	s_waitcnt vmcnt(8)
	s_setprio 1
	s_barrier
	s_waitcnt lgkmcnt(0)
	v_mfma_f32_16x16x32_bf16 v[124:127], v[128:131], v[162:165], 0
	v_mfma_f32_16x16x32_bf16 v[120:123], v[136:139], v[162:165], 0
	v_mfma_f32_16x16x32_bf16 v[116:119], v[128:131], v[176:179], 0
	v_mfma_f32_16x16x32_bf16 v[112:115], v[136:139], v[176:179], 0
	v_mfma_f32_16x16x32_bf16 v[108:111], v[128:131], v[184:187], 0
	v_mfma_f32_16x16x32_bf16 v[100:103], v[136:139], v[184:187], 0
	v_mfma_f32_16x16x32_bf16 v[76:79], v[128:131], v[192:195], 0
	v_mfma_f32_16x16x32_bf16 v[72:75], v[136:139], v[192:195], 0
	v_mfma_f32_16x16x32_bf16 v[124:127], v[132:135], v[172:175], v[124:127]
	v_mfma_f32_16x16x32_bf16 v[120:123], v[140:143], v[172:175], v[120:123]
	v_mfma_f32_16x16x32_bf16 v[116:119], v[132:135], v[180:183], v[116:119]
	v_mfma_f32_16x16x32_bf16 v[112:115], v[140:143], v[180:183], v[112:115]
	v_mfma_f32_16x16x32_bf16 v[108:111], v[132:135], v[188:191], v[108:111]
	v_mfma_f32_16x16x32_bf16 v[100:103], v[140:143], v[188:191], v[100:103]
	v_mfma_f32_16x16x32_bf16 v[76:79], v[132:135], v[196:199], v[76:79]
	v_mfma_f32_16x16x32_bf16 v[72:75], v[140:143], v[196:199], v[72:75]
	s_barrier
	s_setprio 0
	s_add_i32 s44, s35, s24
	s_mov_b32 m0, s44
	ds_read_b128 v[202:205], v170
	ds_read_b128 v[206:209], v170 offset:1024
	ds_read_b128 v[210:213], v170 offset:2048
	ds_read_b128 v[214:217], v170 offset:3072
	global_load_lds_dwordx4 v146, s[16:17]
	s_add_i32 m0, s44, 0x2000
	s_nop 0
	global_load_lds_dwordx4 v150, s[16:17]
	s_waitcnt vmcnt(8)
	s_setprio 1
	s_barrier
	s_waitcnt lgkmcnt(0)
	v_mfma_f32_16x16x32_bf16 v[104:107], v[202:205], v[162:165], 0
	v_mfma_f32_16x16x32_bf16 v[96:99], v[210:213], v[162:165], 0
	v_mfma_f32_16x16x32_bf16 v[92:95], v[202:205], v[176:179], 0
	v_mfma_f32_16x16x32_bf16 v[88:91], v[210:213], v[176:179], 0
	v_mfma_f32_16x16x32_bf16 v[84:87], v[202:205], v[184:187], 0
	v_mfma_f32_16x16x32_bf16 v[80:83], v[210:213], v[184:187], 0
	v_mfma_f32_16x16x32_bf16 v[68:71], v[202:205], v[192:195], 0
	v_mfma_f32_16x16x32_bf16 v[64:67], v[210:213], v[192:195], 0
	v_mfma_f32_16x16x32_bf16 v[104:107], v[206:209], v[172:175], v[104:107]
	v_mfma_f32_16x16x32_bf16 v[96:99], v[214:217], v[172:175], v[96:99]
	v_mfma_f32_16x16x32_bf16 v[92:95], v[206:209], v[180:183], v[92:95]
	v_mfma_f32_16x16x32_bf16 v[88:91], v[214:217], v[180:183], v[88:91]
	v_mfma_f32_16x16x32_bf16 v[84:87], v[206:209], v[188:191], v[84:87]
	v_mfma_f32_16x16x32_bf16 v[80:83], v[214:217], v[188:191], v[80:83]
	v_mfma_f32_16x16x32_bf16 v[68:71], v[206:209], v[196:199], v[68:71]
	v_mfma_f32_16x16x32_bf16 v[64:67], v[214:217], v[196:199], v[64:67]
	s_barrier
	s_setprio 0
	s_mov_b32 m0, s13
	v_lshl_add_u64 v[222:223], s[18:19], 0, v[144:145]
	ds_read_b128 v[162:165], v169 offset:16384
	ds_read_b128 v[172:175], v169 offset:17408
	ds_read_b128 v[176:179], v169 offset:18432
	ds_read_b128 v[180:183], v169 offset:19456
	ds_read_b128 v[184:187], v169 offset:20480
	ds_read_b128 v[188:191], v169 offset:21504
	ds_read_b128 v[192:195], v169 offset:22528
	ds_read_b128 v[196:199], v169 offset:23552
	global_load_lds_dwordx4 v144, s[18:19]
	v_lshl_add_u64 v[224:225], s[18:19], 0, v[148:149]
	s_mov_b32 m0, s25
	s_nop 0
	global_load_lds_dwordx4 v148, s[18:19]
	s_setprio 1
	s_barrier
	s_waitcnt lgkmcnt(0)
	v_mfma_f32_16x16x32_bf16 v[60:63], v[128:131], v[162:165], 0
	v_mfma_f32_16x16x32_bf16 v[56:59], v[136:139], v[162:165], 0
	v_mfma_f32_16x16x32_bf16 v[48:51], v[128:131], v[176:179], 0
	v_mfma_f32_16x16x32_bf16 v[40:43], v[136:139], v[176:179], 0
	v_mfma_f32_16x16x32_bf16 v[32:35], v[128:131], v[184:187], 0
	v_mfma_f32_16x16x32_bf16 v[24:27], v[136:139], v[184:187], 0
	v_mfma_f32_16x16x32_bf16 v[16:19], v[128:131], v[192:195], 0
	v_mfma_f32_16x16x32_bf16 v[8:11], v[136:139], v[192:195], 0
	v_mfma_f32_16x16x32_bf16 v[60:63], v[132:135], v[172:175], v[60:63]
	v_mfma_f32_16x16x32_bf16 v[56:59], v[140:143], v[172:175], v[56:59]
	v_mfma_f32_16x16x32_bf16 v[48:51], v[132:135], v[180:183], v[48:51]
	v_mfma_f32_16x16x32_bf16 v[40:43], v[140:143], v[180:183], v[40:43]
	v_mfma_f32_16x16x32_bf16 v[32:35], v[132:135], v[188:191], v[32:35]
	v_mfma_f32_16x16x32_bf16 v[24:27], v[140:143], v[188:191], v[24:27]
	v_mfma_f32_16x16x32_bf16 v[16:19], v[132:135], v[196:199], v[16:19]
	v_mfma_f32_16x16x32_bf16 v[8:11], v[140:143], v[196:199], v[8:11]
	s_barrier
; #define PG8_STAGE(bufoff, gbase, voff) do { _Pragma("unroll") for (int _i = 0; _i < 2; ++_i) \
;         __builtin_amdgcn_global_load_lds((const unsigned*)((const char*)(gbase) + (voff)[_i]), (LAS unsigned*)(lds + (bufoff) + ldsw + _i * 8192), 16, 0, 0); } while (0)
; #define PG8_LDA(dst, b, h) do { _Pragma("unroll") for (int m = 0; m < 4; ++m) _Pragma("unroll") for (int k = 0; k < 2; ++k) dst[m][k] = *(const LAS bf16x8*)(lds + PG8_SA(b, h) + aoff + m * 2048 + k * 1024); } while (0)
; #define PG8_LDB(dst, b, h) do { _Pragma("unroll") for (int n = 0; n < 2; ++n) _Pragma("unroll") for (int k = 0; k < 2; ++k) dst[n][k] = *(const LAS bf16x8*)(lds + PG8_SB(b, h) + boff + n * 2048 + k * 1024); } while (0)
; #define PG8_MMA(ai, bj, At, Bt) do { __builtin_amdgcn_s_setprio(1); _Pragma("unroll") for (int m = 0; m < 4; ++m) _Pragma("unroll") for (int n = 0; n < 2; ++n) _Pragma("unroll") for (int k = 0; k < 2; ++k) \
;         acc[ai][bj][m][n] = __builtin_amdgcn_mfma_f32_16x16x32_bf16(Bt[n][k], At[m][k], acc[ai][bj][m][n], 0, 0, 0); __builtin_amdgcn_s_setprio(0); } while (0)
; #define PG8_WAIT_V(n) asm volatile("s_waitcnt vmcnt(" #n ")" ::: "memory")
; #define PG8_WAIT_L(n) asm volatile("s_waitcnt lgkmcnt(" #n ")" ::: "memory")
; template <class Epi, class Sched>
; __device__ __forceinline__ void gemm_phase(LAS unsigned char* lds, const Gemm g, const Sched& S, const Epi& E) {
;     ...
;         for (int t = 0; t < nt; t += 2) {
;             const bool last = (t == nt - 2);
;             const char* a1 = cA + (size_t)(t + 1) * kstep;
;             const char* a2 = last ? nA : cA + (size_t)(t + 2) * kstep; const char* b2 = last ? nB : cB + (size_t)(t + 2) * kstep;
;             const char* a3 = a2 + kstep; const char* b3 = b2 + kstep;
;             PG8_LDB(B0, 0, 0); PG8_SCHED; PG8_LDA(At, 0, 0); PG8_STAGE(PG8_SA(1, 1), a1 + hstep, voffA);
;             PG8_WAIT_L(8); PG8_BAR; PG8_WAIT_L(0); PG8_MMA(0, 0, At, B0); PG8_BAR; PG8_SCHED;
;             PG8_LDB(B1, 0, 1); PG8_STAGE(PG8_SB(0, 0), b2, voffB);
;             PG8_BAR; PG8_WAIT_L(0); PG8_MMA(0, 1, At, B1); PG8_BAR;
;             PG8_LDA(At, 0, 1); PG8_STAGE(PG8_SA(0, 0), a2, voffA);
;             PG8_BAR; PG8_WAIT_L(0); PG8_MMA(1, 0, At, B0); PG8_BAR; PG8_SCHED;
;             PG8_STAGE(PG8_SB(0, 1), b2 + hstep, voffB);
;             PG8_WAIT_V(6); PG8_BAR; PG8_MMA(1, 1, At, B1); PG8_BAR;
	s_setprio 0
	s_add_u32 s44, s16, 0x80000
	s_addc_u32 s45, s17, 0
	s_add_i32 s46, s36, s24
	s_mov_b32 m0, s46
	s_nop 0
	global_load_lds_dwordx4 v146, s[44:45]
	s_add_i32 m0, s46, 0x2000
	s_nop 0
	global_load_lds_dwordx4 v150, s[44:45]
	s_add_u32 s18, s18, 0x80000
	s_addc_u32 s19, s19, 0
	s_mov_b32 m0, s26
	s_nop 0
	global_load_lds_dwordx4 v144, s[18:19]
	s_mov_b32 m0, s27
	s_nop 0
	global_load_lds_dwordx4 v148, s[18:19]
	s_waitcnt vmcnt(10)
	s_setprio 1
	s_barrier
	v_mfma_f32_16x16x32_bf16 v[52:55], v[202:205], v[162:165], 0
	v_mfma_f32_16x16x32_bf16 v[44:47], v[210:213], v[162:165], 0
	v_mfma_f32_16x16x32_bf16 v[36:39], v[202:205], v[176:179], 0
	v_mfma_f32_16x16x32_bf16 v[28:31], v[210:213], v[176:179], 0
	v_mfma_f32_16x16x32_bf16 v[20:23], v[202:205], v[184:187], 0
	v_mfma_f32_16x16x32_bf16 v[12:15], v[210:213], v[184:187], 0
	v_mfma_f32_16x16x32_bf16 v[4:7], v[202:205], v[192:195], 0
	v_mfma_f32_16x16x32_bf16 v[0:3], v[210:213], v[192:195], 0
	v_mfma_f32_16x16x32_bf16 v[52:55], v[206:209], v[172:175], v[52:55]
	v_mfma_f32_16x16x32_bf16 v[44:47], v[214:217], v[172:175], v[44:47]
	v_mfma_f32_16x16x32_bf16 v[36:39], v[206:209], v[180:183], v[36:39]
	v_mfma_f32_16x16x32_bf16 v[28:31], v[214:217], v[180:183], v[28:31]
	v_mfma_f32_16x16x32_bf16 v[20:23], v[206:209], v[188:191], v[20:23]
	v_mfma_f32_16x16x32_bf16 v[12:15], v[214:217], v[188:191], v[12:15]
	v_mfma_f32_16x16x32_bf16 v[4:7], v[206:209], v[196:199], v[4:7]
	v_mfma_f32_16x16x32_bf16 v[0:3], v[214:217], v[196:199], v[0:3]
	s_barrier
	s_setprio 0
	s_add_i32 s44, 0, 0x18000
	v_add_u32_e32 v140, s44, v167
	ds_read_b128 v[128:131], v140
	ds_read_b128 v[132:135], v140 offset:1024
	ds_read_b128 v[136:139], v140 offset:2048
	ds_read_b128 v[140:143], v140 offset:3072
	ds_read_b128 v[162:165], v169 offset:32768
	ds_read_b128 v[172:175], v169 offset:33792
	ds_read_b128 v[176:179], v169 offset:34816
	ds_read_b128 v[180:183], v169 offset:35840
	ds_read_b128 v[184:187], v169 offset:36864
	ds_read_b128 v[188:191], v169 offset:37888
	ds_read_b128 v[192:195], v169 offset:38912
	ds_read_b128 v[196:199], v169 offset:39936
	s_waitcnt lgkmcnt(8)
	s_waitcnt vmcnt(8)
	s_setprio 1
	s_barrier
	s_waitcnt lgkmcnt(0)
	v_mfma_f32_16x16x32_bf16 v[124:127], v[128:131], v[162:165], v[124:127]
	v_mfma_f32_16x16x32_bf16 v[120:123], v[136:139], v[162:165], v[120:123]
	v_mfma_f32_16x16x32_bf16 v[116:119], v[128:131], v[176:179], v[116:119]
	v_mfma_f32_16x16x32_bf16 v[112:115], v[136:139], v[176:179], v[112:115]
	v_mfma_f32_16x16x32_bf16 v[108:111], v[128:131], v[184:187], v[108:111]
	v_mfma_f32_16x16x32_bf16 v[100:103], v[136:139], v[184:187], v[100:103]
	v_mfma_f32_16x16x32_bf16 v[76:79], v[128:131], v[192:195], v[76:79]
	v_mfma_f32_16x16x32_bf16 v[72:75], v[136:139], v[192:195], v[72:75]
	v_mfma_f32_16x16x32_bf16 v[124:127], v[132:135], v[172:175], v[124:127]
	v_mfma_f32_16x16x32_bf16 v[120:123], v[140:143], v[172:175], v[120:123]
	v_mfma_f32_16x16x32_bf16 v[116:119], v[132:135], v[180:183], v[116:119]
	v_mfma_f32_16x16x32_bf16 v[112:115], v[140:143], v[180:183], v[112:115]
	v_mfma_f32_16x16x32_bf16 v[108:111], v[132:135], v[188:191], v[108:111]
	v_mfma_f32_16x16x32_bf16 v[100:103], v[140:143], v[188:191], v[100:103]
	v_mfma_f32_16x16x32_bf16 v[76:79], v[132:135], v[196:199], v[76:79]
	v_mfma_f32_16x16x32_bf16 v[72:75], v[140:143], v[196:199], v[72:75]
	s_barrier
	s_setprio 0
	s_add_i32 s18, 0, 0x1c000
	s_add_i32 s19, s44, s24
	v_add_u32_e32 v160, s18, v167
	s_add_u32 s0, s16, 0x80
	s_addc_u32 s1, s17, 0
	s_mov_b32 m0, s19
	ds_read_b128 v[202:205], v160
	ds_read_b128 v[206:209], v160 offset:1024
	ds_read_b128 v[210:213], v160 offset:2048
	ds_read_b128 v[214:217], v160 offset:3072
	global_load_lds_dwordx4 v146, s[0:1]
	s_add_i32 m0, s19, 0x2000
	s_nop 0
	global_load_lds_dwordx4 v150, s[0:1]
	s_waitcnt vmcnt(8)
	s_setprio 1
	s_barrier
	s_waitcnt lgkmcnt(0)
	v_mfma_f32_16x16x32_bf16 v[104:107], v[202:205], v[162:165], v[104:107]
	v_mfma_f32_16x16x32_bf16 v[96:99], v[210:213], v[162:165], v[96:99]
	v_mfma_f32_16x16x32_bf16 v[92:95], v[202:205], v[176:179], v[92:95]
	v_mfma_f32_16x16x32_bf16 v[88:91], v[210:213], v[176:179], v[88:91]
	v_mfma_f32_16x16x32_bf16 v[84:87], v[202:205], v[184:187], v[84:87]
	v_mfma_f32_16x16x32_bf16 v[80:83], v[210:213], v[184:187], v[80:83]
	v_mfma_f32_16x16x32_bf16 v[68:71], v[202:205], v[192:195], v[68:71]
	v_mfma_f32_16x16x32_bf16 v[64:67], v[210:213], v[192:195], v[64:67]
	v_mfma_f32_16x16x32_bf16 v[104:107], v[206:209], v[172:175], v[104:107]
	v_mfma_f32_16x16x32_bf16 v[96:99], v[214:217], v[172:175], v[96:99]
	v_mfma_f32_16x16x32_bf16 v[92:95], v[206:209], v[180:183], v[92:95]
	v_mfma_f32_16x16x32_bf16 v[88:91], v[214:217], v[180:183], v[88:91]
	v_mfma_f32_16x16x32_bf16 v[84:87], v[206:209], v[188:191], v[84:87]
	v_mfma_f32_16x16x32_bf16 v[80:83], v[214:217], v[188:191], v[80:83]
	v_mfma_f32_16x16x32_bf16 v[68:71], v[206:209], v[196:199], v[68:71]
	v_mfma_f32_16x16x32_bf16 v[64:67], v[214:217], v[196:199], v[64:67]
	s_barrier
	s_setprio 0
	s_mov_b32 m0, s31
	s_mov_b64 s[0:1], 0x80
	v_lshl_add_u64 v[218:219], v[222:223], 0, s[0:1]
	ds_read_b128 v[162:165], v169 offset:49152
	ds_read_b128 v[172:175], v169 offset:50176
	ds_read_b128 v[176:179], v169 offset:51200
	ds_read_b128 v[180:183], v169 offset:52224
	ds_read_b128 v[184:187], v169 offset:53248
	ds_read_b128 v[188:191], v169 offset:54272
	ds_read_b128 v[192:195], v169 offset:55296
	ds_read_b128 v[196:199], v169 offset:56320
	global_load_lds_dwordx4 v[218:219], off
	v_lshl_add_u64 v[218:219], v[224:225], 0, s[0:1]
	s_mov_b32 m0, s33
	s_nop 0
	global_load_lds_dwordx4 v[218:219], off
	s_setprio 1
	s_barrier
; #define PG8_STAGE(bufoff, gbase, voff) do { _Pragma("unroll") for (int _i = 0; _i < 2; ++_i) \
;         __builtin_amdgcn_global_load_lds((const unsigned*)((const char*)(gbase) + (voff)[_i]), (LAS unsigned*)(lds + (bufoff) + ldsw + _i * 8192), 16, 0, 0); } while (0)
; #define PG8_LDA(dst, b, h) do { _Pragma("unroll") for (int m = 0; m < 4; ++m) _Pragma("unroll") for (int k = 0; k < 2; ++k) dst[m][k] = *(const LAS bf16x8*)(lds + PG8_SA(b, h) + aoff + m * 2048 + k * 1024); } while (0)
; #define PG8_WAIT_V(n) asm volatile("s_waitcnt vmcnt(" #n ")" ::: "memory")
; #define PG8_WAIT_L(n) asm volatile("s_waitcnt lgkmcnt(" #n ")" ::: "memory")
; template <class Epi, class Sched>
; __device__ __forceinline__ void gemm_phase(LAS unsigned char* lds, const Gemm g, const Sched& S, const Epi& E) {
;     ...
;         for (int t = 0; t < nt; t += 2) {
;             const bool last = (t == nt - 2);
;             const char* a1 = cA + (size_t)(t + 1) * kstep;
;             const char* a2 = last ? nA : cA + (size_t)(t + 2) * kstep; const char* b2 = last ? nB : cB + (size_t)(t + 2) * kstep;
;             const char* a3 = a2 + kstep; const char* b3 = b2 + kstep;
;             PG8_LDB(B0, 0, 0); PG8_SCHED; PG8_LDA(At, 0, 0); PG8_STAGE(PG8_SA(1, 1), a1 + hstep, voffA);
;             PG8_WAIT_L(8); PG8_BAR; PG8_WAIT_L(0); PG8_MMA(0, 0, At, B0); PG8_BAR; PG8_SCHED;
;             PG8_LDB(B1, 0, 1); PG8_STAGE(PG8_SB(0, 0), b2, voffB);
;             PG8_BAR; PG8_WAIT_L(0); PG8_MMA(0, 1, At, B1); PG8_BAR;
;             PG8_LDA(At, 0, 1); PG8_STAGE(PG8_SA(0, 0), a2, voffA);
;             PG8_BAR; PG8_WAIT_L(0); PG8_MMA(1, 0, At, B0); PG8_BAR; PG8_SCHED;
;             PG8_STAGE(PG8_SB(0, 1), b2 + hstep, voffB);
;             PG8_WAIT_V(6); PG8_BAR; PG8_MMA(1, 1, At, B1); PG8_BAR;
;             PG8_LDB(B0, 1, 0); PG8_SCHED; PG8_LDA(At, 1, 0); PG8_STAGE(PG8_SA(0, 1), a2 + hstep, voffA);
;             PG8_WAIT_L(8); PG8_BAR; PG8_WAIT_L(0); PG8_MMA(0, 0, At, B0); PG8_BAR; PG8_SCHED;
;             PG8_LDB(B1, 1, 1); PG8_STAGE(PG8_SB(1, 0), b3, voffB);
;             PG8_BAR; PG8_WAIT_L(0); PG8_MMA(0, 1, At, B1); PG8_BAR;
;             PG8_LDA(At, 1, 1); PG8_STAGE(PG8_SA(1, 0), a3, voffA);
;             PG8_BAR; PG8_WAIT_L(0); PG8_MMA(1, 0, At, B0); PG8_BAR; PG8_SCHED;
;             PG8_STAGE(PG8_SB(1, 1), b3 + hstep, voffB);
;             PG8_WAIT_V(6); PG8_BAR; PG8_MMA(1, 1, At, B1); PG8_BAR;
	s_waitcnt lgkmcnt(0)
	v_mfma_f32_16x16x32_bf16 v[60:63], v[128:131], v[162:165], v[60:63]
	v_mfma_f32_16x16x32_bf16 v[56:59], v[136:139], v[162:165], v[56:59]
	v_mfma_f32_16x16x32_bf16 v[48:51], v[128:131], v[176:179], v[48:51]
	v_mfma_f32_16x16x32_bf16 v[40:43], v[136:139], v[176:179], v[40:43]
	v_mfma_f32_16x16x32_bf16 v[32:35], v[128:131], v[184:187], v[32:35]
	v_mfma_f32_16x16x32_bf16 v[24:27], v[136:139], v[184:187], v[24:27]
	v_mfma_f32_16x16x32_bf16 v[16:19], v[128:131], v[192:195], v[16:19]
	v_mfma_f32_16x16x32_bf16 v[8:11], v[136:139], v[192:195], v[8:11]
	v_mfma_f32_16x16x32_bf16 v[60:63], v[132:135], v[172:175], v[60:63]
	v_mfma_f32_16x16x32_bf16 v[56:59], v[140:143], v[172:175], v[56:59]
	v_mfma_f32_16x16x32_bf16 v[48:51], v[132:135], v[180:183], v[48:51]
	v_mfma_f32_16x16x32_bf16 v[40:43], v[140:143], v[180:183], v[40:43]
	v_mfma_f32_16x16x32_bf16 v[32:35], v[132:135], v[188:191], v[32:35]
	v_mfma_f32_16x16x32_bf16 v[24:27], v[140:143], v[188:191], v[24:27]
	v_mfma_f32_16x16x32_bf16 v[16:19], v[132:135], v[196:199], v[16:19]
	v_mfma_f32_16x16x32_bf16 v[8:11], v[140:143], v[196:199], v[8:11]
	s_barrier
	s_setprio 0
	s_add_u32 s16, s16, 0x80080
	s_addc_u32 s17, s17, 0
	s_add_i32 s18, s18, s24
	s_mov_b32 m0, s18
	s_nop 0
	global_load_lds_dwordx4 v146, s[16:17]
	s_add_i32 m0, s18, 0x2000
	s_nop 0
	global_load_lds_dwordx4 v150, s[16:17]
	s_waitcnt vmcnt(8)
	s_setprio 1
	s_barrier
	v_mfma_f32_16x16x32_bf16 v[52:55], v[202:205], v[162:165], v[52:55]
	v_mfma_f32_16x16x32_bf16 v[44:47], v[210:213], v[162:165], v[44:47]
	v_mfma_f32_16x16x32_bf16 v[36:39], v[202:205], v[176:179], v[36:39]
	v_mfma_f32_16x16x32_bf16 v[28:31], v[210:213], v[176:179], v[28:31]
	v_mfma_f32_16x16x32_bf16 v[20:23], v[202:205], v[184:187], v[20:23]
	v_mfma_f32_16x16x32_bf16 v[12:15], v[210:213], v[184:187], v[12:15]
	v_mfma_f32_16x16x32_bf16 v[4:7], v[202:205], v[192:195], v[4:7]
	v_mfma_f32_16x16x32_bf16 v[0:3], v[210:213], v[192:195], v[0:3]
	v_mfma_f32_16x16x32_bf16 v[52:55], v[206:209], v[172:175], v[52:55]
	v_mfma_f32_16x16x32_bf16 v[44:47], v[214:217], v[172:175], v[44:47]
	v_mfma_f32_16x16x32_bf16 v[36:39], v[206:209], v[180:183], v[36:39]
	v_mfma_f32_16x16x32_bf16 v[28:31], v[214:217], v[180:183], v[28:31]
	v_mfma_f32_16x16x32_bf16 v[20:23], v[206:209], v[188:191], v[20:23]
	v_mfma_f32_16x16x32_bf16 v[12:15], v[214:217], v[188:191], v[12:15]
	v_mfma_f32_16x16x32_bf16 v[4:7], v[206:209], v[196:199], v[4:7]
	v_mfma_f32_16x16x32_bf16 v[0:3], v[214:217], v[196:199], v[0:3]
	s_barrier
	s_setprio 0
	s_add_i32 s43, s43, 2
	s_add_u32 s14, s14, 0x100
	s_addc_u32 s15, s15, 0
	s_add_u32 s41, s41, 0x100
	s_addc_u32 s42, s42, 0
	s_cmp_gt_u32 s43, 29
.LBB0_826:
	ds_read_b128 v[128:131], v168
	ds_read_b128 v[132:135], v168 offset:1024
	ds_read_b128 v[136:139], v168 offset:2048
	ds_read_b128 v[140:143], v168 offset:3072
	s_add_u32 s16, s14, 0xfff80080
	s_addc_u32 s17, s15, -1
	s_cmp_eq_u32 s43, 28
	s_cselect_b32 s19, s7, s17
	s_cselect_b32 s18, s39, s16
	s_cselect_b32 s17, s5, s42
	s_cselect_b32 s16, s40, s41
	s_add_i32 m0, s13, 0xc000
	ds_read_b128 v[162:165], v169
	ds_read_b128 v[172:175], v169 offset:1024
	ds_read_b128 v[176:179], v169 offset:2048
	ds_read_b128 v[180:183], v169 offset:3072
	ds_read_b128 v[184:187], v169 offset:4096
	ds_read_b128 v[188:191], v169 offset:5120
	ds_read_b128 v[192:195], v169 offset:6144
	ds_read_b128 v[196:199], v169 offset:7168
	global_load_lds_dwordx4 v152, s[14:15]
	s_add_i32 m0, s13, 0xe000
	s_nop 0
	global_load_lds_dwordx4 v154, s[14:15]
	s_waitcnt lgkmcnt(8)
	s_waitcnt vmcnt(8)
	s_setprio 1
	s_barrier
	s_waitcnt lgkmcnt(0)
	v_mfma_f32_16x16x32_bf16 v[124:127], v[128:131], v[162:165], v[124:127]
	v_mfma_f32_16x16x32_bf16 v[120:123], v[136:139], v[162:165], v[120:123]
	v_mfma_f32_16x16x32_bf16 v[116:119], v[128:131], v[176:179], v[116:119]
	v_mfma_f32_16x16x32_bf16 v[112:115], v[136:139], v[176:179], v[112:115]
	v_mfma_f32_16x16x32_bf16 v[108:111], v[128:131], v[184:187], v[108:111]
	v_mfma_f32_16x16x32_bf16 v[100:103], v[136:139], v[184:187], v[100:103]
	v_mfma_f32_16x16x32_bf16 v[76:79], v[128:131], v[192:195], v[76:79]
	v_mfma_f32_16x16x32_bf16 v[72:75], v[136:139], v[192:195], v[72:75]
	v_mfma_f32_16x16x32_bf16 v[124:127], v[132:135], v[172:175], v[124:127]
	v_mfma_f32_16x16x32_bf16 v[120:123], v[140:143], v[172:175], v[120:123]
	v_mfma_f32_16x16x32_bf16 v[116:119], v[132:135], v[180:183], v[116:119]
	v_mfma_f32_16x16x32_bf16 v[112:115], v[140:143], v[180:183], v[112:115]
	v_mfma_f32_16x16x32_bf16 v[108:111], v[132:135], v[188:191], v[108:111]
	v_mfma_f32_16x16x32_bf16 v[100:103], v[140:143], v[188:191], v[100:103]
	v_mfma_f32_16x16x32_bf16 v[76:79], v[132:135], v[196:199], v[76:79]
	v_mfma_f32_16x16x32_bf16 v[72:75], v[140:143], v[196:199], v[72:75]
	s_barrier
	s_setprio 0
	s_add_i32 s44, s35, s24
	s_mov_b32 m0, s44
	ds_read_b128 v[202:205], v170
	ds_read_b128 v[206:209], v170 offset:1024
	ds_read_b128 v[210:213], v170 offset:2048
	ds_read_b128 v[214:217], v170 offset:3072
	global_load_lds_dwordx4 v146, s[16:17]
	s_add_i32 m0, s44, 0x2000
	s_nop 0
	global_load_lds_dwordx4 v150, s[16:17]
	s_waitcnt vmcnt(8)
	s_setprio 1
	s_barrier
; #define PG8_STAGE(bufoff, gbase, voff) do { _Pragma("unroll") for (int _i = 0; _i < 2; ++_i) \
;         __builtin_amdgcn_global_load_lds((const unsigned*)((const char*)(gbase) + (voff)[_i]), (LAS unsigned*)(lds + (bufoff) + ldsw + _i * 8192), 16, 0, 0); } while (0)
; #define PG8_LDA(dst, b, h) do { _Pragma("unroll") for (int m = 0; m < 4; ++m) _Pragma("unroll") for (int k = 0; k < 2; ++k) dst[m][k] = *(const LAS bf16x8*)(lds + PG8_SA(b, h) + aoff + m * 2048 + k * 1024); } while (0)
; #define PG8_WAIT_V(n) asm volatile("s_waitcnt vmcnt(" #n ")" ::: "memory")
; #define PG8_WAIT_L(n) asm volatile("s_waitcnt lgkmcnt(" #n ")" ::: "memory")
; template <class Epi, class Sched>
; __device__ __forceinline__ void gemm_phase(LAS unsigned char* lds, const Gemm g, const Sched& S, const Epi& E) {
;     ...
;         for (int t = 0; t < nt; t += 2) {
;             const bool last = (t == nt - 2);
;             const char* a1 = cA + (size_t)(t + 1) * kstep;
;             const char* a2 = last ? nA : cA + (size_t)(t + 2) * kstep; const char* b2 = last ? nB : cB + (size_t)(t + 2) * kstep;
;             const char* a3 = a2 + kstep; const char* b3 = b2 + kstep;
;             PG8_LDB(B0, 0, 0); PG8_SCHED; PG8_LDA(At, 0, 0); PG8_STAGE(PG8_SA(1, 1), a1 + hstep, voffA);
;             PG8_WAIT_L(8); PG8_BAR; PG8_WAIT_L(0); PG8_MMA(0, 0, At, B0); PG8_BAR; PG8_SCHED;
;             PG8_LDB(B1, 0, 1); PG8_STAGE(PG8_SB(0, 0), b2, voffB);
;             PG8_BAR; PG8_WAIT_L(0); PG8_MMA(0, 1, At, B1); PG8_BAR;
;             PG8_LDA(At, 0, 1); PG8_STAGE(PG8_SA(0, 0), a2, voffA);
;             PG8_BAR; PG8_WAIT_L(0); PG8_MMA(1, 0, At, B0); PG8_BAR; PG8_SCHED;
;             PG8_STAGE(PG8_SB(0, 1), b2 + hstep, voffB);
;             PG8_WAIT_V(6); PG8_BAR; PG8_MMA(1, 1, At, B1); PG8_BAR;
;             PG8_LDB(B0, 1, 0); PG8_SCHED; PG8_LDA(At, 1, 0); PG8_STAGE(PG8_SA(0, 1), a2 + hstep, voffA);
;             PG8_WAIT_L(8); PG8_BAR; PG8_WAIT_L(0); PG8_MMA(0, 0, At, B0); PG8_BAR; PG8_SCHED;
;             PG8_LDB(B1, 1, 1); PG8_STAGE(PG8_SB(1, 0), b3, voffB);
;             PG8_BAR; PG8_WAIT_L(0); PG8_MMA(0, 1, At, B1); PG8_BAR;
;             PG8_LDA(At, 1, 1); PG8_STAGE(PG8_SA(1, 0), a3, voffA);
;             PG8_BAR; PG8_WAIT_L(0); PG8_MMA(1, 0, At, B0); PG8_BAR; PG8_SCHED;
;             PG8_STAGE(PG8_SB(1, 1), b3 + hstep, voffB);
;             PG8_WAIT_V(6); PG8_BAR; PG8_MMA(1, 1, At, B1); PG8_BAR;
	s_waitcnt lgkmcnt(0)
	v_mfma_f32_16x16x32_bf16 v[104:107], v[202:205], v[162:165], v[104:107]
	v_mfma_f32_16x16x32_bf16 v[96:99], v[210:213], v[162:165], v[96:99]
	v_mfma_f32_16x16x32_bf16 v[92:95], v[202:205], v[176:179], v[92:95]
	v_mfma_f32_16x16x32_bf16 v[88:91], v[210:213], v[176:179], v[88:91]
	v_mfma_f32_16x16x32_bf16 v[84:87], v[202:205], v[184:187], v[84:87]
	v_mfma_f32_16x16x32_bf16 v[80:83], v[210:213], v[184:187], v[80:83]
	v_mfma_f32_16x16x32_bf16 v[68:71], v[202:205], v[192:195], v[68:71]
	v_mfma_f32_16x16x32_bf16 v[64:67], v[210:213], v[192:195], v[64:67]
	v_mfma_f32_16x16x32_bf16 v[104:107], v[206:209], v[172:175], v[104:107]
	v_mfma_f32_16x16x32_bf16 v[96:99], v[214:217], v[172:175], v[96:99]
	v_mfma_f32_16x16x32_bf16 v[92:95], v[206:209], v[180:183], v[92:95]
	v_mfma_f32_16x16x32_bf16 v[88:91], v[214:217], v[180:183], v[88:91]
	v_mfma_f32_16x16x32_bf16 v[84:87], v[206:209], v[188:191], v[84:87]
	v_mfma_f32_16x16x32_bf16 v[80:83], v[214:217], v[188:191], v[80:83]
	v_mfma_f32_16x16x32_bf16 v[68:71], v[206:209], v[196:199], v[68:71]
	v_mfma_f32_16x16x32_bf16 v[64:67], v[214:217], v[196:199], v[64:67]
	s_barrier
	s_setprio 0
	s_mov_b32 m0, s13
	v_lshl_add_u64 v[222:223], s[18:19], 0, v[144:145]
	ds_read_b128 v[162:165], v169 offset:16384
	ds_read_b128 v[172:175], v169 offset:17408
	ds_read_b128 v[176:179], v169 offset:18432
	ds_read_b128 v[180:183], v169 offset:19456
	ds_read_b128 v[184:187], v169 offset:20480
	ds_read_b128 v[188:191], v169 offset:21504
	ds_read_b128 v[192:195], v169 offset:22528
	ds_read_b128 v[196:199], v169 offset:23552
	global_load_lds_dwordx4 v144, s[18:19]
	v_lshl_add_u64 v[224:225], s[18:19], 0, v[148:149]
	s_mov_b32 m0, s25
	s_nop 0
	global_load_lds_dwordx4 v148, s[18:19]
	s_setprio 1
	s_barrier
	s_waitcnt lgkmcnt(0)
	v_mfma_f32_16x16x32_bf16 v[60:63], v[128:131], v[162:165], v[60:63]
	v_mfma_f32_16x16x32_bf16 v[56:59], v[136:139], v[162:165], v[56:59]
	v_mfma_f32_16x16x32_bf16 v[48:51], v[128:131], v[176:179], v[48:51]
	v_mfma_f32_16x16x32_bf16 v[40:43], v[136:139], v[176:179], v[40:43]
	v_mfma_f32_16x16x32_bf16 v[32:35], v[128:131], v[184:187], v[32:35]
	v_mfma_f32_16x16x32_bf16 v[24:27], v[136:139], v[184:187], v[24:27]
	v_mfma_f32_16x16x32_bf16 v[16:19], v[128:131], v[192:195], v[16:19]
	v_mfma_f32_16x16x32_bf16 v[8:11], v[136:139], v[192:195], v[8:11]
	v_mfma_f32_16x16x32_bf16 v[60:63], v[132:135], v[172:175], v[60:63]
	v_mfma_f32_16x16x32_bf16 v[56:59], v[140:143], v[172:175], v[56:59]
	v_mfma_f32_16x16x32_bf16 v[48:51], v[132:135], v[180:183], v[48:51]
	v_mfma_f32_16x16x32_bf16 v[40:43], v[140:143], v[180:183], v[40:43]
	v_mfma_f32_16x16x32_bf16 v[32:35], v[132:135], v[188:191], v[32:35]
	v_mfma_f32_16x16x32_bf16 v[24:27], v[140:143], v[188:191], v[24:27]
	v_mfma_f32_16x16x32_bf16 v[16:19], v[132:135], v[196:199], v[16:19]
	v_mfma_f32_16x16x32_bf16 v[8:11], v[140:143], v[196:199], v[8:11]
	s_barrier
	s_setprio 0
	s_add_u32 s44, s16, 0x80000
	s_addc_u32 s45, s17, 0
	s_add_i32 s46, s36, s24
	s_mov_b32 m0, s46
	s_nop 0
	global_load_lds_dwordx4 v146, s[44:45]
	s_add_i32 m0, s46, 0x2000
	s_nop 0
	global_load_lds_dwordx4 v150, s[44:45]
	s_add_u32 s18, s18, 0x80000
	s_addc_u32 s19, s19, 0
	s_mov_b32 m0, s26
	s_nop 0
	global_load_lds_dwordx4 v144, s[18:19]
	s_mov_b32 m0, s27
	s_nop 0
	global_load_lds_dwordx4 v148, s[18:19]
	s_waitcnt vmcnt(10)
	s_setprio 1
	s_barrier
	v_mfma_f32_16x16x32_bf16 v[52:55], v[202:205], v[162:165], v[52:55]
	v_mfma_f32_16x16x32_bf16 v[44:47], v[210:213], v[162:165], v[44:47]
	v_mfma_f32_16x16x32_bf16 v[36:39], v[202:205], v[176:179], v[36:39]
	v_mfma_f32_16x16x32_bf16 v[28:31], v[210:213], v[176:179], v[28:31]
	v_mfma_f32_16x16x32_bf16 v[20:23], v[202:205], v[184:187], v[20:23]
	v_mfma_f32_16x16x32_bf16 v[12:15], v[210:213], v[184:187], v[12:15]
	v_mfma_f32_16x16x32_bf16 v[4:7], v[202:205], v[192:195], v[4:7]
	v_mfma_f32_16x16x32_bf16 v[0:3], v[210:213], v[192:195], v[0:3]
	v_mfma_f32_16x16x32_bf16 v[52:55], v[206:209], v[172:175], v[52:55]
	v_mfma_f32_16x16x32_bf16 v[44:47], v[214:217], v[172:175], v[44:47]
	v_mfma_f32_16x16x32_bf16 v[36:39], v[206:209], v[180:183], v[36:39]
	v_mfma_f32_16x16x32_bf16 v[28:31], v[214:217], v[180:183], v[28:31]
	v_mfma_f32_16x16x32_bf16 v[20:23], v[206:209], v[188:191], v[20:23]
	v_mfma_f32_16x16x32_bf16 v[12:15], v[214:217], v[188:191], v[12:15]
	v_mfma_f32_16x16x32_bf16 v[4:7], v[206:209], v[196:199], v[4:7]
	v_mfma_f32_16x16x32_bf16 v[0:3], v[214:217], v[196:199], v[0:3]
	s_barrier
	s_setprio 0
	s_add_i32 s44, 0, 0x18000
	v_add_u32_e32 v140, s44, v167
	ds_read_b128 v[128:131], v140
	ds_read_b128 v[132:135], v140 offset:1024
	ds_read_b128 v[136:139], v140 offset:2048
	ds_read_b128 v[140:143], v140 offset:3072
	ds_read_b128 v[162:165], v169 offset:32768
	ds_read_b128 v[172:175], v169 offset:33792
	ds_read_b128 v[176:179], v169 offset:34816
	ds_read_b128 v[180:183], v169 offset:35840
	ds_read_b128 v[184:187], v169 offset:36864
	ds_read_b128 v[188:191], v169 offset:37888
	ds_read_b128 v[192:195], v169 offset:38912
	ds_read_b128 v[196:199], v169 offset:39936
	s_waitcnt lgkmcnt(8)
	s_waitcnt vmcnt(8)
	s_setprio 1
	s_barrier
; #define PG8_STAGE(bufoff, gbase, voff) do { _Pragma("unroll") for (int _i = 0; _i < 2; ++_i) \
;         __builtin_amdgcn_global_load_lds((const unsigned*)((const char*)(gbase) + (voff)[_i]), (LAS unsigned*)(lds + (bufoff) + ldsw + _i * 8192), 16, 0, 0); } while (0)
; #define PG8_LDA(dst, b, h) do { _Pragma("unroll") for (int m = 0; m < 4; ++m) _Pragma("unroll") for (int k = 0; k < 2; ++k) dst[m][k] = *(const LAS bf16x8*)(lds + PG8_SA(b, h) + aoff + m * 2048 + k * 1024); } while (0)
; #define PG8_WAIT_V(n) asm volatile("s_waitcnt vmcnt(" #n ")" ::: "memory")
; #define PG8_WAIT_L(n) asm volatile("s_waitcnt lgkmcnt(" #n ")" ::: "memory")
; template <class Epi, class Sched>
; __device__ __forceinline__ void gemm_phase(LAS unsigned char* lds, const Gemm g, const Sched& S, const Epi& E) {
;     ...
;         for (int t = 0; t < nt; t += 2) {
;             const bool last = (t == nt - 2);
;             const char* a1 = cA + (size_t)(t + 1) * kstep;
;             const char* a2 = last ? nA : cA + (size_t)(t + 2) * kstep; const char* b2 = last ? nB : cB + (size_t)(t + 2) * kstep;
;             const char* a3 = a2 + kstep; const char* b3 = b2 + kstep;
;             PG8_LDB(B0, 0, 0); PG8_SCHED; PG8_LDA(At, 0, 0); PG8_STAGE(PG8_SA(1, 1), a1 + hstep, voffA);
;             PG8_WAIT_L(8); PG8_BAR; PG8_WAIT_L(0); PG8_MMA(0, 0, At, B0); PG8_BAR; PG8_SCHED;
;             PG8_LDB(B1, 0, 1); PG8_STAGE(PG8_SB(0, 0), b2, voffB);
;             PG8_BAR; PG8_WAIT_L(0); PG8_MMA(0, 1, At, B1); PG8_BAR;
;             PG8_LDA(At, 0, 1); PG8_STAGE(PG8_SA(0, 0), a2, voffA);
;             PG8_BAR; PG8_WAIT_L(0); PG8_MMA(1, 0, At, B0); PG8_BAR; PG8_SCHED;
;             PG8_STAGE(PG8_SB(0, 1), b2 + hstep, voffB);
;             PG8_WAIT_V(6); PG8_BAR; PG8_MMA(1, 1, At, B1); PG8_BAR;
;             PG8_LDB(B0, 1, 0); PG8_SCHED; PG8_LDA(At, 1, 0); PG8_STAGE(PG8_SA(0, 1), a2 + hstep, voffA);
;             PG8_WAIT_L(8); PG8_BAR; PG8_WAIT_L(0); PG8_MMA(0, 0, At, B0); PG8_BAR; PG8_SCHED;
;             PG8_LDB(B1, 1, 1); PG8_STAGE(PG8_SB(1, 0), b3, voffB);
;             PG8_BAR; PG8_WAIT_L(0); PG8_MMA(0, 1, At, B1); PG8_BAR;
;             PG8_LDA(At, 1, 1); PG8_STAGE(PG8_SA(1, 0), a3, voffA);
;             PG8_BAR; PG8_WAIT_L(0); PG8_MMA(1, 0, At, B0); PG8_BAR; PG8_SCHED;
;             PG8_STAGE(PG8_SB(1, 1), b3 + hstep, voffB);
;             PG8_WAIT_V(6); PG8_BAR; PG8_MMA(1, 1, At, B1); PG8_BAR;
	s_waitcnt lgkmcnt(0)
	v_mfma_f32_16x16x32_bf16 v[124:127], v[128:131], v[162:165], v[124:127]
	v_mfma_f32_16x16x32_bf16 v[120:123], v[136:139], v[162:165], v[120:123]
	v_mfma_f32_16x16x32_bf16 v[116:119], v[128:131], v[176:179], v[116:119]
	v_mfma_f32_16x16x32_bf16 v[112:115], v[136:139], v[176:179], v[112:115]
	v_mfma_f32_16x16x32_bf16 v[108:111], v[128:131], v[184:187], v[108:111]
	v_mfma_f32_16x16x32_bf16 v[100:103], v[136:139], v[184:187], v[100:103]
	v_mfma_f32_16x16x32_bf16 v[76:79], v[128:131], v[192:195], v[76:79]
	v_mfma_f32_16x16x32_bf16 v[72:75], v[136:139], v[192:195], v[72:75]
	v_mfma_f32_16x16x32_bf16 v[124:127], v[132:135], v[172:175], v[124:127]
	v_mfma_f32_16x16x32_bf16 v[120:123], v[140:143], v[172:175], v[120:123]
	v_mfma_f32_16x16x32_bf16 v[116:119], v[132:135], v[180:183], v[116:119]
	v_mfma_f32_16x16x32_bf16 v[112:115], v[140:143], v[180:183], v[112:115]
	v_mfma_f32_16x16x32_bf16 v[108:111], v[132:135], v[188:191], v[108:111]
	v_mfma_f32_16x16x32_bf16 v[100:103], v[140:143], v[188:191], v[100:103]
	v_mfma_f32_16x16x32_bf16 v[76:79], v[132:135], v[196:199], v[76:79]
	v_mfma_f32_16x16x32_bf16 v[72:75], v[140:143], v[196:199], v[72:75]
	s_barrier
	s_setprio 0
	s_add_i32 s18, 0, 0x1c000
	s_add_i32 s19, s44, s24
	v_add_u32_e32 v160, s18, v167
	s_add_u32 s0, s16, 0x80
	s_addc_u32 s1, s17, 0
	s_mov_b32 m0, s19
	ds_read_b128 v[202:205], v160
	ds_read_b128 v[206:209], v160 offset:1024
	ds_read_b128 v[210:213], v160 offset:2048
	ds_read_b128 v[214:217], v160 offset:3072
	global_load_lds_dwordx4 v146, s[0:1]
	s_add_i32 m0, s19, 0x2000
	s_nop 0
	global_load_lds_dwordx4 v150, s[0:1]
	s_waitcnt vmcnt(8)
	s_setprio 1
	s_barrier
	s_waitcnt lgkmcnt(0)
	v_mfma_f32_16x16x32_bf16 v[104:107], v[202:205], v[162:165], v[104:107]
	v_mfma_f32_16x16x32_bf16 v[96:99], v[210:213], v[162:165], v[96:99]
	v_mfma_f32_16x16x32_bf16 v[92:95], v[202:205], v[176:179], v[92:95]
	v_mfma_f32_16x16x32_bf16 v[88:91], v[210:213], v[176:179], v[88:91]
	v_mfma_f32_16x16x32_bf16 v[84:87], v[202:205], v[184:187], v[84:87]
	v_mfma_f32_16x16x32_bf16 v[80:83], v[210:213], v[184:187], v[80:83]
	v_mfma_f32_16x16x32_bf16 v[68:71], v[202:205], v[192:195], v[68:71]
	v_mfma_f32_16x16x32_bf16 v[64:67], v[210:213], v[192:195], v[64:67]
	v_mfma_f32_16x16x32_bf16 v[104:107], v[206:209], v[172:175], v[104:107]
	v_mfma_f32_16x16x32_bf16 v[96:99], v[214:217], v[172:175], v[96:99]
	v_mfma_f32_16x16x32_bf16 v[92:95], v[206:209], v[180:183], v[92:95]
	v_mfma_f32_16x16x32_bf16 v[88:91], v[214:217], v[180:183], v[88:91]
	v_mfma_f32_16x16x32_bf16 v[84:87], v[206:209], v[188:191], v[84:87]
	v_mfma_f32_16x16x32_bf16 v[80:83], v[214:217], v[188:191], v[80:83]
	v_mfma_f32_16x16x32_bf16 v[68:71], v[206:209], v[196:199], v[68:71]
	v_mfma_f32_16x16x32_bf16 v[64:67], v[214:217], v[196:199], v[64:67]
	s_barrier
	s_setprio 0
	s_mov_b32 m0, s31
	s_mov_b64 s[0:1], 0x80
	v_lshl_add_u64 v[218:219], v[222:223], 0, s[0:1]
	ds_read_b128 v[162:165], v169 offset:49152
	ds_read_b128 v[172:175], v169 offset:50176
	ds_read_b128 v[176:179], v169 offset:51200
	ds_read_b128 v[180:183], v169 offset:52224
	ds_read_b128 v[184:187], v169 offset:53248
	ds_read_b128 v[188:191], v169 offset:54272
	ds_read_b128 v[192:195], v169 offset:55296
	ds_read_b128 v[196:199], v169 offset:56320
	global_load_lds_dwordx4 v[218:219], off
	v_lshl_add_u64 v[218:219], v[224:225], 0, s[0:1]
	s_mov_b32 m0, s33
	s_nop 0
	global_load_lds_dwordx4 v[218:219], off
	s_setprio 1
	s_barrier
	s_waitcnt lgkmcnt(0)
	v_mfma_f32_16x16x32_bf16 v[60:63], v[128:131], v[162:165], v[60:63]
	v_mfma_f32_16x16x32_bf16 v[56:59], v[136:139], v[162:165], v[56:59]
	v_mfma_f32_16x16x32_bf16 v[48:51], v[128:131], v[176:179], v[48:51]
	v_mfma_f32_16x16x32_bf16 v[40:43], v[136:139], v[176:179], v[40:43]
	v_mfma_f32_16x16x32_bf16 v[32:35], v[128:131], v[184:187], v[32:35]
	v_mfma_f32_16x16x32_bf16 v[24:27], v[136:139], v[184:187], v[24:27]
	v_mfma_f32_16x16x32_bf16 v[16:19], v[128:131], v[192:195], v[16:19]
	v_mfma_f32_16x16x32_bf16 v[8:11], v[136:139], v[192:195], v[8:11]
	v_mfma_f32_16x16x32_bf16 v[60:63], v[132:135], v[172:175], v[60:63]
	v_mfma_f32_16x16x32_bf16 v[56:59], v[140:143], v[172:175], v[56:59]
	v_mfma_f32_16x16x32_bf16 v[48:51], v[132:135], v[180:183], v[48:51]
	v_mfma_f32_16x16x32_bf16 v[40:43], v[140:143], v[180:183], v[40:43]
	v_mfma_f32_16x16x32_bf16 v[32:35], v[132:135], v[188:191], v[32:35]
	v_mfma_f32_16x16x32_bf16 v[24:27], v[140:143], v[188:191], v[24:27]
	v_mfma_f32_16x16x32_bf16 v[16:19], v[132:135], v[196:199], v[16:19]
	v_mfma_f32_16x16x32_bf16 v[8:11], v[140:143], v[196:199], v[8:11]
	s_barrier
	s_setprio 0
	s_add_u32 s16, s16, 0x80080
	s_addc_u32 s17, s17, 0
	s_add_i32 s18, s18, s24
	s_mov_b32 m0, s18
	s_nop 0
	global_load_lds_dwordx4 v146, s[16:17]
	s_add_i32 m0, s18, 0x2000
	s_nop 0
	global_load_lds_dwordx4 v150, s[16:17]
	s_waitcnt vmcnt(8)
	s_setprio 1
	s_barrier
	v_mfma_f32_16x16x32_bf16 v[52:55], v[202:205], v[162:165], v[52:55]
	v_mfma_f32_16x16x32_bf16 v[44:47], v[210:213], v[162:165], v[44:47]
	v_mfma_f32_16x16x32_bf16 v[36:39], v[202:205], v[176:179], v[36:39]
	v_mfma_f32_16x16x32_bf16 v[28:31], v[210:213], v[176:179], v[28:31]
	v_mfma_f32_16x16x32_bf16 v[20:23], v[202:205], v[184:187], v[20:23]
	v_mfma_f32_16x16x32_bf16 v[12:15], v[210:213], v[184:187], v[12:15]
	v_mfma_f32_16x16x32_bf16 v[4:7], v[202:205], v[192:195], v[4:7]
	v_mfma_f32_16x16x32_bf16 v[0:3], v[210:213], v[192:195], v[0:3]
	v_mfma_f32_16x16x32_bf16 v[52:55], v[206:209], v[172:175], v[52:55]
	v_mfma_f32_16x16x32_bf16 v[44:47], v[214:217], v[172:175], v[44:47]
	v_mfma_f32_16x16x32_bf16 v[36:39], v[206:209], v[180:183], v[36:39]
	v_mfma_f32_16x16x32_bf16 v[28:31], v[214:217], v[180:183], v[28:31]
	v_mfma_f32_16x16x32_bf16 v[20:23], v[206:209], v[188:191], v[20:23]
	v_mfma_f32_16x16x32_bf16 v[12:15], v[214:217], v[188:191], v[12:15]
	v_mfma_f32_16x16x32_bf16 v[4:7], v[206:209], v[196:199], v[4:7]
	v_mfma_f32_16x16x32_bf16 v[0:3], v[214:217], v[196:199], v[0:3]
	s_barrier
; __device__ __forceinline__ unsigned cvt_pk_bf16(float lo, float hi) { unsigned r; asm volatile("v_cvt_pk_bf16_f32 %0, %1, %2" : "=v"(r) : "v"(lo), "v"(hi)); return r; }
;     __device__ __forceinline__ void operator()(const AccT& acc, const Unit& u, int wr, int wc, int fr, int fq) const {
;     ...
;         const int row0 = u.pm * 256 + wr * 64 + fr; const int b = u.pn >> 1, ch0 = (u.pn & 1) * 256 + wc * 32 + 8 * fq;
;         const float sg = (fr & 1) ? -1.0f : 1.0f;
;         f32x4 yh[2][2];
; #pragma unroll
;         for (int bj = 0; bj < 2; ++bj)
; #pragma unroll
;             for (int n = 0; n < 2; ++n) yh[bj][n] = *(const f32x4*)(YCH + b * 512 + ch0 + bj * 128 + 4 * n) * sg;
; #pragma unroll
;         for (int ai = 0; ai < 2; ++ai)
; #pragma unroll
;             for (int m = 0; m < 4; ++m) {
;                 const int k = row0 + ai * 128 + m * 16;
; #pragma unroll
;                 for (int bj = 0; bj < 2; ++bj) {
;                     const f32x4 v0 = acc[ai][bj][m][0] + yh[bj][0], v1 = acc[ai][bj][m][1] + yh[bj][1];
;                     u32x4 w; w.x = cvt_pk_bf16(v0[0], v0[1]); w.y = cvt_pk_bf16(v0[2], v0[3]); w.z = cvt_pk_bf16(v1[0], v1[1]); w.w = cvt_pk_bf16(v1[2], v1[3]);
;                     *(u32x4*)(CAT + (size_t)(b * 2048 + k) * CATW + 1024 + ch0 + bj * 128) = w;
;                 }
	s_setprio 0
	s_add_i32 s43, s43, 2
	s_add_u32 s14, s14, 0x100
	s_addc_u32 s15, s15, 0
	s_add_u32 s41, s41, 0x100
	s_addc_u32 s42, s42, 0
	s_cmp_gt_u32 s43, 29
	s_cbranch_scc0 .LBB0_826
	s_ashr_i32 s5, s38, 1
	s_lshl_b32 s7, s38, 8
	s_lshl_b32 s14, s5, 9
	s_and_b32 s7, s7, 0x100
	s_ashr_i32 s15, s14, 31
	v_mov_b32_e32 v171, v161
	v_mov_b32_e32 v128, v166
	s_or_b32 s7, s7, s30
	s_lshl_b64 s[14:15], s[14:15], 2
	s_add_u32 s14, s48, s14
	v_lshl_add_u32 v164, v128, 3, s7
	s_addc_u32 s15, s49, s15
	v_ashrrev_i32_e32 v165, 31, v164
	v_lshl_add_u64 v[128:129], v[164:165], 2, s[14:15]
	global_load_dwordx4 v[140:143], v[128:129], off
	global_load_dwordx4 v[136:139], v[128:129], off offset:16
	global_load_dwordx4 v[132:135], v[128:129], off offset:512
	s_nop 0
	global_load_dwordx4 v[128:131], v[128:129], off offset:528
	s_lshl_b32 s7, s12, 8
	s_lshl_b32 s5, s5, 11
	s_add_i32 s7, s7, s29
	v_and_b32_e32 v160, 1, v171
	s_add_i32 s7, s7, s5
	v_mov_b64_e32 v[162:163], s[96:97]
	v_cmp_eq_u32_e32 vcc, 0, v160
	v_add_u32_e32 v171, s7, v171
	v_lshlrev_b64 v[164:165], 1, v[164:165]
	v_cndmask_b32_e64 v160, -1.0, 1.0, vcc
	v_mad_i64_i32 v[172:173], s[14:15], v171, s37, v[162:163]
	v_add_u32_e32 v174, 16, v171
	v_lshl_add_u64 v[172:173], v[172:173], 0, v[164:165]
	v_mad_i64_i32 v[174:175], s[14:15], v174, s37, v[162:163]
	v_add_u32_e32 v176, 32, v171
	v_lshl_add_u64 v[174:175], v[174:175], 0, v[164:165]
	v_mad_i64_i32 v[176:177], s[14:15], v176, s37, v[162:163]
	v_lshl_add_u64 v[176:177], v[176:177], 0, v[164:165]
	v_add_u32_e32 v182, 48, v171
	s_and_b64 vcc, exec, s[2:3]
	s_mov_b32 s38, s4
	s_mov_b32 s12, s6
	s_mov_b64 s[16:17], s[10:11]
	s_waitcnt vmcnt(0)
	v_pk_fma_f32 v[126:127], v[142:143], v[160:161], v[126:127] op_sel_hi:[1,0,1]
	v_pk_fma_f32 v[124:125], v[140:141], v[160:161], v[124:125] op_sel_hi:[1,0,1]
	v_pk_fma_f32 v[122:123], v[138:139], v[160:161], v[122:123] op_sel_hi:[1,0,1]
	v_pk_fma_f32 v[180:181], v[128:129], v[160:161], v[80:81] op_sel_hi:[1,0,1]
	v_cvt_pk_bf16_f32 v80, v124, v125
	v_cvt_pk_bf16_f32 v81, v126, v127
	v_pk_fma_f32 v[120:121], v[136:137], v[160:161], v[120:121] op_sel_hi:[1,0,1]
	v_pk_fma_f32 v[106:107], v[134:135], v[160:161], v[106:107] op_sel_hi:[1,0,1]
	v_pk_fma_f32 v[104:105], v[132:133], v[160:161], v[104:105] op_sel_hi:[1,0,1]
	v_pk_fma_f32 v[178:179], v[130:131], v[160:161], v[82:83] op_sel_hi:[1,0,1]
	v_cvt_pk_bf16_f32 v82, v120, v121
	v_cvt_pk_bf16_f32 v83, v122, v123
	global_store_dwordx4 v[172:173], v[80:83], off offset:2048
	v_pk_fma_f32 v[98:99], v[130:131], v[160:161], v[98:99] op_sel_hi:[1,0,1]
	v_pk_fma_f32 v[96:97], v[128:129], v[160:161], v[96:97] op_sel_hi:[1,0,1]
	v_cvt_pk_bf16_f32 v80, v104, v105
	v_cvt_pk_bf16_f32 v81, v106, v107
	v_pk_fma_f32 v[118:119], v[142:143], v[160:161], v[118:119] op_sel_hi:[1,0,1]
	v_pk_fma_f32 v[116:117], v[140:141], v[160:161], v[116:117] op_sel_hi:[1,0,1]
	v_cvt_pk_bf16_f32 v82, v96, v97
	v_cvt_pk_bf16_f32 v83, v98, v99
	global_store_dwordx4 v[172:173], v[80:83], off offset:2304
	v_pk_fma_f32 v[114:115], v[138:139], v[160:161], v[114:115] op_sel_hi:[1,0,1]
	v_pk_fma_f32 v[112:113], v[136:137], v[160:161], v[112:113] op_sel_hi:[1,0,1]
	v_cvt_pk_bf16_f32 v80, v116, v117
	v_cvt_pk_bf16_f32 v81, v118, v119
	v_pk_fma_f32 v[94:95], v[134:135], v[160:161], v[94:95] op_sel_hi:[1,0,1]
	v_pk_fma_f32 v[92:93], v[132:133], v[160:161], v[92:93] op_sel_hi:[1,0,1]
	v_cvt_pk_bf16_f32 v82, v112, v113
	v_cvt_pk_bf16_f32 v83, v114, v115
	global_store_dwordx4 v[174:175], v[80:83], off offset:2048
	v_pk_fma_f32 v[90:91], v[130:131], v[160:161], v[90:91] op_sel_hi:[1,0,1]
	v_pk_fma_f32 v[88:89], v[128:129], v[160:161], v[88:89] op_sel_hi:[1,0,1]
	v_cvt_pk_bf16_f32 v80, v92, v93
	v_cvt_pk_bf16_f32 v81, v94, v95
	v_pk_fma_f32 v[110:111], v[142:143], v[160:161], v[110:111] op_sel_hi:[1,0,1]
	v_pk_fma_f32 v[108:109], v[140:141], v[160:161], v[108:109] op_sel_hi:[1,0,1]
	v_cvt_pk_bf16_f32 v82, v88, v89
	v_cvt_pk_bf16_f32 v83, v90, v91
	global_store_dwordx4 v[174:175], v[80:83], off offset:2304
	v_pk_fma_f32 v[102:103], v[138:139], v[160:161], v[102:103] op_sel_hi:[1,0,1]
	v_pk_fma_f32 v[100:101], v[136:137], v[160:161], v[100:101] op_sel_hi:[1,0,1]
	v_cvt_pk_bf16_f32 v80, v108, v109
	v_cvt_pk_bf16_f32 v81, v110, v111
	v_pk_fma_f32 v[86:87], v[134:135], v[160:161], v[86:87] op_sel_hi:[1,0,1]
	v_pk_fma_f32 v[84:85], v[132:133], v[160:161], v[84:85] op_sel_hi:[1,0,1]
	v_cvt_pk_bf16_f32 v82, v100, v101
	v_cvt_pk_bf16_f32 v83, v102, v103
	global_store_dwordx4 v[176:177], v[80:83], off offset:2048
	v_pk_fma_f32 v[76:77], v[140:141], v[160:161], v[76:77] op_sel_hi:[1,0,1]
	v_pk_fma_f32 v[78:79], v[142:143], v[160:161], v[78:79] op_sel_hi:[1,0,1]
	v_cvt_pk_bf16_f32 v80, v84, v85
	v_cvt_pk_bf16_f32 v81, v86, v87
	v_cvt_pk_bf16_f32 v82, v180, v181
	v_cvt_pk_bf16_f32 v83, v178, v179
	global_store_dwordx4 v[176:177], v[80:83], off offset:2304
	v_pk_fma_f32 v[70:71], v[134:135], v[160:161], v[70:71] op_sel_hi:[1,0,1]
	v_pk_fma_f32 v[68:69], v[132:133], v[160:161], v[68:69] op_sel_hi:[1,0,1]
	v_pk_fma_f32 v[80:81], v[138:139], v[160:161], v[74:75] op_sel_hi:[1,0,1]
	v_pk_fma_f32 v[74:75], v[136:137], v[160:161], v[72:73] op_sel_hi:[1,0,1]
	v_cvt_pk_bf16_f32 v72, v76, v77
; __device__ __forceinline__ unsigned cvt_pk_bf16(float lo, float hi) { unsigned r; asm volatile("v_cvt_pk_bf16_f32 %0, %1, %2" : "=v"(r) : "v"(lo), "v"(hi)); return r; }
; #define PG8_WAIT_V(n) asm volatile("s_waitcnt vmcnt(" #n ")" ::: "memory")
; #define PG8_BAR __builtin_amdgcn_s_barrier()
; template <class Epi, class Sched>
; __device__ __forceinline__ void gemm_phase(LAS unsigned char* lds, const Gemm g, const Sched& S, const Epi& E) {
;     ...
;     PG8_WAIT_V(0);
;     if (wr == 0) PG8_BAR;
;     PG8_BAR;
;     __device__ __forceinline__ void operator()(const AccT& acc, const Unit& u, int wr, int wc, int fr, int fq) const {
;     ...
;         for (int ai = 0; ai < 2; ++ai)
; #pragma unroll
;             for (int m = 0; m < 4; ++m) {
;                 const int k = row0 + ai * 128 + m * 16;
; #pragma unroll
;                 for (int bj = 0; bj < 2; ++bj) {
;                     const f32x4 v0 = acc[ai][bj][m][0] + yh[bj][0], v1 = acc[ai][bj][m][1] + yh[bj][1];
;                     u32x4 w; w.x = cvt_pk_bf16(v0[0], v0[1]); w.y = cvt_pk_bf16(v0[2], v0[3]); w.z = cvt_pk_bf16(v1[0], v1[1]); w.w = cvt_pk_bf16(v1[2], v1[3]);
;                     *(u32x4*)(CAT + (size_t)(b * 2048 + k) * CATW + 1024 + ch0 + bj * 128) = w;
;                 }
	v_mad_i64_i32 v[76:77], s[14:15], v182, s37, v[162:163]
	v_cvt_pk_bf16_f32 v73, v78, v79
	v_lshl_add_u64 v[76:77], v[76:77], 0, v[164:165]
	v_cvt_pk_bf16_f32 v74, v74, v75
	v_cvt_pk_bf16_f32 v75, v80, v81
	global_store_dwordx4 v[76:77], v[72:75], off offset:2048
	v_pk_fma_f32 v[60:61], v[140:141], v[160:161], v[60:61] op_sel_hi:[1,0,1]
	v_pk_fma_f32 v[62:63], v[142:143], v[160:161], v[62:63] op_sel_hi:[1,0,1]
	v_pk_fma_f32 v[72:73], v[130:131], v[160:161], v[66:67] op_sel_hi:[1,0,1]
	v_pk_fma_f32 v[66:67], v[128:129], v[160:161], v[64:65] op_sel_hi:[1,0,1]
	v_cvt_pk_bf16_f32 v64, v68, v69
	v_cvt_pk_bf16_f32 v65, v70, v71
	v_pk_fma_f32 v[54:55], v[134:135], v[160:161], v[54:55] op_sel_hi:[1,0,1]
	v_cvt_pk_bf16_f32 v66, v66, v67
	v_cvt_pk_bf16_f32 v67, v72, v73
	global_store_dwordx4 v[76:77], v[64:67], off offset:2304
	v_pk_fma_f32 v[52:53], v[132:133], v[160:161], v[52:53] op_sel_hi:[1,0,1]
	v_pk_fma_f32 v[38:39], v[134:135], v[160:161], v[38:39] op_sel_hi:[1,0,1]
	v_add_u32_e32 v66, 0x80, v171
	v_pk_fma_f32 v[64:65], v[138:139], v[160:161], v[58:59] op_sel_hi:[1,0,1]
	v_pk_fma_f32 v[58:59], v[136:137], v[160:161], v[56:57] op_sel_hi:[1,0,1]
	v_cvt_pk_bf16_f32 v56, v60, v61
	v_mad_i64_i32 v[60:61], s[14:15], v66, s37, v[162:163]
	v_cvt_pk_bf16_f32 v57, v62, v63
	v_lshl_add_u64 v[60:61], v[60:61], 0, v[164:165]
	v_cvt_pk_bf16_f32 v58, v58, v59
	v_cvt_pk_bf16_f32 v59, v64, v65
	global_store_dwordx4 v[60:61], v[56:59], off offset:2048
	v_pk_fma_f32 v[36:37], v[132:133], v[160:161], v[36:37] op_sel_hi:[1,0,1]
	v_pk_fma_f32 v[22:23], v[134:135], v[160:161], v[22:23] op_sel_hi:[1,0,1]
	v_pk_fma_f32 v[56:57], v[130:131], v[160:161], v[46:47] op_sel_hi:[1,0,1]
	v_pk_fma_f32 v[46:47], v[128:129], v[160:161], v[44:45] op_sel_hi:[1,0,1]
	v_cvt_pk_bf16_f32 v44, v52, v53
	v_cvt_pk_bf16_f32 v45, v54, v55
	v_add_u32_e32 v52, 0x90, v171
	v_cvt_pk_bf16_f32 v46, v46, v47
	v_cvt_pk_bf16_f32 v47, v56, v57
	global_store_dwordx4 v[60:61], v[44:47], off offset:2304
	v_pk_fma_f32 v[20:21], v[132:133], v[160:161], v[20:21] op_sel_hi:[1,0,1]
	v_pk_fma_f32 v[6:7], v[134:135], v[160:161], v[6:7] op_sel_hi:[1,0,1]
	v_pk_fma_f32 v[44:45], v[142:143], v[160:161], v[50:51] op_sel_hi:[1,0,1]
	v_pk_fma_f32 v[46:47], v[140:141], v[160:161], v[48:49] op_sel_hi:[1,0,1]
	v_pk_fma_f32 v[48:49], v[138:139], v[160:161], v[42:43] op_sel_hi:[1,0,1]
	v_pk_fma_f32 v[42:43], v[136:137], v[160:161], v[40:41] op_sel_hi:[1,0,1]
	v_cvt_pk_bf16_f32 v40, v46, v47
	v_cvt_pk_bf16_f32 v41, v44, v45
	v_mad_i64_i32 v[44:45], s[14:15], v52, s37, v[162:163]
	v_lshl_add_u64 v[44:45], v[44:45], 0, v[164:165]
	v_cvt_pk_bf16_f32 v42, v42, v43
	v_cvt_pk_bf16_f32 v43, v48, v49
	global_store_dwordx4 v[44:45], v[40:43], off offset:2048
	v_pk_fma_f32 v[4:5], v[132:133], v[160:161], v[4:5] op_sel_hi:[1,0,1]
	s_nop 0
	v_pk_fma_f32 v[40:41], v[130:131], v[160:161], v[30:31] op_sel_hi:[1,0,1]
	v_pk_fma_f32 v[30:31], v[128:129], v[160:161], v[28:29] op_sel_hi:[1,0,1]
	v_cvt_pk_bf16_f32 v28, v36, v37
	v_cvt_pk_bf16_f32 v29, v38, v39
	v_add_u32_e32 v36, 0xa0, v171
	v_cvt_pk_bf16_f32 v30, v30, v31
	v_cvt_pk_bf16_f32 v31, v40, v41
	global_store_dwordx4 v[44:45], v[28:31], off offset:2304
	s_nop 1
	v_pk_fma_f32 v[28:29], v[142:143], v[160:161], v[34:35] op_sel_hi:[1,0,1]
	v_pk_fma_f32 v[30:31], v[140:141], v[160:161], v[32:33] op_sel_hi:[1,0,1]
	v_pk_fma_f32 v[32:33], v[138:139], v[160:161], v[26:27] op_sel_hi:[1,0,1]
	v_pk_fma_f32 v[26:27], v[136:137], v[160:161], v[24:25] op_sel_hi:[1,0,1]
	v_cvt_pk_bf16_f32 v24, v30, v31
	v_cvt_pk_bf16_f32 v25, v28, v29
	v_mad_i64_i32 v[28:29], s[14:15], v36, s37, v[162:163]
	v_lshl_add_u64 v[28:29], v[28:29], 0, v[164:165]
	v_cvt_pk_bf16_f32 v26, v26, v27
	v_cvt_pk_bf16_f32 v27, v32, v33
	global_store_dwordx4 v[28:29], v[24:27], off offset:2048
	s_nop 1
	v_pk_fma_f32 v[24:25], v[130:131], v[160:161], v[14:15] op_sel_hi:[1,0,1]
	v_pk_fma_f32 v[14:15], v[128:129], v[160:161], v[12:13] op_sel_hi:[1,0,1]
	v_cvt_pk_bf16_f32 v12, v20, v21
	v_cvt_pk_bf16_f32 v13, v22, v23
	v_add_u32_e32 v20, 0xb0, v171
	v_cvt_pk_bf16_f32 v14, v14, v15
	v_cvt_pk_bf16_f32 v15, v24, v25
	global_store_dwordx4 v[28:29], v[12:15], off offset:2304
	s_nop 1
	v_pk_fma_f32 v[12:13], v[142:143], v[160:161], v[18:19] op_sel_hi:[1,0,1]
	v_pk_fma_f32 v[14:15], v[140:141], v[160:161], v[16:17] op_sel_hi:[1,0,1]
	v_pk_fma_f32 v[16:17], v[138:139], v[160:161], v[10:11] op_sel_hi:[1,0,1]
	v_pk_fma_f32 v[10:11], v[136:137], v[160:161], v[8:9] op_sel_hi:[1,0,1]
	v_cvt_pk_bf16_f32 v8, v14, v15
	v_cvt_pk_bf16_f32 v9, v12, v13
	v_mad_i64_i32 v[12:13], s[14:15], v20, s37, v[162:163]
	v_lshl_add_u64 v[12:13], v[12:13], 0, v[164:165]
	v_cvt_pk_bf16_f32 v10, v10, v11
	v_cvt_pk_bf16_f32 v11, v16, v17
	global_store_dwordx4 v[12:13], v[8:11], off offset:2048
	s_mov_b64 s[14:15], s[8:9]
	s_nop 0
	v_pk_fma_f32 v[8:9], v[130:131], v[160:161], v[2:3] op_sel_hi:[1,0,1]
	v_pk_fma_f32 v[2:3], v[128:129], v[160:161], v[0:1] op_sel_hi:[1,0,1]
	v_cvt_pk_bf16_f32 v0, v4, v5
	v_cvt_pk_bf16_f32 v1, v6, v7
	s_nop 0
	v_cvt_pk_bf16_f32 v2, v2, v3
	v_cvt_pk_bf16_f32 v3, v8, v9
	global_store_dwordx4 v[12:13], v[0:3], off offset:2304
	s_cbranch_vccz .LBB0_819
	s_waitcnt vmcnt(0)
	s_cmpk_gt_u32 s20, 0xff
	s_cbranch_scc1 .LBB0_830
	s_barrier

; #define PG8_STAGE(bufoff, gbase, voff) do { _Pragma("unroll") for (int _i = 0; _i < 2; ++_i) \
;         __builtin_amdgcn_global_load_lds((const unsigned*)((const char*)(gbase) + (voff)[_i]), (LAS unsigned*)(lds + (bufoff) + ldsw + _i * 8192), 16, 0, 0); } while (0)
; #define PG8_WAIT_V(n) asm volatile("s_waitcnt vmcnt(" #n ")" ::: "memory")
; #define PG8_WAIT_L(n) asm volatile("s_waitcnt lgkmcnt(" #n ")" ::: "memory")
; template <class Epi, class Sched>
; __device__ __forceinline__ void gemm_phase(LAS unsigned char* lds, const Gemm g, const Sched& S, const Epi& E) {
;     ...
;         const bool has_next = S.next(ui + 1, nxt);
;         const char* nA = has_next ? (const char*)g.A + (size_t)nxt.pm * tstep : cA; const char* nB = has_next ? (const char*)g.Bt + (size_t)nxt.pn * tstep : cB;
;         for (int t = 0; t < nt; t += 2) {
;             const bool last = (t == nt - 2);
;             const char* a1 = cA + (size_t)(t + 1) * kstep;
;             const char* a2 = last ? nA : cA + (size_t)(t + 2) * kstep; const char* b2 = last ? nB : cB + (size_t)(t + 2) * kstep;
;             const char* a3 = a2 + kstep; const char* b3 = b2 + kstep;
;             PG8_LDB(B0, 0, 0); PG8_SCHED; PG8_LDA(At, 0, 0); PG8_STAGE(PG8_SA(1, 1), a1 + hstep, voffA);
;             PG8_WAIT_L(8); PG8_BAR; PG8_WAIT_L(0); PG8_MMA(0, 0, At, B0); PG8_BAR; PG8_SCHED;
;             PG8_LDB(B1, 0, 1); PG8_STAGE(PG8_SB(0, 0), b2, voffB);
;             PG8_BAR; PG8_WAIT_L(0); PG8_MMA(0, 1, At, B1); PG8_BAR;
;             PG8_LDA(At, 0, 1); PG8_STAGE(PG8_SA(0, 0), a2, voffA);
;             PG8_BAR; PG8_WAIT_L(0); PG8_MMA(1, 0, At, B0); PG8_BAR; PG8_SCHED;
;             PG8_STAGE(PG8_SB(0, 1), b2 + hstep, voffB);
;             PG8_WAIT_V(6); PG8_BAR; PG8_MMA(1, 1, At, B1); PG8_BAR;
;             PG8_LDB(B0, 1, 0); PG8_SCHED; PG8_LDA(At, 1, 0); PG8_STAGE(PG8_SA(0, 1), a2 + hstep, voffA);
;             PG8_WAIT_L(8); PG8_BAR; PG8_WAIT_L(0); PG8_MMA(0, 0, At, B0); PG8_BAR; PG8_SCHED;
;             PG8_LDB(B1, 1, 1); PG8_STAGE(PG8_SB(1, 0), b3, voffB);
;             PG8_BAR; PG8_WAIT_L(0); PG8_MMA(0, 1, At, B1); PG8_BAR;
;             PG8_LDA(At, 1, 1); PG8_STAGE(PG8_SA(1, 0), a3, voffA);
;             PG8_BAR; PG8_WAIT_L(0); PG8_MMA(1, 0, At, B0); PG8_BAR; PG8_SCHED;
;             PG8_STAGE(PG8_SB(1, 1), b3 + hstep, voffB);
;             PG8_WAIT_V(6); PG8_BAR; PG8_MMA(1, 1, At, B1); PG8_BAR;
.LBB0_901:
	s_add_u32 s56, s26, 0x100
	s_addc_u32 s57, s27, 0
	s_mov_b32 s58, -2
	s_waitcnt vmcnt(0)
	ds_read_b128 v[128:131], v237
	ds_read_b128 v[132:135], v237 offset:1024
	ds_read_b128 v[136:139], v237 offset:2048
	ds_read_b128 v[140:143], v237 offset:3072
	s_add_u32 s26, s24, 0x100
	s_addc_u32 s27, s25, 0
	s_cmp_eq_u32 s58, 20
	s_cselect_b32 s31, s5, s27
	s_cselect_b32 s30, s4, s26
	s_cselect_b32 s29, s7, s57
	s_cselect_b32 s28, s6, s56
	v_lshl_add_u64 v[176:177], s[24:25], 0, v[210:211]
	s_add_i32 m0, s38, 0xc000
	ds_read_b128 v[144:147], v238
	ds_read_b128 v[148:151], v238 offset:1024
	ds_read_b128 v[152:155], v238 offset:2048
	ds_read_b128 v[156:159], v238 offset:3072
	ds_read_b128 v[160:163], v238 offset:4096
	ds_read_b128 v[164:167], v238 offset:5120
	ds_read_b128 v[168:171], v238 offset:6144
	ds_read_b128 v[172:175], v238 offset:7168
	global_load_lds_dwordx4 v[176:177], off
	v_lshl_add_u64 v[176:177], s[24:25], 0, v[212:213]
	s_add_i32 m0, s38, 0xe000
	s_nop 0
	global_load_lds_dwordx4 v[176:177], off
	s_waitcnt lgkmcnt(8)
	s_waitcnt vmcnt(8)
	s_setprio 1
	s_barrier
	s_waitcnt lgkmcnt(0)
	v_mfma_f32_16x16x32_bf16 v[124:127], v[128:131], v[144:147], 0
	v_mfma_f32_16x16x32_bf16 v[120:123], v[136:139], v[144:147], 0
	v_mfma_f32_16x16x32_bf16 v[108:111], v[128:131], v[152:155], 0
	v_mfma_f32_16x16x32_bf16 v[104:107], v[136:139], v[152:155], 0
	v_mfma_f32_16x16x32_bf16 v[92:95], v[128:131], v[160:163], 0
	v_mfma_f32_16x16x32_bf16 v[88:91], v[136:139], v[160:163], 0
	v_mfma_f32_16x16x32_bf16 v[76:79], v[128:131], v[168:171], 0
	v_mfma_f32_16x16x32_bf16 v[72:75], v[136:139], v[168:171], 0
	v_mfma_f32_16x16x32_bf16 v[124:127], v[132:135], v[148:151], v[124:127]
	v_mfma_f32_16x16x32_bf16 v[120:123], v[140:143], v[148:151], v[120:123]
	v_mfma_f32_16x16x32_bf16 v[108:111], v[132:135], v[156:159], v[108:111]
	v_mfma_f32_16x16x32_bf16 v[104:107], v[140:143], v[156:159], v[104:107]
	v_mfma_f32_16x16x32_bf16 v[92:95], v[132:135], v[164:167], v[92:95]
	v_mfma_f32_16x16x32_bf16 v[88:91], v[140:143], v[164:167], v[88:91]
	v_mfma_f32_16x16x32_bf16 v[76:79], v[132:135], v[172:175], v[76:79]
	v_mfma_f32_16x16x32_bf16 v[72:75], v[140:143], v[172:175], v[72:75]
	s_barrier
	s_setprio 0
	s_add_i32 s24, s50, s37
	s_mov_b32 m0, s24
	ds_read_b128 v[176:179], v239
	ds_read_b128 v[180:183], v239 offset:1024
	ds_read_b128 v[184:187], v239 offset:2048
	ds_read_b128 v[188:191], v239 offset:3072
	global_load_lds_dwordx4 v204, s[28:29]
	s_add_i32 m0, s24, 0x2000
	s_nop 0
	global_load_lds_dwordx4 v208, s[28:29]
	s_waitcnt vmcnt(8)
	s_setprio 1
	s_barrier
	s_waitcnt lgkmcnt(0)
	v_mfma_f32_16x16x32_bf16 v[116:119], v[176:179], v[144:147], 0
	v_mfma_f32_16x16x32_bf16 v[112:115], v[184:187], v[144:147], 0
	v_mfma_f32_16x16x32_bf16 v[100:103], v[176:179], v[152:155], 0
	v_mfma_f32_16x16x32_bf16 v[96:99], v[184:187], v[152:155], 0
	v_mfma_f32_16x16x32_bf16 v[84:87], v[176:179], v[160:163], 0
	v_mfma_f32_16x16x32_bf16 v[80:83], v[184:187], v[160:163], 0
	v_mfma_f32_16x16x32_bf16 v[68:71], v[176:179], v[168:171], 0
	v_mfma_f32_16x16x32_bf16 v[64:67], v[184:187], v[168:171], 0
	v_mfma_f32_16x16x32_bf16 v[116:119], v[180:183], v[148:151], v[116:119]
	v_mfma_f32_16x16x32_bf16 v[112:115], v[188:191], v[148:151], v[112:115]
	v_mfma_f32_16x16x32_bf16 v[100:103], v[180:183], v[156:159], v[100:103]
	v_mfma_f32_16x16x32_bf16 v[96:99], v[188:191], v[156:159], v[96:99]
	v_mfma_f32_16x16x32_bf16 v[84:87], v[180:183], v[164:167], v[84:87]
	v_mfma_f32_16x16x32_bf16 v[80:83], v[188:191], v[164:167], v[80:83]
	v_mfma_f32_16x16x32_bf16 v[68:71], v[180:183], v[172:175], v[68:71]
	v_mfma_f32_16x16x32_bf16 v[64:67], v[188:191], v[172:175], v[64:67]
	s_barrier
	s_setprio 0
	s_mov_b32 m0, s38
	v_lshl_add_u64 v[196:197], s[30:31], 0, v[202:203]
	ds_read_b128 v[144:147], v238 offset:16384
	ds_read_b128 v[148:151], v238 offset:17408
	ds_read_b128 v[152:155], v238 offset:18432
	ds_read_b128 v[156:159], v238 offset:19456
	ds_read_b128 v[160:163], v238 offset:20480
	ds_read_b128 v[164:167], v238 offset:21504
	ds_read_b128 v[168:171], v238 offset:22528
	ds_read_b128 v[172:175], v238 offset:23552
	global_load_lds_dwordx4 v202, s[30:31]
	v_lshl_add_u64 v[198:199], s[30:31], 0, v[206:207]
	s_mov_b32 m0, s39
	s_nop 0
	global_load_lds_dwordx4 v206, s[30:31]
	s_setprio 1
	s_barrier
	s_waitcnt lgkmcnt(0)
	v_mfma_f32_16x16x32_bf16 v[60:63], v[128:131], v[144:147], 0
	v_mfma_f32_16x16x32_bf16 v[56:59], v[136:139], v[144:147], 0
	v_mfma_f32_16x16x32_bf16 v[44:47], v[128:131], v[152:155], 0
	v_mfma_f32_16x16x32_bf16 v[40:43], v[136:139], v[152:155], 0
	v_mfma_f32_16x16x32_bf16 v[28:31], v[128:131], v[160:163], 0
	v_mfma_f32_16x16x32_bf16 v[24:27], v[136:139], v[160:163], 0
	v_mfma_f32_16x16x32_bf16 v[12:15], v[128:131], v[168:171], 0
	v_mfma_f32_16x16x32_bf16 v[8:11], v[136:139], v[168:171], 0
	v_mfma_f32_16x16x32_bf16 v[60:63], v[132:135], v[148:151], v[60:63]
	v_mfma_f32_16x16x32_bf16 v[56:59], v[140:143], v[148:151], v[56:59]
	v_mfma_f32_16x16x32_bf16 v[44:47], v[132:135], v[156:159], v[44:47]
	v_mfma_f32_16x16x32_bf16 v[40:43], v[140:143], v[156:159], v[40:43]
	v_mfma_f32_16x16x32_bf16 v[28:31], v[132:135], v[164:167], v[28:31]
	v_mfma_f32_16x16x32_bf16 v[24:27], v[140:143], v[164:167], v[24:27]
	v_mfma_f32_16x16x32_bf16 v[12:15], v[132:135], v[172:175], v[12:15]
	v_mfma_f32_16x16x32_bf16 v[8:11], v[140:143], v[172:175], v[8:11]
	s_barrier
	s_setprio 0
	s_add_u32 s24, s28, 0x60000
	s_addc_u32 s25, s29, 0
	s_add_i32 s59, s51, s37
	s_mov_b32 m0, s59
	s_nop 0
	global_load_lds_dwordx4 v204, s[24:25]
	s_add_i32 m0, s59, 0x2000
	s_nop 0
	global_load_lds_dwordx4 v208, s[24:25]
	s_add_u32 s24, s30, 0x60000
	s_addc_u32 s25, s31, 0
	s_mov_b32 m0, s40
	s_nop 0
	global_load_lds_dwordx4 v202, s[24:25]
	s_mov_b32 m0, s41
	s_nop 0
	global_load_lds_dwordx4 v206, s[24:25]
	s_waitcnt vmcnt(10)
	s_setprio 1
	s_barrier
; #define PG8_STAGE(bufoff, gbase, voff) do { _Pragma("unroll") for (int _i = 0; _i < 2; ++_i) \
;         __builtin_amdgcn_global_load_lds((const unsigned*)((const char*)(gbase) + (voff)[_i]), (LAS unsigned*)(lds + (bufoff) + ldsw + _i * 8192), 16, 0, 0); } while (0)
; #define PG8_LDA(dst, b, h) do { _Pragma("unroll") for (int m = 0; m < 4; ++m) _Pragma("unroll") for (int k = 0; k < 2; ++k) dst[m][k] = *(const LAS bf16x8*)(lds + PG8_SA(b, h) + aoff + m * 2048 + k * 1024); } while (0)
; #define PG8_WAIT_V(n) asm volatile("s_waitcnt vmcnt(" #n ")" ::: "memory")
; #define PG8_WAIT_L(n) asm volatile("s_waitcnt lgkmcnt(" #n ")" ::: "memory")
; template <class Epi, class Sched>
; __device__ __forceinline__ void gemm_phase(LAS unsigned char* lds, const Gemm g, const Sched& S, const Epi& E) {
;     ...
;         for (int t = 0; t < nt; t += 2) {
;             const bool last = (t == nt - 2);
;             const char* a1 = cA + (size_t)(t + 1) * kstep;
;             const char* a2 = last ? nA : cA + (size_t)(t + 2) * kstep; const char* b2 = last ? nB : cB + (size_t)(t + 2) * kstep;
;             const char* a3 = a2 + kstep; const char* b3 = b2 + kstep;
;             PG8_LDB(B0, 0, 0); PG8_SCHED; PG8_LDA(At, 0, 0); PG8_STAGE(PG8_SA(1, 1), a1 + hstep, voffA);
;             PG8_WAIT_L(8); PG8_BAR; PG8_WAIT_L(0); PG8_MMA(0, 0, At, B0); PG8_BAR; PG8_SCHED;
;             PG8_LDB(B1, 0, 1); PG8_STAGE(PG8_SB(0, 0), b2, voffB);
;             PG8_BAR; PG8_WAIT_L(0); PG8_MMA(0, 1, At, B1); PG8_BAR;
;             PG8_LDA(At, 0, 1); PG8_STAGE(PG8_SA(0, 0), a2, voffA);
;             PG8_BAR; PG8_WAIT_L(0); PG8_MMA(1, 0, At, B0); PG8_BAR; PG8_SCHED;
;             PG8_STAGE(PG8_SB(0, 1), b2 + hstep, voffB);
;             PG8_WAIT_V(6); PG8_BAR; PG8_MMA(1, 1, At, B1); PG8_BAR;
;             PG8_LDB(B0, 1, 0); PG8_SCHED; PG8_LDA(At, 1, 0); PG8_STAGE(PG8_SA(0, 1), a2 + hstep, voffA);
;             PG8_WAIT_L(8); PG8_BAR; PG8_WAIT_L(0); PG8_MMA(0, 0, At, B0); PG8_BAR; PG8_SCHED;
;             PG8_LDB(B1, 1, 1); PG8_STAGE(PG8_SB(1, 0), b3, voffB);
;             PG8_BAR; PG8_WAIT_L(0); PG8_MMA(0, 1, At, B1); PG8_BAR;
;             PG8_LDA(At, 1, 1); PG8_STAGE(PG8_SA(1, 0), a3, voffA);
;             PG8_BAR; PG8_WAIT_L(0); PG8_MMA(1, 0, At, B0); PG8_BAR; PG8_SCHED;
;             PG8_STAGE(PG8_SB(1, 1), b3 + hstep, voffB);
;             PG8_WAIT_V(6); PG8_BAR; PG8_MMA(1, 1, At, B1); PG8_BAR;
	v_mfma_f32_16x16x32_bf16 v[52:55], v[176:179], v[144:147], 0
	v_mfma_f32_16x16x32_bf16 v[48:51], v[184:187], v[144:147], 0
	v_mfma_f32_16x16x32_bf16 v[36:39], v[176:179], v[152:155], 0
	v_mfma_f32_16x16x32_bf16 v[32:35], v[184:187], v[152:155], 0
	v_mfma_f32_16x16x32_bf16 v[20:23], v[176:179], v[160:163], 0
	v_mfma_f32_16x16x32_bf16 v[16:19], v[184:187], v[160:163], 0
	v_mfma_f32_16x16x32_bf16 v[4:7], v[176:179], v[168:171], 0
	v_mfma_f32_16x16x32_bf16 v[0:3], v[184:187], v[168:171], 0
	v_mfma_f32_16x16x32_bf16 v[52:55], v[180:183], v[148:151], v[52:55]
	v_mfma_f32_16x16x32_bf16 v[48:51], v[188:191], v[148:151], v[48:51]
	v_mfma_f32_16x16x32_bf16 v[36:39], v[180:183], v[156:159], v[36:39]
	v_mfma_f32_16x16x32_bf16 v[32:35], v[188:191], v[156:159], v[32:35]
	v_mfma_f32_16x16x32_bf16 v[20:23], v[180:183], v[164:167], v[20:23]
	v_mfma_f32_16x16x32_bf16 v[16:19], v[188:191], v[164:167], v[16:19]
	v_mfma_f32_16x16x32_bf16 v[4:7], v[180:183], v[172:175], v[4:7]
	v_mfma_f32_16x16x32_bf16 v[0:3], v[188:191], v[172:175], v[0:3]
	s_barrier
	s_setprio 0
	s_add_i32 s59, 0, 0x18000
	v_add_u32_e32 v140, s59, v236
	ds_read_b128 v[128:131], v140
	ds_read_b128 v[132:135], v140 offset:1024
	ds_read_b128 v[136:139], v140 offset:2048
	ds_read_b128 v[140:143], v140 offset:3072
	ds_read_b128 v[144:147], v238 offset:32768
	ds_read_b128 v[148:151], v238 offset:33792
	ds_read_b128 v[152:155], v238 offset:34816
	ds_read_b128 v[156:159], v238 offset:35840
	ds_read_b128 v[160:163], v238 offset:36864
	ds_read_b128 v[164:167], v238 offset:37888
	ds_read_b128 v[168:171], v238 offset:38912
	ds_read_b128 v[172:175], v238 offset:39936
	s_waitcnt lgkmcnt(8)
	s_waitcnt vmcnt(8)
	s_setprio 1
	s_barrier
	s_waitcnt lgkmcnt(0)
	v_mfma_f32_16x16x32_bf16 v[124:127], v[128:131], v[144:147], v[124:127]
	v_mfma_f32_16x16x32_bf16 v[120:123], v[136:139], v[144:147], v[120:123]
	v_mfma_f32_16x16x32_bf16 v[108:111], v[128:131], v[152:155], v[108:111]
	v_mfma_f32_16x16x32_bf16 v[104:107], v[136:139], v[152:155], v[104:107]
	v_mfma_f32_16x16x32_bf16 v[92:95], v[128:131], v[160:163], v[92:95]
	v_mfma_f32_16x16x32_bf16 v[88:91], v[136:139], v[160:163], v[88:91]
	v_mfma_f32_16x16x32_bf16 v[76:79], v[128:131], v[168:171], v[76:79]
	v_mfma_f32_16x16x32_bf16 v[72:75], v[136:139], v[168:171], v[72:75]
	v_mfma_f32_16x16x32_bf16 v[124:127], v[132:135], v[148:151], v[124:127]
	v_mfma_f32_16x16x32_bf16 v[120:123], v[140:143], v[148:151], v[120:123]
	v_mfma_f32_16x16x32_bf16 v[108:111], v[132:135], v[156:159], v[108:111]
	v_mfma_f32_16x16x32_bf16 v[104:107], v[140:143], v[156:159], v[104:107]
	v_mfma_f32_16x16x32_bf16 v[92:95], v[132:135], v[164:167], v[92:95]
	v_mfma_f32_16x16x32_bf16 v[88:91], v[140:143], v[164:167], v[88:91]
	v_mfma_f32_16x16x32_bf16 v[76:79], v[132:135], v[172:175], v[76:79]
	v_mfma_f32_16x16x32_bf16 v[72:75], v[140:143], v[172:175], v[72:75]
	s_barrier
	s_setprio 0
	s_add_i32 s30, 0, 0x1c000
	s_add_i32 s24, s59, s37
	v_add_u32_e32 v188, s30, v236
	s_add_u32 s0, s28, 0x80
	s_addc_u32 s1, s29, 0
	s_mov_b32 m0, s24
	ds_read_b128 v[176:179], v188
	ds_read_b128 v[180:183], v188 offset:1024
	ds_read_b128 v[184:187], v188 offset:2048
	ds_read_b128 v[188:191], v188 offset:3072
	global_load_lds_dwordx4 v204, s[0:1]
	s_add_i32 m0, s24, 0x2000
	s_nop 0
	global_load_lds_dwordx4 v208, s[0:1]
	s_waitcnt vmcnt(8)
	s_setprio 1
	s_barrier
	s_waitcnt lgkmcnt(0)
	v_mfma_f32_16x16x32_bf16 v[116:119], v[176:179], v[144:147], v[116:119]
	v_mfma_f32_16x16x32_bf16 v[112:115], v[184:187], v[144:147], v[112:115]
	v_mfma_f32_16x16x32_bf16 v[100:103], v[176:179], v[152:155], v[100:103]
	v_mfma_f32_16x16x32_bf16 v[96:99], v[184:187], v[152:155], v[96:99]
	v_mfma_f32_16x16x32_bf16 v[84:87], v[176:179], v[160:163], v[84:87]
	v_mfma_f32_16x16x32_bf16 v[80:83], v[184:187], v[160:163], v[80:83]
	v_mfma_f32_16x16x32_bf16 v[68:71], v[176:179], v[168:171], v[68:71]
	v_mfma_f32_16x16x32_bf16 v[64:67], v[184:187], v[168:171], v[64:67]
	v_mfma_f32_16x16x32_bf16 v[116:119], v[180:183], v[148:151], v[116:119]
	v_mfma_f32_16x16x32_bf16 v[112:115], v[188:191], v[148:151], v[112:115]
	v_mfma_f32_16x16x32_bf16 v[100:103], v[180:183], v[156:159], v[100:103]
	v_mfma_f32_16x16x32_bf16 v[96:99], v[188:191], v[156:159], v[96:99]
	v_mfma_f32_16x16x32_bf16 v[84:87], v[180:183], v[164:167], v[84:87]
	v_mfma_f32_16x16x32_bf16 v[80:83], v[188:191], v[164:167], v[80:83]
	v_mfma_f32_16x16x32_bf16 v[68:71], v[180:183], v[172:175], v[68:71]
	v_mfma_f32_16x16x32_bf16 v[64:67], v[188:191], v[172:175], v[64:67]
	s_barrier
	s_setprio 0
	s_mov_b32 m0, s47
	s_mov_b64 s[0:1], 0x80
	v_lshl_add_u64 v[192:193], v[196:197], 0, s[0:1]
	ds_read_b128 v[144:147], v238 offset:49152
	ds_read_b128 v[148:151], v238 offset:50176
	ds_read_b128 v[152:155], v238 offset:51200
	ds_read_b128 v[156:159], v238 offset:52224
	ds_read_b128 v[160:163], v238 offset:53248
	ds_read_b128 v[164:167], v238 offset:54272
	ds_read_b128 v[168:171], v238 offset:55296
	ds_read_b128 v[172:175], v238 offset:56320
	global_load_lds_dwordx4 v[192:193], off
	v_lshl_add_u64 v[192:193], v[198:199], 0, s[0:1]
	s_mov_b32 m0, s48
	s_nop 0
	global_load_lds_dwordx4 v[192:193], off
	s_setprio 1
	s_barrier
; #define PG8_STAGE(bufoff, gbase, voff) do { _Pragma("unroll") for (int _i = 0; _i < 2; ++_i) \
;         __builtin_amdgcn_global_load_lds((const unsigned*)((const char*)(gbase) + (voff)[_i]), (LAS unsigned*)(lds + (bufoff) + ldsw + _i * 8192), 16, 0, 0); } while (0)
; #define PG8_LDA(dst, b, h) do { _Pragma("unroll") for (int m = 0; m < 4; ++m) _Pragma("unroll") for (int k = 0; k < 2; ++k) dst[m][k] = *(const LAS bf16x8*)(lds + PG8_SA(b, h) + aoff + m * 2048 + k * 1024); } while (0)
; #define PG8_WAIT_V(n) asm volatile("s_waitcnt vmcnt(" #n ")" ::: "memory")
; #define PG8_WAIT_L(n) asm volatile("s_waitcnt lgkmcnt(" #n ")" ::: "memory")
; template <class Epi, class Sched>
; __device__ __forceinline__ void gemm_phase(LAS unsigned char* lds, const Gemm g, const Sched& S, const Epi& E) {
;     ...
;         for (int t = 0; t < nt; t += 2) {
;             const bool last = (t == nt - 2);
;             const char* a1 = cA + (size_t)(t + 1) * kstep;
;             const char* a2 = last ? nA : cA + (size_t)(t + 2) * kstep; const char* b2 = last ? nB : cB + (size_t)(t + 2) * kstep;
;             const char* a3 = a2 + kstep; const char* b3 = b2 + kstep;
;             PG8_LDB(B0, 0, 0); PG8_SCHED; PG8_LDA(At, 0, 0); PG8_STAGE(PG8_SA(1, 1), a1 + hstep, voffA);
;             PG8_WAIT_L(8); PG8_BAR; PG8_WAIT_L(0); PG8_MMA(0, 0, At, B0); PG8_BAR; PG8_SCHED;
;             PG8_LDB(B1, 0, 1); PG8_STAGE(PG8_SB(0, 0), b2, voffB);
;             PG8_BAR; PG8_WAIT_L(0); PG8_MMA(0, 1, At, B1); PG8_BAR;
;             PG8_LDA(At, 0, 1); PG8_STAGE(PG8_SA(0, 0), a2, voffA);
;             PG8_BAR; PG8_WAIT_L(0); PG8_MMA(1, 0, At, B0); PG8_BAR; PG8_SCHED;
;             PG8_STAGE(PG8_SB(0, 1), b2 + hstep, voffB);
;             PG8_WAIT_V(6); PG8_BAR; PG8_MMA(1, 1, At, B1); PG8_BAR;
;             PG8_LDB(B0, 1, 0); PG8_SCHED; PG8_LDA(At, 1, 0); PG8_STAGE(PG8_SA(0, 1), a2 + hstep, voffA);
;             PG8_WAIT_L(8); PG8_BAR; PG8_WAIT_L(0); PG8_MMA(0, 0, At, B0); PG8_BAR; PG8_SCHED;
;             PG8_LDB(B1, 1, 1); PG8_STAGE(PG8_SB(1, 0), b3, voffB);
;             PG8_BAR; PG8_WAIT_L(0); PG8_MMA(0, 1, At, B1); PG8_BAR;
;             PG8_LDA(At, 1, 1); PG8_STAGE(PG8_SA(1, 0), a3, voffA);
;             PG8_BAR; PG8_WAIT_L(0); PG8_MMA(1, 0, At, B0); PG8_BAR; PG8_SCHED;
;             PG8_STAGE(PG8_SB(1, 1), b3 + hstep, voffB);
;             PG8_WAIT_V(6); PG8_BAR; PG8_MMA(1, 1, At, B1); PG8_BAR;
	s_waitcnt lgkmcnt(0)
	v_mfma_f32_16x16x32_bf16 v[60:63], v[128:131], v[144:147], v[60:63]
	v_mfma_f32_16x16x32_bf16 v[56:59], v[136:139], v[144:147], v[56:59]
	v_mfma_f32_16x16x32_bf16 v[44:47], v[128:131], v[152:155], v[44:47]
	v_mfma_f32_16x16x32_bf16 v[40:43], v[136:139], v[152:155], v[40:43]
	v_mfma_f32_16x16x32_bf16 v[28:31], v[128:131], v[160:163], v[28:31]
	v_mfma_f32_16x16x32_bf16 v[24:27], v[136:139], v[160:163], v[24:27]
	v_mfma_f32_16x16x32_bf16 v[12:15], v[128:131], v[168:171], v[12:15]
	v_mfma_f32_16x16x32_bf16 v[8:11], v[136:139], v[168:171], v[8:11]
	v_mfma_f32_16x16x32_bf16 v[60:63], v[132:135], v[148:151], v[60:63]
	v_mfma_f32_16x16x32_bf16 v[56:59], v[140:143], v[148:151], v[56:59]
	v_mfma_f32_16x16x32_bf16 v[44:47], v[132:135], v[156:159], v[44:47]
	v_mfma_f32_16x16x32_bf16 v[40:43], v[140:143], v[156:159], v[40:43]
	v_mfma_f32_16x16x32_bf16 v[28:31], v[132:135], v[164:167], v[28:31]
	v_mfma_f32_16x16x32_bf16 v[24:27], v[140:143], v[164:167], v[24:27]
	v_mfma_f32_16x16x32_bf16 v[12:15], v[132:135], v[172:175], v[12:15]
	v_mfma_f32_16x16x32_bf16 v[8:11], v[140:143], v[172:175], v[8:11]
	s_barrier
	s_setprio 0
	s_add_u32 s24, s28, 0x60080
	s_addc_u32 s25, s29, 0
	s_add_i32 s28, s30, s37
	s_mov_b32 m0, s28
	s_nop 0
	global_load_lds_dwordx4 v204, s[24:25]
	s_add_i32 m0, s28, 0x2000
	s_nop 0
	global_load_lds_dwordx4 v208, s[24:25]
	s_waitcnt vmcnt(8)
	s_setprio 1
	s_barrier
	v_mfma_f32_16x16x32_bf16 v[52:55], v[176:179], v[144:147], v[52:55]
	v_mfma_f32_16x16x32_bf16 v[48:51], v[184:187], v[144:147], v[48:51]
	v_mfma_f32_16x16x32_bf16 v[36:39], v[176:179], v[152:155], v[36:39]
	v_mfma_f32_16x16x32_bf16 v[32:35], v[184:187], v[152:155], v[32:35]
	v_mfma_f32_16x16x32_bf16 v[20:23], v[176:179], v[160:163], v[20:23]
	v_mfma_f32_16x16x32_bf16 v[16:19], v[184:187], v[160:163], v[16:19]
	v_mfma_f32_16x16x32_bf16 v[4:7], v[176:179], v[168:171], v[4:7]
	v_mfma_f32_16x16x32_bf16 v[0:3], v[184:187], v[168:171], v[0:3]
	v_mfma_f32_16x16x32_bf16 v[52:55], v[180:183], v[148:151], v[52:55]
	v_mfma_f32_16x16x32_bf16 v[48:51], v[188:191], v[148:151], v[48:51]
	v_mfma_f32_16x16x32_bf16 v[36:39], v[180:183], v[156:159], v[36:39]
	v_mfma_f32_16x16x32_bf16 v[32:35], v[188:191], v[156:159], v[32:35]
	v_mfma_f32_16x16x32_bf16 v[20:23], v[180:183], v[164:167], v[20:23]
	v_mfma_f32_16x16x32_bf16 v[16:19], v[188:191], v[164:167], v[16:19]
	v_mfma_f32_16x16x32_bf16 v[4:7], v[180:183], v[172:175], v[4:7]
	v_mfma_f32_16x16x32_bf16 v[0:3], v[188:191], v[172:175], v[0:3]
	s_barrier
	s_setprio 0
	s_add_i32 s58, s58, 2
	s_add_u32 s56, s56, 0x100
	s_addc_u32 s57, s57, 0
	s_cmp_gt_u32 s58, 21
	s_mov_b64 s[24:25], s[26:27]
.LBB0_902:
	ds_read_b128 v[128:131], v237
	ds_read_b128 v[132:135], v237 offset:1024
	ds_read_b128 v[136:139], v237 offset:2048
	ds_read_b128 v[140:143], v237 offset:3072
	s_add_u32 s26, s24, 0x100
	s_addc_u32 s27, s25, 0
	s_cmp_eq_u32 s58, 20
	s_cselect_b32 s31, s5, s27
	s_cselect_b32 s30, s4, s26
	s_cselect_b32 s29, s7, s57
	s_cselect_b32 s28, s6, s56
	v_lshl_add_u64 v[176:177], s[24:25], 0, v[210:211]
	s_add_i32 m0, s38, 0xc000
	ds_read_b128 v[144:147], v238
	ds_read_b128 v[148:151], v238 offset:1024
	ds_read_b128 v[152:155], v238 offset:2048
	ds_read_b128 v[156:159], v238 offset:3072
	ds_read_b128 v[160:163], v238 offset:4096
	ds_read_b128 v[164:167], v238 offset:5120
	ds_read_b128 v[168:171], v238 offset:6144
	ds_read_b128 v[172:175], v238 offset:7168
	global_load_lds_dwordx4 v[176:177], off
	v_lshl_add_u64 v[176:177], s[24:25], 0, v[212:213]
	s_add_i32 m0, s38, 0xe000
	s_nop 0
	global_load_lds_dwordx4 v[176:177], off
	s_waitcnt lgkmcnt(8)
	s_waitcnt vmcnt(8)
	s_setprio 1
	s_barrier
	s_waitcnt lgkmcnt(0)
	v_mfma_f32_16x16x32_bf16 v[124:127], v[128:131], v[144:147], v[124:127]
	v_mfma_f32_16x16x32_bf16 v[120:123], v[136:139], v[144:147], v[120:123]
	v_mfma_f32_16x16x32_bf16 v[108:111], v[128:131], v[152:155], v[108:111]
	v_mfma_f32_16x16x32_bf16 v[104:107], v[136:139], v[152:155], v[104:107]
	v_mfma_f32_16x16x32_bf16 v[92:95], v[128:131], v[160:163], v[92:95]
	v_mfma_f32_16x16x32_bf16 v[88:91], v[136:139], v[160:163], v[88:91]
	v_mfma_f32_16x16x32_bf16 v[76:79], v[128:131], v[168:171], v[76:79]
	v_mfma_f32_16x16x32_bf16 v[72:75], v[136:139], v[168:171], v[72:75]
	v_mfma_f32_16x16x32_bf16 v[124:127], v[132:135], v[148:151], v[124:127]
	v_mfma_f32_16x16x32_bf16 v[120:123], v[140:143], v[148:151], v[120:123]
	v_mfma_f32_16x16x32_bf16 v[108:111], v[132:135], v[156:159], v[108:111]
	v_mfma_f32_16x16x32_bf16 v[104:107], v[140:143], v[156:159], v[104:107]
	v_mfma_f32_16x16x32_bf16 v[92:95], v[132:135], v[164:167], v[92:95]
	v_mfma_f32_16x16x32_bf16 v[88:91], v[140:143], v[164:167], v[88:91]
	v_mfma_f32_16x16x32_bf16 v[76:79], v[132:135], v[172:175], v[76:79]
	v_mfma_f32_16x16x32_bf16 v[72:75], v[140:143], v[172:175], v[72:75]
	s_barrier
	s_setprio 0
	s_add_i32 s24, s50, s37
	s_mov_b32 m0, s24
	ds_read_b128 v[176:179], v239
	ds_read_b128 v[180:183], v239 offset:1024
	ds_read_b128 v[184:187], v239 offset:2048
	ds_read_b128 v[188:191], v239 offset:3072
	global_load_lds_dwordx4 v204, s[28:29]
	s_add_i32 m0, s24, 0x2000
	s_nop 0
	global_load_lds_dwordx4 v208, s[28:29]
	s_waitcnt vmcnt(8)
	s_setprio 1
	s_barrier
; #define PG8_STAGE(bufoff, gbase, voff) do { _Pragma("unroll") for (int _i = 0; _i < 2; ++_i) \
;         __builtin_amdgcn_global_load_lds((const unsigned*)((const char*)(gbase) + (voff)[_i]), (LAS unsigned*)(lds + (bufoff) + ldsw + _i * 8192), 16, 0, 0); } while (0)
; #define PG8_LDA(dst, b, h) do { _Pragma("unroll") for (int m = 0; m < 4; ++m) _Pragma("unroll") for (int k = 0; k < 2; ++k) dst[m][k] = *(const LAS bf16x8*)(lds + PG8_SA(b, h) + aoff + m * 2048 + k * 1024); } while (0)
; #define PG8_WAIT_V(n) asm volatile("s_waitcnt vmcnt(" #n ")" ::: "memory")
; #define PG8_WAIT_L(n) asm volatile("s_waitcnt lgkmcnt(" #n ")" ::: "memory")
; template <class Epi, class Sched>
; __device__ __forceinline__ void gemm_phase(LAS unsigned char* lds, const Gemm g, const Sched& S, const Epi& E) {
;     ...
;         for (int t = 0; t < nt; t += 2) {
;             const bool last = (t == nt - 2);
;             const char* a1 = cA + (size_t)(t + 1) * kstep;
;             const char* a2 = last ? nA : cA + (size_t)(t + 2) * kstep; const char* b2 = last ? nB : cB + (size_t)(t + 2) * kstep;
;             const char* a3 = a2 + kstep; const char* b3 = b2 + kstep;
;             PG8_LDB(B0, 0, 0); PG8_SCHED; PG8_LDA(At, 0, 0); PG8_STAGE(PG8_SA(1, 1), a1 + hstep, voffA);
;             PG8_WAIT_L(8); PG8_BAR; PG8_WAIT_L(0); PG8_MMA(0, 0, At, B0); PG8_BAR; PG8_SCHED;
;             PG8_LDB(B1, 0, 1); PG8_STAGE(PG8_SB(0, 0), b2, voffB);
;             PG8_BAR; PG8_WAIT_L(0); PG8_MMA(0, 1, At, B1); PG8_BAR;
;             PG8_LDA(At, 0, 1); PG8_STAGE(PG8_SA(0, 0), a2, voffA);
;             PG8_BAR; PG8_WAIT_L(0); PG8_MMA(1, 0, At, B0); PG8_BAR; PG8_SCHED;
;             PG8_STAGE(PG8_SB(0, 1), b2 + hstep, voffB);
;             PG8_WAIT_V(6); PG8_BAR; PG8_MMA(1, 1, At, B1); PG8_BAR;
;             PG8_LDB(B0, 1, 0); PG8_SCHED; PG8_LDA(At, 1, 0); PG8_STAGE(PG8_SA(0, 1), a2 + hstep, voffA);
;             PG8_WAIT_L(8); PG8_BAR; PG8_WAIT_L(0); PG8_MMA(0, 0, At, B0); PG8_BAR; PG8_SCHED;
;             PG8_LDB(B1, 1, 1); PG8_STAGE(PG8_SB(1, 0), b3, voffB);
;             PG8_BAR; PG8_WAIT_L(0); PG8_MMA(0, 1, At, B1); PG8_BAR;
;             PG8_LDA(At, 1, 1); PG8_STAGE(PG8_SA(1, 0), a3, voffA);
;             PG8_BAR; PG8_WAIT_L(0); PG8_MMA(1, 0, At, B0); PG8_BAR; PG8_SCHED;
;             PG8_STAGE(PG8_SB(1, 1), b3 + hstep, voffB);
;             PG8_WAIT_V(6); PG8_BAR; PG8_MMA(1, 1, At, B1); PG8_BAR;
	s_waitcnt lgkmcnt(0)
	v_mfma_f32_16x16x32_bf16 v[116:119], v[176:179], v[144:147], v[116:119]
	v_mfma_f32_16x16x32_bf16 v[112:115], v[184:187], v[144:147], v[112:115]
	v_mfma_f32_16x16x32_bf16 v[100:103], v[176:179], v[152:155], v[100:103]
	v_mfma_f32_16x16x32_bf16 v[96:99], v[184:187], v[152:155], v[96:99]
	v_mfma_f32_16x16x32_bf16 v[84:87], v[176:179], v[160:163], v[84:87]
	v_mfma_f32_16x16x32_bf16 v[80:83], v[184:187], v[160:163], v[80:83]
	v_mfma_f32_16x16x32_bf16 v[68:71], v[176:179], v[168:171], v[68:71]
	v_mfma_f32_16x16x32_bf16 v[64:67], v[184:187], v[168:171], v[64:67]
	v_mfma_f32_16x16x32_bf16 v[116:119], v[180:183], v[148:151], v[116:119]
	v_mfma_f32_16x16x32_bf16 v[112:115], v[188:191], v[148:151], v[112:115]
	v_mfma_f32_16x16x32_bf16 v[100:103], v[180:183], v[156:159], v[100:103]
	v_mfma_f32_16x16x32_bf16 v[96:99], v[188:191], v[156:159], v[96:99]
	v_mfma_f32_16x16x32_bf16 v[84:87], v[180:183], v[164:167], v[84:87]
	v_mfma_f32_16x16x32_bf16 v[80:83], v[188:191], v[164:167], v[80:83]
	v_mfma_f32_16x16x32_bf16 v[68:71], v[180:183], v[172:175], v[68:71]
	v_mfma_f32_16x16x32_bf16 v[64:67], v[188:191], v[172:175], v[64:67]
	s_barrier
	s_setprio 0
	s_mov_b32 m0, s38
	v_lshl_add_u64 v[196:197], s[30:31], 0, v[202:203]
	ds_read_b128 v[144:147], v238 offset:16384
	ds_read_b128 v[148:151], v238 offset:17408
	ds_read_b128 v[152:155], v238 offset:18432
	ds_read_b128 v[156:159], v238 offset:19456
	ds_read_b128 v[160:163], v238 offset:20480
	ds_read_b128 v[164:167], v238 offset:21504
	ds_read_b128 v[168:171], v238 offset:22528
	ds_read_b128 v[172:175], v238 offset:23552
	global_load_lds_dwordx4 v202, s[30:31]
	v_lshl_add_u64 v[198:199], s[30:31], 0, v[206:207]
	s_mov_b32 m0, s39
	s_nop 0
	global_load_lds_dwordx4 v206, s[30:31]
	s_setprio 1
	s_barrier
	s_waitcnt lgkmcnt(0)
	v_mfma_f32_16x16x32_bf16 v[60:63], v[128:131], v[144:147], v[60:63]
	v_mfma_f32_16x16x32_bf16 v[56:59], v[136:139], v[144:147], v[56:59]
	v_mfma_f32_16x16x32_bf16 v[44:47], v[128:131], v[152:155], v[44:47]
	v_mfma_f32_16x16x32_bf16 v[40:43], v[136:139], v[152:155], v[40:43]
	v_mfma_f32_16x16x32_bf16 v[28:31], v[128:131], v[160:163], v[28:31]
	v_mfma_f32_16x16x32_bf16 v[24:27], v[136:139], v[160:163], v[24:27]
	v_mfma_f32_16x16x32_bf16 v[12:15], v[128:131], v[168:171], v[12:15]
	v_mfma_f32_16x16x32_bf16 v[8:11], v[136:139], v[168:171], v[8:11]
	v_mfma_f32_16x16x32_bf16 v[60:63], v[132:135], v[148:151], v[60:63]
	v_mfma_f32_16x16x32_bf16 v[56:59], v[140:143], v[148:151], v[56:59]
	v_mfma_f32_16x16x32_bf16 v[44:47], v[132:135], v[156:159], v[44:47]
	v_mfma_f32_16x16x32_bf16 v[40:43], v[140:143], v[156:159], v[40:43]
	v_mfma_f32_16x16x32_bf16 v[28:31], v[132:135], v[164:167], v[28:31]
	v_mfma_f32_16x16x32_bf16 v[24:27], v[140:143], v[164:167], v[24:27]
	v_mfma_f32_16x16x32_bf16 v[12:15], v[132:135], v[172:175], v[12:15]
	v_mfma_f32_16x16x32_bf16 v[8:11], v[140:143], v[172:175], v[8:11]
	s_barrier
	s_setprio 0
	s_add_u32 s24, s28, 0x60000
	s_addc_u32 s25, s29, 0
	s_add_i32 s59, s51, s37
	s_mov_b32 m0, s59
	s_nop 0
	global_load_lds_dwordx4 v204, s[24:25]
	s_add_i32 m0, s59, 0x2000
	s_nop 0
	global_load_lds_dwordx4 v208, s[24:25]
	s_add_u32 s24, s30, 0x60000
	s_addc_u32 s25, s31, 0
	s_mov_b32 m0, s40
	s_nop 0
	global_load_lds_dwordx4 v202, s[24:25]
	s_mov_b32 m0, s41
	s_nop 0
	global_load_lds_dwordx4 v206, s[24:25]
	s_waitcnt vmcnt(10)
	s_setprio 1
	s_barrier
	v_mfma_f32_16x16x32_bf16 v[52:55], v[176:179], v[144:147], v[52:55]
	v_mfma_f32_16x16x32_bf16 v[48:51], v[184:187], v[144:147], v[48:51]
	v_mfma_f32_16x16x32_bf16 v[36:39], v[176:179], v[152:155], v[36:39]
	v_mfma_f32_16x16x32_bf16 v[32:35], v[184:187], v[152:155], v[32:35]
	v_mfma_f32_16x16x32_bf16 v[20:23], v[176:179], v[160:163], v[20:23]
	v_mfma_f32_16x16x32_bf16 v[16:19], v[184:187], v[160:163], v[16:19]
	v_mfma_f32_16x16x32_bf16 v[4:7], v[176:179], v[168:171], v[4:7]
	v_mfma_f32_16x16x32_bf16 v[0:3], v[184:187], v[168:171], v[0:3]
	v_mfma_f32_16x16x32_bf16 v[52:55], v[180:183], v[148:151], v[52:55]
	v_mfma_f32_16x16x32_bf16 v[48:51], v[188:191], v[148:151], v[48:51]
	v_mfma_f32_16x16x32_bf16 v[36:39], v[180:183], v[156:159], v[36:39]
	v_mfma_f32_16x16x32_bf16 v[32:35], v[188:191], v[156:159], v[32:35]
	v_mfma_f32_16x16x32_bf16 v[20:23], v[180:183], v[164:167], v[20:23]
	v_mfma_f32_16x16x32_bf16 v[16:19], v[188:191], v[164:167], v[16:19]
	v_mfma_f32_16x16x32_bf16 v[4:7], v[180:183], v[172:175], v[4:7]
	v_mfma_f32_16x16x32_bf16 v[0:3], v[188:191], v[172:175], v[0:3]
	s_barrier
	s_setprio 0
	s_add_i32 s59, 0, 0x18000
	v_add_u32_e32 v140, s59, v236
	ds_read_b128 v[128:131], v140
	ds_read_b128 v[132:135], v140 offset:1024
	ds_read_b128 v[136:139], v140 offset:2048
	ds_read_b128 v[140:143], v140 offset:3072
	ds_read_b128 v[144:147], v238 offset:32768
	ds_read_b128 v[148:151], v238 offset:33792
	ds_read_b128 v[152:155], v238 offset:34816
	ds_read_b128 v[156:159], v238 offset:35840
	ds_read_b128 v[160:163], v238 offset:36864
	ds_read_b128 v[164:167], v238 offset:37888
	ds_read_b128 v[168:171], v238 offset:38912
	ds_read_b128 v[172:175], v238 offset:39936
	s_waitcnt lgkmcnt(8)
	s_waitcnt vmcnt(8)
	s_setprio 1
	s_barrier
; #define PG8_STAGE(bufoff, gbase, voff) do { _Pragma("unroll") for (int _i = 0; _i < 2; ++_i) \
;         __builtin_amdgcn_global_load_lds((const unsigned*)((const char*)(gbase) + (voff)[_i]), (LAS unsigned*)(lds + (bufoff) + ldsw + _i * 8192), 16, 0, 0); } while (0)
; #define PG8_LDA(dst, b, h) do { _Pragma("unroll") for (int m = 0; m < 4; ++m) _Pragma("unroll") for (int k = 0; k < 2; ++k) dst[m][k] = *(const LAS bf16x8*)(lds + PG8_SA(b, h) + aoff + m * 2048 + k * 1024); } while (0)
; #define PG8_WAIT_V(n) asm volatile("s_waitcnt vmcnt(" #n ")" ::: "memory")
; #define PG8_WAIT_L(n) asm volatile("s_waitcnt lgkmcnt(" #n ")" ::: "memory")
; template <class Epi, class Sched>
; __device__ __forceinline__ void gemm_phase(LAS unsigned char* lds, const Gemm g, const Sched& S, const Epi& E) {
;     ...
;         for (int t = 0; t < nt; t += 2) {
;             const bool last = (t == nt - 2);
;             const char* a1 = cA + (size_t)(t + 1) * kstep;
;             const char* a2 = last ? nA : cA + (size_t)(t + 2) * kstep; const char* b2 = last ? nB : cB + (size_t)(t + 2) * kstep;
;             const char* a3 = a2 + kstep; const char* b3 = b2 + kstep;
;             PG8_LDB(B0, 0, 0); PG8_SCHED; PG8_LDA(At, 0, 0); PG8_STAGE(PG8_SA(1, 1), a1 + hstep, voffA);
;             PG8_WAIT_L(8); PG8_BAR; PG8_WAIT_L(0); PG8_MMA(0, 0, At, B0); PG8_BAR; PG8_SCHED;
;             PG8_LDB(B1, 0, 1); PG8_STAGE(PG8_SB(0, 0), b2, voffB);
;             PG8_BAR; PG8_WAIT_L(0); PG8_MMA(0, 1, At, B1); PG8_BAR;
;             PG8_LDA(At, 0, 1); PG8_STAGE(PG8_SA(0, 0), a2, voffA);
;             PG8_BAR; PG8_WAIT_L(0); PG8_MMA(1, 0, At, B0); PG8_BAR; PG8_SCHED;
;             PG8_STAGE(PG8_SB(0, 1), b2 + hstep, voffB);
;             PG8_WAIT_V(6); PG8_BAR; PG8_MMA(1, 1, At, B1); PG8_BAR;
;             PG8_LDB(B0, 1, 0); PG8_SCHED; PG8_LDA(At, 1, 0); PG8_STAGE(PG8_SA(0, 1), a2 + hstep, voffA);
;             PG8_WAIT_L(8); PG8_BAR; PG8_WAIT_L(0); PG8_MMA(0, 0, At, B0); PG8_BAR; PG8_SCHED;
;             PG8_LDB(B1, 1, 1); PG8_STAGE(PG8_SB(1, 0), b3, voffB);
;             PG8_BAR; PG8_WAIT_L(0); PG8_MMA(0, 1, At, B1); PG8_BAR;
;             PG8_LDA(At, 1, 1); PG8_STAGE(PG8_SA(1, 0), a3, voffA);
;             PG8_BAR; PG8_WAIT_L(0); PG8_MMA(1, 0, At, B0); PG8_BAR; PG8_SCHED;
;             PG8_STAGE(PG8_SB(1, 1), b3 + hstep, voffB);
;             PG8_WAIT_V(6); PG8_BAR; PG8_MMA(1, 1, At, B1); PG8_BAR;
	s_waitcnt lgkmcnt(0)
	v_mfma_f32_16x16x32_bf16 v[124:127], v[128:131], v[144:147], v[124:127]
	v_mfma_f32_16x16x32_bf16 v[120:123], v[136:139], v[144:147], v[120:123]
	v_mfma_f32_16x16x32_bf16 v[108:111], v[128:131], v[152:155], v[108:111]
	v_mfma_f32_16x16x32_bf16 v[104:107], v[136:139], v[152:155], v[104:107]
	v_mfma_f32_16x16x32_bf16 v[92:95], v[128:131], v[160:163], v[92:95]
	v_mfma_f32_16x16x32_bf16 v[88:91], v[136:139], v[160:163], v[88:91]
	v_mfma_f32_16x16x32_bf16 v[76:79], v[128:131], v[168:171], v[76:79]
	v_mfma_f32_16x16x32_bf16 v[72:75], v[136:139], v[168:171], v[72:75]
	v_mfma_f32_16x16x32_bf16 v[124:127], v[132:135], v[148:151], v[124:127]
	v_mfma_f32_16x16x32_bf16 v[120:123], v[140:143], v[148:151], v[120:123]
	v_mfma_f32_16x16x32_bf16 v[108:111], v[132:135], v[156:159], v[108:111]
	v_mfma_f32_16x16x32_bf16 v[104:107], v[140:143], v[156:159], v[104:107]
	v_mfma_f32_16x16x32_bf16 v[92:95], v[132:135], v[164:167], v[92:95]
	v_mfma_f32_16x16x32_bf16 v[88:91], v[140:143], v[164:167], v[88:91]
	v_mfma_f32_16x16x32_bf16 v[76:79], v[132:135], v[172:175], v[76:79]
	v_mfma_f32_16x16x32_bf16 v[72:75], v[140:143], v[172:175], v[72:75]
	s_barrier
	s_setprio 0
	s_add_i32 s30, 0, 0x1c000
	s_add_i32 s24, s59, s37
	v_add_u32_e32 v188, s30, v236
	s_add_u32 s0, s28, 0x80
	s_addc_u32 s1, s29, 0
	s_mov_b32 m0, s24
	ds_read_b128 v[176:179], v188
	ds_read_b128 v[180:183], v188 offset:1024
	ds_read_b128 v[184:187], v188 offset:2048
	ds_read_b128 v[188:191], v188 offset:3072
	global_load_lds_dwordx4 v204, s[0:1]
	s_add_i32 m0, s24, 0x2000
	s_nop 0
	global_load_lds_dwordx4 v208, s[0:1]
	s_waitcnt vmcnt(8)
	s_setprio 1
	s_barrier
	s_waitcnt lgkmcnt(0)
	v_mfma_f32_16x16x32_bf16 v[116:119], v[176:179], v[144:147], v[116:119]
	v_mfma_f32_16x16x32_bf16 v[112:115], v[184:187], v[144:147], v[112:115]
	v_mfma_f32_16x16x32_bf16 v[100:103], v[176:179], v[152:155], v[100:103]
	v_mfma_f32_16x16x32_bf16 v[96:99], v[184:187], v[152:155], v[96:99]
	v_mfma_f32_16x16x32_bf16 v[84:87], v[176:179], v[160:163], v[84:87]
	v_mfma_f32_16x16x32_bf16 v[80:83], v[184:187], v[160:163], v[80:83]
	v_mfma_f32_16x16x32_bf16 v[68:71], v[176:179], v[168:171], v[68:71]
	v_mfma_f32_16x16x32_bf16 v[64:67], v[184:187], v[168:171], v[64:67]
	v_mfma_f32_16x16x32_bf16 v[116:119], v[180:183], v[148:151], v[116:119]
	v_mfma_f32_16x16x32_bf16 v[112:115], v[188:191], v[148:151], v[112:115]
	v_mfma_f32_16x16x32_bf16 v[100:103], v[180:183], v[156:159], v[100:103]
	v_mfma_f32_16x16x32_bf16 v[96:99], v[188:191], v[156:159], v[96:99]
	v_mfma_f32_16x16x32_bf16 v[84:87], v[180:183], v[164:167], v[84:87]
	v_mfma_f32_16x16x32_bf16 v[80:83], v[188:191], v[164:167], v[80:83]
	v_mfma_f32_16x16x32_bf16 v[68:71], v[180:183], v[172:175], v[68:71]
	v_mfma_f32_16x16x32_bf16 v[64:67], v[188:191], v[172:175], v[64:67]
	s_barrier
	s_setprio 0
	s_mov_b32 m0, s47
	s_mov_b64 s[0:1], 0x80
	v_lshl_add_u64 v[192:193], v[196:197], 0, s[0:1]
	ds_read_b128 v[144:147], v238 offset:49152
	ds_read_b128 v[148:151], v238 offset:50176
	ds_read_b128 v[152:155], v238 offset:51200
	ds_read_b128 v[156:159], v238 offset:52224
	ds_read_b128 v[160:163], v238 offset:53248
	ds_read_b128 v[164:167], v238 offset:54272
	ds_read_b128 v[168:171], v238 offset:55296
	ds_read_b128 v[172:175], v238 offset:56320
	global_load_lds_dwordx4 v[192:193], off
	v_lshl_add_u64 v[192:193], v[198:199], 0, s[0:1]
	s_mov_b32 m0, s48
	s_nop 0
	global_load_lds_dwordx4 v[192:193], off
	s_setprio 1
	s_barrier
	s_waitcnt lgkmcnt(0)
	v_mfma_f32_16x16x32_bf16 v[60:63], v[128:131], v[144:147], v[60:63]
	v_mfma_f32_16x16x32_bf16 v[56:59], v[136:139], v[144:147], v[56:59]
	v_mfma_f32_16x16x32_bf16 v[44:47], v[128:131], v[152:155], v[44:47]
	v_mfma_f32_16x16x32_bf16 v[40:43], v[136:139], v[152:155], v[40:43]
	v_mfma_f32_16x16x32_bf16 v[28:31], v[128:131], v[160:163], v[28:31]
	v_mfma_f32_16x16x32_bf16 v[24:27], v[136:139], v[160:163], v[24:27]
	v_mfma_f32_16x16x32_bf16 v[12:15], v[128:131], v[168:171], v[12:15]
	v_mfma_f32_16x16x32_bf16 v[8:11], v[136:139], v[168:171], v[8:11]
	v_mfma_f32_16x16x32_bf16 v[60:63], v[132:135], v[148:151], v[60:63]
	v_mfma_f32_16x16x32_bf16 v[56:59], v[140:143], v[148:151], v[56:59]
	v_mfma_f32_16x16x32_bf16 v[44:47], v[132:135], v[156:159], v[44:47]
	v_mfma_f32_16x16x32_bf16 v[40:43], v[140:143], v[156:159], v[40:43]
	v_mfma_f32_16x16x32_bf16 v[28:31], v[132:135], v[164:167], v[28:31]
	v_mfma_f32_16x16x32_bf16 v[24:27], v[140:143], v[164:167], v[24:27]
	v_mfma_f32_16x16x32_bf16 v[12:15], v[132:135], v[172:175], v[12:15]
	v_mfma_f32_16x16x32_bf16 v[8:11], v[140:143], v[172:175], v[8:11]
	s_barrier
	s_setprio 0
	s_add_u32 s24, s28, 0x60080
	s_addc_u32 s25, s29, 0
	s_add_i32 s28, s30, s37
	s_mov_b32 m0, s28
	s_nop 0
	global_load_lds_dwordx4 v204, s[24:25]
	s_add_i32 m0, s28, 0x2000
	s_nop 0
	global_load_lds_dwordx4 v208, s[24:25]
	s_waitcnt vmcnt(8)
	s_setprio 1
	s_barrier
	v_mfma_f32_16x16x32_bf16 v[52:55], v[176:179], v[144:147], v[52:55]
	v_mfma_f32_16x16x32_bf16 v[48:51], v[184:187], v[144:147], v[48:51]
	v_mfma_f32_16x16x32_bf16 v[36:39], v[176:179], v[152:155], v[36:39]
	v_mfma_f32_16x16x32_bf16 v[32:35], v[184:187], v[152:155], v[32:35]
	v_mfma_f32_16x16x32_bf16 v[20:23], v[176:179], v[160:163], v[20:23]
	v_mfma_f32_16x16x32_bf16 v[16:19], v[184:187], v[160:163], v[16:19]
	v_mfma_f32_16x16x32_bf16 v[4:7], v[176:179], v[168:171], v[4:7]
	v_mfma_f32_16x16x32_bf16 v[0:3], v[184:187], v[168:171], v[0:3]
	v_mfma_f32_16x16x32_bf16 v[52:55], v[180:183], v[148:151], v[52:55]
	v_mfma_f32_16x16x32_bf16 v[48:51], v[188:191], v[148:151], v[48:51]
	v_mfma_f32_16x16x32_bf16 v[36:39], v[180:183], v[156:159], v[36:39]
	v_mfma_f32_16x16x32_bf16 v[32:35], v[188:191], v[156:159], v[32:35]
	v_mfma_f32_16x16x32_bf16 v[20:23], v[180:183], v[164:167], v[20:23]
	v_mfma_f32_16x16x32_bf16 v[16:19], v[188:191], v[164:167], v[16:19]
	v_mfma_f32_16x16x32_bf16 v[4:7], v[180:183], v[172:175], v[4:7]
	v_mfma_f32_16x16x32_bf16 v[0:3], v[188:191], v[172:175], v[0:3]
	s_barrier
; __device__ __forceinline__ unsigned cvt_pk_bf16(float lo, float hi) { unsigned r; asm volatile("v_cvt_pk_bf16_f32 %0, %1, %2" : "=v"(r) : "v"(lo), "v"(hi)); return r; }
; __device__ __forceinline__ float bf_lo(unsigned u) { return __uint_as_float(u << 16); }
; __device__ __forceinline__ float bf_hi(unsigned u) { return __uint_as_float(u & 0xffff0000u); }
;     __device__ __forceinline__ void operator()(const AccT& acc, const Unit& u, int wr, int wc, int fr, int fq) const {
;     ...
;         const int rowt = u.pm * 256; const int b = rowt >> 11;
;         const bf16_t* res = res_b + (size_t)rowt * DM; bf16_t* out = hb + (size_t)rowt * DM;
;         const int col0 = u.pn * 256 + wc * 32 + 8 * fq;
;         f32x4 gv[2][2];
; #pragma unroll
;         for (int bj = 0; bj < 2; ++bj)
; #pragma unroll
;             for (int n = 0; n < 2; ++n) gv[bj][n] = *(const f32x4*)(gate + (size_t)b * NMOD + col0 + bj * 128 + n * 4) * gs;
;         u32x4 r[2][4][2];
; #pragma unroll
;         for (int ai = 0; ai < 2; ++ai)
; #pragma unroll
;             for (int m = 0; m < 4; ++m)
; #pragma unroll
;                 for (int bj = 0; bj < 2; ++bj) r[ai][m][bj] = *(const u32x4*)(res + (size_t)(wr * 64 + fr + ai * 128 + m * 16) * DM + col0 + bj * 128);
; #pragma unroll
;         for (int ai = 0; ai < 2; ++ai)
; #pragma unroll
;             for (int m = 0; m < 4; ++m)
; #pragma unroll
;                 for (int bj = 0; bj < 2; ++bj) {
;                     const u32x4 q = r[ai][m][bj];
;                     const f32x4 r0 = {bf_lo(q.x), bf_hi(q.x), bf_lo(q.y), bf_hi(q.y)}, r1 = {bf_lo(q.z), bf_hi(q.z), bf_lo(q.w), bf_hi(q.w)};
;                     const f32x4 h0 = r0 + gv[bj][0] * acc[ai][bj][m][0], h1 = r1 + gv[bj][1] * acc[ai][bj][m][1];
;                     u32x4 w; w.x = cvt_pk_bf16(h0[0], h0[1]); w.y = cvt_pk_bf16(h0[2], h0[3]); w.z = cvt_pk_bf16(h1[0], h1[1]); w.w = cvt_pk_bf16(h1[2], h1[3]);
;                     *(u32x4*)(out + (size_t)(wr * 64 + fr + ai * 128 + m * 16) * DM + col0 + bj * 128) = w;
	s_setprio 0
	s_add_i32 s58, s58, 2
	s_add_u32 s56, s56, 0x100
	s_addc_u32 s57, s57, 0
	s_cmp_gt_u32 s58, 21
	s_mov_b64 s[24:25], s[26:27]
	s_cbranch_scc0 .LBB0_902
	s_lshl_b32 s27, s55, 8
	v_mov_b32_e32 v146, v235
	v_mov_b32_e32 v128, v234
	s_lshl_b32 s24, s54, 8
	s_ashr_i32 s26, s54, 3
	s_or_b32 s27, s27, s46
	s_ashr_i32 s25, s24, 31
	v_lshl_add_u32 v144, v128, 3, s27
	s_mul_hi_i32 s27, s26, 0x9000
	s_mul_i32 s26, s26, 0x9000
	s_add_u32 s26, s43, s26
	s_addc_u32 s27, s44, s27
	v_ashrrev_i32_e32 v145, 31, v144
	s_lshl_b64 s[24:25], s[24:25], 11
	v_lshl_add_u64 v[132:133], v[144:145], 2, s[26:27]
	s_add_u32 s26, s62, s24
	v_add_u32_e32 v146, s45, v146
	s_addc_u32 s27, s63, s25
	v_lshlrev_b64 v[222:223], 1, v[144:145]
	v_ashrrev_i32_e32 v147, 31, v146
	v_lshl_add_u64 v[144:145], s[26:27], 0, v[222:223]
	v_lshlrev_b64 v[248:249], 11, v[146:147]
	v_lshl_add_u64 v[146:147], v[144:145], 0, v[248:249]
	global_load_dwordx4 v[136:139], v[132:133], off offset:16
	global_load_dwordx4 v[140:143], v[132:133], off
	global_load_dwordx4 v[128:131], v[132:133], off offset:528
	s_nop 0
	global_load_dwordx4 v[132:135], v[132:133], off offset:512
	s_nop 0
	global_load_dwordx4 v[240:243], v[146:147], off
	global_load_dwordx4 v[244:247], v[146:147], off offset:256
	v_lshl_add_u64 v[232:233], v[248:249], 0, s[10:11]
	v_lshl_add_u64 v[146:147], v[144:145], 0, v[232:233]
	global_load_dwordx4 v[196:199], v[146:147], off
	global_load_dwordx4 v[192:195], v[146:147], off offset:256
	v_lshl_add_u64 v[230:231], v[248:249], 0, s[12:13]
	v_lshl_add_u64 v[146:147], v[144:145], 0, v[230:231]
	global_load_dwordx4 v[188:191], v[146:147], off
	global_load_dwordx4 v[184:187], v[146:147], off offset:256
	v_lshl_add_u64 v[228:229], v[248:249], 0, s[14:15]
	v_lshl_add_u64 v[146:147], v[144:145], 0, v[228:229]
	global_load_dwordx4 v[180:183], v[146:147], off
	global_load_dwordx4 v[176:179], v[146:147], off offset:256
	v_lshl_add_u64 v[226:227], v[248:249], 0, s[16:17]
	v_lshl_add_u64 v[146:147], v[144:145], 0, v[226:227]
	global_load_dwordx4 v[172:175], v[146:147], off
	global_load_dwordx4 v[168:171], v[146:147], off offset:256
	v_lshl_add_u64 v[224:225], v[248:249], 0, s[18:19]
	v_lshl_add_u64 v[146:147], v[144:145], 0, v[224:225]
	global_load_dwordx4 v[164:167], v[146:147], off
	global_load_dwordx4 v[160:163], v[146:147], off offset:256
	v_lshl_add_u64 v[220:221], v[248:249], 0, s[20:21]
	v_lshl_add_u64 v[146:147], v[144:145], 0, v[220:221]
	global_load_dwordx4 v[156:159], v[146:147], off
	global_load_dwordx4 v[152:155], v[146:147], off offset:256
	v_lshl_add_u64 v[218:219], v[248:249], 0, s[22:23]
	v_lshl_add_u64 v[144:145], v[144:145], 0, v[218:219]
	global_load_dwordx4 v[148:151], v[144:145], off
	s_nop 0
	global_load_dwordx4 v[144:147], v[144:145], off offset:256
	s_add_u32 s24, s80, s24
	s_addc_u32 s25, s81, s25
	v_lshl_add_u64 v[222:223], s[24:25], 0, v[222:223]
	v_lshl_add_u64 v[248:249], v[222:223], 0, v[248:249]
	s_and_b64 vcc, exec, s[2:3]
	s_mov_b32 s55, s52
	s_mov_b32 s54, s53
	s_mov_b64 s[26:27], s[6:7]
	s_mov_b64 s[24:25], s[4:5]
	s_waitcnt vmcnt(0)
	v_lshlrev_b32_e32 v250, 16, v240
	v_and_b32_e32 v251, 0xffff0000, v240
	v_lshlrev_b32_e32 v240, 16, v241
	v_and_b32_e32 v241, 0xffff0000, v241
	v_lshlrev_b32_e32 v252, 16, v242
	v_and_b32_e32 v253, 0xffff0000, v242
	v_lshlrev_b32_e32 v242, 16, v243
	v_and_b32_e32 v243, 0xffff0000, v243
	v_pk_fma_f32 v[126:127], v[126:127], v[142:143], v[240:241]
	v_pk_fma_f32 v[124:125], v[124:125], v[140:141], v[250:251]
	v_pk_fma_f32 v[240:241], v[122:123], v[138:139], v[242:243]
	v_pk_fma_f32 v[122:123], v[120:121], v[136:137], v[252:253]
	v_cvt_pk_bf16_f32 v120, v124, v125
	v_cvt_pk_bf16_f32 v121, v126, v127
	v_lshlrev_b32_e32 v124, 16, v246
	v_cvt_pk_bf16_f32 v122, v122, v123
	v_cvt_pk_bf16_f32 v123, v240, v241
	global_store_dwordx4 v[248:249], v[120:123], off
	v_and_b32_e32 v125, 0xffff0000, v246
	v_lshlrev_b32_e32 v126, 16, v247
	v_lshlrev_b32_e32 v120, 16, v244
	v_and_b32_e32 v121, 0xffff0000, v244
	v_and_b32_e32 v127, 0xffff0000, v247
	v_lshlrev_b32_e32 v122, 16, v245
	v_and_b32_e32 v123, 0xffff0000, v245
	v_pk_fma_f32 v[116:117], v[116:117], v[132:133], v[120:121]
	v_pk_fma_f32 v[120:121], v[114:115], v[130:131], v[126:127]
	v_pk_fma_f32 v[114:115], v[112:113], v[128:129], v[124:125]
	v_pk_fma_f32 v[118:119], v[118:119], v[134:135], v[122:123]
	v_cvt_pk_bf16_f32 v112, v116, v117
	v_lshlrev_b32_e32 v116, 16, v197
	v_cvt_pk_bf16_f32 v113, v118, v119
	v_cvt_pk_bf16_f32 v114, v114, v115
	v_cvt_pk_bf16_f32 v115, v120, v121
	global_store_dwordx4 v[248:249], v[112:115], off offset:256
	v_and_b32_e32 v117, 0xffff0000, v197
	v_lshlrev_b32_e32 v118, 16, v198
	v_lshlrev_b32_e32 v114, 16, v196
	v_and_b32_e32 v115, 0xffff0000, v196
	v_and_b32_e32 v119, 0xffff0000, v198
	v_lshlrev_b32_e32 v120, 16, v199
	v_and_b32_e32 v121, 0xffff0000, v199
	v_lshl_add_u64 v[112:113], v[222:223], 0, v[232:233]
	v_pk_fma_f32 v[110:111], v[110:111], v[142:143], v[116:117]
	v_pk_fma_f32 v[108:109], v[108:109], v[140:141], v[114:115]
	v_pk_fma_f32 v[114:115], v[106:107], v[138:139], v[120:121]
	v_pk_fma_f32 v[106:107], v[104:105], v[136:137], v[118:119]
	v_cvt_pk_bf16_f32 v104, v108, v109
	v_cvt_pk_bf16_f32 v105, v110, v111
	v_lshlrev_b32_e32 v108, 16, v194
	v_cvt_pk_bf16_f32 v106, v106, v107
	v_cvt_pk_bf16_f32 v107, v114, v115
	global_store_dwordx4 v[112:113], v[104:107], off
	v_and_b32_e32 v109, 0xffff0000, v194
	v_lshlrev_b32_e32 v110, 16, v195
	v_lshlrev_b32_e32 v104, 16, v192
	v_and_b32_e32 v105, 0xffff0000, v192
	v_and_b32_e32 v111, 0xffff0000, v195
	v_lshlrev_b32_e32 v106, 16, v193
	v_and_b32_e32 v107, 0xffff0000, v193
; __device__ __forceinline__ unsigned cvt_pk_bf16(float lo, float hi) { unsigned r; asm volatile("v_cvt_pk_bf16_f32 %0, %1, %2" : "=v"(r) : "v"(lo), "v"(hi)); return r; }
; __device__ __forceinline__ float bf_lo(unsigned u) { return __uint_as_float(u << 16); }
; __device__ __forceinline__ float bf_hi(unsigned u) { return __uint_as_float(u & 0xffff0000u); }
;     __device__ __forceinline__ void operator()(const AccT& acc, const Unit& u, int wr, int wc, int fr, int fq) const {
;     ...
;         for (int ai = 0; ai < 2; ++ai)
; #pragma unroll
;             for (int m = 0; m < 4; ++m)
; #pragma unroll
;                 for (int bj = 0; bj < 2; ++bj) {
;                     const u32x4 q = r[ai][m][bj];
;                     const f32x4 r0 = {bf_lo(q.x), bf_hi(q.x), bf_lo(q.y), bf_hi(q.y)}, r1 = {bf_lo(q.z), bf_hi(q.z), bf_lo(q.w), bf_hi(q.w)};
;                     const f32x4 h0 = r0 + gv[bj][0] * acc[ai][bj][m][0], h1 = r1 + gv[bj][1] * acc[ai][bj][m][1];
;                     u32x4 w; w.x = cvt_pk_bf16(h0[0], h0[1]); w.y = cvt_pk_bf16(h0[2], h0[3]); w.z = cvt_pk_bf16(h1[0], h1[1]); w.w = cvt_pk_bf16(h1[2], h1[3]);
;                     *(u32x4*)(out + (size_t)(wr * 64 + fr + ai * 128 + m * 16) * DM + col0 + bj * 128) = w;
	v_pk_fma_f32 v[100:101], v[100:101], v[132:133], v[104:105]
	v_pk_fma_f32 v[104:105], v[98:99], v[130:131], v[110:111]
	v_pk_fma_f32 v[98:99], v[96:97], v[128:129], v[108:109]
	v_pk_fma_f32 v[102:103], v[102:103], v[134:135], v[106:107]
	v_cvt_pk_bf16_f32 v96, v100, v101
	v_lshlrev_b32_e32 v100, 16, v189
	v_cvt_pk_bf16_f32 v97, v102, v103
	v_cvt_pk_bf16_f32 v98, v98, v99
	v_cvt_pk_bf16_f32 v99, v104, v105
	global_store_dwordx4 v[112:113], v[96:99], off offset:256
	v_and_b32_e32 v101, 0xffff0000, v189
	v_lshlrev_b32_e32 v102, 16, v190
	v_lshlrev_b32_e32 v98, 16, v188
	v_and_b32_e32 v99, 0xffff0000, v188
	v_and_b32_e32 v103, 0xffff0000, v190
	v_lshlrev_b32_e32 v104, 16, v191
	v_and_b32_e32 v105, 0xffff0000, v191
	v_lshl_add_u64 v[96:97], v[222:223], 0, v[230:231]
	v_pk_fma_f32 v[94:95], v[94:95], v[142:143], v[100:101]
	v_pk_fma_f32 v[92:93], v[92:93], v[140:141], v[98:99]
	v_pk_fma_f32 v[98:99], v[90:91], v[138:139], v[104:105]
	v_pk_fma_f32 v[90:91], v[88:89], v[136:137], v[102:103]
	v_cvt_pk_bf16_f32 v88, v92, v93
	v_cvt_pk_bf16_f32 v89, v94, v95
	v_lshlrev_b32_e32 v92, 16, v186
	v_cvt_pk_bf16_f32 v90, v90, v91
	v_cvt_pk_bf16_f32 v91, v98, v99
	global_store_dwordx4 v[96:97], v[88:91], off
	v_and_b32_e32 v93, 0xffff0000, v186
	v_lshlrev_b32_e32 v94, 16, v187
	v_lshlrev_b32_e32 v88, 16, v184
	v_and_b32_e32 v89, 0xffff0000, v184
	v_and_b32_e32 v95, 0xffff0000, v187
	v_lshlrev_b32_e32 v90, 16, v185
	v_and_b32_e32 v91, 0xffff0000, v185
	v_pk_fma_f32 v[84:85], v[84:85], v[132:133], v[88:89]
	v_pk_fma_f32 v[88:89], v[82:83], v[130:131], v[94:95]
	v_pk_fma_f32 v[82:83], v[80:81], v[128:129], v[92:93]
	v_pk_fma_f32 v[86:87], v[86:87], v[134:135], v[90:91]
	v_cvt_pk_bf16_f32 v80, v84, v85
	v_lshlrev_b32_e32 v84, 16, v181
	v_cvt_pk_bf16_f32 v81, v86, v87
	v_cvt_pk_bf16_f32 v82, v82, v83
	v_cvt_pk_bf16_f32 v83, v88, v89
	global_store_dwordx4 v[96:97], v[80:83], off offset:256
	v_and_b32_e32 v85, 0xffff0000, v181
	v_lshlrev_b32_e32 v86, 16, v182
	v_lshlrev_b32_e32 v82, 16, v180
	v_and_b32_e32 v83, 0xffff0000, v180
	v_and_b32_e32 v87, 0xffff0000, v182
	v_lshlrev_b32_e32 v88, 16, v183
	v_and_b32_e32 v89, 0xffff0000, v183
	v_lshl_add_u64 v[80:81], v[222:223], 0, v[228:229]
	v_pk_fma_f32 v[78:79], v[78:79], v[142:143], v[84:85]
	v_pk_fma_f32 v[76:77], v[76:77], v[140:141], v[82:83]
	v_pk_fma_f32 v[82:83], v[74:75], v[138:139], v[88:89]
	v_pk_fma_f32 v[74:75], v[72:73], v[136:137], v[86:87]
	v_cvt_pk_bf16_f32 v72, v76, v77
	v_cvt_pk_bf16_f32 v73, v78, v79
	v_lshlrev_b32_e32 v76, 16, v178
	v_cvt_pk_bf16_f32 v74, v74, v75
	v_cvt_pk_bf16_f32 v75, v82, v83
	global_store_dwordx4 v[80:81], v[72:75], off
	v_and_b32_e32 v77, 0xffff0000, v178
	v_lshlrev_b32_e32 v78, 16, v179
	v_lshlrev_b32_e32 v72, 16, v176
	v_and_b32_e32 v73, 0xffff0000, v176
	v_and_b32_e32 v79, 0xffff0000, v179
	v_lshlrev_b32_e32 v74, 16, v177
	v_and_b32_e32 v75, 0xffff0000, v177
	v_pk_fma_f32 v[68:69], v[68:69], v[132:133], v[72:73]
	v_pk_fma_f32 v[72:73], v[66:67], v[130:131], v[78:79]
	v_pk_fma_f32 v[66:67], v[64:65], v[128:129], v[76:77]
	v_pk_fma_f32 v[70:71], v[70:71], v[134:135], v[74:75]
	v_cvt_pk_bf16_f32 v64, v68, v69
	v_lshlrev_b32_e32 v68, 16, v173
	v_cvt_pk_bf16_f32 v65, v70, v71
	v_cvt_pk_bf16_f32 v66, v66, v67
	v_cvt_pk_bf16_f32 v67, v72, v73
	global_store_dwordx4 v[80:81], v[64:67], off offset:256
	v_and_b32_e32 v69, 0xffff0000, v173
	v_lshlrev_b32_e32 v70, 16, v174
	v_lshlrev_b32_e32 v66, 16, v172
	v_and_b32_e32 v67, 0xffff0000, v172
	v_and_b32_e32 v71, 0xffff0000, v174
	v_lshlrev_b32_e32 v72, 16, v175
	v_and_b32_e32 v73, 0xffff0000, v175
	v_lshl_add_u64 v[64:65], v[222:223], 0, v[226:227]
	v_pk_fma_f32 v[62:63], v[62:63], v[142:143], v[68:69]
	v_pk_fma_f32 v[60:61], v[60:61], v[140:141], v[66:67]
	v_pk_fma_f32 v[66:67], v[58:59], v[138:139], v[72:73]
	v_pk_fma_f32 v[58:59], v[56:57], v[136:137], v[70:71]
	v_cvt_pk_bf16_f32 v56, v60, v61
	v_cvt_pk_bf16_f32 v57, v62, v63
	v_lshlrev_b32_e32 v60, 16, v170
	v_cvt_pk_bf16_f32 v58, v58, v59
	v_cvt_pk_bf16_f32 v59, v66, v67
	global_store_dwordx4 v[64:65], v[56:59], off
	v_and_b32_e32 v61, 0xffff0000, v170
	v_lshlrev_b32_e32 v62, 16, v171
	v_lshlrev_b32_e32 v56, 16, v168
	v_and_b32_e32 v57, 0xffff0000, v168
	v_and_b32_e32 v63, 0xffff0000, v171
	v_lshlrev_b32_e32 v58, 16, v169
	v_and_b32_e32 v59, 0xffff0000, v169
	v_pk_fma_f32 v[52:53], v[52:53], v[132:133], v[56:57]
	v_pk_fma_f32 v[56:57], v[50:51], v[130:131], v[62:63]
	v_pk_fma_f32 v[50:51], v[48:49], v[128:129], v[60:61]
	v_pk_fma_f32 v[54:55], v[54:55], v[134:135], v[58:59]
; __device__ __forceinline__ unsigned cvt_pk_bf16(float lo, float hi) { unsigned r; asm volatile("v_cvt_pk_bf16_f32 %0, %1, %2" : "=v"(r) : "v"(lo), "v"(hi)); return r; }
; __device__ __forceinline__ float bf_lo(unsigned u) { return __uint_as_float(u << 16); }
; __device__ __forceinline__ float bf_hi(unsigned u) { return __uint_as_float(u & 0xffff0000u); }
; #define PG8_WAIT_V(n) asm volatile("s_waitcnt vmcnt(" #n ")" ::: "memory")
; #define PG8_BAR __builtin_amdgcn_s_barrier()
; template <class Epi, class Sched>
; __device__ __forceinline__ void gemm_phase(LAS unsigned char* lds, const Gemm g, const Sched& S, const Epi& E) {
;     ...
;     PG8_WAIT_V(0);
;     if (wr == 0) PG8_BAR;
;     PG8_BAR;
;     __device__ __forceinline__ void operator()(const AccT& acc, const Unit& u, int wr, int wc, int fr, int fq) const {
;     ...
;         for (int ai = 0; ai < 2; ++ai)
; #pragma unroll
;             for (int m = 0; m < 4; ++m)
; #pragma unroll
;                 for (int bj = 0; bj < 2; ++bj) {
;                     const u32x4 q = r[ai][m][bj];
;                     const f32x4 r0 = {bf_lo(q.x), bf_hi(q.x), bf_lo(q.y), bf_hi(q.y)}, r1 = {bf_lo(q.z), bf_hi(q.z), bf_lo(q.w), bf_hi(q.w)};
;                     const f32x4 h0 = r0 + gv[bj][0] * acc[ai][bj][m][0], h1 = r1 + gv[bj][1] * acc[ai][bj][m][1];
;                     u32x4 w; w.x = cvt_pk_bf16(h0[0], h0[1]); w.y = cvt_pk_bf16(h0[2], h0[3]); w.z = cvt_pk_bf16(h1[0], h1[1]); w.w = cvt_pk_bf16(h1[2], h1[3]);
;                     *(u32x4*)(out + (size_t)(wr * 64 + fr + ai * 128 + m * 16) * DM + col0 + bj * 128) = w;
	v_cvt_pk_bf16_f32 v48, v52, v53
	v_lshlrev_b32_e32 v52, 16, v165
	v_cvt_pk_bf16_f32 v49, v54, v55
	v_cvt_pk_bf16_f32 v50, v50, v51
	v_cvt_pk_bf16_f32 v51, v56, v57
	global_store_dwordx4 v[64:65], v[48:51], off offset:256
	v_and_b32_e32 v53, 0xffff0000, v165
	v_lshlrev_b32_e32 v54, 16, v166
	v_lshlrev_b32_e32 v50, 16, v164
	v_and_b32_e32 v51, 0xffff0000, v164
	v_and_b32_e32 v55, 0xffff0000, v166
	v_lshlrev_b32_e32 v56, 16, v167
	v_and_b32_e32 v57, 0xffff0000, v167
	v_lshl_add_u64 v[48:49], v[222:223], 0, v[224:225]
	v_pk_fma_f32 v[46:47], v[46:47], v[142:143], v[52:53]
	v_pk_fma_f32 v[44:45], v[44:45], v[140:141], v[50:51]
	v_pk_fma_f32 v[50:51], v[42:43], v[138:139], v[56:57]
	v_pk_fma_f32 v[42:43], v[40:41], v[136:137], v[54:55]
	v_cvt_pk_bf16_f32 v40, v44, v45
	v_cvt_pk_bf16_f32 v41, v46, v47
	v_lshlrev_b32_e32 v44, 16, v162
	v_cvt_pk_bf16_f32 v42, v42, v43
	v_cvt_pk_bf16_f32 v43, v50, v51
	global_store_dwordx4 v[48:49], v[40:43], off
	v_and_b32_e32 v45, 0xffff0000, v162
	v_lshlrev_b32_e32 v46, 16, v163
	v_lshlrev_b32_e32 v40, 16, v160
	v_and_b32_e32 v41, 0xffff0000, v160
	v_and_b32_e32 v47, 0xffff0000, v163
	v_lshlrev_b32_e32 v42, 16, v161
	v_and_b32_e32 v43, 0xffff0000, v161
	v_pk_fma_f32 v[36:37], v[36:37], v[132:133], v[40:41]
	v_pk_fma_f32 v[40:41], v[34:35], v[130:131], v[46:47]
	v_pk_fma_f32 v[34:35], v[32:33], v[128:129], v[44:45]
	v_pk_fma_f32 v[38:39], v[38:39], v[134:135], v[42:43]
	v_cvt_pk_bf16_f32 v32, v36, v37
	v_lshlrev_b32_e32 v36, 16, v157
	v_cvt_pk_bf16_f32 v33, v38, v39
	v_cvt_pk_bf16_f32 v34, v34, v35
	v_cvt_pk_bf16_f32 v35, v40, v41
	global_store_dwordx4 v[48:49], v[32:35], off offset:256
	v_and_b32_e32 v37, 0xffff0000, v157
	v_lshlrev_b32_e32 v38, 16, v158
	v_lshlrev_b32_e32 v34, 16, v156
	v_and_b32_e32 v35, 0xffff0000, v156
	v_and_b32_e32 v39, 0xffff0000, v158
	v_lshlrev_b32_e32 v40, 16, v159
	v_and_b32_e32 v41, 0xffff0000, v159
	v_lshl_add_u64 v[32:33], v[222:223], 0, v[220:221]
	v_pk_fma_f32 v[30:31], v[30:31], v[142:143], v[36:37]
	v_pk_fma_f32 v[28:29], v[28:29], v[140:141], v[34:35]
	v_pk_fma_f32 v[34:35], v[26:27], v[138:139], v[40:41]
	v_pk_fma_f32 v[26:27], v[24:25], v[136:137], v[38:39]
	v_cvt_pk_bf16_f32 v24, v28, v29
	v_cvt_pk_bf16_f32 v25, v30, v31
	v_lshlrev_b32_e32 v28, 16, v154
	v_cvt_pk_bf16_f32 v26, v26, v27
	v_cvt_pk_bf16_f32 v27, v34, v35
	global_store_dwordx4 v[32:33], v[24:27], off
	v_and_b32_e32 v29, 0xffff0000, v154
	v_lshlrev_b32_e32 v30, 16, v155
	v_lshlrev_b32_e32 v24, 16, v152
	v_and_b32_e32 v25, 0xffff0000, v152
	v_and_b32_e32 v31, 0xffff0000, v155
	v_lshlrev_b32_e32 v26, 16, v153
	v_and_b32_e32 v27, 0xffff0000, v153
	v_pk_fma_f32 v[20:21], v[20:21], v[132:133], v[24:25]
	v_pk_fma_f32 v[24:25], v[18:19], v[130:131], v[30:31]
	v_pk_fma_f32 v[18:19], v[16:17], v[128:129], v[28:29]
	v_pk_fma_f32 v[22:23], v[22:23], v[134:135], v[26:27]
	v_cvt_pk_bf16_f32 v16, v20, v21
	v_lshlrev_b32_e32 v20, 16, v149
	v_cvt_pk_bf16_f32 v17, v22, v23
	v_cvt_pk_bf16_f32 v18, v18, v19
	v_cvt_pk_bf16_f32 v19, v24, v25
	global_store_dwordx4 v[32:33], v[16:19], off offset:256
	v_and_b32_e32 v21, 0xffff0000, v149
	v_lshlrev_b32_e32 v22, 16, v150
	v_lshlrev_b32_e32 v18, 16, v148
	v_and_b32_e32 v19, 0xffff0000, v148
	v_and_b32_e32 v23, 0xffff0000, v150
	v_lshlrev_b32_e32 v24, 16, v151
	v_and_b32_e32 v25, 0xffff0000, v151
	v_lshl_add_u64 v[16:17], v[222:223], 0, v[218:219]
	v_pk_fma_f32 v[14:15], v[14:15], v[142:143], v[20:21]
	v_pk_fma_f32 v[12:13], v[12:13], v[140:141], v[18:19]
	v_pk_fma_f32 v[18:19], v[10:11], v[138:139], v[24:25]
	v_pk_fma_f32 v[10:11], v[8:9], v[136:137], v[22:23]
	v_cvt_pk_bf16_f32 v8, v12, v13
	v_cvt_pk_bf16_f32 v9, v14, v15
	v_lshlrev_b32_e32 v12, 16, v146
	v_cvt_pk_bf16_f32 v10, v10, v11
	v_cvt_pk_bf16_f32 v11, v18, v19
	global_store_dwordx4 v[16:17], v[8:11], off
	v_and_b32_e32 v13, 0xffff0000, v146
	v_lshlrev_b32_e32 v14, 16, v147
	v_lshlrev_b32_e32 v8, 16, v144
	v_and_b32_e32 v9, 0xffff0000, v144
	v_and_b32_e32 v15, 0xffff0000, v147
	v_lshlrev_b32_e32 v10, 16, v145
	v_and_b32_e32 v11, 0xffff0000, v145
	v_pk_fma_f32 v[4:5], v[4:5], v[132:133], v[8:9]
	v_pk_fma_f32 v[8:9], v[2:3], v[130:131], v[14:15]
	v_pk_fma_f32 v[2:3], v[0:1], v[128:129], v[12:13]
	v_pk_fma_f32 v[6:7], v[6:7], v[134:135], v[10:11]
	v_cvt_pk_bf16_f32 v0, v4, v5
	s_nop 0
	v_cvt_pk_bf16_f32 v1, v6, v7
	v_cvt_pk_bf16_f32 v2, v2, v3
	v_cvt_pk_bf16_f32 v3, v8, v9
	global_store_dwordx4 v[16:17], v[0:3], off offset:256
	s_cbranch_vccz .LBB0_891
	s_waitcnt vmcnt(0)
	s_cmpk_gt_u32 s33, 0xff
	s_cbranch_scc1 .LBB0_906
	s_barrier

; #define PG8_STAGE(bufoff, gbase, voff) do { _Pragma("unroll") for (int _i = 0; _i < 2; ++_i) \
;         __builtin_amdgcn_global_load_lds((const unsigned*)((const char*)(gbase) + (voff)[_i]), (LAS unsigned*)(lds + (bufoff) + ldsw + _i * 8192), 16, 0, 0); } while (0)
; #define PG8_WAIT_V(n) asm volatile("s_waitcnt vmcnt(" #n ")" ::: "memory")
; #define PG8_WAIT_L(n) asm volatile("s_waitcnt lgkmcnt(" #n ")" ::: "memory")
; template <class Epi, class Sched>
; __device__ __forceinline__ void gemm_phase(LAS unsigned char* lds, const Gemm g, const Sched& S, const Epi& E) {
;     ...
;         const bool has_next = S.next(ui + 1, nxt);
;         const char* nA = has_next ? (const char*)g.A + (size_t)nxt.pm * tstep : cA; const char* nB = has_next ? (const char*)g.Bt + (size_t)nxt.pn * tstep : cB;
;         for (int t = 0; t < nt; t += 2) {
;             const bool last = (t == nt - 2);
;             const char* a1 = cA + (size_t)(t + 1) * kstep;
;             const char* a2 = last ? nA : cA + (size_t)(t + 2) * kstep; const char* b2 = last ? nB : cB + (size_t)(t + 2) * kstep;
;             const char* a3 = a2 + kstep; const char* b3 = b2 + kstep;
;             PG8_LDB(B0, 0, 0); PG8_SCHED; PG8_LDA(At, 0, 0); PG8_STAGE(PG8_SA(1, 1), a1 + hstep, voffA);
;             PG8_WAIT_L(8); PG8_BAR; PG8_WAIT_L(0); PG8_MMA(0, 0, At, B0); PG8_BAR; PG8_SCHED;
;             PG8_LDB(B1, 0, 1); PG8_STAGE(PG8_SB(0, 0), b2, voffB);
;             PG8_BAR; PG8_WAIT_L(0); PG8_MMA(0, 1, At, B1); PG8_BAR;
;             PG8_LDA(At, 0, 1); PG8_STAGE(PG8_SA(0, 0), a2, voffA);
;             PG8_BAR; PG8_WAIT_L(0); PG8_MMA(1, 0, At, B0); PG8_BAR; PG8_SCHED;
;             PG8_STAGE(PG8_SB(0, 1), b2 + hstep, voffB);
;             PG8_WAIT_V(6); PG8_BAR; PG8_MMA(1, 1, At, B1); PG8_BAR;
;             PG8_LDB(B0, 1, 0); PG8_SCHED; PG8_LDA(At, 1, 0); PG8_STAGE(PG8_SA(0, 1), a2 + hstep, voffA);
;             PG8_WAIT_L(8); PG8_BAR; PG8_WAIT_L(0); PG8_MMA(0, 0, At, B0); PG8_BAR; PG8_SCHED;
;             PG8_LDB(B1, 1, 1); PG8_STAGE(PG8_SB(1, 0), b3, voffB);
;             PG8_BAR; PG8_WAIT_L(0); PG8_MMA(0, 1, At, B1); PG8_BAR;
;             PG8_LDA(At, 1, 1); PG8_STAGE(PG8_SA(1, 0), a3, voffA);
;             PG8_BAR; PG8_WAIT_L(0); PG8_MMA(1, 0, At, B0); PG8_BAR; PG8_SCHED;
;             PG8_STAGE(PG8_SB(1, 1), b3 + hstep, voffB);
;             PG8_WAIT_V(6); PG8_BAR; PG8_MMA(1, 1, At, B1); PG8_BAR;
.LBB0_1020:
	s_ashr_i32 s7, s6, 31
	v_cmp_lt_i64_e32 vcc, s[10:11], v[140:141]
	s_lshl_b64 s[10:11], s[6:7], 19
	s_add_u32 s10, s96, s10
	s_addc_u32 s11, s97, s11
	s_and_b64 s[12:13], vcc, exec
	s_cselect_b32 s7, s11, s17
	s_cselect_b32 s42, s10, s16
	s_ashr_i32 s5, s4, 31
	s_lshl_b64 s[12:13], s[4:5], 19
	s_add_u32 s12, s23, s12
	s_addc_u32 s13, s24, s13
	s_and_b64 s[20:21], vcc, exec
	s_cselect_b32 s5, s13, s19
	s_cselect_b32 s43, s12, s18
	s_add_u32 s16, s16, 0x40080
	s_addc_u32 s17, s17, 0
	s_add_u32 s44, s18, 0x100
	s_addc_u32 s45, s19, 0
	s_mov_b32 s46, -2
	ds_read_b128 v[150:153], v147
	ds_read_b128 v[154:157], v147 offset:1024
	ds_read_b128 v[158:161], v147 offset:2048
	ds_read_b128 v[162:165], v147 offset:3072
	s_add_u32 s18, s16, 0xfffc0080
	s_addc_u32 s19, s17, -1
	s_cmp_eq_u32 s46, 12
	s_cselect_b32 s21, s7, s19
	s_cselect_b32 s20, s42, s18
	s_cselect_b32 s19, s5, s45
	s_cselect_b32 s18, s43, s44
	s_add_i32 m0, s15, 0xc000
	ds_read_b128 v[166:169], v148
	ds_read_b128 v[170:173], v148 offset:1024
	ds_read_b128 v[174:177], v148 offset:2048
	ds_read_b128 v[178:181], v148 offset:3072
	ds_read_b128 v[182:185], v148 offset:4096
	ds_read_b128 v[186:189], v148 offset:5120
	ds_read_b128 v[190:193], v148 offset:6144
	ds_read_b128 v[194:197], v148 offset:7168
	global_load_lds_dwordx4 v136, s[16:17]
	s_add_i32 m0, s15, 0xe000
	s_nop 0
	global_load_lds_dwordx4 v138, s[16:17]
	s_waitcnt lgkmcnt(8)
	s_waitcnt vmcnt(8)
	s_setprio 1
	s_barrier
	s_waitcnt lgkmcnt(0)
	v_mfma_f32_16x16x32_bf16 v[124:127], v[150:153], v[166:169], 0
	v_mfma_f32_16x16x32_bf16 v[116:119], v[158:161], v[166:169], 0
	v_mfma_f32_16x16x32_bf16 v[108:111], v[150:153], v[174:177], 0
	v_mfma_f32_16x16x32_bf16 v[100:103], v[158:161], v[174:177], 0
	v_mfma_f32_16x16x32_bf16 v[92:95], v[150:153], v[182:185], 0
	v_mfma_f32_16x16x32_bf16 v[84:87], v[158:161], v[182:185], 0
	v_mfma_f32_16x16x32_bf16 v[76:79], v[150:153], v[190:193], 0
	v_mfma_f32_16x16x32_bf16 v[68:71], v[158:161], v[190:193], 0
	v_mfma_f32_16x16x32_bf16 v[124:127], v[154:157], v[170:173], v[124:127]
	v_mfma_f32_16x16x32_bf16 v[116:119], v[162:165], v[170:173], v[116:119]
	v_mfma_f32_16x16x32_bf16 v[108:111], v[154:157], v[178:181], v[108:111]
	v_mfma_f32_16x16x32_bf16 v[100:103], v[162:165], v[178:181], v[100:103]
	v_mfma_f32_16x16x32_bf16 v[92:95], v[154:157], v[186:189], v[92:95]
	v_mfma_f32_16x16x32_bf16 v[84:87], v[162:165], v[186:189], v[84:87]
	v_mfma_f32_16x16x32_bf16 v[76:79], v[154:157], v[194:197], v[76:79]
	v_mfma_f32_16x16x32_bf16 v[68:71], v[162:165], v[194:197], v[68:71]
	s_barrier
	s_setprio 0
	s_add_i32 s47, s38, s25
	s_mov_b32 m0, s47
	ds_read_b128 v[202:205], v149
	ds_read_b128 v[206:209], v149 offset:1024
	ds_read_b128 v[210:213], v149 offset:2048
	ds_read_b128 v[214:217], v149 offset:3072
	global_load_lds_dwordx4 v132, s[18:19]
	s_add_i32 m0, s47, 0x2000
	s_nop 0
	global_load_lds_dwordx4 v128, s[18:19]
	s_waitcnt vmcnt(8)
	s_setprio 1
	s_barrier
	s_waitcnt lgkmcnt(0)
	v_mfma_f32_16x16x32_bf16 v[120:123], v[202:205], v[166:169], 0
	v_mfma_f32_16x16x32_bf16 v[112:115], v[210:213], v[166:169], 0
	v_mfma_f32_16x16x32_bf16 v[104:107], v[202:205], v[174:177], 0
	v_mfma_f32_16x16x32_bf16 v[96:99], v[210:213], v[174:177], 0
	v_mfma_f32_16x16x32_bf16 v[88:91], v[202:205], v[182:185], 0
	v_mfma_f32_16x16x32_bf16 v[80:83], v[210:213], v[182:185], 0
	v_mfma_f32_16x16x32_bf16 v[72:75], v[202:205], v[190:193], 0
	v_mfma_f32_16x16x32_bf16 v[64:67], v[210:213], v[190:193], 0
	v_mfma_f32_16x16x32_bf16 v[120:123], v[206:209], v[170:173], v[120:123]
	v_mfma_f32_16x16x32_bf16 v[112:115], v[214:217], v[170:173], v[112:115]
	v_mfma_f32_16x16x32_bf16 v[104:107], v[206:209], v[178:181], v[104:107]
	v_mfma_f32_16x16x32_bf16 v[96:99], v[214:217], v[178:181], v[96:99]
	v_mfma_f32_16x16x32_bf16 v[88:91], v[206:209], v[186:189], v[88:91]
	v_mfma_f32_16x16x32_bf16 v[80:83], v[214:217], v[186:189], v[80:83]
	v_mfma_f32_16x16x32_bf16 v[72:75], v[206:209], v[194:197], v[72:75]
	v_mfma_f32_16x16x32_bf16 v[64:67], v[214:217], v[194:197], v[64:67]
	s_barrier
	s_setprio 0
	s_mov_b32 m0, s15
	v_lshl_add_u64 v[220:221], s[20:21], 0, v[134:135]
	ds_read_b128 v[166:169], v148 offset:16384
	ds_read_b128 v[170:173], v148 offset:17408
	ds_read_b128 v[174:177], v148 offset:18432
	ds_read_b128 v[178:181], v148 offset:19456
	ds_read_b128 v[182:185], v148 offset:20480
	ds_read_b128 v[186:189], v148 offset:21504
	ds_read_b128 v[190:193], v148 offset:22528
	ds_read_b128 v[194:197], v148 offset:23552
	global_load_lds_dwordx4 v134, s[20:21]
	v_lshl_add_u64 v[222:223], s[20:21], 0, v[130:131]
	s_mov_b32 m0, s28
	s_nop 0
	global_load_lds_dwordx4 v130, s[20:21]
	s_setprio 1
	s_barrier
	s_waitcnt lgkmcnt(0)
	v_mfma_f32_16x16x32_bf16 v[60:63], v[150:153], v[166:169], 0
	v_mfma_f32_16x16x32_bf16 v[56:59], v[158:161], v[166:169], 0
	v_mfma_f32_16x16x32_bf16 v[44:47], v[150:153], v[174:177], 0
	v_mfma_f32_16x16x32_bf16 v[40:43], v[158:161], v[174:177], 0
	v_mfma_f32_16x16x32_bf16 v[28:31], v[150:153], v[182:185], 0
	v_mfma_f32_16x16x32_bf16 v[24:27], v[158:161], v[182:185], 0
	v_mfma_f32_16x16x32_bf16 v[12:15], v[150:153], v[190:193], 0
	v_mfma_f32_16x16x32_bf16 v[8:11], v[158:161], v[190:193], 0
	v_mfma_f32_16x16x32_bf16 v[60:63], v[154:157], v[170:173], v[60:63]
	v_mfma_f32_16x16x32_bf16 v[56:59], v[162:165], v[170:173], v[56:59]
	v_mfma_f32_16x16x32_bf16 v[44:47], v[154:157], v[178:181], v[44:47]
	v_mfma_f32_16x16x32_bf16 v[40:43], v[162:165], v[178:181], v[40:43]
	v_mfma_f32_16x16x32_bf16 v[28:31], v[154:157], v[186:189], v[28:31]
	v_mfma_f32_16x16x32_bf16 v[24:27], v[162:165], v[186:189], v[24:27]
	v_mfma_f32_16x16x32_bf16 v[12:15], v[154:157], v[194:197], v[12:15]
	v_mfma_f32_16x16x32_bf16 v[8:11], v[162:165], v[194:197], v[8:11]
	s_barrier
; #define PG8_STAGE(bufoff, gbase, voff) do { _Pragma("unroll") for (int _i = 0; _i < 2; ++_i) \
;         __builtin_amdgcn_global_load_lds((const unsigned*)((const char*)(gbase) + (voff)[_i]), (LAS unsigned*)(lds + (bufoff) + ldsw + _i * 8192), 16, 0, 0); } while (0)
; #define PG8_LDA(dst, b, h) do { _Pragma("unroll") for (int m = 0; m < 4; ++m) _Pragma("unroll") for (int k = 0; k < 2; ++k) dst[m][k] = *(const LAS bf16x8*)(lds + PG8_SA(b, h) + aoff + m * 2048 + k * 1024); } while (0)
; #define PG8_WAIT_V(n) asm volatile("s_waitcnt vmcnt(" #n ")" ::: "memory")
; #define PG8_WAIT_L(n) asm volatile("s_waitcnt lgkmcnt(" #n ")" ::: "memory")
; template <class Epi, class Sched>
; __device__ __forceinline__ void gemm_phase(LAS unsigned char* lds, const Gemm g, const Sched& S, const Epi& E) {
;     ...
;         for (int t = 0; t < nt; t += 2) {
;             const bool last = (t == nt - 2);
;             const char* a1 = cA + (size_t)(t + 1) * kstep;
;             const char* a2 = last ? nA : cA + (size_t)(t + 2) * kstep; const char* b2 = last ? nB : cB + (size_t)(t + 2) * kstep;
;             const char* a3 = a2 + kstep; const char* b3 = b2 + kstep;
;             PG8_LDB(B0, 0, 0); PG8_SCHED; PG8_LDA(At, 0, 0); PG8_STAGE(PG8_SA(1, 1), a1 + hstep, voffA);
;             PG8_WAIT_L(8); PG8_BAR; PG8_WAIT_L(0); PG8_MMA(0, 0, At, B0); PG8_BAR; PG8_SCHED;
;             PG8_LDB(B1, 0, 1); PG8_STAGE(PG8_SB(0, 0), b2, voffB);
;             PG8_BAR; PG8_WAIT_L(0); PG8_MMA(0, 1, At, B1); PG8_BAR;
;             PG8_LDA(At, 0, 1); PG8_STAGE(PG8_SA(0, 0), a2, voffA);
;             PG8_BAR; PG8_WAIT_L(0); PG8_MMA(1, 0, At, B0); PG8_BAR; PG8_SCHED;
;             PG8_STAGE(PG8_SB(0, 1), b2 + hstep, voffB);
;             PG8_WAIT_V(6); PG8_BAR; PG8_MMA(1, 1, At, B1); PG8_BAR;
;             PG8_LDB(B0, 1, 0); PG8_SCHED; PG8_LDA(At, 1, 0); PG8_STAGE(PG8_SA(0, 1), a2 + hstep, voffA);
;             PG8_WAIT_L(8); PG8_BAR; PG8_WAIT_L(0); PG8_MMA(0, 0, At, B0); PG8_BAR; PG8_SCHED;
;             PG8_LDB(B1, 1, 1); PG8_STAGE(PG8_SB(1, 0), b3, voffB);
;             PG8_BAR; PG8_WAIT_L(0); PG8_MMA(0, 1, At, B1); PG8_BAR;
;             PG8_LDA(At, 1, 1); PG8_STAGE(PG8_SA(1, 0), a3, voffA);
;             PG8_BAR; PG8_WAIT_L(0); PG8_MMA(1, 0, At, B0); PG8_BAR; PG8_SCHED;
;             PG8_STAGE(PG8_SB(1, 1), b3 + hstep, voffB);
;             PG8_WAIT_V(6); PG8_BAR; PG8_MMA(1, 1, At, B1); PG8_BAR;
	s_setprio 0
	s_add_u32 s48, s18, 0x40000
	s_addc_u32 s49, s19, 0
	s_add_i32 s47, s39, s25
	s_mov_b32 m0, s47
	s_nop 0
	global_load_lds_dwordx4 v132, s[48:49]
	s_add_i32 m0, s47, 0x2000
	s_nop 0
	global_load_lds_dwordx4 v128, s[48:49]
	s_add_u32 s20, s20, 0x40000
	s_addc_u32 s21, s21, 0
	s_mov_b32 m0, s29
	s_nop 0
	global_load_lds_dwordx4 v134, s[20:21]
	s_mov_b32 m0, s30
	s_nop 0
	global_load_lds_dwordx4 v130, s[20:21]
	s_waitcnt vmcnt(10)
	s_setprio 1
	s_barrier
	v_mfma_f32_16x16x32_bf16 v[52:55], v[202:205], v[166:169], 0
	v_mfma_f32_16x16x32_bf16 v[48:51], v[210:213], v[166:169], 0
	v_mfma_f32_16x16x32_bf16 v[36:39], v[202:205], v[174:177], 0
	v_mfma_f32_16x16x32_bf16 v[32:35], v[210:213], v[174:177], 0
	v_mfma_f32_16x16x32_bf16 v[20:23], v[202:205], v[182:185], 0
	v_mfma_f32_16x16x32_bf16 v[16:19], v[210:213], v[182:185], 0
	v_mfma_f32_16x16x32_bf16 v[4:7], v[202:205], v[190:193], 0
	v_mfma_f32_16x16x32_bf16 v[0:3], v[210:213], v[190:193], 0
	v_mfma_f32_16x16x32_bf16 v[52:55], v[206:209], v[170:173], v[52:55]
	v_mfma_f32_16x16x32_bf16 v[48:51], v[214:217], v[170:173], v[48:51]
	v_mfma_f32_16x16x32_bf16 v[36:39], v[206:209], v[178:181], v[36:39]
	v_mfma_f32_16x16x32_bf16 v[32:35], v[214:217], v[178:181], v[32:35]
	v_mfma_f32_16x16x32_bf16 v[20:23], v[206:209], v[186:189], v[20:23]
	v_mfma_f32_16x16x32_bf16 v[16:19], v[214:217], v[186:189], v[16:19]
	v_mfma_f32_16x16x32_bf16 v[4:7], v[206:209], v[194:197], v[4:7]
	v_mfma_f32_16x16x32_bf16 v[0:3], v[214:217], v[194:197], v[0:3]
	s_barrier
	s_setprio 0
	s_add_i32 s47, 0, 0x18000
	v_add_u32_e32 v162, s47, v146
	ds_read_b128 v[150:153], v162
	ds_read_b128 v[154:157], v162 offset:1024
	ds_read_b128 v[158:161], v162 offset:2048
	ds_read_b128 v[162:165], v162 offset:3072
	ds_read_b128 v[166:169], v148 offset:32768
	ds_read_b128 v[170:173], v148 offset:33792
	ds_read_b128 v[174:177], v148 offset:34816
	ds_read_b128 v[178:181], v148 offset:35840
	ds_read_b128 v[182:185], v148 offset:36864
	ds_read_b128 v[186:189], v148 offset:37888
	ds_read_b128 v[190:193], v148 offset:38912
	ds_read_b128 v[194:197], v148 offset:39936
	s_waitcnt lgkmcnt(8)
	s_waitcnt vmcnt(8)
	s_setprio 1
	s_barrier
	s_waitcnt lgkmcnt(0)
	v_mfma_f32_16x16x32_bf16 v[124:127], v[150:153], v[166:169], v[124:127]
	v_mfma_f32_16x16x32_bf16 v[116:119], v[158:161], v[166:169], v[116:119]
	v_mfma_f32_16x16x32_bf16 v[108:111], v[150:153], v[174:177], v[108:111]
	v_mfma_f32_16x16x32_bf16 v[100:103], v[158:161], v[174:177], v[100:103]
	v_mfma_f32_16x16x32_bf16 v[92:95], v[150:153], v[182:185], v[92:95]
	v_mfma_f32_16x16x32_bf16 v[84:87], v[158:161], v[182:185], v[84:87]
	v_mfma_f32_16x16x32_bf16 v[76:79], v[150:153], v[190:193], v[76:79]
	v_mfma_f32_16x16x32_bf16 v[68:71], v[158:161], v[190:193], v[68:71]
	v_mfma_f32_16x16x32_bf16 v[124:127], v[154:157], v[170:173], v[124:127]
	v_mfma_f32_16x16x32_bf16 v[116:119], v[162:165], v[170:173], v[116:119]
	v_mfma_f32_16x16x32_bf16 v[108:111], v[154:157], v[178:181], v[108:111]
	v_mfma_f32_16x16x32_bf16 v[100:103], v[162:165], v[178:181], v[100:103]
	v_mfma_f32_16x16x32_bf16 v[92:95], v[154:157], v[186:189], v[92:95]
	v_mfma_f32_16x16x32_bf16 v[84:87], v[162:165], v[186:189], v[84:87]
	v_mfma_f32_16x16x32_bf16 v[76:79], v[154:157], v[194:197], v[76:79]
	v_mfma_f32_16x16x32_bf16 v[68:71], v[162:165], v[194:197], v[68:71]
	s_barrier
	s_setprio 0
	s_add_i32 s20, 0, 0x1c000
	s_add_i32 s21, s47, s25
	v_add_u32_e32 v214, s20, v146
	s_add_u32 s0, s18, 0x80
	s_addc_u32 s1, s19, 0
	s_mov_b32 m0, s21
	ds_read_b128 v[202:205], v214
	ds_read_b128 v[206:209], v214 offset:1024
	ds_read_b128 v[210:213], v214 offset:2048
	ds_read_b128 v[214:217], v214 offset:3072
	global_load_lds_dwordx4 v132, s[0:1]
	s_add_i32 m0, s21, 0x2000
	s_nop 0
	global_load_lds_dwordx4 v128, s[0:1]
	s_waitcnt vmcnt(8)
	s_setprio 1
	s_barrier
	s_waitcnt lgkmcnt(0)
	v_mfma_f32_16x16x32_bf16 v[120:123], v[202:205], v[166:169], v[120:123]
	v_mfma_f32_16x16x32_bf16 v[112:115], v[210:213], v[166:169], v[112:115]
	v_mfma_f32_16x16x32_bf16 v[104:107], v[202:205], v[174:177], v[104:107]
	v_mfma_f32_16x16x32_bf16 v[96:99], v[210:213], v[174:177], v[96:99]
	v_mfma_f32_16x16x32_bf16 v[88:91], v[202:205], v[182:185], v[88:91]
	v_mfma_f32_16x16x32_bf16 v[80:83], v[210:213], v[182:185], v[80:83]
	v_mfma_f32_16x16x32_bf16 v[72:75], v[202:205], v[190:193], v[72:75]
	v_mfma_f32_16x16x32_bf16 v[64:67], v[210:213], v[190:193], v[64:67]
	v_mfma_f32_16x16x32_bf16 v[120:123], v[206:209], v[170:173], v[120:123]
	v_mfma_f32_16x16x32_bf16 v[112:115], v[214:217], v[170:173], v[112:115]
	v_mfma_f32_16x16x32_bf16 v[104:107], v[206:209], v[178:181], v[104:107]
	v_mfma_f32_16x16x32_bf16 v[96:99], v[214:217], v[178:181], v[96:99]
	v_mfma_f32_16x16x32_bf16 v[88:91], v[206:209], v[186:189], v[88:91]
	v_mfma_f32_16x16x32_bf16 v[80:83], v[214:217], v[186:189], v[80:83]
	v_mfma_f32_16x16x32_bf16 v[72:75], v[206:209], v[194:197], v[72:75]
	v_mfma_f32_16x16x32_bf16 v[64:67], v[214:217], v[194:197], v[64:67]
	s_barrier
	s_setprio 0
	s_mov_b32 m0, s35
	s_mov_b64 s[0:1], 0x80
	v_lshl_add_u64 v[198:199], v[220:221], 0, s[0:1]
	ds_read_b128 v[166:169], v148 offset:49152
	ds_read_b128 v[170:173], v148 offset:50176
	ds_read_b128 v[174:177], v148 offset:51200
	ds_read_b128 v[178:181], v148 offset:52224
	ds_read_b128 v[182:185], v148 offset:53248
	ds_read_b128 v[186:189], v148 offset:54272
	ds_read_b128 v[190:193], v148 offset:55296
	ds_read_b128 v[194:197], v148 offset:56320
	global_load_lds_dwordx4 v[198:199], off
	v_lshl_add_u64 v[198:199], v[222:223], 0, s[0:1]
	s_mov_b32 m0, s36
	s_nop 0
	global_load_lds_dwordx4 v[198:199], off
	s_setprio 1
	s_barrier
; #define PG8_STAGE(bufoff, gbase, voff) do { _Pragma("unroll") for (int _i = 0; _i < 2; ++_i) \
;         __builtin_amdgcn_global_load_lds((const unsigned*)((const char*)(gbase) + (voff)[_i]), (LAS unsigned*)(lds + (bufoff) + ldsw + _i * 8192), 16, 0, 0); } while (0)
; #define PG8_LDA(dst, b, h) do { _Pragma("unroll") for (int m = 0; m < 4; ++m) _Pragma("unroll") for (int k = 0; k < 2; ++k) dst[m][k] = *(const LAS bf16x8*)(lds + PG8_SA(b, h) + aoff + m * 2048 + k * 1024); } while (0)
; #define PG8_WAIT_V(n) asm volatile("s_waitcnt vmcnt(" #n ")" ::: "memory")
; #define PG8_WAIT_L(n) asm volatile("s_waitcnt lgkmcnt(" #n ")" ::: "memory")
; template <class Epi, class Sched>
; __device__ __forceinline__ void gemm_phase(LAS unsigned char* lds, const Gemm g, const Sched& S, const Epi& E) {
;     ...
;         for (int t = 0; t < nt; t += 2) {
;             const bool last = (t == nt - 2);
;             const char* a1 = cA + (size_t)(t + 1) * kstep;
;             const char* a2 = last ? nA : cA + (size_t)(t + 2) * kstep; const char* b2 = last ? nB : cB + (size_t)(t + 2) * kstep;
;             const char* a3 = a2 + kstep; const char* b3 = b2 + kstep;
;             PG8_LDB(B0, 0, 0); PG8_SCHED; PG8_LDA(At, 0, 0); PG8_STAGE(PG8_SA(1, 1), a1 + hstep, voffA);
;             PG8_WAIT_L(8); PG8_BAR; PG8_WAIT_L(0); PG8_MMA(0, 0, At, B0); PG8_BAR; PG8_SCHED;
;             PG8_LDB(B1, 0, 1); PG8_STAGE(PG8_SB(0, 0), b2, voffB);
;             PG8_BAR; PG8_WAIT_L(0); PG8_MMA(0, 1, At, B1); PG8_BAR;
;             PG8_LDA(At, 0, 1); PG8_STAGE(PG8_SA(0, 0), a2, voffA);
;             PG8_BAR; PG8_WAIT_L(0); PG8_MMA(1, 0, At, B0); PG8_BAR; PG8_SCHED;
;             PG8_STAGE(PG8_SB(0, 1), b2 + hstep, voffB);
;             PG8_WAIT_V(6); PG8_BAR; PG8_MMA(1, 1, At, B1); PG8_BAR;
;             PG8_LDB(B0, 1, 0); PG8_SCHED; PG8_LDA(At, 1, 0); PG8_STAGE(PG8_SA(0, 1), a2 + hstep, voffA);
;             PG8_WAIT_L(8); PG8_BAR; PG8_WAIT_L(0); PG8_MMA(0, 0, At, B0); PG8_BAR; PG8_SCHED;
;             PG8_LDB(B1, 1, 1); PG8_STAGE(PG8_SB(1, 0), b3, voffB);
;             PG8_BAR; PG8_WAIT_L(0); PG8_MMA(0, 1, At, B1); PG8_BAR;
;             PG8_LDA(At, 1, 1); PG8_STAGE(PG8_SA(1, 0), a3, voffA);
;             PG8_BAR; PG8_WAIT_L(0); PG8_MMA(1, 0, At, B0); PG8_BAR; PG8_SCHED;
;             PG8_STAGE(PG8_SB(1, 1), b3 + hstep, voffB);
;             PG8_WAIT_V(6); PG8_BAR; PG8_MMA(1, 1, At, B1); PG8_BAR;
	s_waitcnt lgkmcnt(0)
	v_mfma_f32_16x16x32_bf16 v[60:63], v[150:153], v[166:169], v[60:63]
	v_mfma_f32_16x16x32_bf16 v[56:59], v[158:161], v[166:169], v[56:59]
	v_mfma_f32_16x16x32_bf16 v[44:47], v[150:153], v[174:177], v[44:47]
	v_mfma_f32_16x16x32_bf16 v[40:43], v[158:161], v[174:177], v[40:43]
	v_mfma_f32_16x16x32_bf16 v[28:31], v[150:153], v[182:185], v[28:31]
	v_mfma_f32_16x16x32_bf16 v[24:27], v[158:161], v[182:185], v[24:27]
	v_mfma_f32_16x16x32_bf16 v[12:15], v[150:153], v[190:193], v[12:15]
	v_mfma_f32_16x16x32_bf16 v[8:11], v[158:161], v[190:193], v[8:11]
	v_mfma_f32_16x16x32_bf16 v[60:63], v[154:157], v[170:173], v[60:63]
	v_mfma_f32_16x16x32_bf16 v[56:59], v[162:165], v[170:173], v[56:59]
	v_mfma_f32_16x16x32_bf16 v[44:47], v[154:157], v[178:181], v[44:47]
	v_mfma_f32_16x16x32_bf16 v[40:43], v[162:165], v[178:181], v[40:43]
	v_mfma_f32_16x16x32_bf16 v[28:31], v[154:157], v[186:189], v[28:31]
	v_mfma_f32_16x16x32_bf16 v[24:27], v[162:165], v[186:189], v[24:27]
	v_mfma_f32_16x16x32_bf16 v[12:15], v[154:157], v[194:197], v[12:15]
	v_mfma_f32_16x16x32_bf16 v[8:11], v[162:165], v[194:197], v[8:11]
	s_barrier
	s_setprio 0
	s_add_u32 s18, s18, 0x40080
	s_addc_u32 s19, s19, 0
	s_add_i32 s20, s20, s25
	s_mov_b32 m0, s20
	s_nop 0
	global_load_lds_dwordx4 v132, s[18:19]
	s_add_i32 m0, s20, 0x2000
	s_nop 0
	global_load_lds_dwordx4 v128, s[18:19]
	s_waitcnt vmcnt(8)
	s_setprio 1
	s_barrier
	v_mfma_f32_16x16x32_bf16 v[52:55], v[202:205], v[166:169], v[52:55]
	v_mfma_f32_16x16x32_bf16 v[48:51], v[210:213], v[166:169], v[48:51]
	v_mfma_f32_16x16x32_bf16 v[36:39], v[202:205], v[174:177], v[36:39]
	v_mfma_f32_16x16x32_bf16 v[32:35], v[210:213], v[174:177], v[32:35]
	v_mfma_f32_16x16x32_bf16 v[20:23], v[202:205], v[182:185], v[20:23]
	v_mfma_f32_16x16x32_bf16 v[16:19], v[210:213], v[182:185], v[16:19]
	v_mfma_f32_16x16x32_bf16 v[4:7], v[202:205], v[190:193], v[4:7]
	v_mfma_f32_16x16x32_bf16 v[0:3], v[210:213], v[190:193], v[0:3]
	v_mfma_f32_16x16x32_bf16 v[52:55], v[206:209], v[170:173], v[52:55]
	v_mfma_f32_16x16x32_bf16 v[48:51], v[214:217], v[170:173], v[48:51]
	v_mfma_f32_16x16x32_bf16 v[36:39], v[206:209], v[178:181], v[36:39]
	v_mfma_f32_16x16x32_bf16 v[32:35], v[214:217], v[178:181], v[32:35]
	v_mfma_f32_16x16x32_bf16 v[20:23], v[206:209], v[186:189], v[20:23]
	v_mfma_f32_16x16x32_bf16 v[16:19], v[214:217], v[186:189], v[16:19]
	v_mfma_f32_16x16x32_bf16 v[4:7], v[206:209], v[194:197], v[4:7]
	v_mfma_f32_16x16x32_bf16 v[0:3], v[214:217], v[194:197], v[0:3]
	s_barrier
	s_setprio 0
	s_add_i32 s46, s46, 2
	s_add_u32 s16, s16, 0x100
	s_addc_u32 s17, s17, 0
	s_add_u32 s44, s44, 0x100
	s_addc_u32 s45, s45, 0
	s_cmp_gt_u32 s46, 13
.LBB0_1021:
	ds_read_b128 v[150:153], v147
	ds_read_b128 v[154:157], v147 offset:1024
	ds_read_b128 v[158:161], v147 offset:2048
	ds_read_b128 v[162:165], v147 offset:3072
	s_add_u32 s18, s16, 0xfffc0080
	s_addc_u32 s19, s17, -1
	s_cmp_eq_u32 s46, 12
	s_cselect_b32 s21, s7, s19
	s_cselect_b32 s20, s42, s18
	s_cselect_b32 s19, s5, s45
	s_cselect_b32 s18, s43, s44
	s_add_i32 m0, s15, 0xc000
	ds_read_b128 v[166:169], v148
	ds_read_b128 v[170:173], v148 offset:1024
	ds_read_b128 v[174:177], v148 offset:2048
	ds_read_b128 v[178:181], v148 offset:3072
	ds_read_b128 v[182:185], v148 offset:4096
	ds_read_b128 v[186:189], v148 offset:5120
	ds_read_b128 v[190:193], v148 offset:6144
	ds_read_b128 v[194:197], v148 offset:7168
	global_load_lds_dwordx4 v136, s[16:17]
	s_add_i32 m0, s15, 0xe000
	s_nop 0
	global_load_lds_dwordx4 v138, s[16:17]
	s_waitcnt lgkmcnt(8)
	s_waitcnt vmcnt(8)
	s_setprio 1
	s_barrier
	s_waitcnt lgkmcnt(0)
	v_mfma_f32_16x16x32_bf16 v[124:127], v[150:153], v[166:169], v[124:127]
	v_mfma_f32_16x16x32_bf16 v[116:119], v[158:161], v[166:169], v[116:119]
	v_mfma_f32_16x16x32_bf16 v[108:111], v[150:153], v[174:177], v[108:111]
	v_mfma_f32_16x16x32_bf16 v[100:103], v[158:161], v[174:177], v[100:103]
	v_mfma_f32_16x16x32_bf16 v[92:95], v[150:153], v[182:185], v[92:95]
	v_mfma_f32_16x16x32_bf16 v[84:87], v[158:161], v[182:185], v[84:87]
	v_mfma_f32_16x16x32_bf16 v[76:79], v[150:153], v[190:193], v[76:79]
	v_mfma_f32_16x16x32_bf16 v[68:71], v[158:161], v[190:193], v[68:71]
	v_mfma_f32_16x16x32_bf16 v[124:127], v[154:157], v[170:173], v[124:127]
	v_mfma_f32_16x16x32_bf16 v[116:119], v[162:165], v[170:173], v[116:119]
	v_mfma_f32_16x16x32_bf16 v[108:111], v[154:157], v[178:181], v[108:111]
	v_mfma_f32_16x16x32_bf16 v[100:103], v[162:165], v[178:181], v[100:103]
	v_mfma_f32_16x16x32_bf16 v[92:95], v[154:157], v[186:189], v[92:95]
	v_mfma_f32_16x16x32_bf16 v[84:87], v[162:165], v[186:189], v[84:87]
	v_mfma_f32_16x16x32_bf16 v[76:79], v[154:157], v[194:197], v[76:79]
	v_mfma_f32_16x16x32_bf16 v[68:71], v[162:165], v[194:197], v[68:71]
	s_barrier
	s_setprio 0
	s_add_i32 s47, s38, s25
	s_mov_b32 m0, s47
	ds_read_b128 v[202:205], v149
	ds_read_b128 v[206:209], v149 offset:1024
	ds_read_b128 v[210:213], v149 offset:2048
	ds_read_b128 v[214:217], v149 offset:3072
	global_load_lds_dwordx4 v132, s[18:19]
	s_add_i32 m0, s47, 0x2000
	s_nop 0
	global_load_lds_dwordx4 v128, s[18:19]
	s_waitcnt vmcnt(8)
	s_setprio 1
	s_barrier
; #define PG8_STAGE(bufoff, gbase, voff) do { _Pragma("unroll") for (int _i = 0; _i < 2; ++_i) \
;         __builtin_amdgcn_global_load_lds((const unsigned*)((const char*)(gbase) + (voff)[_i]), (LAS unsigned*)(lds + (bufoff) + ldsw + _i * 8192), 16, 0, 0); } while (0)
; #define PG8_LDA(dst, b, h) do { _Pragma("unroll") for (int m = 0; m < 4; ++m) _Pragma("unroll") for (int k = 0; k < 2; ++k) dst[m][k] = *(const LAS bf16x8*)(lds + PG8_SA(b, h) + aoff + m * 2048 + k * 1024); } while (0)
; #define PG8_WAIT_V(n) asm volatile("s_waitcnt vmcnt(" #n ")" ::: "memory")
; #define PG8_WAIT_L(n) asm volatile("s_waitcnt lgkmcnt(" #n ")" ::: "memory")
; template <class Epi, class Sched>
; __device__ __forceinline__ void gemm_phase(LAS unsigned char* lds, const Gemm g, const Sched& S, const Epi& E) {
;     ...
;         for (int t = 0; t < nt; t += 2) {
;             const bool last = (t == nt - 2);
;             const char* a1 = cA + (size_t)(t + 1) * kstep;
;             const char* a2 = last ? nA : cA + (size_t)(t + 2) * kstep; const char* b2 = last ? nB : cB + (size_t)(t + 2) * kstep;
;             const char* a3 = a2 + kstep; const char* b3 = b2 + kstep;
;             PG8_LDB(B0, 0, 0); PG8_SCHED; PG8_LDA(At, 0, 0); PG8_STAGE(PG8_SA(1, 1), a1 + hstep, voffA);
;             PG8_WAIT_L(8); PG8_BAR; PG8_WAIT_L(0); PG8_MMA(0, 0, At, B0); PG8_BAR; PG8_SCHED;
;             PG8_LDB(B1, 0, 1); PG8_STAGE(PG8_SB(0, 0), b2, voffB);
;             PG8_BAR; PG8_WAIT_L(0); PG8_MMA(0, 1, At, B1); PG8_BAR;
;             PG8_LDA(At, 0, 1); PG8_STAGE(PG8_SA(0, 0), a2, voffA);
;             PG8_BAR; PG8_WAIT_L(0); PG8_MMA(1, 0, At, B0); PG8_BAR; PG8_SCHED;
;             PG8_STAGE(PG8_SB(0, 1), b2 + hstep, voffB);
;             PG8_WAIT_V(6); PG8_BAR; PG8_MMA(1, 1, At, B1); PG8_BAR;
;             PG8_LDB(B0, 1, 0); PG8_SCHED; PG8_LDA(At, 1, 0); PG8_STAGE(PG8_SA(0, 1), a2 + hstep, voffA);
;             PG8_WAIT_L(8); PG8_BAR; PG8_WAIT_L(0); PG8_MMA(0, 0, At, B0); PG8_BAR; PG8_SCHED;
;             PG8_LDB(B1, 1, 1); PG8_STAGE(PG8_SB(1, 0), b3, voffB);
;             PG8_BAR; PG8_WAIT_L(0); PG8_MMA(0, 1, At, B1); PG8_BAR;
;             PG8_LDA(At, 1, 1); PG8_STAGE(PG8_SA(1, 0), a3, voffA);
;             PG8_BAR; PG8_WAIT_L(0); PG8_MMA(1, 0, At, B0); PG8_BAR; PG8_SCHED;
;             PG8_STAGE(PG8_SB(1, 1), b3 + hstep, voffB);
;             PG8_WAIT_V(6); PG8_BAR; PG8_MMA(1, 1, At, B1); PG8_BAR;
	s_waitcnt lgkmcnt(0)
	v_mfma_f32_16x16x32_bf16 v[120:123], v[202:205], v[166:169], v[120:123]
	v_mfma_f32_16x16x32_bf16 v[112:115], v[210:213], v[166:169], v[112:115]
	v_mfma_f32_16x16x32_bf16 v[104:107], v[202:205], v[174:177], v[104:107]
	v_mfma_f32_16x16x32_bf16 v[96:99], v[210:213], v[174:177], v[96:99]
	v_mfma_f32_16x16x32_bf16 v[88:91], v[202:205], v[182:185], v[88:91]
	v_mfma_f32_16x16x32_bf16 v[80:83], v[210:213], v[182:185], v[80:83]
	v_mfma_f32_16x16x32_bf16 v[72:75], v[202:205], v[190:193], v[72:75]
	v_mfma_f32_16x16x32_bf16 v[64:67], v[210:213], v[190:193], v[64:67]
	v_mfma_f32_16x16x32_bf16 v[120:123], v[206:209], v[170:173], v[120:123]
	v_mfma_f32_16x16x32_bf16 v[112:115], v[214:217], v[170:173], v[112:115]
	v_mfma_f32_16x16x32_bf16 v[104:107], v[206:209], v[178:181], v[104:107]
	v_mfma_f32_16x16x32_bf16 v[96:99], v[214:217], v[178:181], v[96:99]
	v_mfma_f32_16x16x32_bf16 v[88:91], v[206:209], v[186:189], v[88:91]
	v_mfma_f32_16x16x32_bf16 v[80:83], v[214:217], v[186:189], v[80:83]
	v_mfma_f32_16x16x32_bf16 v[72:75], v[206:209], v[194:197], v[72:75]
	v_mfma_f32_16x16x32_bf16 v[64:67], v[214:217], v[194:197], v[64:67]
	s_barrier
	s_setprio 0
	s_mov_b32 m0, s15
	v_lshl_add_u64 v[220:221], s[20:21], 0, v[134:135]
	ds_read_b128 v[166:169], v148 offset:16384
	ds_read_b128 v[170:173], v148 offset:17408
	ds_read_b128 v[174:177], v148 offset:18432
	ds_read_b128 v[178:181], v148 offset:19456
	ds_read_b128 v[182:185], v148 offset:20480
	ds_read_b128 v[186:189], v148 offset:21504
	ds_read_b128 v[190:193], v148 offset:22528
	ds_read_b128 v[194:197], v148 offset:23552
	global_load_lds_dwordx4 v134, s[20:21]
	v_lshl_add_u64 v[222:223], s[20:21], 0, v[130:131]
	s_mov_b32 m0, s28
	s_nop 0
	global_load_lds_dwordx4 v130, s[20:21]
	s_setprio 1
	s_barrier
	s_waitcnt lgkmcnt(0)
	v_mfma_f32_16x16x32_bf16 v[60:63], v[150:153], v[166:169], v[60:63]
	v_mfma_f32_16x16x32_bf16 v[56:59], v[158:161], v[166:169], v[56:59]
	v_mfma_f32_16x16x32_bf16 v[44:47], v[150:153], v[174:177], v[44:47]
	v_mfma_f32_16x16x32_bf16 v[40:43], v[158:161], v[174:177], v[40:43]
	v_mfma_f32_16x16x32_bf16 v[28:31], v[150:153], v[182:185], v[28:31]
	v_mfma_f32_16x16x32_bf16 v[24:27], v[158:161], v[182:185], v[24:27]
	v_mfma_f32_16x16x32_bf16 v[12:15], v[150:153], v[190:193], v[12:15]
	v_mfma_f32_16x16x32_bf16 v[8:11], v[158:161], v[190:193], v[8:11]
	v_mfma_f32_16x16x32_bf16 v[60:63], v[154:157], v[170:173], v[60:63]
	v_mfma_f32_16x16x32_bf16 v[56:59], v[162:165], v[170:173], v[56:59]
	v_mfma_f32_16x16x32_bf16 v[44:47], v[154:157], v[178:181], v[44:47]
	v_mfma_f32_16x16x32_bf16 v[40:43], v[162:165], v[178:181], v[40:43]
	v_mfma_f32_16x16x32_bf16 v[28:31], v[154:157], v[186:189], v[28:31]
	v_mfma_f32_16x16x32_bf16 v[24:27], v[162:165], v[186:189], v[24:27]
	v_mfma_f32_16x16x32_bf16 v[12:15], v[154:157], v[194:197], v[12:15]
	v_mfma_f32_16x16x32_bf16 v[8:11], v[162:165], v[194:197], v[8:11]
	s_barrier
	s_setprio 0
	s_add_u32 s48, s18, 0x40000
	s_addc_u32 s49, s19, 0
	s_add_i32 s47, s39, s25
	s_mov_b32 m0, s47
	s_nop 0
	global_load_lds_dwordx4 v132, s[48:49]
	s_add_i32 m0, s47, 0x2000
	s_nop 0
	global_load_lds_dwordx4 v128, s[48:49]
	s_add_u32 s20, s20, 0x40000
	s_addc_u32 s21, s21, 0
	s_mov_b32 m0, s29
	s_nop 0
	global_load_lds_dwordx4 v134, s[20:21]
	s_mov_b32 m0, s30
	s_nop 0
	global_load_lds_dwordx4 v130, s[20:21]
	s_waitcnt vmcnt(10)
	s_setprio 1
	s_barrier
	v_mfma_f32_16x16x32_bf16 v[52:55], v[202:205], v[166:169], v[52:55]
	v_mfma_f32_16x16x32_bf16 v[48:51], v[210:213], v[166:169], v[48:51]
	v_mfma_f32_16x16x32_bf16 v[36:39], v[202:205], v[174:177], v[36:39]
	v_mfma_f32_16x16x32_bf16 v[32:35], v[210:213], v[174:177], v[32:35]
	v_mfma_f32_16x16x32_bf16 v[20:23], v[202:205], v[182:185], v[20:23]
	v_mfma_f32_16x16x32_bf16 v[16:19], v[210:213], v[182:185], v[16:19]
	v_mfma_f32_16x16x32_bf16 v[4:7], v[202:205], v[190:193], v[4:7]
	v_mfma_f32_16x16x32_bf16 v[0:3], v[210:213], v[190:193], v[0:3]
	v_mfma_f32_16x16x32_bf16 v[52:55], v[206:209], v[170:173], v[52:55]
	v_mfma_f32_16x16x32_bf16 v[48:51], v[214:217], v[170:173], v[48:51]
	v_mfma_f32_16x16x32_bf16 v[36:39], v[206:209], v[178:181], v[36:39]
	v_mfma_f32_16x16x32_bf16 v[32:35], v[214:217], v[178:181], v[32:35]
	v_mfma_f32_16x16x32_bf16 v[20:23], v[206:209], v[186:189], v[20:23]
	v_mfma_f32_16x16x32_bf16 v[16:19], v[214:217], v[186:189], v[16:19]
	v_mfma_f32_16x16x32_bf16 v[4:7], v[206:209], v[194:197], v[4:7]
	v_mfma_f32_16x16x32_bf16 v[0:3], v[214:217], v[194:197], v[0:3]
	s_barrier
	s_setprio 0
	s_add_i32 s47, 0, 0x18000
	v_add_u32_e32 v162, s47, v146
	ds_read_b128 v[150:153], v162
	ds_read_b128 v[154:157], v162 offset:1024
	ds_read_b128 v[158:161], v162 offset:2048
	ds_read_b128 v[162:165], v162 offset:3072
	ds_read_b128 v[166:169], v148 offset:32768
	ds_read_b128 v[170:173], v148 offset:33792
	ds_read_b128 v[174:177], v148 offset:34816
	ds_read_b128 v[178:181], v148 offset:35840
	ds_read_b128 v[182:185], v148 offset:36864
	ds_read_b128 v[186:189], v148 offset:37888
	ds_read_b128 v[190:193], v148 offset:38912
	ds_read_b128 v[194:197], v148 offset:39936
	s_waitcnt lgkmcnt(8)
	s_waitcnt vmcnt(8)
	s_setprio 1
	s_barrier
; #define PG8_STAGE(bufoff, gbase, voff) do { _Pragma("unroll") for (int _i = 0; _i < 2; ++_i) \
;         __builtin_amdgcn_global_load_lds((const unsigned*)((const char*)(gbase) + (voff)[_i]), (LAS unsigned*)(lds + (bufoff) + ldsw + _i * 8192), 16, 0, 0); } while (0)
; #define PG8_LDA(dst, b, h) do { _Pragma("unroll") for (int m = 0; m < 4; ++m) _Pragma("unroll") for (int k = 0; k < 2; ++k) dst[m][k] = *(const LAS bf16x8*)(lds + PG8_SA(b, h) + aoff + m * 2048 + k * 1024); } while (0)
; #define PG8_WAIT_V(n) asm volatile("s_waitcnt vmcnt(" #n ")" ::: "memory")
; #define PG8_WAIT_L(n) asm volatile("s_waitcnt lgkmcnt(" #n ")" ::: "memory")
; template <class Epi, class Sched>
; __device__ __forceinline__ void gemm_phase(LAS unsigned char* lds, const Gemm g, const Sched& S, const Epi& E) {
;     ...
;         for (int t = 0; t < nt; t += 2) {
;             const bool last = (t == nt - 2);
;             const char* a1 = cA + (size_t)(t + 1) * kstep;
;             const char* a2 = last ? nA : cA + (size_t)(t + 2) * kstep; const char* b2 = last ? nB : cB + (size_t)(t + 2) * kstep;
;             const char* a3 = a2 + kstep; const char* b3 = b2 + kstep;
;             PG8_LDB(B0, 0, 0); PG8_SCHED; PG8_LDA(At, 0, 0); PG8_STAGE(PG8_SA(1, 1), a1 + hstep, voffA);
;             PG8_WAIT_L(8); PG8_BAR; PG8_WAIT_L(0); PG8_MMA(0, 0, At, B0); PG8_BAR; PG8_SCHED;
;             PG8_LDB(B1, 0, 1); PG8_STAGE(PG8_SB(0, 0), b2, voffB);
;             PG8_BAR; PG8_WAIT_L(0); PG8_MMA(0, 1, At, B1); PG8_BAR;
;             PG8_LDA(At, 0, 1); PG8_STAGE(PG8_SA(0, 0), a2, voffA);
;             PG8_BAR; PG8_WAIT_L(0); PG8_MMA(1, 0, At, B0); PG8_BAR; PG8_SCHED;
;             PG8_STAGE(PG8_SB(0, 1), b2 + hstep, voffB);
;             PG8_WAIT_V(6); PG8_BAR; PG8_MMA(1, 1, At, B1); PG8_BAR;
;             PG8_LDB(B0, 1, 0); PG8_SCHED; PG8_LDA(At, 1, 0); PG8_STAGE(PG8_SA(0, 1), a2 + hstep, voffA);
;             PG8_WAIT_L(8); PG8_BAR; PG8_WAIT_L(0); PG8_MMA(0, 0, At, B0); PG8_BAR; PG8_SCHED;
;             PG8_LDB(B1, 1, 1); PG8_STAGE(PG8_SB(1, 0), b3, voffB);
;             PG8_BAR; PG8_WAIT_L(0); PG8_MMA(0, 1, At, B1); PG8_BAR;
;             PG8_LDA(At, 1, 1); PG8_STAGE(PG8_SA(1, 0), a3, voffA);
;             PG8_BAR; PG8_WAIT_L(0); PG8_MMA(1, 0, At, B0); PG8_BAR; PG8_SCHED;
;             PG8_STAGE(PG8_SB(1, 1), b3 + hstep, voffB);
;             PG8_WAIT_V(6); PG8_BAR; PG8_MMA(1, 1, At, B1); PG8_BAR;
	s_waitcnt lgkmcnt(0)
	v_mfma_f32_16x16x32_bf16 v[124:127], v[150:153], v[166:169], v[124:127]
	v_mfma_f32_16x16x32_bf16 v[116:119], v[158:161], v[166:169], v[116:119]
	v_mfma_f32_16x16x32_bf16 v[108:111], v[150:153], v[174:177], v[108:111]
	v_mfma_f32_16x16x32_bf16 v[100:103], v[158:161], v[174:177], v[100:103]
	v_mfma_f32_16x16x32_bf16 v[92:95], v[150:153], v[182:185], v[92:95]
	v_mfma_f32_16x16x32_bf16 v[84:87], v[158:161], v[182:185], v[84:87]
	v_mfma_f32_16x16x32_bf16 v[76:79], v[150:153], v[190:193], v[76:79]
	v_mfma_f32_16x16x32_bf16 v[68:71], v[158:161], v[190:193], v[68:71]
	v_mfma_f32_16x16x32_bf16 v[124:127], v[154:157], v[170:173], v[124:127]
	v_mfma_f32_16x16x32_bf16 v[116:119], v[162:165], v[170:173], v[116:119]
	v_mfma_f32_16x16x32_bf16 v[108:111], v[154:157], v[178:181], v[108:111]
	v_mfma_f32_16x16x32_bf16 v[100:103], v[162:165], v[178:181], v[100:103]
	v_mfma_f32_16x16x32_bf16 v[92:95], v[154:157], v[186:189], v[92:95]
	v_mfma_f32_16x16x32_bf16 v[84:87], v[162:165], v[186:189], v[84:87]
	v_mfma_f32_16x16x32_bf16 v[76:79], v[154:157], v[194:197], v[76:79]
	v_mfma_f32_16x16x32_bf16 v[68:71], v[162:165], v[194:197], v[68:71]
	s_barrier
	s_setprio 0
	s_add_i32 s20, 0, 0x1c000
	s_add_i32 s21, s47, s25
	v_add_u32_e32 v214, s20, v146
	s_add_u32 s0, s18, 0x80
	s_addc_u32 s1, s19, 0
	s_mov_b32 m0, s21
	ds_read_b128 v[202:205], v214
	ds_read_b128 v[206:209], v214 offset:1024
	ds_read_b128 v[210:213], v214 offset:2048
	ds_read_b128 v[214:217], v214 offset:3072
	global_load_lds_dwordx4 v132, s[0:1]
	s_add_i32 m0, s21, 0x2000
	s_nop 0
	global_load_lds_dwordx4 v128, s[0:1]
	s_waitcnt vmcnt(8)
	s_setprio 1
	s_barrier
	s_waitcnt lgkmcnt(0)
	v_mfma_f32_16x16x32_bf16 v[120:123], v[202:205], v[166:169], v[120:123]
	v_mfma_f32_16x16x32_bf16 v[112:115], v[210:213], v[166:169], v[112:115]
	v_mfma_f32_16x16x32_bf16 v[104:107], v[202:205], v[174:177], v[104:107]
	v_mfma_f32_16x16x32_bf16 v[96:99], v[210:213], v[174:177], v[96:99]
	v_mfma_f32_16x16x32_bf16 v[88:91], v[202:205], v[182:185], v[88:91]
	v_mfma_f32_16x16x32_bf16 v[80:83], v[210:213], v[182:185], v[80:83]
	v_mfma_f32_16x16x32_bf16 v[72:75], v[202:205], v[190:193], v[72:75]
	v_mfma_f32_16x16x32_bf16 v[64:67], v[210:213], v[190:193], v[64:67]
	v_mfma_f32_16x16x32_bf16 v[120:123], v[206:209], v[170:173], v[120:123]
	v_mfma_f32_16x16x32_bf16 v[112:115], v[214:217], v[170:173], v[112:115]
	v_mfma_f32_16x16x32_bf16 v[104:107], v[206:209], v[178:181], v[104:107]
	v_mfma_f32_16x16x32_bf16 v[96:99], v[214:217], v[178:181], v[96:99]
	v_mfma_f32_16x16x32_bf16 v[88:91], v[206:209], v[186:189], v[88:91]
	v_mfma_f32_16x16x32_bf16 v[80:83], v[214:217], v[186:189], v[80:83]
	v_mfma_f32_16x16x32_bf16 v[72:75], v[206:209], v[194:197], v[72:75]
	v_mfma_f32_16x16x32_bf16 v[64:67], v[214:217], v[194:197], v[64:67]
	s_barrier
	s_setprio 0
	s_mov_b32 m0, s35
	s_mov_b64 s[0:1], 0x80
	v_lshl_add_u64 v[198:199], v[220:221], 0, s[0:1]
	ds_read_b128 v[166:169], v148 offset:49152
	ds_read_b128 v[170:173], v148 offset:50176
	ds_read_b128 v[174:177], v148 offset:51200
	ds_read_b128 v[178:181], v148 offset:52224
	ds_read_b128 v[182:185], v148 offset:53248
	ds_read_b128 v[186:189], v148 offset:54272
	ds_read_b128 v[190:193], v148 offset:55296
	ds_read_b128 v[194:197], v148 offset:56320
	global_load_lds_dwordx4 v[198:199], off
	v_lshl_add_u64 v[198:199], v[222:223], 0, s[0:1]
	s_mov_b32 m0, s36
	s_nop 0
	global_load_lds_dwordx4 v[198:199], off
	s_setprio 1
	s_barrier
	s_waitcnt lgkmcnt(0)
	v_mfma_f32_16x16x32_bf16 v[60:63], v[150:153], v[166:169], v[60:63]
	v_mfma_f32_16x16x32_bf16 v[56:59], v[158:161], v[166:169], v[56:59]
	v_mfma_f32_16x16x32_bf16 v[44:47], v[150:153], v[174:177], v[44:47]
	v_mfma_f32_16x16x32_bf16 v[40:43], v[158:161], v[174:177], v[40:43]
	v_mfma_f32_16x16x32_bf16 v[28:31], v[150:153], v[182:185], v[28:31]
	v_mfma_f32_16x16x32_bf16 v[24:27], v[158:161], v[182:185], v[24:27]
	v_mfma_f32_16x16x32_bf16 v[12:15], v[150:153], v[190:193], v[12:15]
	v_mfma_f32_16x16x32_bf16 v[8:11], v[158:161], v[190:193], v[8:11]
	v_mfma_f32_16x16x32_bf16 v[60:63], v[154:157], v[170:173], v[60:63]
	v_mfma_f32_16x16x32_bf16 v[56:59], v[162:165], v[170:173], v[56:59]
	v_mfma_f32_16x16x32_bf16 v[44:47], v[154:157], v[178:181], v[44:47]
	v_mfma_f32_16x16x32_bf16 v[40:43], v[162:165], v[178:181], v[40:43]
	v_mfma_f32_16x16x32_bf16 v[28:31], v[154:157], v[186:189], v[28:31]
	v_mfma_f32_16x16x32_bf16 v[24:27], v[162:165], v[186:189], v[24:27]
	v_mfma_f32_16x16x32_bf16 v[12:15], v[154:157], v[194:197], v[12:15]
	v_mfma_f32_16x16x32_bf16 v[8:11], v[162:165], v[194:197], v[8:11]
	s_barrier
	s_setprio 0
	s_add_u32 s18, s18, 0x40080
	s_addc_u32 s19, s19, 0
	s_add_i32 s20, s20, s25
	s_mov_b32 m0, s20
	s_nop 0
	global_load_lds_dwordx4 v132, s[18:19]
	s_add_i32 m0, s20, 0x2000
	s_nop 0
	global_load_lds_dwordx4 v128, s[18:19]
	s_waitcnt vmcnt(8)
	s_setprio 1
	s_barrier
	v_mfma_f32_16x16x32_bf16 v[52:55], v[202:205], v[166:169], v[52:55]
	v_mfma_f32_16x16x32_bf16 v[48:51], v[210:213], v[166:169], v[48:51]
	v_mfma_f32_16x16x32_bf16 v[36:39], v[202:205], v[174:177], v[36:39]
	v_mfma_f32_16x16x32_bf16 v[32:35], v[210:213], v[174:177], v[32:35]
	v_mfma_f32_16x16x32_bf16 v[20:23], v[202:205], v[182:185], v[20:23]
	v_mfma_f32_16x16x32_bf16 v[16:19], v[210:213], v[182:185], v[16:19]
	v_mfma_f32_16x16x32_bf16 v[4:7], v[202:205], v[190:193], v[4:7]
	v_mfma_f32_16x16x32_bf16 v[0:3], v[210:213], v[190:193], v[0:3]
	v_mfma_f32_16x16x32_bf16 v[52:55], v[206:209], v[170:173], v[52:55]
	v_mfma_f32_16x16x32_bf16 v[48:51], v[214:217], v[170:173], v[48:51]
	v_mfma_f32_16x16x32_bf16 v[36:39], v[206:209], v[178:181], v[36:39]
	v_mfma_f32_16x16x32_bf16 v[32:35], v[214:217], v[178:181], v[32:35]
	v_mfma_f32_16x16x32_bf16 v[20:23], v[206:209], v[186:189], v[20:23]
	v_mfma_f32_16x16x32_bf16 v[16:19], v[214:217], v[186:189], v[16:19]
	v_mfma_f32_16x16x32_bf16 v[4:7], v[206:209], v[194:197], v[4:7]
	v_mfma_f32_16x16x32_bf16 v[0:3], v[214:217], v[194:197], v[0:3]
	s_setprio 0
	s_add_i32 s46, s46, 2
	s_add_u32 s16, s16, 0x100
	s_addc_u32 s17, s17, 0
	s_add_u32 s44, s44, 0x100
	s_addc_u32 s45, s45, 0
	s_cmp_gt_u32 s46, 13
	s_cbranch_scc1 .Lconc_last_g11
	s_barrier
	s_branch .LBB0_1021

; #define PG8_STAGE(bufoff, gbase, voff) do { _Pragma("unroll") for (int _i = 0; _i < 2; ++_i) \
;         __builtin_amdgcn_global_load_lds((const unsigned*)((const char*)(gbase) + (voff)[_i]), (LAS unsigned*)(lds + (bufoff) + ldsw + _i * 8192), 16, 0, 0); } while (0)
; #define PG8_WAIT_V(n) asm volatile("s_waitcnt vmcnt(" #n ")" ::: "memory")
; #define PG8_WAIT_L(n) asm volatile("s_waitcnt lgkmcnt(" #n ")" ::: "memory")
; template <class Epi, class Sched>
; __device__ __forceinline__ void gemm_phase(LAS unsigned char* lds, const Gemm g, const Sched& S, const Epi& E) {
;     ...
;         const bool has_next = S.next(ui + 1, nxt);
;         const char* nA = has_next ? (const char*)g.A + (size_t)nxt.pm * tstep : cA; const char* nB = has_next ? (const char*)g.Bt + (size_t)nxt.pn * tstep : cB;
;         for (int t = 0; t < nt; t += 2) {
;             const bool last = (t == nt - 2);
;             const char* a1 = cA + (size_t)(t + 1) * kstep;
;             const char* a2 = last ? nA : cA + (size_t)(t + 2) * kstep; const char* b2 = last ? nB : cB + (size_t)(t + 2) * kstep;
;             const char* a3 = a2 + kstep; const char* b3 = b2 + kstep;
;             PG8_LDB(B0, 0, 0); PG8_SCHED; PG8_LDA(At, 0, 0); PG8_STAGE(PG8_SA(1, 1), a1 + hstep, voffA);
;             PG8_WAIT_L(8); PG8_BAR; PG8_WAIT_L(0); PG8_MMA(0, 0, At, B0); PG8_BAR; PG8_SCHED;
;             PG8_LDB(B1, 0, 1); PG8_STAGE(PG8_SB(0, 0), b2, voffB);
;             PG8_BAR; PG8_WAIT_L(0); PG8_MMA(0, 1, At, B1); PG8_BAR;
;             PG8_LDA(At, 0, 1); PG8_STAGE(PG8_SA(0, 0), a2, voffA);
;             PG8_BAR; PG8_WAIT_L(0); PG8_MMA(1, 0, At, B0); PG8_BAR; PG8_SCHED;
;             PG8_STAGE(PG8_SB(0, 1), b2 + hstep, voffB);
;             PG8_WAIT_V(6); PG8_BAR; PG8_MMA(1, 1, At, B1); PG8_BAR;
;             PG8_LDB(B0, 1, 0); PG8_SCHED; PG8_LDA(At, 1, 0); PG8_STAGE(PG8_SA(0, 1), a2 + hstep, voffA);
;             PG8_WAIT_L(8); PG8_BAR; PG8_WAIT_L(0); PG8_MMA(0, 0, At, B0); PG8_BAR; PG8_SCHED;
;             PG8_LDB(B1, 1, 1); PG8_STAGE(PG8_SB(1, 0), b3, voffB);
;             PG8_BAR; PG8_WAIT_L(0); PG8_MMA(0, 1, At, B1); PG8_BAR;
;             PG8_LDA(At, 1, 1); PG8_STAGE(PG8_SA(1, 0), a3, voffA);
;             PG8_BAR; PG8_WAIT_L(0); PG8_MMA(1, 0, At, B0); PG8_BAR; PG8_SCHED;
;             PG8_STAGE(PG8_SB(1, 1), b3 + hstep, voffB);
;             PG8_WAIT_V(6); PG8_BAR; PG8_MMA(1, 1, At, B1); PG8_BAR;
.LBB0_1096:
	s_add_u32 s54, s24, 0x100
	s_addc_u32 s55, s25, 0
	s_mov_b32 s56, -2
	ds_read_b128 v[128:131], v241
	ds_read_b128 v[132:135], v241 offset:1024
	ds_read_b128 v[136:139], v241 offset:2048
	ds_read_b128 v[140:143], v241 offset:3072
	s_add_u32 s24, s22, 0x100
	s_addc_u32 s25, s23, 0
	s_cmp_eq_u32 s56, 40
	s_cselect_b32 s29, s5, s25
	s_cselect_b32 s28, s4, s24
	s_cselect_b32 s27, s7, s55
	s_cselect_b32 s26, s6, s54
	v_lshl_add_u64 v[176:177], s[22:23], 0, v[196:197]
	s_add_i32 m0, s35, 0xc000
	ds_read_b128 v[144:147], v242
	ds_read_b128 v[148:151], v242 offset:1024
	ds_read_b128 v[152:155], v242 offset:2048
	ds_read_b128 v[156:159], v242 offset:3072
	ds_read_b128 v[160:163], v242 offset:4096
	ds_read_b128 v[164:167], v242 offset:5120
	ds_read_b128 v[168:171], v242 offset:6144
	ds_read_b128 v[172:175], v242 offset:7168
	global_load_lds_dwordx4 v[176:177], off
	v_lshl_add_u64 v[176:177], s[22:23], 0, v[198:199]
	s_add_i32 m0, s35, 0xe000
	s_nop 0
	global_load_lds_dwordx4 v[176:177], off
	s_waitcnt lgkmcnt(8)
	s_waitcnt vmcnt(8)
	s_setprio 1
	s_barrier
	s_waitcnt lgkmcnt(0)
	v_mfma_f32_16x16x32_bf16 v[124:127], v[128:131], v[144:147], 0
	v_mfma_f32_16x16x32_bf16 v[120:123], v[136:139], v[144:147], 0
	v_mfma_f32_16x16x32_bf16 v[108:111], v[128:131], v[152:155], 0
	v_mfma_f32_16x16x32_bf16 v[104:107], v[136:139], v[152:155], 0
	v_mfma_f32_16x16x32_bf16 v[92:95], v[128:131], v[160:163], 0
	v_mfma_f32_16x16x32_bf16 v[88:91], v[136:139], v[160:163], 0
	v_mfma_f32_16x16x32_bf16 v[76:79], v[128:131], v[168:171], 0
	v_mfma_f32_16x16x32_bf16 v[72:75], v[136:139], v[168:171], 0
	v_mfma_f32_16x16x32_bf16 v[124:127], v[132:135], v[148:151], v[124:127]
	v_mfma_f32_16x16x32_bf16 v[120:123], v[140:143], v[148:151], v[120:123]
	v_mfma_f32_16x16x32_bf16 v[108:111], v[132:135], v[156:159], v[108:111]
	v_mfma_f32_16x16x32_bf16 v[104:107], v[140:143], v[156:159], v[104:107]
	v_mfma_f32_16x16x32_bf16 v[92:95], v[132:135], v[164:167], v[92:95]
	v_mfma_f32_16x16x32_bf16 v[88:91], v[140:143], v[164:167], v[88:91]
	v_mfma_f32_16x16x32_bf16 v[76:79], v[132:135], v[172:175], v[76:79]
	v_mfma_f32_16x16x32_bf16 v[72:75], v[140:143], v[172:175], v[72:75]
	s_barrier
	s_setprio 0
	s_add_i32 s22, s48, s34
	s_mov_b32 m0, s22
	ds_read_b128 v[176:179], v243
	ds_read_b128 v[180:183], v243 offset:1024
	ds_read_b128 v[184:187], v243 offset:2048
	ds_read_b128 v[206:209], v243 offset:3072
	global_load_lds_dwordx4 v190, s[26:27]
	s_add_i32 m0, s22, 0x2000
	s_nop 0
	global_load_lds_dwordx4 v194, s[26:27]
	s_waitcnt vmcnt(8)
	s_setprio 1
	s_barrier
	s_waitcnt lgkmcnt(0)
	v_mfma_f32_16x16x32_bf16 v[116:119], v[176:179], v[144:147], 0
	v_mfma_f32_16x16x32_bf16 v[112:115], v[184:187], v[144:147], 0
	v_mfma_f32_16x16x32_bf16 v[100:103], v[176:179], v[152:155], 0
	v_mfma_f32_16x16x32_bf16 v[96:99], v[184:187], v[152:155], 0
	v_mfma_f32_16x16x32_bf16 v[84:87], v[176:179], v[160:163], 0
	v_mfma_f32_16x16x32_bf16 v[80:83], v[184:187], v[160:163], 0
	v_mfma_f32_16x16x32_bf16 v[68:71], v[176:179], v[168:171], 0
	v_mfma_f32_16x16x32_bf16 v[64:67], v[184:187], v[168:171], 0
	v_mfma_f32_16x16x32_bf16 v[116:119], v[180:183], v[148:151], v[116:119]
	v_mfma_f32_16x16x32_bf16 v[112:115], v[206:209], v[148:151], v[112:115]
	v_mfma_f32_16x16x32_bf16 v[100:103], v[180:183], v[156:159], v[100:103]
	v_mfma_f32_16x16x32_bf16 v[96:99], v[206:209], v[156:159], v[96:99]
	v_mfma_f32_16x16x32_bf16 v[84:87], v[180:183], v[164:167], v[84:87]
	v_mfma_f32_16x16x32_bf16 v[80:83], v[206:209], v[164:167], v[80:83]
	v_mfma_f32_16x16x32_bf16 v[68:71], v[180:183], v[172:175], v[68:71]
	v_mfma_f32_16x16x32_bf16 v[64:67], v[206:209], v[172:175], v[64:67]
	s_barrier
	s_setprio 0
	s_mov_b32 m0, s35
	v_lshl_add_u64 v[214:215], s[28:29], 0, v[188:189]
	ds_read_b128 v[144:147], v242 offset:16384
	ds_read_b128 v[148:151], v242 offset:17408
	ds_read_b128 v[152:155], v242 offset:18432
	ds_read_b128 v[156:159], v242 offset:19456
	ds_read_b128 v[160:163], v242 offset:20480
	ds_read_b128 v[164:167], v242 offset:21504
	ds_read_b128 v[168:171], v242 offset:22528
	ds_read_b128 v[172:175], v242 offset:23552
	global_load_lds_dwordx4 v188, s[28:29]
	v_lshl_add_u64 v[216:217], s[28:29], 0, v[192:193]
	s_mov_b32 m0, s36
	s_nop 0
	global_load_lds_dwordx4 v192, s[28:29]
	s_setprio 1
	s_barrier
	s_waitcnt lgkmcnt(0)
	v_mfma_f32_16x16x32_bf16 v[60:63], v[128:131], v[144:147], 0
	v_mfma_f32_16x16x32_bf16 v[56:59], v[136:139], v[144:147], 0
	v_mfma_f32_16x16x32_bf16 v[44:47], v[128:131], v[152:155], 0
	v_mfma_f32_16x16x32_bf16 v[40:43], v[136:139], v[152:155], 0
	v_mfma_f32_16x16x32_bf16 v[28:31], v[128:131], v[160:163], 0
	v_mfma_f32_16x16x32_bf16 v[24:27], v[136:139], v[160:163], 0
	v_mfma_f32_16x16x32_bf16 v[12:15], v[128:131], v[168:171], 0
	v_mfma_f32_16x16x32_bf16 v[8:11], v[136:139], v[168:171], 0
	v_mfma_f32_16x16x32_bf16 v[60:63], v[132:135], v[148:151], v[60:63]
	v_mfma_f32_16x16x32_bf16 v[56:59], v[140:143], v[148:151], v[56:59]
	v_mfma_f32_16x16x32_bf16 v[44:47], v[132:135], v[156:159], v[44:47]
	v_mfma_f32_16x16x32_bf16 v[40:43], v[140:143], v[156:159], v[40:43]
	v_mfma_f32_16x16x32_bf16 v[28:31], v[132:135], v[164:167], v[28:31]
	v_mfma_f32_16x16x32_bf16 v[24:27], v[140:143], v[164:167], v[24:27]
	v_mfma_f32_16x16x32_bf16 v[12:15], v[132:135], v[172:175], v[12:15]
	v_mfma_f32_16x16x32_bf16 v[8:11], v[140:143], v[172:175], v[8:11]
	s_barrier
	s_setprio 0
	s_add_u32 s22, s26, 0xb0000
	s_addc_u32 s23, s27, 0
	s_add_i32 s57, s49, s34
	s_mov_b32 m0, s57
	s_nop 0
	global_load_lds_dwordx4 v190, s[22:23]
	s_add_i32 m0, s57, 0x2000
	s_nop 0
	global_load_lds_dwordx4 v194, s[22:23]
	s_add_u32 s22, s28, 0xb0000
	s_addc_u32 s23, s29, 0
	s_mov_b32 m0, s37
	s_nop 0
	global_load_lds_dwordx4 v188, s[22:23]
	s_mov_b32 m0, s38
	s_nop 0
	global_load_lds_dwordx4 v192, s[22:23]
	s_waitcnt vmcnt(10)
	s_setprio 1
	s_barrier
; #define PG8_STAGE(bufoff, gbase, voff) do { _Pragma("unroll") for (int _i = 0; _i < 2; ++_i) \
;         __builtin_amdgcn_global_load_lds((const unsigned*)((const char*)(gbase) + (voff)[_i]), (LAS unsigned*)(lds + (bufoff) + ldsw + _i * 8192), 16, 0, 0); } while (0)
; #define PG8_LDA(dst, b, h) do { _Pragma("unroll") for (int m = 0; m < 4; ++m) _Pragma("unroll") for (int k = 0; k < 2; ++k) dst[m][k] = *(const LAS bf16x8*)(lds + PG8_SA(b, h) + aoff + m * 2048 + k * 1024); } while (0)
; #define PG8_WAIT_V(n) asm volatile("s_waitcnt vmcnt(" #n ")" ::: "memory")
; #define PG8_WAIT_L(n) asm volatile("s_waitcnt lgkmcnt(" #n ")" ::: "memory")
; template <class Epi, class Sched>
; __device__ __forceinline__ void gemm_phase(LAS unsigned char* lds, const Gemm g, const Sched& S, const Epi& E) {
;     ...
;         for (int t = 0; t < nt; t += 2) {
;             const bool last = (t == nt - 2);
;             const char* a1 = cA + (size_t)(t + 1) * kstep;
;             const char* a2 = last ? nA : cA + (size_t)(t + 2) * kstep; const char* b2 = last ? nB : cB + (size_t)(t + 2) * kstep;
;             const char* a3 = a2 + kstep; const char* b3 = b2 + kstep;
;             PG8_LDB(B0, 0, 0); PG8_SCHED; PG8_LDA(At, 0, 0); PG8_STAGE(PG8_SA(1, 1), a1 + hstep, voffA);
;             PG8_WAIT_L(8); PG8_BAR; PG8_WAIT_L(0); PG8_MMA(0, 0, At, B0); PG8_BAR; PG8_SCHED;
;             PG8_LDB(B1, 0, 1); PG8_STAGE(PG8_SB(0, 0), b2, voffB);
;             PG8_BAR; PG8_WAIT_L(0); PG8_MMA(0, 1, At, B1); PG8_BAR;
;             PG8_LDA(At, 0, 1); PG8_STAGE(PG8_SA(0, 0), a2, voffA);
;             PG8_BAR; PG8_WAIT_L(0); PG8_MMA(1, 0, At, B0); PG8_BAR; PG8_SCHED;
;             PG8_STAGE(PG8_SB(0, 1), b2 + hstep, voffB);
;             PG8_WAIT_V(6); PG8_BAR; PG8_MMA(1, 1, At, B1); PG8_BAR;
;             PG8_LDB(B0, 1, 0); PG8_SCHED; PG8_LDA(At, 1, 0); PG8_STAGE(PG8_SA(0, 1), a2 + hstep, voffA);
;             PG8_WAIT_L(8); PG8_BAR; PG8_WAIT_L(0); PG8_MMA(0, 0, At, B0); PG8_BAR; PG8_SCHED;
;             PG8_LDB(B1, 1, 1); PG8_STAGE(PG8_SB(1, 0), b3, voffB);
;             PG8_BAR; PG8_WAIT_L(0); PG8_MMA(0, 1, At, B1); PG8_BAR;
;             PG8_LDA(At, 1, 1); PG8_STAGE(PG8_SA(1, 0), a3, voffA);
;             PG8_BAR; PG8_WAIT_L(0); PG8_MMA(1, 0, At, B0); PG8_BAR; PG8_SCHED;
;             PG8_STAGE(PG8_SB(1, 1), b3 + hstep, voffB);
;             PG8_WAIT_V(6); PG8_BAR; PG8_MMA(1, 1, At, B1); PG8_BAR;
	v_mfma_f32_16x16x32_bf16 v[52:55], v[176:179], v[144:147], 0
	v_mfma_f32_16x16x32_bf16 v[48:51], v[184:187], v[144:147], 0
	v_mfma_f32_16x16x32_bf16 v[36:39], v[176:179], v[152:155], 0
	v_mfma_f32_16x16x32_bf16 v[32:35], v[184:187], v[152:155], 0
	v_mfma_f32_16x16x32_bf16 v[20:23], v[176:179], v[160:163], 0
	v_mfma_f32_16x16x32_bf16 v[16:19], v[184:187], v[160:163], 0
	v_mfma_f32_16x16x32_bf16 v[4:7], v[176:179], v[168:171], 0
	v_mfma_f32_16x16x32_bf16 v[0:3], v[184:187], v[168:171], 0
	v_mfma_f32_16x16x32_bf16 v[52:55], v[180:183], v[148:151], v[52:55]
	v_mfma_f32_16x16x32_bf16 v[48:51], v[206:209], v[148:151], v[48:51]
	v_mfma_f32_16x16x32_bf16 v[36:39], v[180:183], v[156:159], v[36:39]
	v_mfma_f32_16x16x32_bf16 v[32:35], v[206:209], v[156:159], v[32:35]
	v_mfma_f32_16x16x32_bf16 v[20:23], v[180:183], v[164:167], v[20:23]
	v_mfma_f32_16x16x32_bf16 v[16:19], v[206:209], v[164:167], v[16:19]
	v_mfma_f32_16x16x32_bf16 v[4:7], v[180:183], v[172:175], v[4:7]
	v_mfma_f32_16x16x32_bf16 v[0:3], v[206:209], v[172:175], v[0:3]
	s_barrier
	s_setprio 0
	s_add_i32 s57, 0, 0x18000
	v_add_u32_e32 v140, s57, v240
	ds_read_b128 v[128:131], v140
	ds_read_b128 v[132:135], v140 offset:1024
	ds_read_b128 v[136:139], v140 offset:2048
	ds_read_b128 v[140:143], v140 offset:3072
	ds_read_b128 v[144:147], v242 offset:32768
	ds_read_b128 v[148:151], v242 offset:33792
	ds_read_b128 v[152:155], v242 offset:34816
	ds_read_b128 v[156:159], v242 offset:35840
	ds_read_b128 v[160:163], v242 offset:36864
	ds_read_b128 v[164:167], v242 offset:37888
	ds_read_b128 v[168:171], v242 offset:38912
	ds_read_b128 v[172:175], v242 offset:39936
	s_waitcnt lgkmcnt(8)
	s_waitcnt vmcnt(8)
	s_setprio 1
	s_barrier
	s_waitcnt lgkmcnt(0)
	v_mfma_f32_16x16x32_bf16 v[124:127], v[128:131], v[144:147], v[124:127]
	v_mfma_f32_16x16x32_bf16 v[120:123], v[136:139], v[144:147], v[120:123]
	v_mfma_f32_16x16x32_bf16 v[108:111], v[128:131], v[152:155], v[108:111]
	v_mfma_f32_16x16x32_bf16 v[104:107], v[136:139], v[152:155], v[104:107]
	v_mfma_f32_16x16x32_bf16 v[92:95], v[128:131], v[160:163], v[92:95]
	v_mfma_f32_16x16x32_bf16 v[88:91], v[136:139], v[160:163], v[88:91]
	v_mfma_f32_16x16x32_bf16 v[76:79], v[128:131], v[168:171], v[76:79]
	v_mfma_f32_16x16x32_bf16 v[72:75], v[136:139], v[168:171], v[72:75]
	v_mfma_f32_16x16x32_bf16 v[124:127], v[132:135], v[148:151], v[124:127]
	v_mfma_f32_16x16x32_bf16 v[120:123], v[140:143], v[148:151], v[120:123]
	v_mfma_f32_16x16x32_bf16 v[108:111], v[132:135], v[156:159], v[108:111]
	v_mfma_f32_16x16x32_bf16 v[104:107], v[140:143], v[156:159], v[104:107]
	v_mfma_f32_16x16x32_bf16 v[92:95], v[132:135], v[164:167], v[92:95]
	v_mfma_f32_16x16x32_bf16 v[88:91], v[140:143], v[164:167], v[88:91]
	v_mfma_f32_16x16x32_bf16 v[76:79], v[132:135], v[172:175], v[76:79]
	v_mfma_f32_16x16x32_bf16 v[72:75], v[140:143], v[172:175], v[72:75]
	s_barrier
	s_setprio 0
	s_add_i32 s28, 0, 0x1c000
	s_add_i32 s22, s57, s34
	v_add_u32_e32 v206, s28, v240
	s_add_u32 s0, s26, 0x80
	s_addc_u32 s1, s27, 0
	s_mov_b32 m0, s22
	ds_read_b128 v[176:179], v206
	ds_read_b128 v[180:183], v206 offset:1024
	ds_read_b128 v[184:187], v206 offset:2048
	ds_read_b128 v[206:209], v206 offset:3072
	global_load_lds_dwordx4 v190, s[0:1]
	s_add_i32 m0, s22, 0x2000
	s_nop 0
	global_load_lds_dwordx4 v194, s[0:1]
	s_waitcnt vmcnt(8)
	s_setprio 1
	s_barrier
	s_waitcnt lgkmcnt(0)
	v_mfma_f32_16x16x32_bf16 v[116:119], v[176:179], v[144:147], v[116:119]
	v_mfma_f32_16x16x32_bf16 v[112:115], v[184:187], v[144:147], v[112:115]
	v_mfma_f32_16x16x32_bf16 v[100:103], v[176:179], v[152:155], v[100:103]
	v_mfma_f32_16x16x32_bf16 v[96:99], v[184:187], v[152:155], v[96:99]
	v_mfma_f32_16x16x32_bf16 v[84:87], v[176:179], v[160:163], v[84:87]
	v_mfma_f32_16x16x32_bf16 v[80:83], v[184:187], v[160:163], v[80:83]
	v_mfma_f32_16x16x32_bf16 v[68:71], v[176:179], v[168:171], v[68:71]
	v_mfma_f32_16x16x32_bf16 v[64:67], v[184:187], v[168:171], v[64:67]
	v_mfma_f32_16x16x32_bf16 v[116:119], v[180:183], v[148:151], v[116:119]
	v_mfma_f32_16x16x32_bf16 v[112:115], v[206:209], v[148:151], v[112:115]
	v_mfma_f32_16x16x32_bf16 v[100:103], v[180:183], v[156:159], v[100:103]
	v_mfma_f32_16x16x32_bf16 v[96:99], v[206:209], v[156:159], v[96:99]
	v_mfma_f32_16x16x32_bf16 v[84:87], v[180:183], v[164:167], v[84:87]
	v_mfma_f32_16x16x32_bf16 v[80:83], v[206:209], v[164:167], v[80:83]
	v_mfma_f32_16x16x32_bf16 v[68:71], v[180:183], v[172:175], v[68:71]
	v_mfma_f32_16x16x32_bf16 v[64:67], v[206:209], v[172:175], v[64:67]
	s_barrier
	s_setprio 0
	s_mov_b32 m0, s44
	s_mov_b64 s[0:1], 0x80
	v_lshl_add_u64 v[210:211], v[214:215], 0, s[0:1]
	ds_read_b128 v[144:147], v242 offset:49152
	ds_read_b128 v[148:151], v242 offset:50176
	ds_read_b128 v[152:155], v242 offset:51200
	ds_read_b128 v[156:159], v242 offset:52224
	ds_read_b128 v[160:163], v242 offset:53248
	ds_read_b128 v[164:167], v242 offset:54272
	ds_read_b128 v[168:171], v242 offset:55296
	ds_read_b128 v[172:175], v242 offset:56320
	global_load_lds_dwordx4 v[210:211], off
	v_lshl_add_u64 v[210:211], v[216:217], 0, s[0:1]
	s_mov_b32 m0, s45
	s_nop 0
	global_load_lds_dwordx4 v[210:211], off
	s_setprio 1
	s_barrier
; #define PG8_STAGE(bufoff, gbase, voff) do { _Pragma("unroll") for (int _i = 0; _i < 2; ++_i) \
;         __builtin_amdgcn_global_load_lds((const unsigned*)((const char*)(gbase) + (voff)[_i]), (LAS unsigned*)(lds + (bufoff) + ldsw + _i * 8192), 16, 0, 0); } while (0)
; #define PG8_LDA(dst, b, h) do { _Pragma("unroll") for (int m = 0; m < 4; ++m) _Pragma("unroll") for (int k = 0; k < 2; ++k) dst[m][k] = *(const LAS bf16x8*)(lds + PG8_SA(b, h) + aoff + m * 2048 + k * 1024); } while (0)
; #define PG8_WAIT_V(n) asm volatile("s_waitcnt vmcnt(" #n ")" ::: "memory")
; #define PG8_WAIT_L(n) asm volatile("s_waitcnt lgkmcnt(" #n ")" ::: "memory")
; template <class Epi, class Sched>
; __device__ __forceinline__ void gemm_phase(LAS unsigned char* lds, const Gemm g, const Sched& S, const Epi& E) {
;     ...
;         for (int t = 0; t < nt; t += 2) {
;             const bool last = (t == nt - 2);
;             const char* a1 = cA + (size_t)(t + 1) * kstep;
;             const char* a2 = last ? nA : cA + (size_t)(t + 2) * kstep; const char* b2 = last ? nB : cB + (size_t)(t + 2) * kstep;
;             const char* a3 = a2 + kstep; const char* b3 = b2 + kstep;
;             PG8_LDB(B0, 0, 0); PG8_SCHED; PG8_LDA(At, 0, 0); PG8_STAGE(PG8_SA(1, 1), a1 + hstep, voffA);
;             PG8_WAIT_L(8); PG8_BAR; PG8_WAIT_L(0); PG8_MMA(0, 0, At, B0); PG8_BAR; PG8_SCHED;
;             PG8_LDB(B1, 0, 1); PG8_STAGE(PG8_SB(0, 0), b2, voffB);
;             PG8_BAR; PG8_WAIT_L(0); PG8_MMA(0, 1, At, B1); PG8_BAR;
;             PG8_LDA(At, 0, 1); PG8_STAGE(PG8_SA(0, 0), a2, voffA);
;             PG8_BAR; PG8_WAIT_L(0); PG8_MMA(1, 0, At, B0); PG8_BAR; PG8_SCHED;
;             PG8_STAGE(PG8_SB(0, 1), b2 + hstep, voffB);
;             PG8_WAIT_V(6); PG8_BAR; PG8_MMA(1, 1, At, B1); PG8_BAR;
;             PG8_LDB(B0, 1, 0); PG8_SCHED; PG8_LDA(At, 1, 0); PG8_STAGE(PG8_SA(0, 1), a2 + hstep, voffA);
;             PG8_WAIT_L(8); PG8_BAR; PG8_WAIT_L(0); PG8_MMA(0, 0, At, B0); PG8_BAR; PG8_SCHED;
;             PG8_LDB(B1, 1, 1); PG8_STAGE(PG8_SB(1, 0), b3, voffB);
;             PG8_BAR; PG8_WAIT_L(0); PG8_MMA(0, 1, At, B1); PG8_BAR;
;             PG8_LDA(At, 1, 1); PG8_STAGE(PG8_SA(1, 0), a3, voffA);
;             PG8_BAR; PG8_WAIT_L(0); PG8_MMA(1, 0, At, B0); PG8_BAR; PG8_SCHED;
;             PG8_STAGE(PG8_SB(1, 1), b3 + hstep, voffB);
;             PG8_WAIT_V(6); PG8_BAR; PG8_MMA(1, 1, At, B1); PG8_BAR;
	s_waitcnt lgkmcnt(0)
	v_mfma_f32_16x16x32_bf16 v[60:63], v[128:131], v[144:147], v[60:63]
	v_mfma_f32_16x16x32_bf16 v[56:59], v[136:139], v[144:147], v[56:59]
	v_mfma_f32_16x16x32_bf16 v[44:47], v[128:131], v[152:155], v[44:47]
	v_mfma_f32_16x16x32_bf16 v[40:43], v[136:139], v[152:155], v[40:43]
	v_mfma_f32_16x16x32_bf16 v[28:31], v[128:131], v[160:163], v[28:31]
	v_mfma_f32_16x16x32_bf16 v[24:27], v[136:139], v[160:163], v[24:27]
	v_mfma_f32_16x16x32_bf16 v[12:15], v[128:131], v[168:171], v[12:15]
	v_mfma_f32_16x16x32_bf16 v[8:11], v[136:139], v[168:171], v[8:11]
	v_mfma_f32_16x16x32_bf16 v[60:63], v[132:135], v[148:151], v[60:63]
	v_mfma_f32_16x16x32_bf16 v[56:59], v[140:143], v[148:151], v[56:59]
	v_mfma_f32_16x16x32_bf16 v[44:47], v[132:135], v[156:159], v[44:47]
	v_mfma_f32_16x16x32_bf16 v[40:43], v[140:143], v[156:159], v[40:43]
	v_mfma_f32_16x16x32_bf16 v[28:31], v[132:135], v[164:167], v[28:31]
	v_mfma_f32_16x16x32_bf16 v[24:27], v[140:143], v[164:167], v[24:27]
	v_mfma_f32_16x16x32_bf16 v[12:15], v[132:135], v[172:175], v[12:15]
	v_mfma_f32_16x16x32_bf16 v[8:11], v[140:143], v[172:175], v[8:11]
	s_barrier
	s_setprio 0
	s_add_u32 s22, s26, 0xb0080
	s_addc_u32 s23, s27, 0
	s_add_i32 s26, s28, s34
	s_mov_b32 m0, s26
	s_nop 0
	global_load_lds_dwordx4 v190, s[22:23]
	s_add_i32 m0, s26, 0x2000
	s_nop 0
	global_load_lds_dwordx4 v194, s[22:23]
	s_waitcnt vmcnt(8)
	s_setprio 1
	s_barrier
	v_mfma_f32_16x16x32_bf16 v[52:55], v[176:179], v[144:147], v[52:55]
	v_mfma_f32_16x16x32_bf16 v[48:51], v[184:187], v[144:147], v[48:51]
	v_mfma_f32_16x16x32_bf16 v[36:39], v[176:179], v[152:155], v[36:39]
	v_mfma_f32_16x16x32_bf16 v[32:35], v[184:187], v[152:155], v[32:35]
	v_mfma_f32_16x16x32_bf16 v[20:23], v[176:179], v[160:163], v[20:23]
	v_mfma_f32_16x16x32_bf16 v[16:19], v[184:187], v[160:163], v[16:19]
	v_mfma_f32_16x16x32_bf16 v[4:7], v[176:179], v[168:171], v[4:7]
	v_mfma_f32_16x16x32_bf16 v[0:3], v[184:187], v[168:171], v[0:3]
	v_mfma_f32_16x16x32_bf16 v[52:55], v[180:183], v[148:151], v[52:55]
	v_mfma_f32_16x16x32_bf16 v[48:51], v[206:209], v[148:151], v[48:51]
	v_mfma_f32_16x16x32_bf16 v[36:39], v[180:183], v[156:159], v[36:39]
	v_mfma_f32_16x16x32_bf16 v[32:35], v[206:209], v[156:159], v[32:35]
	v_mfma_f32_16x16x32_bf16 v[20:23], v[180:183], v[164:167], v[20:23]
	v_mfma_f32_16x16x32_bf16 v[16:19], v[206:209], v[164:167], v[16:19]
	v_mfma_f32_16x16x32_bf16 v[4:7], v[180:183], v[172:175], v[4:7]
	v_mfma_f32_16x16x32_bf16 v[0:3], v[206:209], v[172:175], v[0:3]
	s_barrier
	s_setprio 0
	s_add_i32 s56, s56, 2
	s_add_u32 s54, s54, 0x100
	s_addc_u32 s55, s55, 0
	s_cmp_gt_u32 s56, 41
	s_mov_b64 s[22:23], s[24:25]
.LBB0_1097:
	ds_read_b128 v[128:131], v241
	ds_read_b128 v[132:135], v241 offset:1024
	ds_read_b128 v[136:139], v241 offset:2048
	ds_read_b128 v[140:143], v241 offset:3072
	s_add_u32 s24, s22, 0x100
	s_addc_u32 s25, s23, 0
	s_cmp_eq_u32 s56, 40
	s_cselect_b32 s29, s5, s25
	s_cselect_b32 s28, s4, s24
	s_cselect_b32 s27, s7, s55
	s_cselect_b32 s26, s6, s54
	v_lshl_add_u64 v[176:177], s[22:23], 0, v[196:197]
	s_add_i32 m0, s35, 0xc000
	ds_read_b128 v[144:147], v242
	ds_read_b128 v[148:151], v242 offset:1024
	ds_read_b128 v[152:155], v242 offset:2048
	ds_read_b128 v[156:159], v242 offset:3072
	ds_read_b128 v[160:163], v242 offset:4096
	ds_read_b128 v[164:167], v242 offset:5120
	ds_read_b128 v[168:171], v242 offset:6144
	ds_read_b128 v[172:175], v242 offset:7168
	global_load_lds_dwordx4 v[176:177], off
	v_lshl_add_u64 v[176:177], s[22:23], 0, v[198:199]
	s_add_i32 m0, s35, 0xe000
	s_nop 0
	global_load_lds_dwordx4 v[176:177], off
	s_waitcnt lgkmcnt(8)
	s_waitcnt vmcnt(8)
	s_setprio 1
	s_barrier
	s_waitcnt lgkmcnt(0)
	v_mfma_f32_16x16x32_bf16 v[124:127], v[128:131], v[144:147], v[124:127]
	v_mfma_f32_16x16x32_bf16 v[120:123], v[136:139], v[144:147], v[120:123]
	v_mfma_f32_16x16x32_bf16 v[108:111], v[128:131], v[152:155], v[108:111]
	v_mfma_f32_16x16x32_bf16 v[104:107], v[136:139], v[152:155], v[104:107]
	v_mfma_f32_16x16x32_bf16 v[92:95], v[128:131], v[160:163], v[92:95]
	v_mfma_f32_16x16x32_bf16 v[88:91], v[136:139], v[160:163], v[88:91]
	v_mfma_f32_16x16x32_bf16 v[76:79], v[128:131], v[168:171], v[76:79]
	v_mfma_f32_16x16x32_bf16 v[72:75], v[136:139], v[168:171], v[72:75]
	v_mfma_f32_16x16x32_bf16 v[124:127], v[132:135], v[148:151], v[124:127]
	v_mfma_f32_16x16x32_bf16 v[120:123], v[140:143], v[148:151], v[120:123]
	v_mfma_f32_16x16x32_bf16 v[108:111], v[132:135], v[156:159], v[108:111]
	v_mfma_f32_16x16x32_bf16 v[104:107], v[140:143], v[156:159], v[104:107]
	v_mfma_f32_16x16x32_bf16 v[92:95], v[132:135], v[164:167], v[92:95]
	v_mfma_f32_16x16x32_bf16 v[88:91], v[140:143], v[164:167], v[88:91]
	v_mfma_f32_16x16x32_bf16 v[76:79], v[132:135], v[172:175], v[76:79]
	v_mfma_f32_16x16x32_bf16 v[72:75], v[140:143], v[172:175], v[72:75]
	s_barrier
	s_setprio 0
	s_add_i32 s22, s48, s34
	s_mov_b32 m0, s22
	ds_read_b128 v[176:179], v243
	ds_read_b128 v[180:183], v243 offset:1024
	ds_read_b128 v[184:187], v243 offset:2048
	ds_read_b128 v[206:209], v243 offset:3072
	global_load_lds_dwordx4 v190, s[26:27]
	s_add_i32 m0, s22, 0x2000
	s_nop 0
	global_load_lds_dwordx4 v194, s[26:27]
	s_waitcnt vmcnt(8)
	s_setprio 1
	s_barrier
; #define PG8_STAGE(bufoff, gbase, voff) do { _Pragma("unroll") for (int _i = 0; _i < 2; ++_i) \
;         __builtin_amdgcn_global_load_lds((const unsigned*)((const char*)(gbase) + (voff)[_i]), (LAS unsigned*)(lds + (bufoff) + ldsw + _i * 8192), 16, 0, 0); } while (0)
; #define PG8_LDA(dst, b, h) do { _Pragma("unroll") for (int m = 0; m < 4; ++m) _Pragma("unroll") for (int k = 0; k < 2; ++k) dst[m][k] = *(const LAS bf16x8*)(lds + PG8_SA(b, h) + aoff + m * 2048 + k * 1024); } while (0)
; #define PG8_WAIT_V(n) asm volatile("s_waitcnt vmcnt(" #n ")" ::: "memory")
; #define PG8_WAIT_L(n) asm volatile("s_waitcnt lgkmcnt(" #n ")" ::: "memory")
; template <class Epi, class Sched>
; __device__ __forceinline__ void gemm_phase(LAS unsigned char* lds, const Gemm g, const Sched& S, const Epi& E) {
;     ...
;         for (int t = 0; t < nt; t += 2) {
;             const bool last = (t == nt - 2);
;             const char* a1 = cA + (size_t)(t + 1) * kstep;
;             const char* a2 = last ? nA : cA + (size_t)(t + 2) * kstep; const char* b2 = last ? nB : cB + (size_t)(t + 2) * kstep;
;             const char* a3 = a2 + kstep; const char* b3 = b2 + kstep;
;             PG8_LDB(B0, 0, 0); PG8_SCHED; PG8_LDA(At, 0, 0); PG8_STAGE(PG8_SA(1, 1), a1 + hstep, voffA);
;             PG8_WAIT_L(8); PG8_BAR; PG8_WAIT_L(0); PG8_MMA(0, 0, At, B0); PG8_BAR; PG8_SCHED;
;             PG8_LDB(B1, 0, 1); PG8_STAGE(PG8_SB(0, 0), b2, voffB);
;             PG8_BAR; PG8_WAIT_L(0); PG8_MMA(0, 1, At, B1); PG8_BAR;
;             PG8_LDA(At, 0, 1); PG8_STAGE(PG8_SA(0, 0), a2, voffA);
;             PG8_BAR; PG8_WAIT_L(0); PG8_MMA(1, 0, At, B0); PG8_BAR; PG8_SCHED;
;             PG8_STAGE(PG8_SB(0, 1), b2 + hstep, voffB);
;             PG8_WAIT_V(6); PG8_BAR; PG8_MMA(1, 1, At, B1); PG8_BAR;
;             PG8_LDB(B0, 1, 0); PG8_SCHED; PG8_LDA(At, 1, 0); PG8_STAGE(PG8_SA(0, 1), a2 + hstep, voffA);
;             PG8_WAIT_L(8); PG8_BAR; PG8_WAIT_L(0); PG8_MMA(0, 0, At, B0); PG8_BAR; PG8_SCHED;
;             PG8_LDB(B1, 1, 1); PG8_STAGE(PG8_SB(1, 0), b3, voffB);
;             PG8_BAR; PG8_WAIT_L(0); PG8_MMA(0, 1, At, B1); PG8_BAR;
;             PG8_LDA(At, 1, 1); PG8_STAGE(PG8_SA(1, 0), a3, voffA);
;             PG8_BAR; PG8_WAIT_L(0); PG8_MMA(1, 0, At, B0); PG8_BAR; PG8_SCHED;
;             PG8_STAGE(PG8_SB(1, 1), b3 + hstep, voffB);
;             PG8_WAIT_V(6); PG8_BAR; PG8_MMA(1, 1, At, B1); PG8_BAR;
	s_waitcnt lgkmcnt(0)
	v_mfma_f32_16x16x32_bf16 v[116:119], v[176:179], v[144:147], v[116:119]
	v_mfma_f32_16x16x32_bf16 v[112:115], v[184:187], v[144:147], v[112:115]
	v_mfma_f32_16x16x32_bf16 v[100:103], v[176:179], v[152:155], v[100:103]
	v_mfma_f32_16x16x32_bf16 v[96:99], v[184:187], v[152:155], v[96:99]
	v_mfma_f32_16x16x32_bf16 v[84:87], v[176:179], v[160:163], v[84:87]
	v_mfma_f32_16x16x32_bf16 v[80:83], v[184:187], v[160:163], v[80:83]
	v_mfma_f32_16x16x32_bf16 v[68:71], v[176:179], v[168:171], v[68:71]
	v_mfma_f32_16x16x32_bf16 v[64:67], v[184:187], v[168:171], v[64:67]
	v_mfma_f32_16x16x32_bf16 v[116:119], v[180:183], v[148:151], v[116:119]
	v_mfma_f32_16x16x32_bf16 v[112:115], v[206:209], v[148:151], v[112:115]
	v_mfma_f32_16x16x32_bf16 v[100:103], v[180:183], v[156:159], v[100:103]
	v_mfma_f32_16x16x32_bf16 v[96:99], v[206:209], v[156:159], v[96:99]
	v_mfma_f32_16x16x32_bf16 v[84:87], v[180:183], v[164:167], v[84:87]
	v_mfma_f32_16x16x32_bf16 v[80:83], v[206:209], v[164:167], v[80:83]
	v_mfma_f32_16x16x32_bf16 v[68:71], v[180:183], v[172:175], v[68:71]
	v_mfma_f32_16x16x32_bf16 v[64:67], v[206:209], v[172:175], v[64:67]
	s_barrier
	s_setprio 0
	s_mov_b32 m0, s35
	v_lshl_add_u64 v[214:215], s[28:29], 0, v[188:189]
	ds_read_b128 v[144:147], v242 offset:16384
	ds_read_b128 v[148:151], v242 offset:17408
	ds_read_b128 v[152:155], v242 offset:18432
	ds_read_b128 v[156:159], v242 offset:19456
	ds_read_b128 v[160:163], v242 offset:20480
	ds_read_b128 v[164:167], v242 offset:21504
	ds_read_b128 v[168:171], v242 offset:22528
	ds_read_b128 v[172:175], v242 offset:23552
	global_load_lds_dwordx4 v188, s[28:29]
	v_lshl_add_u64 v[216:217], s[28:29], 0, v[192:193]
	s_mov_b32 m0, s36
	s_nop 0
	global_load_lds_dwordx4 v192, s[28:29]
	s_setprio 1
	s_barrier
	s_waitcnt lgkmcnt(0)
	v_mfma_f32_16x16x32_bf16 v[60:63], v[128:131], v[144:147], v[60:63]
	v_mfma_f32_16x16x32_bf16 v[56:59], v[136:139], v[144:147], v[56:59]
	v_mfma_f32_16x16x32_bf16 v[44:47], v[128:131], v[152:155], v[44:47]
	v_mfma_f32_16x16x32_bf16 v[40:43], v[136:139], v[152:155], v[40:43]
	v_mfma_f32_16x16x32_bf16 v[28:31], v[128:131], v[160:163], v[28:31]
	v_mfma_f32_16x16x32_bf16 v[24:27], v[136:139], v[160:163], v[24:27]
	v_mfma_f32_16x16x32_bf16 v[12:15], v[128:131], v[168:171], v[12:15]
	v_mfma_f32_16x16x32_bf16 v[8:11], v[136:139], v[168:171], v[8:11]
	v_mfma_f32_16x16x32_bf16 v[60:63], v[132:135], v[148:151], v[60:63]
	v_mfma_f32_16x16x32_bf16 v[56:59], v[140:143], v[148:151], v[56:59]
	v_mfma_f32_16x16x32_bf16 v[44:47], v[132:135], v[156:159], v[44:47]
	v_mfma_f32_16x16x32_bf16 v[40:43], v[140:143], v[156:159], v[40:43]
	v_mfma_f32_16x16x32_bf16 v[28:31], v[132:135], v[164:167], v[28:31]
	v_mfma_f32_16x16x32_bf16 v[24:27], v[140:143], v[164:167], v[24:27]
	v_mfma_f32_16x16x32_bf16 v[12:15], v[132:135], v[172:175], v[12:15]
	v_mfma_f32_16x16x32_bf16 v[8:11], v[140:143], v[172:175], v[8:11]
	s_barrier
	s_setprio 0
	s_add_u32 s22, s26, 0xb0000
	s_addc_u32 s23, s27, 0
	s_add_i32 s57, s49, s34
	s_mov_b32 m0, s57
	s_nop 0
	global_load_lds_dwordx4 v190, s[22:23]
	s_add_i32 m0, s57, 0x2000
	s_nop 0
	global_load_lds_dwordx4 v194, s[22:23]
	s_add_u32 s22, s28, 0xb0000
	s_addc_u32 s23, s29, 0
	s_mov_b32 m0, s37
	s_nop 0
	global_load_lds_dwordx4 v188, s[22:23]
	s_mov_b32 m0, s38
	s_nop 0
	global_load_lds_dwordx4 v192, s[22:23]
	s_waitcnt vmcnt(10)
	s_setprio 1
	s_barrier
	v_mfma_f32_16x16x32_bf16 v[52:55], v[176:179], v[144:147], v[52:55]
	v_mfma_f32_16x16x32_bf16 v[48:51], v[184:187], v[144:147], v[48:51]
	v_mfma_f32_16x16x32_bf16 v[36:39], v[176:179], v[152:155], v[36:39]
	v_mfma_f32_16x16x32_bf16 v[32:35], v[184:187], v[152:155], v[32:35]
	v_mfma_f32_16x16x32_bf16 v[20:23], v[176:179], v[160:163], v[20:23]
	v_mfma_f32_16x16x32_bf16 v[16:19], v[184:187], v[160:163], v[16:19]
	v_mfma_f32_16x16x32_bf16 v[4:7], v[176:179], v[168:171], v[4:7]
	v_mfma_f32_16x16x32_bf16 v[0:3], v[184:187], v[168:171], v[0:3]
	v_mfma_f32_16x16x32_bf16 v[52:55], v[180:183], v[148:151], v[52:55]
	v_mfma_f32_16x16x32_bf16 v[48:51], v[206:209], v[148:151], v[48:51]
	v_mfma_f32_16x16x32_bf16 v[36:39], v[180:183], v[156:159], v[36:39]
	v_mfma_f32_16x16x32_bf16 v[32:35], v[206:209], v[156:159], v[32:35]
	v_mfma_f32_16x16x32_bf16 v[20:23], v[180:183], v[164:167], v[20:23]
	v_mfma_f32_16x16x32_bf16 v[16:19], v[206:209], v[164:167], v[16:19]
	v_mfma_f32_16x16x32_bf16 v[4:7], v[180:183], v[172:175], v[4:7]
	v_mfma_f32_16x16x32_bf16 v[0:3], v[206:209], v[172:175], v[0:3]
	s_barrier
	s_setprio 0
	s_add_i32 s57, 0, 0x18000
	v_add_u32_e32 v140, s57, v240
	ds_read_b128 v[128:131], v140
	ds_read_b128 v[132:135], v140 offset:1024
	ds_read_b128 v[136:139], v140 offset:2048
	ds_read_b128 v[140:143], v140 offset:3072
	ds_read_b128 v[144:147], v242 offset:32768
	ds_read_b128 v[148:151], v242 offset:33792
	ds_read_b128 v[152:155], v242 offset:34816
	ds_read_b128 v[156:159], v242 offset:35840
	ds_read_b128 v[160:163], v242 offset:36864
	ds_read_b128 v[164:167], v242 offset:37888
	ds_read_b128 v[168:171], v242 offset:38912
	ds_read_b128 v[172:175], v242 offset:39936
	s_waitcnt lgkmcnt(8)
	s_waitcnt vmcnt(8)
	s_setprio 1
	s_barrier
; #define PG8_STAGE(bufoff, gbase, voff) do { _Pragma("unroll") for (int _i = 0; _i < 2; ++_i) \
;         __builtin_amdgcn_global_load_lds((const unsigned*)((const char*)(gbase) + (voff)[_i]), (LAS unsigned*)(lds + (bufoff) + ldsw + _i * 8192), 16, 0, 0); } while (0)
; #define PG8_LDA(dst, b, h) do { _Pragma("unroll") for (int m = 0; m < 4; ++m) _Pragma("unroll") for (int k = 0; k < 2; ++k) dst[m][k] = *(const LAS bf16x8*)(lds + PG8_SA(b, h) + aoff + m * 2048 + k * 1024); } while (0)
; #define PG8_WAIT_V(n) asm volatile("s_waitcnt vmcnt(" #n ")" ::: "memory")
; #define PG8_WAIT_L(n) asm volatile("s_waitcnt lgkmcnt(" #n ")" ::: "memory")
; template <class Epi, class Sched>
; __device__ __forceinline__ void gemm_phase(LAS unsigned char* lds, const Gemm g, const Sched& S, const Epi& E) {
;     ...
;         for (int t = 0; t < nt; t += 2) {
;             const bool last = (t == nt - 2);
;             const char* a1 = cA + (size_t)(t + 1) * kstep;
;             const char* a2 = last ? nA : cA + (size_t)(t + 2) * kstep; const char* b2 = last ? nB : cB + (size_t)(t + 2) * kstep;
;             const char* a3 = a2 + kstep; const char* b3 = b2 + kstep;
;             PG8_LDB(B0, 0, 0); PG8_SCHED; PG8_LDA(At, 0, 0); PG8_STAGE(PG8_SA(1, 1), a1 + hstep, voffA);
;             PG8_WAIT_L(8); PG8_BAR; PG8_WAIT_L(0); PG8_MMA(0, 0, At, B0); PG8_BAR; PG8_SCHED;
;             PG8_LDB(B1, 0, 1); PG8_STAGE(PG8_SB(0, 0), b2, voffB);
;             PG8_BAR; PG8_WAIT_L(0); PG8_MMA(0, 1, At, B1); PG8_BAR;
;             PG8_LDA(At, 0, 1); PG8_STAGE(PG8_SA(0, 0), a2, voffA);
;             PG8_BAR; PG8_WAIT_L(0); PG8_MMA(1, 0, At, B0); PG8_BAR; PG8_SCHED;
;             PG8_STAGE(PG8_SB(0, 1), b2 + hstep, voffB);
;             PG8_WAIT_V(6); PG8_BAR; PG8_MMA(1, 1, At, B1); PG8_BAR;
;             PG8_LDB(B0, 1, 0); PG8_SCHED; PG8_LDA(At, 1, 0); PG8_STAGE(PG8_SA(0, 1), a2 + hstep, voffA);
;             PG8_WAIT_L(8); PG8_BAR; PG8_WAIT_L(0); PG8_MMA(0, 0, At, B0); PG8_BAR; PG8_SCHED;
;             PG8_LDB(B1, 1, 1); PG8_STAGE(PG8_SB(1, 0), b3, voffB);
;             PG8_BAR; PG8_WAIT_L(0); PG8_MMA(0, 1, At, B1); PG8_BAR;
;             PG8_LDA(At, 1, 1); PG8_STAGE(PG8_SA(1, 0), a3, voffA);
;             PG8_BAR; PG8_WAIT_L(0); PG8_MMA(1, 0, At, B0); PG8_BAR; PG8_SCHED;
;             PG8_STAGE(PG8_SB(1, 1), b3 + hstep, voffB);
;             PG8_WAIT_V(6); PG8_BAR; PG8_MMA(1, 1, At, B1); PG8_BAR;
	s_waitcnt lgkmcnt(0)
	v_mfma_f32_16x16x32_bf16 v[124:127], v[128:131], v[144:147], v[124:127]
	v_mfma_f32_16x16x32_bf16 v[120:123], v[136:139], v[144:147], v[120:123]
	v_mfma_f32_16x16x32_bf16 v[108:111], v[128:131], v[152:155], v[108:111]
	v_mfma_f32_16x16x32_bf16 v[104:107], v[136:139], v[152:155], v[104:107]
	v_mfma_f32_16x16x32_bf16 v[92:95], v[128:131], v[160:163], v[92:95]
	v_mfma_f32_16x16x32_bf16 v[88:91], v[136:139], v[160:163], v[88:91]
	v_mfma_f32_16x16x32_bf16 v[76:79], v[128:131], v[168:171], v[76:79]
	v_mfma_f32_16x16x32_bf16 v[72:75], v[136:139], v[168:171], v[72:75]
	v_mfma_f32_16x16x32_bf16 v[124:127], v[132:135], v[148:151], v[124:127]
	v_mfma_f32_16x16x32_bf16 v[120:123], v[140:143], v[148:151], v[120:123]
	v_mfma_f32_16x16x32_bf16 v[108:111], v[132:135], v[156:159], v[108:111]
	v_mfma_f32_16x16x32_bf16 v[104:107], v[140:143], v[156:159], v[104:107]
	v_mfma_f32_16x16x32_bf16 v[92:95], v[132:135], v[164:167], v[92:95]
	v_mfma_f32_16x16x32_bf16 v[88:91], v[140:143], v[164:167], v[88:91]
	v_mfma_f32_16x16x32_bf16 v[76:79], v[132:135], v[172:175], v[76:79]
	v_mfma_f32_16x16x32_bf16 v[72:75], v[140:143], v[172:175], v[72:75]
	s_barrier
	s_setprio 0
	s_add_i32 s28, 0, 0x1c000
	s_add_i32 s22, s57, s34
	v_add_u32_e32 v206, s28, v240
	s_add_u32 s0, s26, 0x80
	s_addc_u32 s1, s27, 0
	s_mov_b32 m0, s22
	ds_read_b128 v[176:179], v206
	ds_read_b128 v[180:183], v206 offset:1024
	ds_read_b128 v[184:187], v206 offset:2048
	ds_read_b128 v[206:209], v206 offset:3072
	global_load_lds_dwordx4 v190, s[0:1]
	s_add_i32 m0, s22, 0x2000
	s_nop 0
	global_load_lds_dwordx4 v194, s[0:1]
	s_waitcnt vmcnt(8)
	s_setprio 1
	s_barrier
	s_waitcnt lgkmcnt(0)
	v_mfma_f32_16x16x32_bf16 v[116:119], v[176:179], v[144:147], v[116:119]
	v_mfma_f32_16x16x32_bf16 v[112:115], v[184:187], v[144:147], v[112:115]
	v_mfma_f32_16x16x32_bf16 v[100:103], v[176:179], v[152:155], v[100:103]
	v_mfma_f32_16x16x32_bf16 v[96:99], v[184:187], v[152:155], v[96:99]
	v_mfma_f32_16x16x32_bf16 v[84:87], v[176:179], v[160:163], v[84:87]
	v_mfma_f32_16x16x32_bf16 v[80:83], v[184:187], v[160:163], v[80:83]
	v_mfma_f32_16x16x32_bf16 v[68:71], v[176:179], v[168:171], v[68:71]
	v_mfma_f32_16x16x32_bf16 v[64:67], v[184:187], v[168:171], v[64:67]
	v_mfma_f32_16x16x32_bf16 v[116:119], v[180:183], v[148:151], v[116:119]
	v_mfma_f32_16x16x32_bf16 v[112:115], v[206:209], v[148:151], v[112:115]
	v_mfma_f32_16x16x32_bf16 v[100:103], v[180:183], v[156:159], v[100:103]
	v_mfma_f32_16x16x32_bf16 v[96:99], v[206:209], v[156:159], v[96:99]
	v_mfma_f32_16x16x32_bf16 v[84:87], v[180:183], v[164:167], v[84:87]
	v_mfma_f32_16x16x32_bf16 v[80:83], v[206:209], v[164:167], v[80:83]
	v_mfma_f32_16x16x32_bf16 v[68:71], v[180:183], v[172:175], v[68:71]
	v_mfma_f32_16x16x32_bf16 v[64:67], v[206:209], v[172:175], v[64:67]
	s_barrier
	s_setprio 0
	s_mov_b32 m0, s44
	s_mov_b64 s[0:1], 0x80
	v_lshl_add_u64 v[210:211], v[214:215], 0, s[0:1]
	ds_read_b128 v[144:147], v242 offset:49152
	ds_read_b128 v[148:151], v242 offset:50176
	ds_read_b128 v[152:155], v242 offset:51200
	ds_read_b128 v[156:159], v242 offset:52224
	ds_read_b128 v[160:163], v242 offset:53248
	ds_read_b128 v[164:167], v242 offset:54272
	ds_read_b128 v[168:171], v242 offset:55296
	ds_read_b128 v[172:175], v242 offset:56320
	global_load_lds_dwordx4 v[210:211], off
	v_lshl_add_u64 v[210:211], v[216:217], 0, s[0:1]
	s_mov_b32 m0, s45
	s_nop 0
	global_load_lds_dwordx4 v[210:211], off
	s_setprio 1
	s_barrier
	s_waitcnt lgkmcnt(0)
	v_mfma_f32_16x16x32_bf16 v[60:63], v[128:131], v[144:147], v[60:63]
	v_mfma_f32_16x16x32_bf16 v[56:59], v[136:139], v[144:147], v[56:59]
	v_mfma_f32_16x16x32_bf16 v[44:47], v[128:131], v[152:155], v[44:47]
	v_mfma_f32_16x16x32_bf16 v[40:43], v[136:139], v[152:155], v[40:43]
	v_mfma_f32_16x16x32_bf16 v[28:31], v[128:131], v[160:163], v[28:31]
	v_mfma_f32_16x16x32_bf16 v[24:27], v[136:139], v[160:163], v[24:27]
	v_mfma_f32_16x16x32_bf16 v[12:15], v[128:131], v[168:171], v[12:15]
	v_mfma_f32_16x16x32_bf16 v[8:11], v[136:139], v[168:171], v[8:11]
	v_mfma_f32_16x16x32_bf16 v[60:63], v[132:135], v[148:151], v[60:63]
	v_mfma_f32_16x16x32_bf16 v[56:59], v[140:143], v[148:151], v[56:59]
	v_mfma_f32_16x16x32_bf16 v[44:47], v[132:135], v[156:159], v[44:47]
	v_mfma_f32_16x16x32_bf16 v[40:43], v[140:143], v[156:159], v[40:43]
	v_mfma_f32_16x16x32_bf16 v[28:31], v[132:135], v[164:167], v[28:31]
	v_mfma_f32_16x16x32_bf16 v[24:27], v[140:143], v[164:167], v[24:27]
	v_mfma_f32_16x16x32_bf16 v[12:15], v[132:135], v[172:175], v[12:15]
	v_mfma_f32_16x16x32_bf16 v[8:11], v[140:143], v[172:175], v[8:11]
	s_barrier
	s_setprio 0
	s_add_u32 s22, s26, 0xb0080
	s_addc_u32 s23, s27, 0
	s_add_i32 s26, s28, s34
	s_mov_b32 m0, s26
	s_nop 0
	global_load_lds_dwordx4 v190, s[22:23]
	s_add_i32 m0, s26, 0x2000
	s_nop 0
	global_load_lds_dwordx4 v194, s[22:23]
	s_waitcnt vmcnt(8)
	s_setprio 1
	s_barrier
	v_mfma_f32_16x16x32_bf16 v[52:55], v[176:179], v[144:147], v[52:55]
	v_mfma_f32_16x16x32_bf16 v[48:51], v[184:187], v[144:147], v[48:51]
	v_mfma_f32_16x16x32_bf16 v[36:39], v[176:179], v[152:155], v[36:39]
	v_mfma_f32_16x16x32_bf16 v[32:35], v[184:187], v[152:155], v[32:35]
	v_mfma_f32_16x16x32_bf16 v[20:23], v[176:179], v[160:163], v[20:23]
	v_mfma_f32_16x16x32_bf16 v[16:19], v[184:187], v[160:163], v[16:19]
	v_mfma_f32_16x16x32_bf16 v[4:7], v[176:179], v[168:171], v[4:7]
	v_mfma_f32_16x16x32_bf16 v[0:3], v[184:187], v[168:171], v[0:3]
	v_mfma_f32_16x16x32_bf16 v[52:55], v[180:183], v[148:151], v[52:55]
	v_mfma_f32_16x16x32_bf16 v[48:51], v[206:209], v[148:151], v[48:51]
	v_mfma_f32_16x16x32_bf16 v[36:39], v[180:183], v[156:159], v[36:39]
	v_mfma_f32_16x16x32_bf16 v[32:35], v[206:209], v[156:159], v[32:35]
	v_mfma_f32_16x16x32_bf16 v[20:23], v[180:183], v[164:167], v[20:23]
	v_mfma_f32_16x16x32_bf16 v[16:19], v[206:209], v[164:167], v[16:19]
	v_mfma_f32_16x16x32_bf16 v[4:7], v[180:183], v[172:175], v[4:7]
	v_mfma_f32_16x16x32_bf16 v[0:3], v[206:209], v[172:175], v[0:3]
	s_barrier
; __device__ __forceinline__ unsigned cvt_pk_bf16(float lo, float hi) { unsigned r; asm volatile("v_cvt_pk_bf16_f32 %0, %1, %2" : "=v"(r) : "v"(lo), "v"(hi)); return r; }
; __device__ __forceinline__ float bf_lo(unsigned u) { return __uint_as_float(u << 16); }
; __device__ __forceinline__ float bf_hi(unsigned u) { return __uint_as_float(u & 0xffff0000u); }
; template <class Epi, class Sched>
; __device__ __forceinline__ void gemm_phase(LAS unsigned char* lds, const Gemm g, const Sched& S, const Epi& E) {
;     ...
;             PG8_WAIT_V(6); PG8_BAR; PG8_MMA(1, 1, At, B1); PG8_BAR;
;         }
;         E(acc, cur, wr, wc, fr, fq);
;         if (!has_next) break;
;     __device__ __forceinline__ void operator()(const AccT& acc, const Unit& u, int wr, int wc, int fr, int fq) const {
;         asm volatile("" : "+v"(fr), "+v"(fq));
;         const int rowt = u.pm * 256; const int b = rowt >> 11;
;         const bf16_t* res = res_b + (size_t)rowt * DM; bf16_t* out = hb + (size_t)rowt * DM;
;         const int col0 = u.pn * 256 + wc * 32 + 8 * fq;
;         f32x4 gv[2][2];
; #pragma unroll
;         for (int bj = 0; bj < 2; ++bj)
; #pragma unroll
;             for (int n = 0; n < 2; ++n) gv[bj][n] = *(const f32x4*)(gate + (size_t)b * NMOD + col0 + bj * 128 + n * 4) * gs;
;         u32x4 r[2][4][2];
; #pragma unroll
;         for (int ai = 0; ai < 2; ++ai)
; #pragma unroll
;             for (int m = 0; m < 4; ++m)
; #pragma unroll
;                 for (int bj = 0; bj < 2; ++bj) r[ai][m][bj] = *(const u32x4*)(res + (size_t)(wr * 64 + fr + ai * 128 + m * 16) * DM + col0 + bj * 128);
; #pragma unroll
;         for (int ai = 0; ai < 2; ++ai)
; #pragma unroll
;             for (int m = 0; m < 4; ++m)
; #pragma unroll
;                 for (int bj = 0; bj < 2; ++bj) {
;                     const u32x4 q = r[ai][m][bj];
;                     const f32x4 r0 = {bf_lo(q.x), bf_hi(q.x), bf_lo(q.y), bf_hi(q.y)}, r1 = {bf_lo(q.z), bf_hi(q.z), bf_lo(q.w), bf_hi(q.w)};
;                     const f32x4 h0 = r0 + gv[bj][0] * acc[ai][bj][m][0], h1 = r1 + gv[bj][1] * acc[ai][bj][m][1];
;                     u32x4 w; w.x = cvt_pk_bf16(h0[0], h0[1]); w.y = cvt_pk_bf16(h0[2], h0[3]); w.z = cvt_pk_bf16(h1[0], h1[1]); w.w = cvt_pk_bf16(h1[2], h1[3]);
;                     *(u32x4*)(out + (size_t)(wr * 64 + fr + ai * 128 + m * 16) * DM + col0 + bj * 128) = w;
;                 }
	s_setprio 0
	s_add_i32 s56, s56, 2
	s_add_u32 s54, s54, 0x100
	s_addc_u32 s55, s55, 0
	s_cmp_gt_u32 s56, 41
	s_mov_b64 s[22:23], s[24:25]
	s_cbranch_scc0 .LBB0_1097
	s_lshl_b32 s25, s52, 8
	v_mov_b32_e32 v140, v239
	v_mov_b32_e32 v128, v238
	s_lshl_b32 s22, s53, 8
	s_ashr_i32 s24, s53, 3
	s_or_b32 s25, s25, s43
	s_ashr_i32 s23, s22, 31
	v_lshl_add_u32 v136, v128, 3, s25
	s_mul_hi_i32 s25, s24, 0x9000
	s_mul_i32 s24, s24, 0x9000
	s_add_u32 s24, s40, s24
	s_addc_u32 s25, s41, s25
	v_ashrrev_i32_e32 v137, 31, v136
	v_lshl_add_u64 v[138:139], v[136:137], 2, s[24:25]
	global_load_dwordx4 v[128:131], v[138:139], off offset:16
	global_load_dwordx4 v[132:135], v[138:139], off
	s_lshl_b64 s[22:23], s[22:23], 11
	s_add_u32 s24, s80, s22
	s_addc_u32 s25, s81, s23
	v_lshlrev_b64 v[226:227], 1, v[136:137]
	s_add_u32 s22, s96, s22
	s_addc_u32 s23, s97, s23
	s_and_b64 vcc, exec, s[2:3]
	s_mov_b32 s52, s50
	s_mov_b32 s53, s51
	s_waitcnt vmcnt(0)
	v_pk_mul_f32 v[216:217], v[130:131], 0.5 op_sel_hi:[1,0]
	v_pk_mul_f32 v[220:221], v[134:135], 0.5 op_sel_hi:[1,0]
	v_pk_mul_f32 v[218:219], v[132:133], 0.5 op_sel_hi:[1,0]
	v_pk_mul_f32 v[214:215], v[128:129], 0.5 op_sel_hi:[1,0]
	global_load_dwordx4 v[128:131], v[138:139], off offset:528
	global_load_dwordx4 v[132:135], v[138:139], off offset:512
	s_waitcnt vmcnt(0)
	v_pk_mul_f32 v[206:207], v[128:129], 0.5 op_sel_hi:[1,0]
	v_add_u32_e32 v128, s42, v140
	v_ashrrev_i32_e32 v129, 31, v128
	v_pk_mul_f32 v[208:209], v[130:131], 0.5 op_sel_hi:[1,0]
	v_lshl_add_u64 v[130:131], s[24:25], 0, v[226:227]
	v_lshlrev_b64 v[248:249], 11, v[128:129]
	v_lshl_add_u64 v[128:129], v[130:131], 0, v[248:249]
	global_load_dwordx4 v[244:247], v[128:129], off
	global_load_dwordx4 v[184:187], v[128:129], off offset:256
	v_lshl_add_u64 v[236:237], v[248:249], 0, s[8:9]
	v_lshl_add_u64 v[128:129], v[130:131], 0, v[236:237]
	global_load_dwordx4 v[180:183], v[128:129], off
	global_load_dwordx4 v[176:179], v[128:129], off offset:256
	v_lshl_add_u64 v[234:235], v[248:249], 0, s[10:11]
	v_lshl_add_u64 v[128:129], v[130:131], 0, v[234:235]
	global_load_dwordx4 v[172:175], v[128:129], off
	global_load_dwordx4 v[168:171], v[128:129], off offset:256
	v_lshl_add_u64 v[232:233], v[248:249], 0, s[12:13]
	v_lshl_add_u64 v[128:129], v[130:131], 0, v[232:233]
	global_load_dwordx4 v[164:167], v[128:129], off
	global_load_dwordx4 v[160:163], v[128:129], off offset:256
	v_lshl_add_u64 v[230:231], v[248:249], 0, s[14:15]
	v_lshl_add_u64 v[128:129], v[130:131], 0, v[230:231]
	global_load_dwordx4 v[156:159], v[128:129], off
	global_load_dwordx4 v[152:155], v[128:129], off offset:256
	v_lshl_add_u64 v[228:229], v[248:249], 0, s[16:17]
	v_lshl_add_u64 v[128:129], v[130:131], 0, v[228:229]
	global_load_dwordx4 v[148:151], v[128:129], off
	global_load_dwordx4 v[144:147], v[128:129], off offset:256
	v_lshl_add_u64 v[224:225], v[248:249], 0, s[18:19]
	v_lshl_add_u64 v[128:129], v[130:131], 0, v[224:225]
	global_load_dwordx4 v[140:143], v[128:129], off
	global_load_dwordx4 v[136:139], v[128:129], off offset:256
	v_lshl_add_u64 v[222:223], v[248:249], 0, s[20:21]
	v_lshl_add_u64 v[128:129], v[130:131], 0, v[222:223]
	v_pk_mul_f32 v[212:213], v[134:135], 0.5 op_sel_hi:[1,0]
	v_pk_mul_f32 v[210:211], v[132:133], 0.5 op_sel_hi:[1,0]
	global_load_dwordx4 v[132:135], v[128:129], off
	s_nop 0
	global_load_dwordx4 v[128:131], v[128:129], off offset:256
	v_lshl_add_u64 v[226:227], s[22:23], 0, v[226:227]
	v_lshl_add_u64 v[248:249], v[226:227], 0, v[248:249]
	s_mov_b64 s[24:25], s[6:7]
	s_mov_b64 s[22:23], s[4:5]
	s_waitcnt vmcnt(0)
	v_lshlrev_b32_e32 v250, 16, v244
	v_and_b32_e32 v251, 0xffff0000, v244
	v_lshlrev_b32_e32 v244, 16, v245
	v_and_b32_e32 v245, 0xffff0000, v245
	v_lshlrev_b32_e32 v252, 16, v246
	v_and_b32_e32 v253, 0xffff0000, v246
	v_lshlrev_b32_e32 v246, 16, v247
	v_and_b32_e32 v247, 0xffff0000, v247
	v_pk_fma_f32 v[126:127], v[126:127], v[220:221], v[244:245]
	v_pk_fma_f32 v[124:125], v[124:125], v[218:219], v[250:251]
	v_pk_fma_f32 v[244:245], v[122:123], v[216:217], v[246:247]
	v_pk_fma_f32 v[122:123], v[120:121], v[214:215], v[252:253]
	v_cvt_pk_bf16_f32 v120, v124, v125
	v_cvt_pk_bf16_f32 v121, v126, v127
	v_lshlrev_b32_e32 v124, 16, v186
	v_cvt_pk_bf16_f32 v122, v122, v123
	v_cvt_pk_bf16_f32 v123, v244, v245
	global_store_dwordx4 v[248:249], v[120:123], off
	v_and_b32_e32 v125, 0xffff0000, v186
	v_lshlrev_b32_e32 v126, 16, v187
	v_lshlrev_b32_e32 v120, 16, v184
	v_and_b32_e32 v121, 0xffff0000, v184
	v_and_b32_e32 v127, 0xffff0000, v187
	v_lshlrev_b32_e32 v122, 16, v185
	v_and_b32_e32 v123, 0xffff0000, v185
	v_pk_fma_f32 v[116:117], v[116:117], v[210:211], v[120:121]
	v_pk_fma_f32 v[120:121], v[114:115], v[208:209], v[126:127]
	v_pk_fma_f32 v[114:115], v[112:113], v[206:207], v[124:125]
	v_pk_fma_f32 v[118:119], v[118:119], v[212:213], v[122:123]
	v_cvt_pk_bf16_f32 v112, v116, v117
	v_lshlrev_b32_e32 v116, 16, v181
	v_cvt_pk_bf16_f32 v113, v118, v119
	v_cvt_pk_bf16_f32 v114, v114, v115
	v_cvt_pk_bf16_f32 v115, v120, v121
	global_store_dwordx4 v[248:249], v[112:115], off offset:256
	v_and_b32_e32 v117, 0xffff0000, v181
	v_lshlrev_b32_e32 v118, 16, v182
	v_lshlrev_b32_e32 v114, 16, v180
	v_and_b32_e32 v115, 0xffff0000, v180
	v_and_b32_e32 v119, 0xffff0000, v182
	v_lshlrev_b32_e32 v120, 16, v183
	v_and_b32_e32 v121, 0xffff0000, v183
	v_lshl_add_u64 v[112:113], v[226:227], 0, v[236:237]
	v_pk_fma_f32 v[110:111], v[110:111], v[220:221], v[116:117]
	v_pk_fma_f32 v[108:109], v[108:109], v[218:219], v[114:115]
	v_pk_fma_f32 v[114:115], v[106:107], v[216:217], v[120:121]
	v_pk_fma_f32 v[106:107], v[104:105], v[214:215], v[118:119]
	v_cvt_pk_bf16_f32 v104, v108, v109
; __device__ __forceinline__ unsigned cvt_pk_bf16(float lo, float hi) { unsigned r; asm volatile("v_cvt_pk_bf16_f32 %0, %1, %2" : "=v"(r) : "v"(lo), "v"(hi)); return r; }
; __device__ __forceinline__ float bf_lo(unsigned u) { return __uint_as_float(u << 16); }
; __device__ __forceinline__ float bf_hi(unsigned u) { return __uint_as_float(u & 0xffff0000u); }
;     __device__ __forceinline__ void operator()(const AccT& acc, const Unit& u, int wr, int wc, int fr, int fq) const {
;     ...
;                 for (int bj = 0; bj < 2; ++bj) {
;                     const u32x4 q = r[ai][m][bj];
;                     const f32x4 r0 = {bf_lo(q.x), bf_hi(q.x), bf_lo(q.y), bf_hi(q.y)}, r1 = {bf_lo(q.z), bf_hi(q.z), bf_lo(q.w), bf_hi(q.w)};
;                     const f32x4 h0 = r0 + gv[bj][0] * acc[ai][bj][m][0], h1 = r1 + gv[bj][1] * acc[ai][bj][m][1];
;                     u32x4 w; w.x = cvt_pk_bf16(h0[0], h0[1]); w.y = cvt_pk_bf16(h0[2], h0[3]); w.z = cvt_pk_bf16(h1[0], h1[1]); w.w = cvt_pk_bf16(h1[2], h1[3]);
;                     *(u32x4*)(out + (size_t)(wr * 64 + fr + ai * 128 + m * 16) * DM + col0 + bj * 128) = w;
;                 }
	v_cvt_pk_bf16_f32 v105, v110, v111
	v_lshlrev_b32_e32 v108, 16, v178
	v_cvt_pk_bf16_f32 v106, v106, v107
	v_cvt_pk_bf16_f32 v107, v114, v115
	global_store_dwordx4 v[112:113], v[104:107], off
	v_and_b32_e32 v109, 0xffff0000, v178
	v_lshlrev_b32_e32 v110, 16, v179
	v_lshlrev_b32_e32 v104, 16, v176
	v_and_b32_e32 v105, 0xffff0000, v176
	v_and_b32_e32 v111, 0xffff0000, v179
	v_lshlrev_b32_e32 v106, 16, v177
	v_and_b32_e32 v107, 0xffff0000, v177
	v_pk_fma_f32 v[100:101], v[100:101], v[210:211], v[104:105]
	v_pk_fma_f32 v[104:105], v[98:99], v[208:209], v[110:111]
	v_pk_fma_f32 v[98:99], v[96:97], v[206:207], v[108:109]
	v_pk_fma_f32 v[102:103], v[102:103], v[212:213], v[106:107]
	v_cvt_pk_bf16_f32 v96, v100, v101
	v_lshlrev_b32_e32 v100, 16, v173
	v_cvt_pk_bf16_f32 v97, v102, v103
	v_cvt_pk_bf16_f32 v98, v98, v99
	v_cvt_pk_bf16_f32 v99, v104, v105
	global_store_dwordx4 v[112:113], v[96:99], off offset:256
	v_and_b32_e32 v101, 0xffff0000, v173
	v_lshlrev_b32_e32 v102, 16, v174
	v_lshlrev_b32_e32 v98, 16, v172
	v_and_b32_e32 v99, 0xffff0000, v172
	v_and_b32_e32 v103, 0xffff0000, v174
	v_lshlrev_b32_e32 v104, 16, v175
	v_and_b32_e32 v105, 0xffff0000, v175
	v_lshl_add_u64 v[96:97], v[226:227], 0, v[234:235]
	v_pk_fma_f32 v[94:95], v[94:95], v[220:221], v[100:101]
	v_pk_fma_f32 v[92:93], v[92:93], v[218:219], v[98:99]
	v_pk_fma_f32 v[98:99], v[90:91], v[216:217], v[104:105]
	v_pk_fma_f32 v[90:91], v[88:89], v[214:215], v[102:103]
	v_cvt_pk_bf16_f32 v88, v92, v93
	v_cvt_pk_bf16_f32 v89, v94, v95
	v_lshlrev_b32_e32 v92, 16, v170
	v_cvt_pk_bf16_f32 v90, v90, v91
	v_cvt_pk_bf16_f32 v91, v98, v99
	global_store_dwordx4 v[96:97], v[88:91], off
	v_and_b32_e32 v93, 0xffff0000, v170
	v_lshlrev_b32_e32 v94, 16, v171
	v_lshlrev_b32_e32 v88, 16, v168
	v_and_b32_e32 v89, 0xffff0000, v168
	v_and_b32_e32 v95, 0xffff0000, v171
	v_lshlrev_b32_e32 v90, 16, v169
	v_and_b32_e32 v91, 0xffff0000, v169
	v_pk_fma_f32 v[84:85], v[84:85], v[210:211], v[88:89]
	v_pk_fma_f32 v[88:89], v[82:83], v[208:209], v[94:95]
	v_pk_fma_f32 v[82:83], v[80:81], v[206:207], v[92:93]
	v_pk_fma_f32 v[86:87], v[86:87], v[212:213], v[90:91]
	v_cvt_pk_bf16_f32 v80, v84, v85
	v_lshlrev_b32_e32 v84, 16, v165
	v_cvt_pk_bf16_f32 v81, v86, v87
	v_cvt_pk_bf16_f32 v82, v82, v83
	v_cvt_pk_bf16_f32 v83, v88, v89
	global_store_dwordx4 v[96:97], v[80:83], off offset:256
	v_and_b32_e32 v85, 0xffff0000, v165
	v_lshlrev_b32_e32 v86, 16, v166
	v_lshlrev_b32_e32 v82, 16, v164
	v_and_b32_e32 v83, 0xffff0000, v164
	v_and_b32_e32 v87, 0xffff0000, v166
	v_lshlrev_b32_e32 v88, 16, v167
	v_and_b32_e32 v89, 0xffff0000, v167
	v_lshl_add_u64 v[80:81], v[226:227], 0, v[232:233]
	v_pk_fma_f32 v[78:79], v[78:79], v[220:221], v[84:85]
	v_pk_fma_f32 v[76:77], v[76:77], v[218:219], v[82:83]
	v_pk_fma_f32 v[82:83], v[74:75], v[216:217], v[88:89]
	v_pk_fma_f32 v[74:75], v[72:73], v[214:215], v[86:87]
	v_cvt_pk_bf16_f32 v72, v76, v77
	v_cvt_pk_bf16_f32 v73, v78, v79
	v_lshlrev_b32_e32 v76, 16, v162
	v_cvt_pk_bf16_f32 v74, v74, v75
	v_cvt_pk_bf16_f32 v75, v82, v83
	global_store_dwordx4 v[80:81], v[72:75], off
	v_and_b32_e32 v77, 0xffff0000, v162
	v_lshlrev_b32_e32 v78, 16, v163
	v_lshlrev_b32_e32 v72, 16, v160
	v_and_b32_e32 v73, 0xffff0000, v160
	v_and_b32_e32 v79, 0xffff0000, v163
	v_lshlrev_b32_e32 v74, 16, v161
	v_and_b32_e32 v75, 0xffff0000, v161
	v_pk_fma_f32 v[68:69], v[68:69], v[210:211], v[72:73]
	v_pk_fma_f32 v[72:73], v[66:67], v[208:209], v[78:79]
	v_pk_fma_f32 v[66:67], v[64:65], v[206:207], v[76:77]
	v_pk_fma_f32 v[70:71], v[70:71], v[212:213], v[74:75]
	v_cvt_pk_bf16_f32 v64, v68, v69
	v_lshlrev_b32_e32 v68, 16, v157
	v_cvt_pk_bf16_f32 v65, v70, v71
	v_cvt_pk_bf16_f32 v66, v66, v67
	v_cvt_pk_bf16_f32 v67, v72, v73
	global_store_dwordx4 v[80:81], v[64:67], off offset:256
	v_and_b32_e32 v69, 0xffff0000, v157
	v_lshlrev_b32_e32 v70, 16, v158
	v_lshlrev_b32_e32 v66, 16, v156
	v_and_b32_e32 v67, 0xffff0000, v156
	v_and_b32_e32 v71, 0xffff0000, v158
	v_lshlrev_b32_e32 v72, 16, v159
	v_and_b32_e32 v73, 0xffff0000, v159
	v_lshl_add_u64 v[64:65], v[226:227], 0, v[230:231]
	v_pk_fma_f32 v[62:63], v[62:63], v[220:221], v[68:69]
	v_pk_fma_f32 v[60:61], v[60:61], v[218:219], v[66:67]
	v_pk_fma_f32 v[66:67], v[58:59], v[216:217], v[72:73]
	v_pk_fma_f32 v[58:59], v[56:57], v[214:215], v[70:71]
	v_cvt_pk_bf16_f32 v56, v60, v61
	v_cvt_pk_bf16_f32 v57, v62, v63
	v_lshlrev_b32_e32 v60, 16, v154
	v_cvt_pk_bf16_f32 v58, v58, v59
	v_cvt_pk_bf16_f32 v59, v66, v67
	global_store_dwordx4 v[64:65], v[56:59], off
	v_and_b32_e32 v61, 0xffff0000, v154
	v_lshlrev_b32_e32 v62, 16, v155
	v_lshlrev_b32_e32 v56, 16, v152
	v_and_b32_e32 v57, 0xffff0000, v152
	v_and_b32_e32 v63, 0xffff0000, v155
	v_lshlrev_b32_e32 v58, 16, v153
	v_and_b32_e32 v59, 0xffff0000, v153
; __device__ __forceinline__ unsigned cvt_pk_bf16(float lo, float hi) { unsigned r; asm volatile("v_cvt_pk_bf16_f32 %0, %1, %2" : "=v"(r) : "v"(lo), "v"(hi)); return r; }
; __device__ __forceinline__ float bf_lo(unsigned u) { return __uint_as_float(u << 16); }
; __device__ __forceinline__ float bf_hi(unsigned u) { return __uint_as_float(u & 0xffff0000u); }
; #define PG8_WAIT_V(n) asm volatile("s_waitcnt vmcnt(" #n ")" ::: "memory")
; #define PG8_BAR __builtin_amdgcn_s_barrier()
; template <class Epi, class Sched>
; __device__ __forceinline__ void gemm_phase(LAS unsigned char* lds, const Gemm g, const Sched& S, const Epi& E) {
;     ...
;         if (!has_next) break;
; #pragma unroll
;         for (int a = 0; a < 2; ++a)
; #pragma unroll
;             for (int b = 0; b < 2; ++b)
; #pragma unroll
;                 for (int m = 0; m < 4; ++m)
; #pragma unroll
;                     for (int n = 0; n < 2; ++n) acc[a][b][m][n] = (f32x4){0.f, 0.f, 0.f, 0.f};
;         cur = nxt; cA = nA; cB = nB; ++ui;
;     }
;     PG8_WAIT_V(0);
;     if (wr == 0) PG8_BAR;
;     PG8_BAR;
;     __device__ __forceinline__ void operator()(const AccT& acc, const Unit& u, int wr, int wc, int fr, int fq) const {
;     ...
;                 for (int bj = 0; bj < 2; ++bj) {
;                     const u32x4 q = r[ai][m][bj];
;                     const f32x4 r0 = {bf_lo(q.x), bf_hi(q.x), bf_lo(q.y), bf_hi(q.y)}, r1 = {bf_lo(q.z), bf_hi(q.z), bf_lo(q.w), bf_hi(q.w)};
;                     const f32x4 h0 = r0 + gv[bj][0] * acc[ai][bj][m][0], h1 = r1 + gv[bj][1] * acc[ai][bj][m][1];
;                     u32x4 w; w.x = cvt_pk_bf16(h0[0], h0[1]); w.y = cvt_pk_bf16(h0[2], h0[3]); w.z = cvt_pk_bf16(h1[0], h1[1]); w.w = cvt_pk_bf16(h1[2], h1[3]);
;                     *(u32x4*)(out + (size_t)(wr * 64 + fr + ai * 128 + m * 16) * DM + col0 + bj * 128) = w;
;                 }
	v_pk_fma_f32 v[52:53], v[52:53], v[210:211], v[56:57]
	v_pk_fma_f32 v[56:57], v[50:51], v[208:209], v[62:63]
	v_pk_fma_f32 v[50:51], v[48:49], v[206:207], v[60:61]
	v_pk_fma_f32 v[54:55], v[54:55], v[212:213], v[58:59]
	v_cvt_pk_bf16_f32 v48, v52, v53
	v_lshlrev_b32_e32 v52, 16, v149
	v_cvt_pk_bf16_f32 v49, v54, v55
	v_cvt_pk_bf16_f32 v50, v50, v51
	v_cvt_pk_bf16_f32 v51, v56, v57
	global_store_dwordx4 v[64:65], v[48:51], off offset:256
	v_and_b32_e32 v53, 0xffff0000, v149
	v_lshlrev_b32_e32 v54, 16, v150
	v_lshlrev_b32_e32 v50, 16, v148
	v_and_b32_e32 v51, 0xffff0000, v148
	v_and_b32_e32 v55, 0xffff0000, v150
	v_lshlrev_b32_e32 v56, 16, v151
	v_and_b32_e32 v57, 0xffff0000, v151
	v_lshl_add_u64 v[48:49], v[226:227], 0, v[228:229]
	v_pk_fma_f32 v[46:47], v[46:47], v[220:221], v[52:53]
	v_pk_fma_f32 v[44:45], v[44:45], v[218:219], v[50:51]
	v_pk_fma_f32 v[50:51], v[42:43], v[216:217], v[56:57]
	v_pk_fma_f32 v[42:43], v[40:41], v[214:215], v[54:55]
	v_cvt_pk_bf16_f32 v40, v44, v45
	v_cvt_pk_bf16_f32 v41, v46, v47
	v_lshlrev_b32_e32 v44, 16, v146
	v_cvt_pk_bf16_f32 v42, v42, v43
	v_cvt_pk_bf16_f32 v43, v50, v51
	global_store_dwordx4 v[48:49], v[40:43], off
	v_and_b32_e32 v45, 0xffff0000, v146
	v_lshlrev_b32_e32 v46, 16, v147
	v_lshlrev_b32_e32 v40, 16, v144
	v_and_b32_e32 v41, 0xffff0000, v144
	v_and_b32_e32 v47, 0xffff0000, v147
	v_lshlrev_b32_e32 v42, 16, v145
	v_and_b32_e32 v43, 0xffff0000, v145
	v_pk_fma_f32 v[36:37], v[36:37], v[210:211], v[40:41]
	v_pk_fma_f32 v[40:41], v[34:35], v[208:209], v[46:47]
	v_pk_fma_f32 v[34:35], v[32:33], v[206:207], v[44:45]
	v_pk_fma_f32 v[38:39], v[38:39], v[212:213], v[42:43]
	v_cvt_pk_bf16_f32 v32, v36, v37
	v_lshlrev_b32_e32 v36, 16, v141
	v_cvt_pk_bf16_f32 v33, v38, v39
	v_cvt_pk_bf16_f32 v34, v34, v35
	v_cvt_pk_bf16_f32 v35, v40, v41
	global_store_dwordx4 v[48:49], v[32:35], off offset:256
	v_and_b32_e32 v37, 0xffff0000, v141
	v_lshlrev_b32_e32 v38, 16, v142
	v_lshlrev_b32_e32 v34, 16, v140
	v_and_b32_e32 v35, 0xffff0000, v140
	v_and_b32_e32 v39, 0xffff0000, v142
	v_lshlrev_b32_e32 v40, 16, v143
	v_and_b32_e32 v41, 0xffff0000, v143
	v_lshl_add_u64 v[32:33], v[226:227], 0, v[224:225]
	v_pk_fma_f32 v[30:31], v[30:31], v[220:221], v[36:37]
	v_pk_fma_f32 v[28:29], v[28:29], v[218:219], v[34:35]
	v_pk_fma_f32 v[34:35], v[26:27], v[216:217], v[40:41]
	v_pk_fma_f32 v[26:27], v[24:25], v[214:215], v[38:39]
	v_cvt_pk_bf16_f32 v24, v28, v29
	v_cvt_pk_bf16_f32 v25, v30, v31
	v_lshlrev_b32_e32 v28, 16, v138
	v_cvt_pk_bf16_f32 v26, v26, v27
	v_cvt_pk_bf16_f32 v27, v34, v35
	global_store_dwordx4 v[32:33], v[24:27], off
	v_and_b32_e32 v29, 0xffff0000, v138
	v_lshlrev_b32_e32 v30, 16, v139
	v_lshlrev_b32_e32 v24, 16, v136
	v_and_b32_e32 v25, 0xffff0000, v136
	v_and_b32_e32 v31, 0xffff0000, v139
	v_lshlrev_b32_e32 v26, 16, v137
	v_and_b32_e32 v27, 0xffff0000, v137
	v_pk_fma_f32 v[20:21], v[20:21], v[210:211], v[24:25]
	v_pk_fma_f32 v[24:25], v[18:19], v[208:209], v[30:31]
	v_pk_fma_f32 v[18:19], v[16:17], v[206:207], v[28:29]
	v_pk_fma_f32 v[22:23], v[22:23], v[212:213], v[26:27]
	v_cvt_pk_bf16_f32 v16, v20, v21
	v_lshlrev_b32_e32 v20, 16, v133
	v_cvt_pk_bf16_f32 v17, v22, v23
	v_cvt_pk_bf16_f32 v18, v18, v19
	v_cvt_pk_bf16_f32 v19, v24, v25
	global_store_dwordx4 v[32:33], v[16:19], off offset:256
	v_and_b32_e32 v21, 0xffff0000, v133
	v_lshlrev_b32_e32 v22, 16, v134
	v_lshlrev_b32_e32 v18, 16, v132
	v_and_b32_e32 v19, 0xffff0000, v132
	v_and_b32_e32 v23, 0xffff0000, v134
	v_lshlrev_b32_e32 v24, 16, v135
	v_and_b32_e32 v25, 0xffff0000, v135
	v_lshl_add_u64 v[16:17], v[226:227], 0, v[222:223]
	v_pk_fma_f32 v[14:15], v[14:15], v[220:221], v[20:21]
	v_pk_fma_f32 v[12:13], v[12:13], v[218:219], v[18:19]
	v_pk_fma_f32 v[18:19], v[10:11], v[216:217], v[24:25]
	v_pk_fma_f32 v[10:11], v[8:9], v[214:215], v[22:23]
	v_cvt_pk_bf16_f32 v8, v12, v13
	v_cvt_pk_bf16_f32 v9, v14, v15
	v_lshlrev_b32_e32 v12, 16, v130
	v_cvt_pk_bf16_f32 v10, v10, v11
	v_cvt_pk_bf16_f32 v11, v18, v19
	global_store_dwordx4 v[16:17], v[8:11], off
	v_and_b32_e32 v13, 0xffff0000, v130
	v_lshlrev_b32_e32 v14, 16, v131
	v_lshlrev_b32_e32 v8, 16, v128
	v_and_b32_e32 v9, 0xffff0000, v128
	v_and_b32_e32 v15, 0xffff0000, v131
	v_lshlrev_b32_e32 v10, 16, v129
	v_and_b32_e32 v11, 0xffff0000, v129
	v_pk_fma_f32 v[4:5], v[4:5], v[210:211], v[8:9]
	v_pk_fma_f32 v[8:9], v[2:3], v[208:209], v[14:15]
	v_pk_fma_f32 v[2:3], v[0:1], v[206:207], v[12:13]
	v_pk_fma_f32 v[6:7], v[6:7], v[212:213], v[10:11]
	v_cvt_pk_bf16_f32 v0, v4, v5
	s_nop 0
	v_cvt_pk_bf16_f32 v1, v6, v7
	v_cvt_pk_bf16_f32 v2, v2, v3
	v_cvt_pk_bf16_f32 v3, v8, v9
	global_store_dwordx4 v[16:17], v[0:3], off offset:256
	s_cbranch_vccz .LBB0_1086
	s_waitcnt vmcnt(0)
	s_cmpk_gt_u32 s30, 0xff
	s_cbranch_scc1 .LBB0_1101
	s_barrier
